# plus: K-loop workgroup barrier moved ahead of each k-iteration's last 4 MFMAs so the next k-iteration's first LDS writes and fragment reads issue under them
# speedup vs baseline: 1.0123x; 1.0123x over previous
; template <bool trans>
; DI void gemm_core(const GTile& tl, const GTile& nx, bool has_next  , bool chain  , bool pre, u32x4 (&ra)[4], u32x4 (&rb)[4], char* smem, f32x16 (&acc)[2][4]) {
;     ...
;   const int nk = K / 64;
;   if (!pre) { G_LOAD(0); G_STORE(0); G_LOAD(1); }
;   for (int kt = 0; kt < nk; ++kt) {
;     __syncthreads();
;     G_COMPUTE(kt & 1, kt);
;   }
.LBB0_103:
	v_lshl_add_u64 v[190:191], s[0:1], 0, v[192:193]
	v_lshl_add_u64 v[188:189], s[6:7], 0, v[192:193]
	s_waitcnt lgkmcnt(0)
	s_barrier
	global_load_dwordx4 v[218:221], v[190:191], off offset:256
	global_load_dwordx4 v[222:225], v[188:189], off offset:256
	s_lshr_b32 s1, s33, 1
	s_and_b32 s0, s33, 0xc0
	v_and_b32_e32 v10, 31, v8
	s_and_b32 s1, s1, 0xfffff80
	v_or_b32_e32 v12, s1, v10
	v_or_b32_e32 v10, s0, v10
	v_add3_u32 v215, 16, v11, v9
	v_lshrrev_b32_e32 v8, 1, v8
	v_mul_u32_u24_e32 v242, 0x90, v10
	v_and_b32_e32 v243, 16, v8
	v_add_u32_e32 v209, 0x12000, v215
	v_mul_lo_u32 v208, v12, s45
	v_add3_u32 v205, 16, v242, v243
	v_add_u32_e32 v210, 0x1b000, v215
	ds_write_b128 v209, v[0:3]
	s_waitcnt vmcnt(6)
	ds_write_b128 v210, v[4:7]
	v_add3_u32 v204, 16, v208, v243
	ds_read_b128 v[0:3], v205 offset:36864
	ds_read_b128 v[4:7], v205 offset:41472
	ds_read_b128 v[8:11], v204
	ds_read_b128 v[12:15], v204 offset:4608
	v_lshl_add_u64 v[184:185], v[190:191], 0, s[42:43]
	v_lshl_add_u64 v[186:187], s[28:29], 0, v[192:193]
	v_lshl_add_u64 v[194:195], v[190:191], 0, s[34:35]
	v_lshl_add_u64 v[196:197], s[26:27], 0, v[192:193]
	s_setprio 1
	s_waitcnt lgkmcnt(1)
	v_mfma_f32_32x32x16_bf16 v[112:127], v[8:11], v[0:3], 0
	v_mfma_f32_32x32x16_bf16 v[48:63], v[8:11], v[4:7], 0
	s_waitcnt lgkmcnt(0)
	v_mfma_f32_32x32x16_bf16 v[96:111], v[12:15], v[0:3], 0
	v_mfma_f32_32x32x16_bf16 v[32:47], v[12:15], v[4:7], 0
	ds_read_b128 v[8:11], v204 offset:9216
	ds_read_b128 v[12:15], v204 offset:13824
	s_waitcnt lgkmcnt(1)
	v_mfma_f32_32x32x16_bf16 v[80:95], v[8:11], v[0:3], 0
	v_mfma_f32_32x32x16_bf16 v[16:31], v[8:11], v[4:7], 0
	s_waitcnt lgkmcnt(0)
	v_mfma_f32_32x32x16_bf16 v[64:79], v[12:15], v[0:3], 0
	v_mfma_f32_32x32x16_bf16 v[0:15], v[12:15], v[4:7], 0
	s_setprio 0
	global_load_dwordx4 v[226:229], v[194:195], off offset:256
	global_load_dwordx4 v[230:233], v[196:197], off offset:256
	v_add_u32_e32 v212, 0x14400, v215
	v_add_u32_e32 v211, 0x1d400, v215
	ds_write_b128 v212, v[176:179]
	s_waitcnt vmcnt(7)
	ds_write_b128 v211, v[180:183]
	ds_read_b128 v[176:179], v205 offset:36896
	ds_read_b128 v[180:183], v205 offset:41504
	ds_read_b128 v[198:201], v204 offset:32
	ds_read_b128 v[234:237], v204 offset:4640
	s_setprio 1
	s_waitcnt lgkmcnt(1)
	v_mfma_f32_32x32x16_bf16 v[112:127], v[198:201], v[176:179], v[112:127]
	v_mfma_f32_32x32x16_bf16 v[48:63], v[198:201], v[180:183], v[48:63]
	s_waitcnt lgkmcnt(0)
	v_mfma_f32_32x32x16_bf16 v[96:111], v[234:237], v[176:179], v[96:111]
	v_mfma_f32_32x32x16_bf16 v[32:47], v[234:237], v[180:183], v[32:47]
	ds_read_b128 v[198:201], v204 offset:9248
	ds_read_b128 v[234:237], v204 offset:13856
	s_waitcnt lgkmcnt(1)
	v_mfma_f32_32x32x16_bf16 v[80:95], v[198:201], v[176:179], v[80:95]
	v_mfma_f32_32x32x16_bf16 v[16:31], v[198:201], v[180:183], v[16:31]
	s_waitcnt lgkmcnt(0)
	v_mfma_f32_32x32x16_bf16 v[64:79], v[234:237], v[176:179], v[64:79]
	v_mfma_f32_32x32x16_bf16 v[0:15], v[234:237], v[180:183], v[0:15]
	s_setprio 0
	global_load_dwordx4 v[176:179], v[184:185], off offset:256
	global_load_dwordx4 v[180:183], v[186:187], off offset:256
	v_add_u32_e32 v214, 0x16800, v215
	v_add_u32_e32 v213, 0x1f800, v215
	ds_write_b128 v214, v[168:171]
	s_waitcnt vmcnt(8)
	ds_write_b128 v213, v[172:175]
	ds_read_b128 v[168:171], v205 offset:36928
	ds_read_b128 v[172:175], v205 offset:41536
	ds_read_b128 v[198:201], v204 offset:64
	ds_read_b128 v[234:237], v204 offset:4672
	s_setprio 1
	s_waitcnt lgkmcnt(1)
	v_mfma_f32_32x32x16_bf16 v[112:127], v[198:201], v[168:171], v[112:127]
	v_mfma_f32_32x32x16_bf16 v[48:63], v[198:201], v[172:175], v[48:63]
	s_waitcnt lgkmcnt(0)
	v_mfma_f32_32x32x16_bf16 v[96:111], v[234:237], v[168:171], v[96:111]
	v_mfma_f32_32x32x16_bf16 v[32:47], v[234:237], v[172:175], v[32:47]
	ds_read_b128 v[198:201], v204 offset:9280
	ds_read_b128 v[234:237], v204 offset:13888
	s_waitcnt lgkmcnt(1)
	v_mfma_f32_32x32x16_bf16 v[80:95], v[198:201], v[168:171], v[80:95]
	v_mfma_f32_32x32x16_bf16 v[16:31], v[198:201], v[172:175], v[16:31]
	s_waitcnt lgkmcnt(0)
	v_mfma_f32_32x32x16_bf16 v[64:79], v[234:237], v[168:171], v[64:79]
	v_mfma_f32_32x32x16_bf16 v[0:15], v[234:237], v[172:175], v[0:15]
	s_setprio 0
	v_add_co_u32_e32 v198, vcc, s44, v190
	v_add_u32_e32 v217, 0x18c00, v215
	s_nop 0
	v_addc_co_u32_e32 v199, vcc, 0, v191, vcc
	v_add_co_u32_e32 v200, vcc, s44, v188
	v_add_u32_e32 v216, 0x21c00, v215
	s_nop 0
	v_addc_co_u32_e32 v201, vcc, 0, v189, vcc
	global_load_dwordx4 v[168:171], v[198:199], off offset:256
	global_load_dwordx4 v[172:175], v[200:201], off offset:256
	s_waitcnt vmcnt(8)
	ds_write_b128 v217, v[164:167]
	ds_write_b128 v216, v[160:163]
	ds_read_b128 v[160:163], v205 offset:36960
	ds_read_b128 v[164:167], v205 offset:41568
	ds_read_b128 v[234:237], v204 offset:96
	ds_read_b128 v[238:241], v204 offset:4704
	s_setprio 1
	s_waitcnt lgkmcnt(1)
	v_mfma_f32_32x32x16_bf16 v[112:127], v[234:237], v[160:163], v[112:127]
	v_mfma_f32_32x32x16_bf16 v[48:63], v[234:237], v[164:167], v[48:63]
	s_waitcnt lgkmcnt(0)
	v_mfma_f32_32x32x16_bf16 v[96:111], v[238:241], v[160:163], v[96:111]
	v_mfma_f32_32x32x16_bf16 v[32:47], v[238:241], v[164:167], v[32:47]
	ds_read_b128 v[234:237], v204 offset:9312
	ds_read_b128 v[238:241], v204 offset:13920
	s_waitcnt lgkmcnt(1)
	v_mfma_f32_32x32x16_bf16 v[80:95], v[234:237], v[160:163], v[80:95]
	v_mfma_f32_32x32x16_bf16 v[16:31], v[234:237], v[164:167], v[16:31]
	s_waitcnt lgkmcnt(0)
	v_mfma_f32_32x32x16_bf16 v[64:79], v[238:241], v[160:163], v[64:79]
	v_mfma_f32_32x32x16_bf16 v[0:15], v[238:241], v[164:167], v[0:15]
	s_setprio 0
	global_load_dwordx4 v[160:163], v[190:191], off offset:384
	global_load_dwordx4 v[164:167], v[188:189], off offset:384
	s_barrier
; template <bool trans>
; DI void gemm_core(const GTile& tl, const GTile& nx, bool has_next  , bool chain  , bool pre, u32x4 (&ra)[4], u32x4 (&rb)[4], char* smem, f32x16 (&acc)[2][4]) {
;     ...
;   const int nk = K / 64;
;   if (!pre) { G_LOAD(0); G_STORE(0); G_LOAD(1); }
;   for (int kt = 0; kt < nk; ++kt) {
;     __syncthreads();
;     G_COMPUTE(kt & 1, kt);
;   }
	s_add_i32 s0, 16, 0x12000
	v_add3_u32 v192, s0, v208, v243
	s_add_i32 s0, 16, 0x1b000
	v_add3_u32 v208, s0, v242, v243
	s_waitcnt vmcnt(9)
	ds_write_b128 v215, v[218:221]
	s_waitcnt vmcnt(8)
	ds_write_b128 v215, v[222:225] offset:36864
	ds_read_b128 v[218:221], v208
	ds_read_b128 v[222:225], v208 offset:4608
	ds_read_b128 v[234:237], v192
	ds_read_b128 v[238:241], v192 offset:4608
	s_setprio 1
	s_waitcnt lgkmcnt(1)
	v_mfma_f32_32x32x16_bf16 v[112:127], v[234:237], v[218:221], v[112:127]
	v_mfma_f32_32x32x16_bf16 v[48:63], v[234:237], v[222:225], v[48:63]
	s_waitcnt lgkmcnt(0)
	v_mfma_f32_32x32x16_bf16 v[96:111], v[238:241], v[218:221], v[96:111]
	v_mfma_f32_32x32x16_bf16 v[32:47], v[238:241], v[222:225], v[32:47]
	ds_read_b128 v[234:237], v192 offset:9216
	ds_read_b128 v[238:241], v192 offset:13824
	s_waitcnt lgkmcnt(1)
	v_mfma_f32_32x32x16_bf16 v[80:95], v[234:237], v[218:221], v[80:95]
	v_mfma_f32_32x32x16_bf16 v[16:31], v[234:237], v[222:225], v[16:31]
	s_waitcnt lgkmcnt(0)
	v_mfma_f32_32x32x16_bf16 v[64:79], v[238:241], v[218:221], v[64:79]
	v_mfma_f32_32x32x16_bf16 v[0:15], v[238:241], v[222:225], v[0:15]
	s_setprio 0
	global_load_dwordx4 v[218:221], v[194:195], off offset:384
	global_load_dwordx4 v[222:225], v[196:197], off offset:384
	s_waitcnt vmcnt(9)
	ds_write_b128 v215, v[226:229] offset:9216
	s_waitcnt vmcnt(8)
	ds_write_b128 v215, v[230:233] offset:46080
	ds_read_b128 v[226:229], v208 offset:32
	ds_read_b128 v[230:233], v208 offset:4640
	ds_read_b128 v[234:237], v192 offset:32
	ds_read_b128 v[238:241], v192 offset:4640
	s_setprio 1
	s_waitcnt lgkmcnt(1)
	v_mfma_f32_32x32x16_bf16 v[112:127], v[234:237], v[226:229], v[112:127]
	v_mfma_f32_32x32x16_bf16 v[48:63], v[234:237], v[230:233], v[48:63]
	s_waitcnt lgkmcnt(0)
	v_mfma_f32_32x32x16_bf16 v[96:111], v[238:241], v[226:229], v[96:111]
	v_mfma_f32_32x32x16_bf16 v[32:47], v[238:241], v[230:233], v[32:47]
	ds_read_b128 v[234:237], v192 offset:9248
	ds_read_b128 v[238:241], v192 offset:13856
	s_waitcnt lgkmcnt(1)
	v_mfma_f32_32x32x16_bf16 v[80:95], v[234:237], v[226:229], v[80:95]
	v_mfma_f32_32x32x16_bf16 v[16:31], v[234:237], v[230:233], v[16:31]
	s_waitcnt lgkmcnt(0)
	v_mfma_f32_32x32x16_bf16 v[64:79], v[238:241], v[226:229], v[64:79]
	v_mfma_f32_32x32x16_bf16 v[0:15], v[238:241], v[230:233], v[0:15]
	s_setprio 0
	global_load_dwordx4 v[226:229], v[184:185], off offset:384
	global_load_dwordx4 v[230:233], v[186:187], off offset:384
	s_waitcnt vmcnt(9)
	ds_write_b128 v215, v[176:179] offset:18432
	s_waitcnt vmcnt(8)
	ds_write_b128 v215, v[180:183] offset:55296
	ds_read_b128 v[176:179], v208 offset:64
	ds_read_b128 v[180:183], v208 offset:4672
	ds_read_b128 v[234:237], v192 offset:64
	ds_read_b128 v[238:241], v192 offset:4672
	s_setprio 1
	s_waitcnt lgkmcnt(1)
	v_mfma_f32_32x32x16_bf16 v[112:127], v[234:237], v[176:179], v[112:127]
	v_mfma_f32_32x32x16_bf16 v[48:63], v[234:237], v[180:183], v[48:63]
	s_waitcnt lgkmcnt(0)
	v_mfma_f32_32x32x16_bf16 v[96:111], v[238:241], v[176:179], v[96:111]
	v_mfma_f32_32x32x16_bf16 v[32:47], v[238:241], v[180:183], v[32:47]
	ds_read_b128 v[234:237], v192 offset:9280
	ds_read_b128 v[238:241], v192 offset:13888
	s_waitcnt lgkmcnt(1)
	v_mfma_f32_32x32x16_bf16 v[80:95], v[234:237], v[176:179], v[80:95]
	v_mfma_f32_32x32x16_bf16 v[16:31], v[234:237], v[180:183], v[16:31]
	s_waitcnt lgkmcnt(0)
	v_mfma_f32_32x32x16_bf16 v[64:79], v[238:241], v[176:179], v[64:79]
	v_mfma_f32_32x32x16_bf16 v[0:15], v[238:241], v[180:183], v[0:15]
	s_setprio 0
	global_load_dwordx4 v[176:179], v[198:199], off offset:384
	global_load_dwordx4 v[180:183], v[200:201], off offset:384
	s_waitcnt vmcnt(9)
	ds_write_b128 v215, v[168:171] offset:27648
	s_waitcnt vmcnt(8)
	ds_write_b128 v215, v[172:175] offset:64512
	ds_read_b128 v[168:171], v208 offset:96
	ds_read_b128 v[172:175], v208 offset:4704
	ds_read_b128 v[234:237], v192 offset:96
	ds_read_b128 v[238:241], v192 offset:4704
	s_setprio 1
	s_waitcnt lgkmcnt(1)
	v_mfma_f32_32x32x16_bf16 v[112:127], v[234:237], v[168:171], v[112:127]
	v_mfma_f32_32x32x16_bf16 v[48:63], v[234:237], v[172:175], v[48:63]
	s_waitcnt lgkmcnt(0)
	v_mfma_f32_32x32x16_bf16 v[96:111], v[238:241], v[168:171], v[96:111]
	v_mfma_f32_32x32x16_bf16 v[32:47], v[238:241], v[172:175], v[32:47]
	ds_read_b128 v[234:237], v192 offset:9312
	ds_read_b128 v[238:241], v192 offset:13920
	s_waitcnt lgkmcnt(1)
	v_mfma_f32_32x32x16_bf16 v[80:95], v[234:237], v[168:171], v[80:95]
	v_mfma_f32_32x32x16_bf16 v[16:31], v[234:237], v[172:175], v[16:31]
	s_waitcnt lgkmcnt(0)
	v_mfma_f32_32x32x16_bf16 v[64:79], v[238:241], v[168:171], v[64:79]
	v_mfma_f32_32x32x16_bf16 v[0:15], v[238:241], v[172:175], v[0:15]
	s_setprio 0
	global_load_dwordx4 v[168:171], v[190:191], off offset:512
	global_load_dwordx4 v[172:175], v[188:189], off offset:512
	s_barrier
; template <bool trans>
; DI void gemm_core(const GTile& tl, const GTile& nx, bool has_next  , bool chain  , bool pre, u32x4 (&ra)[4], u32x4 (&rb)[4], char* smem, f32x16 (&acc)[2][4]) {
;     ...
;   const int nk = K / 64;
;   if (!pre) { G_LOAD(0); G_STORE(0); G_LOAD(1); }
;   for (int kt = 0; kt < nk; ++kt) {
;     __syncthreads();
;     G_COMPUTE(kt & 1, kt);
;   }
	s_waitcnt vmcnt(9)
	ds_write_b128 v209, v[160:163]
	s_waitcnt vmcnt(8)
	ds_write_b128 v210, v[164:167]
	ds_read_b128 v[160:163], v205 offset:36864
	ds_read_b128 v[164:167], v205 offset:41472
	ds_read_b128 v[234:237], v204
	ds_read_b128 v[238:241], v204 offset:4608
	s_setprio 1
	s_waitcnt lgkmcnt(1)
	v_mfma_f32_32x32x16_bf16 v[112:127], v[234:237], v[160:163], v[112:127]
	v_mfma_f32_32x32x16_bf16 v[48:63], v[234:237], v[164:167], v[48:63]
	s_waitcnt lgkmcnt(0)
	v_mfma_f32_32x32x16_bf16 v[96:111], v[238:241], v[160:163], v[96:111]
	v_mfma_f32_32x32x16_bf16 v[32:47], v[238:241], v[164:167], v[32:47]
	ds_read_b128 v[234:237], v204 offset:9216
	ds_read_b128 v[238:241], v204 offset:13824
	s_waitcnt vmcnt(7)
	ds_write_b128 v212, v[218:221]
	s_waitcnt vmcnt(6)
	ds_write_b128 v211, v[222:225]
	ds_read_b128 v[218:221], v205 offset:36896
	ds_read_b128 v[222:225], v205 offset:41504
	s_waitcnt lgkmcnt(5)
	v_mfma_f32_32x32x16_bf16 v[80:95], v[234:237], v[160:163], v[80:95]
	v_mfma_f32_32x32x16_bf16 v[16:31], v[234:237], v[164:167], v[16:31]
	ds_read_b128 v[234:237], v204 offset:32
	s_waitcnt lgkmcnt(5)
	v_mfma_f32_32x32x16_bf16 v[64:79], v[238:241], v[160:163], v[64:79]
	v_mfma_f32_32x32x16_bf16 v[0:15], v[238:241], v[164:167], v[0:15]
	ds_read_b128 v[238:241], v204 offset:4640
	s_setprio 0
	global_load_dwordx4 v[160:163], v[194:195], off offset:512
	global_load_dwordx4 v[164:167], v[196:197], off offset:512
	s_setprio 1
	s_waitcnt lgkmcnt(1)
	v_mfma_f32_32x32x16_bf16 v[112:127], v[234:237], v[218:221], v[112:127]
	v_mfma_f32_32x32x16_bf16 v[48:63], v[234:237], v[222:225], v[48:63]
	s_waitcnt lgkmcnt(0)
	v_mfma_f32_32x32x16_bf16 v[96:111], v[238:241], v[218:221], v[96:111]
	v_mfma_f32_32x32x16_bf16 v[32:47], v[238:241], v[222:225], v[32:47]
	ds_read_b128 v[234:237], v204 offset:9248
	ds_read_b128 v[238:241], v204 offset:13856
	s_waitcnt vmcnt(7)
	ds_write_b128 v214, v[226:229]
	s_waitcnt vmcnt(6)
	ds_write_b128 v213, v[230:233]
	ds_read_b128 v[226:229], v205 offset:36928
	ds_read_b128 v[230:233], v205 offset:41536
	s_waitcnt lgkmcnt(5)
	v_mfma_f32_32x32x16_bf16 v[80:95], v[234:237], v[218:221], v[80:95]
	v_mfma_f32_32x32x16_bf16 v[16:31], v[234:237], v[222:225], v[16:31]
	ds_read_b128 v[234:237], v204 offset:64
	s_waitcnt lgkmcnt(5)
	v_mfma_f32_32x32x16_bf16 v[64:79], v[238:241], v[218:221], v[64:79]
	v_mfma_f32_32x32x16_bf16 v[0:15], v[238:241], v[222:225], v[0:15]
	ds_read_b128 v[238:241], v204 offset:4672
	s_setprio 0
	global_load_dwordx4 v[218:221], v[184:185], off offset:512
	global_load_dwordx4 v[222:225], v[186:187], off offset:512
	s_setprio 1
	s_waitcnt lgkmcnt(1)
	v_mfma_f32_32x32x16_bf16 v[112:127], v[234:237], v[226:229], v[112:127]
	v_mfma_f32_32x32x16_bf16 v[48:63], v[234:237], v[230:233], v[48:63]
	s_waitcnt lgkmcnt(0)
	v_mfma_f32_32x32x16_bf16 v[96:111], v[238:241], v[226:229], v[96:111]
	v_mfma_f32_32x32x16_bf16 v[32:47], v[238:241], v[230:233], v[32:47]
	ds_read_b128 v[234:237], v204 offset:9280
	ds_read_b128 v[238:241], v204 offset:13888
	s_waitcnt vmcnt(7)
	ds_write_b128 v217, v[176:179]
	s_waitcnt vmcnt(6)
	ds_write_b128 v216, v[180:183]
	ds_read_b128 v[176:179], v205 offset:36960
	ds_read_b128 v[180:183], v205 offset:41568
	s_waitcnt lgkmcnt(5)
	v_mfma_f32_32x32x16_bf16 v[80:95], v[234:237], v[226:229], v[80:95]
	v_mfma_f32_32x32x16_bf16 v[16:31], v[234:237], v[230:233], v[16:31]
	ds_read_b128 v[234:237], v204 offset:96
	s_waitcnt lgkmcnt(5)
	v_mfma_f32_32x32x16_bf16 v[64:79], v[238:241], v[226:229], v[64:79]
	v_mfma_f32_32x32x16_bf16 v[0:15], v[238:241], v[230:233], v[0:15]
	ds_read_b128 v[238:241], v204 offset:4704
	s_setprio 0
	global_load_dwordx4 v[226:229], v[198:199], off offset:512
	global_load_dwordx4 v[230:233], v[200:201], off offset:512
	s_setprio 1
	s_waitcnt lgkmcnt(1)
	v_mfma_f32_32x32x16_bf16 v[112:127], v[234:237], v[176:179], v[112:127]
	v_mfma_f32_32x32x16_bf16 v[48:63], v[234:237], v[180:183], v[48:63]
	s_waitcnt lgkmcnt(0)
	v_mfma_f32_32x32x16_bf16 v[96:111], v[238:241], v[176:179], v[96:111]
	v_mfma_f32_32x32x16_bf16 v[32:47], v[238:241], v[180:183], v[32:47]
	ds_read_b128 v[234:237], v204 offset:9312
	ds_read_b128 v[238:241], v204 offset:13920
	s_waitcnt lgkmcnt(0)
	s_barrier
	s_waitcnt vmcnt(7)
	ds_write_b128 v215, v[168:171]
	s_waitcnt vmcnt(6)
	ds_write_b128 v215, v[172:175] offset:36864
	ds_read_b128 v[168:171], v208
	ds_read_b128 v[172:175], v208 offset:4608
	v_mfma_f32_32x32x16_bf16 v[80:95], v[234:237], v[176:179], v[80:95]
	v_mfma_f32_32x32x16_bf16 v[16:31], v[234:237], v[180:183], v[16:31]
	ds_read_b128 v[234:237], v192
	v_mfma_f32_32x32x16_bf16 v[64:79], v[238:241], v[176:179], v[64:79]
	v_mfma_f32_32x32x16_bf16 v[0:15], v[238:241], v[180:183], v[0:15]
	ds_read_b128 v[238:241], v192 offset:4608
	s_setprio 0
	global_load_dwordx4 v[176:179], v[190:191], off offset:640
	global_load_dwordx4 v[180:183], v[188:189], off offset:640
	s_setprio 1
	s_waitcnt lgkmcnt(1)
	v_mfma_f32_32x32x16_bf16 v[112:127], v[234:237], v[168:171], v[112:127]
	v_mfma_f32_32x32x16_bf16 v[48:63], v[234:237], v[172:175], v[48:63]
	s_waitcnt lgkmcnt(0)
	v_mfma_f32_32x32x16_bf16 v[96:111], v[238:241], v[168:171], v[96:111]
	v_mfma_f32_32x32x16_bf16 v[32:47], v[238:241], v[172:175], v[32:47]
	ds_read_b128 v[234:237], v192 offset:9216
	ds_read_b128 v[238:241], v192 offset:13824
	s_waitcnt vmcnt(7)
	ds_write_b128 v215, v[160:163] offset:9216
	s_waitcnt vmcnt(6)
	ds_write_b128 v215, v[164:167] offset:46080
	ds_read_b128 v[160:163], v208 offset:32
	ds_read_b128 v[164:167], v208 offset:4640
	s_waitcnt lgkmcnt(5)
	v_mfma_f32_32x32x16_bf16 v[80:95], v[234:237], v[168:171], v[80:95]
	v_mfma_f32_32x32x16_bf16 v[16:31], v[234:237], v[172:175], v[16:31]
	ds_read_b128 v[234:237], v192 offset:32
	s_waitcnt lgkmcnt(5)
; template <bool trans>
; DI void gemm_core(const GTile& tl, const GTile& nx, bool has_next  , bool chain  , bool pre, u32x4 (&ra)[4], u32x4 (&rb)[4], char* smem, f32x16 (&acc)[2][4]) {
;     ...
;   const int nk = K / 64;
;   if (!pre) { G_LOAD(0); G_STORE(0); G_LOAD(1); }
;   for (int kt = 0; kt < nk; ++kt) {
;     __syncthreads();
;     G_COMPUTE(kt & 1, kt);
;   }
	v_mfma_f32_32x32x16_bf16 v[64:79], v[238:241], v[168:171], v[64:79]
	v_mfma_f32_32x32x16_bf16 v[0:15], v[238:241], v[172:175], v[0:15]
	ds_read_b128 v[238:241], v192 offset:4640
	s_setprio 0
	global_load_dwordx4 v[168:171], v[194:195], off offset:640
	global_load_dwordx4 v[172:175], v[196:197], off offset:640
	s_setprio 1
	s_waitcnt lgkmcnt(1)
	v_mfma_f32_32x32x16_bf16 v[112:127], v[234:237], v[160:163], v[112:127]
	v_mfma_f32_32x32x16_bf16 v[48:63], v[234:237], v[164:167], v[48:63]
	s_waitcnt lgkmcnt(0)
	v_mfma_f32_32x32x16_bf16 v[96:111], v[238:241], v[160:163], v[96:111]
	v_mfma_f32_32x32x16_bf16 v[32:47], v[238:241], v[164:167], v[32:47]
	ds_read_b128 v[234:237], v192 offset:9248
	ds_read_b128 v[238:241], v192 offset:13856
	s_waitcnt vmcnt(7)
	ds_write_b128 v215, v[218:221] offset:18432
	s_waitcnt vmcnt(6)
	ds_write_b128 v215, v[222:225] offset:55296
	ds_read_b128 v[218:221], v208 offset:64
	ds_read_b128 v[222:225], v208 offset:4672
	s_waitcnt lgkmcnt(5)
	v_mfma_f32_32x32x16_bf16 v[80:95], v[234:237], v[160:163], v[80:95]
	v_mfma_f32_32x32x16_bf16 v[16:31], v[234:237], v[164:167], v[16:31]
	ds_read_b128 v[234:237], v192 offset:64
	s_waitcnt lgkmcnt(5)
	v_mfma_f32_32x32x16_bf16 v[64:79], v[238:241], v[160:163], v[64:79]
	v_mfma_f32_32x32x16_bf16 v[0:15], v[238:241], v[164:167], v[0:15]
	ds_read_b128 v[238:241], v192 offset:4672
	s_setprio 0
	global_load_dwordx4 v[160:163], v[184:185], off offset:640
	global_load_dwordx4 v[164:167], v[186:187], off offset:640
	s_setprio 1
	s_waitcnt lgkmcnt(1)
	v_mfma_f32_32x32x16_bf16 v[112:127], v[234:237], v[218:221], v[112:127]
	v_mfma_f32_32x32x16_bf16 v[48:63], v[234:237], v[222:225], v[48:63]
	s_waitcnt lgkmcnt(0)
	v_mfma_f32_32x32x16_bf16 v[96:111], v[238:241], v[218:221], v[96:111]
	v_mfma_f32_32x32x16_bf16 v[32:47], v[238:241], v[222:225], v[32:47]
	ds_read_b128 v[234:237], v192 offset:9280
	ds_read_b128 v[238:241], v192 offset:13888
	s_waitcnt vmcnt(7)
	ds_write_b128 v215, v[226:229] offset:27648
	s_waitcnt vmcnt(6)
	ds_write_b128 v215, v[230:233] offset:64512
	ds_read_b128 v[226:229], v208 offset:96
	ds_read_b128 v[230:233], v208 offset:4704
	s_waitcnt lgkmcnt(5)
	v_mfma_f32_32x32x16_bf16 v[80:95], v[234:237], v[218:221], v[80:95]
	v_mfma_f32_32x32x16_bf16 v[16:31], v[234:237], v[222:225], v[16:31]
	ds_read_b128 v[234:237], v192 offset:96
	s_waitcnt lgkmcnt(5)
	v_mfma_f32_32x32x16_bf16 v[64:79], v[238:241], v[218:221], v[64:79]
	v_mfma_f32_32x32x16_bf16 v[0:15], v[238:241], v[222:225], v[0:15]
	ds_read_b128 v[238:241], v192 offset:4704
	s_setprio 0
	global_load_dwordx4 v[218:221], v[198:199], off offset:640
	global_load_dwordx4 v[222:225], v[200:201], off offset:640
	s_setprio 1
	s_waitcnt lgkmcnt(1)
	v_mfma_f32_32x32x16_bf16 v[112:127], v[234:237], v[226:229], v[112:127]
	v_mfma_f32_32x32x16_bf16 v[48:63], v[234:237], v[230:233], v[48:63]
	s_waitcnt lgkmcnt(0)
	v_mfma_f32_32x32x16_bf16 v[96:111], v[238:241], v[226:229], v[96:111]
	v_mfma_f32_32x32x16_bf16 v[32:47], v[238:241], v[230:233], v[32:47]
	ds_read_b128 v[234:237], v192 offset:9312
	ds_read_b128 v[238:241], v192 offset:13920
	s_waitcnt lgkmcnt(0)
	s_barrier
	s_waitcnt vmcnt(7)
	ds_write_b128 v209, v[176:179]
	s_waitcnt vmcnt(6)
	ds_write_b128 v210, v[180:183]
	ds_read_b128 v[176:179], v205 offset:36864
	ds_read_b128 v[180:183], v205 offset:41472
	v_mfma_f32_32x32x16_bf16 v[80:95], v[234:237], v[226:229], v[80:95]
	v_mfma_f32_32x32x16_bf16 v[16:31], v[234:237], v[230:233], v[16:31]
	ds_read_b128 v[234:237], v204
	v_mfma_f32_32x32x16_bf16 v[64:79], v[238:241], v[226:229], v[64:79]
	v_mfma_f32_32x32x16_bf16 v[0:15], v[238:241], v[230:233], v[0:15]
	ds_read_b128 v[238:241], v204 offset:4608
	s_setprio 0
	global_load_dwordx4 v[226:229], v[190:191], off offset:768
	global_load_dwordx4 v[230:233], v[188:189], off offset:768
	s_setprio 1
	s_waitcnt lgkmcnt(1)
	v_mfma_f32_32x32x16_bf16 v[112:127], v[234:237], v[176:179], v[112:127]
	v_mfma_f32_32x32x16_bf16 v[48:63], v[234:237], v[180:183], v[48:63]
	s_waitcnt lgkmcnt(0)
	v_mfma_f32_32x32x16_bf16 v[96:111], v[238:241], v[176:179], v[96:111]
	v_mfma_f32_32x32x16_bf16 v[32:47], v[238:241], v[180:183], v[32:47]
	ds_read_b128 v[234:237], v204 offset:9216
	ds_read_b128 v[238:241], v204 offset:13824
	s_waitcnt vmcnt(7)
	ds_write_b128 v212, v[168:171]
	s_waitcnt vmcnt(6)
	ds_write_b128 v211, v[172:175]
	ds_read_b128 v[168:171], v205 offset:36896
	ds_read_b128 v[172:175], v205 offset:41504
	s_waitcnt lgkmcnt(5)
	v_mfma_f32_32x32x16_bf16 v[80:95], v[234:237], v[176:179], v[80:95]
	v_mfma_f32_32x32x16_bf16 v[16:31], v[234:237], v[180:183], v[16:31]
	ds_read_b128 v[234:237], v204 offset:32
	s_waitcnt lgkmcnt(5)
	v_mfma_f32_32x32x16_bf16 v[64:79], v[238:241], v[176:179], v[64:79]
	v_mfma_f32_32x32x16_bf16 v[0:15], v[238:241], v[180:183], v[0:15]
	ds_read_b128 v[238:241], v204 offset:4640
	s_setprio 0
	global_load_dwordx4 v[176:179], v[194:195], off offset:768
	global_load_dwordx4 v[180:183], v[196:197], off offset:768
	s_setprio 1
	s_waitcnt lgkmcnt(1)
	v_mfma_f32_32x32x16_bf16 v[112:127], v[234:237], v[168:171], v[112:127]
	v_mfma_f32_32x32x16_bf16 v[48:63], v[234:237], v[172:175], v[48:63]
	s_waitcnt lgkmcnt(0)
	v_mfma_f32_32x32x16_bf16 v[96:111], v[238:241], v[168:171], v[96:111]
	v_mfma_f32_32x32x16_bf16 v[32:47], v[238:241], v[172:175], v[32:47]
	ds_read_b128 v[234:237], v204 offset:9248
	ds_read_b128 v[238:241], v204 offset:13856
	s_waitcnt vmcnt(7)
	ds_write_b128 v214, v[160:163]
	s_waitcnt vmcnt(6)
	ds_write_b128 v213, v[164:167]
	ds_read_b128 v[160:163], v205 offset:36928
	ds_read_b128 v[164:167], v205 offset:41536
	s_waitcnt lgkmcnt(5)
; template <bool trans>
; DI void gemm_core(const GTile& tl, const GTile& nx, bool has_next  , bool chain  , bool pre, u32x4 (&ra)[4], u32x4 (&rb)[4], char* smem, f32x16 (&acc)[2][4]) {
;     ...
;   const int nk = K / 64;
;   if (!pre) { G_LOAD(0); G_STORE(0); G_LOAD(1); }
;   for (int kt = 0; kt < nk; ++kt) {
;     __syncthreads();
;     G_COMPUTE(kt & 1, kt);
;   }
	v_mfma_f32_32x32x16_bf16 v[80:95], v[234:237], v[168:171], v[80:95]
	v_mfma_f32_32x32x16_bf16 v[16:31], v[234:237], v[172:175], v[16:31]
	ds_read_b128 v[234:237], v204 offset:64
	s_waitcnt lgkmcnt(5)
	v_mfma_f32_32x32x16_bf16 v[64:79], v[238:241], v[168:171], v[64:79]
	v_mfma_f32_32x32x16_bf16 v[0:15], v[238:241], v[172:175], v[0:15]
	ds_read_b128 v[238:241], v204 offset:4672
	s_setprio 0
	global_load_dwordx4 v[168:171], v[184:185], off offset:768
	global_load_dwordx4 v[172:175], v[186:187], off offset:768
	s_setprio 1
	s_waitcnt lgkmcnt(1)
	v_mfma_f32_32x32x16_bf16 v[112:127], v[234:237], v[160:163], v[112:127]
	v_mfma_f32_32x32x16_bf16 v[48:63], v[234:237], v[164:167], v[48:63]
	s_waitcnt lgkmcnt(0)
	v_mfma_f32_32x32x16_bf16 v[96:111], v[238:241], v[160:163], v[96:111]
	v_mfma_f32_32x32x16_bf16 v[32:47], v[238:241], v[164:167], v[32:47]
	ds_read_b128 v[234:237], v204 offset:9280
	ds_read_b128 v[238:241], v204 offset:13888
	s_waitcnt vmcnt(7)
	ds_write_b128 v217, v[218:221]
	s_waitcnt vmcnt(6)
	ds_write_b128 v216, v[222:225]
	ds_read_b128 v[218:221], v205 offset:36960
	ds_read_b128 v[222:225], v205 offset:41568
	s_waitcnt lgkmcnt(5)
	v_mfma_f32_32x32x16_bf16 v[80:95], v[234:237], v[160:163], v[80:95]
	v_mfma_f32_32x32x16_bf16 v[16:31], v[234:237], v[164:167], v[16:31]
	ds_read_b128 v[234:237], v204 offset:96
	s_waitcnt lgkmcnt(5)
	v_mfma_f32_32x32x16_bf16 v[64:79], v[238:241], v[160:163], v[64:79]
	v_mfma_f32_32x32x16_bf16 v[0:15], v[238:241], v[164:167], v[0:15]
	ds_read_b128 v[238:241], v204 offset:4704
	s_setprio 0
	global_load_dwordx4 v[160:163], v[198:199], off offset:768
	global_load_dwordx4 v[164:167], v[200:201], off offset:768
	s_setprio 1
	s_waitcnt lgkmcnt(1)
	v_mfma_f32_32x32x16_bf16 v[112:127], v[234:237], v[218:221], v[112:127]
	v_mfma_f32_32x32x16_bf16 v[48:63], v[234:237], v[222:225], v[48:63]
	s_waitcnt lgkmcnt(0)
	v_mfma_f32_32x32x16_bf16 v[96:111], v[238:241], v[218:221], v[96:111]
	v_mfma_f32_32x32x16_bf16 v[32:47], v[238:241], v[222:225], v[32:47]
	ds_read_b128 v[234:237], v204 offset:9312
	ds_read_b128 v[238:241], v204 offset:13920
	s_waitcnt lgkmcnt(0)
	s_barrier
	s_waitcnt vmcnt(7)
	ds_write_b128 v215, v[226:229]
	s_waitcnt vmcnt(6)
	ds_write_b128 v215, v[230:233] offset:36864
	ds_read_b128 v[226:229], v208
	ds_read_b128 v[230:233], v208 offset:4608
	v_mfma_f32_32x32x16_bf16 v[80:95], v[234:237], v[218:221], v[80:95]
	v_mfma_f32_32x32x16_bf16 v[16:31], v[234:237], v[222:225], v[16:31]
	ds_read_b128 v[234:237], v192
	v_mfma_f32_32x32x16_bf16 v[64:79], v[238:241], v[218:221], v[64:79]
	v_mfma_f32_32x32x16_bf16 v[0:15], v[238:241], v[222:225], v[0:15]
	ds_read_b128 v[238:241], v192 offset:4608
	s_setprio 0
	global_load_dwordx4 v[218:221], v[190:191], off offset:896
	global_load_dwordx4 v[222:225], v[188:189], off offset:896
	s_setprio 1
	s_waitcnt lgkmcnt(1)
	v_mfma_f32_32x32x16_bf16 v[112:127], v[234:237], v[226:229], v[112:127]
	v_mfma_f32_32x32x16_bf16 v[48:63], v[234:237], v[230:233], v[48:63]
	s_waitcnt lgkmcnt(0)
	v_mfma_f32_32x32x16_bf16 v[96:111], v[238:241], v[226:229], v[96:111]
	v_mfma_f32_32x32x16_bf16 v[32:47], v[238:241], v[230:233], v[32:47]
	ds_read_b128 v[234:237], v192 offset:9216
	ds_read_b128 v[238:241], v192 offset:13824
	s_waitcnt vmcnt(7)
	ds_write_b128 v215, v[176:179] offset:9216
	s_waitcnt vmcnt(6)
	ds_write_b128 v215, v[180:183] offset:46080
	ds_read_b128 v[176:179], v208 offset:32
	ds_read_b128 v[180:183], v208 offset:4640
	s_waitcnt lgkmcnt(5)
	v_mfma_f32_32x32x16_bf16 v[80:95], v[234:237], v[226:229], v[80:95]
	v_mfma_f32_32x32x16_bf16 v[16:31], v[234:237], v[230:233], v[16:31]
	ds_read_b128 v[234:237], v192 offset:32
	s_waitcnt lgkmcnt(5)
	v_mfma_f32_32x32x16_bf16 v[64:79], v[238:241], v[226:229], v[64:79]
	v_mfma_f32_32x32x16_bf16 v[0:15], v[238:241], v[230:233], v[0:15]
	ds_read_b128 v[238:241], v192 offset:4640
	s_setprio 0
	global_load_dwordx4 v[226:229], v[194:195], off offset:896
	global_load_dwordx4 v[230:233], v[196:197], off offset:896
	s_setprio 1
	s_waitcnt lgkmcnt(1)
	v_mfma_f32_32x32x16_bf16 v[112:127], v[234:237], v[176:179], v[112:127]
	v_mfma_f32_32x32x16_bf16 v[48:63], v[234:237], v[180:183], v[48:63]
	s_waitcnt lgkmcnt(0)
	v_mfma_f32_32x32x16_bf16 v[96:111], v[238:241], v[176:179], v[96:111]
	v_mfma_f32_32x32x16_bf16 v[32:47], v[238:241], v[180:183], v[32:47]
	ds_read_b128 v[234:237], v192 offset:9248
	ds_read_b128 v[238:241], v192 offset:13856
	s_waitcnt vmcnt(7)
	ds_write_b128 v215, v[168:171] offset:18432
	s_waitcnt vmcnt(6)
	ds_write_b128 v215, v[172:175] offset:55296
	ds_read_b128 v[168:171], v208 offset:64
	ds_read_b128 v[172:175], v208 offset:4672
	s_waitcnt lgkmcnt(5)
	v_mfma_f32_32x32x16_bf16 v[80:95], v[234:237], v[176:179], v[80:95]
	v_mfma_f32_32x32x16_bf16 v[16:31], v[234:237], v[180:183], v[16:31]
	ds_read_b128 v[234:237], v192 offset:64
	s_waitcnt lgkmcnt(5)
	v_mfma_f32_32x32x16_bf16 v[64:79], v[238:241], v[176:179], v[64:79]
	v_mfma_f32_32x32x16_bf16 v[0:15], v[238:241], v[180:183], v[0:15]
	ds_read_b128 v[238:241], v192 offset:4672
	s_setprio 0
	global_load_dwordx4 v[176:179], v[184:185], off offset:896
	global_load_dwordx4 v[180:183], v[186:187], off offset:896
	s_setprio 1
	s_waitcnt lgkmcnt(1)
	v_mfma_f32_32x32x16_bf16 v[112:127], v[234:237], v[168:171], v[112:127]
	v_mfma_f32_32x32x16_bf16 v[48:63], v[234:237], v[172:175], v[48:63]
	s_waitcnt lgkmcnt(0)
	v_mfma_f32_32x32x16_bf16 v[96:111], v[238:241], v[168:171], v[96:111]
	v_mfma_f32_32x32x16_bf16 v[32:47], v[238:241], v[172:175], v[32:47]
	ds_read_b128 v[234:237], v192 offset:9280
	ds_read_b128 v[238:241], v192 offset:13888
	s_waitcnt vmcnt(7)
	ds_write_b128 v215, v[160:163] offset:27648
	s_waitcnt vmcnt(6)
	ds_write_b128 v215, v[164:167] offset:64512
	ds_read_b128 v[160:163], v208 offset:96
	ds_read_b128 v[164:167], v208 offset:4704
	s_waitcnt lgkmcnt(5)
	v_mfma_f32_32x32x16_bf16 v[80:95], v[234:237], v[168:171], v[80:95]
	v_mfma_f32_32x32x16_bf16 v[16:31], v[234:237], v[172:175], v[16:31]
	ds_read_b128 v[234:237], v192 offset:96
	s_waitcnt lgkmcnt(5)
	v_mfma_f32_32x32x16_bf16 v[64:79], v[238:241], v[168:171], v[64:79]
	v_mfma_f32_32x32x16_bf16 v[0:15], v[238:241], v[172:175], v[0:15]
	ds_read_b128 v[238:241], v192 offset:4704
	s_setprio 0
	global_load_dwordx4 v[168:171], v[198:199], off offset:896
	global_load_dwordx4 v[172:175], v[200:201], off offset:896
	s_setprio 1
	s_waitcnt lgkmcnt(1)
	v_mfma_f32_32x32x16_bf16 v[112:127], v[234:237], v[160:163], v[112:127]
	v_mfma_f32_32x32x16_bf16 v[48:63], v[234:237], v[164:167], v[48:63]
	s_waitcnt lgkmcnt(0)
	v_mfma_f32_32x32x16_bf16 v[96:111], v[238:241], v[160:163], v[96:111]
	v_mfma_f32_32x32x16_bf16 v[32:47], v[238:241], v[164:167], v[32:47]
	ds_read_b128 v[234:237], v192 offset:9312
	ds_read_b128 v[238:241], v192 offset:13920
	s_waitcnt lgkmcnt(0)
	s_barrier
; template <bool trans>
; DI void gemm_core(const GTile& tl, const GTile& nx, bool has_next  , bool chain  , bool pre, u32x4 (&ra)[4], u32x4 (&rb)[4], char* smem, f32x16 (&acc)[2][4]) {
;     ...
;   const int nk = K / 64;
;   if (!pre) { G_LOAD(0); G_STORE(0); G_LOAD(1); }
;   for (int kt = 0; kt < nk; ++kt) {
;     __syncthreads();
;     G_COMPUTE(kt & 1, kt);
;   }
	s_waitcnt vmcnt(7)
	ds_write_b128 v209, v[218:221]
	s_waitcnt vmcnt(6)
	ds_write_b128 v210, v[222:225]
	ds_read_b128 v[218:221], v205 offset:36864
	ds_read_b128 v[222:225], v205 offset:41472
	v_mfma_f32_32x32x16_bf16 v[80:95], v[234:237], v[160:163], v[80:95]
	v_mfma_f32_32x32x16_bf16 v[16:31], v[234:237], v[164:167], v[16:31]
	ds_read_b128 v[234:237], v204
	v_mfma_f32_32x32x16_bf16 v[64:79], v[238:241], v[160:163], v[64:79]
	v_mfma_f32_32x32x16_bf16 v[0:15], v[238:241], v[164:167], v[0:15]
	ds_read_b128 v[238:241], v204 offset:4608
	s_setprio 0
	global_load_dwordx4 v[160:163], v[190:191], off offset:1024
	global_load_dwordx4 v[164:167], v[188:189], off offset:1024
	s_setprio 1
	s_waitcnt lgkmcnt(1)
	v_mfma_f32_32x32x16_bf16 v[112:127], v[234:237], v[218:221], v[112:127]
	v_mfma_f32_32x32x16_bf16 v[48:63], v[234:237], v[222:225], v[48:63]
	s_waitcnt lgkmcnt(0)
	v_mfma_f32_32x32x16_bf16 v[96:111], v[238:241], v[218:221], v[96:111]
	v_mfma_f32_32x32x16_bf16 v[32:47], v[238:241], v[222:225], v[32:47]
	ds_read_b128 v[234:237], v204 offset:9216
	ds_read_b128 v[238:241], v204 offset:13824
	s_waitcnt vmcnt(7)
	ds_write_b128 v212, v[226:229]
	s_waitcnt vmcnt(6)
	ds_write_b128 v211, v[230:233]
	ds_read_b128 v[226:229], v205 offset:36896
	ds_read_b128 v[230:233], v205 offset:41504
	s_waitcnt lgkmcnt(5)
	v_mfma_f32_32x32x16_bf16 v[80:95], v[234:237], v[218:221], v[80:95]
	v_mfma_f32_32x32x16_bf16 v[16:31], v[234:237], v[222:225], v[16:31]
	ds_read_b128 v[234:237], v204 offset:32
	s_waitcnt lgkmcnt(5)
	v_mfma_f32_32x32x16_bf16 v[64:79], v[238:241], v[218:221], v[64:79]
	v_mfma_f32_32x32x16_bf16 v[0:15], v[238:241], v[222:225], v[0:15]
	ds_read_b128 v[238:241], v204 offset:4640
	s_setprio 0
	global_load_dwordx4 v[218:221], v[194:195], off offset:1024
	global_load_dwordx4 v[222:225], v[196:197], off offset:1024
	s_setprio 1
	s_waitcnt lgkmcnt(1)
	v_mfma_f32_32x32x16_bf16 v[112:127], v[234:237], v[226:229], v[112:127]
	v_mfma_f32_32x32x16_bf16 v[48:63], v[234:237], v[230:233], v[48:63]
	s_waitcnt lgkmcnt(0)
	v_mfma_f32_32x32x16_bf16 v[96:111], v[238:241], v[226:229], v[96:111]
	v_mfma_f32_32x32x16_bf16 v[32:47], v[238:241], v[230:233], v[32:47]
	ds_read_b128 v[234:237], v204 offset:9248
	ds_read_b128 v[238:241], v204 offset:13856
	s_waitcnt vmcnt(7)
	ds_write_b128 v214, v[176:179]
	s_waitcnt vmcnt(6)
	ds_write_b128 v213, v[180:183]
	ds_read_b128 v[176:179], v205 offset:36928
	ds_read_b128 v[180:183], v205 offset:41536
	s_waitcnt lgkmcnt(5)
	v_mfma_f32_32x32x16_bf16 v[80:95], v[234:237], v[226:229], v[80:95]
	v_mfma_f32_32x32x16_bf16 v[16:31], v[234:237], v[230:233], v[16:31]
	ds_read_b128 v[234:237], v204 offset:64
	s_waitcnt lgkmcnt(5)
	v_mfma_f32_32x32x16_bf16 v[64:79], v[238:241], v[226:229], v[64:79]
	v_mfma_f32_32x32x16_bf16 v[0:15], v[238:241], v[230:233], v[0:15]
	ds_read_b128 v[238:241], v204 offset:4672
	s_setprio 0
	global_load_dwordx4 v[226:229], v[184:185], off offset:1024
	global_load_dwordx4 v[230:233], v[186:187], off offset:1024
	s_setprio 1
	s_waitcnt lgkmcnt(1)
	v_mfma_f32_32x32x16_bf16 v[112:127], v[234:237], v[176:179], v[112:127]
	v_mfma_f32_32x32x16_bf16 v[48:63], v[234:237], v[180:183], v[48:63]
	s_waitcnt lgkmcnt(0)
	v_mfma_f32_32x32x16_bf16 v[96:111], v[238:241], v[176:179], v[96:111]
	v_mfma_f32_32x32x16_bf16 v[32:47], v[238:241], v[180:183], v[32:47]
	ds_read_b128 v[234:237], v204 offset:9280
	ds_read_b128 v[238:241], v204 offset:13888
	s_waitcnt vmcnt(7)
	ds_write_b128 v217, v[168:171]
	s_waitcnt vmcnt(6)
	ds_write_b128 v216, v[172:175]
	ds_read_b128 v[168:171], v205 offset:36960
	ds_read_b128 v[172:175], v205 offset:41568
	s_waitcnt lgkmcnt(5)
	v_mfma_f32_32x32x16_bf16 v[80:95], v[234:237], v[176:179], v[80:95]
	v_mfma_f32_32x32x16_bf16 v[16:31], v[234:237], v[180:183], v[16:31]
	ds_read_b128 v[234:237], v204 offset:96
	s_waitcnt lgkmcnt(5)
	v_mfma_f32_32x32x16_bf16 v[64:79], v[238:241], v[176:179], v[64:79]
	v_mfma_f32_32x32x16_bf16 v[0:15], v[238:241], v[180:183], v[0:15]
	ds_read_b128 v[238:241], v204 offset:4704
	s_setprio 0
	global_load_dwordx4 v[176:179], v[198:199], off offset:1024
	global_load_dwordx4 v[180:183], v[200:201], off offset:1024
	s_setprio 1
	s_waitcnt lgkmcnt(1)
	v_mfma_f32_32x32x16_bf16 v[112:127], v[234:237], v[168:171], v[112:127]
	v_mfma_f32_32x32x16_bf16 v[48:63], v[234:237], v[172:175], v[48:63]
	s_waitcnt lgkmcnt(0)
	v_mfma_f32_32x32x16_bf16 v[96:111], v[238:241], v[168:171], v[96:111]
	v_mfma_f32_32x32x16_bf16 v[32:47], v[238:241], v[172:175], v[32:47]
	ds_read_b128 v[234:237], v204 offset:9312
	ds_read_b128 v[238:241], v204 offset:13920
	s_waitcnt lgkmcnt(0)
	s_barrier
; template <bool trans>
; DI void gemm_core(const GTile& tl, const GTile& nx, bool has_next  , bool chain  , bool pre, u32x4 (&ra)[4], u32x4 (&rb)[4], char* smem, f32x16 (&acc)[2][4]) {
;     ...
;   const int nk = K / 64;
;   if (!pre) { G_LOAD(0); G_STORE(0); G_LOAD(1); }
;   for (int kt = 0; kt < nk; ++kt) {
;     __syncthreads();
;     G_COMPUTE(kt & 1, kt);
;   }
	s_waitcnt vmcnt(7)
	ds_write_b128 v215, v[160:163]
	s_waitcnt vmcnt(6)
	ds_write_b128 v215, v[164:167] offset:36864
	ds_read_b128 v[160:163], v208
	ds_read_b128 v[164:167], v208 offset:4608
	v_mfma_f32_32x32x16_bf16 v[80:95], v[234:237], v[168:171], v[80:95]
	v_mfma_f32_32x32x16_bf16 v[16:31], v[234:237], v[172:175], v[16:31]
	ds_read_b128 v[234:237], v192
	v_mfma_f32_32x32x16_bf16 v[64:79], v[238:241], v[168:171], v[64:79]
	v_mfma_f32_32x32x16_bf16 v[0:15], v[238:241], v[172:175], v[0:15]
	ds_read_b128 v[238:241], v192 offset:4608
	s_setprio 0
	global_load_dwordx4 v[168:171], v[190:191], off offset:1152
	global_load_dwordx4 v[172:175], v[188:189], off offset:1152
	s_setprio 1
	s_waitcnt lgkmcnt(1)
	v_mfma_f32_32x32x16_bf16 v[112:127], v[234:237], v[160:163], v[112:127]
	v_mfma_f32_32x32x16_bf16 v[48:63], v[234:237], v[164:167], v[48:63]
	s_waitcnt lgkmcnt(0)
	v_mfma_f32_32x32x16_bf16 v[96:111], v[238:241], v[160:163], v[96:111]
	v_mfma_f32_32x32x16_bf16 v[32:47], v[238:241], v[164:167], v[32:47]
	ds_read_b128 v[234:237], v192 offset:9216
	ds_read_b128 v[238:241], v192 offset:13824
	s_waitcnt vmcnt(7)
	ds_write_b128 v215, v[218:221] offset:9216
	s_waitcnt vmcnt(6)
	ds_write_b128 v215, v[222:225] offset:46080
	ds_read_b128 v[218:221], v208 offset:32
	ds_read_b128 v[222:225], v208 offset:4640
	s_waitcnt lgkmcnt(5)
	v_mfma_f32_32x32x16_bf16 v[80:95], v[234:237], v[160:163], v[80:95]
	v_mfma_f32_32x32x16_bf16 v[16:31], v[234:237], v[164:167], v[16:31]
	ds_read_b128 v[234:237], v192 offset:32
	s_waitcnt lgkmcnt(5)
	v_mfma_f32_32x32x16_bf16 v[64:79], v[238:241], v[160:163], v[64:79]
	v_mfma_f32_32x32x16_bf16 v[0:15], v[238:241], v[164:167], v[0:15]
	ds_read_b128 v[238:241], v192 offset:4640
	s_setprio 0
	global_load_dwordx4 v[160:163], v[194:195], off offset:1152
	global_load_dwordx4 v[164:167], v[196:197], off offset:1152
	s_setprio 1
	s_waitcnt lgkmcnt(1)
	v_mfma_f32_32x32x16_bf16 v[112:127], v[234:237], v[218:221], v[112:127]
	v_mfma_f32_32x32x16_bf16 v[48:63], v[234:237], v[222:225], v[48:63]
	s_waitcnt lgkmcnt(0)
	v_mfma_f32_32x32x16_bf16 v[96:111], v[238:241], v[218:221], v[96:111]
	v_mfma_f32_32x32x16_bf16 v[32:47], v[238:241], v[222:225], v[32:47]
	ds_read_b128 v[234:237], v192 offset:9248
	ds_read_b128 v[238:241], v192 offset:13856
	s_waitcnt vmcnt(7)
	ds_write_b128 v215, v[226:229] offset:18432
	s_waitcnt vmcnt(6)
	ds_write_b128 v215, v[230:233] offset:55296
	ds_read_b128 v[226:229], v208 offset:64
	ds_read_b128 v[230:233], v208 offset:4672
	s_waitcnt lgkmcnt(5)
	v_mfma_f32_32x32x16_bf16 v[80:95], v[234:237], v[218:221], v[80:95]
	v_mfma_f32_32x32x16_bf16 v[16:31], v[234:237], v[222:225], v[16:31]
	ds_read_b128 v[234:237], v192 offset:64
	s_waitcnt lgkmcnt(5)
	v_mfma_f32_32x32x16_bf16 v[64:79], v[238:241], v[218:221], v[64:79]
	v_mfma_f32_32x32x16_bf16 v[0:15], v[238:241], v[222:225], v[0:15]
	ds_read_b128 v[238:241], v192 offset:4672
	s_setprio 0
	global_load_dwordx4 v[218:221], v[184:185], off offset:1152
	global_load_dwordx4 v[222:225], v[186:187], off offset:1152
	s_setprio 1
	s_waitcnt lgkmcnt(1)
	v_mfma_f32_32x32x16_bf16 v[112:127], v[234:237], v[226:229], v[112:127]
	v_mfma_f32_32x32x16_bf16 v[48:63], v[234:237], v[230:233], v[48:63]
	s_waitcnt lgkmcnt(0)
	v_mfma_f32_32x32x16_bf16 v[96:111], v[238:241], v[226:229], v[96:111]
	v_mfma_f32_32x32x16_bf16 v[32:47], v[238:241], v[230:233], v[32:47]
	ds_read_b128 v[234:237], v192 offset:9280
	ds_read_b128 v[238:241], v192 offset:13888
	s_waitcnt vmcnt(7)
	ds_write_b128 v215, v[176:179] offset:27648
	s_waitcnt vmcnt(6)
	ds_write_b128 v215, v[180:183] offset:64512
	ds_read_b128 v[176:179], v208 offset:96
	ds_read_b128 v[180:183], v208 offset:4704
	s_waitcnt lgkmcnt(5)
	v_mfma_f32_32x32x16_bf16 v[80:95], v[234:237], v[226:229], v[80:95]
	v_mfma_f32_32x32x16_bf16 v[16:31], v[234:237], v[230:233], v[16:31]
	ds_read_b128 v[234:237], v192 offset:96
	s_waitcnt lgkmcnt(5)
	v_mfma_f32_32x32x16_bf16 v[64:79], v[238:241], v[226:229], v[64:79]
	v_mfma_f32_32x32x16_bf16 v[0:15], v[238:241], v[230:233], v[0:15]
	ds_read_b128 v[238:241], v192 offset:4704
	s_setprio 0
	global_load_dwordx4 v[226:229], v[198:199], off offset:1152
	global_load_dwordx4 v[230:233], v[200:201], off offset:1152
	s_setprio 1
	s_waitcnt lgkmcnt(1)
	v_mfma_f32_32x32x16_bf16 v[112:127], v[234:237], v[176:179], v[112:127]
	v_mfma_f32_32x32x16_bf16 v[48:63], v[234:237], v[180:183], v[48:63]
	s_waitcnt lgkmcnt(0)
	v_mfma_f32_32x32x16_bf16 v[96:111], v[238:241], v[176:179], v[96:111]
	v_mfma_f32_32x32x16_bf16 v[32:47], v[238:241], v[180:183], v[32:47]
	ds_read_b128 v[234:237], v192 offset:9312
	ds_read_b128 v[238:241], v192 offset:13920
	s_waitcnt lgkmcnt(0)
	s_barrier
; template <bool trans>
; DI void gemm_core(const GTile& tl, const GTile& nx, bool has_next  , bool chain  , bool pre, u32x4 (&ra)[4], u32x4 (&rb)[4], char* smem, f32x16 (&acc)[2][4]) {
;     ...
;   const int nk = K / 64;
;   if (!pre) { G_LOAD(0); G_STORE(0); G_LOAD(1); }
;   for (int kt = 0; kt < nk; ++kt) {
;     __syncthreads();
;     G_COMPUTE(kt & 1, kt);
;   }
	s_waitcnt vmcnt(7)
	ds_write_b128 v209, v[168:171]
	s_waitcnt vmcnt(6)
	ds_write_b128 v210, v[172:175]
	ds_read_b128 v[168:171], v205 offset:36864
	ds_read_b128 v[172:175], v205 offset:41472
	v_mfma_f32_32x32x16_bf16 v[80:95], v[234:237], v[176:179], v[80:95]
	v_mfma_f32_32x32x16_bf16 v[16:31], v[234:237], v[180:183], v[16:31]
	ds_read_b128 v[234:237], v204
	v_mfma_f32_32x32x16_bf16 v[64:79], v[238:241], v[176:179], v[64:79]
	v_mfma_f32_32x32x16_bf16 v[0:15], v[238:241], v[180:183], v[0:15]
	ds_read_b128 v[238:241], v204 offset:4608
	s_setprio 0
	global_load_dwordx4 v[176:179], v[190:191], off offset:1280
	global_load_dwordx4 v[180:183], v[188:189], off offset:1280
	s_setprio 1
	s_waitcnt lgkmcnt(1)
	v_mfma_f32_32x32x16_bf16 v[112:127], v[234:237], v[168:171], v[112:127]
	v_mfma_f32_32x32x16_bf16 v[48:63], v[234:237], v[172:175], v[48:63]
	s_waitcnt lgkmcnt(0)
	v_mfma_f32_32x32x16_bf16 v[96:111], v[238:241], v[168:171], v[96:111]
	v_mfma_f32_32x32x16_bf16 v[32:47], v[238:241], v[172:175], v[32:47]
	ds_read_b128 v[234:237], v204 offset:9216
	ds_read_b128 v[238:241], v204 offset:13824
	s_waitcnt vmcnt(7)
	ds_write_b128 v212, v[160:163]
	s_waitcnt vmcnt(6)
	ds_write_b128 v211, v[164:167]
	ds_read_b128 v[160:163], v205 offset:36896
	ds_read_b128 v[164:167], v205 offset:41504
	s_waitcnt lgkmcnt(5)
	v_mfma_f32_32x32x16_bf16 v[80:95], v[234:237], v[168:171], v[80:95]
	v_mfma_f32_32x32x16_bf16 v[16:31], v[234:237], v[172:175], v[16:31]
	ds_read_b128 v[234:237], v204 offset:32
	s_waitcnt lgkmcnt(5)
	v_mfma_f32_32x32x16_bf16 v[64:79], v[238:241], v[168:171], v[64:79]
	v_mfma_f32_32x32x16_bf16 v[0:15], v[238:241], v[172:175], v[0:15]
	ds_read_b128 v[238:241], v204 offset:4640
	s_setprio 0
	global_load_dwordx4 v[168:171], v[194:195], off offset:1280
	global_load_dwordx4 v[172:175], v[196:197], off offset:1280
	s_setprio 1
	s_waitcnt lgkmcnt(1)
	v_mfma_f32_32x32x16_bf16 v[112:127], v[234:237], v[160:163], v[112:127]
	v_mfma_f32_32x32x16_bf16 v[48:63], v[234:237], v[164:167], v[48:63]
	s_waitcnt lgkmcnt(0)
	v_mfma_f32_32x32x16_bf16 v[96:111], v[238:241], v[160:163], v[96:111]
	v_mfma_f32_32x32x16_bf16 v[32:47], v[238:241], v[164:167], v[32:47]
	ds_read_b128 v[234:237], v204 offset:9248
	ds_read_b128 v[238:241], v204 offset:13856
	s_waitcnt vmcnt(7)
	ds_write_b128 v214, v[218:221]
	s_waitcnt vmcnt(6)
	ds_write_b128 v213, v[222:225]
	ds_read_b128 v[218:221], v205 offset:36928
	ds_read_b128 v[222:225], v205 offset:41536
	s_waitcnt lgkmcnt(5)
	v_mfma_f32_32x32x16_bf16 v[80:95], v[234:237], v[160:163], v[80:95]
	v_mfma_f32_32x32x16_bf16 v[16:31], v[234:237], v[164:167], v[16:31]
	ds_read_b128 v[234:237], v204 offset:64
	s_waitcnt lgkmcnt(5)
	v_mfma_f32_32x32x16_bf16 v[64:79], v[238:241], v[160:163], v[64:79]
	v_mfma_f32_32x32x16_bf16 v[0:15], v[238:241], v[164:167], v[0:15]
	ds_read_b128 v[238:241], v204 offset:4672
	s_setprio 0
	global_load_dwordx4 v[160:163], v[184:185], off offset:1280
	global_load_dwordx4 v[164:167], v[186:187], off offset:1280
	s_setprio 1
	s_waitcnt lgkmcnt(1)
	v_mfma_f32_32x32x16_bf16 v[112:127], v[234:237], v[218:221], v[112:127]
	v_mfma_f32_32x32x16_bf16 v[48:63], v[234:237], v[222:225], v[48:63]
	s_waitcnt lgkmcnt(0)
	v_mfma_f32_32x32x16_bf16 v[96:111], v[238:241], v[218:221], v[96:111]
	v_mfma_f32_32x32x16_bf16 v[32:47], v[238:241], v[222:225], v[32:47]
	ds_read_b128 v[234:237], v204 offset:9280
	ds_read_b128 v[238:241], v204 offset:13888
	s_waitcnt vmcnt(7)
	ds_write_b128 v217, v[226:229]
	s_waitcnt vmcnt(6)
	ds_write_b128 v216, v[230:233]
	ds_read_b128 v[226:229], v205 offset:36960
	ds_read_b128 v[230:233], v205 offset:41568
	s_waitcnt lgkmcnt(5)
	v_mfma_f32_32x32x16_bf16 v[80:95], v[234:237], v[218:221], v[80:95]
	v_mfma_f32_32x32x16_bf16 v[16:31], v[234:237], v[222:225], v[16:31]
	ds_read_b128 v[234:237], v204 offset:96
	s_waitcnt lgkmcnt(5)
	v_mfma_f32_32x32x16_bf16 v[64:79], v[238:241], v[218:221], v[64:79]
	v_mfma_f32_32x32x16_bf16 v[0:15], v[238:241], v[222:225], v[0:15]
	ds_read_b128 v[238:241], v204 offset:4704
	s_setprio 0
	global_load_dwordx4 v[218:221], v[198:199], off offset:1280
	global_load_dwordx4 v[222:225], v[200:201], off offset:1280
	s_setprio 1
	s_waitcnt lgkmcnt(1)
	v_mfma_f32_32x32x16_bf16 v[112:127], v[234:237], v[226:229], v[112:127]
	v_mfma_f32_32x32x16_bf16 v[48:63], v[234:237], v[230:233], v[48:63]
	s_waitcnt lgkmcnt(0)
	v_mfma_f32_32x32x16_bf16 v[96:111], v[238:241], v[226:229], v[96:111]
	v_mfma_f32_32x32x16_bf16 v[32:47], v[238:241], v[230:233], v[32:47]
	ds_read_b128 v[234:237], v204 offset:9312
	ds_read_b128 v[238:241], v204 offset:13920
	s_waitcnt lgkmcnt(0)
	s_barrier
; template <bool trans>
; DI void gemm_core(const GTile& tl, const GTile& nx, bool has_next  , bool chain  , bool pre, u32x4 (&ra)[4], u32x4 (&rb)[4], char* smem, f32x16 (&acc)[2][4]) {
;     ...
;   const int nk = K / 64;
;   if (!pre) { G_LOAD(0); G_STORE(0); G_LOAD(1); }
;   for (int kt = 0; kt < nk; ++kt) {
;     __syncthreads();
;     G_COMPUTE(kt & 1, kt);
;   }
	s_waitcnt vmcnt(7)
	ds_write_b128 v215, v[176:179]
	s_waitcnt vmcnt(6)
	ds_write_b128 v215, v[180:183] offset:36864
	ds_read_b128 v[176:179], v208
	ds_read_b128 v[180:183], v208 offset:4608
	v_mfma_f32_32x32x16_bf16 v[80:95], v[234:237], v[226:229], v[80:95]
	v_mfma_f32_32x32x16_bf16 v[16:31], v[234:237], v[230:233], v[16:31]
	ds_read_b128 v[234:237], v192
	v_mfma_f32_32x32x16_bf16 v[64:79], v[238:241], v[226:229], v[64:79]
	v_mfma_f32_32x32x16_bf16 v[0:15], v[238:241], v[230:233], v[0:15]
	ds_read_b128 v[238:241], v192 offset:4608
	s_setprio 0
	global_load_dwordx4 v[226:229], v[190:191], off offset:1408
	global_load_dwordx4 v[230:233], v[188:189], off offset:1408
	s_setprio 1
	s_waitcnt lgkmcnt(1)
	v_mfma_f32_32x32x16_bf16 v[112:127], v[234:237], v[176:179], v[112:127]
	v_mfma_f32_32x32x16_bf16 v[48:63], v[234:237], v[180:183], v[48:63]
	s_waitcnt lgkmcnt(0)
	v_mfma_f32_32x32x16_bf16 v[96:111], v[238:241], v[176:179], v[96:111]
	v_mfma_f32_32x32x16_bf16 v[32:47], v[238:241], v[180:183], v[32:47]
	ds_read_b128 v[234:237], v192 offset:9216
	ds_read_b128 v[238:241], v192 offset:13824
	s_waitcnt vmcnt(7)
	ds_write_b128 v215, v[168:171] offset:9216
	s_waitcnt vmcnt(6)
	ds_write_b128 v215, v[172:175] offset:46080
	ds_read_b128 v[168:171], v208 offset:32
	ds_read_b128 v[172:175], v208 offset:4640
	s_waitcnt lgkmcnt(5)
	v_mfma_f32_32x32x16_bf16 v[80:95], v[234:237], v[176:179], v[80:95]
	v_mfma_f32_32x32x16_bf16 v[16:31], v[234:237], v[180:183], v[16:31]
	ds_read_b128 v[234:237], v192 offset:32
	s_waitcnt lgkmcnt(5)
	v_mfma_f32_32x32x16_bf16 v[64:79], v[238:241], v[176:179], v[64:79]
	v_mfma_f32_32x32x16_bf16 v[0:15], v[238:241], v[180:183], v[0:15]
	ds_read_b128 v[238:241], v192 offset:4640
	s_setprio 0
	global_load_dwordx4 v[176:179], v[194:195], off offset:1408
	global_load_dwordx4 v[180:183], v[196:197], off offset:1408
	s_setprio 1
	s_waitcnt lgkmcnt(1)
	v_mfma_f32_32x32x16_bf16 v[112:127], v[234:237], v[168:171], v[112:127]
	v_mfma_f32_32x32x16_bf16 v[48:63], v[234:237], v[172:175], v[48:63]
	s_waitcnt lgkmcnt(0)
	v_mfma_f32_32x32x16_bf16 v[96:111], v[238:241], v[168:171], v[96:111]
	v_mfma_f32_32x32x16_bf16 v[32:47], v[238:241], v[172:175], v[32:47]
	ds_read_b128 v[234:237], v192 offset:9248
	ds_read_b128 v[238:241], v192 offset:13856
	s_waitcnt vmcnt(7)
	ds_write_b128 v215, v[160:163] offset:18432
	s_waitcnt vmcnt(6)
	ds_write_b128 v215, v[164:167] offset:55296
	ds_read_b128 v[160:163], v208 offset:64
	ds_read_b128 v[164:167], v208 offset:4672
	s_waitcnt lgkmcnt(5)
	v_mfma_f32_32x32x16_bf16 v[80:95], v[234:237], v[168:171], v[80:95]
	v_mfma_f32_32x32x16_bf16 v[16:31], v[234:237], v[172:175], v[16:31]
	ds_read_b128 v[234:237], v192 offset:64
	s_waitcnt lgkmcnt(5)
	v_mfma_f32_32x32x16_bf16 v[64:79], v[238:241], v[168:171], v[64:79]
	v_mfma_f32_32x32x16_bf16 v[0:15], v[238:241], v[172:175], v[0:15]
	ds_read_b128 v[238:241], v192 offset:4672
	s_setprio 0
	global_load_dwordx4 v[168:171], v[184:185], off offset:1408
	global_load_dwordx4 v[172:175], v[186:187], off offset:1408
	s_setprio 1
	s_waitcnt lgkmcnt(1)
	v_mfma_f32_32x32x16_bf16 v[112:127], v[234:237], v[160:163], v[112:127]
	v_mfma_f32_32x32x16_bf16 v[48:63], v[234:237], v[164:167], v[48:63]
	s_waitcnt lgkmcnt(0)
	v_mfma_f32_32x32x16_bf16 v[96:111], v[238:241], v[160:163], v[96:111]
	v_mfma_f32_32x32x16_bf16 v[32:47], v[238:241], v[164:167], v[32:47]
	ds_read_b128 v[234:237], v192 offset:9280
	ds_read_b128 v[238:241], v192 offset:13888
	s_waitcnt vmcnt(7)
	ds_write_b128 v215, v[218:221] offset:27648
	s_waitcnt vmcnt(6)
	ds_write_b128 v215, v[222:225] offset:64512
	ds_read_b128 v[218:221], v208 offset:96
	ds_read_b128 v[222:225], v208 offset:4704
	s_waitcnt lgkmcnt(5)
	v_mfma_f32_32x32x16_bf16 v[80:95], v[234:237], v[160:163], v[80:95]
	v_mfma_f32_32x32x16_bf16 v[16:31], v[234:237], v[164:167], v[16:31]
	ds_read_b128 v[234:237], v192 offset:96
	s_waitcnt lgkmcnt(5)
	v_mfma_f32_32x32x16_bf16 v[64:79], v[238:241], v[160:163], v[64:79]
	v_mfma_f32_32x32x16_bf16 v[0:15], v[238:241], v[164:167], v[0:15]
	ds_read_b128 v[238:241], v192 offset:4704
	s_setprio 0
	global_load_dwordx4 v[160:163], v[198:199], off offset:1408
	global_load_dwordx4 v[164:167], v[200:201], off offset:1408
	s_setprio 1
	s_waitcnt lgkmcnt(1)
	v_mfma_f32_32x32x16_bf16 v[112:127], v[234:237], v[218:221], v[112:127]
	v_mfma_f32_32x32x16_bf16 v[48:63], v[234:237], v[222:225], v[48:63]
	s_waitcnt lgkmcnt(0)
	v_mfma_f32_32x32x16_bf16 v[96:111], v[238:241], v[218:221], v[96:111]
	v_mfma_f32_32x32x16_bf16 v[32:47], v[238:241], v[222:225], v[32:47]
	ds_read_b128 v[234:237], v192 offset:9312
	ds_read_b128 v[238:241], v192 offset:13920
	s_waitcnt lgkmcnt(0)
	s_barrier
; template <bool trans>
; DI void gemm_core(const GTile& tl, const GTile& nx, bool has_next  , bool chain  , bool pre, u32x4 (&ra)[4], u32x4 (&rb)[4], char* smem, f32x16 (&acc)[2][4]) {
;     ...
;   const int nk = K / 64;
;   if (!pre) { G_LOAD(0); G_STORE(0); G_LOAD(1); }
;   for (int kt = 0; kt < nk; ++kt) {
;     __syncthreads();
;     G_COMPUTE(kt & 1, kt);
;   }
	s_waitcnt vmcnt(7)
	ds_write_b128 v209, v[226:229]
	s_waitcnt vmcnt(6)
	ds_write_b128 v210, v[230:233]
	ds_read_b128 v[226:229], v205 offset:36864
	ds_read_b128 v[230:233], v205 offset:41472
	v_mfma_f32_32x32x16_bf16 v[80:95], v[234:237], v[218:221], v[80:95]
	v_mfma_f32_32x32x16_bf16 v[16:31], v[234:237], v[222:225], v[16:31]
	ds_read_b128 v[234:237], v204
	v_mfma_f32_32x32x16_bf16 v[64:79], v[238:241], v[218:221], v[64:79]
	v_mfma_f32_32x32x16_bf16 v[0:15], v[238:241], v[222:225], v[0:15]
	ds_read_b128 v[238:241], v204 offset:4608
	s_setprio 0
	global_load_dwordx4 v[218:221], v[190:191], off offset:1536
	global_load_dwordx4 v[222:225], v[188:189], off offset:1536
	s_setprio 1
	s_waitcnt lgkmcnt(1)
	v_mfma_f32_32x32x16_bf16 v[112:127], v[234:237], v[226:229], v[112:127]
	v_mfma_f32_32x32x16_bf16 v[48:63], v[234:237], v[230:233], v[48:63]
	s_waitcnt lgkmcnt(0)
	v_mfma_f32_32x32x16_bf16 v[96:111], v[238:241], v[226:229], v[96:111]
	v_mfma_f32_32x32x16_bf16 v[32:47], v[238:241], v[230:233], v[32:47]
	ds_read_b128 v[234:237], v204 offset:9216
	ds_read_b128 v[238:241], v204 offset:13824
	s_waitcnt vmcnt(7)
	ds_write_b128 v212, v[176:179]
	s_waitcnt vmcnt(6)
	ds_write_b128 v211, v[180:183]
	ds_read_b128 v[176:179], v205 offset:36896
	ds_read_b128 v[180:183], v205 offset:41504
	s_waitcnt lgkmcnt(5)
	v_mfma_f32_32x32x16_bf16 v[80:95], v[234:237], v[226:229], v[80:95]
	v_mfma_f32_32x32x16_bf16 v[16:31], v[234:237], v[230:233], v[16:31]
	ds_read_b128 v[234:237], v204 offset:32
	s_waitcnt lgkmcnt(5)
	v_mfma_f32_32x32x16_bf16 v[64:79], v[238:241], v[226:229], v[64:79]
	v_mfma_f32_32x32x16_bf16 v[0:15], v[238:241], v[230:233], v[0:15]
	ds_read_b128 v[238:241], v204 offset:4640
	s_setprio 0
	global_load_dwordx4 v[226:229], v[194:195], off offset:1536
	global_load_dwordx4 v[230:233], v[196:197], off offset:1536
	s_setprio 1
	s_waitcnt lgkmcnt(1)
	v_mfma_f32_32x32x16_bf16 v[112:127], v[234:237], v[176:179], v[112:127]
	v_mfma_f32_32x32x16_bf16 v[48:63], v[234:237], v[180:183], v[48:63]
	s_waitcnt lgkmcnt(0)
	v_mfma_f32_32x32x16_bf16 v[96:111], v[238:241], v[176:179], v[96:111]
	v_mfma_f32_32x32x16_bf16 v[32:47], v[238:241], v[180:183], v[32:47]
	ds_read_b128 v[234:237], v204 offset:9248
	ds_read_b128 v[238:241], v204 offset:13856
	s_waitcnt vmcnt(7)
	ds_write_b128 v214, v[168:171]
	s_waitcnt vmcnt(6)
	ds_write_b128 v213, v[172:175]
	ds_read_b128 v[168:171], v205 offset:36928
	ds_read_b128 v[172:175], v205 offset:41536
	s_waitcnt lgkmcnt(5)
	v_mfma_f32_32x32x16_bf16 v[80:95], v[234:237], v[176:179], v[80:95]
	v_mfma_f32_32x32x16_bf16 v[16:31], v[234:237], v[180:183], v[16:31]
	ds_read_b128 v[234:237], v204 offset:64
	s_waitcnt lgkmcnt(5)
	v_mfma_f32_32x32x16_bf16 v[64:79], v[238:241], v[176:179], v[64:79]
	v_mfma_f32_32x32x16_bf16 v[0:15], v[238:241], v[180:183], v[0:15]
	ds_read_b128 v[238:241], v204 offset:4672
	s_setprio 0
	global_load_dwordx4 v[176:179], v[184:185], off offset:1536
	global_load_dwordx4 v[180:183], v[186:187], off offset:1536
	s_setprio 1
	s_waitcnt lgkmcnt(1)
	v_mfma_f32_32x32x16_bf16 v[112:127], v[234:237], v[168:171], v[112:127]
	v_mfma_f32_32x32x16_bf16 v[48:63], v[234:237], v[172:175], v[48:63]
	s_waitcnt lgkmcnt(0)
	v_mfma_f32_32x32x16_bf16 v[96:111], v[238:241], v[168:171], v[96:111]
	v_mfma_f32_32x32x16_bf16 v[32:47], v[238:241], v[172:175], v[32:47]
	ds_read_b128 v[234:237], v204 offset:9280
	ds_read_b128 v[238:241], v204 offset:13888
	s_waitcnt vmcnt(7)
	ds_write_b128 v217, v[160:163]
	s_waitcnt vmcnt(6)
	ds_write_b128 v216, v[164:167]
	ds_read_b128 v[160:163], v205 offset:36960
	ds_read_b128 v[164:167], v205 offset:41568
	s_waitcnt lgkmcnt(5)
	v_mfma_f32_32x32x16_bf16 v[80:95], v[234:237], v[168:171], v[80:95]
	v_mfma_f32_32x32x16_bf16 v[16:31], v[234:237], v[172:175], v[16:31]
	ds_read_b128 v[234:237], v204 offset:96
	s_waitcnt lgkmcnt(5)
	v_mfma_f32_32x32x16_bf16 v[64:79], v[238:241], v[168:171], v[64:79]
	v_mfma_f32_32x32x16_bf16 v[0:15], v[238:241], v[172:175], v[0:15]
	ds_read_b128 v[238:241], v204 offset:4704
	s_setprio 0
	global_load_dwordx4 v[168:171], v[198:199], off offset:1536
	global_load_dwordx4 v[172:175], v[200:201], off offset:1536
	s_setprio 1
	s_waitcnt lgkmcnt(1)
	v_mfma_f32_32x32x16_bf16 v[112:127], v[234:237], v[160:163], v[112:127]
	v_mfma_f32_32x32x16_bf16 v[48:63], v[234:237], v[164:167], v[48:63]
	s_waitcnt lgkmcnt(0)
	v_mfma_f32_32x32x16_bf16 v[96:111], v[238:241], v[160:163], v[96:111]
	v_mfma_f32_32x32x16_bf16 v[32:47], v[238:241], v[164:167], v[32:47]
	ds_read_b128 v[234:237], v204 offset:9312
	ds_read_b128 v[238:241], v204 offset:13920
	s_waitcnt lgkmcnt(0)
	s_barrier
; template <bool trans>
; DI void gemm_core(const GTile& tl, const GTile& nx, bool has_next  , bool chain  , bool pre, u32x4 (&ra)[4], u32x4 (&rb)[4], char* smem, f32x16 (&acc)[2][4]) {
;     ...
;   const int nk = K / 64;
;   if (!pre) { G_LOAD(0); G_STORE(0); G_LOAD(1); }
;   for (int kt = 0; kt < nk; ++kt) {
;     __syncthreads();
;     G_COMPUTE(kt & 1, kt);
;   }
	s_waitcnt vmcnt(7)
	ds_write_b128 v215, v[218:221]
	s_waitcnt vmcnt(6)
	ds_write_b128 v215, v[222:225] offset:36864
	ds_read_b128 v[218:221], v208
	ds_read_b128 v[222:225], v208 offset:4608
	v_mfma_f32_32x32x16_bf16 v[80:95], v[234:237], v[160:163], v[80:95]
	v_mfma_f32_32x32x16_bf16 v[16:31], v[234:237], v[164:167], v[16:31]
	ds_read_b128 v[234:237], v192
	v_mfma_f32_32x32x16_bf16 v[64:79], v[238:241], v[160:163], v[64:79]
	v_mfma_f32_32x32x16_bf16 v[0:15], v[238:241], v[164:167], v[0:15]
	ds_read_b128 v[238:241], v192 offset:4608
	s_setprio 0
	global_load_dwordx4 v[160:163], v[190:191], off offset:1664
	global_load_dwordx4 v[164:167], v[188:189], off offset:1664
	s_setprio 1
	s_waitcnt lgkmcnt(1)
	v_mfma_f32_32x32x16_bf16 v[112:127], v[234:237], v[218:221], v[112:127]
	v_mfma_f32_32x32x16_bf16 v[48:63], v[234:237], v[222:225], v[48:63]
	s_waitcnt lgkmcnt(0)
	v_mfma_f32_32x32x16_bf16 v[96:111], v[238:241], v[218:221], v[96:111]
	v_mfma_f32_32x32x16_bf16 v[32:47], v[238:241], v[222:225], v[32:47]
	ds_read_b128 v[234:237], v192 offset:9216
	ds_read_b128 v[238:241], v192 offset:13824
	s_waitcnt vmcnt(7)
	ds_write_b128 v215, v[226:229] offset:9216
	s_waitcnt vmcnt(6)
	ds_write_b128 v215, v[230:233] offset:46080
	ds_read_b128 v[226:229], v208 offset:32
	ds_read_b128 v[230:233], v208 offset:4640
	s_waitcnt lgkmcnt(5)
	v_mfma_f32_32x32x16_bf16 v[80:95], v[234:237], v[218:221], v[80:95]
	v_mfma_f32_32x32x16_bf16 v[16:31], v[234:237], v[222:225], v[16:31]
	ds_read_b128 v[234:237], v192 offset:32
	s_waitcnt lgkmcnt(5)
	v_mfma_f32_32x32x16_bf16 v[64:79], v[238:241], v[218:221], v[64:79]
	v_mfma_f32_32x32x16_bf16 v[0:15], v[238:241], v[222:225], v[0:15]
	ds_read_b128 v[238:241], v192 offset:4640
	s_setprio 0
	global_load_dwordx4 v[218:221], v[194:195], off offset:1664
	global_load_dwordx4 v[222:225], v[196:197], off offset:1664
	s_setprio 1
	s_waitcnt lgkmcnt(1)
	v_mfma_f32_32x32x16_bf16 v[112:127], v[234:237], v[226:229], v[112:127]
	v_mfma_f32_32x32x16_bf16 v[48:63], v[234:237], v[230:233], v[48:63]
	s_waitcnt lgkmcnt(0)
	v_mfma_f32_32x32x16_bf16 v[96:111], v[238:241], v[226:229], v[96:111]
	v_mfma_f32_32x32x16_bf16 v[32:47], v[238:241], v[230:233], v[32:47]
	ds_read_b128 v[234:237], v192 offset:9248
	ds_read_b128 v[238:241], v192 offset:13856
	s_waitcnt vmcnt(7)
	ds_write_b128 v215, v[176:179] offset:18432
	s_waitcnt vmcnt(6)
	ds_write_b128 v215, v[180:183] offset:55296
	ds_read_b128 v[176:179], v208 offset:64
	ds_read_b128 v[180:183], v208 offset:4672
	s_waitcnt lgkmcnt(5)
	v_mfma_f32_32x32x16_bf16 v[80:95], v[234:237], v[226:229], v[80:95]
	v_mfma_f32_32x32x16_bf16 v[16:31], v[234:237], v[230:233], v[16:31]
	ds_read_b128 v[234:237], v192 offset:64
	s_waitcnt lgkmcnt(5)
	v_mfma_f32_32x32x16_bf16 v[64:79], v[238:241], v[226:229], v[64:79]
	v_mfma_f32_32x32x16_bf16 v[0:15], v[238:241], v[230:233], v[0:15]
	ds_read_b128 v[238:241], v192 offset:4672
	s_setprio 0
	global_load_dwordx4 v[226:229], v[184:185], off offset:1664
	global_load_dwordx4 v[230:233], v[186:187], off offset:1664
	s_setprio 1
	s_waitcnt lgkmcnt(1)
	v_mfma_f32_32x32x16_bf16 v[112:127], v[234:237], v[176:179], v[112:127]
	v_mfma_f32_32x32x16_bf16 v[48:63], v[234:237], v[180:183], v[48:63]
	s_waitcnt lgkmcnt(0)
	v_mfma_f32_32x32x16_bf16 v[96:111], v[238:241], v[176:179], v[96:111]
	v_mfma_f32_32x32x16_bf16 v[32:47], v[238:241], v[180:183], v[32:47]
	ds_read_b128 v[234:237], v192 offset:9280
	ds_read_b128 v[238:241], v192 offset:13888
	s_waitcnt vmcnt(7)
	ds_write_b128 v215, v[168:171] offset:27648
	s_waitcnt vmcnt(6)
	ds_write_b128 v215, v[172:175] offset:64512
	ds_read_b128 v[168:171], v208 offset:96
	ds_read_b128 v[172:175], v208 offset:4704
	s_waitcnt lgkmcnt(5)
	v_mfma_f32_32x32x16_bf16 v[80:95], v[234:237], v[176:179], v[80:95]
	v_mfma_f32_32x32x16_bf16 v[16:31], v[234:237], v[180:183], v[16:31]
	ds_read_b128 v[234:237], v192 offset:96
	s_waitcnt lgkmcnt(5)
	v_mfma_f32_32x32x16_bf16 v[64:79], v[238:241], v[176:179], v[64:79]
	v_mfma_f32_32x32x16_bf16 v[0:15], v[238:241], v[180:183], v[0:15]
	ds_read_b128 v[238:241], v192 offset:4704
	s_setprio 0
	global_load_dwordx4 v[176:179], v[198:199], off offset:1664
	global_load_dwordx4 v[180:183], v[200:201], off offset:1664
	s_setprio 1
	s_waitcnt lgkmcnt(1)
	v_mfma_f32_32x32x16_bf16 v[112:127], v[234:237], v[168:171], v[112:127]
	v_mfma_f32_32x32x16_bf16 v[48:63], v[234:237], v[172:175], v[48:63]
	s_waitcnt lgkmcnt(0)
	v_mfma_f32_32x32x16_bf16 v[96:111], v[238:241], v[168:171], v[96:111]
	v_mfma_f32_32x32x16_bf16 v[32:47], v[238:241], v[172:175], v[32:47]
	ds_read_b128 v[234:237], v192 offset:9312
	ds_read_b128 v[238:241], v192 offset:13920
	s_waitcnt lgkmcnt(0)
	s_barrier
; template <bool trans>
; DI void gemm_core(const GTile& tl, const GTile& nx, bool has_next  , bool chain  , bool pre, u32x4 (&ra)[4], u32x4 (&rb)[4], char* smem, f32x16 (&acc)[2][4]) {
;     ...
;   const int nk = K / 64;
;   if (!pre) { G_LOAD(0); G_STORE(0); G_LOAD(1); }
;   for (int kt = 0; kt < nk; ++kt) {
;     __syncthreads();
;     G_COMPUTE(kt & 1, kt);
;   }
	s_waitcnt vmcnt(7)
	ds_write_b128 v209, v[160:163]
	s_waitcnt vmcnt(6)
	ds_write_b128 v210, v[164:167]
	ds_read_b128 v[160:163], v205 offset:36864
	ds_read_b128 v[164:167], v205 offset:41472
	v_mfma_f32_32x32x16_bf16 v[80:95], v[234:237], v[168:171], v[80:95]
	v_mfma_f32_32x32x16_bf16 v[16:31], v[234:237], v[172:175], v[16:31]
	ds_read_b128 v[234:237], v204
	v_mfma_f32_32x32x16_bf16 v[64:79], v[238:241], v[168:171], v[64:79]
	v_mfma_f32_32x32x16_bf16 v[0:15], v[238:241], v[172:175], v[0:15]
	ds_read_b128 v[238:241], v204 offset:4608
	s_setprio 0
	global_load_dwordx4 v[168:171], v[190:191], off offset:1792
	global_load_dwordx4 v[172:175], v[188:189], off offset:1792
	s_setprio 1
	s_waitcnt lgkmcnt(1)
	v_mfma_f32_32x32x16_bf16 v[112:127], v[234:237], v[160:163], v[112:127]
	v_mfma_f32_32x32x16_bf16 v[48:63], v[234:237], v[164:167], v[48:63]
	s_waitcnt lgkmcnt(0)
	v_mfma_f32_32x32x16_bf16 v[96:111], v[238:241], v[160:163], v[96:111]
	v_mfma_f32_32x32x16_bf16 v[32:47], v[238:241], v[164:167], v[32:47]
	ds_read_b128 v[234:237], v204 offset:9216
	ds_read_b128 v[238:241], v204 offset:13824
	s_waitcnt vmcnt(7)
	ds_write_b128 v212, v[218:221]
	s_waitcnt vmcnt(6)
	ds_write_b128 v211, v[222:225]
	ds_read_b128 v[218:221], v205 offset:36896
	ds_read_b128 v[222:225], v205 offset:41504
	s_waitcnt lgkmcnt(5)
	v_mfma_f32_32x32x16_bf16 v[80:95], v[234:237], v[160:163], v[80:95]
	v_mfma_f32_32x32x16_bf16 v[16:31], v[234:237], v[164:167], v[16:31]
	ds_read_b128 v[234:237], v204 offset:32
	s_waitcnt lgkmcnt(5)
	v_mfma_f32_32x32x16_bf16 v[64:79], v[238:241], v[160:163], v[64:79]
	v_mfma_f32_32x32x16_bf16 v[0:15], v[238:241], v[164:167], v[0:15]
	ds_read_b128 v[238:241], v204 offset:4640
	s_setprio 0
	global_load_dwordx4 v[160:163], v[194:195], off offset:1792
	global_load_dwordx4 v[164:167], v[196:197], off offset:1792
	s_setprio 1
	s_waitcnt lgkmcnt(1)
	v_mfma_f32_32x32x16_bf16 v[112:127], v[234:237], v[218:221], v[112:127]
	v_mfma_f32_32x32x16_bf16 v[48:63], v[234:237], v[222:225], v[48:63]
	s_waitcnt lgkmcnt(0)
	v_mfma_f32_32x32x16_bf16 v[96:111], v[238:241], v[218:221], v[96:111]
	v_mfma_f32_32x32x16_bf16 v[32:47], v[238:241], v[222:225], v[32:47]
	ds_read_b128 v[234:237], v204 offset:9248
	ds_read_b128 v[238:241], v204 offset:13856
	s_waitcnt vmcnt(7)
	ds_write_b128 v214, v[226:229]
	s_waitcnt vmcnt(6)
	ds_write_b128 v213, v[230:233]
	ds_read_b128 v[226:229], v205 offset:36928
	ds_read_b128 v[230:233], v205 offset:41536
	s_waitcnt lgkmcnt(5)
	v_mfma_f32_32x32x16_bf16 v[80:95], v[234:237], v[218:221], v[80:95]
	v_mfma_f32_32x32x16_bf16 v[16:31], v[234:237], v[222:225], v[16:31]
	ds_read_b128 v[234:237], v204 offset:64
	s_waitcnt lgkmcnt(5)
	v_mfma_f32_32x32x16_bf16 v[64:79], v[238:241], v[218:221], v[64:79]
	v_mfma_f32_32x32x16_bf16 v[0:15], v[238:241], v[222:225], v[0:15]
	ds_read_b128 v[238:241], v204 offset:4672
	s_setprio 0
	global_load_dwordx4 v[218:221], v[184:185], off offset:1792
	global_load_dwordx4 v[222:225], v[186:187], off offset:1792
	s_setprio 1
	s_waitcnt lgkmcnt(1)
	v_mfma_f32_32x32x16_bf16 v[112:127], v[234:237], v[226:229], v[112:127]
	v_mfma_f32_32x32x16_bf16 v[48:63], v[234:237], v[230:233], v[48:63]
	s_waitcnt lgkmcnt(0)
	v_mfma_f32_32x32x16_bf16 v[96:111], v[238:241], v[226:229], v[96:111]
	v_mfma_f32_32x32x16_bf16 v[32:47], v[238:241], v[230:233], v[32:47]
	ds_read_b128 v[234:237], v204 offset:9280
	ds_read_b128 v[238:241], v204 offset:13888
	s_waitcnt vmcnt(7)
	ds_write_b128 v217, v[176:179]
	s_waitcnt vmcnt(6)
	ds_write_b128 v216, v[180:183]
	ds_read_b128 v[176:179], v205 offset:36960
	ds_read_b128 v[180:183], v205 offset:41568
	s_waitcnt lgkmcnt(5)
	v_mfma_f32_32x32x16_bf16 v[80:95], v[234:237], v[226:229], v[80:95]
	v_mfma_f32_32x32x16_bf16 v[16:31], v[234:237], v[230:233], v[16:31]
	ds_read_b128 v[234:237], v204 offset:96
	s_waitcnt lgkmcnt(5)
	v_mfma_f32_32x32x16_bf16 v[64:79], v[238:241], v[226:229], v[64:79]
	v_mfma_f32_32x32x16_bf16 v[0:15], v[238:241], v[230:233], v[0:15]
	ds_read_b128 v[238:241], v204 offset:4704
	s_setprio 0
	global_load_dwordx4 v[226:229], v[198:199], off offset:1792
	global_load_dwordx4 v[230:233], v[200:201], off offset:1792
	s_setprio 1
	s_waitcnt lgkmcnt(1)
	v_mfma_f32_32x32x16_bf16 v[112:127], v[234:237], v[176:179], v[112:127]
	v_mfma_f32_32x32x16_bf16 v[48:63], v[234:237], v[180:183], v[48:63]
	s_waitcnt lgkmcnt(0)
	v_mfma_f32_32x32x16_bf16 v[96:111], v[238:241], v[176:179], v[96:111]
	v_mfma_f32_32x32x16_bf16 v[32:47], v[238:241], v[180:183], v[32:47]
	ds_read_b128 v[234:237], v204 offset:9312
	ds_read_b128 v[238:241], v204 offset:13920
	s_waitcnt lgkmcnt(0)
	s_barrier
; template <bool trans>
; DI void gemm_core(const GTile& tl, const GTile& nx, bool has_next  , bool chain  , bool pre, u32x4 (&ra)[4], u32x4 (&rb)[4], char* smem, f32x16 (&acc)[2][4]) {
;     ...
;   const int nk = K / 64;
;   if (!pre) { G_LOAD(0); G_STORE(0); G_LOAD(1); }
;   for (int kt = 0; kt < nk; ++kt) {
;     __syncthreads();
;     G_COMPUTE(kt & 1, kt);
;   }
	s_waitcnt vmcnt(7)
	ds_write_b128 v215, v[168:171]
	s_waitcnt vmcnt(6)
	ds_write_b128 v215, v[172:175] offset:36864
	ds_read_b128 v[168:171], v208
	ds_read_b128 v[172:175], v208 offset:4608
	v_mfma_f32_32x32x16_bf16 v[80:95], v[234:237], v[176:179], v[80:95]
	v_mfma_f32_32x32x16_bf16 v[16:31], v[234:237], v[180:183], v[16:31]
	ds_read_b128 v[234:237], v192
	v_mfma_f32_32x32x16_bf16 v[64:79], v[238:241], v[176:179], v[64:79]
	v_mfma_f32_32x32x16_bf16 v[0:15], v[238:241], v[180:183], v[0:15]
	ds_read_b128 v[238:241], v192 offset:4608
	s_setprio 0
	global_load_dwordx4 v[176:179], v[190:191], off offset:1920
	global_load_dwordx4 v[180:183], v[188:189], off offset:1920
	s_setprio 1
	s_waitcnt lgkmcnt(1)
	v_mfma_f32_32x32x16_bf16 v[112:127], v[234:237], v[168:171], v[112:127]
	v_mfma_f32_32x32x16_bf16 v[48:63], v[234:237], v[172:175], v[48:63]
	s_waitcnt lgkmcnt(0)
	v_mfma_f32_32x32x16_bf16 v[96:111], v[238:241], v[168:171], v[96:111]
	v_mfma_f32_32x32x16_bf16 v[32:47], v[238:241], v[172:175], v[32:47]
	ds_read_b128 v[234:237], v192 offset:9216
	ds_read_b128 v[238:241], v192 offset:13824
	s_waitcnt vmcnt(7)
	ds_write_b128 v215, v[160:163] offset:9216
	s_waitcnt vmcnt(6)
	ds_write_b128 v215, v[164:167] offset:46080
	ds_read_b128 v[160:163], v208 offset:32
	ds_read_b128 v[164:167], v208 offset:4640
	s_waitcnt lgkmcnt(5)
	v_mfma_f32_32x32x16_bf16 v[80:95], v[234:237], v[168:171], v[80:95]
	v_mfma_f32_32x32x16_bf16 v[16:31], v[234:237], v[172:175], v[16:31]
	ds_read_b128 v[234:237], v192 offset:32
	s_waitcnt lgkmcnt(5)
	v_mfma_f32_32x32x16_bf16 v[64:79], v[238:241], v[168:171], v[64:79]
	v_mfma_f32_32x32x16_bf16 v[0:15], v[238:241], v[172:175], v[0:15]
	ds_read_b128 v[238:241], v192 offset:4640
	s_setprio 0
	global_load_dwordx4 v[168:171], v[194:195], off offset:1920
	global_load_dwordx4 v[172:175], v[196:197], off offset:1920
	s_setprio 1
	s_waitcnt lgkmcnt(1)
	v_mfma_f32_32x32x16_bf16 v[112:127], v[234:237], v[160:163], v[112:127]
	v_mfma_f32_32x32x16_bf16 v[48:63], v[234:237], v[164:167], v[48:63]
	s_waitcnt lgkmcnt(0)
	v_mfma_f32_32x32x16_bf16 v[96:111], v[238:241], v[160:163], v[96:111]
	v_mfma_f32_32x32x16_bf16 v[32:47], v[238:241], v[164:167], v[32:47]
	ds_read_b128 v[234:237], v192 offset:9248
	ds_read_b128 v[238:241], v192 offset:13856
	s_waitcnt vmcnt(7)
	ds_write_b128 v215, v[218:221] offset:18432
	s_waitcnt vmcnt(6)
	ds_write_b128 v215, v[222:225] offset:55296
	ds_read_b128 v[218:221], v208 offset:64
	ds_read_b128 v[222:225], v208 offset:4672
	s_waitcnt lgkmcnt(5)
	v_mfma_f32_32x32x16_bf16 v[80:95], v[234:237], v[160:163], v[80:95]
	v_mfma_f32_32x32x16_bf16 v[16:31], v[234:237], v[164:167], v[16:31]
	ds_read_b128 v[234:237], v192 offset:64
	s_waitcnt lgkmcnt(5)
	v_mfma_f32_32x32x16_bf16 v[64:79], v[238:241], v[160:163], v[64:79]
	v_mfma_f32_32x32x16_bf16 v[0:15], v[238:241], v[164:167], v[0:15]
	ds_read_b128 v[238:241], v192 offset:4672
	s_setprio 0
	global_load_dwordx4 v[160:163], v[184:185], off offset:1920
	global_load_dwordx4 v[164:167], v[186:187], off offset:1920
	s_setprio 1
	s_waitcnt lgkmcnt(1)
	v_mfma_f32_32x32x16_bf16 v[112:127], v[234:237], v[218:221], v[112:127]
	v_mfma_f32_32x32x16_bf16 v[48:63], v[234:237], v[222:225], v[48:63]
	s_waitcnt lgkmcnt(0)
	v_mfma_f32_32x32x16_bf16 v[96:111], v[238:241], v[218:221], v[96:111]
	v_mfma_f32_32x32x16_bf16 v[32:47], v[238:241], v[222:225], v[32:47]
	ds_read_b128 v[234:237], v192 offset:9280
	ds_read_b128 v[238:241], v192 offset:13888
	s_waitcnt vmcnt(7)
	ds_write_b128 v215, v[226:229] offset:27648
	s_waitcnt vmcnt(6)
	ds_write_b128 v215, v[230:233] offset:64512
	ds_read_b128 v[226:229], v208 offset:96
	ds_read_b128 v[230:233], v208 offset:4704
	s_waitcnt lgkmcnt(5)
	v_mfma_f32_32x32x16_bf16 v[80:95], v[234:237], v[218:221], v[80:95]
	v_mfma_f32_32x32x16_bf16 v[16:31], v[234:237], v[222:225], v[16:31]
	ds_read_b128 v[234:237], v192 offset:96
	s_waitcnt lgkmcnt(5)
	v_mfma_f32_32x32x16_bf16 v[64:79], v[238:241], v[218:221], v[64:79]
	v_mfma_f32_32x32x16_bf16 v[0:15], v[238:241], v[222:225], v[0:15]
	ds_read_b128 v[238:241], v192 offset:4704
	s_setprio 0
	global_load_dwordx4 v[218:221], v[198:199], off offset:1920
	global_load_dwordx4 v[222:225], v[200:201], off offset:1920
	s_setprio 1
	s_waitcnt lgkmcnt(1)
	v_mfma_f32_32x32x16_bf16 v[112:127], v[234:237], v[226:229], v[112:127]
	v_mfma_f32_32x32x16_bf16 v[48:63], v[234:237], v[230:233], v[48:63]
	s_waitcnt lgkmcnt(0)
	v_mfma_f32_32x32x16_bf16 v[96:111], v[238:241], v[226:229], v[96:111]
	v_mfma_f32_32x32x16_bf16 v[32:47], v[238:241], v[230:233], v[32:47]
	ds_read_b128 v[234:237], v192 offset:9312
	ds_read_b128 v[238:241], v192 offset:13920
	s_waitcnt lgkmcnt(0)
	s_barrier
; template <bool trans>
; DI void gemm_core(const GTile& tl, const GTile& nx, bool has_next  , bool chain  , bool pre, u32x4 (&ra)[4], u32x4 (&rb)[4], char* smem, f32x16 (&acc)[2][4]) {
;     ...
;   const int nk = K / 64;
;   if (!pre) { G_LOAD(0); G_STORE(0); G_LOAD(1); }
;   for (int kt = 0; kt < nk; ++kt) {
;     __syncthreads();
;     G_COMPUTE(kt & 1, kt);
;   }
	s_waitcnt vmcnt(7)
	ds_write_b128 v209, v[176:179]
	s_waitcnt vmcnt(6)
	ds_write_b128 v210, v[180:183]
	ds_read_b128 v[176:179], v205 offset:36864
	ds_read_b128 v[180:183], v205 offset:41472
	v_mfma_f32_32x32x16_bf16 v[80:95], v[234:237], v[226:229], v[80:95]
	v_mfma_f32_32x32x16_bf16 v[16:31], v[234:237], v[230:233], v[16:31]
	ds_read_b128 v[234:237], v204
	v_mfma_f32_32x32x16_bf16 v[64:79], v[238:241], v[226:229], v[64:79]
	v_mfma_f32_32x32x16_bf16 v[0:15], v[238:241], v[230:233], v[0:15]
	ds_read_b128 v[238:241], v204 offset:4608
	s_setprio 0
	global_load_dwordx4 v[226:229], v[190:191], off offset:2048
	global_load_dwordx4 v[230:233], v[188:189], off offset:2048
	s_setprio 1
	s_waitcnt lgkmcnt(1)
	v_mfma_f32_32x32x16_bf16 v[112:127], v[234:237], v[176:179], v[112:127]
	v_mfma_f32_32x32x16_bf16 v[48:63], v[234:237], v[180:183], v[48:63]
	s_waitcnt lgkmcnt(0)
	v_mfma_f32_32x32x16_bf16 v[96:111], v[238:241], v[176:179], v[96:111]
	v_mfma_f32_32x32x16_bf16 v[32:47], v[238:241], v[180:183], v[32:47]
	ds_read_b128 v[234:237], v204 offset:9216
	ds_read_b128 v[238:241], v204 offset:13824
	s_waitcnt vmcnt(7)
	ds_write_b128 v212, v[168:171]
	s_waitcnt vmcnt(6)
	ds_write_b128 v211, v[172:175]
	ds_read_b128 v[168:171], v205 offset:36896
	ds_read_b128 v[172:175], v205 offset:41504
	s_waitcnt lgkmcnt(5)
	v_mfma_f32_32x32x16_bf16 v[80:95], v[234:237], v[176:179], v[80:95]
	v_mfma_f32_32x32x16_bf16 v[16:31], v[234:237], v[180:183], v[16:31]
	ds_read_b128 v[234:237], v204 offset:32
	s_waitcnt lgkmcnt(5)
	v_mfma_f32_32x32x16_bf16 v[64:79], v[238:241], v[176:179], v[64:79]
	v_mfma_f32_32x32x16_bf16 v[0:15], v[238:241], v[180:183], v[0:15]
	ds_read_b128 v[238:241], v204 offset:4640
	s_setprio 0
	global_load_dwordx4 v[176:179], v[194:195], off offset:2048
	global_load_dwordx4 v[180:183], v[196:197], off offset:2048
	s_setprio 1
	s_waitcnt lgkmcnt(1)
	v_mfma_f32_32x32x16_bf16 v[112:127], v[234:237], v[168:171], v[112:127]
	v_mfma_f32_32x32x16_bf16 v[48:63], v[234:237], v[172:175], v[48:63]
	s_waitcnt lgkmcnt(0)
	v_mfma_f32_32x32x16_bf16 v[96:111], v[238:241], v[168:171], v[96:111]
	v_mfma_f32_32x32x16_bf16 v[32:47], v[238:241], v[172:175], v[32:47]
	ds_read_b128 v[234:237], v204 offset:9248
	ds_read_b128 v[238:241], v204 offset:13856
	s_waitcnt vmcnt(7)
	ds_write_b128 v214, v[160:163]
	s_waitcnt vmcnt(6)
	ds_write_b128 v213, v[164:167]
	ds_read_b128 v[160:163], v205 offset:36928
	ds_read_b128 v[164:167], v205 offset:41536
	s_waitcnt lgkmcnt(5)
	v_mfma_f32_32x32x16_bf16 v[80:95], v[234:237], v[168:171], v[80:95]
	v_mfma_f32_32x32x16_bf16 v[16:31], v[234:237], v[172:175], v[16:31]
	ds_read_b128 v[234:237], v204 offset:64
	s_waitcnt lgkmcnt(5)
	v_mfma_f32_32x32x16_bf16 v[64:79], v[238:241], v[168:171], v[64:79]
	v_mfma_f32_32x32x16_bf16 v[0:15], v[238:241], v[172:175], v[0:15]
	ds_read_b128 v[238:241], v204 offset:4672
	s_setprio 0
	global_load_dwordx4 v[168:171], v[184:185], off offset:2048
	global_load_dwordx4 v[172:175], v[186:187], off offset:2048
	s_setprio 1
	s_waitcnt lgkmcnt(1)
	v_mfma_f32_32x32x16_bf16 v[112:127], v[234:237], v[160:163], v[112:127]
	v_mfma_f32_32x32x16_bf16 v[48:63], v[234:237], v[164:167], v[48:63]
	s_waitcnt lgkmcnt(0)
	v_mfma_f32_32x32x16_bf16 v[96:111], v[238:241], v[160:163], v[96:111]
	v_mfma_f32_32x32x16_bf16 v[32:47], v[238:241], v[164:167], v[32:47]
	ds_read_b128 v[234:237], v204 offset:9280
	ds_read_b128 v[238:241], v204 offset:13888
	s_waitcnt vmcnt(7)
	ds_write_b128 v217, v[218:221]
	s_waitcnt vmcnt(6)
	ds_write_b128 v216, v[222:225]
	ds_read_b128 v[218:221], v205 offset:36960
	ds_read_b128 v[222:225], v205 offset:41568
	s_waitcnt lgkmcnt(5)
	v_mfma_f32_32x32x16_bf16 v[80:95], v[234:237], v[160:163], v[80:95]
	v_mfma_f32_32x32x16_bf16 v[16:31], v[234:237], v[164:167], v[16:31]
	ds_read_b128 v[234:237], v204 offset:96
	s_waitcnt lgkmcnt(5)
	v_mfma_f32_32x32x16_bf16 v[64:79], v[238:241], v[160:163], v[64:79]
	v_mfma_f32_32x32x16_bf16 v[0:15], v[238:241], v[164:167], v[0:15]
	ds_read_b128 v[238:241], v204 offset:4704
	s_setprio 0
	global_load_dwordx4 v[160:163], v[198:199], off offset:2048
	global_load_dwordx4 v[164:167], v[200:201], off offset:2048
	s_setprio 1
	s_waitcnt lgkmcnt(1)
	v_mfma_f32_32x32x16_bf16 v[112:127], v[234:237], v[218:221], v[112:127]
	v_mfma_f32_32x32x16_bf16 v[48:63], v[234:237], v[222:225], v[48:63]
	s_waitcnt lgkmcnt(0)
	v_mfma_f32_32x32x16_bf16 v[96:111], v[238:241], v[218:221], v[96:111]
	v_mfma_f32_32x32x16_bf16 v[32:47], v[238:241], v[222:225], v[32:47]
	ds_read_b128 v[234:237], v204 offset:9312
	ds_read_b128 v[238:241], v204 offset:13920
	s_waitcnt lgkmcnt(0)
	s_barrier
; template <bool trans>
; DI void gemm_core(const GTile& tl, const GTile& nx, bool has_next  , bool chain  , bool pre, u32x4 (&ra)[4], u32x4 (&rb)[4], char* smem, f32x16 (&acc)[2][4]) {
;     ...
;   const int nk = K / 64;
;   if (!pre) { G_LOAD(0); G_STORE(0); G_LOAD(1); }
;   for (int kt = 0; kt < nk; ++kt) {
;     __syncthreads();
;     G_COMPUTE(kt & 1, kt);
;   }
	s_waitcnt vmcnt(7)
	ds_write_b128 v215, v[226:229]
	s_waitcnt vmcnt(6)
	ds_write_b128 v215, v[230:233] offset:36864
	ds_read_b128 v[226:229], v208
	ds_read_b128 v[230:233], v208 offset:4608
	v_mfma_f32_32x32x16_bf16 v[80:95], v[234:237], v[218:221], v[80:95]
	v_mfma_f32_32x32x16_bf16 v[16:31], v[234:237], v[222:225], v[16:31]
	ds_read_b128 v[234:237], v192
	v_mfma_f32_32x32x16_bf16 v[64:79], v[238:241], v[218:221], v[64:79]
	v_mfma_f32_32x32x16_bf16 v[0:15], v[238:241], v[222:225], v[0:15]
	ds_read_b128 v[238:241], v192 offset:4608
	s_setprio 0
	global_load_dwordx4 v[218:221], v[190:191], off offset:2176
	global_load_dwordx4 v[222:225], v[188:189], off offset:2176
	s_setprio 1
	s_waitcnt lgkmcnt(1)
	v_mfma_f32_32x32x16_bf16 v[112:127], v[234:237], v[226:229], v[112:127]
	v_mfma_f32_32x32x16_bf16 v[48:63], v[234:237], v[230:233], v[48:63]
	s_waitcnt lgkmcnt(0)
	v_mfma_f32_32x32x16_bf16 v[96:111], v[238:241], v[226:229], v[96:111]
	v_mfma_f32_32x32x16_bf16 v[32:47], v[238:241], v[230:233], v[32:47]
	ds_read_b128 v[234:237], v192 offset:9216
	ds_read_b128 v[238:241], v192 offset:13824
	s_waitcnt vmcnt(7)
	ds_write_b128 v215, v[176:179] offset:9216
	s_waitcnt vmcnt(6)
	ds_write_b128 v215, v[180:183] offset:46080
	ds_read_b128 v[176:179], v208 offset:32
	ds_read_b128 v[180:183], v208 offset:4640
	s_waitcnt lgkmcnt(5)
	v_mfma_f32_32x32x16_bf16 v[80:95], v[234:237], v[226:229], v[80:95]
	v_mfma_f32_32x32x16_bf16 v[16:31], v[234:237], v[230:233], v[16:31]
	ds_read_b128 v[234:237], v192 offset:32
	s_waitcnt lgkmcnt(5)
	v_mfma_f32_32x32x16_bf16 v[64:79], v[238:241], v[226:229], v[64:79]
	v_mfma_f32_32x32x16_bf16 v[0:15], v[238:241], v[230:233], v[0:15]
	ds_read_b128 v[238:241], v192 offset:4640
	s_setprio 0
	global_load_dwordx4 v[226:229], v[194:195], off offset:2176
	global_load_dwordx4 v[230:233], v[196:197], off offset:2176
	s_setprio 1
	s_waitcnt lgkmcnt(1)
	v_mfma_f32_32x32x16_bf16 v[112:127], v[234:237], v[176:179], v[112:127]
	v_mfma_f32_32x32x16_bf16 v[48:63], v[234:237], v[180:183], v[48:63]
	s_waitcnt lgkmcnt(0)
	v_mfma_f32_32x32x16_bf16 v[96:111], v[238:241], v[176:179], v[96:111]
	v_mfma_f32_32x32x16_bf16 v[32:47], v[238:241], v[180:183], v[32:47]
	ds_read_b128 v[234:237], v192 offset:9248
	ds_read_b128 v[238:241], v192 offset:13856
	s_waitcnt vmcnt(7)
	ds_write_b128 v215, v[168:171] offset:18432
	s_waitcnt vmcnt(6)
	ds_write_b128 v215, v[172:175] offset:55296
	ds_read_b128 v[168:171], v208 offset:64
	ds_read_b128 v[172:175], v208 offset:4672
	s_waitcnt lgkmcnt(5)
	v_mfma_f32_32x32x16_bf16 v[80:95], v[234:237], v[176:179], v[80:95]
	v_mfma_f32_32x32x16_bf16 v[16:31], v[234:237], v[180:183], v[16:31]
	ds_read_b128 v[234:237], v192 offset:64
	s_waitcnt lgkmcnt(5)
	v_mfma_f32_32x32x16_bf16 v[64:79], v[238:241], v[176:179], v[64:79]
	v_mfma_f32_32x32x16_bf16 v[0:15], v[238:241], v[180:183], v[0:15]
	ds_read_b128 v[238:241], v192 offset:4672
	s_setprio 0
	global_load_dwordx4 v[176:179], v[184:185], off offset:2176
	global_load_dwordx4 v[180:183], v[186:187], off offset:2176
	s_setprio 1
	s_waitcnt lgkmcnt(1)
	v_mfma_f32_32x32x16_bf16 v[112:127], v[234:237], v[168:171], v[112:127]
	v_mfma_f32_32x32x16_bf16 v[48:63], v[234:237], v[172:175], v[48:63]
	s_waitcnt lgkmcnt(0)
	v_mfma_f32_32x32x16_bf16 v[96:111], v[238:241], v[168:171], v[96:111]
	v_mfma_f32_32x32x16_bf16 v[32:47], v[238:241], v[172:175], v[32:47]
	ds_read_b128 v[234:237], v192 offset:9280
	ds_read_b128 v[238:241], v192 offset:13888
	s_waitcnt vmcnt(7)
	ds_write_b128 v215, v[160:163] offset:27648
	s_waitcnt vmcnt(6)
	ds_write_b128 v215, v[164:167] offset:64512
	ds_read_b128 v[160:163], v208 offset:96
	ds_read_b128 v[164:167], v208 offset:4704
	s_waitcnt lgkmcnt(5)
	v_mfma_f32_32x32x16_bf16 v[80:95], v[234:237], v[168:171], v[80:95]
	v_mfma_f32_32x32x16_bf16 v[16:31], v[234:237], v[172:175], v[16:31]
	ds_read_b128 v[234:237], v192 offset:96
	s_waitcnt lgkmcnt(5)
	v_mfma_f32_32x32x16_bf16 v[64:79], v[238:241], v[168:171], v[64:79]
	v_mfma_f32_32x32x16_bf16 v[0:15], v[238:241], v[172:175], v[0:15]
	ds_read_b128 v[238:241], v192 offset:4704
	s_setprio 0
	global_load_dwordx4 v[168:171], v[198:199], off offset:2176
	global_load_dwordx4 v[172:175], v[200:201], off offset:2176
	s_setprio 1
	s_waitcnt lgkmcnt(1)
	v_mfma_f32_32x32x16_bf16 v[112:127], v[234:237], v[160:163], v[112:127]
	v_mfma_f32_32x32x16_bf16 v[48:63], v[234:237], v[164:167], v[48:63]
	s_waitcnt lgkmcnt(0)
	v_mfma_f32_32x32x16_bf16 v[96:111], v[238:241], v[160:163], v[96:111]
	v_mfma_f32_32x32x16_bf16 v[32:47], v[238:241], v[164:167], v[32:47]
	ds_read_b128 v[234:237], v192 offset:9312
	ds_read_b128 v[238:241], v192 offset:13920
	s_waitcnt lgkmcnt(0)
	s_barrier
; template <bool trans>
; DI void gemm_core(const GTile& tl, const GTile& nx, bool has_next  , bool chain  , bool pre, u32x4 (&ra)[4], u32x4 (&rb)[4], char* smem, f32x16 (&acc)[2][4]) {
;     ...
;   const int nk = K / 64;
;   if (!pre) { G_LOAD(0); G_STORE(0); G_LOAD(1); }
;   for (int kt = 0; kt < nk; ++kt) {
;     __syncthreads();
;     G_COMPUTE(kt & 1, kt);
;   }
	s_waitcnt vmcnt(7)
	ds_write_b128 v209, v[218:221]
	s_waitcnt vmcnt(6)
	ds_write_b128 v210, v[222:225]
	ds_read_b128 v[218:221], v205 offset:36864
	ds_read_b128 v[222:225], v205 offset:41472
	v_mfma_f32_32x32x16_bf16 v[80:95], v[234:237], v[160:163], v[80:95]
	v_mfma_f32_32x32x16_bf16 v[16:31], v[234:237], v[164:167], v[16:31]
	ds_read_b128 v[234:237], v204
	v_mfma_f32_32x32x16_bf16 v[64:79], v[238:241], v[160:163], v[64:79]
	v_mfma_f32_32x32x16_bf16 v[0:15], v[238:241], v[164:167], v[0:15]
	ds_read_b128 v[238:241], v204 offset:4608
	s_setprio 0
	global_load_dwordx4 v[160:163], v[190:191], off offset:2304
	global_load_dwordx4 v[164:167], v[188:189], off offset:2304
	s_setprio 1
	s_waitcnt lgkmcnt(1)
	v_mfma_f32_32x32x16_bf16 v[112:127], v[234:237], v[218:221], v[112:127]
	v_mfma_f32_32x32x16_bf16 v[48:63], v[234:237], v[222:225], v[48:63]
	s_waitcnt lgkmcnt(0)
	v_mfma_f32_32x32x16_bf16 v[96:111], v[238:241], v[218:221], v[96:111]
	v_mfma_f32_32x32x16_bf16 v[32:47], v[238:241], v[222:225], v[32:47]
	ds_read_b128 v[234:237], v204 offset:9216
	ds_read_b128 v[238:241], v204 offset:13824
	s_waitcnt vmcnt(7)
	ds_write_b128 v212, v[226:229]
	s_waitcnt vmcnt(6)
	ds_write_b128 v211, v[230:233]
	ds_read_b128 v[226:229], v205 offset:36896
	ds_read_b128 v[230:233], v205 offset:41504
	s_waitcnt lgkmcnt(5)
	v_mfma_f32_32x32x16_bf16 v[80:95], v[234:237], v[218:221], v[80:95]
	v_mfma_f32_32x32x16_bf16 v[16:31], v[234:237], v[222:225], v[16:31]
	ds_read_b128 v[234:237], v204 offset:32
	s_waitcnt lgkmcnt(5)
	v_mfma_f32_32x32x16_bf16 v[64:79], v[238:241], v[218:221], v[64:79]
	v_mfma_f32_32x32x16_bf16 v[0:15], v[238:241], v[222:225], v[0:15]
	ds_read_b128 v[238:241], v204 offset:4640
	s_setprio 0
	global_load_dwordx4 v[218:221], v[194:195], off offset:2304
	global_load_dwordx4 v[222:225], v[196:197], off offset:2304
	s_setprio 1
	s_waitcnt lgkmcnt(1)
	v_mfma_f32_32x32x16_bf16 v[112:127], v[234:237], v[226:229], v[112:127]
	v_mfma_f32_32x32x16_bf16 v[48:63], v[234:237], v[230:233], v[48:63]
	s_waitcnt lgkmcnt(0)
	v_mfma_f32_32x32x16_bf16 v[96:111], v[238:241], v[226:229], v[96:111]
	v_mfma_f32_32x32x16_bf16 v[32:47], v[238:241], v[230:233], v[32:47]
	ds_read_b128 v[234:237], v204 offset:9248
	ds_read_b128 v[238:241], v204 offset:13856
	s_waitcnt vmcnt(7)
	ds_write_b128 v214, v[176:179]
	s_waitcnt vmcnt(6)
	ds_write_b128 v213, v[180:183]
	ds_read_b128 v[176:179], v205 offset:36928
	ds_read_b128 v[180:183], v205 offset:41536
	s_waitcnt lgkmcnt(5)
	v_mfma_f32_32x32x16_bf16 v[80:95], v[234:237], v[226:229], v[80:95]
	v_mfma_f32_32x32x16_bf16 v[16:31], v[234:237], v[230:233], v[16:31]
	ds_read_b128 v[234:237], v204 offset:64
	s_waitcnt lgkmcnt(5)
	v_mfma_f32_32x32x16_bf16 v[64:79], v[238:241], v[226:229], v[64:79]
	v_mfma_f32_32x32x16_bf16 v[0:15], v[238:241], v[230:233], v[0:15]
	ds_read_b128 v[238:241], v204 offset:4672
	s_setprio 0
	global_load_dwordx4 v[226:229], v[184:185], off offset:2304
	global_load_dwordx4 v[230:233], v[186:187], off offset:2304
	s_setprio 1
	s_waitcnt lgkmcnt(1)
	v_mfma_f32_32x32x16_bf16 v[112:127], v[234:237], v[176:179], v[112:127]
	v_mfma_f32_32x32x16_bf16 v[48:63], v[234:237], v[180:183], v[48:63]
	s_waitcnt lgkmcnt(0)
	v_mfma_f32_32x32x16_bf16 v[96:111], v[238:241], v[176:179], v[96:111]
	v_mfma_f32_32x32x16_bf16 v[32:47], v[238:241], v[180:183], v[32:47]
	ds_read_b128 v[234:237], v204 offset:9280
	ds_read_b128 v[238:241], v204 offset:13888
	s_waitcnt vmcnt(7)
	ds_write_b128 v217, v[168:171]
	s_waitcnt vmcnt(6)
	ds_write_b128 v216, v[172:175]
	ds_read_b128 v[168:171], v205 offset:36960
	ds_read_b128 v[172:175], v205 offset:41568
	s_waitcnt lgkmcnt(5)
	v_mfma_f32_32x32x16_bf16 v[80:95], v[234:237], v[176:179], v[80:95]
	v_mfma_f32_32x32x16_bf16 v[16:31], v[234:237], v[180:183], v[16:31]
	ds_read_b128 v[234:237], v204 offset:96
	s_waitcnt lgkmcnt(5)
	v_mfma_f32_32x32x16_bf16 v[64:79], v[238:241], v[176:179], v[64:79]
	v_mfma_f32_32x32x16_bf16 v[0:15], v[238:241], v[180:183], v[0:15]
	ds_read_b128 v[238:241], v204 offset:4704
	s_setprio 0
	global_load_dwordx4 v[176:179], v[198:199], off offset:2304
	global_load_dwordx4 v[180:183], v[200:201], off offset:2304
	s_setprio 1
	s_waitcnt lgkmcnt(1)
	v_mfma_f32_32x32x16_bf16 v[112:127], v[234:237], v[168:171], v[112:127]
	v_mfma_f32_32x32x16_bf16 v[48:63], v[234:237], v[172:175], v[48:63]
	s_waitcnt lgkmcnt(0)
	v_mfma_f32_32x32x16_bf16 v[96:111], v[238:241], v[168:171], v[96:111]
	v_mfma_f32_32x32x16_bf16 v[32:47], v[238:241], v[172:175], v[32:47]
	ds_read_b128 v[234:237], v204 offset:9312
	ds_read_b128 v[238:241], v204 offset:13920
	s_waitcnt lgkmcnt(0)
	s_barrier
; template <bool trans>
; DI void gemm_core(const GTile& tl, const GTile& nx, bool has_next  , bool chain  , bool pre, u32x4 (&ra)[4], u32x4 (&rb)[4], char* smem, f32x16 (&acc)[2][4]) {
;     ...
;   const int nk = K / 64;
;   if (!pre) { G_LOAD(0); G_STORE(0); G_LOAD(1); }
;   for (int kt = 0; kt < nk; ++kt) {
;     __syncthreads();
;     G_COMPUTE(kt & 1, kt);
;   }
	s_waitcnt vmcnt(7)
	ds_write_b128 v215, v[160:163]
	s_waitcnt vmcnt(6)
	ds_write_b128 v215, v[164:167] offset:36864
	ds_read_b128 v[160:163], v208
	ds_read_b128 v[164:167], v208 offset:4608
	v_mfma_f32_32x32x16_bf16 v[80:95], v[234:237], v[168:171], v[80:95]
	v_mfma_f32_32x32x16_bf16 v[16:31], v[234:237], v[172:175], v[16:31]
	ds_read_b128 v[234:237], v192
	v_mfma_f32_32x32x16_bf16 v[64:79], v[238:241], v[168:171], v[64:79]
	v_mfma_f32_32x32x16_bf16 v[0:15], v[238:241], v[172:175], v[0:15]
	ds_read_b128 v[238:241], v192 offset:4608
	s_setprio 0
	global_load_dwordx4 v[168:171], v[190:191], off offset:2432
	global_load_dwordx4 v[172:175], v[188:189], off offset:2432
	s_setprio 1
	s_waitcnt lgkmcnt(1)
	v_mfma_f32_32x32x16_bf16 v[112:127], v[234:237], v[160:163], v[112:127]
	v_mfma_f32_32x32x16_bf16 v[48:63], v[234:237], v[164:167], v[48:63]
	s_waitcnt lgkmcnt(0)
	v_mfma_f32_32x32x16_bf16 v[96:111], v[238:241], v[160:163], v[96:111]
	v_mfma_f32_32x32x16_bf16 v[32:47], v[238:241], v[164:167], v[32:47]
	ds_read_b128 v[234:237], v192 offset:9216
	ds_read_b128 v[238:241], v192 offset:13824
	s_waitcnt vmcnt(7)
	ds_write_b128 v215, v[218:221] offset:9216
	s_waitcnt vmcnt(6)
	ds_write_b128 v215, v[222:225] offset:46080
	ds_read_b128 v[218:221], v208 offset:32
	ds_read_b128 v[222:225], v208 offset:4640
	s_waitcnt lgkmcnt(5)
	v_mfma_f32_32x32x16_bf16 v[80:95], v[234:237], v[160:163], v[80:95]
	v_mfma_f32_32x32x16_bf16 v[16:31], v[234:237], v[164:167], v[16:31]
	ds_read_b128 v[234:237], v192 offset:32
	s_waitcnt lgkmcnt(5)
	v_mfma_f32_32x32x16_bf16 v[64:79], v[238:241], v[160:163], v[64:79]
	v_mfma_f32_32x32x16_bf16 v[0:15], v[238:241], v[164:167], v[0:15]
	ds_read_b128 v[238:241], v192 offset:4640
	s_setprio 0
	global_load_dwordx4 v[160:163], v[194:195], off offset:2432
	global_load_dwordx4 v[164:167], v[196:197], off offset:2432
	s_setprio 1
	s_waitcnt lgkmcnt(1)
	v_mfma_f32_32x32x16_bf16 v[112:127], v[234:237], v[218:221], v[112:127]
	v_mfma_f32_32x32x16_bf16 v[48:63], v[234:237], v[222:225], v[48:63]
	s_waitcnt lgkmcnt(0)
	v_mfma_f32_32x32x16_bf16 v[96:111], v[238:241], v[218:221], v[96:111]
	v_mfma_f32_32x32x16_bf16 v[32:47], v[238:241], v[222:225], v[32:47]
	ds_read_b128 v[234:237], v192 offset:9248
	ds_read_b128 v[238:241], v192 offset:13856
	s_waitcnt vmcnt(7)
	ds_write_b128 v215, v[226:229] offset:18432
	s_waitcnt vmcnt(6)
	ds_write_b128 v215, v[230:233] offset:55296
	ds_read_b128 v[226:229], v208 offset:64
	ds_read_b128 v[230:233], v208 offset:4672
	s_waitcnt lgkmcnt(5)
	v_mfma_f32_32x32x16_bf16 v[80:95], v[234:237], v[218:221], v[80:95]
	v_mfma_f32_32x32x16_bf16 v[16:31], v[234:237], v[222:225], v[16:31]
	ds_read_b128 v[234:237], v192 offset:64
	s_waitcnt lgkmcnt(5)
	v_mfma_f32_32x32x16_bf16 v[64:79], v[238:241], v[218:221], v[64:79]
	v_mfma_f32_32x32x16_bf16 v[0:15], v[238:241], v[222:225], v[0:15]
	ds_read_b128 v[238:241], v192 offset:4672
	s_setprio 0
	global_load_dwordx4 v[218:221], v[184:185], off offset:2432
	global_load_dwordx4 v[222:225], v[186:187], off offset:2432
	s_setprio 1
	s_waitcnt lgkmcnt(1)
	v_mfma_f32_32x32x16_bf16 v[112:127], v[234:237], v[226:229], v[112:127]
	v_mfma_f32_32x32x16_bf16 v[48:63], v[234:237], v[230:233], v[48:63]
	s_waitcnt lgkmcnt(0)
	v_mfma_f32_32x32x16_bf16 v[96:111], v[238:241], v[226:229], v[96:111]
	v_mfma_f32_32x32x16_bf16 v[32:47], v[238:241], v[230:233], v[32:47]
	ds_read_b128 v[234:237], v192 offset:9280
	ds_read_b128 v[238:241], v192 offset:13888
	s_waitcnt vmcnt(7)
	ds_write_b128 v215, v[176:179] offset:27648
	s_waitcnt vmcnt(6)
	ds_write_b128 v215, v[180:183] offset:64512
	ds_read_b128 v[176:179], v208 offset:96
	ds_read_b128 v[180:183], v208 offset:4704
	s_waitcnt lgkmcnt(5)
	v_mfma_f32_32x32x16_bf16 v[80:95], v[234:237], v[226:229], v[80:95]
	v_mfma_f32_32x32x16_bf16 v[16:31], v[234:237], v[230:233], v[16:31]
	ds_read_b128 v[234:237], v192 offset:96
	s_waitcnt lgkmcnt(5)
	v_mfma_f32_32x32x16_bf16 v[64:79], v[238:241], v[226:229], v[64:79]
	v_mfma_f32_32x32x16_bf16 v[0:15], v[238:241], v[230:233], v[0:15]
	ds_read_b128 v[238:241], v192 offset:4704
	s_setprio 0
	global_load_dwordx4 v[226:229], v[198:199], off offset:2432
	global_load_dwordx4 v[230:233], v[200:201], off offset:2432
	s_setprio 1
	s_waitcnt lgkmcnt(1)
	v_mfma_f32_32x32x16_bf16 v[112:127], v[234:237], v[176:179], v[112:127]
	v_mfma_f32_32x32x16_bf16 v[48:63], v[234:237], v[180:183], v[48:63]
	s_waitcnt lgkmcnt(0)
	v_mfma_f32_32x32x16_bf16 v[96:111], v[238:241], v[176:179], v[96:111]
	v_mfma_f32_32x32x16_bf16 v[32:47], v[238:241], v[180:183], v[32:47]
	ds_read_b128 v[234:237], v192 offset:9312
	ds_read_b128 v[238:241], v192 offset:13920
	s_waitcnt lgkmcnt(0)
	s_barrier
; template <bool trans>
; DI void gemm_core(const GTile& tl, const GTile& nx, bool has_next  , bool chain  , bool pre, u32x4 (&ra)[4], u32x4 (&rb)[4], char* smem, f32x16 (&acc)[2][4]) {
;     ...
;   const int nk = K / 64;
;   if (!pre) { G_LOAD(0); G_STORE(0); G_LOAD(1); }
;   for (int kt = 0; kt < nk; ++kt) {
;     __syncthreads();
;     G_COMPUTE(kt & 1, kt);
;   }
	s_waitcnt vmcnt(7)
	ds_write_b128 v209, v[168:171]
	s_waitcnt vmcnt(6)
	ds_write_b128 v210, v[172:175]
	ds_read_b128 v[168:171], v205 offset:36864
	ds_read_b128 v[172:175], v205 offset:41472
	v_mfma_f32_32x32x16_bf16 v[80:95], v[234:237], v[176:179], v[80:95]
	v_mfma_f32_32x32x16_bf16 v[16:31], v[234:237], v[180:183], v[16:31]
	ds_read_b128 v[234:237], v204
	v_mfma_f32_32x32x16_bf16 v[64:79], v[238:241], v[176:179], v[64:79]
	v_mfma_f32_32x32x16_bf16 v[0:15], v[238:241], v[180:183], v[0:15]
	ds_read_b128 v[238:241], v204 offset:4608
	s_setprio 0
	global_load_dwordx4 v[176:179], v[190:191], off offset:2560
	global_load_dwordx4 v[180:183], v[188:189], off offset:2560
	s_setprio 1
	s_waitcnt lgkmcnt(1)
	v_mfma_f32_32x32x16_bf16 v[112:127], v[234:237], v[168:171], v[112:127]
	v_mfma_f32_32x32x16_bf16 v[48:63], v[234:237], v[172:175], v[48:63]
	s_waitcnt lgkmcnt(0)
	v_mfma_f32_32x32x16_bf16 v[96:111], v[238:241], v[168:171], v[96:111]
	v_mfma_f32_32x32x16_bf16 v[32:47], v[238:241], v[172:175], v[32:47]
	ds_read_b128 v[234:237], v204 offset:9216
	ds_read_b128 v[238:241], v204 offset:13824
	s_waitcnt vmcnt(7)
	ds_write_b128 v212, v[160:163]
	s_waitcnt vmcnt(6)
	ds_write_b128 v211, v[164:167]
	ds_read_b128 v[160:163], v205 offset:36896
	ds_read_b128 v[164:167], v205 offset:41504
	s_waitcnt lgkmcnt(5)
	v_mfma_f32_32x32x16_bf16 v[80:95], v[234:237], v[168:171], v[80:95]
	v_mfma_f32_32x32x16_bf16 v[16:31], v[234:237], v[172:175], v[16:31]
	ds_read_b128 v[234:237], v204 offset:32
	s_waitcnt lgkmcnt(5)
	v_mfma_f32_32x32x16_bf16 v[64:79], v[238:241], v[168:171], v[64:79]
	v_mfma_f32_32x32x16_bf16 v[0:15], v[238:241], v[172:175], v[0:15]
	ds_read_b128 v[238:241], v204 offset:4640
	s_setprio 0
	global_load_dwordx4 v[168:171], v[194:195], off offset:2560
	global_load_dwordx4 v[172:175], v[196:197], off offset:2560
	s_setprio 1
	s_waitcnt lgkmcnt(1)
	v_mfma_f32_32x32x16_bf16 v[112:127], v[234:237], v[160:163], v[112:127]
	v_mfma_f32_32x32x16_bf16 v[48:63], v[234:237], v[164:167], v[48:63]
	s_waitcnt lgkmcnt(0)
	v_mfma_f32_32x32x16_bf16 v[96:111], v[238:241], v[160:163], v[96:111]
	v_mfma_f32_32x32x16_bf16 v[32:47], v[238:241], v[164:167], v[32:47]
	ds_read_b128 v[234:237], v204 offset:9248
	ds_read_b128 v[238:241], v204 offset:13856
	s_waitcnt vmcnt(7)
	ds_write_b128 v214, v[218:221]
	s_waitcnt vmcnt(6)
	ds_write_b128 v213, v[222:225]
	ds_read_b128 v[218:221], v205 offset:36928
	ds_read_b128 v[222:225], v205 offset:41536
	s_waitcnt lgkmcnt(5)
	v_mfma_f32_32x32x16_bf16 v[80:95], v[234:237], v[160:163], v[80:95]
	v_mfma_f32_32x32x16_bf16 v[16:31], v[234:237], v[164:167], v[16:31]
	ds_read_b128 v[234:237], v204 offset:64
	s_waitcnt lgkmcnt(5)
	v_mfma_f32_32x32x16_bf16 v[64:79], v[238:241], v[160:163], v[64:79]
	v_mfma_f32_32x32x16_bf16 v[0:15], v[238:241], v[164:167], v[0:15]
	ds_read_b128 v[238:241], v204 offset:4672
	s_setprio 0
	global_load_dwordx4 v[160:163], v[184:185], off offset:2560
	global_load_dwordx4 v[164:167], v[186:187], off offset:2560
	s_setprio 1
	s_waitcnt lgkmcnt(1)
	v_mfma_f32_32x32x16_bf16 v[112:127], v[234:237], v[218:221], v[112:127]
	v_mfma_f32_32x32x16_bf16 v[48:63], v[234:237], v[222:225], v[48:63]
	s_waitcnt lgkmcnt(0)
	v_mfma_f32_32x32x16_bf16 v[96:111], v[238:241], v[218:221], v[96:111]
	v_mfma_f32_32x32x16_bf16 v[32:47], v[238:241], v[222:225], v[32:47]
	ds_read_b128 v[234:237], v204 offset:9280
	ds_read_b128 v[238:241], v204 offset:13888
	s_waitcnt vmcnt(7)
	ds_write_b128 v217, v[226:229]
	s_waitcnt vmcnt(6)
	ds_write_b128 v216, v[230:233]
	ds_read_b128 v[226:229], v205 offset:36960
	ds_read_b128 v[230:233], v205 offset:41568
	s_waitcnt lgkmcnt(5)
	v_mfma_f32_32x32x16_bf16 v[80:95], v[234:237], v[218:221], v[80:95]
	v_mfma_f32_32x32x16_bf16 v[16:31], v[234:237], v[222:225], v[16:31]
	ds_read_b128 v[234:237], v204 offset:96
	s_waitcnt lgkmcnt(5)
	v_mfma_f32_32x32x16_bf16 v[64:79], v[238:241], v[218:221], v[64:79]
	v_mfma_f32_32x32x16_bf16 v[0:15], v[238:241], v[222:225], v[0:15]
	ds_read_b128 v[238:241], v204 offset:4704
	s_setprio 0
	global_load_dwordx4 v[218:221], v[198:199], off offset:2560
	global_load_dwordx4 v[222:225], v[200:201], off offset:2560
	s_setprio 1
	s_waitcnt lgkmcnt(1)
	v_mfma_f32_32x32x16_bf16 v[112:127], v[234:237], v[226:229], v[112:127]
	v_mfma_f32_32x32x16_bf16 v[48:63], v[234:237], v[230:233], v[48:63]
	s_waitcnt lgkmcnt(0)
	v_mfma_f32_32x32x16_bf16 v[96:111], v[238:241], v[226:229], v[96:111]
	v_mfma_f32_32x32x16_bf16 v[32:47], v[238:241], v[230:233], v[32:47]
	ds_read_b128 v[234:237], v204 offset:9312
	ds_read_b128 v[238:241], v204 offset:13920
	s_waitcnt lgkmcnt(0)
	s_barrier
; template <bool trans>
; DI void gemm_core(const GTile& tl, const GTile& nx, bool has_next  , bool chain  , bool pre, u32x4 (&ra)[4], u32x4 (&rb)[4], char* smem, f32x16 (&acc)[2][4]) {
;     ...
;   const int nk = K / 64;
;   if (!pre) { G_LOAD(0); G_STORE(0); G_LOAD(1); }
;   for (int kt = 0; kt < nk; ++kt) {
;     __syncthreads();
;     G_COMPUTE(kt & 1, kt);
;   }
	s_waitcnt vmcnt(7)
	ds_write_b128 v215, v[176:179]
	s_waitcnt vmcnt(6)
	ds_write_b128 v215, v[180:183] offset:36864
	ds_read_b128 v[176:179], v208
	ds_read_b128 v[180:183], v208 offset:4608
	v_mfma_f32_32x32x16_bf16 v[80:95], v[234:237], v[226:229], v[80:95]
	v_mfma_f32_32x32x16_bf16 v[16:31], v[234:237], v[230:233], v[16:31]
	ds_read_b128 v[234:237], v192
	v_mfma_f32_32x32x16_bf16 v[64:79], v[238:241], v[226:229], v[64:79]
	v_mfma_f32_32x32x16_bf16 v[0:15], v[238:241], v[230:233], v[0:15]
	ds_read_b128 v[238:241], v192 offset:4608
	s_setprio 0
	global_load_dwordx4 v[226:229], v[190:191], off offset:2688
	global_load_dwordx4 v[230:233], v[188:189], off offset:2688
	s_setprio 1
	s_waitcnt lgkmcnt(1)
	v_mfma_f32_32x32x16_bf16 v[112:127], v[234:237], v[176:179], v[112:127]
	v_mfma_f32_32x32x16_bf16 v[48:63], v[234:237], v[180:183], v[48:63]
	s_waitcnt lgkmcnt(0)
	v_mfma_f32_32x32x16_bf16 v[96:111], v[238:241], v[176:179], v[96:111]
	v_mfma_f32_32x32x16_bf16 v[32:47], v[238:241], v[180:183], v[32:47]
	ds_read_b128 v[234:237], v192 offset:9216
	ds_read_b128 v[238:241], v192 offset:13824
	s_waitcnt vmcnt(7)
	ds_write_b128 v215, v[168:171] offset:9216
	s_waitcnt vmcnt(6)
	ds_write_b128 v215, v[172:175] offset:46080
	ds_read_b128 v[168:171], v208 offset:32
	ds_read_b128 v[172:175], v208 offset:4640
	s_waitcnt lgkmcnt(5)
	v_mfma_f32_32x32x16_bf16 v[80:95], v[234:237], v[176:179], v[80:95]
	v_mfma_f32_32x32x16_bf16 v[16:31], v[234:237], v[180:183], v[16:31]
	ds_read_b128 v[234:237], v192 offset:32
	s_waitcnt lgkmcnt(5)
	v_mfma_f32_32x32x16_bf16 v[64:79], v[238:241], v[176:179], v[64:79]
	v_mfma_f32_32x32x16_bf16 v[0:15], v[238:241], v[180:183], v[0:15]
	ds_read_b128 v[238:241], v192 offset:4640
	s_setprio 0
	global_load_dwordx4 v[176:179], v[194:195], off offset:2688
	global_load_dwordx4 v[180:183], v[196:197], off offset:2688
	s_setprio 1
	s_waitcnt lgkmcnt(1)
	v_mfma_f32_32x32x16_bf16 v[112:127], v[234:237], v[168:171], v[112:127]
	v_mfma_f32_32x32x16_bf16 v[48:63], v[234:237], v[172:175], v[48:63]
	s_waitcnt lgkmcnt(0)
	v_mfma_f32_32x32x16_bf16 v[96:111], v[238:241], v[168:171], v[96:111]
	v_mfma_f32_32x32x16_bf16 v[32:47], v[238:241], v[172:175], v[32:47]
	ds_read_b128 v[234:237], v192 offset:9248
	ds_read_b128 v[238:241], v192 offset:13856
	s_waitcnt vmcnt(7)
	ds_write_b128 v215, v[160:163] offset:18432
	s_waitcnt vmcnt(6)
	ds_write_b128 v215, v[164:167] offset:55296
	ds_read_b128 v[160:163], v208 offset:64
	ds_read_b128 v[164:167], v208 offset:4672
	s_waitcnt lgkmcnt(5)
	v_mfma_f32_32x32x16_bf16 v[80:95], v[234:237], v[168:171], v[80:95]
	v_mfma_f32_32x32x16_bf16 v[16:31], v[234:237], v[172:175], v[16:31]
	ds_read_b128 v[234:237], v192 offset:64
	s_waitcnt lgkmcnt(5)
	v_mfma_f32_32x32x16_bf16 v[64:79], v[238:241], v[168:171], v[64:79]
	v_mfma_f32_32x32x16_bf16 v[0:15], v[238:241], v[172:175], v[0:15]
	ds_read_b128 v[238:241], v192 offset:4672
	s_setprio 0
	global_load_dwordx4 v[168:171], v[184:185], off offset:2688
	global_load_dwordx4 v[172:175], v[186:187], off offset:2688
	s_setprio 1
	s_waitcnt lgkmcnt(1)
	v_mfma_f32_32x32x16_bf16 v[112:127], v[234:237], v[160:163], v[112:127]
	v_mfma_f32_32x32x16_bf16 v[48:63], v[234:237], v[164:167], v[48:63]
	s_waitcnt lgkmcnt(0)
	v_mfma_f32_32x32x16_bf16 v[96:111], v[238:241], v[160:163], v[96:111]
	v_mfma_f32_32x32x16_bf16 v[32:47], v[238:241], v[164:167], v[32:47]
	ds_read_b128 v[234:237], v192 offset:9280
	ds_read_b128 v[238:241], v192 offset:13888
	s_waitcnt vmcnt(7)
	ds_write_b128 v215, v[218:221] offset:27648
	s_waitcnt vmcnt(6)
	ds_write_b128 v215, v[222:225] offset:64512
	ds_read_b128 v[218:221], v208 offset:96
	ds_read_b128 v[222:225], v208 offset:4704
	s_waitcnt lgkmcnt(5)
	v_mfma_f32_32x32x16_bf16 v[80:95], v[234:237], v[160:163], v[80:95]
	v_mfma_f32_32x32x16_bf16 v[16:31], v[234:237], v[164:167], v[16:31]
	ds_read_b128 v[234:237], v192 offset:96
	s_waitcnt lgkmcnt(5)
	v_mfma_f32_32x32x16_bf16 v[64:79], v[238:241], v[160:163], v[64:79]
	v_mfma_f32_32x32x16_bf16 v[0:15], v[238:241], v[164:167], v[0:15]
	ds_read_b128 v[238:241], v192 offset:4704
	s_setprio 0
	global_load_dwordx4 v[160:163], v[198:199], off offset:2688
	global_load_dwordx4 v[164:167], v[200:201], off offset:2688
	s_setprio 1
	s_waitcnt lgkmcnt(1)
	v_mfma_f32_32x32x16_bf16 v[112:127], v[234:237], v[218:221], v[112:127]
	v_mfma_f32_32x32x16_bf16 v[48:63], v[234:237], v[222:225], v[48:63]
	s_waitcnt lgkmcnt(0)
	v_mfma_f32_32x32x16_bf16 v[96:111], v[238:241], v[218:221], v[96:111]
	v_mfma_f32_32x32x16_bf16 v[32:47], v[238:241], v[222:225], v[32:47]
	ds_read_b128 v[234:237], v192 offset:9312
	ds_read_b128 v[238:241], v192 offset:13920
	s_waitcnt lgkmcnt(0)
	s_barrier
; template <bool trans>
; DI void gemm_core(const GTile& tl, const GTile& nx, bool has_next  , bool chain  , bool pre, u32x4 (&ra)[4], u32x4 (&rb)[4], char* smem, f32x16 (&acc)[2][4]) {
;     ...
;   const int nk = K / 64;
;   if (!pre) { G_LOAD(0); G_STORE(0); G_LOAD(1); }
;   for (int kt = 0; kt < nk; ++kt) {
;     __syncthreads();
;     G_COMPUTE(kt & 1, kt);
;   }
	s_waitcnt vmcnt(7)
	ds_write_b128 v209, v[226:229]
	s_waitcnt vmcnt(6)
	ds_write_b128 v210, v[230:233]
	ds_read_b128 v[226:229], v205 offset:36864
	ds_read_b128 v[230:233], v205 offset:41472
	v_mfma_f32_32x32x16_bf16 v[80:95], v[234:237], v[218:221], v[80:95]
	v_mfma_f32_32x32x16_bf16 v[16:31], v[234:237], v[222:225], v[16:31]
	ds_read_b128 v[234:237], v204
	v_mfma_f32_32x32x16_bf16 v[64:79], v[238:241], v[218:221], v[64:79]
	v_mfma_f32_32x32x16_bf16 v[0:15], v[238:241], v[222:225], v[0:15]
	ds_read_b128 v[238:241], v204 offset:4608
	s_setprio 0
	global_load_dwordx4 v[218:221], v[190:191], off offset:2816
	global_load_dwordx4 v[222:225], v[188:189], off offset:2816
	s_setprio 1
	s_waitcnt lgkmcnt(1)
	v_mfma_f32_32x32x16_bf16 v[112:127], v[234:237], v[226:229], v[112:127]
	v_mfma_f32_32x32x16_bf16 v[48:63], v[234:237], v[230:233], v[48:63]
	s_waitcnt lgkmcnt(0)
	v_mfma_f32_32x32x16_bf16 v[96:111], v[238:241], v[226:229], v[96:111]
	v_mfma_f32_32x32x16_bf16 v[32:47], v[238:241], v[230:233], v[32:47]
	ds_read_b128 v[234:237], v204 offset:9216
	ds_read_b128 v[238:241], v204 offset:13824
	s_waitcnt vmcnt(7)
	ds_write_b128 v212, v[176:179]
	s_waitcnt vmcnt(6)
	ds_write_b128 v211, v[180:183]
	ds_read_b128 v[176:179], v205 offset:36896
	ds_read_b128 v[180:183], v205 offset:41504
	s_waitcnt lgkmcnt(5)
	v_mfma_f32_32x32x16_bf16 v[80:95], v[234:237], v[226:229], v[80:95]
	v_mfma_f32_32x32x16_bf16 v[16:31], v[234:237], v[230:233], v[16:31]
	ds_read_b128 v[234:237], v204 offset:32
	s_waitcnt lgkmcnt(5)
	v_mfma_f32_32x32x16_bf16 v[64:79], v[238:241], v[226:229], v[64:79]
	v_mfma_f32_32x32x16_bf16 v[0:15], v[238:241], v[230:233], v[0:15]
	ds_read_b128 v[238:241], v204 offset:4640
	s_setprio 0
	global_load_dwordx4 v[226:229], v[194:195], off offset:2816
	global_load_dwordx4 v[230:233], v[196:197], off offset:2816
	s_setprio 1
	s_waitcnt lgkmcnt(1)
	v_mfma_f32_32x32x16_bf16 v[112:127], v[234:237], v[176:179], v[112:127]
	v_mfma_f32_32x32x16_bf16 v[48:63], v[234:237], v[180:183], v[48:63]
	s_waitcnt lgkmcnt(0)
	v_mfma_f32_32x32x16_bf16 v[96:111], v[238:241], v[176:179], v[96:111]
	v_mfma_f32_32x32x16_bf16 v[32:47], v[238:241], v[180:183], v[32:47]
	ds_read_b128 v[234:237], v204 offset:9248
	ds_read_b128 v[238:241], v204 offset:13856
	s_waitcnt vmcnt(7)
	ds_write_b128 v214, v[168:171]
	s_waitcnt vmcnt(6)
	ds_write_b128 v213, v[172:175]
	ds_read_b128 v[168:171], v205 offset:36928
	ds_read_b128 v[172:175], v205 offset:41536
	s_waitcnt lgkmcnt(5)
	v_mfma_f32_32x32x16_bf16 v[80:95], v[234:237], v[176:179], v[80:95]
	v_mfma_f32_32x32x16_bf16 v[16:31], v[234:237], v[180:183], v[16:31]
	ds_read_b128 v[234:237], v204 offset:64
	s_waitcnt lgkmcnt(5)
	v_mfma_f32_32x32x16_bf16 v[64:79], v[238:241], v[176:179], v[64:79]
	v_mfma_f32_32x32x16_bf16 v[0:15], v[238:241], v[180:183], v[0:15]
	ds_read_b128 v[238:241], v204 offset:4672
	s_setprio 0
	global_load_dwordx4 v[176:179], v[184:185], off offset:2816
	global_load_dwordx4 v[180:183], v[186:187], off offset:2816
	s_setprio 1
	s_waitcnt lgkmcnt(1)
	v_mfma_f32_32x32x16_bf16 v[112:127], v[234:237], v[168:171], v[112:127]
	v_mfma_f32_32x32x16_bf16 v[48:63], v[234:237], v[172:175], v[48:63]
	s_waitcnt lgkmcnt(0)
	v_mfma_f32_32x32x16_bf16 v[96:111], v[238:241], v[168:171], v[96:111]
	v_mfma_f32_32x32x16_bf16 v[32:47], v[238:241], v[172:175], v[32:47]
	ds_read_b128 v[234:237], v204 offset:9280
	ds_read_b128 v[238:241], v204 offset:13888
	s_waitcnt vmcnt(7)
	ds_write_b128 v217, v[160:163]
	s_waitcnt vmcnt(6)
	ds_write_b128 v216, v[164:167]
	ds_read_b128 v[160:163], v205 offset:36960
	ds_read_b128 v[164:167], v205 offset:41568
	s_waitcnt lgkmcnt(5)
	v_mfma_f32_32x32x16_bf16 v[80:95], v[234:237], v[168:171], v[80:95]
	v_mfma_f32_32x32x16_bf16 v[16:31], v[234:237], v[172:175], v[16:31]
	ds_read_b128 v[234:237], v204 offset:96
	s_waitcnt lgkmcnt(5)
	v_mfma_f32_32x32x16_bf16 v[64:79], v[238:241], v[168:171], v[64:79]
	v_mfma_f32_32x32x16_bf16 v[0:15], v[238:241], v[172:175], v[0:15]
	ds_read_b128 v[238:241], v204 offset:4704
	s_setprio 0
	global_load_dwordx4 v[168:171], v[198:199], off offset:2816
	global_load_dwordx4 v[172:175], v[200:201], off offset:2816
	s_setprio 1
	s_waitcnt lgkmcnt(1)
	v_mfma_f32_32x32x16_bf16 v[112:127], v[234:237], v[160:163], v[112:127]
	v_mfma_f32_32x32x16_bf16 v[48:63], v[234:237], v[164:167], v[48:63]
	s_waitcnt lgkmcnt(0)
	v_mfma_f32_32x32x16_bf16 v[96:111], v[238:241], v[160:163], v[96:111]
	v_mfma_f32_32x32x16_bf16 v[32:47], v[238:241], v[164:167], v[32:47]
	ds_read_b128 v[234:237], v204 offset:9312
	ds_read_b128 v[238:241], v204 offset:13920
	s_waitcnt lgkmcnt(0)
	s_barrier
; template <bool trans>
; DI void gemm_core(const GTile& tl, const GTile& nx, bool has_next  , bool chain  , bool pre, u32x4 (&ra)[4], u32x4 (&rb)[4], char* smem, f32x16 (&acc)[2][4]) {
;     ...
;   const int nk = K / 64;
;   if (!pre) { G_LOAD(0); G_STORE(0); G_LOAD(1); }
;   for (int kt = 0; kt < nk; ++kt) {
;     __syncthreads();
;     G_COMPUTE(kt & 1, kt);
;   }
	s_waitcnt vmcnt(7)
	ds_write_b128 v215, v[218:221]
	s_waitcnt vmcnt(6)
	ds_write_b128 v215, v[222:225] offset:36864
	ds_read_b128 v[218:221], v208
	ds_read_b128 v[222:225], v208 offset:4608
	v_mfma_f32_32x32x16_bf16 v[80:95], v[234:237], v[160:163], v[80:95]
	v_mfma_f32_32x32x16_bf16 v[16:31], v[234:237], v[164:167], v[16:31]
	ds_read_b128 v[234:237], v192
	v_mfma_f32_32x32x16_bf16 v[64:79], v[238:241], v[160:163], v[64:79]
	v_mfma_f32_32x32x16_bf16 v[0:15], v[238:241], v[164:167], v[0:15]
	ds_read_b128 v[238:241], v192 offset:4608
	s_setprio 0
	global_load_dwordx4 v[160:163], v[190:191], off offset:2944
	global_load_dwordx4 v[164:167], v[188:189], off offset:2944
	s_setprio 1
	s_waitcnt lgkmcnt(1)
	v_mfma_f32_32x32x16_bf16 v[112:127], v[234:237], v[218:221], v[112:127]
	v_mfma_f32_32x32x16_bf16 v[48:63], v[234:237], v[222:225], v[48:63]
	s_waitcnt lgkmcnt(0)
	v_mfma_f32_32x32x16_bf16 v[96:111], v[238:241], v[218:221], v[96:111]
	v_mfma_f32_32x32x16_bf16 v[32:47], v[238:241], v[222:225], v[32:47]
	ds_read_b128 v[234:237], v192 offset:9216
	ds_read_b128 v[238:241], v192 offset:13824
	s_waitcnt vmcnt(7)
	ds_write_b128 v215, v[226:229] offset:9216
	s_waitcnt vmcnt(6)
	ds_write_b128 v215, v[230:233] offset:46080
	ds_read_b128 v[226:229], v208 offset:32
	ds_read_b128 v[230:233], v208 offset:4640
	s_waitcnt lgkmcnt(5)
	v_mfma_f32_32x32x16_bf16 v[80:95], v[234:237], v[218:221], v[80:95]
	v_mfma_f32_32x32x16_bf16 v[16:31], v[234:237], v[222:225], v[16:31]
	ds_read_b128 v[234:237], v192 offset:32
	s_waitcnt lgkmcnt(5)
	v_mfma_f32_32x32x16_bf16 v[64:79], v[238:241], v[218:221], v[64:79]
	v_mfma_f32_32x32x16_bf16 v[0:15], v[238:241], v[222:225], v[0:15]
	ds_read_b128 v[238:241], v192 offset:4640
	s_setprio 0
	global_load_dwordx4 v[218:221], v[194:195], off offset:2944
	global_load_dwordx4 v[222:225], v[196:197], off offset:2944
	s_setprio 1
	s_waitcnt lgkmcnt(1)
	v_mfma_f32_32x32x16_bf16 v[112:127], v[234:237], v[226:229], v[112:127]
	v_mfma_f32_32x32x16_bf16 v[48:63], v[234:237], v[230:233], v[48:63]
	s_waitcnt lgkmcnt(0)
	v_mfma_f32_32x32x16_bf16 v[96:111], v[238:241], v[226:229], v[96:111]
	v_mfma_f32_32x32x16_bf16 v[32:47], v[238:241], v[230:233], v[32:47]
	ds_read_b128 v[234:237], v192 offset:9248
	ds_read_b128 v[238:241], v192 offset:13856
	s_waitcnt vmcnt(7)
	ds_write_b128 v215, v[176:179] offset:18432
	s_waitcnt vmcnt(6)
	ds_write_b128 v215, v[180:183] offset:55296
	ds_read_b128 v[176:179], v208 offset:64
	ds_read_b128 v[180:183], v208 offset:4672
	s_waitcnt lgkmcnt(5)
	v_mfma_f32_32x32x16_bf16 v[80:95], v[234:237], v[226:229], v[80:95]
	v_mfma_f32_32x32x16_bf16 v[16:31], v[234:237], v[230:233], v[16:31]
	ds_read_b128 v[234:237], v192 offset:64
	s_waitcnt lgkmcnt(5)
	v_mfma_f32_32x32x16_bf16 v[64:79], v[238:241], v[226:229], v[64:79]
	v_mfma_f32_32x32x16_bf16 v[0:15], v[238:241], v[230:233], v[0:15]
	ds_read_b128 v[238:241], v192 offset:4672
	s_setprio 0
	global_load_dwordx4 v[226:229], v[184:185], off offset:2944
	global_load_dwordx4 v[230:233], v[186:187], off offset:2944
	s_setprio 1
	s_waitcnt lgkmcnt(1)
	v_mfma_f32_32x32x16_bf16 v[112:127], v[234:237], v[176:179], v[112:127]
	v_mfma_f32_32x32x16_bf16 v[48:63], v[234:237], v[180:183], v[48:63]
	s_waitcnt lgkmcnt(0)
	v_mfma_f32_32x32x16_bf16 v[96:111], v[238:241], v[176:179], v[96:111]
	v_mfma_f32_32x32x16_bf16 v[32:47], v[238:241], v[180:183], v[32:47]
	ds_read_b128 v[234:237], v192 offset:9280
	ds_read_b128 v[238:241], v192 offset:13888
	s_waitcnt vmcnt(7)
	ds_write_b128 v215, v[168:171] offset:27648
	s_waitcnt vmcnt(6)
	ds_write_b128 v215, v[172:175] offset:64512
	ds_read_b128 v[168:171], v208 offset:96
	ds_read_b128 v[172:175], v208 offset:4704
	s_waitcnt lgkmcnt(5)
	v_mfma_f32_32x32x16_bf16 v[80:95], v[234:237], v[176:179], v[80:95]
	v_mfma_f32_32x32x16_bf16 v[16:31], v[234:237], v[180:183], v[16:31]
	ds_read_b128 v[234:237], v192 offset:96
	s_waitcnt lgkmcnt(5)
	v_mfma_f32_32x32x16_bf16 v[64:79], v[238:241], v[176:179], v[64:79]
	v_mfma_f32_32x32x16_bf16 v[0:15], v[238:241], v[180:183], v[0:15]
	ds_read_b128 v[238:241], v192 offset:4704
	s_setprio 0
	global_load_dwordx4 v[176:179], v[198:199], off offset:2944
	global_load_dwordx4 v[180:183], v[200:201], off offset:2944
	s_setprio 1
	s_waitcnt lgkmcnt(1)
	v_mfma_f32_32x32x16_bf16 v[112:127], v[234:237], v[168:171], v[112:127]
	v_mfma_f32_32x32x16_bf16 v[48:63], v[234:237], v[172:175], v[48:63]
	s_waitcnt lgkmcnt(0)
	v_mfma_f32_32x32x16_bf16 v[96:111], v[238:241], v[168:171], v[96:111]
	v_mfma_f32_32x32x16_bf16 v[32:47], v[238:241], v[172:175], v[32:47]
	ds_read_b128 v[234:237], v192 offset:9312
	ds_read_b128 v[238:241], v192 offset:13920
	s_waitcnt lgkmcnt(0)
	s_barrier
; template <bool trans>
; DI void gemm_core(const GTile& tl, const GTile& nx, bool has_next  , bool chain  , bool pre, u32x4 (&ra)[4], u32x4 (&rb)[4], char* smem, f32x16 (&acc)[2][4]) {
;     ...
;   const int nk = K / 64;
;   if (!pre) { G_LOAD(0); G_STORE(0); G_LOAD(1); }
;   for (int kt = 0; kt < nk; ++kt) {
;     __syncthreads();
;     G_COMPUTE(kt & 1, kt);
;   }
	s_waitcnt vmcnt(7)
	ds_write_b128 v209, v[160:163]
	s_waitcnt vmcnt(6)
	ds_write_b128 v210, v[164:167]
	ds_read_b128 v[160:163], v205 offset:36864
	ds_read_b128 v[164:167], v205 offset:41472
	v_mfma_f32_32x32x16_bf16 v[80:95], v[234:237], v[168:171], v[80:95]
	v_mfma_f32_32x32x16_bf16 v[16:31], v[234:237], v[172:175], v[16:31]
	ds_read_b128 v[234:237], v204
	v_mfma_f32_32x32x16_bf16 v[64:79], v[238:241], v[168:171], v[64:79]
	v_mfma_f32_32x32x16_bf16 v[0:15], v[238:241], v[172:175], v[0:15]
	ds_read_b128 v[238:241], v204 offset:4608
	s_setprio 0
	global_load_dwordx4 v[168:171], v[190:191], off offset:3072
	global_load_dwordx4 v[172:175], v[188:189], off offset:3072
	s_setprio 1
	s_waitcnt lgkmcnt(1)
	v_mfma_f32_32x32x16_bf16 v[112:127], v[234:237], v[160:163], v[112:127]
	v_mfma_f32_32x32x16_bf16 v[48:63], v[234:237], v[164:167], v[48:63]
	s_waitcnt lgkmcnt(0)
	v_mfma_f32_32x32x16_bf16 v[96:111], v[238:241], v[160:163], v[96:111]
	v_mfma_f32_32x32x16_bf16 v[32:47], v[238:241], v[164:167], v[32:47]
	ds_read_b128 v[234:237], v204 offset:9216
	ds_read_b128 v[238:241], v204 offset:13824
	s_waitcnt vmcnt(7)
	ds_write_b128 v212, v[218:221]
	s_waitcnt vmcnt(6)
	ds_write_b128 v211, v[222:225]
	ds_read_b128 v[218:221], v205 offset:36896
	ds_read_b128 v[222:225], v205 offset:41504
	s_waitcnt lgkmcnt(5)
	v_mfma_f32_32x32x16_bf16 v[80:95], v[234:237], v[160:163], v[80:95]
	v_mfma_f32_32x32x16_bf16 v[16:31], v[234:237], v[164:167], v[16:31]
	ds_read_b128 v[234:237], v204 offset:32
	s_waitcnt lgkmcnt(5)
	v_mfma_f32_32x32x16_bf16 v[64:79], v[238:241], v[160:163], v[64:79]
	v_mfma_f32_32x32x16_bf16 v[0:15], v[238:241], v[164:167], v[0:15]
	ds_read_b128 v[238:241], v204 offset:4640
	s_setprio 0
	global_load_dwordx4 v[160:163], v[194:195], off offset:3072
	global_load_dwordx4 v[164:167], v[196:197], off offset:3072
	s_setprio 1
	s_waitcnt lgkmcnt(1)
	v_mfma_f32_32x32x16_bf16 v[112:127], v[234:237], v[218:221], v[112:127]
	v_mfma_f32_32x32x16_bf16 v[48:63], v[234:237], v[222:225], v[48:63]
	s_waitcnt lgkmcnt(0)
	v_mfma_f32_32x32x16_bf16 v[96:111], v[238:241], v[218:221], v[96:111]
	v_mfma_f32_32x32x16_bf16 v[32:47], v[238:241], v[222:225], v[32:47]
	ds_read_b128 v[234:237], v204 offset:9248
	ds_read_b128 v[238:241], v204 offset:13856
	s_waitcnt vmcnt(7)
	ds_write_b128 v214, v[226:229]
	s_waitcnt vmcnt(6)
	ds_write_b128 v213, v[230:233]
	ds_read_b128 v[226:229], v205 offset:36928
	ds_read_b128 v[230:233], v205 offset:41536
	s_waitcnt lgkmcnt(5)
	v_mfma_f32_32x32x16_bf16 v[80:95], v[234:237], v[218:221], v[80:95]
	v_mfma_f32_32x32x16_bf16 v[16:31], v[234:237], v[222:225], v[16:31]
	ds_read_b128 v[234:237], v204 offset:64
	s_waitcnt lgkmcnt(5)
	v_mfma_f32_32x32x16_bf16 v[64:79], v[238:241], v[218:221], v[64:79]
	v_mfma_f32_32x32x16_bf16 v[0:15], v[238:241], v[222:225], v[0:15]
	ds_read_b128 v[238:241], v204 offset:4672
	s_setprio 0
	global_load_dwordx4 v[218:221], v[184:185], off offset:3072
	global_load_dwordx4 v[222:225], v[186:187], off offset:3072
	s_setprio 1
	s_waitcnt lgkmcnt(1)
	v_mfma_f32_32x32x16_bf16 v[112:127], v[234:237], v[226:229], v[112:127]
	v_mfma_f32_32x32x16_bf16 v[48:63], v[234:237], v[230:233], v[48:63]
	s_waitcnt lgkmcnt(0)
	v_mfma_f32_32x32x16_bf16 v[96:111], v[238:241], v[226:229], v[96:111]
	v_mfma_f32_32x32x16_bf16 v[32:47], v[238:241], v[230:233], v[32:47]
	ds_read_b128 v[234:237], v204 offset:9280
	ds_read_b128 v[238:241], v204 offset:13888
	s_waitcnt vmcnt(7)
	ds_write_b128 v217, v[176:179]
	s_waitcnt vmcnt(6)
	ds_write_b128 v216, v[180:183]
	ds_read_b128 v[176:179], v205 offset:36960
	ds_read_b128 v[180:183], v205 offset:41568
	s_waitcnt lgkmcnt(5)
	v_mfma_f32_32x32x16_bf16 v[80:95], v[234:237], v[226:229], v[80:95]
	v_mfma_f32_32x32x16_bf16 v[16:31], v[234:237], v[230:233], v[16:31]
	ds_read_b128 v[234:237], v204 offset:96
	s_waitcnt lgkmcnt(5)
	v_mfma_f32_32x32x16_bf16 v[64:79], v[238:241], v[226:229], v[64:79]
	v_mfma_f32_32x32x16_bf16 v[0:15], v[238:241], v[230:233], v[0:15]
	ds_read_b128 v[238:241], v204 offset:4704
	s_setprio 0
	global_load_dwordx4 v[226:229], v[198:199], off offset:3072
	global_load_dwordx4 v[230:233], v[200:201], off offset:3072
	s_setprio 1
	s_waitcnt lgkmcnt(1)
	v_mfma_f32_32x32x16_bf16 v[112:127], v[234:237], v[176:179], v[112:127]
	v_mfma_f32_32x32x16_bf16 v[48:63], v[234:237], v[180:183], v[48:63]
	s_waitcnt lgkmcnt(0)
	v_mfma_f32_32x32x16_bf16 v[96:111], v[238:241], v[176:179], v[96:111]
	v_mfma_f32_32x32x16_bf16 v[32:47], v[238:241], v[180:183], v[32:47]
	ds_read_b128 v[234:237], v204 offset:9312
	ds_read_b128 v[238:241], v204 offset:13920
	s_waitcnt lgkmcnt(0)
	s_barrier
; template <bool trans>
; DI void gemm_core(const GTile& tl, const GTile& nx, bool has_next  , bool chain  , bool pre, u32x4 (&ra)[4], u32x4 (&rb)[4], char* smem, f32x16 (&acc)[2][4]) {
;     ...
;   const int nk = K / 64;
;   if (!pre) { G_LOAD(0); G_STORE(0); G_LOAD(1); }
;   for (int kt = 0; kt < nk; ++kt) {
;     __syncthreads();
;     G_COMPUTE(kt & 1, kt);
;   }
	s_waitcnt vmcnt(7)
	ds_write_b128 v215, v[168:171]
	s_waitcnt vmcnt(6)
	ds_write_b128 v215, v[172:175] offset:36864
	ds_read_b128 v[168:171], v208
	ds_read_b128 v[172:175], v208 offset:4608
	v_mfma_f32_32x32x16_bf16 v[80:95], v[234:237], v[176:179], v[80:95]
	v_mfma_f32_32x32x16_bf16 v[16:31], v[234:237], v[180:183], v[16:31]
	ds_read_b128 v[234:237], v192
	v_mfma_f32_32x32x16_bf16 v[64:79], v[238:241], v[176:179], v[64:79]
	v_mfma_f32_32x32x16_bf16 v[0:15], v[238:241], v[180:183], v[0:15]
	ds_read_b128 v[238:241], v192 offset:4608
	s_setprio 0
	global_load_dwordx4 v[176:179], v[190:191], off offset:3200
	global_load_dwordx4 v[180:183], v[188:189], off offset:3200
	s_setprio 1
	s_waitcnt lgkmcnt(1)
	v_mfma_f32_32x32x16_bf16 v[112:127], v[234:237], v[168:171], v[112:127]
	v_mfma_f32_32x32x16_bf16 v[48:63], v[234:237], v[172:175], v[48:63]
	s_waitcnt lgkmcnt(0)
	v_mfma_f32_32x32x16_bf16 v[96:111], v[238:241], v[168:171], v[96:111]
	v_mfma_f32_32x32x16_bf16 v[32:47], v[238:241], v[172:175], v[32:47]
	ds_read_b128 v[234:237], v192 offset:9216
	ds_read_b128 v[238:241], v192 offset:13824
	s_waitcnt vmcnt(7)
	ds_write_b128 v215, v[160:163] offset:9216
	s_waitcnt vmcnt(6)
	ds_write_b128 v215, v[164:167] offset:46080
	ds_read_b128 v[160:163], v208 offset:32
	ds_read_b128 v[164:167], v208 offset:4640
	s_waitcnt lgkmcnt(5)
	v_mfma_f32_32x32x16_bf16 v[80:95], v[234:237], v[168:171], v[80:95]
	v_mfma_f32_32x32x16_bf16 v[16:31], v[234:237], v[172:175], v[16:31]
	ds_read_b128 v[234:237], v192 offset:32
	s_waitcnt lgkmcnt(5)
	v_mfma_f32_32x32x16_bf16 v[64:79], v[238:241], v[168:171], v[64:79]
	v_mfma_f32_32x32x16_bf16 v[0:15], v[238:241], v[172:175], v[0:15]
	ds_read_b128 v[238:241], v192 offset:4640
	s_setprio 0
	global_load_dwordx4 v[168:171], v[194:195], off offset:3200
	global_load_dwordx4 v[172:175], v[196:197], off offset:3200
	s_setprio 1
	s_waitcnt lgkmcnt(1)
	v_mfma_f32_32x32x16_bf16 v[112:127], v[234:237], v[160:163], v[112:127]
	v_mfma_f32_32x32x16_bf16 v[48:63], v[234:237], v[164:167], v[48:63]
	s_waitcnt lgkmcnt(0)
	v_mfma_f32_32x32x16_bf16 v[96:111], v[238:241], v[160:163], v[96:111]
	v_mfma_f32_32x32x16_bf16 v[32:47], v[238:241], v[164:167], v[32:47]
	ds_read_b128 v[234:237], v192 offset:9248
	ds_read_b128 v[238:241], v192 offset:13856
	s_waitcnt vmcnt(7)
	ds_write_b128 v215, v[218:221] offset:18432
	s_waitcnt vmcnt(6)
	ds_write_b128 v215, v[222:225] offset:55296
	ds_read_b128 v[218:221], v208 offset:64
	ds_read_b128 v[222:225], v208 offset:4672
	s_waitcnt lgkmcnt(5)
	v_mfma_f32_32x32x16_bf16 v[80:95], v[234:237], v[160:163], v[80:95]
	v_mfma_f32_32x32x16_bf16 v[16:31], v[234:237], v[164:167], v[16:31]
	ds_read_b128 v[234:237], v192 offset:64
	s_waitcnt lgkmcnt(5)
	v_mfma_f32_32x32x16_bf16 v[64:79], v[238:241], v[160:163], v[64:79]
	v_mfma_f32_32x32x16_bf16 v[0:15], v[238:241], v[164:167], v[0:15]
	ds_read_b128 v[238:241], v192 offset:4672
	s_setprio 0
	global_load_dwordx4 v[160:163], v[184:185], off offset:3200
	global_load_dwordx4 v[164:167], v[186:187], off offset:3200
	s_setprio 1
	s_waitcnt lgkmcnt(1)
	v_mfma_f32_32x32x16_bf16 v[112:127], v[234:237], v[218:221], v[112:127]
	v_mfma_f32_32x32x16_bf16 v[48:63], v[234:237], v[222:225], v[48:63]
	s_waitcnt lgkmcnt(0)
	v_mfma_f32_32x32x16_bf16 v[96:111], v[238:241], v[218:221], v[96:111]
	v_mfma_f32_32x32x16_bf16 v[32:47], v[238:241], v[222:225], v[32:47]
	ds_read_b128 v[234:237], v192 offset:9280
	ds_read_b128 v[238:241], v192 offset:13888
	s_waitcnt vmcnt(7)
	ds_write_b128 v215, v[226:229] offset:27648
	s_waitcnt vmcnt(6)
	ds_write_b128 v215, v[230:233] offset:64512
	ds_read_b128 v[226:229], v208 offset:96
	ds_read_b128 v[230:233], v208 offset:4704
	s_waitcnt lgkmcnt(5)
	v_mfma_f32_32x32x16_bf16 v[80:95], v[234:237], v[218:221], v[80:95]
	v_mfma_f32_32x32x16_bf16 v[16:31], v[234:237], v[222:225], v[16:31]
	ds_read_b128 v[234:237], v192 offset:96
	s_waitcnt lgkmcnt(5)
	v_mfma_f32_32x32x16_bf16 v[64:79], v[238:241], v[218:221], v[64:79]
	v_mfma_f32_32x32x16_bf16 v[0:15], v[238:241], v[222:225], v[0:15]
	ds_read_b128 v[238:241], v192 offset:4704
	s_setprio 0
	global_load_dwordx4 v[218:221], v[198:199], off offset:3200
	global_load_dwordx4 v[222:225], v[200:201], off offset:3200
	s_setprio 1
	s_waitcnt lgkmcnt(1)
	v_mfma_f32_32x32x16_bf16 v[112:127], v[234:237], v[226:229], v[112:127]
	v_mfma_f32_32x32x16_bf16 v[48:63], v[234:237], v[230:233], v[48:63]
	s_waitcnt lgkmcnt(0)
	v_mfma_f32_32x32x16_bf16 v[96:111], v[238:241], v[226:229], v[96:111]
	v_mfma_f32_32x32x16_bf16 v[32:47], v[238:241], v[230:233], v[32:47]
	ds_read_b128 v[234:237], v192 offset:9312
	ds_read_b128 v[238:241], v192 offset:13920
	s_waitcnt lgkmcnt(0)
	s_barrier
; template <bool trans>
; DI void gemm_core(const GTile& tl, const GTile& nx, bool has_next  , bool chain  , bool pre, u32x4 (&ra)[4], u32x4 (&rb)[4], char* smem, f32x16 (&acc)[2][4]) {
;     ...
;   const int nk = K / 64;
;   if (!pre) { G_LOAD(0); G_STORE(0); G_LOAD(1); }
;   for (int kt = 0; kt < nk; ++kt) {
;     __syncthreads();
;     G_COMPUTE(kt & 1, kt);
;   }
	s_waitcnt vmcnt(7)
	ds_write_b128 v209, v[176:179]
	s_waitcnt vmcnt(6)
	ds_write_b128 v210, v[180:183]
	ds_read_b128 v[176:179], v205 offset:36864
	ds_read_b128 v[180:183], v205 offset:41472
	v_mfma_f32_32x32x16_bf16 v[80:95], v[234:237], v[226:229], v[80:95]
	v_mfma_f32_32x32x16_bf16 v[16:31], v[234:237], v[230:233], v[16:31]
	ds_read_b128 v[234:237], v204
	v_mfma_f32_32x32x16_bf16 v[64:79], v[238:241], v[226:229], v[64:79]
	v_mfma_f32_32x32x16_bf16 v[0:15], v[238:241], v[230:233], v[0:15]
	ds_read_b128 v[238:241], v204 offset:4608
	s_setprio 0
	global_load_dwordx4 v[226:229], v[190:191], off offset:3328
	global_load_dwordx4 v[230:233], v[188:189], off offset:3328
	s_setprio 1
	s_waitcnt lgkmcnt(1)
	v_mfma_f32_32x32x16_bf16 v[112:127], v[234:237], v[176:179], v[112:127]
	v_mfma_f32_32x32x16_bf16 v[48:63], v[234:237], v[180:183], v[48:63]
	s_waitcnt lgkmcnt(0)
	v_mfma_f32_32x32x16_bf16 v[96:111], v[238:241], v[176:179], v[96:111]
	v_mfma_f32_32x32x16_bf16 v[32:47], v[238:241], v[180:183], v[32:47]
	ds_read_b128 v[234:237], v204 offset:9216
	ds_read_b128 v[238:241], v204 offset:13824
	s_waitcnt vmcnt(7)
	ds_write_b128 v212, v[168:171]
	s_waitcnt vmcnt(6)
	ds_write_b128 v211, v[172:175]
	ds_read_b128 v[168:171], v205 offset:36896
	ds_read_b128 v[172:175], v205 offset:41504
	s_waitcnt lgkmcnt(5)
	v_mfma_f32_32x32x16_bf16 v[80:95], v[234:237], v[176:179], v[80:95]
	v_mfma_f32_32x32x16_bf16 v[16:31], v[234:237], v[180:183], v[16:31]
	ds_read_b128 v[234:237], v204 offset:32
	s_waitcnt lgkmcnt(5)
	v_mfma_f32_32x32x16_bf16 v[64:79], v[238:241], v[176:179], v[64:79]
	v_mfma_f32_32x32x16_bf16 v[0:15], v[238:241], v[180:183], v[0:15]
	ds_read_b128 v[238:241], v204 offset:4640
	s_setprio 0
	global_load_dwordx4 v[176:179], v[194:195], off offset:3328
	global_load_dwordx4 v[180:183], v[196:197], off offset:3328
	s_setprio 1
	s_waitcnt lgkmcnt(1)
	v_mfma_f32_32x32x16_bf16 v[112:127], v[234:237], v[168:171], v[112:127]
	v_mfma_f32_32x32x16_bf16 v[48:63], v[234:237], v[172:175], v[48:63]
	s_waitcnt lgkmcnt(0)
	v_mfma_f32_32x32x16_bf16 v[96:111], v[238:241], v[168:171], v[96:111]
	v_mfma_f32_32x32x16_bf16 v[32:47], v[238:241], v[172:175], v[32:47]
	ds_read_b128 v[234:237], v204 offset:9248
	ds_read_b128 v[238:241], v204 offset:13856
	s_waitcnt vmcnt(7)
	ds_write_b128 v214, v[160:163]
	s_waitcnt vmcnt(6)
	ds_write_b128 v213, v[164:167]
	ds_read_b128 v[160:163], v205 offset:36928
	ds_read_b128 v[164:167], v205 offset:41536
	s_waitcnt lgkmcnt(5)
	v_mfma_f32_32x32x16_bf16 v[80:95], v[234:237], v[168:171], v[80:95]
	v_mfma_f32_32x32x16_bf16 v[16:31], v[234:237], v[172:175], v[16:31]
	ds_read_b128 v[234:237], v204 offset:64
	s_waitcnt lgkmcnt(5)
	v_mfma_f32_32x32x16_bf16 v[64:79], v[238:241], v[168:171], v[64:79]
	v_mfma_f32_32x32x16_bf16 v[0:15], v[238:241], v[172:175], v[0:15]
	ds_read_b128 v[238:241], v204 offset:4672
	s_setprio 0
	global_load_dwordx4 v[168:171], v[184:185], off offset:3328
	global_load_dwordx4 v[172:175], v[186:187], off offset:3328
	s_setprio 1
	s_waitcnt lgkmcnt(1)
	v_mfma_f32_32x32x16_bf16 v[112:127], v[234:237], v[160:163], v[112:127]
	v_mfma_f32_32x32x16_bf16 v[48:63], v[234:237], v[164:167], v[48:63]
	s_waitcnt lgkmcnt(0)
	v_mfma_f32_32x32x16_bf16 v[96:111], v[238:241], v[160:163], v[96:111]
	v_mfma_f32_32x32x16_bf16 v[32:47], v[238:241], v[164:167], v[32:47]
	ds_read_b128 v[234:237], v204 offset:9280
	ds_read_b128 v[238:241], v204 offset:13888
	s_waitcnt vmcnt(7)
	ds_write_b128 v217, v[218:221]
	s_waitcnt vmcnt(6)
	ds_write_b128 v216, v[222:225]
	ds_read_b128 v[218:221], v205 offset:36960
	ds_read_b128 v[222:225], v205 offset:41568
	s_waitcnt lgkmcnt(5)
	v_mfma_f32_32x32x16_bf16 v[80:95], v[234:237], v[160:163], v[80:95]
	v_mfma_f32_32x32x16_bf16 v[16:31], v[234:237], v[164:167], v[16:31]
	ds_read_b128 v[234:237], v204 offset:96
	s_waitcnt lgkmcnt(5)
	v_mfma_f32_32x32x16_bf16 v[64:79], v[238:241], v[160:163], v[64:79]
	v_mfma_f32_32x32x16_bf16 v[0:15], v[238:241], v[164:167], v[0:15]
	ds_read_b128 v[238:241], v204 offset:4704
	s_setprio 0
	global_load_dwordx4 v[160:163], v[198:199], off offset:3328
	global_load_dwordx4 v[164:167], v[200:201], off offset:3328
	s_setprio 1
	s_waitcnt lgkmcnt(1)
	v_mfma_f32_32x32x16_bf16 v[112:127], v[234:237], v[218:221], v[112:127]
	v_mfma_f32_32x32x16_bf16 v[48:63], v[234:237], v[222:225], v[48:63]
	s_waitcnt lgkmcnt(0)
	v_mfma_f32_32x32x16_bf16 v[96:111], v[238:241], v[218:221], v[96:111]
	v_mfma_f32_32x32x16_bf16 v[32:47], v[238:241], v[222:225], v[32:47]
	ds_read_b128 v[234:237], v204 offset:9312
	ds_read_b128 v[238:241], v204 offset:13920
	s_waitcnt lgkmcnt(0)
	s_barrier
; template <bool trans>
; DI void gemm_core(const GTile& tl, const GTile& nx, bool has_next  , bool chain  , bool pre, u32x4 (&ra)[4], u32x4 (&rb)[4], char* smem, f32x16 (&acc)[2][4]) {
;     ...
;   const int nk = K / 64;
;   if (!pre) { G_LOAD(0); G_STORE(0); G_LOAD(1); }
;   for (int kt = 0; kt < nk; ++kt) {
;     __syncthreads();
;     G_COMPUTE(kt & 1, kt);
;   }
	s_waitcnt vmcnt(7)
	ds_write_b128 v215, v[226:229]
	s_waitcnt vmcnt(6)
	ds_write_b128 v215, v[230:233] offset:36864
	ds_read_b128 v[226:229], v208
	ds_read_b128 v[230:233], v208 offset:4608
	v_mfma_f32_32x32x16_bf16 v[80:95], v[234:237], v[218:221], v[80:95]
	v_mfma_f32_32x32x16_bf16 v[16:31], v[234:237], v[222:225], v[16:31]
	ds_read_b128 v[234:237], v192
	v_mfma_f32_32x32x16_bf16 v[64:79], v[238:241], v[218:221], v[64:79]
	v_mfma_f32_32x32x16_bf16 v[0:15], v[238:241], v[222:225], v[0:15]
	ds_read_b128 v[238:241], v192 offset:4608
	s_setprio 0
	global_load_dwordx4 v[218:221], v[190:191], off offset:3456
	global_load_dwordx4 v[222:225], v[188:189], off offset:3456
	s_setprio 1
	s_waitcnt lgkmcnt(1)
	v_mfma_f32_32x32x16_bf16 v[112:127], v[234:237], v[226:229], v[112:127]
	v_mfma_f32_32x32x16_bf16 v[48:63], v[234:237], v[230:233], v[48:63]
	s_waitcnt lgkmcnt(0)
	v_mfma_f32_32x32x16_bf16 v[96:111], v[238:241], v[226:229], v[96:111]
	v_mfma_f32_32x32x16_bf16 v[32:47], v[238:241], v[230:233], v[32:47]
	ds_read_b128 v[234:237], v192 offset:9216
	ds_read_b128 v[238:241], v192 offset:13824
	s_waitcnt vmcnt(7)
	ds_write_b128 v215, v[176:179] offset:9216
	s_waitcnt vmcnt(6)
	ds_write_b128 v215, v[180:183] offset:46080
	ds_read_b128 v[176:179], v208 offset:32
	ds_read_b128 v[180:183], v208 offset:4640
	s_waitcnt lgkmcnt(5)
	v_mfma_f32_32x32x16_bf16 v[80:95], v[234:237], v[226:229], v[80:95]
	v_mfma_f32_32x32x16_bf16 v[16:31], v[234:237], v[230:233], v[16:31]
	ds_read_b128 v[234:237], v192 offset:32
	s_waitcnt lgkmcnt(5)
	v_mfma_f32_32x32x16_bf16 v[64:79], v[238:241], v[226:229], v[64:79]
	v_mfma_f32_32x32x16_bf16 v[0:15], v[238:241], v[230:233], v[0:15]
	ds_read_b128 v[238:241], v192 offset:4640
	s_setprio 0
	global_load_dwordx4 v[226:229], v[194:195], off offset:3456
	global_load_dwordx4 v[230:233], v[196:197], off offset:3456
	s_setprio 1
	s_waitcnt lgkmcnt(1)
	v_mfma_f32_32x32x16_bf16 v[112:127], v[234:237], v[176:179], v[112:127]
	v_mfma_f32_32x32x16_bf16 v[48:63], v[234:237], v[180:183], v[48:63]
	s_waitcnt lgkmcnt(0)
	v_mfma_f32_32x32x16_bf16 v[96:111], v[238:241], v[176:179], v[96:111]
	v_mfma_f32_32x32x16_bf16 v[32:47], v[238:241], v[180:183], v[32:47]
	ds_read_b128 v[234:237], v192 offset:9248
	ds_read_b128 v[238:241], v192 offset:13856
	s_waitcnt vmcnt(7)
	ds_write_b128 v215, v[168:171] offset:18432
	s_waitcnt vmcnt(6)
	ds_write_b128 v215, v[172:175] offset:55296
	ds_read_b128 v[168:171], v208 offset:64
	ds_read_b128 v[172:175], v208 offset:4672
	s_waitcnt lgkmcnt(5)
	v_mfma_f32_32x32x16_bf16 v[80:95], v[234:237], v[176:179], v[80:95]
	v_mfma_f32_32x32x16_bf16 v[16:31], v[234:237], v[180:183], v[16:31]
	ds_read_b128 v[234:237], v192 offset:64
	s_waitcnt lgkmcnt(5)
	v_mfma_f32_32x32x16_bf16 v[64:79], v[238:241], v[176:179], v[64:79]
	v_mfma_f32_32x32x16_bf16 v[0:15], v[238:241], v[180:183], v[0:15]
	ds_read_b128 v[238:241], v192 offset:4672
	s_setprio 0
	global_load_dwordx4 v[176:179], v[184:185], off offset:3456
	global_load_dwordx4 v[180:183], v[186:187], off offset:3456
	s_setprio 1
	s_waitcnt lgkmcnt(1)
	v_mfma_f32_32x32x16_bf16 v[112:127], v[234:237], v[168:171], v[112:127]
	v_mfma_f32_32x32x16_bf16 v[48:63], v[234:237], v[172:175], v[48:63]
	s_waitcnt lgkmcnt(0)
	v_mfma_f32_32x32x16_bf16 v[96:111], v[238:241], v[168:171], v[96:111]
	v_mfma_f32_32x32x16_bf16 v[32:47], v[238:241], v[172:175], v[32:47]
	ds_read_b128 v[234:237], v192 offset:9280
	ds_read_b128 v[238:241], v192 offset:13888
	s_waitcnt vmcnt(7)
	ds_write_b128 v215, v[160:163] offset:27648
	s_waitcnt vmcnt(6)
	ds_write_b128 v215, v[164:167] offset:64512
	ds_read_b128 v[160:163], v208 offset:96
	ds_read_b128 v[164:167], v208 offset:4704
	s_waitcnt lgkmcnt(5)
	v_mfma_f32_32x32x16_bf16 v[80:95], v[234:237], v[168:171], v[80:95]
	v_mfma_f32_32x32x16_bf16 v[16:31], v[234:237], v[172:175], v[16:31]
	ds_read_b128 v[234:237], v192 offset:96
	s_waitcnt lgkmcnt(5)
	v_mfma_f32_32x32x16_bf16 v[64:79], v[238:241], v[168:171], v[64:79]
	v_mfma_f32_32x32x16_bf16 v[0:15], v[238:241], v[172:175], v[0:15]
	ds_read_b128 v[238:241], v192 offset:4704
	s_setprio 0
	global_load_dwordx4 v[168:171], v[198:199], off offset:3456
	global_load_dwordx4 v[172:175], v[200:201], off offset:3456
	s_setprio 1
	s_waitcnt lgkmcnt(1)
	v_mfma_f32_32x32x16_bf16 v[112:127], v[234:237], v[160:163], v[112:127]
	v_mfma_f32_32x32x16_bf16 v[48:63], v[234:237], v[164:167], v[48:63]
	s_waitcnt lgkmcnt(0)
	v_mfma_f32_32x32x16_bf16 v[96:111], v[238:241], v[160:163], v[96:111]
	v_mfma_f32_32x32x16_bf16 v[32:47], v[238:241], v[164:167], v[32:47]
	ds_read_b128 v[234:237], v192 offset:9312
	ds_read_b128 v[238:241], v192 offset:13920
	s_waitcnt lgkmcnt(0)
	s_barrier
; template <bool trans>
; DI void gemm_core(const GTile& tl, const GTile& nx, bool has_next  , bool chain  , bool pre, u32x4 (&ra)[4], u32x4 (&rb)[4], char* smem, f32x16 (&acc)[2][4]) {
;     ...
;   const int nk = K / 64;
;   if (!pre) { G_LOAD(0); G_STORE(0); G_LOAD(1); }
;   for (int kt = 0; kt < nk; ++kt) {
;     __syncthreads();
;     G_COMPUTE(kt & 1, kt);
;   }
	s_waitcnt vmcnt(7)
	ds_write_b128 v209, v[218:221]
	s_waitcnt vmcnt(6)
	ds_write_b128 v210, v[222:225]
	ds_read_b128 v[218:221], v205 offset:36864
	ds_read_b128 v[222:225], v205 offset:41472
	v_mfma_f32_32x32x16_bf16 v[80:95], v[234:237], v[160:163], v[80:95]
	v_mfma_f32_32x32x16_bf16 v[16:31], v[234:237], v[164:167], v[16:31]
	ds_read_b128 v[234:237], v204
	v_mfma_f32_32x32x16_bf16 v[64:79], v[238:241], v[160:163], v[64:79]
	v_mfma_f32_32x32x16_bf16 v[0:15], v[238:241], v[164:167], v[0:15]
	ds_read_b128 v[238:241], v204 offset:4608
	s_setprio 0
	global_load_dwordx4 v[160:163], v[190:191], off offset:3584
	global_load_dwordx4 v[164:167], v[188:189], off offset:3584
	s_setprio 1
	s_waitcnt lgkmcnt(1)
	v_mfma_f32_32x32x16_bf16 v[112:127], v[234:237], v[218:221], v[112:127]
	v_mfma_f32_32x32x16_bf16 v[48:63], v[234:237], v[222:225], v[48:63]
	s_waitcnt lgkmcnt(0)
	v_mfma_f32_32x32x16_bf16 v[96:111], v[238:241], v[218:221], v[96:111]
	v_mfma_f32_32x32x16_bf16 v[32:47], v[238:241], v[222:225], v[32:47]
	ds_read_b128 v[234:237], v204 offset:9216
	ds_read_b128 v[238:241], v204 offset:13824
	s_waitcnt vmcnt(7)
	ds_write_b128 v212, v[226:229]
	s_waitcnt vmcnt(6)
	ds_write_b128 v211, v[230:233]
	ds_read_b128 v[226:229], v205 offset:36896
	ds_read_b128 v[230:233], v205 offset:41504
	s_waitcnt lgkmcnt(5)
	v_mfma_f32_32x32x16_bf16 v[80:95], v[234:237], v[218:221], v[80:95]
	v_mfma_f32_32x32x16_bf16 v[16:31], v[234:237], v[222:225], v[16:31]
	ds_read_b128 v[234:237], v204 offset:32
	s_waitcnt lgkmcnt(5)
	v_mfma_f32_32x32x16_bf16 v[64:79], v[238:241], v[218:221], v[64:79]
	v_mfma_f32_32x32x16_bf16 v[0:15], v[238:241], v[222:225], v[0:15]
	ds_read_b128 v[238:241], v204 offset:4640
	s_setprio 0
	global_load_dwordx4 v[218:221], v[194:195], off offset:3584
	global_load_dwordx4 v[222:225], v[196:197], off offset:3584
	s_setprio 1
	s_waitcnt lgkmcnt(1)
	v_mfma_f32_32x32x16_bf16 v[112:127], v[234:237], v[226:229], v[112:127]
	v_mfma_f32_32x32x16_bf16 v[48:63], v[234:237], v[230:233], v[48:63]
	s_waitcnt lgkmcnt(0)
	v_mfma_f32_32x32x16_bf16 v[96:111], v[238:241], v[226:229], v[96:111]
	v_mfma_f32_32x32x16_bf16 v[32:47], v[238:241], v[230:233], v[32:47]
	ds_read_b128 v[234:237], v204 offset:9248
	ds_read_b128 v[238:241], v204 offset:13856
	s_waitcnt vmcnt(7)
	ds_write_b128 v214, v[176:179]
	s_waitcnt vmcnt(6)
	ds_write_b128 v213, v[180:183]
	ds_read_b128 v[176:179], v205 offset:36928
	ds_read_b128 v[180:183], v205 offset:41536
	s_waitcnt lgkmcnt(5)
	v_mfma_f32_32x32x16_bf16 v[80:95], v[234:237], v[226:229], v[80:95]
	v_mfma_f32_32x32x16_bf16 v[16:31], v[234:237], v[230:233], v[16:31]
	ds_read_b128 v[234:237], v204 offset:64
	s_waitcnt lgkmcnt(5)
	v_mfma_f32_32x32x16_bf16 v[64:79], v[238:241], v[226:229], v[64:79]
	v_mfma_f32_32x32x16_bf16 v[0:15], v[238:241], v[230:233], v[0:15]
	ds_read_b128 v[238:241], v204 offset:4672
	s_setprio 0
	global_load_dwordx4 v[226:229], v[184:185], off offset:3584
	global_load_dwordx4 v[230:233], v[186:187], off offset:3584
	s_setprio 1
	s_waitcnt lgkmcnt(1)
	v_mfma_f32_32x32x16_bf16 v[112:127], v[234:237], v[176:179], v[112:127]
	v_mfma_f32_32x32x16_bf16 v[48:63], v[234:237], v[180:183], v[48:63]
	s_waitcnt lgkmcnt(0)
	v_mfma_f32_32x32x16_bf16 v[96:111], v[238:241], v[176:179], v[96:111]
	v_mfma_f32_32x32x16_bf16 v[32:47], v[238:241], v[180:183], v[32:47]
	ds_read_b128 v[234:237], v204 offset:9280
	ds_read_b128 v[238:241], v204 offset:13888
	s_waitcnt vmcnt(7)
	ds_write_b128 v217, v[168:171]
	s_waitcnt vmcnt(6)
	ds_write_b128 v216, v[172:175]
	ds_read_b128 v[168:171], v205 offset:36960
	ds_read_b128 v[172:175], v205 offset:41568
	s_waitcnt lgkmcnt(5)
	v_mfma_f32_32x32x16_bf16 v[80:95], v[234:237], v[176:179], v[80:95]
	v_mfma_f32_32x32x16_bf16 v[16:31], v[234:237], v[180:183], v[16:31]
	ds_read_b128 v[234:237], v204 offset:96
	s_waitcnt lgkmcnt(5)
	v_mfma_f32_32x32x16_bf16 v[64:79], v[238:241], v[176:179], v[64:79]
	v_mfma_f32_32x32x16_bf16 v[0:15], v[238:241], v[180:183], v[0:15]
	ds_read_b128 v[238:241], v204 offset:4704
	s_setprio 0
	global_load_dwordx4 v[176:179], v[198:199], off offset:3584
	global_load_dwordx4 v[180:183], v[200:201], off offset:3584
	s_setprio 1
	s_waitcnt lgkmcnt(1)
	v_mfma_f32_32x32x16_bf16 v[112:127], v[234:237], v[168:171], v[112:127]
	v_mfma_f32_32x32x16_bf16 v[48:63], v[234:237], v[172:175], v[48:63]
	s_waitcnt lgkmcnt(0)
	v_mfma_f32_32x32x16_bf16 v[96:111], v[238:241], v[168:171], v[96:111]
	v_mfma_f32_32x32x16_bf16 v[32:47], v[238:241], v[172:175], v[32:47]
	ds_read_b128 v[234:237], v204 offset:9312
	ds_read_b128 v[238:241], v204 offset:13920
	s_waitcnt lgkmcnt(0)
	s_barrier
; template <bool trans>
; DI void gemm_core(const GTile& tl, const GTile& nx, bool has_next  , bool chain  , bool pre, u32x4 (&ra)[4], u32x4 (&rb)[4], char* smem, f32x16 (&acc)[2][4]) {
;     ...
;   const int nk = K / 64;
;   if (!pre) { G_LOAD(0); G_STORE(0); G_LOAD(1); }
;   for (int kt = 0; kt < nk; ++kt) {
;     __syncthreads();
;     G_COMPUTE(kt & 1, kt);
;   }
	s_waitcnt vmcnt(7)
	ds_write_b128 v215, v[160:163]
	s_waitcnt vmcnt(6)
	ds_write_b128 v215, v[164:167] offset:36864
	ds_read_b128 v[160:163], v208
	ds_read_b128 v[164:167], v208 offset:4608
	v_mfma_f32_32x32x16_bf16 v[80:95], v[234:237], v[168:171], v[80:95]
	v_mfma_f32_32x32x16_bf16 v[16:31], v[234:237], v[172:175], v[16:31]
	ds_read_b128 v[234:237], v192
	v_mfma_f32_32x32x16_bf16 v[64:79], v[238:241], v[168:171], v[64:79]
	v_mfma_f32_32x32x16_bf16 v[0:15], v[238:241], v[172:175], v[0:15]
	ds_read_b128 v[238:241], v192 offset:4608
	s_setprio 0
	global_load_dwordx4 v[168:171], v[190:191], off offset:3712
	global_load_dwordx4 v[172:175], v[188:189], off offset:3712
	s_setprio 1
	s_waitcnt lgkmcnt(1)
	v_mfma_f32_32x32x16_bf16 v[112:127], v[234:237], v[160:163], v[112:127]
	v_mfma_f32_32x32x16_bf16 v[48:63], v[234:237], v[164:167], v[48:63]
	s_waitcnt lgkmcnt(0)
	v_mfma_f32_32x32x16_bf16 v[96:111], v[238:241], v[160:163], v[96:111]
	v_mfma_f32_32x32x16_bf16 v[32:47], v[238:241], v[164:167], v[32:47]
	ds_read_b128 v[234:237], v192 offset:9216
	ds_read_b128 v[238:241], v192 offset:13824
	s_waitcnt vmcnt(7)
	ds_write_b128 v215, v[218:221] offset:9216
	s_waitcnt vmcnt(6)
	ds_write_b128 v215, v[222:225] offset:46080
	ds_read_b128 v[218:221], v208 offset:32
	ds_read_b128 v[222:225], v208 offset:4640
	s_waitcnt lgkmcnt(5)
	v_mfma_f32_32x32x16_bf16 v[80:95], v[234:237], v[160:163], v[80:95]
	v_mfma_f32_32x32x16_bf16 v[16:31], v[234:237], v[164:167], v[16:31]
	ds_read_b128 v[234:237], v192 offset:32
	s_waitcnt lgkmcnt(5)
	v_mfma_f32_32x32x16_bf16 v[64:79], v[238:241], v[160:163], v[64:79]
	v_mfma_f32_32x32x16_bf16 v[0:15], v[238:241], v[164:167], v[0:15]
	ds_read_b128 v[238:241], v192 offset:4640
	s_setprio 0
	global_load_dwordx4 v[160:163], v[194:195], off offset:3712
	global_load_dwordx4 v[164:167], v[196:197], off offset:3712
	s_setprio 1
	s_waitcnt lgkmcnt(1)
	v_mfma_f32_32x32x16_bf16 v[112:127], v[234:237], v[218:221], v[112:127]
	v_mfma_f32_32x32x16_bf16 v[48:63], v[234:237], v[222:225], v[48:63]
	s_waitcnt lgkmcnt(0)
	v_mfma_f32_32x32x16_bf16 v[96:111], v[238:241], v[218:221], v[96:111]
	v_mfma_f32_32x32x16_bf16 v[32:47], v[238:241], v[222:225], v[32:47]
	ds_read_b128 v[234:237], v192 offset:9248
	ds_read_b128 v[238:241], v192 offset:13856
	s_waitcnt vmcnt(7)
	ds_write_b128 v215, v[226:229] offset:18432
	s_waitcnt vmcnt(6)
	ds_write_b128 v215, v[230:233] offset:55296
	ds_read_b128 v[226:229], v208 offset:64
	ds_read_b128 v[230:233], v208 offset:4672
	s_waitcnt lgkmcnt(5)
	v_mfma_f32_32x32x16_bf16 v[80:95], v[234:237], v[218:221], v[80:95]
	v_mfma_f32_32x32x16_bf16 v[16:31], v[234:237], v[222:225], v[16:31]
	ds_read_b128 v[234:237], v192 offset:64
	s_waitcnt lgkmcnt(5)
	v_mfma_f32_32x32x16_bf16 v[64:79], v[238:241], v[218:221], v[64:79]
	v_mfma_f32_32x32x16_bf16 v[0:15], v[238:241], v[222:225], v[0:15]
	ds_read_b128 v[238:241], v192 offset:4672
	s_setprio 0
	global_load_dwordx4 v[218:221], v[184:185], off offset:3712
	global_load_dwordx4 v[222:225], v[186:187], off offset:3712
	s_setprio 1
	s_waitcnt lgkmcnt(1)
	v_mfma_f32_32x32x16_bf16 v[112:127], v[234:237], v[226:229], v[112:127]
	v_mfma_f32_32x32x16_bf16 v[48:63], v[234:237], v[230:233], v[48:63]
	s_waitcnt lgkmcnt(0)
	v_mfma_f32_32x32x16_bf16 v[96:111], v[238:241], v[226:229], v[96:111]
	v_mfma_f32_32x32x16_bf16 v[32:47], v[238:241], v[230:233], v[32:47]
	ds_read_b128 v[234:237], v192 offset:9280
	ds_read_b128 v[238:241], v192 offset:13888
	s_waitcnt vmcnt(7)
	ds_write_b128 v215, v[176:179] offset:27648
	s_waitcnt vmcnt(6)
	ds_write_b128 v215, v[180:183] offset:64512
	ds_read_b128 v[176:179], v208 offset:96
	ds_read_b128 v[180:183], v208 offset:4704
	s_waitcnt lgkmcnt(5)
	v_mfma_f32_32x32x16_bf16 v[80:95], v[234:237], v[226:229], v[80:95]
	v_mfma_f32_32x32x16_bf16 v[16:31], v[234:237], v[230:233], v[16:31]
	ds_read_b128 v[234:237], v192 offset:96
	s_waitcnt lgkmcnt(5)
	v_mfma_f32_32x32x16_bf16 v[64:79], v[238:241], v[226:229], v[64:79]
	v_mfma_f32_32x32x16_bf16 v[0:15], v[238:241], v[230:233], v[0:15]
	ds_read_b128 v[238:241], v192 offset:4704
	s_setprio 0
	global_load_dwordx4 v[226:229], v[198:199], off offset:3712
	global_load_dwordx4 v[230:233], v[200:201], off offset:3712
	s_setprio 1
	s_waitcnt lgkmcnt(1)
	v_mfma_f32_32x32x16_bf16 v[112:127], v[234:237], v[176:179], v[112:127]
	v_mfma_f32_32x32x16_bf16 v[48:63], v[234:237], v[180:183], v[48:63]
	s_waitcnt lgkmcnt(0)
	v_mfma_f32_32x32x16_bf16 v[96:111], v[238:241], v[176:179], v[96:111]
	v_mfma_f32_32x32x16_bf16 v[32:47], v[238:241], v[180:183], v[32:47]
	ds_read_b128 v[234:237], v192 offset:9312
	ds_read_b128 v[238:241], v192 offset:13920
	s_waitcnt lgkmcnt(1)
	v_mfma_f32_32x32x16_bf16 v[80:95], v[234:237], v[176:179], v[80:95]
	v_mfma_f32_32x32x16_bf16 v[16:31], v[234:237], v[180:183], v[16:31]
	s_waitcnt lgkmcnt(0)
	v_mfma_f32_32x32x16_bf16 v[64:79], v[238:241], v[176:179], v[64:79]
	v_mfma_f32_32x32x16_bf16 v[0:15], v[238:241], v[180:183], v[0:15]
	s_setprio 0
	global_load_dwordx4 v[176:179], v[190:191], off offset:3840
	global_load_dwordx4 v[180:183], v[188:189], off offset:3840
	s_barrier
; template <bool trans>
; DI void gemm_core(const GTile& tl, const GTile& nx, bool has_next  , bool chain  , bool pre, u32x4 (&ra)[4], u32x4 (&rb)[4], char* smem, f32x16 (&acc)[2][4]) {
;     ...
;   const int nk = K / 64;
;   if (!pre) { G_LOAD(0); G_STORE(0); G_LOAD(1); }
;   for (int kt = 0; kt < nk; ++kt) {
;     __syncthreads();
;     G_COMPUTE(kt & 1, kt);
;   }
	s_waitcnt vmcnt(9)
	ds_write_b128 v209, v[168:171]
	s_waitcnt vmcnt(8)
	ds_write_b128 v210, v[172:175]
	ds_read_b128 v[168:171], v205 offset:36864
	ds_read_b128 v[172:175], v205 offset:41472
	ds_read_b128 v[234:237], v204
	ds_read_b128 v[238:241], v204 offset:4608
	s_setprio 1
	s_waitcnt lgkmcnt(1)
	v_mfma_f32_32x32x16_bf16 v[112:127], v[234:237], v[168:171], v[112:127]
	v_mfma_f32_32x32x16_bf16 v[48:63], v[234:237], v[172:175], v[48:63]
	s_waitcnt lgkmcnt(0)
	v_mfma_f32_32x32x16_bf16 v[96:111], v[238:241], v[168:171], v[96:111]
	v_mfma_f32_32x32x16_bf16 v[32:47], v[238:241], v[172:175], v[32:47]
	ds_read_b128 v[234:237], v204 offset:9216
	ds_read_b128 v[238:241], v204 offset:13824
	s_waitcnt lgkmcnt(1)
	v_mfma_f32_32x32x16_bf16 v[80:95], v[234:237], v[168:171], v[80:95]
	v_mfma_f32_32x32x16_bf16 v[16:31], v[234:237], v[172:175], v[16:31]
	s_waitcnt lgkmcnt(0)
	v_mfma_f32_32x32x16_bf16 v[64:79], v[238:241], v[168:171], v[64:79]
	v_mfma_f32_32x32x16_bf16 v[0:15], v[238:241], v[172:175], v[0:15]
	s_setprio 0
	global_load_dwordx4 v[234:237], v[194:195], off offset:3840
	global_load_dwordx4 v[238:241], v[196:197], off offset:3840
	s_waitcnt vmcnt(9)
	ds_write_b128 v212, v[160:163]
	s_waitcnt vmcnt(8)
	ds_write_b128 v211, v[164:167]
	ds_read_b128 v[160:163], v205 offset:36896
	ds_read_b128 v[164:167], v205 offset:41504
	ds_read_b128 v[168:171], v204 offset:32
	ds_read_b128 v[172:175], v204 offset:4640
	s_setprio 1
	s_waitcnt lgkmcnt(1)
	v_mfma_f32_32x32x16_bf16 v[112:127], v[168:171], v[160:163], v[112:127]
	v_mfma_f32_32x32x16_bf16 v[48:63], v[168:171], v[164:167], v[48:63]
	s_waitcnt lgkmcnt(0)
	v_mfma_f32_32x32x16_bf16 v[96:111], v[172:175], v[160:163], v[96:111]
	v_mfma_f32_32x32x16_bf16 v[32:47], v[172:175], v[164:167], v[32:47]
	ds_read_b128 v[168:171], v204 offset:9248
	ds_read_b128 v[172:175], v204 offset:13856
	s_waitcnt lgkmcnt(1)
	v_mfma_f32_32x32x16_bf16 v[80:95], v[168:171], v[160:163], v[80:95]
	v_mfma_f32_32x32x16_bf16 v[16:31], v[168:171], v[164:167], v[16:31]
	s_waitcnt lgkmcnt(0)
	v_mfma_f32_32x32x16_bf16 v[64:79], v[172:175], v[160:163], v[64:79]
	v_mfma_f32_32x32x16_bf16 v[0:15], v[172:175], v[164:167], v[0:15]
	s_setprio 0
	global_load_dwordx4 v[242:245], v[184:185], off offset:3840
	global_load_dwordx4 v[246:249], v[186:187], off offset:3840
	s_waitcnt vmcnt(9)
	ds_write_b128 v214, v[218:221]
	s_waitcnt vmcnt(8)
	ds_write_b128 v213, v[222:225]
	ds_read_b128 v[160:163], v205 offset:36928
	ds_read_b128 v[164:167], v205 offset:41536
	ds_read_b128 v[168:171], v204 offset:64
	ds_read_b128 v[172:175], v204 offset:4672
	s_setprio 1
	s_waitcnt lgkmcnt(1)
	v_mfma_f32_32x32x16_bf16 v[112:127], v[168:171], v[160:163], v[112:127]
	v_mfma_f32_32x32x16_bf16 v[48:63], v[168:171], v[164:167], v[48:63]
	s_waitcnt lgkmcnt(0)
	v_mfma_f32_32x32x16_bf16 v[96:111], v[172:175], v[160:163], v[96:111]
	v_mfma_f32_32x32x16_bf16 v[32:47], v[172:175], v[164:167], v[32:47]
	ds_read_b128 v[168:171], v204 offset:9280
	ds_read_b128 v[172:175], v204 offset:13888
	s_waitcnt lgkmcnt(1)
	v_mfma_f32_32x32x16_bf16 v[80:95], v[168:171], v[160:163], v[80:95]
	v_mfma_f32_32x32x16_bf16 v[16:31], v[168:171], v[164:167], v[16:31]
	s_waitcnt lgkmcnt(0)
	v_mfma_f32_32x32x16_bf16 v[64:79], v[172:175], v[160:163], v[64:79]
	v_mfma_f32_32x32x16_bf16 v[0:15], v[172:175], v[164:167], v[0:15]
	s_setprio 0
	global_load_dwordx4 v[218:221], v[198:199], off offset:3840
	global_load_dwordx4 v[222:225], v[200:201], off offset:3840
	s_waitcnt vmcnt(9)
	ds_write_b128 v217, v[226:229]
	s_waitcnt vmcnt(8)
	ds_write_b128 v216, v[230:233]
	ds_read_b128 v[160:163], v205 offset:36960
	ds_read_b128 v[164:167], v205 offset:41568
	ds_read_b128 v[168:171], v204 offset:96
	ds_read_b128 v[172:175], v204 offset:4704
	s_setprio 1
	s_waitcnt lgkmcnt(1)
	v_mfma_f32_32x32x16_bf16 v[112:127], v[168:171], v[160:163], v[112:127]
	v_mfma_f32_32x32x16_bf16 v[48:63], v[168:171], v[164:167], v[48:63]
	s_waitcnt lgkmcnt(0)
	v_mfma_f32_32x32x16_bf16 v[96:111], v[172:175], v[160:163], v[96:111]
	v_mfma_f32_32x32x16_bf16 v[32:47], v[172:175], v[164:167], v[32:47]
	ds_read_b128 v[168:171], v204 offset:9312
	ds_read_b128 v[172:175], v204 offset:13920
	s_waitcnt lgkmcnt(1)
	v_mfma_f32_32x32x16_bf16 v[80:95], v[168:171], v[160:163], v[80:95]
	v_mfma_f32_32x32x16_bf16 v[16:31], v[168:171], v[164:167], v[16:31]
	s_waitcnt lgkmcnt(0)
	v_mfma_f32_32x32x16_bf16 v[64:79], v[172:175], v[160:163], v[64:79]
	v_mfma_f32_32x32x16_bf16 v[0:15], v[172:175], v[164:167], v[0:15]
	s_setprio 0
	global_load_dwordx4 v[160:163], v[190:191], off offset:3968
	global_load_dwordx4 v[164:167], v[188:189], off offset:3968
	s_barrier
; template <bool trans>
; DI void gemm_core(const GTile& tl, const GTile& nx, bool has_next  , bool chain  , bool pre, u32x4 (&ra)[4], u32x4 (&rb)[4], char* smem, f32x16 (&acc)[2][4]) {
;     ...
;   const int nk = K / 64;
;   if (!pre) { G_LOAD(0); G_STORE(0); G_LOAD(1); }
;   for (int kt = 0; kt < nk; ++kt) {
;     __syncthreads();
;     G_COMPUTE(kt & 1, kt);
;   }
	s_waitcnt vmcnt(9)
	ds_write_b128 v215, v[176:179]
	s_waitcnt vmcnt(8)
	ds_write_b128 v215, v[180:183] offset:36864
	ds_read_b128 v[168:171], v208
	ds_read_b128 v[172:175], v208 offset:4608
	ds_read_b128 v[176:179], v192
	ds_read_b128 v[180:183], v192 offset:4608
	s_setprio 1
	s_waitcnt lgkmcnt(1)
	v_mfma_f32_32x32x16_bf16 v[112:127], v[176:179], v[168:171], v[112:127]
	v_mfma_f32_32x32x16_bf16 v[48:63], v[176:179], v[172:175], v[48:63]
	s_waitcnt lgkmcnt(0)
	v_mfma_f32_32x32x16_bf16 v[96:111], v[180:183], v[168:171], v[96:111]
	v_mfma_f32_32x32x16_bf16 v[32:47], v[180:183], v[172:175], v[32:47]
	ds_read_b128 v[176:179], v192 offset:9216
	ds_read_b128 v[180:183], v192 offset:13824
	s_waitcnt lgkmcnt(1)
	v_mfma_f32_32x32x16_bf16 v[80:95], v[176:179], v[168:171], v[80:95]
	v_mfma_f32_32x32x16_bf16 v[16:31], v[176:179], v[172:175], v[16:31]
	s_waitcnt lgkmcnt(0)
	v_mfma_f32_32x32x16_bf16 v[64:79], v[180:183], v[168:171], v[64:79]
	v_mfma_f32_32x32x16_bf16 v[0:15], v[180:183], v[172:175], v[0:15]
	s_setprio 0
	global_load_dwordx4 v[168:171], v[194:195], off offset:3968
	global_load_dwordx4 v[172:175], v[196:197], off offset:3968
	s_waitcnt vmcnt(9)
	ds_write_b128 v215, v[234:237] offset:9216
	s_waitcnt vmcnt(8)
	ds_write_b128 v215, v[238:241] offset:46080
	ds_read_b128 v[176:179], v208 offset:32
	ds_read_b128 v[180:183], v208 offset:4640
	ds_read_b128 v[188:191], v192 offset:32
	ds_read_b128 v[194:197], v192 offset:4640
	s_setprio 1
	s_waitcnt lgkmcnt(1)
	v_mfma_f32_32x32x16_bf16 v[112:127], v[188:191], v[176:179], v[112:127]
	v_mfma_f32_32x32x16_bf16 v[48:63], v[188:191], v[180:183], v[48:63]
	s_waitcnt lgkmcnt(0)
	v_mfma_f32_32x32x16_bf16 v[96:111], v[194:197], v[176:179], v[96:111]
	v_mfma_f32_32x32x16_bf16 v[32:47], v[194:197], v[180:183], v[32:47]
	ds_read_b128 v[188:191], v192 offset:9248
	ds_read_b128 v[194:197], v192 offset:13856
	s_waitcnt lgkmcnt(1)
	v_mfma_f32_32x32x16_bf16 v[80:95], v[188:191], v[176:179], v[80:95]
	v_mfma_f32_32x32x16_bf16 v[16:31], v[188:191], v[180:183], v[16:31]
	s_waitcnt lgkmcnt(0)
	v_mfma_f32_32x32x16_bf16 v[64:79], v[194:197], v[176:179], v[64:79]
	v_mfma_f32_32x32x16_bf16 v[0:15], v[194:197], v[180:183], v[0:15]
	s_setprio 0
	global_load_dwordx4 v[176:179], v[184:185], off offset:3968
	global_load_dwordx4 v[180:183], v[186:187], off offset:3968
	s_waitcnt vmcnt(9)
	ds_write_b128 v215, v[242:245] offset:18432
	s_waitcnt vmcnt(8)
	ds_write_b128 v215, v[246:249] offset:55296
	ds_read_b128 v[184:187], v208 offset:64
	ds_read_b128 v[188:191], v208 offset:4672
	ds_read_b128 v[194:197], v192 offset:64
	ds_read_b128 v[226:229], v192 offset:4672
	s_setprio 1
	s_waitcnt lgkmcnt(1)
	v_mfma_f32_32x32x16_bf16 v[112:127], v[194:197], v[184:187], v[112:127]
	v_mfma_f32_32x32x16_bf16 v[48:63], v[194:197], v[188:191], v[48:63]
	s_waitcnt lgkmcnt(0)
	v_mfma_f32_32x32x16_bf16 v[96:111], v[226:229], v[184:187], v[96:111]
	v_mfma_f32_32x32x16_bf16 v[32:47], v[226:229], v[188:191], v[32:47]
	ds_read_b128 v[194:197], v192 offset:9280
	ds_read_b128 v[226:229], v192 offset:13888
	s_waitcnt lgkmcnt(1)
	v_mfma_f32_32x32x16_bf16 v[80:95], v[194:197], v[184:187], v[80:95]
	v_mfma_f32_32x32x16_bf16 v[16:31], v[194:197], v[188:191], v[16:31]
	s_waitcnt lgkmcnt(0)
	v_mfma_f32_32x32x16_bf16 v[64:79], v[226:229], v[184:187], v[64:79]
	v_mfma_f32_32x32x16_bf16 v[0:15], v[226:229], v[188:191], v[0:15]
	s_setprio 0
	global_load_dwordx4 v[184:187], v[198:199], off offset:3968
	global_load_dwordx4 v[188:191], v[200:201], off offset:3968
	s_waitcnt vmcnt(9)
	ds_write_b128 v215, v[218:221] offset:27648
	s_waitcnt vmcnt(8)
	ds_write_b128 v215, v[222:225] offset:64512
	ds_read_b128 v[194:197], v208 offset:96
	ds_read_b128 v[198:201], v208 offset:4704
	ds_read_b128 v[218:221], v192 offset:96
	ds_read_b128 v[222:225], v192 offset:4704
	s_setprio 1
	s_waitcnt lgkmcnt(1)
	v_mfma_f32_32x32x16_bf16 v[112:127], v[218:221], v[194:197], v[112:127]
	v_mfma_f32_32x32x16_bf16 v[48:63], v[218:221], v[198:201], v[48:63]
	s_waitcnt lgkmcnt(0)
	v_mfma_f32_32x32x16_bf16 v[96:111], v[222:225], v[194:197], v[96:111]
	v_mfma_f32_32x32x16_bf16 v[32:47], v[222:225], v[198:201], v[32:47]
	ds_read_b128 v[218:221], v192 offset:9312
	ds_read_b128 v[222:225], v192 offset:13920
	s_waitcnt lgkmcnt(1)
	v_mfma_f32_32x32x16_bf16 v[80:95], v[218:221], v[194:197], v[80:95]
	v_mfma_f32_32x32x16_bf16 v[16:31], v[218:221], v[198:201], v[16:31]
	s_waitcnt lgkmcnt(0)
	v_mfma_f32_32x32x16_bf16 v[64:79], v[222:225], v[194:197], v[64:79]
	v_mfma_f32_32x32x16_bf16 v[0:15], v[222:225], v[198:201], v[0:15]
	s_setprio 0
	s_barrier
; template <bool trans>
; DI void gemm_core(const GTile& tl, const GTile& nx, bool has_next  , bool chain  , bool pre, u32x4 (&ra)[4], u32x4 (&rb)[4], char* smem, f32x16 (&acc)[2][4]) {
;     ...
;   const int nk = K / 64;
;   if (!pre) { G_LOAD(0); G_STORE(0); G_LOAD(1); }
;   for (int kt = 0; kt < nk; ++kt) {
;     __syncthreads();
;     G_COMPUTE(kt & 1, kt);
;   }
	s_waitcnt vmcnt(7)
	ds_write_b128 v209, v[160:163]
	s_waitcnt vmcnt(6)
	ds_write_b128 v210, v[164:167]
	ds_read_b128 v[194:197], v205 offset:36864
	ds_read_b128 v[198:201], v205 offset:41472
	ds_read_b128 v[218:221], v204
	ds_read_b128 v[222:225], v204 offset:4608
	s_setprio 1
	s_waitcnt lgkmcnt(1)
	v_mfma_f32_32x32x16_bf16 v[112:127], v[218:221], v[194:197], v[112:127]
	v_mfma_f32_32x32x16_bf16 v[48:63], v[218:221], v[198:201], v[48:63]
	s_waitcnt lgkmcnt(0)
	v_mfma_f32_32x32x16_bf16 v[96:111], v[222:225], v[194:197], v[96:111]
	v_mfma_f32_32x32x16_bf16 v[32:47], v[222:225], v[198:201], v[32:47]
	ds_read_b128 v[218:221], v204 offset:9216
	ds_read_b128 v[222:225], v204 offset:13824
	s_waitcnt lgkmcnt(1)
	v_mfma_f32_32x32x16_bf16 v[80:95], v[218:221], v[194:197], v[80:95]
	v_mfma_f32_32x32x16_bf16 v[16:31], v[218:221], v[198:201], v[16:31]
	s_waitcnt lgkmcnt(0)
	v_mfma_f32_32x32x16_bf16 v[64:79], v[222:225], v[194:197], v[64:79]
	v_mfma_f32_32x32x16_bf16 v[0:15], v[222:225], v[198:201], v[0:15]
	s_setprio 0
	s_waitcnt vmcnt(5)
	ds_write_b128 v212, v[168:171]
	s_waitcnt vmcnt(4)
	ds_write_b128 v211, v[172:175]
	ds_read_b128 v[194:197], v205 offset:36896
	ds_read_b128 v[198:201], v205 offset:41504
	ds_read_b128 v[218:221], v204 offset:32
	ds_read_b128 v[222:225], v204 offset:4640
	s_setprio 1
	s_waitcnt lgkmcnt(1)
	v_mfma_f32_32x32x16_bf16 v[112:127], v[218:221], v[194:197], v[112:127]
	v_mfma_f32_32x32x16_bf16 v[48:63], v[218:221], v[198:201], v[48:63]
	s_waitcnt lgkmcnt(0)
	v_mfma_f32_32x32x16_bf16 v[96:111], v[222:225], v[194:197], v[96:111]
	v_mfma_f32_32x32x16_bf16 v[32:47], v[222:225], v[198:201], v[32:47]
	ds_read_b128 v[218:221], v204 offset:9248
	ds_read_b128 v[222:225], v204 offset:13856
	s_waitcnt lgkmcnt(1)
	v_mfma_f32_32x32x16_bf16 v[80:95], v[218:221], v[194:197], v[80:95]
	v_mfma_f32_32x32x16_bf16 v[16:31], v[218:221], v[198:201], v[16:31]
	s_waitcnt lgkmcnt(0)
	v_mfma_f32_32x32x16_bf16 v[64:79], v[222:225], v[194:197], v[64:79]
	v_mfma_f32_32x32x16_bf16 v[0:15], v[222:225], v[198:201], v[0:15]
	s_setprio 0
	s_waitcnt vmcnt(3)
	ds_write_b128 v214, v[176:179]
	s_waitcnt vmcnt(2)
	ds_write_b128 v213, v[180:183]
	ds_read_b128 v[194:197], v205 offset:36928
	ds_read_b128 v[198:201], v205 offset:41536
	ds_read_b128 v[210:213], v204 offset:64
	ds_read_b128 v[218:221], v204 offset:4672
	s_setprio 1
	s_waitcnt lgkmcnt(1)
	v_mfma_f32_32x32x16_bf16 v[112:127], v[210:213], v[194:197], v[112:127]
	v_mfma_f32_32x32x16_bf16 v[48:63], v[210:213], v[198:201], v[48:63]
	s_waitcnt lgkmcnt(0)
	v_mfma_f32_32x32x16_bf16 v[96:111], v[218:221], v[194:197], v[96:111]
	v_mfma_f32_32x32x16_bf16 v[32:47], v[218:221], v[198:201], v[32:47]
	ds_read_b128 v[210:213], v204 offset:9280
	ds_read_b128 v[218:221], v204 offset:13888
	s_waitcnt lgkmcnt(1)
	v_mfma_f32_32x32x16_bf16 v[80:95], v[210:213], v[194:197], v[80:95]
	v_mfma_f32_32x32x16_bf16 v[16:31], v[210:213], v[198:201], v[16:31]
	s_waitcnt lgkmcnt(0)
	v_mfma_f32_32x32x16_bf16 v[64:79], v[218:221], v[194:197], v[64:79]
	v_mfma_f32_32x32x16_bf16 v[0:15], v[218:221], v[198:201], v[0:15]
	s_setprio 0
	s_waitcnt vmcnt(1)
	ds_write_b128 v217, v[184:187]
	s_waitcnt vmcnt(0)
	ds_write_b128 v216, v[188:191]
	ds_read_b128 v[194:197], v205 offset:36960
	ds_read_b128 v[198:201], v205 offset:41568
	ds_read_b128 v[210:213], v204 offset:96
	ds_read_b128 v[214:217], v204 offset:4704
	s_setprio 1
	s_waitcnt lgkmcnt(1)
	v_mfma_f32_32x32x16_bf16 v[112:127], v[210:213], v[194:197], v[112:127]
	v_mfma_f32_32x32x16_bf16 v[48:63], v[210:213], v[198:201], v[48:63]
	s_waitcnt lgkmcnt(0)
	v_mfma_f32_32x32x16_bf16 v[96:111], v[214:217], v[194:197], v[96:111]
	v_mfma_f32_32x32x16_bf16 v[32:47], v[214:217], v[198:201], v[32:47]
	ds_read_b128 v[210:213], v204 offset:9312
	ds_read_b128 v[214:217], v204 offset:13920
	s_waitcnt lgkmcnt(1)
	v_mfma_f32_32x32x16_bf16 v[80:95], v[210:213], v[194:197], v[80:95]
	v_mfma_f32_32x32x16_bf16 v[16:31], v[210:213], v[198:201], v[16:31]
	s_waitcnt lgkmcnt(0)
	v_mfma_f32_32x32x16_bf16 v[64:79], v[214:217], v[194:197], v[64:79]
	v_mfma_f32_32x32x16_bf16 v[0:15], v[214:217], v[198:201], v[0:15]
	s_setprio 0
	s_barrier
; template <bool trans>
; DI void gemm_core(const GTile& tl, const GTile& nx, bool has_next  , bool chain  , bool pre, u32x4 (&ra)[4], u32x4 (&rb)[4], char* smem, f32x16 (&acc)[2][4]) {
;     ...
;   const int nk = K / 64;
;   if (!pre) { G_LOAD(0); G_STORE(0); G_LOAD(1); }
;   for (int kt = 0; kt < nk; ++kt) {
;     __syncthreads();
;     G_COMPUTE(kt & 1, kt);
;   }
;   if (!has_next) __syncthreads();
	ds_read_b128 v[194:197], v208
	ds_read_b128 v[198:201], v208 offset:4608
	ds_read_b128 v[210:213], v192
	ds_read_b128 v[214:217], v192 offset:4608
	s_setprio 1
	s_waitcnt lgkmcnt(1)
	v_mfma_f32_32x32x16_bf16 v[112:127], v[210:213], v[194:197], v[112:127]
	v_mfma_f32_32x32x16_bf16 v[48:63], v[210:213], v[198:201], v[48:63]
	s_waitcnt lgkmcnt(0)
	v_mfma_f32_32x32x16_bf16 v[96:111], v[214:217], v[194:197], v[96:111]
	v_mfma_f32_32x32x16_bf16 v[32:47], v[214:217], v[198:201], v[32:47]
	ds_read_b128 v[210:213], v192 offset:9216
	ds_read_b128 v[214:217], v192 offset:13824
	s_waitcnt lgkmcnt(1)
	v_mfma_f32_32x32x16_bf16 v[80:95], v[210:213], v[194:197], v[80:95]
	v_mfma_f32_32x32x16_bf16 v[16:31], v[210:213], v[198:201], v[16:31]
	s_waitcnt lgkmcnt(0)
	v_mfma_f32_32x32x16_bf16 v[64:79], v[214:217], v[194:197], v[64:79]
	v_mfma_f32_32x32x16_bf16 v[0:15], v[214:217], v[198:201], v[0:15]
	s_setprio 0
	ds_read_b128 v[194:197], v208 offset:32
	ds_read_b128 v[198:201], v208 offset:4640
	ds_read_b128 v[210:213], v192 offset:32
	ds_read_b128 v[214:217], v192 offset:4640
	s_setprio 1
	s_waitcnt lgkmcnt(1)
	v_mfma_f32_32x32x16_bf16 v[112:127], v[210:213], v[194:197], v[112:127]
	v_mfma_f32_32x32x16_bf16 v[48:63], v[210:213], v[198:201], v[48:63]
	s_waitcnt lgkmcnt(0)
	v_mfma_f32_32x32x16_bf16 v[96:111], v[214:217], v[194:197], v[96:111]
	v_mfma_f32_32x32x16_bf16 v[32:47], v[214:217], v[198:201], v[32:47]
	ds_read_b128 v[210:213], v192 offset:9248
	ds_read_b128 v[214:217], v192 offset:13856
	s_waitcnt lgkmcnt(1)
	v_mfma_f32_32x32x16_bf16 v[80:95], v[210:213], v[194:197], v[80:95]
	v_mfma_f32_32x32x16_bf16 v[16:31], v[210:213], v[198:201], v[16:31]
	s_waitcnt lgkmcnt(0)
	v_mfma_f32_32x32x16_bf16 v[64:79], v[214:217], v[194:197], v[64:79]
	v_mfma_f32_32x32x16_bf16 v[0:15], v[214:217], v[198:201], v[0:15]
	s_setprio 0
	ds_read_b128 v[194:197], v208 offset:64
	ds_read_b128 v[198:201], v208 offset:4672
	ds_read_b128 v[210:213], v192 offset:64
	ds_read_b128 v[214:217], v192 offset:4672
	s_setprio 1
	s_waitcnt lgkmcnt(1)
	v_mfma_f32_32x32x16_bf16 v[112:127], v[210:213], v[194:197], v[112:127]
	v_mfma_f32_32x32x16_bf16 v[48:63], v[210:213], v[198:201], v[48:63]
	s_waitcnt lgkmcnt(0)
	v_mfma_f32_32x32x16_bf16 v[96:111], v[214:217], v[194:197], v[96:111]
	v_mfma_f32_32x32x16_bf16 v[32:47], v[214:217], v[198:201], v[32:47]
	ds_read_b128 v[210:213], v192 offset:9280
	ds_read_b128 v[214:217], v192 offset:13888
	s_waitcnt lgkmcnt(1)
	v_mfma_f32_32x32x16_bf16 v[80:95], v[210:213], v[194:197], v[80:95]
	v_mfma_f32_32x32x16_bf16 v[16:31], v[210:213], v[198:201], v[16:31]
	s_waitcnt lgkmcnt(0)
	v_mfma_f32_32x32x16_bf16 v[64:79], v[214:217], v[194:197], v[64:79]
	v_mfma_f32_32x32x16_bf16 v[0:15], v[214:217], v[198:201], v[0:15]
	s_setprio 0
	ds_read_b128 v[194:197], v208 offset:96
	ds_read_b128 v[198:201], v208 offset:4704
	ds_read_b128 v[208:211], v192 offset:96
	ds_read_b128 v[212:215], v192 offset:4704
	s_setprio 1
	s_waitcnt lgkmcnt(1)
	v_mfma_f32_32x32x16_bf16 v[112:127], v[208:211], v[194:197], v[112:127]
	v_mfma_f32_32x32x16_bf16 v[48:63], v[208:211], v[198:201], v[48:63]
	s_waitcnt lgkmcnt(0)
	v_mfma_f32_32x32x16_bf16 v[96:111], v[212:215], v[194:197], v[96:111]
	v_mfma_f32_32x32x16_bf16 v[32:47], v[212:215], v[198:201], v[32:47]
	ds_read_b128 v[208:211], v192 offset:9312
	ds_read_b128 v[212:215], v192 offset:13920
	s_waitcnt lgkmcnt(1)
	v_mfma_f32_32x32x16_bf16 v[80:95], v[208:211], v[194:197], v[80:95]
	v_mfma_f32_32x32x16_bf16 v[16:31], v[208:211], v[198:201], v[16:31]
	s_waitcnt lgkmcnt(0)
	v_mfma_f32_32x32x16_bf16 v[64:79], v[212:215], v[194:197], v[64:79]
	v_mfma_f32_32x32x16_bf16 v[0:15], v[212:215], v[198:201], v[0:15]
	s_setprio 0
	s_andn2_b64 vcc, exec, s[48:49]
	s_cbranch_vccnz .LBB0_105
	s_barrier

; template <bool trans>
; DI void gemm_core(const GTile& tl, const GTile& nx, bool has_next  , bool chain  , bool pre, u32x4 (&ra)[4], u32x4 (&rb)[4], char* smem, f32x16 (&acc)[2][4]) {
;     ...
;   const int lrow = tid >> 3, kc = tid & 7;
;   const unsigned aoff = (unsigned)(lrow * lda + kc * 8) * 2u, boff = (unsigned)(lrow * ldb + kc * 8) * 2u;
;   const char* ag = (const char*)(A + (size_t)m0 * lda);
;   const char* bg = (const char*)(Bt + (size_t)n0 * ldb);
;   const unsigned aoffn = (unsigned)(lrow * nx.lda + kc * 8) * 2u, boffn = (unsigned)(lrow * nx.ldb + kc * 8) * 2u;
;   const char* agn = (const char*)(nx.A + (size_t)nx.m0 * nx.lda);
;   const char* bgn = (const char*)(nx.Bt + (size_t)nx.n0 * nx.ldb);
;     ...
;   const int nk = K / 64;
;   if (!pre) { G_LOAD(0); G_STORE(0); G_LOAD(1); }
;   for (int kt = 0; kt < nk; ++kt) {
;     __syncthreads();
;     G_COMPUTE(kt & 1, kt);
;   }
.LBB0_111:
	v_lshl_add_u64 v[136:137], s[0:1], 0, v[192:193]
	v_lshl_add_u64 v[138:139], s[2:3], 0, v[192:193]
	s_waitcnt lgkmcnt(0)
	s_barrier
	global_load_dwordx4 v[184:187], v[136:137], off offset:256
	global_load_dwordx4 v[188:191], v[138:139], off offset:256
	s_and_b32 s1, s36, 0x1f80000
	s_and_b32 s0, s38, 0xffffff00
	s_and_b32 s4, s33, 0xc0
	s_lshl_b32 s1, s1, 1
	s_add_u32 s2, s16, s1
	s_addc_u32 s3, s17, 0
	s_ashr_i32 s1, s0, 31
	s_lshl_b64 s[0:1], s[0:1], 12
	s_add_u32 s0, s22, s0
	s_addc_u32 s1, s23, s1
	s_lshr_b32 s5, s33, 1
	v_and_b32_e32 v11, 31, v8
	s_and_b32 s5, s5, 0xfffff80
	v_or_b32_e32 v12, s5, v11
	v_or_b32_e32 v11, s4, v11
	v_add3_u32 v148, 16, v10, v9
	v_lshrrev_b32_e32 v8, 1, v8
	v_mul_u32_u24_e32 v150, 0x90, v11
	v_lshl_add_u64 v[130:131], s[2:3], 0, v[192:193]
	v_lshl_add_u64 v[128:129], s[0:1], 0, v[192:193]
	v_and_b32_e32 v204, 16, v8
	v_add_u32_e32 v192, 0x12000, v148
	v_mul_lo_u32 v149, v12, s45
	v_add3_u32 v152, 16, v150, v204
	v_add_u32_e32 v159, 0x1b000, v148
	ds_write_b128 v192, v[0:3]
	s_waitcnt vmcnt(5)
	ds_write_b128 v159, v[4:7]
	v_add3_u32 v151, 16, v149, v204
	ds_read_b128 v[0:3], v152 offset:36864
	ds_read_b128 v[4:7], v152 offset:41472
	ds_read_b128 v[8:11], v151
	ds_read_b128 v[12:15], v151 offset:4608
	v_lshl_add_u64 v[140:141], v[136:137], 0, s[34:35]
	v_lshl_add_u64 v[142:143], v[138:139], 0, s[34:35]
	v_lshl_add_u64 v[132:133], v[136:137], 0, s[42:43]
	v_lshl_add_u64 v[134:135], v[138:139], 0, s[42:43]
	s_setprio 1
	s_waitcnt lgkmcnt(1)
	v_mfma_f32_32x32x16_bf16 v[112:127], v[0:3], v[8:11], 0
	v_mfma_f32_32x32x16_bf16 v[48:63], v[4:7], v[8:11], 0
	s_waitcnt lgkmcnt(0)
	v_mfma_f32_32x32x16_bf16 v[96:111], v[0:3], v[12:15], 0
	v_mfma_f32_32x32x16_bf16 v[32:47], v[4:7], v[12:15], 0
	ds_read_b128 v[8:11], v151 offset:9216
	ds_read_b128 v[12:15], v151 offset:13824
	s_waitcnt lgkmcnt(1)
	v_mfma_f32_32x32x16_bf16 v[80:95], v[0:3], v[8:11], 0
	v_mfma_f32_32x32x16_bf16 v[16:31], v[4:7], v[8:11], 0
	s_waitcnt lgkmcnt(0)
	v_mfma_f32_32x32x16_bf16 v[64:79], v[0:3], v[12:15], 0
	v_mfma_f32_32x32x16_bf16 v[0:15], v[4:7], v[12:15], 0
	s_setprio 0
	global_load_dwordx4 v[194:197], v[140:141], off offset:256
	global_load_dwordx4 v[198:201], v[142:143], off offset:256
	v_add_u32_e32 v158, 0x14400, v148
	v_add_u32_e32 v157, 0x1d400, v148
	ds_write_b128 v158, v[176:179]
	s_waitcnt vmcnt(6)
	ds_write_b128 v157, v[180:183]
	ds_read_b128 v[144:147], v152 offset:36896
	ds_read_b128 v[176:179], v152 offset:41504
	ds_read_b128 v[180:183], v151 offset:32
	ds_read_b128 v[208:211], v151 offset:4640
	s_setprio 1
	s_waitcnt lgkmcnt(1)
	v_mfma_f32_32x32x16_bf16 v[112:127], v[144:147], v[180:183], v[112:127]
	v_mfma_f32_32x32x16_bf16 v[48:63], v[176:179], v[180:183], v[48:63]
	s_waitcnt lgkmcnt(0)
	v_mfma_f32_32x32x16_bf16 v[96:111], v[144:147], v[208:211], v[96:111]
	v_mfma_f32_32x32x16_bf16 v[32:47], v[176:179], v[208:211], v[32:47]
	ds_read_b128 v[180:183], v151 offset:9248
	ds_read_b128 v[208:211], v151 offset:13856
	s_waitcnt lgkmcnt(1)
	v_mfma_f32_32x32x16_bf16 v[80:95], v[144:147], v[180:183], v[80:95]
	v_mfma_f32_32x32x16_bf16 v[16:31], v[176:179], v[180:183], v[16:31]
	s_waitcnt lgkmcnt(0)
	v_mfma_f32_32x32x16_bf16 v[64:79], v[144:147], v[208:211], v[64:79]
	v_mfma_f32_32x32x16_bf16 v[0:15], v[176:179], v[208:211], v[0:15]
	s_setprio 0
	global_load_dwordx4 v[176:179], v[132:133], off offset:256
	global_load_dwordx4 v[180:183], v[134:135], off offset:256
	v_add_u32_e32 v154, 0x16800, v148
	v_add_u32_e32 v153, 0x1f800, v148
	ds_write_b128 v154, v[168:171]
	s_waitcnt vmcnt(7)
	ds_write_b128 v153, v[172:175]
	ds_read_b128 v[144:147], v152 offset:36928
	ds_read_b128 v[168:171], v152 offset:41536
	ds_read_b128 v[172:175], v151 offset:64
	ds_read_b128 v[208:211], v151 offset:4672
	s_setprio 1
	s_waitcnt lgkmcnt(1)
	v_mfma_f32_32x32x16_bf16 v[112:127], v[144:147], v[172:175], v[112:127]
	v_mfma_f32_32x32x16_bf16 v[48:63], v[168:171], v[172:175], v[48:63]
	s_waitcnt lgkmcnt(0)
	v_mfma_f32_32x32x16_bf16 v[96:111], v[144:147], v[208:211], v[96:111]
	v_mfma_f32_32x32x16_bf16 v[32:47], v[168:171], v[208:211], v[32:47]
	ds_read_b128 v[172:175], v151 offset:9280
	ds_read_b128 v[208:211], v151 offset:13888
	s_waitcnt lgkmcnt(1)
	v_mfma_f32_32x32x16_bf16 v[80:95], v[144:147], v[172:175], v[80:95]
	v_mfma_f32_32x32x16_bf16 v[16:31], v[168:171], v[172:175], v[16:31]
	s_waitcnt lgkmcnt(0)
	v_mfma_f32_32x32x16_bf16 v[64:79], v[144:147], v[208:211], v[64:79]
	v_mfma_f32_32x32x16_bf16 v[0:15], v[168:171], v[208:211], v[0:15]
	s_setprio 0
	v_add_co_u32_e32 v144, vcc, s44, v136
	v_add_u32_e32 v156, 0x18c00, v148
	s_nop 0
	v_addc_co_u32_e32 v145, vcc, 0, v137, vcc
	v_add_co_u32_e32 v146, vcc, s44, v138
	v_add_u32_e32 v155, 0x21c00, v148
	s_nop 0
	v_addc_co_u32_e32 v147, vcc, 0, v139, vcc
	global_load_dwordx4 v[168:171], v[144:145], off offset:256
	global_load_dwordx4 v[172:175], v[146:147], off offset:256
	ds_write_b128 v156, v[160:163]
	s_waitcnt vmcnt(8)
	ds_write_b128 v155, v[164:167]
	ds_read_b128 v[160:163], v152 offset:36960
	ds_read_b128 v[164:167], v152 offset:41568
	ds_read_b128 v[208:211], v151 offset:96
	ds_read_b128 v[212:215], v151 offset:4704
	s_setprio 1
	s_waitcnt lgkmcnt(1)
	v_mfma_f32_32x32x16_bf16 v[112:127], v[160:163], v[208:211], v[112:127]
	v_mfma_f32_32x32x16_bf16 v[48:63], v[164:167], v[208:211], v[48:63]
	s_waitcnt lgkmcnt(0)
	v_mfma_f32_32x32x16_bf16 v[96:111], v[160:163], v[212:215], v[96:111]
	v_mfma_f32_32x32x16_bf16 v[32:47], v[164:167], v[212:215], v[32:47]
	ds_read_b128 v[208:211], v151 offset:9312
	ds_read_b128 v[212:215], v151 offset:13920
	s_waitcnt lgkmcnt(1)
	v_mfma_f32_32x32x16_bf16 v[80:95], v[160:163], v[208:211], v[80:95]
	v_mfma_f32_32x32x16_bf16 v[16:31], v[164:167], v[208:211], v[16:31]
	s_waitcnt lgkmcnt(0)
	v_mfma_f32_32x32x16_bf16 v[64:79], v[160:163], v[212:215], v[64:79]
	v_mfma_f32_32x32x16_bf16 v[0:15], v[164:167], v[212:215], v[0:15]
	s_setprio 0
	global_load_dwordx4 v[160:163], v[136:137], off offset:384
	global_load_dwordx4 v[164:167], v[138:139], off offset:384
	s_barrier
; template <bool trans>
; DI void gemm_core(const GTile& tl, const GTile& nx, bool has_next  , bool chain  , bool pre, u32x4 (&ra)[4], u32x4 (&rb)[4], char* smem, f32x16 (&acc)[2][4]) {
;     ...
;   const int nk = K / 64;
;   if (!pre) { G_LOAD(0); G_STORE(0); G_LOAD(1); }
;   for (int kt = 0; kt < nk; ++kt) {
;     __syncthreads();
;     G_COMPUTE(kt & 1, kt);
;   }
	s_add_i32 s0, 16, 0x12000
	v_add3_u32 v149, s0, v149, v204
	s_add_i32 s0, 16, 0x1b000
	v_add3_u32 v150, s0, v150, v204
	s_waitcnt vmcnt(9)
	ds_write_b128 v148, v[184:187]
	s_waitcnt vmcnt(8)
	ds_write_b128 v148, v[188:191] offset:36864
	ds_read_b128 v[184:187], v150
	ds_read_b128 v[188:191], v150 offset:4608
	ds_read_b128 v[208:211], v149
	ds_read_b128 v[212:215], v149 offset:4608
	s_setprio 1
	s_waitcnt lgkmcnt(1)
	v_mfma_f32_32x32x16_bf16 v[112:127], v[184:187], v[208:211], v[112:127]
	v_mfma_f32_32x32x16_bf16 v[48:63], v[188:191], v[208:211], v[48:63]
	s_waitcnt lgkmcnt(0)
	v_mfma_f32_32x32x16_bf16 v[96:111], v[184:187], v[212:215], v[96:111]
	v_mfma_f32_32x32x16_bf16 v[32:47], v[188:191], v[212:215], v[32:47]
	ds_read_b128 v[208:211], v149 offset:9216
	ds_read_b128 v[212:215], v149 offset:13824
	s_waitcnt lgkmcnt(1)
	v_mfma_f32_32x32x16_bf16 v[80:95], v[184:187], v[208:211], v[80:95]
	v_mfma_f32_32x32x16_bf16 v[16:31], v[188:191], v[208:211], v[16:31]
	s_waitcnt lgkmcnt(0)
	v_mfma_f32_32x32x16_bf16 v[64:79], v[184:187], v[212:215], v[64:79]
	v_mfma_f32_32x32x16_bf16 v[0:15], v[188:191], v[212:215], v[0:15]
	s_setprio 0
	global_load_dwordx4 v[184:187], v[140:141], off offset:384
	global_load_dwordx4 v[188:191], v[142:143], off offset:384
	s_waitcnt vmcnt(9)
	ds_write_b128 v148, v[194:197] offset:9216
	s_waitcnt vmcnt(8)
	ds_write_b128 v148, v[198:201] offset:46080
	ds_read_b128 v[194:197], v150 offset:32
	ds_read_b128 v[198:201], v150 offset:4640
	ds_read_b128 v[208:211], v149 offset:32
	ds_read_b128 v[212:215], v149 offset:4640
	s_setprio 1
	s_waitcnt lgkmcnt(1)
	v_mfma_f32_32x32x16_bf16 v[112:127], v[194:197], v[208:211], v[112:127]
	v_mfma_f32_32x32x16_bf16 v[48:63], v[198:201], v[208:211], v[48:63]
	s_waitcnt lgkmcnt(0)
	v_mfma_f32_32x32x16_bf16 v[96:111], v[194:197], v[212:215], v[96:111]
	v_mfma_f32_32x32x16_bf16 v[32:47], v[198:201], v[212:215], v[32:47]
	ds_read_b128 v[208:211], v149 offset:9248
	ds_read_b128 v[212:215], v149 offset:13856
	s_waitcnt lgkmcnt(1)
	v_mfma_f32_32x32x16_bf16 v[80:95], v[194:197], v[208:211], v[80:95]
	v_mfma_f32_32x32x16_bf16 v[16:31], v[198:201], v[208:211], v[16:31]
	s_waitcnt lgkmcnt(0)
	v_mfma_f32_32x32x16_bf16 v[64:79], v[194:197], v[212:215], v[64:79]
	v_mfma_f32_32x32x16_bf16 v[0:15], v[198:201], v[212:215], v[0:15]
	s_setprio 0
	global_load_dwordx4 v[194:197], v[132:133], off offset:384
	global_load_dwordx4 v[198:201], v[134:135], off offset:384
	s_waitcnt vmcnt(9)
	ds_write_b128 v148, v[176:179] offset:18432
	s_waitcnt vmcnt(8)
	ds_write_b128 v148, v[180:183] offset:55296
	ds_read_b128 v[176:179], v150 offset:64
	ds_read_b128 v[180:183], v150 offset:4672
	ds_read_b128 v[208:211], v149 offset:64
	ds_read_b128 v[212:215], v149 offset:4672
	s_setprio 1
	s_waitcnt lgkmcnt(1)
	v_mfma_f32_32x32x16_bf16 v[112:127], v[176:179], v[208:211], v[112:127]
	v_mfma_f32_32x32x16_bf16 v[48:63], v[180:183], v[208:211], v[48:63]
	s_waitcnt lgkmcnt(0)
	v_mfma_f32_32x32x16_bf16 v[96:111], v[176:179], v[212:215], v[96:111]
	v_mfma_f32_32x32x16_bf16 v[32:47], v[180:183], v[212:215], v[32:47]
	ds_read_b128 v[208:211], v149 offset:9280
	ds_read_b128 v[212:215], v149 offset:13888
	s_waitcnt lgkmcnt(1)
	v_mfma_f32_32x32x16_bf16 v[80:95], v[176:179], v[208:211], v[80:95]
	v_mfma_f32_32x32x16_bf16 v[16:31], v[180:183], v[208:211], v[16:31]
	s_waitcnt lgkmcnt(0)
	v_mfma_f32_32x32x16_bf16 v[64:79], v[176:179], v[212:215], v[64:79]
	v_mfma_f32_32x32x16_bf16 v[0:15], v[180:183], v[212:215], v[0:15]
	s_setprio 0
	global_load_dwordx4 v[176:179], v[144:145], off offset:384
	global_load_dwordx4 v[180:183], v[146:147], off offset:384
	s_waitcnt vmcnt(9)
	ds_write_b128 v148, v[168:171] offset:27648
	s_waitcnt vmcnt(8)
	ds_write_b128 v148, v[172:175] offset:64512
	ds_read_b128 v[168:171], v150 offset:96
	ds_read_b128 v[172:175], v150 offset:4704
	ds_read_b128 v[208:211], v149 offset:96
	ds_read_b128 v[212:215], v149 offset:4704
	s_setprio 1
	s_waitcnt lgkmcnt(1)
	v_mfma_f32_32x32x16_bf16 v[112:127], v[168:171], v[208:211], v[112:127]
	v_mfma_f32_32x32x16_bf16 v[48:63], v[172:175], v[208:211], v[48:63]
	s_waitcnt lgkmcnt(0)
	v_mfma_f32_32x32x16_bf16 v[96:111], v[168:171], v[212:215], v[96:111]
	v_mfma_f32_32x32x16_bf16 v[32:47], v[172:175], v[212:215], v[32:47]
	ds_read_b128 v[208:211], v149 offset:9312
	ds_read_b128 v[212:215], v149 offset:13920
	s_waitcnt lgkmcnt(1)
	v_mfma_f32_32x32x16_bf16 v[80:95], v[168:171], v[208:211], v[80:95]
	v_mfma_f32_32x32x16_bf16 v[16:31], v[172:175], v[208:211], v[16:31]
	s_waitcnt lgkmcnt(0)
	v_mfma_f32_32x32x16_bf16 v[64:79], v[168:171], v[212:215], v[64:79]
	v_mfma_f32_32x32x16_bf16 v[0:15], v[172:175], v[212:215], v[0:15]
	s_setprio 0
	global_load_dwordx4 v[168:171], v[136:137], off offset:512
	global_load_dwordx4 v[172:175], v[138:139], off offset:512
	s_barrier
; template <bool trans>
; DI void gemm_core(const GTile& tl, const GTile& nx, bool has_next  , bool chain  , bool pre, u32x4 (&ra)[4], u32x4 (&rb)[4], char* smem, f32x16 (&acc)[2][4]) {
;     ...
;   const int nk = K / 64;
;   if (!pre) { G_LOAD(0); G_STORE(0); G_LOAD(1); }
;   for (int kt = 0; kt < nk; ++kt) {
;     __syncthreads();
;     G_COMPUTE(kt & 1, kt);
;   }
	s_waitcnt vmcnt(9)
	ds_write_b128 v192, v[160:163]
	s_waitcnt vmcnt(8)
	ds_write_b128 v159, v[164:167]
	ds_read_b128 v[160:163], v152 offset:36864
	ds_read_b128 v[164:167], v152 offset:41472
	ds_read_b128 v[208:211], v151
	ds_read_b128 v[212:215], v151 offset:4608
	s_setprio 1
	s_waitcnt lgkmcnt(1)
	v_mfma_f32_32x32x16_bf16 v[112:127], v[160:163], v[208:211], v[112:127]
	v_mfma_f32_32x32x16_bf16 v[48:63], v[164:167], v[208:211], v[48:63]
	s_waitcnt lgkmcnt(0)
	v_mfma_f32_32x32x16_bf16 v[96:111], v[160:163], v[212:215], v[96:111]
	v_mfma_f32_32x32x16_bf16 v[32:47], v[164:167], v[212:215], v[32:47]
	ds_read_b128 v[208:211], v151 offset:9216
	ds_read_b128 v[212:215], v151 offset:13824
	s_waitcnt vmcnt(7)
	ds_write_b128 v158, v[184:187]
	s_waitcnt vmcnt(6)
	ds_write_b128 v157, v[188:191]
	ds_read_b128 v[184:187], v152 offset:36896
	ds_read_b128 v[188:191], v152 offset:41504
	s_waitcnt lgkmcnt(5)
	v_mfma_f32_32x32x16_bf16 v[80:95], v[160:163], v[208:211], v[80:95]
	v_mfma_f32_32x32x16_bf16 v[16:31], v[164:167], v[208:211], v[16:31]
	ds_read_b128 v[208:211], v151 offset:32
	s_waitcnt lgkmcnt(5)
	v_mfma_f32_32x32x16_bf16 v[64:79], v[160:163], v[212:215], v[64:79]
	v_mfma_f32_32x32x16_bf16 v[0:15], v[164:167], v[212:215], v[0:15]
	ds_read_b128 v[212:215], v151 offset:4640
	s_setprio 0
	global_load_dwordx4 v[160:163], v[140:141], off offset:512
	global_load_dwordx4 v[164:167], v[142:143], off offset:512
	s_setprio 1
	s_waitcnt lgkmcnt(1)
	v_mfma_f32_32x32x16_bf16 v[112:127], v[184:187], v[208:211], v[112:127]
	v_mfma_f32_32x32x16_bf16 v[48:63], v[188:191], v[208:211], v[48:63]
	s_waitcnt lgkmcnt(0)
	v_mfma_f32_32x32x16_bf16 v[96:111], v[184:187], v[212:215], v[96:111]
	v_mfma_f32_32x32x16_bf16 v[32:47], v[188:191], v[212:215], v[32:47]
	ds_read_b128 v[208:211], v151 offset:9248
	ds_read_b128 v[212:215], v151 offset:13856
	s_waitcnt vmcnt(7)
	ds_write_b128 v154, v[194:197]
	s_waitcnt vmcnt(6)
	ds_write_b128 v153, v[198:201]
	ds_read_b128 v[194:197], v152 offset:36928
	ds_read_b128 v[198:201], v152 offset:41536
	s_waitcnt lgkmcnt(5)
	v_mfma_f32_32x32x16_bf16 v[80:95], v[184:187], v[208:211], v[80:95]
	v_mfma_f32_32x32x16_bf16 v[16:31], v[188:191], v[208:211], v[16:31]
	ds_read_b128 v[208:211], v151 offset:64
	s_waitcnt lgkmcnt(5)
	v_mfma_f32_32x32x16_bf16 v[64:79], v[184:187], v[212:215], v[64:79]
	v_mfma_f32_32x32x16_bf16 v[0:15], v[188:191], v[212:215], v[0:15]
	ds_read_b128 v[212:215], v151 offset:4672
	s_setprio 0
	global_load_dwordx4 v[184:187], v[132:133], off offset:512
	global_load_dwordx4 v[188:191], v[134:135], off offset:512
	s_setprio 1
	s_waitcnt lgkmcnt(1)
	v_mfma_f32_32x32x16_bf16 v[112:127], v[194:197], v[208:211], v[112:127]
	v_mfma_f32_32x32x16_bf16 v[48:63], v[198:201], v[208:211], v[48:63]
	s_waitcnt lgkmcnt(0)
	v_mfma_f32_32x32x16_bf16 v[96:111], v[194:197], v[212:215], v[96:111]
	v_mfma_f32_32x32x16_bf16 v[32:47], v[198:201], v[212:215], v[32:47]
	ds_read_b128 v[208:211], v151 offset:9280
	ds_read_b128 v[212:215], v151 offset:13888
	s_waitcnt vmcnt(7)
	ds_write_b128 v156, v[176:179]
	s_waitcnt vmcnt(6)
	ds_write_b128 v155, v[180:183]
	ds_read_b128 v[176:179], v152 offset:36960
	ds_read_b128 v[180:183], v152 offset:41568
	s_waitcnt lgkmcnt(5)
	v_mfma_f32_32x32x16_bf16 v[80:95], v[194:197], v[208:211], v[80:95]
	v_mfma_f32_32x32x16_bf16 v[16:31], v[198:201], v[208:211], v[16:31]
	ds_read_b128 v[208:211], v151 offset:96
	s_waitcnt lgkmcnt(5)
	v_mfma_f32_32x32x16_bf16 v[64:79], v[194:197], v[212:215], v[64:79]
	v_mfma_f32_32x32x16_bf16 v[0:15], v[198:201], v[212:215], v[0:15]
	ds_read_b128 v[212:215], v151 offset:4704
	s_setprio 0
	global_load_dwordx4 v[194:197], v[144:145], off offset:512
	global_load_dwordx4 v[198:201], v[146:147], off offset:512
	s_setprio 1
	s_waitcnt lgkmcnt(1)
	v_mfma_f32_32x32x16_bf16 v[112:127], v[176:179], v[208:211], v[112:127]
	v_mfma_f32_32x32x16_bf16 v[48:63], v[180:183], v[208:211], v[48:63]
	s_waitcnt lgkmcnt(0)
	v_mfma_f32_32x32x16_bf16 v[96:111], v[176:179], v[212:215], v[96:111]
	v_mfma_f32_32x32x16_bf16 v[32:47], v[180:183], v[212:215], v[32:47]
	ds_read_b128 v[208:211], v151 offset:9312
	ds_read_b128 v[212:215], v151 offset:13920
	s_waitcnt lgkmcnt(0)
	s_barrier
	s_waitcnt vmcnt(7)
	ds_write_b128 v148, v[168:171]
	s_waitcnt vmcnt(6)
	ds_write_b128 v148, v[172:175] offset:36864
	ds_read_b128 v[168:171], v150
	ds_read_b128 v[172:175], v150 offset:4608
	v_mfma_f32_32x32x16_bf16 v[80:95], v[176:179], v[208:211], v[80:95]
	v_mfma_f32_32x32x16_bf16 v[16:31], v[180:183], v[208:211], v[16:31]
	ds_read_b128 v[208:211], v149
	v_mfma_f32_32x32x16_bf16 v[64:79], v[176:179], v[212:215], v[64:79]
	v_mfma_f32_32x32x16_bf16 v[0:15], v[180:183], v[212:215], v[0:15]
	ds_read_b128 v[212:215], v149 offset:4608
	s_setprio 0
	global_load_dwordx4 v[176:179], v[136:137], off offset:640
	global_load_dwordx4 v[180:183], v[138:139], off offset:640
	s_setprio 1
	s_waitcnt lgkmcnt(1)
	v_mfma_f32_32x32x16_bf16 v[112:127], v[168:171], v[208:211], v[112:127]
	v_mfma_f32_32x32x16_bf16 v[48:63], v[172:175], v[208:211], v[48:63]
	s_waitcnt lgkmcnt(0)
	v_mfma_f32_32x32x16_bf16 v[96:111], v[168:171], v[212:215], v[96:111]
	v_mfma_f32_32x32x16_bf16 v[32:47], v[172:175], v[212:215], v[32:47]
	ds_read_b128 v[208:211], v149 offset:9216
	ds_read_b128 v[212:215], v149 offset:13824
	s_waitcnt vmcnt(7)
	ds_write_b128 v148, v[160:163] offset:9216
	s_waitcnt vmcnt(6)
	ds_write_b128 v148, v[164:167] offset:46080
	ds_read_b128 v[160:163], v150 offset:32
	ds_read_b128 v[164:167], v150 offset:4640
	s_waitcnt lgkmcnt(5)
	v_mfma_f32_32x32x16_bf16 v[80:95], v[168:171], v[208:211], v[80:95]
	v_mfma_f32_32x32x16_bf16 v[16:31], v[172:175], v[208:211], v[16:31]
	ds_read_b128 v[208:211], v149 offset:32
	s_waitcnt lgkmcnt(5)
; template <bool trans>
; DI void gemm_core(const GTile& tl, const GTile& nx, bool has_next  , bool chain  , bool pre, u32x4 (&ra)[4], u32x4 (&rb)[4], char* smem, f32x16 (&acc)[2][4]) {
;     ...
;   const int nk = K / 64;
;   if (!pre) { G_LOAD(0); G_STORE(0); G_LOAD(1); }
;   for (int kt = 0; kt < nk; ++kt) {
;     __syncthreads();
;     G_COMPUTE(kt & 1, kt);
;   }
	v_mfma_f32_32x32x16_bf16 v[64:79], v[168:171], v[212:215], v[64:79]
	v_mfma_f32_32x32x16_bf16 v[0:15], v[172:175], v[212:215], v[0:15]
	ds_read_b128 v[212:215], v149 offset:4640
	s_setprio 0
	global_load_dwordx4 v[168:171], v[140:141], off offset:640
	global_load_dwordx4 v[172:175], v[142:143], off offset:640
	s_setprio 1
	s_waitcnt lgkmcnt(1)
	v_mfma_f32_32x32x16_bf16 v[112:127], v[160:163], v[208:211], v[112:127]
	v_mfma_f32_32x32x16_bf16 v[48:63], v[164:167], v[208:211], v[48:63]
	s_waitcnt lgkmcnt(0)
	v_mfma_f32_32x32x16_bf16 v[96:111], v[160:163], v[212:215], v[96:111]
	v_mfma_f32_32x32x16_bf16 v[32:47], v[164:167], v[212:215], v[32:47]
	ds_read_b128 v[208:211], v149 offset:9248
	ds_read_b128 v[212:215], v149 offset:13856
	s_waitcnt vmcnt(7)
	ds_write_b128 v148, v[184:187] offset:18432
	s_waitcnt vmcnt(6)
	ds_write_b128 v148, v[188:191] offset:55296
	ds_read_b128 v[184:187], v150 offset:64
	ds_read_b128 v[188:191], v150 offset:4672
	s_waitcnt lgkmcnt(5)
	v_mfma_f32_32x32x16_bf16 v[80:95], v[160:163], v[208:211], v[80:95]
	v_mfma_f32_32x32x16_bf16 v[16:31], v[164:167], v[208:211], v[16:31]
	ds_read_b128 v[208:211], v149 offset:64
	s_waitcnt lgkmcnt(5)
	v_mfma_f32_32x32x16_bf16 v[64:79], v[160:163], v[212:215], v[64:79]
	v_mfma_f32_32x32x16_bf16 v[0:15], v[164:167], v[212:215], v[0:15]
	ds_read_b128 v[212:215], v149 offset:4672
	s_setprio 0
	global_load_dwordx4 v[160:163], v[132:133], off offset:640
	global_load_dwordx4 v[164:167], v[134:135], off offset:640
	s_setprio 1
	s_waitcnt lgkmcnt(1)
	v_mfma_f32_32x32x16_bf16 v[112:127], v[184:187], v[208:211], v[112:127]
	v_mfma_f32_32x32x16_bf16 v[48:63], v[188:191], v[208:211], v[48:63]
	s_waitcnt lgkmcnt(0)
	v_mfma_f32_32x32x16_bf16 v[96:111], v[184:187], v[212:215], v[96:111]
	v_mfma_f32_32x32x16_bf16 v[32:47], v[188:191], v[212:215], v[32:47]
	ds_read_b128 v[208:211], v149 offset:9280
	ds_read_b128 v[212:215], v149 offset:13888
	s_waitcnt vmcnt(7)
	ds_write_b128 v148, v[194:197] offset:27648
	s_waitcnt vmcnt(6)
	ds_write_b128 v148, v[198:201] offset:64512
	ds_read_b128 v[194:197], v150 offset:96
	ds_read_b128 v[198:201], v150 offset:4704
	s_waitcnt lgkmcnt(5)
	v_mfma_f32_32x32x16_bf16 v[80:95], v[184:187], v[208:211], v[80:95]
	v_mfma_f32_32x32x16_bf16 v[16:31], v[188:191], v[208:211], v[16:31]
	ds_read_b128 v[208:211], v149 offset:96
	s_waitcnt lgkmcnt(5)
	v_mfma_f32_32x32x16_bf16 v[64:79], v[184:187], v[212:215], v[64:79]
	v_mfma_f32_32x32x16_bf16 v[0:15], v[188:191], v[212:215], v[0:15]
	ds_read_b128 v[212:215], v149 offset:4704
	s_setprio 0
	global_load_dwordx4 v[184:187], v[144:145], off offset:640
	global_load_dwordx4 v[188:191], v[146:147], off offset:640
	s_setprio 1
	s_waitcnt lgkmcnt(1)
	v_mfma_f32_32x32x16_bf16 v[112:127], v[194:197], v[208:211], v[112:127]
	v_mfma_f32_32x32x16_bf16 v[48:63], v[198:201], v[208:211], v[48:63]
	s_waitcnt lgkmcnt(0)
	v_mfma_f32_32x32x16_bf16 v[96:111], v[194:197], v[212:215], v[96:111]
	v_mfma_f32_32x32x16_bf16 v[32:47], v[198:201], v[212:215], v[32:47]
	ds_read_b128 v[208:211], v149 offset:9312
	ds_read_b128 v[212:215], v149 offset:13920
	s_waitcnt lgkmcnt(0)
	s_barrier
	s_waitcnt vmcnt(7)
	ds_write_b128 v192, v[176:179]
	s_waitcnt vmcnt(6)
	ds_write_b128 v159, v[180:183]
	ds_read_b128 v[176:179], v152 offset:36864
	ds_read_b128 v[180:183], v152 offset:41472
	v_mfma_f32_32x32x16_bf16 v[80:95], v[194:197], v[208:211], v[80:95]
	v_mfma_f32_32x32x16_bf16 v[16:31], v[198:201], v[208:211], v[16:31]
	ds_read_b128 v[208:211], v151
	v_mfma_f32_32x32x16_bf16 v[64:79], v[194:197], v[212:215], v[64:79]
	v_mfma_f32_32x32x16_bf16 v[0:15], v[198:201], v[212:215], v[0:15]
	ds_read_b128 v[212:215], v151 offset:4608
	s_setprio 0
	global_load_dwordx4 v[194:197], v[136:137], off offset:768
	global_load_dwordx4 v[198:201], v[138:139], off offset:768
	s_setprio 1
	s_waitcnt lgkmcnt(1)
	v_mfma_f32_32x32x16_bf16 v[112:127], v[176:179], v[208:211], v[112:127]
	v_mfma_f32_32x32x16_bf16 v[48:63], v[180:183], v[208:211], v[48:63]
	s_waitcnt lgkmcnt(0)
	v_mfma_f32_32x32x16_bf16 v[96:111], v[176:179], v[212:215], v[96:111]
	v_mfma_f32_32x32x16_bf16 v[32:47], v[180:183], v[212:215], v[32:47]
	ds_read_b128 v[208:211], v151 offset:9216
	ds_read_b128 v[212:215], v151 offset:13824
	s_waitcnt vmcnt(7)
	ds_write_b128 v158, v[168:171]
	s_waitcnt vmcnt(6)
	ds_write_b128 v157, v[172:175]
	ds_read_b128 v[168:171], v152 offset:36896
	ds_read_b128 v[172:175], v152 offset:41504
	s_waitcnt lgkmcnt(5)
	v_mfma_f32_32x32x16_bf16 v[80:95], v[176:179], v[208:211], v[80:95]
	v_mfma_f32_32x32x16_bf16 v[16:31], v[180:183], v[208:211], v[16:31]
	ds_read_b128 v[208:211], v151 offset:32
	s_waitcnt lgkmcnt(5)
	v_mfma_f32_32x32x16_bf16 v[64:79], v[176:179], v[212:215], v[64:79]
	v_mfma_f32_32x32x16_bf16 v[0:15], v[180:183], v[212:215], v[0:15]
	ds_read_b128 v[212:215], v151 offset:4640
	s_setprio 0
	global_load_dwordx4 v[176:179], v[140:141], off offset:768
	global_load_dwordx4 v[180:183], v[142:143], off offset:768
	s_setprio 1
	s_waitcnt lgkmcnt(1)
	v_mfma_f32_32x32x16_bf16 v[112:127], v[168:171], v[208:211], v[112:127]
	v_mfma_f32_32x32x16_bf16 v[48:63], v[172:175], v[208:211], v[48:63]
	s_waitcnt lgkmcnt(0)
	v_mfma_f32_32x32x16_bf16 v[96:111], v[168:171], v[212:215], v[96:111]
	v_mfma_f32_32x32x16_bf16 v[32:47], v[172:175], v[212:215], v[32:47]
	ds_read_b128 v[208:211], v151 offset:9248
	ds_read_b128 v[212:215], v151 offset:13856
	s_waitcnt vmcnt(7)
	ds_write_b128 v154, v[160:163]
	s_waitcnt vmcnt(6)
	ds_write_b128 v153, v[164:167]
	ds_read_b128 v[160:163], v152 offset:36928
	ds_read_b128 v[164:167], v152 offset:41536
	s_waitcnt lgkmcnt(5)
; template <bool trans>
; DI void gemm_core(const GTile& tl, const GTile& nx, bool has_next  , bool chain  , bool pre, u32x4 (&ra)[4], u32x4 (&rb)[4], char* smem, f32x16 (&acc)[2][4]) {
;     ...
;   const int nk = K / 64;
;   if (!pre) { G_LOAD(0); G_STORE(0); G_LOAD(1); }
;   for (int kt = 0; kt < nk; ++kt) {
;     __syncthreads();
;     G_COMPUTE(kt & 1, kt);
;   }
	v_mfma_f32_32x32x16_bf16 v[80:95], v[168:171], v[208:211], v[80:95]
	v_mfma_f32_32x32x16_bf16 v[16:31], v[172:175], v[208:211], v[16:31]
	ds_read_b128 v[208:211], v151 offset:64
	s_waitcnt lgkmcnt(5)
	v_mfma_f32_32x32x16_bf16 v[64:79], v[168:171], v[212:215], v[64:79]
	v_mfma_f32_32x32x16_bf16 v[0:15], v[172:175], v[212:215], v[0:15]
	ds_read_b128 v[212:215], v151 offset:4672
	s_setprio 0
	global_load_dwordx4 v[168:171], v[132:133], off offset:768
	global_load_dwordx4 v[172:175], v[134:135], off offset:768
	s_setprio 1
	s_waitcnt lgkmcnt(1)
	v_mfma_f32_32x32x16_bf16 v[112:127], v[160:163], v[208:211], v[112:127]
	v_mfma_f32_32x32x16_bf16 v[48:63], v[164:167], v[208:211], v[48:63]
	s_waitcnt lgkmcnt(0)
	v_mfma_f32_32x32x16_bf16 v[96:111], v[160:163], v[212:215], v[96:111]
	v_mfma_f32_32x32x16_bf16 v[32:47], v[164:167], v[212:215], v[32:47]
	ds_read_b128 v[208:211], v151 offset:9280
	ds_read_b128 v[212:215], v151 offset:13888
	s_waitcnt vmcnt(7)
	ds_write_b128 v156, v[184:187]
	s_waitcnt vmcnt(6)
	ds_write_b128 v155, v[188:191]
	ds_read_b128 v[184:187], v152 offset:36960
	ds_read_b128 v[188:191], v152 offset:41568
	s_waitcnt lgkmcnt(5)
	v_mfma_f32_32x32x16_bf16 v[80:95], v[160:163], v[208:211], v[80:95]
	v_mfma_f32_32x32x16_bf16 v[16:31], v[164:167], v[208:211], v[16:31]
	ds_read_b128 v[208:211], v151 offset:96
	s_waitcnt lgkmcnt(5)
	v_mfma_f32_32x32x16_bf16 v[64:79], v[160:163], v[212:215], v[64:79]
	v_mfma_f32_32x32x16_bf16 v[0:15], v[164:167], v[212:215], v[0:15]
	ds_read_b128 v[212:215], v151 offset:4704
	s_setprio 0
	global_load_dwordx4 v[160:163], v[144:145], off offset:768
	global_load_dwordx4 v[164:167], v[146:147], off offset:768
	s_setprio 1
	s_waitcnt lgkmcnt(1)
	v_mfma_f32_32x32x16_bf16 v[112:127], v[184:187], v[208:211], v[112:127]
	v_mfma_f32_32x32x16_bf16 v[48:63], v[188:191], v[208:211], v[48:63]
	s_waitcnt lgkmcnt(0)
	v_mfma_f32_32x32x16_bf16 v[96:111], v[184:187], v[212:215], v[96:111]
	v_mfma_f32_32x32x16_bf16 v[32:47], v[188:191], v[212:215], v[32:47]
	ds_read_b128 v[208:211], v151 offset:9312
	ds_read_b128 v[212:215], v151 offset:13920
	s_waitcnt lgkmcnt(0)
	s_barrier
	s_waitcnt vmcnt(7)
	ds_write_b128 v148, v[194:197]
	s_waitcnt vmcnt(6)
	ds_write_b128 v148, v[198:201] offset:36864
	ds_read_b128 v[194:197], v150
	ds_read_b128 v[198:201], v150 offset:4608
	v_mfma_f32_32x32x16_bf16 v[80:95], v[184:187], v[208:211], v[80:95]
	v_mfma_f32_32x32x16_bf16 v[16:31], v[188:191], v[208:211], v[16:31]
	ds_read_b128 v[208:211], v149
	v_mfma_f32_32x32x16_bf16 v[64:79], v[184:187], v[212:215], v[64:79]
	v_mfma_f32_32x32x16_bf16 v[0:15], v[188:191], v[212:215], v[0:15]
	ds_read_b128 v[212:215], v149 offset:4608
	s_setprio 0
	global_load_dwordx4 v[184:187], v[136:137], off offset:896
	global_load_dwordx4 v[188:191], v[138:139], off offset:896
	s_setprio 1
	s_waitcnt lgkmcnt(1)
	v_mfma_f32_32x32x16_bf16 v[112:127], v[194:197], v[208:211], v[112:127]
	v_mfma_f32_32x32x16_bf16 v[48:63], v[198:201], v[208:211], v[48:63]
	s_waitcnt lgkmcnt(0)
	v_mfma_f32_32x32x16_bf16 v[96:111], v[194:197], v[212:215], v[96:111]
	v_mfma_f32_32x32x16_bf16 v[32:47], v[198:201], v[212:215], v[32:47]
	ds_read_b128 v[208:211], v149 offset:9216
	ds_read_b128 v[212:215], v149 offset:13824
	s_waitcnt vmcnt(7)
	ds_write_b128 v148, v[176:179] offset:9216
	s_waitcnt vmcnt(6)
	ds_write_b128 v148, v[180:183] offset:46080
	ds_read_b128 v[176:179], v150 offset:32
	ds_read_b128 v[180:183], v150 offset:4640
	s_waitcnt lgkmcnt(5)
	v_mfma_f32_32x32x16_bf16 v[80:95], v[194:197], v[208:211], v[80:95]
	v_mfma_f32_32x32x16_bf16 v[16:31], v[198:201], v[208:211], v[16:31]
	ds_read_b128 v[208:211], v149 offset:32
	s_waitcnt lgkmcnt(5)
	v_mfma_f32_32x32x16_bf16 v[64:79], v[194:197], v[212:215], v[64:79]
	v_mfma_f32_32x32x16_bf16 v[0:15], v[198:201], v[212:215], v[0:15]
	ds_read_b128 v[212:215], v149 offset:4640
	s_setprio 0
	global_load_dwordx4 v[194:197], v[140:141], off offset:896
	global_load_dwordx4 v[198:201], v[142:143], off offset:896
	s_setprio 1
	s_waitcnt lgkmcnt(1)
	v_mfma_f32_32x32x16_bf16 v[112:127], v[176:179], v[208:211], v[112:127]
	v_mfma_f32_32x32x16_bf16 v[48:63], v[180:183], v[208:211], v[48:63]
	s_waitcnt lgkmcnt(0)
	v_mfma_f32_32x32x16_bf16 v[96:111], v[176:179], v[212:215], v[96:111]
	v_mfma_f32_32x32x16_bf16 v[32:47], v[180:183], v[212:215], v[32:47]
	ds_read_b128 v[208:211], v149 offset:9248
	ds_read_b128 v[212:215], v149 offset:13856
	s_waitcnt vmcnt(7)
	ds_write_b128 v148, v[168:171] offset:18432
	s_waitcnt vmcnt(6)
	ds_write_b128 v148, v[172:175] offset:55296
	ds_read_b128 v[168:171], v150 offset:64
	ds_read_b128 v[172:175], v150 offset:4672
	s_waitcnt lgkmcnt(5)
	v_mfma_f32_32x32x16_bf16 v[80:95], v[176:179], v[208:211], v[80:95]
	v_mfma_f32_32x32x16_bf16 v[16:31], v[180:183], v[208:211], v[16:31]
	ds_read_b128 v[208:211], v149 offset:64
	s_waitcnt lgkmcnt(5)
	v_mfma_f32_32x32x16_bf16 v[64:79], v[176:179], v[212:215], v[64:79]
	v_mfma_f32_32x32x16_bf16 v[0:15], v[180:183], v[212:215], v[0:15]
	ds_read_b128 v[212:215], v149 offset:4672
	s_setprio 0
	global_load_dwordx4 v[176:179], v[132:133], off offset:896
	global_load_dwordx4 v[180:183], v[134:135], off offset:896
	s_setprio 1
	s_waitcnt lgkmcnt(1)
	v_mfma_f32_32x32x16_bf16 v[112:127], v[168:171], v[208:211], v[112:127]
	v_mfma_f32_32x32x16_bf16 v[48:63], v[172:175], v[208:211], v[48:63]
	s_waitcnt lgkmcnt(0)
	v_mfma_f32_32x32x16_bf16 v[96:111], v[168:171], v[212:215], v[96:111]
	v_mfma_f32_32x32x16_bf16 v[32:47], v[172:175], v[212:215], v[32:47]
	ds_read_b128 v[208:211], v149 offset:9280
	ds_read_b128 v[212:215], v149 offset:13888
	s_waitcnt vmcnt(7)
	ds_write_b128 v148, v[160:163] offset:27648
	s_waitcnt vmcnt(6)
	ds_write_b128 v148, v[164:167] offset:64512
	ds_read_b128 v[160:163], v150 offset:96
	ds_read_b128 v[164:167], v150 offset:4704
	s_waitcnt lgkmcnt(5)
	v_mfma_f32_32x32x16_bf16 v[80:95], v[168:171], v[208:211], v[80:95]
	v_mfma_f32_32x32x16_bf16 v[16:31], v[172:175], v[208:211], v[16:31]
	ds_read_b128 v[208:211], v149 offset:96
	s_waitcnt lgkmcnt(5)
	v_mfma_f32_32x32x16_bf16 v[64:79], v[168:171], v[212:215], v[64:79]
	v_mfma_f32_32x32x16_bf16 v[0:15], v[172:175], v[212:215], v[0:15]
	ds_read_b128 v[212:215], v149 offset:4704
	s_setprio 0
	global_load_dwordx4 v[168:171], v[144:145], off offset:896
	global_load_dwordx4 v[172:175], v[146:147], off offset:896
	s_setprio 1
	s_waitcnt lgkmcnt(1)
	v_mfma_f32_32x32x16_bf16 v[112:127], v[160:163], v[208:211], v[112:127]
	v_mfma_f32_32x32x16_bf16 v[48:63], v[164:167], v[208:211], v[48:63]
	s_waitcnt lgkmcnt(0)
	v_mfma_f32_32x32x16_bf16 v[96:111], v[160:163], v[212:215], v[96:111]
	v_mfma_f32_32x32x16_bf16 v[32:47], v[164:167], v[212:215], v[32:47]
	ds_read_b128 v[208:211], v149 offset:9312
	ds_read_b128 v[212:215], v149 offset:13920
	s_waitcnt lgkmcnt(0)
	s_barrier
; template <bool trans>
; DI void gemm_core(const GTile& tl, const GTile& nx, bool has_next  , bool chain  , bool pre, u32x4 (&ra)[4], u32x4 (&rb)[4], char* smem, f32x16 (&acc)[2][4]) {
;     ...
;   const int nk = K / 64;
;   if (!pre) { G_LOAD(0); G_STORE(0); G_LOAD(1); }
;   for (int kt = 0; kt < nk; ++kt) {
;     __syncthreads();
;     G_COMPUTE(kt & 1, kt);
;   }
	s_waitcnt vmcnt(7)
	ds_write_b128 v192, v[184:187]
	s_waitcnt vmcnt(6)
	ds_write_b128 v159, v[188:191]
	ds_read_b128 v[184:187], v152 offset:36864
	ds_read_b128 v[188:191], v152 offset:41472
	v_mfma_f32_32x32x16_bf16 v[80:95], v[160:163], v[208:211], v[80:95]
	v_mfma_f32_32x32x16_bf16 v[16:31], v[164:167], v[208:211], v[16:31]
	ds_read_b128 v[208:211], v151
	v_mfma_f32_32x32x16_bf16 v[64:79], v[160:163], v[212:215], v[64:79]
	v_mfma_f32_32x32x16_bf16 v[0:15], v[164:167], v[212:215], v[0:15]
	ds_read_b128 v[212:215], v151 offset:4608
	s_setprio 0
	global_load_dwordx4 v[160:163], v[136:137], off offset:1024
	global_load_dwordx4 v[164:167], v[138:139], off offset:1024
	s_setprio 1
	s_waitcnt lgkmcnt(1)
	v_mfma_f32_32x32x16_bf16 v[112:127], v[184:187], v[208:211], v[112:127]
	v_mfma_f32_32x32x16_bf16 v[48:63], v[188:191], v[208:211], v[48:63]
	s_waitcnt lgkmcnt(0)
	v_mfma_f32_32x32x16_bf16 v[96:111], v[184:187], v[212:215], v[96:111]
	v_mfma_f32_32x32x16_bf16 v[32:47], v[188:191], v[212:215], v[32:47]
	ds_read_b128 v[208:211], v151 offset:9216
	ds_read_b128 v[212:215], v151 offset:13824
	s_waitcnt vmcnt(7)
	ds_write_b128 v158, v[194:197]
	s_waitcnt vmcnt(6)
	ds_write_b128 v157, v[198:201]
	ds_read_b128 v[194:197], v152 offset:36896
	ds_read_b128 v[198:201], v152 offset:41504
	s_waitcnt lgkmcnt(5)
	v_mfma_f32_32x32x16_bf16 v[80:95], v[184:187], v[208:211], v[80:95]
	v_mfma_f32_32x32x16_bf16 v[16:31], v[188:191], v[208:211], v[16:31]
	ds_read_b128 v[208:211], v151 offset:32
	s_waitcnt lgkmcnt(5)
	v_mfma_f32_32x32x16_bf16 v[64:79], v[184:187], v[212:215], v[64:79]
	v_mfma_f32_32x32x16_bf16 v[0:15], v[188:191], v[212:215], v[0:15]
	ds_read_b128 v[212:215], v151 offset:4640
	s_setprio 0
	global_load_dwordx4 v[184:187], v[140:141], off offset:1024
	global_load_dwordx4 v[188:191], v[142:143], off offset:1024
	s_setprio 1
	s_waitcnt lgkmcnt(1)
	v_mfma_f32_32x32x16_bf16 v[112:127], v[194:197], v[208:211], v[112:127]
	v_mfma_f32_32x32x16_bf16 v[48:63], v[198:201], v[208:211], v[48:63]
	s_waitcnt lgkmcnt(0)
	v_mfma_f32_32x32x16_bf16 v[96:111], v[194:197], v[212:215], v[96:111]
	v_mfma_f32_32x32x16_bf16 v[32:47], v[198:201], v[212:215], v[32:47]
	ds_read_b128 v[208:211], v151 offset:9248
	ds_read_b128 v[212:215], v151 offset:13856
	s_waitcnt vmcnt(7)
	ds_write_b128 v154, v[176:179]
	s_waitcnt vmcnt(6)
	ds_write_b128 v153, v[180:183]
	ds_read_b128 v[176:179], v152 offset:36928
	ds_read_b128 v[180:183], v152 offset:41536
	s_waitcnt lgkmcnt(5)
	v_mfma_f32_32x32x16_bf16 v[80:95], v[194:197], v[208:211], v[80:95]
	v_mfma_f32_32x32x16_bf16 v[16:31], v[198:201], v[208:211], v[16:31]
	ds_read_b128 v[208:211], v151 offset:64
	s_waitcnt lgkmcnt(5)
	v_mfma_f32_32x32x16_bf16 v[64:79], v[194:197], v[212:215], v[64:79]
	v_mfma_f32_32x32x16_bf16 v[0:15], v[198:201], v[212:215], v[0:15]
	ds_read_b128 v[212:215], v151 offset:4672
	s_setprio 0
	global_load_dwordx4 v[194:197], v[132:133], off offset:1024
	global_load_dwordx4 v[198:201], v[134:135], off offset:1024
	s_setprio 1
	s_waitcnt lgkmcnt(1)
	v_mfma_f32_32x32x16_bf16 v[112:127], v[176:179], v[208:211], v[112:127]
	v_mfma_f32_32x32x16_bf16 v[48:63], v[180:183], v[208:211], v[48:63]
	s_waitcnt lgkmcnt(0)
	v_mfma_f32_32x32x16_bf16 v[96:111], v[176:179], v[212:215], v[96:111]
	v_mfma_f32_32x32x16_bf16 v[32:47], v[180:183], v[212:215], v[32:47]
	ds_read_b128 v[208:211], v151 offset:9280
	ds_read_b128 v[212:215], v151 offset:13888
	s_waitcnt vmcnt(7)
	ds_write_b128 v156, v[168:171]
	s_waitcnt vmcnt(6)
	ds_write_b128 v155, v[172:175]
	ds_read_b128 v[168:171], v152 offset:36960
	ds_read_b128 v[172:175], v152 offset:41568
	s_waitcnt lgkmcnt(5)
	v_mfma_f32_32x32x16_bf16 v[80:95], v[176:179], v[208:211], v[80:95]
	v_mfma_f32_32x32x16_bf16 v[16:31], v[180:183], v[208:211], v[16:31]
	ds_read_b128 v[208:211], v151 offset:96
	s_waitcnt lgkmcnt(5)
	v_mfma_f32_32x32x16_bf16 v[64:79], v[176:179], v[212:215], v[64:79]
	v_mfma_f32_32x32x16_bf16 v[0:15], v[180:183], v[212:215], v[0:15]
	ds_read_b128 v[212:215], v151 offset:4704
	s_setprio 0
	global_load_dwordx4 v[176:179], v[144:145], off offset:1024
	global_load_dwordx4 v[180:183], v[146:147], off offset:1024
	s_setprio 1
	s_waitcnt lgkmcnt(1)
	v_mfma_f32_32x32x16_bf16 v[112:127], v[168:171], v[208:211], v[112:127]
	v_mfma_f32_32x32x16_bf16 v[48:63], v[172:175], v[208:211], v[48:63]
	s_waitcnt lgkmcnt(0)
	v_mfma_f32_32x32x16_bf16 v[96:111], v[168:171], v[212:215], v[96:111]
	v_mfma_f32_32x32x16_bf16 v[32:47], v[172:175], v[212:215], v[32:47]
	ds_read_b128 v[208:211], v151 offset:9312
	ds_read_b128 v[212:215], v151 offset:13920
	s_waitcnt lgkmcnt(0)
	s_barrier
; template <bool trans>
; DI void gemm_core(const GTile& tl, const GTile& nx, bool has_next  , bool chain  , bool pre, u32x4 (&ra)[4], u32x4 (&rb)[4], char* smem, f32x16 (&acc)[2][4]) {
;     ...
;   const int nk = K / 64;
;   if (!pre) { G_LOAD(0); G_STORE(0); G_LOAD(1); }
;   for (int kt = 0; kt < nk; ++kt) {
;     __syncthreads();
;     G_COMPUTE(kt & 1, kt);
;   }
	s_waitcnt vmcnt(7)
	ds_write_b128 v148, v[160:163]
	s_waitcnt vmcnt(6)
	ds_write_b128 v148, v[164:167] offset:36864
	ds_read_b128 v[160:163], v150
	ds_read_b128 v[164:167], v150 offset:4608
	v_mfma_f32_32x32x16_bf16 v[80:95], v[168:171], v[208:211], v[80:95]
	v_mfma_f32_32x32x16_bf16 v[16:31], v[172:175], v[208:211], v[16:31]
	ds_read_b128 v[208:211], v149
	v_mfma_f32_32x32x16_bf16 v[64:79], v[168:171], v[212:215], v[64:79]
	v_mfma_f32_32x32x16_bf16 v[0:15], v[172:175], v[212:215], v[0:15]
	ds_read_b128 v[212:215], v149 offset:4608
	s_setprio 0
	global_load_dwordx4 v[168:171], v[136:137], off offset:1152
	global_load_dwordx4 v[172:175], v[138:139], off offset:1152
	s_setprio 1
	s_waitcnt lgkmcnt(1)
	v_mfma_f32_32x32x16_bf16 v[112:127], v[160:163], v[208:211], v[112:127]
	v_mfma_f32_32x32x16_bf16 v[48:63], v[164:167], v[208:211], v[48:63]
	s_waitcnt lgkmcnt(0)
	v_mfma_f32_32x32x16_bf16 v[96:111], v[160:163], v[212:215], v[96:111]
	v_mfma_f32_32x32x16_bf16 v[32:47], v[164:167], v[212:215], v[32:47]
	ds_read_b128 v[208:211], v149 offset:9216
	ds_read_b128 v[212:215], v149 offset:13824
	s_waitcnt vmcnt(7)
	ds_write_b128 v148, v[184:187] offset:9216
	s_waitcnt vmcnt(6)
	ds_write_b128 v148, v[188:191] offset:46080
	ds_read_b128 v[184:187], v150 offset:32
	ds_read_b128 v[188:191], v150 offset:4640
	s_waitcnt lgkmcnt(5)
	v_mfma_f32_32x32x16_bf16 v[80:95], v[160:163], v[208:211], v[80:95]
	v_mfma_f32_32x32x16_bf16 v[16:31], v[164:167], v[208:211], v[16:31]
	ds_read_b128 v[208:211], v149 offset:32
	s_waitcnt lgkmcnt(5)
	v_mfma_f32_32x32x16_bf16 v[64:79], v[160:163], v[212:215], v[64:79]
	v_mfma_f32_32x32x16_bf16 v[0:15], v[164:167], v[212:215], v[0:15]
	ds_read_b128 v[212:215], v149 offset:4640
	s_setprio 0
	global_load_dwordx4 v[160:163], v[140:141], off offset:1152
	global_load_dwordx4 v[164:167], v[142:143], off offset:1152
	s_setprio 1
	s_waitcnt lgkmcnt(1)
	v_mfma_f32_32x32x16_bf16 v[112:127], v[184:187], v[208:211], v[112:127]
	v_mfma_f32_32x32x16_bf16 v[48:63], v[188:191], v[208:211], v[48:63]
	s_waitcnt lgkmcnt(0)
	v_mfma_f32_32x32x16_bf16 v[96:111], v[184:187], v[212:215], v[96:111]
	v_mfma_f32_32x32x16_bf16 v[32:47], v[188:191], v[212:215], v[32:47]
	ds_read_b128 v[208:211], v149 offset:9248
	ds_read_b128 v[212:215], v149 offset:13856
	s_waitcnt vmcnt(7)
	ds_write_b128 v148, v[194:197] offset:18432
	s_waitcnt vmcnt(6)
	ds_write_b128 v148, v[198:201] offset:55296
	ds_read_b128 v[194:197], v150 offset:64
	ds_read_b128 v[198:201], v150 offset:4672
	s_waitcnt lgkmcnt(5)
	v_mfma_f32_32x32x16_bf16 v[80:95], v[184:187], v[208:211], v[80:95]
	v_mfma_f32_32x32x16_bf16 v[16:31], v[188:191], v[208:211], v[16:31]
	ds_read_b128 v[208:211], v149 offset:64
	s_waitcnt lgkmcnt(5)
	v_mfma_f32_32x32x16_bf16 v[64:79], v[184:187], v[212:215], v[64:79]
	v_mfma_f32_32x32x16_bf16 v[0:15], v[188:191], v[212:215], v[0:15]
	ds_read_b128 v[212:215], v149 offset:4672
	s_setprio 0
	global_load_dwordx4 v[184:187], v[132:133], off offset:1152
	global_load_dwordx4 v[188:191], v[134:135], off offset:1152
	s_setprio 1
	s_waitcnt lgkmcnt(1)
	v_mfma_f32_32x32x16_bf16 v[112:127], v[194:197], v[208:211], v[112:127]
	v_mfma_f32_32x32x16_bf16 v[48:63], v[198:201], v[208:211], v[48:63]
	s_waitcnt lgkmcnt(0)
	v_mfma_f32_32x32x16_bf16 v[96:111], v[194:197], v[212:215], v[96:111]
	v_mfma_f32_32x32x16_bf16 v[32:47], v[198:201], v[212:215], v[32:47]
	ds_read_b128 v[208:211], v149 offset:9280
	ds_read_b128 v[212:215], v149 offset:13888
	s_waitcnt vmcnt(7)
	ds_write_b128 v148, v[176:179] offset:27648
	s_waitcnt vmcnt(6)
	ds_write_b128 v148, v[180:183] offset:64512
	ds_read_b128 v[176:179], v150 offset:96
	ds_read_b128 v[180:183], v150 offset:4704
	s_waitcnt lgkmcnt(5)
	v_mfma_f32_32x32x16_bf16 v[80:95], v[194:197], v[208:211], v[80:95]
	v_mfma_f32_32x32x16_bf16 v[16:31], v[198:201], v[208:211], v[16:31]
	ds_read_b128 v[208:211], v149 offset:96
	s_waitcnt lgkmcnt(5)
	v_mfma_f32_32x32x16_bf16 v[64:79], v[194:197], v[212:215], v[64:79]
	v_mfma_f32_32x32x16_bf16 v[0:15], v[198:201], v[212:215], v[0:15]
	ds_read_b128 v[212:215], v149 offset:4704
	s_setprio 0
	global_load_dwordx4 v[194:197], v[144:145], off offset:1152
	global_load_dwordx4 v[198:201], v[146:147], off offset:1152
	s_setprio 1
	s_waitcnt lgkmcnt(1)
	v_mfma_f32_32x32x16_bf16 v[112:127], v[176:179], v[208:211], v[112:127]
	v_mfma_f32_32x32x16_bf16 v[48:63], v[180:183], v[208:211], v[48:63]
	s_waitcnt lgkmcnt(0)
	v_mfma_f32_32x32x16_bf16 v[96:111], v[176:179], v[212:215], v[96:111]
	v_mfma_f32_32x32x16_bf16 v[32:47], v[180:183], v[212:215], v[32:47]
	ds_read_b128 v[208:211], v149 offset:9312
	ds_read_b128 v[212:215], v149 offset:13920
	s_waitcnt lgkmcnt(0)
	s_barrier
; template <bool trans>
; DI void gemm_core(const GTile& tl, const GTile& nx, bool has_next  , bool chain  , bool pre, u32x4 (&ra)[4], u32x4 (&rb)[4], char* smem, f32x16 (&acc)[2][4]) {
;     ...
;   const int nk = K / 64;
;   if (!pre) { G_LOAD(0); G_STORE(0); G_LOAD(1); }
;   for (int kt = 0; kt < nk; ++kt) {
;     __syncthreads();
;     G_COMPUTE(kt & 1, kt);
;   }
	s_waitcnt vmcnt(7)
	ds_write_b128 v192, v[168:171]
	s_waitcnt vmcnt(6)
	ds_write_b128 v159, v[172:175]
	ds_read_b128 v[168:171], v152 offset:36864
	ds_read_b128 v[172:175], v152 offset:41472
	v_mfma_f32_32x32x16_bf16 v[80:95], v[176:179], v[208:211], v[80:95]
	v_mfma_f32_32x32x16_bf16 v[16:31], v[180:183], v[208:211], v[16:31]
	ds_read_b128 v[208:211], v151
	v_mfma_f32_32x32x16_bf16 v[64:79], v[176:179], v[212:215], v[64:79]
	v_mfma_f32_32x32x16_bf16 v[0:15], v[180:183], v[212:215], v[0:15]
	ds_read_b128 v[212:215], v151 offset:4608
	s_setprio 0
	global_load_dwordx4 v[176:179], v[136:137], off offset:1280
	global_load_dwordx4 v[180:183], v[138:139], off offset:1280
	s_setprio 1
	s_waitcnt lgkmcnt(1)
	v_mfma_f32_32x32x16_bf16 v[112:127], v[168:171], v[208:211], v[112:127]
	v_mfma_f32_32x32x16_bf16 v[48:63], v[172:175], v[208:211], v[48:63]
	s_waitcnt lgkmcnt(0)
	v_mfma_f32_32x32x16_bf16 v[96:111], v[168:171], v[212:215], v[96:111]
	v_mfma_f32_32x32x16_bf16 v[32:47], v[172:175], v[212:215], v[32:47]
	ds_read_b128 v[208:211], v151 offset:9216
	ds_read_b128 v[212:215], v151 offset:13824
	s_waitcnt vmcnt(7)
	ds_write_b128 v158, v[160:163]
	s_waitcnt vmcnt(6)
	ds_write_b128 v157, v[164:167]
	ds_read_b128 v[160:163], v152 offset:36896
	ds_read_b128 v[164:167], v152 offset:41504
	s_waitcnt lgkmcnt(5)
	v_mfma_f32_32x32x16_bf16 v[80:95], v[168:171], v[208:211], v[80:95]
	v_mfma_f32_32x32x16_bf16 v[16:31], v[172:175], v[208:211], v[16:31]
	ds_read_b128 v[208:211], v151 offset:32
	s_waitcnt lgkmcnt(5)
	v_mfma_f32_32x32x16_bf16 v[64:79], v[168:171], v[212:215], v[64:79]
	v_mfma_f32_32x32x16_bf16 v[0:15], v[172:175], v[212:215], v[0:15]
	ds_read_b128 v[212:215], v151 offset:4640
	s_setprio 0
	global_load_dwordx4 v[168:171], v[140:141], off offset:1280
	global_load_dwordx4 v[172:175], v[142:143], off offset:1280
	s_setprio 1
	s_waitcnt lgkmcnt(1)
	v_mfma_f32_32x32x16_bf16 v[112:127], v[160:163], v[208:211], v[112:127]
	v_mfma_f32_32x32x16_bf16 v[48:63], v[164:167], v[208:211], v[48:63]
	s_waitcnt lgkmcnt(0)
	v_mfma_f32_32x32x16_bf16 v[96:111], v[160:163], v[212:215], v[96:111]
	v_mfma_f32_32x32x16_bf16 v[32:47], v[164:167], v[212:215], v[32:47]
	ds_read_b128 v[208:211], v151 offset:9248
	ds_read_b128 v[212:215], v151 offset:13856
	s_waitcnt vmcnt(7)
	ds_write_b128 v154, v[184:187]
	s_waitcnt vmcnt(6)
	ds_write_b128 v153, v[188:191]
	ds_read_b128 v[184:187], v152 offset:36928
	ds_read_b128 v[188:191], v152 offset:41536
	s_waitcnt lgkmcnt(5)
	v_mfma_f32_32x32x16_bf16 v[80:95], v[160:163], v[208:211], v[80:95]
	v_mfma_f32_32x32x16_bf16 v[16:31], v[164:167], v[208:211], v[16:31]
	ds_read_b128 v[208:211], v151 offset:64
	s_waitcnt lgkmcnt(5)
	v_mfma_f32_32x32x16_bf16 v[64:79], v[160:163], v[212:215], v[64:79]
	v_mfma_f32_32x32x16_bf16 v[0:15], v[164:167], v[212:215], v[0:15]
	ds_read_b128 v[212:215], v151 offset:4672
	s_setprio 0
	global_load_dwordx4 v[160:163], v[132:133], off offset:1280
	global_load_dwordx4 v[164:167], v[134:135], off offset:1280
	s_setprio 1
	s_waitcnt lgkmcnt(1)
	v_mfma_f32_32x32x16_bf16 v[112:127], v[184:187], v[208:211], v[112:127]
	v_mfma_f32_32x32x16_bf16 v[48:63], v[188:191], v[208:211], v[48:63]
	s_waitcnt lgkmcnt(0)
	v_mfma_f32_32x32x16_bf16 v[96:111], v[184:187], v[212:215], v[96:111]
	v_mfma_f32_32x32x16_bf16 v[32:47], v[188:191], v[212:215], v[32:47]
	ds_read_b128 v[208:211], v151 offset:9280
	ds_read_b128 v[212:215], v151 offset:13888
	s_waitcnt vmcnt(7)
	ds_write_b128 v156, v[194:197]
	s_waitcnt vmcnt(6)
	ds_write_b128 v155, v[198:201]
	ds_read_b128 v[194:197], v152 offset:36960
	ds_read_b128 v[198:201], v152 offset:41568
	s_waitcnt lgkmcnt(5)
	v_mfma_f32_32x32x16_bf16 v[80:95], v[184:187], v[208:211], v[80:95]
	v_mfma_f32_32x32x16_bf16 v[16:31], v[188:191], v[208:211], v[16:31]
	ds_read_b128 v[208:211], v151 offset:96
	s_waitcnt lgkmcnt(5)
	v_mfma_f32_32x32x16_bf16 v[64:79], v[184:187], v[212:215], v[64:79]
	v_mfma_f32_32x32x16_bf16 v[0:15], v[188:191], v[212:215], v[0:15]
	ds_read_b128 v[212:215], v151 offset:4704
	s_setprio 0
	global_load_dwordx4 v[184:187], v[144:145], off offset:1280
	global_load_dwordx4 v[188:191], v[146:147], off offset:1280
	s_setprio 1
	s_waitcnt lgkmcnt(1)
	v_mfma_f32_32x32x16_bf16 v[112:127], v[194:197], v[208:211], v[112:127]
	v_mfma_f32_32x32x16_bf16 v[48:63], v[198:201], v[208:211], v[48:63]
	s_waitcnt lgkmcnt(0)
	v_mfma_f32_32x32x16_bf16 v[96:111], v[194:197], v[212:215], v[96:111]
	v_mfma_f32_32x32x16_bf16 v[32:47], v[198:201], v[212:215], v[32:47]
	ds_read_b128 v[208:211], v151 offset:9312
	ds_read_b128 v[212:215], v151 offset:13920
	s_waitcnt lgkmcnt(0)
	s_barrier
; template <bool trans>
; DI void gemm_core(const GTile& tl, const GTile& nx, bool has_next  , bool chain  , bool pre, u32x4 (&ra)[4], u32x4 (&rb)[4], char* smem, f32x16 (&acc)[2][4]) {
;     ...
;   const int nk = K / 64;
;   if (!pre) { G_LOAD(0); G_STORE(0); G_LOAD(1); }
;   for (int kt = 0; kt < nk; ++kt) {
;     __syncthreads();
;     G_COMPUTE(kt & 1, kt);
;   }
	s_waitcnt vmcnt(7)
	ds_write_b128 v148, v[176:179]
	s_waitcnt vmcnt(6)
	ds_write_b128 v148, v[180:183] offset:36864
	ds_read_b128 v[176:179], v150
	ds_read_b128 v[180:183], v150 offset:4608
	v_mfma_f32_32x32x16_bf16 v[80:95], v[194:197], v[208:211], v[80:95]
	v_mfma_f32_32x32x16_bf16 v[16:31], v[198:201], v[208:211], v[16:31]
	ds_read_b128 v[208:211], v149
	v_mfma_f32_32x32x16_bf16 v[64:79], v[194:197], v[212:215], v[64:79]
	v_mfma_f32_32x32x16_bf16 v[0:15], v[198:201], v[212:215], v[0:15]
	ds_read_b128 v[212:215], v149 offset:4608
	s_setprio 0
	global_load_dwordx4 v[194:197], v[136:137], off offset:1408
	global_load_dwordx4 v[198:201], v[138:139], off offset:1408
	s_setprio 1
	s_waitcnt lgkmcnt(1)
	v_mfma_f32_32x32x16_bf16 v[112:127], v[176:179], v[208:211], v[112:127]
	v_mfma_f32_32x32x16_bf16 v[48:63], v[180:183], v[208:211], v[48:63]
	s_waitcnt lgkmcnt(0)
	v_mfma_f32_32x32x16_bf16 v[96:111], v[176:179], v[212:215], v[96:111]
	v_mfma_f32_32x32x16_bf16 v[32:47], v[180:183], v[212:215], v[32:47]
	ds_read_b128 v[208:211], v149 offset:9216
	ds_read_b128 v[212:215], v149 offset:13824
	s_waitcnt vmcnt(7)
	ds_write_b128 v148, v[168:171] offset:9216
	s_waitcnt vmcnt(6)
	ds_write_b128 v148, v[172:175] offset:46080
	ds_read_b128 v[168:171], v150 offset:32
	ds_read_b128 v[172:175], v150 offset:4640
	s_waitcnt lgkmcnt(5)
	v_mfma_f32_32x32x16_bf16 v[80:95], v[176:179], v[208:211], v[80:95]
	v_mfma_f32_32x32x16_bf16 v[16:31], v[180:183], v[208:211], v[16:31]
	ds_read_b128 v[208:211], v149 offset:32
	s_waitcnt lgkmcnt(5)
	v_mfma_f32_32x32x16_bf16 v[64:79], v[176:179], v[212:215], v[64:79]
	v_mfma_f32_32x32x16_bf16 v[0:15], v[180:183], v[212:215], v[0:15]
	ds_read_b128 v[212:215], v149 offset:4640
	s_setprio 0
	global_load_dwordx4 v[176:179], v[140:141], off offset:1408
	global_load_dwordx4 v[180:183], v[142:143], off offset:1408
	s_setprio 1
	s_waitcnt lgkmcnt(1)
	v_mfma_f32_32x32x16_bf16 v[112:127], v[168:171], v[208:211], v[112:127]
	v_mfma_f32_32x32x16_bf16 v[48:63], v[172:175], v[208:211], v[48:63]
	s_waitcnt lgkmcnt(0)
	v_mfma_f32_32x32x16_bf16 v[96:111], v[168:171], v[212:215], v[96:111]
	v_mfma_f32_32x32x16_bf16 v[32:47], v[172:175], v[212:215], v[32:47]
	ds_read_b128 v[208:211], v149 offset:9248
	ds_read_b128 v[212:215], v149 offset:13856
	s_waitcnt vmcnt(7)
	ds_write_b128 v148, v[160:163] offset:18432
	s_waitcnt vmcnt(6)
	ds_write_b128 v148, v[164:167] offset:55296
	ds_read_b128 v[160:163], v150 offset:64
	ds_read_b128 v[164:167], v150 offset:4672
	s_waitcnt lgkmcnt(5)
	v_mfma_f32_32x32x16_bf16 v[80:95], v[168:171], v[208:211], v[80:95]
	v_mfma_f32_32x32x16_bf16 v[16:31], v[172:175], v[208:211], v[16:31]
	ds_read_b128 v[208:211], v149 offset:64
	s_waitcnt lgkmcnt(5)
	v_mfma_f32_32x32x16_bf16 v[64:79], v[168:171], v[212:215], v[64:79]
	v_mfma_f32_32x32x16_bf16 v[0:15], v[172:175], v[212:215], v[0:15]
	ds_read_b128 v[212:215], v149 offset:4672
	s_setprio 0
	global_load_dwordx4 v[168:171], v[132:133], off offset:1408
	global_load_dwordx4 v[172:175], v[134:135], off offset:1408
	s_setprio 1
	s_waitcnt lgkmcnt(1)
	v_mfma_f32_32x32x16_bf16 v[112:127], v[160:163], v[208:211], v[112:127]
	v_mfma_f32_32x32x16_bf16 v[48:63], v[164:167], v[208:211], v[48:63]
	s_waitcnt lgkmcnt(0)
	v_mfma_f32_32x32x16_bf16 v[96:111], v[160:163], v[212:215], v[96:111]
	v_mfma_f32_32x32x16_bf16 v[32:47], v[164:167], v[212:215], v[32:47]
	ds_read_b128 v[208:211], v149 offset:9280
	ds_read_b128 v[212:215], v149 offset:13888
	s_waitcnt vmcnt(7)
	ds_write_b128 v148, v[184:187] offset:27648
	s_waitcnt vmcnt(6)
	ds_write_b128 v148, v[188:191] offset:64512
	ds_read_b128 v[184:187], v150 offset:96
	ds_read_b128 v[188:191], v150 offset:4704
	s_waitcnt lgkmcnt(5)
	v_mfma_f32_32x32x16_bf16 v[80:95], v[160:163], v[208:211], v[80:95]
	v_mfma_f32_32x32x16_bf16 v[16:31], v[164:167], v[208:211], v[16:31]
	ds_read_b128 v[208:211], v149 offset:96
	s_waitcnt lgkmcnt(5)
	v_mfma_f32_32x32x16_bf16 v[64:79], v[160:163], v[212:215], v[64:79]
	v_mfma_f32_32x32x16_bf16 v[0:15], v[164:167], v[212:215], v[0:15]
	ds_read_b128 v[212:215], v149 offset:4704
	s_setprio 0
	global_load_dwordx4 v[160:163], v[144:145], off offset:1408
	global_load_dwordx4 v[164:167], v[146:147], off offset:1408
	s_setprio 1
	s_waitcnt lgkmcnt(1)
	v_mfma_f32_32x32x16_bf16 v[112:127], v[184:187], v[208:211], v[112:127]
	v_mfma_f32_32x32x16_bf16 v[48:63], v[188:191], v[208:211], v[48:63]
	s_waitcnt lgkmcnt(0)
	v_mfma_f32_32x32x16_bf16 v[96:111], v[184:187], v[212:215], v[96:111]
	v_mfma_f32_32x32x16_bf16 v[32:47], v[188:191], v[212:215], v[32:47]
	ds_read_b128 v[208:211], v149 offset:9312
	ds_read_b128 v[212:215], v149 offset:13920
	s_waitcnt lgkmcnt(0)
	s_barrier
; template <bool trans>
; DI void gemm_core(const GTile& tl, const GTile& nx, bool has_next  , bool chain  , bool pre, u32x4 (&ra)[4], u32x4 (&rb)[4], char* smem, f32x16 (&acc)[2][4]) {
;     ...
;   const int nk = K / 64;
;   if (!pre) { G_LOAD(0); G_STORE(0); G_LOAD(1); }
;   for (int kt = 0; kt < nk; ++kt) {
;     __syncthreads();
;     G_COMPUTE(kt & 1, kt);
;   }
	s_waitcnt vmcnt(7)
	ds_write_b128 v192, v[194:197]
	s_waitcnt vmcnt(6)
	ds_write_b128 v159, v[198:201]
	ds_read_b128 v[194:197], v152 offset:36864
	ds_read_b128 v[198:201], v152 offset:41472
	v_mfma_f32_32x32x16_bf16 v[80:95], v[184:187], v[208:211], v[80:95]
	v_mfma_f32_32x32x16_bf16 v[16:31], v[188:191], v[208:211], v[16:31]
	ds_read_b128 v[208:211], v151
	v_mfma_f32_32x32x16_bf16 v[64:79], v[184:187], v[212:215], v[64:79]
	v_mfma_f32_32x32x16_bf16 v[0:15], v[188:191], v[212:215], v[0:15]
	ds_read_b128 v[212:215], v151 offset:4608
	s_setprio 0
	global_load_dwordx4 v[184:187], v[136:137], off offset:1536
	global_load_dwordx4 v[188:191], v[138:139], off offset:1536
	s_setprio 1
	s_waitcnt lgkmcnt(1)
	v_mfma_f32_32x32x16_bf16 v[112:127], v[194:197], v[208:211], v[112:127]
	v_mfma_f32_32x32x16_bf16 v[48:63], v[198:201], v[208:211], v[48:63]
	s_waitcnt lgkmcnt(0)
	v_mfma_f32_32x32x16_bf16 v[96:111], v[194:197], v[212:215], v[96:111]
	v_mfma_f32_32x32x16_bf16 v[32:47], v[198:201], v[212:215], v[32:47]
	ds_read_b128 v[208:211], v151 offset:9216
	ds_read_b128 v[212:215], v151 offset:13824
	s_waitcnt vmcnt(7)
	ds_write_b128 v158, v[176:179]
	s_waitcnt vmcnt(6)
	ds_write_b128 v157, v[180:183]
	ds_read_b128 v[176:179], v152 offset:36896
	ds_read_b128 v[180:183], v152 offset:41504
	s_waitcnt lgkmcnt(5)
	v_mfma_f32_32x32x16_bf16 v[80:95], v[194:197], v[208:211], v[80:95]
	v_mfma_f32_32x32x16_bf16 v[16:31], v[198:201], v[208:211], v[16:31]
	ds_read_b128 v[208:211], v151 offset:32
	s_waitcnt lgkmcnt(5)
	v_mfma_f32_32x32x16_bf16 v[64:79], v[194:197], v[212:215], v[64:79]
	v_mfma_f32_32x32x16_bf16 v[0:15], v[198:201], v[212:215], v[0:15]
	ds_read_b128 v[212:215], v151 offset:4640
	s_setprio 0
	global_load_dwordx4 v[194:197], v[140:141], off offset:1536
	global_load_dwordx4 v[198:201], v[142:143], off offset:1536
	s_setprio 1
	s_waitcnt lgkmcnt(1)
	v_mfma_f32_32x32x16_bf16 v[112:127], v[176:179], v[208:211], v[112:127]
	v_mfma_f32_32x32x16_bf16 v[48:63], v[180:183], v[208:211], v[48:63]
	s_waitcnt lgkmcnt(0)
	v_mfma_f32_32x32x16_bf16 v[96:111], v[176:179], v[212:215], v[96:111]
	v_mfma_f32_32x32x16_bf16 v[32:47], v[180:183], v[212:215], v[32:47]
	ds_read_b128 v[208:211], v151 offset:9248
	ds_read_b128 v[212:215], v151 offset:13856
	s_waitcnt vmcnt(7)
	ds_write_b128 v154, v[168:171]
	s_waitcnt vmcnt(6)
	ds_write_b128 v153, v[172:175]
	ds_read_b128 v[168:171], v152 offset:36928
	ds_read_b128 v[172:175], v152 offset:41536
	s_waitcnt lgkmcnt(5)
	v_mfma_f32_32x32x16_bf16 v[80:95], v[176:179], v[208:211], v[80:95]
	v_mfma_f32_32x32x16_bf16 v[16:31], v[180:183], v[208:211], v[16:31]
	ds_read_b128 v[208:211], v151 offset:64
	s_waitcnt lgkmcnt(5)
	v_mfma_f32_32x32x16_bf16 v[64:79], v[176:179], v[212:215], v[64:79]
	v_mfma_f32_32x32x16_bf16 v[0:15], v[180:183], v[212:215], v[0:15]
	ds_read_b128 v[212:215], v151 offset:4672
	s_setprio 0
	global_load_dwordx4 v[176:179], v[132:133], off offset:1536
	global_load_dwordx4 v[180:183], v[134:135], off offset:1536
	s_setprio 1
	s_waitcnt lgkmcnt(1)
	v_mfma_f32_32x32x16_bf16 v[112:127], v[168:171], v[208:211], v[112:127]
	v_mfma_f32_32x32x16_bf16 v[48:63], v[172:175], v[208:211], v[48:63]
	s_waitcnt lgkmcnt(0)
	v_mfma_f32_32x32x16_bf16 v[96:111], v[168:171], v[212:215], v[96:111]
	v_mfma_f32_32x32x16_bf16 v[32:47], v[172:175], v[212:215], v[32:47]
	ds_read_b128 v[208:211], v151 offset:9280
	ds_read_b128 v[212:215], v151 offset:13888
	s_waitcnt vmcnt(7)
	ds_write_b128 v156, v[160:163]
	s_waitcnt vmcnt(6)
	ds_write_b128 v155, v[164:167]
	ds_read_b128 v[160:163], v152 offset:36960
	ds_read_b128 v[164:167], v152 offset:41568
	s_waitcnt lgkmcnt(5)
	v_mfma_f32_32x32x16_bf16 v[80:95], v[168:171], v[208:211], v[80:95]
	v_mfma_f32_32x32x16_bf16 v[16:31], v[172:175], v[208:211], v[16:31]
	ds_read_b128 v[208:211], v151 offset:96
	s_waitcnt lgkmcnt(5)
	v_mfma_f32_32x32x16_bf16 v[64:79], v[168:171], v[212:215], v[64:79]
	v_mfma_f32_32x32x16_bf16 v[0:15], v[172:175], v[212:215], v[0:15]
	ds_read_b128 v[212:215], v151 offset:4704
	s_setprio 0
	global_load_dwordx4 v[168:171], v[144:145], off offset:1536
	global_load_dwordx4 v[172:175], v[146:147], off offset:1536
	s_setprio 1
	s_waitcnt lgkmcnt(1)
	v_mfma_f32_32x32x16_bf16 v[112:127], v[160:163], v[208:211], v[112:127]
	v_mfma_f32_32x32x16_bf16 v[48:63], v[164:167], v[208:211], v[48:63]
	s_waitcnt lgkmcnt(0)
	v_mfma_f32_32x32x16_bf16 v[96:111], v[160:163], v[212:215], v[96:111]
	v_mfma_f32_32x32x16_bf16 v[32:47], v[164:167], v[212:215], v[32:47]
	ds_read_b128 v[208:211], v151 offset:9312
	ds_read_b128 v[212:215], v151 offset:13920
	s_waitcnt lgkmcnt(0)
	s_barrier
; template <bool trans>
; DI void gemm_core(const GTile& tl, const GTile& nx, bool has_next  , bool chain  , bool pre, u32x4 (&ra)[4], u32x4 (&rb)[4], char* smem, f32x16 (&acc)[2][4]) {
;     ...
;   const int nk = K / 64;
;   if (!pre) { G_LOAD(0); G_STORE(0); G_LOAD(1); }
;   for (int kt = 0; kt < nk; ++kt) {
;     __syncthreads();
;     G_COMPUTE(kt & 1, kt);
;   }
	s_waitcnt vmcnt(7)
	ds_write_b128 v148, v[184:187]
	s_waitcnt vmcnt(6)
	ds_write_b128 v148, v[188:191] offset:36864
	ds_read_b128 v[184:187], v150
	ds_read_b128 v[188:191], v150 offset:4608
	v_mfma_f32_32x32x16_bf16 v[80:95], v[160:163], v[208:211], v[80:95]
	v_mfma_f32_32x32x16_bf16 v[16:31], v[164:167], v[208:211], v[16:31]
	ds_read_b128 v[208:211], v149
	v_mfma_f32_32x32x16_bf16 v[64:79], v[160:163], v[212:215], v[64:79]
	v_mfma_f32_32x32x16_bf16 v[0:15], v[164:167], v[212:215], v[0:15]
	ds_read_b128 v[212:215], v149 offset:4608
	s_setprio 0
	global_load_dwordx4 v[160:163], v[136:137], off offset:1664
	global_load_dwordx4 v[164:167], v[138:139], off offset:1664
	s_setprio 1
	s_waitcnt lgkmcnt(1)
	v_mfma_f32_32x32x16_bf16 v[112:127], v[184:187], v[208:211], v[112:127]
	v_mfma_f32_32x32x16_bf16 v[48:63], v[188:191], v[208:211], v[48:63]
	s_waitcnt lgkmcnt(0)
	v_mfma_f32_32x32x16_bf16 v[96:111], v[184:187], v[212:215], v[96:111]
	v_mfma_f32_32x32x16_bf16 v[32:47], v[188:191], v[212:215], v[32:47]
	ds_read_b128 v[208:211], v149 offset:9216
	ds_read_b128 v[212:215], v149 offset:13824
	s_waitcnt vmcnt(7)
	ds_write_b128 v148, v[194:197] offset:9216
	s_waitcnt vmcnt(6)
	ds_write_b128 v148, v[198:201] offset:46080
	ds_read_b128 v[194:197], v150 offset:32
	ds_read_b128 v[198:201], v150 offset:4640
	s_waitcnt lgkmcnt(5)
	v_mfma_f32_32x32x16_bf16 v[80:95], v[184:187], v[208:211], v[80:95]
	v_mfma_f32_32x32x16_bf16 v[16:31], v[188:191], v[208:211], v[16:31]
	ds_read_b128 v[208:211], v149 offset:32
	s_waitcnt lgkmcnt(5)
	v_mfma_f32_32x32x16_bf16 v[64:79], v[184:187], v[212:215], v[64:79]
	v_mfma_f32_32x32x16_bf16 v[0:15], v[188:191], v[212:215], v[0:15]
	ds_read_b128 v[212:215], v149 offset:4640
	s_setprio 0
	global_load_dwordx4 v[184:187], v[140:141], off offset:1664
	global_load_dwordx4 v[188:191], v[142:143], off offset:1664
	s_setprio 1
	s_waitcnt lgkmcnt(1)
	v_mfma_f32_32x32x16_bf16 v[112:127], v[194:197], v[208:211], v[112:127]
	v_mfma_f32_32x32x16_bf16 v[48:63], v[198:201], v[208:211], v[48:63]
	s_waitcnt lgkmcnt(0)
	v_mfma_f32_32x32x16_bf16 v[96:111], v[194:197], v[212:215], v[96:111]
	v_mfma_f32_32x32x16_bf16 v[32:47], v[198:201], v[212:215], v[32:47]
	ds_read_b128 v[208:211], v149 offset:9248
	ds_read_b128 v[212:215], v149 offset:13856
	s_waitcnt vmcnt(7)
	ds_write_b128 v148, v[176:179] offset:18432
	s_waitcnt vmcnt(6)
	ds_write_b128 v148, v[180:183] offset:55296
	ds_read_b128 v[176:179], v150 offset:64
	ds_read_b128 v[180:183], v150 offset:4672
	s_waitcnt lgkmcnt(5)
	v_mfma_f32_32x32x16_bf16 v[80:95], v[194:197], v[208:211], v[80:95]
	v_mfma_f32_32x32x16_bf16 v[16:31], v[198:201], v[208:211], v[16:31]
	ds_read_b128 v[208:211], v149 offset:64
	s_waitcnt lgkmcnt(5)
	v_mfma_f32_32x32x16_bf16 v[64:79], v[194:197], v[212:215], v[64:79]
	v_mfma_f32_32x32x16_bf16 v[0:15], v[198:201], v[212:215], v[0:15]
	ds_read_b128 v[212:215], v149 offset:4672
	s_setprio 0
	global_load_dwordx4 v[194:197], v[132:133], off offset:1664
	global_load_dwordx4 v[198:201], v[134:135], off offset:1664
	s_setprio 1
	s_waitcnt lgkmcnt(1)
	v_mfma_f32_32x32x16_bf16 v[112:127], v[176:179], v[208:211], v[112:127]
	v_mfma_f32_32x32x16_bf16 v[48:63], v[180:183], v[208:211], v[48:63]
	s_waitcnt lgkmcnt(0)
	v_mfma_f32_32x32x16_bf16 v[96:111], v[176:179], v[212:215], v[96:111]
	v_mfma_f32_32x32x16_bf16 v[32:47], v[180:183], v[212:215], v[32:47]
	ds_read_b128 v[208:211], v149 offset:9280
	ds_read_b128 v[212:215], v149 offset:13888
	s_waitcnt vmcnt(7)
	ds_write_b128 v148, v[168:171] offset:27648
	s_waitcnt vmcnt(6)
	ds_write_b128 v148, v[172:175] offset:64512
	ds_read_b128 v[168:171], v150 offset:96
	ds_read_b128 v[172:175], v150 offset:4704
	s_waitcnt lgkmcnt(5)
	v_mfma_f32_32x32x16_bf16 v[80:95], v[176:179], v[208:211], v[80:95]
	v_mfma_f32_32x32x16_bf16 v[16:31], v[180:183], v[208:211], v[16:31]
	ds_read_b128 v[208:211], v149 offset:96
	s_waitcnt lgkmcnt(5)
	v_mfma_f32_32x32x16_bf16 v[64:79], v[176:179], v[212:215], v[64:79]
	v_mfma_f32_32x32x16_bf16 v[0:15], v[180:183], v[212:215], v[0:15]
	ds_read_b128 v[212:215], v149 offset:4704
	s_setprio 0
	global_load_dwordx4 v[176:179], v[144:145], off offset:1664
	global_load_dwordx4 v[180:183], v[146:147], off offset:1664
	s_setprio 1
	s_waitcnt lgkmcnt(1)
	v_mfma_f32_32x32x16_bf16 v[112:127], v[168:171], v[208:211], v[112:127]
	v_mfma_f32_32x32x16_bf16 v[48:63], v[172:175], v[208:211], v[48:63]
	s_waitcnt lgkmcnt(0)
	v_mfma_f32_32x32x16_bf16 v[96:111], v[168:171], v[212:215], v[96:111]
	v_mfma_f32_32x32x16_bf16 v[32:47], v[172:175], v[212:215], v[32:47]
	ds_read_b128 v[208:211], v149 offset:9312
	ds_read_b128 v[212:215], v149 offset:13920
	s_waitcnt lgkmcnt(0)
	s_barrier
; template <bool trans>
; DI void gemm_core(const GTile& tl, const GTile& nx, bool has_next  , bool chain  , bool pre, u32x4 (&ra)[4], u32x4 (&rb)[4], char* smem, f32x16 (&acc)[2][4]) {
;     ...
;   const int nk = K / 64;
;   if (!pre) { G_LOAD(0); G_STORE(0); G_LOAD(1); }
;   for (int kt = 0; kt < nk; ++kt) {
;     __syncthreads();
;     G_COMPUTE(kt & 1, kt);
;   }
	s_waitcnt vmcnt(7)
	ds_write_b128 v192, v[160:163]
	s_waitcnt vmcnt(6)
	ds_write_b128 v159, v[164:167]
	ds_read_b128 v[160:163], v152 offset:36864
	ds_read_b128 v[164:167], v152 offset:41472
	v_mfma_f32_32x32x16_bf16 v[80:95], v[168:171], v[208:211], v[80:95]
	v_mfma_f32_32x32x16_bf16 v[16:31], v[172:175], v[208:211], v[16:31]
	ds_read_b128 v[208:211], v151
	v_mfma_f32_32x32x16_bf16 v[64:79], v[168:171], v[212:215], v[64:79]
	v_mfma_f32_32x32x16_bf16 v[0:15], v[172:175], v[212:215], v[0:15]
	ds_read_b128 v[212:215], v151 offset:4608
	s_setprio 0
	global_load_dwordx4 v[168:171], v[136:137], off offset:1792
	global_load_dwordx4 v[172:175], v[138:139], off offset:1792
	s_setprio 1
	s_waitcnt lgkmcnt(1)
	v_mfma_f32_32x32x16_bf16 v[112:127], v[160:163], v[208:211], v[112:127]
	v_mfma_f32_32x32x16_bf16 v[48:63], v[164:167], v[208:211], v[48:63]
	s_waitcnt lgkmcnt(0)
	v_mfma_f32_32x32x16_bf16 v[96:111], v[160:163], v[212:215], v[96:111]
	v_mfma_f32_32x32x16_bf16 v[32:47], v[164:167], v[212:215], v[32:47]
	ds_read_b128 v[208:211], v151 offset:9216
	ds_read_b128 v[212:215], v151 offset:13824
	s_waitcnt vmcnt(7)
	ds_write_b128 v158, v[184:187]
	s_waitcnt vmcnt(6)
	ds_write_b128 v157, v[188:191]
	ds_read_b128 v[184:187], v152 offset:36896
	ds_read_b128 v[188:191], v152 offset:41504
	s_waitcnt lgkmcnt(5)
	v_mfma_f32_32x32x16_bf16 v[80:95], v[160:163], v[208:211], v[80:95]
	v_mfma_f32_32x32x16_bf16 v[16:31], v[164:167], v[208:211], v[16:31]
	ds_read_b128 v[208:211], v151 offset:32
	s_waitcnt lgkmcnt(5)
	v_mfma_f32_32x32x16_bf16 v[64:79], v[160:163], v[212:215], v[64:79]
	v_mfma_f32_32x32x16_bf16 v[0:15], v[164:167], v[212:215], v[0:15]
	ds_read_b128 v[212:215], v151 offset:4640
	s_setprio 0
	global_load_dwordx4 v[160:163], v[140:141], off offset:1792
	global_load_dwordx4 v[164:167], v[142:143], off offset:1792
	s_setprio 1
	s_waitcnt lgkmcnt(1)
	v_mfma_f32_32x32x16_bf16 v[112:127], v[184:187], v[208:211], v[112:127]
	v_mfma_f32_32x32x16_bf16 v[48:63], v[188:191], v[208:211], v[48:63]
	s_waitcnt lgkmcnt(0)
	v_mfma_f32_32x32x16_bf16 v[96:111], v[184:187], v[212:215], v[96:111]
	v_mfma_f32_32x32x16_bf16 v[32:47], v[188:191], v[212:215], v[32:47]
	ds_read_b128 v[208:211], v151 offset:9248
	ds_read_b128 v[212:215], v151 offset:13856
	s_waitcnt vmcnt(7)
	ds_write_b128 v154, v[194:197]
	s_waitcnt vmcnt(6)
	ds_write_b128 v153, v[198:201]
	ds_read_b128 v[194:197], v152 offset:36928
	ds_read_b128 v[198:201], v152 offset:41536
	s_waitcnt lgkmcnt(5)
	v_mfma_f32_32x32x16_bf16 v[80:95], v[184:187], v[208:211], v[80:95]
	v_mfma_f32_32x32x16_bf16 v[16:31], v[188:191], v[208:211], v[16:31]
	ds_read_b128 v[208:211], v151 offset:64
	s_waitcnt lgkmcnt(5)
	v_mfma_f32_32x32x16_bf16 v[64:79], v[184:187], v[212:215], v[64:79]
	v_mfma_f32_32x32x16_bf16 v[0:15], v[188:191], v[212:215], v[0:15]
	ds_read_b128 v[212:215], v151 offset:4672
	s_setprio 0
	global_load_dwordx4 v[184:187], v[132:133], off offset:1792
	global_load_dwordx4 v[188:191], v[134:135], off offset:1792
	s_setprio 1
	s_waitcnt lgkmcnt(1)
	v_mfma_f32_32x32x16_bf16 v[112:127], v[194:197], v[208:211], v[112:127]
	v_mfma_f32_32x32x16_bf16 v[48:63], v[198:201], v[208:211], v[48:63]
	s_waitcnt lgkmcnt(0)
	v_mfma_f32_32x32x16_bf16 v[96:111], v[194:197], v[212:215], v[96:111]
	v_mfma_f32_32x32x16_bf16 v[32:47], v[198:201], v[212:215], v[32:47]
	ds_read_b128 v[208:211], v151 offset:9280
	ds_read_b128 v[212:215], v151 offset:13888
	s_waitcnt vmcnt(7)
	ds_write_b128 v156, v[176:179]
	s_waitcnt vmcnt(6)
	ds_write_b128 v155, v[180:183]
	ds_read_b128 v[176:179], v152 offset:36960
	ds_read_b128 v[180:183], v152 offset:41568
	s_waitcnt lgkmcnt(5)
	v_mfma_f32_32x32x16_bf16 v[80:95], v[194:197], v[208:211], v[80:95]
	v_mfma_f32_32x32x16_bf16 v[16:31], v[198:201], v[208:211], v[16:31]
	ds_read_b128 v[208:211], v151 offset:96
	s_waitcnt lgkmcnt(5)
	v_mfma_f32_32x32x16_bf16 v[64:79], v[194:197], v[212:215], v[64:79]
	v_mfma_f32_32x32x16_bf16 v[0:15], v[198:201], v[212:215], v[0:15]
	ds_read_b128 v[212:215], v151 offset:4704
	s_setprio 0
	global_load_dwordx4 v[194:197], v[144:145], off offset:1792
	global_load_dwordx4 v[198:201], v[146:147], off offset:1792
	s_setprio 1
	s_waitcnt lgkmcnt(1)
	v_mfma_f32_32x32x16_bf16 v[112:127], v[176:179], v[208:211], v[112:127]
	v_mfma_f32_32x32x16_bf16 v[48:63], v[180:183], v[208:211], v[48:63]
	s_waitcnt lgkmcnt(0)
	v_mfma_f32_32x32x16_bf16 v[96:111], v[176:179], v[212:215], v[96:111]
	v_mfma_f32_32x32x16_bf16 v[32:47], v[180:183], v[212:215], v[32:47]
	ds_read_b128 v[208:211], v151 offset:9312
	ds_read_b128 v[212:215], v151 offset:13920
	s_waitcnt lgkmcnt(0)
	s_barrier
; template <bool trans>
; DI void gemm_core(const GTile& tl, const GTile& nx, bool has_next  , bool chain  , bool pre, u32x4 (&ra)[4], u32x4 (&rb)[4], char* smem, f32x16 (&acc)[2][4]) {
;     ...
;   const int nk = K / 64;
;   if (!pre) { G_LOAD(0); G_STORE(0); G_LOAD(1); }
;   for (int kt = 0; kt < nk; ++kt) {
;     __syncthreads();
;     G_COMPUTE(kt & 1, kt);
;   }
	s_waitcnt vmcnt(7)
	ds_write_b128 v148, v[168:171]
	s_waitcnt vmcnt(6)
	ds_write_b128 v148, v[172:175] offset:36864
	ds_read_b128 v[168:171], v150
	ds_read_b128 v[172:175], v150 offset:4608
	v_mfma_f32_32x32x16_bf16 v[80:95], v[176:179], v[208:211], v[80:95]
	v_mfma_f32_32x32x16_bf16 v[16:31], v[180:183], v[208:211], v[16:31]
	ds_read_b128 v[208:211], v149
	v_mfma_f32_32x32x16_bf16 v[64:79], v[176:179], v[212:215], v[64:79]
	v_mfma_f32_32x32x16_bf16 v[0:15], v[180:183], v[212:215], v[0:15]
	ds_read_b128 v[212:215], v149 offset:4608
	s_setprio 0
	global_load_dwordx4 v[176:179], v[136:137], off offset:1920
	global_load_dwordx4 v[180:183], v[138:139], off offset:1920
	s_setprio 1
	s_waitcnt lgkmcnt(1)
	v_mfma_f32_32x32x16_bf16 v[112:127], v[168:171], v[208:211], v[112:127]
	v_mfma_f32_32x32x16_bf16 v[48:63], v[172:175], v[208:211], v[48:63]
	s_waitcnt lgkmcnt(0)
	v_mfma_f32_32x32x16_bf16 v[96:111], v[168:171], v[212:215], v[96:111]
	v_mfma_f32_32x32x16_bf16 v[32:47], v[172:175], v[212:215], v[32:47]
	ds_read_b128 v[208:211], v149 offset:9216
	ds_read_b128 v[212:215], v149 offset:13824
	s_waitcnt vmcnt(7)
	ds_write_b128 v148, v[160:163] offset:9216
	s_waitcnt vmcnt(6)
	ds_write_b128 v148, v[164:167] offset:46080
	ds_read_b128 v[160:163], v150 offset:32
	ds_read_b128 v[164:167], v150 offset:4640
	s_waitcnt lgkmcnt(5)
	v_mfma_f32_32x32x16_bf16 v[80:95], v[168:171], v[208:211], v[80:95]
	v_mfma_f32_32x32x16_bf16 v[16:31], v[172:175], v[208:211], v[16:31]
	ds_read_b128 v[208:211], v149 offset:32
	s_waitcnt lgkmcnt(5)
	v_mfma_f32_32x32x16_bf16 v[64:79], v[168:171], v[212:215], v[64:79]
	v_mfma_f32_32x32x16_bf16 v[0:15], v[172:175], v[212:215], v[0:15]
	ds_read_b128 v[212:215], v149 offset:4640
	s_setprio 0
	global_load_dwordx4 v[168:171], v[140:141], off offset:1920
	global_load_dwordx4 v[172:175], v[142:143], off offset:1920
	s_setprio 1
	s_waitcnt lgkmcnt(1)
	v_mfma_f32_32x32x16_bf16 v[112:127], v[160:163], v[208:211], v[112:127]
	v_mfma_f32_32x32x16_bf16 v[48:63], v[164:167], v[208:211], v[48:63]
	s_waitcnt lgkmcnt(0)
	v_mfma_f32_32x32x16_bf16 v[96:111], v[160:163], v[212:215], v[96:111]
	v_mfma_f32_32x32x16_bf16 v[32:47], v[164:167], v[212:215], v[32:47]
	ds_read_b128 v[208:211], v149 offset:9248
	ds_read_b128 v[212:215], v149 offset:13856
	s_waitcnt vmcnt(7)
	ds_write_b128 v148, v[184:187] offset:18432
	s_waitcnt vmcnt(6)
	ds_write_b128 v148, v[188:191] offset:55296
	ds_read_b128 v[184:187], v150 offset:64
	ds_read_b128 v[188:191], v150 offset:4672
	s_waitcnt lgkmcnt(5)
	v_mfma_f32_32x32x16_bf16 v[80:95], v[160:163], v[208:211], v[80:95]
	v_mfma_f32_32x32x16_bf16 v[16:31], v[164:167], v[208:211], v[16:31]
	ds_read_b128 v[208:211], v149 offset:64
	s_waitcnt lgkmcnt(5)
	v_mfma_f32_32x32x16_bf16 v[64:79], v[160:163], v[212:215], v[64:79]
	v_mfma_f32_32x32x16_bf16 v[0:15], v[164:167], v[212:215], v[0:15]
	ds_read_b128 v[212:215], v149 offset:4672
	s_setprio 0
	global_load_dwordx4 v[160:163], v[132:133], off offset:1920
	global_load_dwordx4 v[164:167], v[134:135], off offset:1920
	s_setprio 1
	s_waitcnt lgkmcnt(1)
	v_mfma_f32_32x32x16_bf16 v[112:127], v[184:187], v[208:211], v[112:127]
	v_mfma_f32_32x32x16_bf16 v[48:63], v[188:191], v[208:211], v[48:63]
	s_waitcnt lgkmcnt(0)
	v_mfma_f32_32x32x16_bf16 v[96:111], v[184:187], v[212:215], v[96:111]
	v_mfma_f32_32x32x16_bf16 v[32:47], v[188:191], v[212:215], v[32:47]
	ds_read_b128 v[208:211], v149 offset:9280
	ds_read_b128 v[212:215], v149 offset:13888
	s_waitcnt vmcnt(7)
	ds_write_b128 v148, v[194:197] offset:27648
	s_waitcnt vmcnt(6)
	ds_write_b128 v148, v[198:201] offset:64512
	ds_read_b128 v[194:197], v150 offset:96
	ds_read_b128 v[198:201], v150 offset:4704
	s_waitcnt lgkmcnt(5)
	v_mfma_f32_32x32x16_bf16 v[80:95], v[184:187], v[208:211], v[80:95]
	v_mfma_f32_32x32x16_bf16 v[16:31], v[188:191], v[208:211], v[16:31]
	ds_read_b128 v[208:211], v149 offset:96
	s_waitcnt lgkmcnt(5)
	v_mfma_f32_32x32x16_bf16 v[64:79], v[184:187], v[212:215], v[64:79]
	v_mfma_f32_32x32x16_bf16 v[0:15], v[188:191], v[212:215], v[0:15]
	ds_read_b128 v[212:215], v149 offset:4704
	s_setprio 0
	global_load_dwordx4 v[184:187], v[144:145], off offset:1920
	global_load_dwordx4 v[188:191], v[146:147], off offset:1920
	s_setprio 1
	s_waitcnt lgkmcnt(1)
	v_mfma_f32_32x32x16_bf16 v[112:127], v[194:197], v[208:211], v[112:127]
	v_mfma_f32_32x32x16_bf16 v[48:63], v[198:201], v[208:211], v[48:63]
	s_waitcnt lgkmcnt(0)
	v_mfma_f32_32x32x16_bf16 v[96:111], v[194:197], v[212:215], v[96:111]
	v_mfma_f32_32x32x16_bf16 v[32:47], v[198:201], v[212:215], v[32:47]
	ds_read_b128 v[208:211], v149 offset:9312
	ds_read_b128 v[212:215], v149 offset:13920
	s_waitcnt lgkmcnt(0)
	s_barrier
; template <bool trans>
; DI void gemm_core(const GTile& tl, const GTile& nx, bool has_next  , bool chain  , bool pre, u32x4 (&ra)[4], u32x4 (&rb)[4], char* smem, f32x16 (&acc)[2][4]) {
;     ...
;   const int nk = K / 64;
;   if (!pre) { G_LOAD(0); G_STORE(0); G_LOAD(1); }
;   for (int kt = 0; kt < nk; ++kt) {
;     __syncthreads();
;     G_COMPUTE(kt & 1, kt);
;   }
	s_waitcnt vmcnt(7)
	ds_write_b128 v192, v[176:179]
	s_waitcnt vmcnt(6)
	ds_write_b128 v159, v[180:183]
	ds_read_b128 v[176:179], v152 offset:36864
	ds_read_b128 v[180:183], v152 offset:41472
	v_mfma_f32_32x32x16_bf16 v[80:95], v[194:197], v[208:211], v[80:95]
	v_mfma_f32_32x32x16_bf16 v[16:31], v[198:201], v[208:211], v[16:31]
	ds_read_b128 v[208:211], v151
	v_mfma_f32_32x32x16_bf16 v[64:79], v[194:197], v[212:215], v[64:79]
	v_mfma_f32_32x32x16_bf16 v[0:15], v[198:201], v[212:215], v[0:15]
	ds_read_b128 v[212:215], v151 offset:4608
	s_setprio 0
	global_load_dwordx4 v[194:197], v[136:137], off offset:2048
	global_load_dwordx4 v[198:201], v[138:139], off offset:2048
	s_setprio 1
	s_waitcnt lgkmcnt(1)
	v_mfma_f32_32x32x16_bf16 v[112:127], v[176:179], v[208:211], v[112:127]
	v_mfma_f32_32x32x16_bf16 v[48:63], v[180:183], v[208:211], v[48:63]
	s_waitcnt lgkmcnt(0)
	v_mfma_f32_32x32x16_bf16 v[96:111], v[176:179], v[212:215], v[96:111]
	v_mfma_f32_32x32x16_bf16 v[32:47], v[180:183], v[212:215], v[32:47]
	ds_read_b128 v[208:211], v151 offset:9216
	ds_read_b128 v[212:215], v151 offset:13824
	s_waitcnt vmcnt(7)
	ds_write_b128 v158, v[168:171]
	s_waitcnt vmcnt(6)
	ds_write_b128 v157, v[172:175]
	ds_read_b128 v[168:171], v152 offset:36896
	ds_read_b128 v[172:175], v152 offset:41504
	s_waitcnt lgkmcnt(5)
	v_mfma_f32_32x32x16_bf16 v[80:95], v[176:179], v[208:211], v[80:95]
	v_mfma_f32_32x32x16_bf16 v[16:31], v[180:183], v[208:211], v[16:31]
	ds_read_b128 v[208:211], v151 offset:32
	s_waitcnt lgkmcnt(5)
	v_mfma_f32_32x32x16_bf16 v[64:79], v[176:179], v[212:215], v[64:79]
	v_mfma_f32_32x32x16_bf16 v[0:15], v[180:183], v[212:215], v[0:15]
	ds_read_b128 v[212:215], v151 offset:4640
	s_setprio 0
	global_load_dwordx4 v[176:179], v[140:141], off offset:2048
	global_load_dwordx4 v[180:183], v[142:143], off offset:2048
	s_setprio 1
	s_waitcnt lgkmcnt(1)
	v_mfma_f32_32x32x16_bf16 v[112:127], v[168:171], v[208:211], v[112:127]
	v_mfma_f32_32x32x16_bf16 v[48:63], v[172:175], v[208:211], v[48:63]
	s_waitcnt lgkmcnt(0)
	v_mfma_f32_32x32x16_bf16 v[96:111], v[168:171], v[212:215], v[96:111]
	v_mfma_f32_32x32x16_bf16 v[32:47], v[172:175], v[212:215], v[32:47]
	ds_read_b128 v[208:211], v151 offset:9248
	ds_read_b128 v[212:215], v151 offset:13856
	s_waitcnt vmcnt(7)
	ds_write_b128 v154, v[160:163]
	s_waitcnt vmcnt(6)
	ds_write_b128 v153, v[164:167]
	ds_read_b128 v[160:163], v152 offset:36928
	ds_read_b128 v[164:167], v152 offset:41536
	s_waitcnt lgkmcnt(5)
	v_mfma_f32_32x32x16_bf16 v[80:95], v[168:171], v[208:211], v[80:95]
	v_mfma_f32_32x32x16_bf16 v[16:31], v[172:175], v[208:211], v[16:31]
	ds_read_b128 v[208:211], v151 offset:64
	s_waitcnt lgkmcnt(5)
	v_mfma_f32_32x32x16_bf16 v[64:79], v[168:171], v[212:215], v[64:79]
	v_mfma_f32_32x32x16_bf16 v[0:15], v[172:175], v[212:215], v[0:15]
	ds_read_b128 v[212:215], v151 offset:4672
	s_setprio 0
	global_load_dwordx4 v[168:171], v[132:133], off offset:2048
	global_load_dwordx4 v[172:175], v[134:135], off offset:2048
	s_setprio 1
	s_waitcnt lgkmcnt(1)
	v_mfma_f32_32x32x16_bf16 v[112:127], v[160:163], v[208:211], v[112:127]
	v_mfma_f32_32x32x16_bf16 v[48:63], v[164:167], v[208:211], v[48:63]
	s_waitcnt lgkmcnt(0)
	v_mfma_f32_32x32x16_bf16 v[96:111], v[160:163], v[212:215], v[96:111]
	v_mfma_f32_32x32x16_bf16 v[32:47], v[164:167], v[212:215], v[32:47]
	ds_read_b128 v[208:211], v151 offset:9280
	ds_read_b128 v[212:215], v151 offset:13888
	s_waitcnt vmcnt(7)
	ds_write_b128 v156, v[184:187]
	s_waitcnt vmcnt(6)
	ds_write_b128 v155, v[188:191]
	ds_read_b128 v[184:187], v152 offset:36960
	ds_read_b128 v[188:191], v152 offset:41568
	s_waitcnt lgkmcnt(5)
	v_mfma_f32_32x32x16_bf16 v[80:95], v[160:163], v[208:211], v[80:95]
	v_mfma_f32_32x32x16_bf16 v[16:31], v[164:167], v[208:211], v[16:31]
	ds_read_b128 v[208:211], v151 offset:96
	s_waitcnt lgkmcnt(5)
	v_mfma_f32_32x32x16_bf16 v[64:79], v[160:163], v[212:215], v[64:79]
	v_mfma_f32_32x32x16_bf16 v[0:15], v[164:167], v[212:215], v[0:15]
	ds_read_b128 v[212:215], v151 offset:4704
	s_setprio 0
	global_load_dwordx4 v[160:163], v[144:145], off offset:2048
	global_load_dwordx4 v[164:167], v[146:147], off offset:2048
	s_setprio 1
	s_waitcnt lgkmcnt(1)
	v_mfma_f32_32x32x16_bf16 v[112:127], v[184:187], v[208:211], v[112:127]
	v_mfma_f32_32x32x16_bf16 v[48:63], v[188:191], v[208:211], v[48:63]
	s_waitcnt lgkmcnt(0)
	v_mfma_f32_32x32x16_bf16 v[96:111], v[184:187], v[212:215], v[96:111]
	v_mfma_f32_32x32x16_bf16 v[32:47], v[188:191], v[212:215], v[32:47]
	ds_read_b128 v[208:211], v151 offset:9312
	ds_read_b128 v[212:215], v151 offset:13920
	s_waitcnt lgkmcnt(0)
	s_barrier
; template <bool trans>
; DI void gemm_core(const GTile& tl, const GTile& nx, bool has_next  , bool chain  , bool pre, u32x4 (&ra)[4], u32x4 (&rb)[4], char* smem, f32x16 (&acc)[2][4]) {
;     ...
;   const int nk = K / 64;
;   if (!pre) { G_LOAD(0); G_STORE(0); G_LOAD(1); }
;   for (int kt = 0; kt < nk; ++kt) {
;     __syncthreads();
;     G_COMPUTE(kt & 1, kt);
;   }
	s_waitcnt vmcnt(7)
	ds_write_b128 v148, v[194:197]
	s_waitcnt vmcnt(6)
	ds_write_b128 v148, v[198:201] offset:36864
	ds_read_b128 v[194:197], v150
	ds_read_b128 v[198:201], v150 offset:4608
	v_mfma_f32_32x32x16_bf16 v[80:95], v[184:187], v[208:211], v[80:95]
	v_mfma_f32_32x32x16_bf16 v[16:31], v[188:191], v[208:211], v[16:31]
	ds_read_b128 v[208:211], v149
	v_mfma_f32_32x32x16_bf16 v[64:79], v[184:187], v[212:215], v[64:79]
	v_mfma_f32_32x32x16_bf16 v[0:15], v[188:191], v[212:215], v[0:15]
	ds_read_b128 v[212:215], v149 offset:4608
	s_setprio 0
	global_load_dwordx4 v[184:187], v[136:137], off offset:2176
	global_load_dwordx4 v[188:191], v[138:139], off offset:2176
	s_setprio 1
	s_waitcnt lgkmcnt(1)
	v_mfma_f32_32x32x16_bf16 v[112:127], v[194:197], v[208:211], v[112:127]
	v_mfma_f32_32x32x16_bf16 v[48:63], v[198:201], v[208:211], v[48:63]
	s_waitcnt lgkmcnt(0)
	v_mfma_f32_32x32x16_bf16 v[96:111], v[194:197], v[212:215], v[96:111]
	v_mfma_f32_32x32x16_bf16 v[32:47], v[198:201], v[212:215], v[32:47]
	ds_read_b128 v[208:211], v149 offset:9216
	ds_read_b128 v[212:215], v149 offset:13824
	s_waitcnt vmcnt(7)
	ds_write_b128 v148, v[176:179] offset:9216
	s_waitcnt vmcnt(6)
	ds_write_b128 v148, v[180:183] offset:46080
	ds_read_b128 v[176:179], v150 offset:32
	ds_read_b128 v[180:183], v150 offset:4640
	s_waitcnt lgkmcnt(5)
	v_mfma_f32_32x32x16_bf16 v[80:95], v[194:197], v[208:211], v[80:95]
	v_mfma_f32_32x32x16_bf16 v[16:31], v[198:201], v[208:211], v[16:31]
	ds_read_b128 v[208:211], v149 offset:32
	s_waitcnt lgkmcnt(5)
	v_mfma_f32_32x32x16_bf16 v[64:79], v[194:197], v[212:215], v[64:79]
	v_mfma_f32_32x32x16_bf16 v[0:15], v[198:201], v[212:215], v[0:15]
	ds_read_b128 v[212:215], v149 offset:4640
	s_setprio 0
	global_load_dwordx4 v[194:197], v[140:141], off offset:2176
	global_load_dwordx4 v[198:201], v[142:143], off offset:2176
	s_setprio 1
	s_waitcnt lgkmcnt(1)
	v_mfma_f32_32x32x16_bf16 v[112:127], v[176:179], v[208:211], v[112:127]
	v_mfma_f32_32x32x16_bf16 v[48:63], v[180:183], v[208:211], v[48:63]
	s_waitcnt lgkmcnt(0)
	v_mfma_f32_32x32x16_bf16 v[96:111], v[176:179], v[212:215], v[96:111]
	v_mfma_f32_32x32x16_bf16 v[32:47], v[180:183], v[212:215], v[32:47]
	ds_read_b128 v[208:211], v149 offset:9248
	ds_read_b128 v[212:215], v149 offset:13856
	s_waitcnt vmcnt(7)
	ds_write_b128 v148, v[168:171] offset:18432
	s_waitcnt vmcnt(6)
	ds_write_b128 v148, v[172:175] offset:55296
	ds_read_b128 v[168:171], v150 offset:64
	ds_read_b128 v[172:175], v150 offset:4672
	s_waitcnt lgkmcnt(5)
	v_mfma_f32_32x32x16_bf16 v[80:95], v[176:179], v[208:211], v[80:95]
	v_mfma_f32_32x32x16_bf16 v[16:31], v[180:183], v[208:211], v[16:31]
	ds_read_b128 v[208:211], v149 offset:64
	s_waitcnt lgkmcnt(5)
	v_mfma_f32_32x32x16_bf16 v[64:79], v[176:179], v[212:215], v[64:79]
	v_mfma_f32_32x32x16_bf16 v[0:15], v[180:183], v[212:215], v[0:15]
	ds_read_b128 v[212:215], v149 offset:4672
	s_setprio 0
	global_load_dwordx4 v[176:179], v[132:133], off offset:2176
	global_load_dwordx4 v[180:183], v[134:135], off offset:2176
	s_setprio 1
	s_waitcnt lgkmcnt(1)
	v_mfma_f32_32x32x16_bf16 v[112:127], v[168:171], v[208:211], v[112:127]
	v_mfma_f32_32x32x16_bf16 v[48:63], v[172:175], v[208:211], v[48:63]
	s_waitcnt lgkmcnt(0)
	v_mfma_f32_32x32x16_bf16 v[96:111], v[168:171], v[212:215], v[96:111]
	v_mfma_f32_32x32x16_bf16 v[32:47], v[172:175], v[212:215], v[32:47]
	ds_read_b128 v[208:211], v149 offset:9280
	ds_read_b128 v[212:215], v149 offset:13888
	s_waitcnt vmcnt(7)
	ds_write_b128 v148, v[160:163] offset:27648
	s_waitcnt vmcnt(6)
	ds_write_b128 v148, v[164:167] offset:64512
	ds_read_b128 v[160:163], v150 offset:96
	ds_read_b128 v[164:167], v150 offset:4704
	s_waitcnt lgkmcnt(5)
	v_mfma_f32_32x32x16_bf16 v[80:95], v[168:171], v[208:211], v[80:95]
	v_mfma_f32_32x32x16_bf16 v[16:31], v[172:175], v[208:211], v[16:31]
	ds_read_b128 v[208:211], v149 offset:96
	s_waitcnt lgkmcnt(5)
	v_mfma_f32_32x32x16_bf16 v[64:79], v[168:171], v[212:215], v[64:79]
	v_mfma_f32_32x32x16_bf16 v[0:15], v[172:175], v[212:215], v[0:15]
	ds_read_b128 v[212:215], v149 offset:4704
	s_setprio 0
	global_load_dwordx4 v[168:171], v[144:145], off offset:2176
	global_load_dwordx4 v[172:175], v[146:147], off offset:2176
	s_setprio 1
	s_waitcnt lgkmcnt(1)
	v_mfma_f32_32x32x16_bf16 v[112:127], v[160:163], v[208:211], v[112:127]
	v_mfma_f32_32x32x16_bf16 v[48:63], v[164:167], v[208:211], v[48:63]
	s_waitcnt lgkmcnt(0)
	v_mfma_f32_32x32x16_bf16 v[96:111], v[160:163], v[212:215], v[96:111]
	v_mfma_f32_32x32x16_bf16 v[32:47], v[164:167], v[212:215], v[32:47]
	ds_read_b128 v[208:211], v149 offset:9312
	ds_read_b128 v[212:215], v149 offset:13920
	s_waitcnt lgkmcnt(0)
	s_barrier
; template <bool trans>
; DI void gemm_core(const GTile& tl, const GTile& nx, bool has_next  , bool chain  , bool pre, u32x4 (&ra)[4], u32x4 (&rb)[4], char* smem, f32x16 (&acc)[2][4]) {
;     ...
;   const int nk = K / 64;
;   if (!pre) { G_LOAD(0); G_STORE(0); G_LOAD(1); }
;   for (int kt = 0; kt < nk; ++kt) {
;     __syncthreads();
;     G_COMPUTE(kt & 1, kt);
;   }
	s_waitcnt vmcnt(7)
	ds_write_b128 v192, v[184:187]
	s_waitcnt vmcnt(6)
	ds_write_b128 v159, v[188:191]
	ds_read_b128 v[184:187], v152 offset:36864
	ds_read_b128 v[188:191], v152 offset:41472
	v_mfma_f32_32x32x16_bf16 v[80:95], v[160:163], v[208:211], v[80:95]
	v_mfma_f32_32x32x16_bf16 v[16:31], v[164:167], v[208:211], v[16:31]
	ds_read_b128 v[208:211], v151
	v_mfma_f32_32x32x16_bf16 v[64:79], v[160:163], v[212:215], v[64:79]
	v_mfma_f32_32x32x16_bf16 v[0:15], v[164:167], v[212:215], v[0:15]
	ds_read_b128 v[212:215], v151 offset:4608
	s_setprio 0
	global_load_dwordx4 v[160:163], v[136:137], off offset:2304
	global_load_dwordx4 v[164:167], v[138:139], off offset:2304
	s_setprio 1
	s_waitcnt lgkmcnt(1)
	v_mfma_f32_32x32x16_bf16 v[112:127], v[184:187], v[208:211], v[112:127]
	v_mfma_f32_32x32x16_bf16 v[48:63], v[188:191], v[208:211], v[48:63]
	s_waitcnt lgkmcnt(0)
	v_mfma_f32_32x32x16_bf16 v[96:111], v[184:187], v[212:215], v[96:111]
	v_mfma_f32_32x32x16_bf16 v[32:47], v[188:191], v[212:215], v[32:47]
	ds_read_b128 v[208:211], v151 offset:9216
	ds_read_b128 v[212:215], v151 offset:13824
	s_waitcnt vmcnt(7)
	ds_write_b128 v158, v[194:197]
	s_waitcnt vmcnt(6)
	ds_write_b128 v157, v[198:201]
	ds_read_b128 v[194:197], v152 offset:36896
	ds_read_b128 v[198:201], v152 offset:41504
	s_waitcnt lgkmcnt(5)
	v_mfma_f32_32x32x16_bf16 v[80:95], v[184:187], v[208:211], v[80:95]
	v_mfma_f32_32x32x16_bf16 v[16:31], v[188:191], v[208:211], v[16:31]
	ds_read_b128 v[208:211], v151 offset:32
	s_waitcnt lgkmcnt(5)
	v_mfma_f32_32x32x16_bf16 v[64:79], v[184:187], v[212:215], v[64:79]
	v_mfma_f32_32x32x16_bf16 v[0:15], v[188:191], v[212:215], v[0:15]
	ds_read_b128 v[212:215], v151 offset:4640
	s_setprio 0
	global_load_dwordx4 v[184:187], v[140:141], off offset:2304
	global_load_dwordx4 v[188:191], v[142:143], off offset:2304
	s_setprio 1
	s_waitcnt lgkmcnt(1)
	v_mfma_f32_32x32x16_bf16 v[112:127], v[194:197], v[208:211], v[112:127]
	v_mfma_f32_32x32x16_bf16 v[48:63], v[198:201], v[208:211], v[48:63]
	s_waitcnt lgkmcnt(0)
	v_mfma_f32_32x32x16_bf16 v[96:111], v[194:197], v[212:215], v[96:111]
	v_mfma_f32_32x32x16_bf16 v[32:47], v[198:201], v[212:215], v[32:47]
	ds_read_b128 v[208:211], v151 offset:9248
	ds_read_b128 v[212:215], v151 offset:13856
	s_waitcnt vmcnt(7)
	ds_write_b128 v154, v[176:179]
	s_waitcnt vmcnt(6)
	ds_write_b128 v153, v[180:183]
	ds_read_b128 v[176:179], v152 offset:36928
	ds_read_b128 v[180:183], v152 offset:41536
	s_waitcnt lgkmcnt(5)
	v_mfma_f32_32x32x16_bf16 v[80:95], v[194:197], v[208:211], v[80:95]
	v_mfma_f32_32x32x16_bf16 v[16:31], v[198:201], v[208:211], v[16:31]
	ds_read_b128 v[208:211], v151 offset:64
	s_waitcnt lgkmcnt(5)
	v_mfma_f32_32x32x16_bf16 v[64:79], v[194:197], v[212:215], v[64:79]
	v_mfma_f32_32x32x16_bf16 v[0:15], v[198:201], v[212:215], v[0:15]
	ds_read_b128 v[212:215], v151 offset:4672
	s_setprio 0
	global_load_dwordx4 v[194:197], v[132:133], off offset:2304
	global_load_dwordx4 v[198:201], v[134:135], off offset:2304
	s_setprio 1
	s_waitcnt lgkmcnt(1)
	v_mfma_f32_32x32x16_bf16 v[112:127], v[176:179], v[208:211], v[112:127]
	v_mfma_f32_32x32x16_bf16 v[48:63], v[180:183], v[208:211], v[48:63]
	s_waitcnt lgkmcnt(0)
	v_mfma_f32_32x32x16_bf16 v[96:111], v[176:179], v[212:215], v[96:111]
	v_mfma_f32_32x32x16_bf16 v[32:47], v[180:183], v[212:215], v[32:47]
	ds_read_b128 v[208:211], v151 offset:9280
	ds_read_b128 v[212:215], v151 offset:13888
	s_waitcnt vmcnt(7)
	ds_write_b128 v156, v[168:171]
	s_waitcnt vmcnt(6)
	ds_write_b128 v155, v[172:175]
	ds_read_b128 v[168:171], v152 offset:36960
	ds_read_b128 v[172:175], v152 offset:41568
	s_waitcnt lgkmcnt(5)
	v_mfma_f32_32x32x16_bf16 v[80:95], v[176:179], v[208:211], v[80:95]
	v_mfma_f32_32x32x16_bf16 v[16:31], v[180:183], v[208:211], v[16:31]
	ds_read_b128 v[208:211], v151 offset:96
	s_waitcnt lgkmcnt(5)
	v_mfma_f32_32x32x16_bf16 v[64:79], v[176:179], v[212:215], v[64:79]
	v_mfma_f32_32x32x16_bf16 v[0:15], v[180:183], v[212:215], v[0:15]
	ds_read_b128 v[212:215], v151 offset:4704
	s_setprio 0
	global_load_dwordx4 v[176:179], v[144:145], off offset:2304
	global_load_dwordx4 v[180:183], v[146:147], off offset:2304
	s_setprio 1
	s_waitcnt lgkmcnt(1)
	v_mfma_f32_32x32x16_bf16 v[112:127], v[168:171], v[208:211], v[112:127]
	v_mfma_f32_32x32x16_bf16 v[48:63], v[172:175], v[208:211], v[48:63]
	s_waitcnt lgkmcnt(0)
	v_mfma_f32_32x32x16_bf16 v[96:111], v[168:171], v[212:215], v[96:111]
	v_mfma_f32_32x32x16_bf16 v[32:47], v[172:175], v[212:215], v[32:47]
	ds_read_b128 v[208:211], v151 offset:9312
	ds_read_b128 v[212:215], v151 offset:13920
	s_waitcnt lgkmcnt(0)
	s_barrier
; template <bool trans>
; DI void gemm_core(const GTile& tl, const GTile& nx, bool has_next  , bool chain  , bool pre, u32x4 (&ra)[4], u32x4 (&rb)[4], char* smem, f32x16 (&acc)[2][4]) {
;     ...
;   const int nk = K / 64;
;   if (!pre) { G_LOAD(0); G_STORE(0); G_LOAD(1); }
;   for (int kt = 0; kt < nk; ++kt) {
;     __syncthreads();
;     G_COMPUTE(kt & 1, kt);
;   }
	s_waitcnt vmcnt(7)
	ds_write_b128 v148, v[160:163]
	s_waitcnt vmcnt(6)
	ds_write_b128 v148, v[164:167] offset:36864
	ds_read_b128 v[160:163], v150
	ds_read_b128 v[164:167], v150 offset:4608
	v_mfma_f32_32x32x16_bf16 v[80:95], v[168:171], v[208:211], v[80:95]
	v_mfma_f32_32x32x16_bf16 v[16:31], v[172:175], v[208:211], v[16:31]
	ds_read_b128 v[208:211], v149
	v_mfma_f32_32x32x16_bf16 v[64:79], v[168:171], v[212:215], v[64:79]
	v_mfma_f32_32x32x16_bf16 v[0:15], v[172:175], v[212:215], v[0:15]
	ds_read_b128 v[212:215], v149 offset:4608
	s_setprio 0
	global_load_dwordx4 v[168:171], v[136:137], off offset:2432
	global_load_dwordx4 v[172:175], v[138:139], off offset:2432
	s_setprio 1
	s_waitcnt lgkmcnt(1)
	v_mfma_f32_32x32x16_bf16 v[112:127], v[160:163], v[208:211], v[112:127]
	v_mfma_f32_32x32x16_bf16 v[48:63], v[164:167], v[208:211], v[48:63]
	s_waitcnt lgkmcnt(0)
	v_mfma_f32_32x32x16_bf16 v[96:111], v[160:163], v[212:215], v[96:111]
	v_mfma_f32_32x32x16_bf16 v[32:47], v[164:167], v[212:215], v[32:47]
	ds_read_b128 v[208:211], v149 offset:9216
	ds_read_b128 v[212:215], v149 offset:13824
	s_waitcnt vmcnt(7)
	ds_write_b128 v148, v[184:187] offset:9216
	s_waitcnt vmcnt(6)
	ds_write_b128 v148, v[188:191] offset:46080
	ds_read_b128 v[184:187], v150 offset:32
	ds_read_b128 v[188:191], v150 offset:4640
	s_waitcnt lgkmcnt(5)
	v_mfma_f32_32x32x16_bf16 v[80:95], v[160:163], v[208:211], v[80:95]
	v_mfma_f32_32x32x16_bf16 v[16:31], v[164:167], v[208:211], v[16:31]
	ds_read_b128 v[208:211], v149 offset:32
	s_waitcnt lgkmcnt(5)
	v_mfma_f32_32x32x16_bf16 v[64:79], v[160:163], v[212:215], v[64:79]
	v_mfma_f32_32x32x16_bf16 v[0:15], v[164:167], v[212:215], v[0:15]
	ds_read_b128 v[212:215], v149 offset:4640
	s_setprio 0
	global_load_dwordx4 v[160:163], v[140:141], off offset:2432
	global_load_dwordx4 v[164:167], v[142:143], off offset:2432
	s_setprio 1
	s_waitcnt lgkmcnt(1)
	v_mfma_f32_32x32x16_bf16 v[112:127], v[184:187], v[208:211], v[112:127]
	v_mfma_f32_32x32x16_bf16 v[48:63], v[188:191], v[208:211], v[48:63]
	s_waitcnt lgkmcnt(0)
	v_mfma_f32_32x32x16_bf16 v[96:111], v[184:187], v[212:215], v[96:111]
	v_mfma_f32_32x32x16_bf16 v[32:47], v[188:191], v[212:215], v[32:47]
	ds_read_b128 v[208:211], v149 offset:9248
	ds_read_b128 v[212:215], v149 offset:13856
	s_waitcnt vmcnt(7)
	ds_write_b128 v148, v[194:197] offset:18432
	s_waitcnt vmcnt(6)
	ds_write_b128 v148, v[198:201] offset:55296
	ds_read_b128 v[194:197], v150 offset:64
	ds_read_b128 v[198:201], v150 offset:4672
	s_waitcnt lgkmcnt(5)
	v_mfma_f32_32x32x16_bf16 v[80:95], v[184:187], v[208:211], v[80:95]
	v_mfma_f32_32x32x16_bf16 v[16:31], v[188:191], v[208:211], v[16:31]
	ds_read_b128 v[208:211], v149 offset:64
	s_waitcnt lgkmcnt(5)
	v_mfma_f32_32x32x16_bf16 v[64:79], v[184:187], v[212:215], v[64:79]
	v_mfma_f32_32x32x16_bf16 v[0:15], v[188:191], v[212:215], v[0:15]
	ds_read_b128 v[212:215], v149 offset:4672
	s_setprio 0
	global_load_dwordx4 v[184:187], v[132:133], off offset:2432
	global_load_dwordx4 v[188:191], v[134:135], off offset:2432
	s_setprio 1
	s_waitcnt lgkmcnt(1)
	v_mfma_f32_32x32x16_bf16 v[112:127], v[194:197], v[208:211], v[112:127]
	v_mfma_f32_32x32x16_bf16 v[48:63], v[198:201], v[208:211], v[48:63]
	s_waitcnt lgkmcnt(0)
	v_mfma_f32_32x32x16_bf16 v[96:111], v[194:197], v[212:215], v[96:111]
	v_mfma_f32_32x32x16_bf16 v[32:47], v[198:201], v[212:215], v[32:47]
	ds_read_b128 v[208:211], v149 offset:9280
	ds_read_b128 v[212:215], v149 offset:13888
	s_waitcnt vmcnt(7)
	ds_write_b128 v148, v[176:179] offset:27648
	s_waitcnt vmcnt(6)
	ds_write_b128 v148, v[180:183] offset:64512
	ds_read_b128 v[176:179], v150 offset:96
	ds_read_b128 v[180:183], v150 offset:4704
	s_waitcnt lgkmcnt(5)
	v_mfma_f32_32x32x16_bf16 v[80:95], v[194:197], v[208:211], v[80:95]
	v_mfma_f32_32x32x16_bf16 v[16:31], v[198:201], v[208:211], v[16:31]
	ds_read_b128 v[208:211], v149 offset:96
	s_waitcnt lgkmcnt(5)
	v_mfma_f32_32x32x16_bf16 v[64:79], v[194:197], v[212:215], v[64:79]
	v_mfma_f32_32x32x16_bf16 v[0:15], v[198:201], v[212:215], v[0:15]
	ds_read_b128 v[212:215], v149 offset:4704
	s_setprio 0
	global_load_dwordx4 v[194:197], v[144:145], off offset:2432
	global_load_dwordx4 v[198:201], v[146:147], off offset:2432
	s_setprio 1
	s_waitcnt lgkmcnt(1)
	v_mfma_f32_32x32x16_bf16 v[112:127], v[176:179], v[208:211], v[112:127]
	v_mfma_f32_32x32x16_bf16 v[48:63], v[180:183], v[208:211], v[48:63]
	s_waitcnt lgkmcnt(0)
	v_mfma_f32_32x32x16_bf16 v[96:111], v[176:179], v[212:215], v[96:111]
	v_mfma_f32_32x32x16_bf16 v[32:47], v[180:183], v[212:215], v[32:47]
	ds_read_b128 v[208:211], v149 offset:9312
	ds_read_b128 v[212:215], v149 offset:13920
	s_waitcnt lgkmcnt(0)
	s_barrier
; template <bool trans>
; DI void gemm_core(const GTile& tl, const GTile& nx, bool has_next  , bool chain  , bool pre, u32x4 (&ra)[4], u32x4 (&rb)[4], char* smem, f32x16 (&acc)[2][4]) {
;     ...
;   const int nk = K / 64;
;   if (!pre) { G_LOAD(0); G_STORE(0); G_LOAD(1); }
;   for (int kt = 0; kt < nk; ++kt) {
;     __syncthreads();
;     G_COMPUTE(kt & 1, kt);
;   }
	s_waitcnt vmcnt(7)
	ds_write_b128 v192, v[168:171]
	s_waitcnt vmcnt(6)
	ds_write_b128 v159, v[172:175]
	ds_read_b128 v[168:171], v152 offset:36864
	ds_read_b128 v[172:175], v152 offset:41472
	v_mfma_f32_32x32x16_bf16 v[80:95], v[176:179], v[208:211], v[80:95]
	v_mfma_f32_32x32x16_bf16 v[16:31], v[180:183], v[208:211], v[16:31]
	ds_read_b128 v[208:211], v151
	v_mfma_f32_32x32x16_bf16 v[64:79], v[176:179], v[212:215], v[64:79]
	v_mfma_f32_32x32x16_bf16 v[0:15], v[180:183], v[212:215], v[0:15]
	ds_read_b128 v[212:215], v151 offset:4608
	s_setprio 0
	global_load_dwordx4 v[176:179], v[136:137], off offset:2560
	global_load_dwordx4 v[180:183], v[138:139], off offset:2560
	s_setprio 1
	s_waitcnt lgkmcnt(1)
	v_mfma_f32_32x32x16_bf16 v[112:127], v[168:171], v[208:211], v[112:127]
	v_mfma_f32_32x32x16_bf16 v[48:63], v[172:175], v[208:211], v[48:63]
	s_waitcnt lgkmcnt(0)
	v_mfma_f32_32x32x16_bf16 v[96:111], v[168:171], v[212:215], v[96:111]
	v_mfma_f32_32x32x16_bf16 v[32:47], v[172:175], v[212:215], v[32:47]
	ds_read_b128 v[208:211], v151 offset:9216
	ds_read_b128 v[212:215], v151 offset:13824
	s_waitcnt vmcnt(7)
	ds_write_b128 v158, v[160:163]
	s_waitcnt vmcnt(6)
	ds_write_b128 v157, v[164:167]
	ds_read_b128 v[160:163], v152 offset:36896
	ds_read_b128 v[164:167], v152 offset:41504
	s_waitcnt lgkmcnt(5)
	v_mfma_f32_32x32x16_bf16 v[80:95], v[168:171], v[208:211], v[80:95]
	v_mfma_f32_32x32x16_bf16 v[16:31], v[172:175], v[208:211], v[16:31]
	ds_read_b128 v[208:211], v151 offset:32
	s_waitcnt lgkmcnt(5)
	v_mfma_f32_32x32x16_bf16 v[64:79], v[168:171], v[212:215], v[64:79]
	v_mfma_f32_32x32x16_bf16 v[0:15], v[172:175], v[212:215], v[0:15]
	ds_read_b128 v[212:215], v151 offset:4640
	s_setprio 0
	global_load_dwordx4 v[168:171], v[140:141], off offset:2560
	global_load_dwordx4 v[172:175], v[142:143], off offset:2560
	s_setprio 1
	s_waitcnt lgkmcnt(1)
	v_mfma_f32_32x32x16_bf16 v[112:127], v[160:163], v[208:211], v[112:127]
	v_mfma_f32_32x32x16_bf16 v[48:63], v[164:167], v[208:211], v[48:63]
	s_waitcnt lgkmcnt(0)
	v_mfma_f32_32x32x16_bf16 v[96:111], v[160:163], v[212:215], v[96:111]
	v_mfma_f32_32x32x16_bf16 v[32:47], v[164:167], v[212:215], v[32:47]
	ds_read_b128 v[208:211], v151 offset:9248
	ds_read_b128 v[212:215], v151 offset:13856
	s_waitcnt vmcnt(7)
	ds_write_b128 v154, v[184:187]
	s_waitcnt vmcnt(6)
	ds_write_b128 v153, v[188:191]
	ds_read_b128 v[184:187], v152 offset:36928
	ds_read_b128 v[188:191], v152 offset:41536
	s_waitcnt lgkmcnt(5)
	v_mfma_f32_32x32x16_bf16 v[80:95], v[160:163], v[208:211], v[80:95]
	v_mfma_f32_32x32x16_bf16 v[16:31], v[164:167], v[208:211], v[16:31]
	ds_read_b128 v[208:211], v151 offset:64
	s_waitcnt lgkmcnt(5)
	v_mfma_f32_32x32x16_bf16 v[64:79], v[160:163], v[212:215], v[64:79]
	v_mfma_f32_32x32x16_bf16 v[0:15], v[164:167], v[212:215], v[0:15]
	ds_read_b128 v[212:215], v151 offset:4672
	s_setprio 0
	global_load_dwordx4 v[160:163], v[132:133], off offset:2560
	global_load_dwordx4 v[164:167], v[134:135], off offset:2560
	s_setprio 1
	s_waitcnt lgkmcnt(1)
	v_mfma_f32_32x32x16_bf16 v[112:127], v[184:187], v[208:211], v[112:127]
	v_mfma_f32_32x32x16_bf16 v[48:63], v[188:191], v[208:211], v[48:63]
	s_waitcnt lgkmcnt(0)
	v_mfma_f32_32x32x16_bf16 v[96:111], v[184:187], v[212:215], v[96:111]
	v_mfma_f32_32x32x16_bf16 v[32:47], v[188:191], v[212:215], v[32:47]
	ds_read_b128 v[208:211], v151 offset:9280
	ds_read_b128 v[212:215], v151 offset:13888
	s_waitcnt vmcnt(7)
	ds_write_b128 v156, v[194:197]
	s_waitcnt vmcnt(6)
	ds_write_b128 v155, v[198:201]
	ds_read_b128 v[194:197], v152 offset:36960
	ds_read_b128 v[198:201], v152 offset:41568
	s_waitcnt lgkmcnt(5)
	v_mfma_f32_32x32x16_bf16 v[80:95], v[184:187], v[208:211], v[80:95]
	v_mfma_f32_32x32x16_bf16 v[16:31], v[188:191], v[208:211], v[16:31]
	ds_read_b128 v[208:211], v151 offset:96
	s_waitcnt lgkmcnt(5)
	v_mfma_f32_32x32x16_bf16 v[64:79], v[184:187], v[212:215], v[64:79]
	v_mfma_f32_32x32x16_bf16 v[0:15], v[188:191], v[212:215], v[0:15]
	ds_read_b128 v[212:215], v151 offset:4704
	s_setprio 0
	global_load_dwordx4 v[184:187], v[144:145], off offset:2560
	global_load_dwordx4 v[188:191], v[146:147], off offset:2560
	s_setprio 1
	s_waitcnt lgkmcnt(1)
	v_mfma_f32_32x32x16_bf16 v[112:127], v[194:197], v[208:211], v[112:127]
	v_mfma_f32_32x32x16_bf16 v[48:63], v[198:201], v[208:211], v[48:63]
	s_waitcnt lgkmcnt(0)
	v_mfma_f32_32x32x16_bf16 v[96:111], v[194:197], v[212:215], v[96:111]
	v_mfma_f32_32x32x16_bf16 v[32:47], v[198:201], v[212:215], v[32:47]
	ds_read_b128 v[208:211], v151 offset:9312
	ds_read_b128 v[212:215], v151 offset:13920
	s_waitcnt lgkmcnt(0)
	s_barrier
; template <bool trans>
; DI void gemm_core(const GTile& tl, const GTile& nx, bool has_next  , bool chain  , bool pre, u32x4 (&ra)[4], u32x4 (&rb)[4], char* smem, f32x16 (&acc)[2][4]) {
;     ...
;   const int nk = K / 64;
;   if (!pre) { G_LOAD(0); G_STORE(0); G_LOAD(1); }
;   for (int kt = 0; kt < nk; ++kt) {
;     __syncthreads();
;     G_COMPUTE(kt & 1, kt);
;   }
	s_waitcnt vmcnt(7)
	ds_write_b128 v148, v[176:179]
	s_waitcnt vmcnt(6)
	ds_write_b128 v148, v[180:183] offset:36864
	ds_read_b128 v[176:179], v150
	ds_read_b128 v[180:183], v150 offset:4608
	v_mfma_f32_32x32x16_bf16 v[80:95], v[194:197], v[208:211], v[80:95]
	v_mfma_f32_32x32x16_bf16 v[16:31], v[198:201], v[208:211], v[16:31]
	ds_read_b128 v[208:211], v149
	v_mfma_f32_32x32x16_bf16 v[64:79], v[194:197], v[212:215], v[64:79]
	v_mfma_f32_32x32x16_bf16 v[0:15], v[198:201], v[212:215], v[0:15]
	ds_read_b128 v[212:215], v149 offset:4608
	s_setprio 0
	global_load_dwordx4 v[194:197], v[136:137], off offset:2688
	global_load_dwordx4 v[198:201], v[138:139], off offset:2688
	s_setprio 1
	s_waitcnt lgkmcnt(1)
	v_mfma_f32_32x32x16_bf16 v[112:127], v[176:179], v[208:211], v[112:127]
	v_mfma_f32_32x32x16_bf16 v[48:63], v[180:183], v[208:211], v[48:63]
	s_waitcnt lgkmcnt(0)
	v_mfma_f32_32x32x16_bf16 v[96:111], v[176:179], v[212:215], v[96:111]
	v_mfma_f32_32x32x16_bf16 v[32:47], v[180:183], v[212:215], v[32:47]
	ds_read_b128 v[208:211], v149 offset:9216
	ds_read_b128 v[212:215], v149 offset:13824
	s_waitcnt vmcnt(7)
	ds_write_b128 v148, v[168:171] offset:9216
	s_waitcnt vmcnt(6)
	ds_write_b128 v148, v[172:175] offset:46080
	ds_read_b128 v[168:171], v150 offset:32
	ds_read_b128 v[172:175], v150 offset:4640
	s_waitcnt lgkmcnt(5)
	v_mfma_f32_32x32x16_bf16 v[80:95], v[176:179], v[208:211], v[80:95]
	v_mfma_f32_32x32x16_bf16 v[16:31], v[180:183], v[208:211], v[16:31]
	ds_read_b128 v[208:211], v149 offset:32
	s_waitcnt lgkmcnt(5)
	v_mfma_f32_32x32x16_bf16 v[64:79], v[176:179], v[212:215], v[64:79]
	v_mfma_f32_32x32x16_bf16 v[0:15], v[180:183], v[212:215], v[0:15]
	ds_read_b128 v[212:215], v149 offset:4640
	s_setprio 0
	global_load_dwordx4 v[176:179], v[140:141], off offset:2688
	global_load_dwordx4 v[180:183], v[142:143], off offset:2688
	s_setprio 1
	s_waitcnt lgkmcnt(1)
	v_mfma_f32_32x32x16_bf16 v[112:127], v[168:171], v[208:211], v[112:127]
	v_mfma_f32_32x32x16_bf16 v[48:63], v[172:175], v[208:211], v[48:63]
	s_waitcnt lgkmcnt(0)
	v_mfma_f32_32x32x16_bf16 v[96:111], v[168:171], v[212:215], v[96:111]
	v_mfma_f32_32x32x16_bf16 v[32:47], v[172:175], v[212:215], v[32:47]
	ds_read_b128 v[208:211], v149 offset:9248
	ds_read_b128 v[212:215], v149 offset:13856
	s_waitcnt vmcnt(7)
	ds_write_b128 v148, v[160:163] offset:18432
	s_waitcnt vmcnt(6)
	ds_write_b128 v148, v[164:167] offset:55296
	ds_read_b128 v[160:163], v150 offset:64
	ds_read_b128 v[164:167], v150 offset:4672
	s_waitcnt lgkmcnt(5)
	v_mfma_f32_32x32x16_bf16 v[80:95], v[168:171], v[208:211], v[80:95]
	v_mfma_f32_32x32x16_bf16 v[16:31], v[172:175], v[208:211], v[16:31]
	ds_read_b128 v[208:211], v149 offset:64
	s_waitcnt lgkmcnt(5)
	v_mfma_f32_32x32x16_bf16 v[64:79], v[168:171], v[212:215], v[64:79]
	v_mfma_f32_32x32x16_bf16 v[0:15], v[172:175], v[212:215], v[0:15]
	ds_read_b128 v[212:215], v149 offset:4672
	s_setprio 0
	global_load_dwordx4 v[168:171], v[132:133], off offset:2688
	global_load_dwordx4 v[172:175], v[134:135], off offset:2688
	s_setprio 1
	s_waitcnt lgkmcnt(1)
	v_mfma_f32_32x32x16_bf16 v[112:127], v[160:163], v[208:211], v[112:127]
	v_mfma_f32_32x32x16_bf16 v[48:63], v[164:167], v[208:211], v[48:63]
	s_waitcnt lgkmcnt(0)
	v_mfma_f32_32x32x16_bf16 v[96:111], v[160:163], v[212:215], v[96:111]
	v_mfma_f32_32x32x16_bf16 v[32:47], v[164:167], v[212:215], v[32:47]
	ds_read_b128 v[208:211], v149 offset:9280
	ds_read_b128 v[212:215], v149 offset:13888
	s_waitcnt vmcnt(7)
	ds_write_b128 v148, v[184:187] offset:27648
	s_waitcnt vmcnt(6)
	ds_write_b128 v148, v[188:191] offset:64512
	ds_read_b128 v[184:187], v150 offset:96
	ds_read_b128 v[188:191], v150 offset:4704
	s_waitcnt lgkmcnt(5)
	v_mfma_f32_32x32x16_bf16 v[80:95], v[160:163], v[208:211], v[80:95]
	v_mfma_f32_32x32x16_bf16 v[16:31], v[164:167], v[208:211], v[16:31]
	ds_read_b128 v[208:211], v149 offset:96
	s_waitcnt lgkmcnt(5)
	v_mfma_f32_32x32x16_bf16 v[64:79], v[160:163], v[212:215], v[64:79]
	v_mfma_f32_32x32x16_bf16 v[0:15], v[164:167], v[212:215], v[0:15]
	ds_read_b128 v[212:215], v149 offset:4704
	s_setprio 0
	global_load_dwordx4 v[160:163], v[144:145], off offset:2688
	global_load_dwordx4 v[164:167], v[146:147], off offset:2688
	s_setprio 1
	s_waitcnt lgkmcnt(1)
	v_mfma_f32_32x32x16_bf16 v[112:127], v[184:187], v[208:211], v[112:127]
	v_mfma_f32_32x32x16_bf16 v[48:63], v[188:191], v[208:211], v[48:63]
	s_waitcnt lgkmcnt(0)
	v_mfma_f32_32x32x16_bf16 v[96:111], v[184:187], v[212:215], v[96:111]
	v_mfma_f32_32x32x16_bf16 v[32:47], v[188:191], v[212:215], v[32:47]
	ds_read_b128 v[208:211], v149 offset:9312
	ds_read_b128 v[212:215], v149 offset:13920
	s_waitcnt lgkmcnt(0)
	s_barrier
; template <bool trans>
; DI void gemm_core(const GTile& tl, const GTile& nx, bool has_next  , bool chain  , bool pre, u32x4 (&ra)[4], u32x4 (&rb)[4], char* smem, f32x16 (&acc)[2][4]) {
;     ...
;   const int nk = K / 64;
;   if (!pre) { G_LOAD(0); G_STORE(0); G_LOAD(1); }
;   for (int kt = 0; kt < nk; ++kt) {
;     __syncthreads();
;     G_COMPUTE(kt & 1, kt);
;   }
	s_waitcnt vmcnt(7)
	ds_write_b128 v192, v[194:197]
	s_waitcnt vmcnt(6)
	ds_write_b128 v159, v[198:201]
	ds_read_b128 v[194:197], v152 offset:36864
	ds_read_b128 v[198:201], v152 offset:41472
	v_mfma_f32_32x32x16_bf16 v[80:95], v[184:187], v[208:211], v[80:95]
	v_mfma_f32_32x32x16_bf16 v[16:31], v[188:191], v[208:211], v[16:31]
	ds_read_b128 v[208:211], v151
	v_mfma_f32_32x32x16_bf16 v[64:79], v[184:187], v[212:215], v[64:79]
	v_mfma_f32_32x32x16_bf16 v[0:15], v[188:191], v[212:215], v[0:15]
	ds_read_b128 v[212:215], v151 offset:4608
	s_setprio 0
	global_load_dwordx4 v[184:187], v[136:137], off offset:2816
	global_load_dwordx4 v[188:191], v[138:139], off offset:2816
	s_setprio 1
	s_waitcnt lgkmcnt(1)
	v_mfma_f32_32x32x16_bf16 v[112:127], v[194:197], v[208:211], v[112:127]
	v_mfma_f32_32x32x16_bf16 v[48:63], v[198:201], v[208:211], v[48:63]
	s_waitcnt lgkmcnt(0)
	v_mfma_f32_32x32x16_bf16 v[96:111], v[194:197], v[212:215], v[96:111]
	v_mfma_f32_32x32x16_bf16 v[32:47], v[198:201], v[212:215], v[32:47]
	ds_read_b128 v[208:211], v151 offset:9216
	ds_read_b128 v[212:215], v151 offset:13824
	s_waitcnt vmcnt(7)
	ds_write_b128 v158, v[176:179]
	s_waitcnt vmcnt(6)
	ds_write_b128 v157, v[180:183]
	ds_read_b128 v[176:179], v152 offset:36896
	ds_read_b128 v[180:183], v152 offset:41504
	s_waitcnt lgkmcnt(5)
	v_mfma_f32_32x32x16_bf16 v[80:95], v[194:197], v[208:211], v[80:95]
	v_mfma_f32_32x32x16_bf16 v[16:31], v[198:201], v[208:211], v[16:31]
	ds_read_b128 v[208:211], v151 offset:32
	s_waitcnt lgkmcnt(5)
	v_mfma_f32_32x32x16_bf16 v[64:79], v[194:197], v[212:215], v[64:79]
	v_mfma_f32_32x32x16_bf16 v[0:15], v[198:201], v[212:215], v[0:15]
	ds_read_b128 v[212:215], v151 offset:4640
	s_setprio 0
	global_load_dwordx4 v[194:197], v[140:141], off offset:2816
	global_load_dwordx4 v[198:201], v[142:143], off offset:2816
	s_setprio 1
	s_waitcnt lgkmcnt(1)
	v_mfma_f32_32x32x16_bf16 v[112:127], v[176:179], v[208:211], v[112:127]
	v_mfma_f32_32x32x16_bf16 v[48:63], v[180:183], v[208:211], v[48:63]
	s_waitcnt lgkmcnt(0)
	v_mfma_f32_32x32x16_bf16 v[96:111], v[176:179], v[212:215], v[96:111]
	v_mfma_f32_32x32x16_bf16 v[32:47], v[180:183], v[212:215], v[32:47]
	ds_read_b128 v[208:211], v151 offset:9248
	ds_read_b128 v[212:215], v151 offset:13856
	s_waitcnt vmcnt(7)
	ds_write_b128 v154, v[168:171]
	s_waitcnt vmcnt(6)
	ds_write_b128 v153, v[172:175]
	ds_read_b128 v[168:171], v152 offset:36928
	ds_read_b128 v[172:175], v152 offset:41536
	s_waitcnt lgkmcnt(5)
	v_mfma_f32_32x32x16_bf16 v[80:95], v[176:179], v[208:211], v[80:95]
	v_mfma_f32_32x32x16_bf16 v[16:31], v[180:183], v[208:211], v[16:31]
	ds_read_b128 v[208:211], v151 offset:64
	s_waitcnt lgkmcnt(5)
	v_mfma_f32_32x32x16_bf16 v[64:79], v[176:179], v[212:215], v[64:79]
	v_mfma_f32_32x32x16_bf16 v[0:15], v[180:183], v[212:215], v[0:15]
	ds_read_b128 v[212:215], v151 offset:4672
	s_setprio 0
	global_load_dwordx4 v[176:179], v[132:133], off offset:2816
	global_load_dwordx4 v[180:183], v[134:135], off offset:2816
	s_setprio 1
	s_waitcnt lgkmcnt(1)
	v_mfma_f32_32x32x16_bf16 v[112:127], v[168:171], v[208:211], v[112:127]
	v_mfma_f32_32x32x16_bf16 v[48:63], v[172:175], v[208:211], v[48:63]
	s_waitcnt lgkmcnt(0)
	v_mfma_f32_32x32x16_bf16 v[96:111], v[168:171], v[212:215], v[96:111]
	v_mfma_f32_32x32x16_bf16 v[32:47], v[172:175], v[212:215], v[32:47]
	ds_read_b128 v[208:211], v151 offset:9280
	ds_read_b128 v[212:215], v151 offset:13888
	s_waitcnt vmcnt(7)
	ds_write_b128 v156, v[160:163]
	s_waitcnt vmcnt(6)
	ds_write_b128 v155, v[164:167]
	ds_read_b128 v[160:163], v152 offset:36960
	ds_read_b128 v[164:167], v152 offset:41568
	s_waitcnt lgkmcnt(5)
	v_mfma_f32_32x32x16_bf16 v[80:95], v[168:171], v[208:211], v[80:95]
	v_mfma_f32_32x32x16_bf16 v[16:31], v[172:175], v[208:211], v[16:31]
	ds_read_b128 v[208:211], v151 offset:96
	s_waitcnt lgkmcnt(5)
	v_mfma_f32_32x32x16_bf16 v[64:79], v[168:171], v[212:215], v[64:79]
	v_mfma_f32_32x32x16_bf16 v[0:15], v[172:175], v[212:215], v[0:15]
	ds_read_b128 v[212:215], v151 offset:4704
	s_setprio 0
	global_load_dwordx4 v[168:171], v[144:145], off offset:2816
	global_load_dwordx4 v[172:175], v[146:147], off offset:2816
	s_setprio 1
	s_waitcnt lgkmcnt(1)
	v_mfma_f32_32x32x16_bf16 v[112:127], v[160:163], v[208:211], v[112:127]
	v_mfma_f32_32x32x16_bf16 v[48:63], v[164:167], v[208:211], v[48:63]
	s_waitcnt lgkmcnt(0)
	v_mfma_f32_32x32x16_bf16 v[96:111], v[160:163], v[212:215], v[96:111]
	v_mfma_f32_32x32x16_bf16 v[32:47], v[164:167], v[212:215], v[32:47]
	ds_read_b128 v[208:211], v151 offset:9312
	ds_read_b128 v[212:215], v151 offset:13920
	s_waitcnt lgkmcnt(0)
	s_barrier
; template <bool trans>
; DI void gemm_core(const GTile& tl, const GTile& nx, bool has_next  , bool chain  , bool pre, u32x4 (&ra)[4], u32x4 (&rb)[4], char* smem, f32x16 (&acc)[2][4]) {
;     ...
;   const int nk = K / 64;
;   if (!pre) { G_LOAD(0); G_STORE(0); G_LOAD(1); }
;   for (int kt = 0; kt < nk; ++kt) {
;     __syncthreads();
;     G_COMPUTE(kt & 1, kt);
;   }
	s_waitcnt vmcnt(7)
	ds_write_b128 v148, v[184:187]
	s_waitcnt vmcnt(6)
	ds_write_b128 v148, v[188:191] offset:36864
	ds_read_b128 v[184:187], v150
	ds_read_b128 v[188:191], v150 offset:4608
	v_mfma_f32_32x32x16_bf16 v[80:95], v[160:163], v[208:211], v[80:95]
	v_mfma_f32_32x32x16_bf16 v[16:31], v[164:167], v[208:211], v[16:31]
	ds_read_b128 v[208:211], v149
	v_mfma_f32_32x32x16_bf16 v[64:79], v[160:163], v[212:215], v[64:79]
	v_mfma_f32_32x32x16_bf16 v[0:15], v[164:167], v[212:215], v[0:15]
	ds_read_b128 v[212:215], v149 offset:4608
	s_setprio 0
	global_load_dwordx4 v[160:163], v[136:137], off offset:2944
	global_load_dwordx4 v[164:167], v[138:139], off offset:2944
	s_setprio 1
	s_waitcnt lgkmcnt(1)
	v_mfma_f32_32x32x16_bf16 v[112:127], v[184:187], v[208:211], v[112:127]
	v_mfma_f32_32x32x16_bf16 v[48:63], v[188:191], v[208:211], v[48:63]
	s_waitcnt lgkmcnt(0)
	v_mfma_f32_32x32x16_bf16 v[96:111], v[184:187], v[212:215], v[96:111]
	v_mfma_f32_32x32x16_bf16 v[32:47], v[188:191], v[212:215], v[32:47]
	ds_read_b128 v[208:211], v149 offset:9216
	ds_read_b128 v[212:215], v149 offset:13824
	s_waitcnt vmcnt(7)
	ds_write_b128 v148, v[194:197] offset:9216
	s_waitcnt vmcnt(6)
	ds_write_b128 v148, v[198:201] offset:46080
	ds_read_b128 v[194:197], v150 offset:32
	ds_read_b128 v[198:201], v150 offset:4640
	s_waitcnt lgkmcnt(5)
	v_mfma_f32_32x32x16_bf16 v[80:95], v[184:187], v[208:211], v[80:95]
	v_mfma_f32_32x32x16_bf16 v[16:31], v[188:191], v[208:211], v[16:31]
	ds_read_b128 v[208:211], v149 offset:32
	s_waitcnt lgkmcnt(5)
	v_mfma_f32_32x32x16_bf16 v[64:79], v[184:187], v[212:215], v[64:79]
	v_mfma_f32_32x32x16_bf16 v[0:15], v[188:191], v[212:215], v[0:15]
	ds_read_b128 v[212:215], v149 offset:4640
	s_setprio 0
	global_load_dwordx4 v[184:187], v[140:141], off offset:2944
	global_load_dwordx4 v[188:191], v[142:143], off offset:2944
	s_setprio 1
	s_waitcnt lgkmcnt(1)
	v_mfma_f32_32x32x16_bf16 v[112:127], v[194:197], v[208:211], v[112:127]
	v_mfma_f32_32x32x16_bf16 v[48:63], v[198:201], v[208:211], v[48:63]
	s_waitcnt lgkmcnt(0)
	v_mfma_f32_32x32x16_bf16 v[96:111], v[194:197], v[212:215], v[96:111]
	v_mfma_f32_32x32x16_bf16 v[32:47], v[198:201], v[212:215], v[32:47]
	ds_read_b128 v[208:211], v149 offset:9248
	ds_read_b128 v[212:215], v149 offset:13856
	s_waitcnt vmcnt(7)
	ds_write_b128 v148, v[176:179] offset:18432
	s_waitcnt vmcnt(6)
	ds_write_b128 v148, v[180:183] offset:55296
	ds_read_b128 v[176:179], v150 offset:64
	ds_read_b128 v[180:183], v150 offset:4672
	s_waitcnt lgkmcnt(5)
	v_mfma_f32_32x32x16_bf16 v[80:95], v[194:197], v[208:211], v[80:95]
	v_mfma_f32_32x32x16_bf16 v[16:31], v[198:201], v[208:211], v[16:31]
	ds_read_b128 v[208:211], v149 offset:64
	s_waitcnt lgkmcnt(5)
	v_mfma_f32_32x32x16_bf16 v[64:79], v[194:197], v[212:215], v[64:79]
	v_mfma_f32_32x32x16_bf16 v[0:15], v[198:201], v[212:215], v[0:15]
	ds_read_b128 v[212:215], v149 offset:4672
	s_setprio 0
	global_load_dwordx4 v[194:197], v[132:133], off offset:2944
	global_load_dwordx4 v[198:201], v[134:135], off offset:2944
	s_setprio 1
	s_waitcnt lgkmcnt(1)
	v_mfma_f32_32x32x16_bf16 v[112:127], v[176:179], v[208:211], v[112:127]
	v_mfma_f32_32x32x16_bf16 v[48:63], v[180:183], v[208:211], v[48:63]
	s_waitcnt lgkmcnt(0)
	v_mfma_f32_32x32x16_bf16 v[96:111], v[176:179], v[212:215], v[96:111]
	v_mfma_f32_32x32x16_bf16 v[32:47], v[180:183], v[212:215], v[32:47]
	ds_read_b128 v[208:211], v149 offset:9280
	ds_read_b128 v[212:215], v149 offset:13888
	s_waitcnt vmcnt(7)
	ds_write_b128 v148, v[168:171] offset:27648
	s_waitcnt vmcnt(6)
	ds_write_b128 v148, v[172:175] offset:64512
	ds_read_b128 v[168:171], v150 offset:96
	ds_read_b128 v[172:175], v150 offset:4704
	s_waitcnt lgkmcnt(5)
	v_mfma_f32_32x32x16_bf16 v[80:95], v[176:179], v[208:211], v[80:95]
	v_mfma_f32_32x32x16_bf16 v[16:31], v[180:183], v[208:211], v[16:31]
	ds_read_b128 v[208:211], v149 offset:96
	s_waitcnt lgkmcnt(5)
	v_mfma_f32_32x32x16_bf16 v[64:79], v[176:179], v[212:215], v[64:79]
	v_mfma_f32_32x32x16_bf16 v[0:15], v[180:183], v[212:215], v[0:15]
	ds_read_b128 v[212:215], v149 offset:4704
	s_setprio 0
	global_load_dwordx4 v[176:179], v[144:145], off offset:2944
	global_load_dwordx4 v[180:183], v[146:147], off offset:2944
	s_setprio 1
	s_waitcnt lgkmcnt(1)
	v_mfma_f32_32x32x16_bf16 v[112:127], v[168:171], v[208:211], v[112:127]
	v_mfma_f32_32x32x16_bf16 v[48:63], v[172:175], v[208:211], v[48:63]
	s_waitcnt lgkmcnt(0)
	v_mfma_f32_32x32x16_bf16 v[96:111], v[168:171], v[212:215], v[96:111]
	v_mfma_f32_32x32x16_bf16 v[32:47], v[172:175], v[212:215], v[32:47]
	ds_read_b128 v[208:211], v149 offset:9312
	ds_read_b128 v[212:215], v149 offset:13920
	s_waitcnt lgkmcnt(0)
	s_barrier
; template <bool trans>
; DI void gemm_core(const GTile& tl, const GTile& nx, bool has_next  , bool chain  , bool pre, u32x4 (&ra)[4], u32x4 (&rb)[4], char* smem, f32x16 (&acc)[2][4]) {
;     ...
;   const int nk = K / 64;
;   if (!pre) { G_LOAD(0); G_STORE(0); G_LOAD(1); }
;   for (int kt = 0; kt < nk; ++kt) {
;     __syncthreads();
;     G_COMPUTE(kt & 1, kt);
;   }
	s_waitcnt vmcnt(7)
	ds_write_b128 v192, v[160:163]
	s_waitcnt vmcnt(6)
	ds_write_b128 v159, v[164:167]
	ds_read_b128 v[160:163], v152 offset:36864
	ds_read_b128 v[164:167], v152 offset:41472
	v_mfma_f32_32x32x16_bf16 v[80:95], v[168:171], v[208:211], v[80:95]
	v_mfma_f32_32x32x16_bf16 v[16:31], v[172:175], v[208:211], v[16:31]
	ds_read_b128 v[208:211], v151
	v_mfma_f32_32x32x16_bf16 v[64:79], v[168:171], v[212:215], v[64:79]
	v_mfma_f32_32x32x16_bf16 v[0:15], v[172:175], v[212:215], v[0:15]
	ds_read_b128 v[212:215], v151 offset:4608
	s_setprio 0
	global_load_dwordx4 v[168:171], v[136:137], off offset:3072
	global_load_dwordx4 v[172:175], v[138:139], off offset:3072
	s_setprio 1
	s_waitcnt lgkmcnt(1)
	v_mfma_f32_32x32x16_bf16 v[112:127], v[160:163], v[208:211], v[112:127]
	v_mfma_f32_32x32x16_bf16 v[48:63], v[164:167], v[208:211], v[48:63]
	s_waitcnt lgkmcnt(0)
	v_mfma_f32_32x32x16_bf16 v[96:111], v[160:163], v[212:215], v[96:111]
	v_mfma_f32_32x32x16_bf16 v[32:47], v[164:167], v[212:215], v[32:47]
	ds_read_b128 v[208:211], v151 offset:9216
	ds_read_b128 v[212:215], v151 offset:13824
	s_waitcnt vmcnt(7)
	ds_write_b128 v158, v[184:187]
	s_waitcnt vmcnt(6)
	ds_write_b128 v157, v[188:191]
	ds_read_b128 v[184:187], v152 offset:36896
	ds_read_b128 v[188:191], v152 offset:41504
	s_waitcnt lgkmcnt(5)
	v_mfma_f32_32x32x16_bf16 v[80:95], v[160:163], v[208:211], v[80:95]
	v_mfma_f32_32x32x16_bf16 v[16:31], v[164:167], v[208:211], v[16:31]
	ds_read_b128 v[208:211], v151 offset:32
	s_waitcnt lgkmcnt(5)
	v_mfma_f32_32x32x16_bf16 v[64:79], v[160:163], v[212:215], v[64:79]
	v_mfma_f32_32x32x16_bf16 v[0:15], v[164:167], v[212:215], v[0:15]
	ds_read_b128 v[212:215], v151 offset:4640
	s_setprio 0
	global_load_dwordx4 v[160:163], v[140:141], off offset:3072
	global_load_dwordx4 v[164:167], v[142:143], off offset:3072
	s_setprio 1
	s_waitcnt lgkmcnt(1)
	v_mfma_f32_32x32x16_bf16 v[112:127], v[184:187], v[208:211], v[112:127]
	v_mfma_f32_32x32x16_bf16 v[48:63], v[188:191], v[208:211], v[48:63]
	s_waitcnt lgkmcnt(0)
	v_mfma_f32_32x32x16_bf16 v[96:111], v[184:187], v[212:215], v[96:111]
	v_mfma_f32_32x32x16_bf16 v[32:47], v[188:191], v[212:215], v[32:47]
	ds_read_b128 v[208:211], v151 offset:9248
	ds_read_b128 v[212:215], v151 offset:13856
	s_waitcnt vmcnt(7)
	ds_write_b128 v154, v[194:197]
	s_waitcnt vmcnt(6)
	ds_write_b128 v153, v[198:201]
	ds_read_b128 v[194:197], v152 offset:36928
	ds_read_b128 v[198:201], v152 offset:41536
	s_waitcnt lgkmcnt(5)
	v_mfma_f32_32x32x16_bf16 v[80:95], v[184:187], v[208:211], v[80:95]
	v_mfma_f32_32x32x16_bf16 v[16:31], v[188:191], v[208:211], v[16:31]
	ds_read_b128 v[208:211], v151 offset:64
	s_waitcnt lgkmcnt(5)
	v_mfma_f32_32x32x16_bf16 v[64:79], v[184:187], v[212:215], v[64:79]
	v_mfma_f32_32x32x16_bf16 v[0:15], v[188:191], v[212:215], v[0:15]
	ds_read_b128 v[212:215], v151 offset:4672
	s_setprio 0
	global_load_dwordx4 v[184:187], v[132:133], off offset:3072
	global_load_dwordx4 v[188:191], v[134:135], off offset:3072
	s_setprio 1
	s_waitcnt lgkmcnt(1)
	v_mfma_f32_32x32x16_bf16 v[112:127], v[194:197], v[208:211], v[112:127]
	v_mfma_f32_32x32x16_bf16 v[48:63], v[198:201], v[208:211], v[48:63]
	s_waitcnt lgkmcnt(0)
	v_mfma_f32_32x32x16_bf16 v[96:111], v[194:197], v[212:215], v[96:111]
	v_mfma_f32_32x32x16_bf16 v[32:47], v[198:201], v[212:215], v[32:47]
	ds_read_b128 v[208:211], v151 offset:9280
	ds_read_b128 v[212:215], v151 offset:13888
	s_waitcnt vmcnt(7)
	ds_write_b128 v156, v[176:179]
	s_waitcnt vmcnt(6)
	ds_write_b128 v155, v[180:183]
	ds_read_b128 v[176:179], v152 offset:36960
	ds_read_b128 v[180:183], v152 offset:41568
	s_waitcnt lgkmcnt(5)
	v_mfma_f32_32x32x16_bf16 v[80:95], v[194:197], v[208:211], v[80:95]
	v_mfma_f32_32x32x16_bf16 v[16:31], v[198:201], v[208:211], v[16:31]
	ds_read_b128 v[208:211], v151 offset:96
	s_waitcnt lgkmcnt(5)
	v_mfma_f32_32x32x16_bf16 v[64:79], v[194:197], v[212:215], v[64:79]
	v_mfma_f32_32x32x16_bf16 v[0:15], v[198:201], v[212:215], v[0:15]
	ds_read_b128 v[212:215], v151 offset:4704
	s_setprio 0
	global_load_dwordx4 v[194:197], v[144:145], off offset:3072
	global_load_dwordx4 v[198:201], v[146:147], off offset:3072
	s_setprio 1
	s_waitcnt lgkmcnt(1)
	v_mfma_f32_32x32x16_bf16 v[112:127], v[176:179], v[208:211], v[112:127]
	v_mfma_f32_32x32x16_bf16 v[48:63], v[180:183], v[208:211], v[48:63]
	s_waitcnt lgkmcnt(0)
	v_mfma_f32_32x32x16_bf16 v[96:111], v[176:179], v[212:215], v[96:111]
	v_mfma_f32_32x32x16_bf16 v[32:47], v[180:183], v[212:215], v[32:47]
	ds_read_b128 v[208:211], v151 offset:9312
	ds_read_b128 v[212:215], v151 offset:13920
	s_waitcnt lgkmcnt(0)
	s_barrier
; template <bool trans>
; DI void gemm_core(const GTile& tl, const GTile& nx, bool has_next  , bool chain  , bool pre, u32x4 (&ra)[4], u32x4 (&rb)[4], char* smem, f32x16 (&acc)[2][4]) {
;     ...
;   const int nk = K / 64;
;   if (!pre) { G_LOAD(0); G_STORE(0); G_LOAD(1); }
;   for (int kt = 0; kt < nk; ++kt) {
;     __syncthreads();
;     G_COMPUTE(kt & 1, kt);
;   }
	s_waitcnt vmcnt(7)
	ds_write_b128 v148, v[168:171]
	s_waitcnt vmcnt(6)
	ds_write_b128 v148, v[172:175] offset:36864
	ds_read_b128 v[168:171], v150
	ds_read_b128 v[172:175], v150 offset:4608
	v_mfma_f32_32x32x16_bf16 v[80:95], v[176:179], v[208:211], v[80:95]
	v_mfma_f32_32x32x16_bf16 v[16:31], v[180:183], v[208:211], v[16:31]
	ds_read_b128 v[208:211], v149
	v_mfma_f32_32x32x16_bf16 v[64:79], v[176:179], v[212:215], v[64:79]
	v_mfma_f32_32x32x16_bf16 v[0:15], v[180:183], v[212:215], v[0:15]
	ds_read_b128 v[212:215], v149 offset:4608
	s_setprio 0
	global_load_dwordx4 v[176:179], v[136:137], off offset:3200
	global_load_dwordx4 v[180:183], v[138:139], off offset:3200
	s_setprio 1
	s_waitcnt lgkmcnt(1)
	v_mfma_f32_32x32x16_bf16 v[112:127], v[168:171], v[208:211], v[112:127]
	v_mfma_f32_32x32x16_bf16 v[48:63], v[172:175], v[208:211], v[48:63]
	s_waitcnt lgkmcnt(0)
	v_mfma_f32_32x32x16_bf16 v[96:111], v[168:171], v[212:215], v[96:111]
	v_mfma_f32_32x32x16_bf16 v[32:47], v[172:175], v[212:215], v[32:47]
	ds_read_b128 v[208:211], v149 offset:9216
	ds_read_b128 v[212:215], v149 offset:13824
	s_waitcnt vmcnt(7)
	ds_write_b128 v148, v[160:163] offset:9216
	s_waitcnt vmcnt(6)
	ds_write_b128 v148, v[164:167] offset:46080
	ds_read_b128 v[160:163], v150 offset:32
	ds_read_b128 v[164:167], v150 offset:4640
	s_waitcnt lgkmcnt(5)
	v_mfma_f32_32x32x16_bf16 v[80:95], v[168:171], v[208:211], v[80:95]
	v_mfma_f32_32x32x16_bf16 v[16:31], v[172:175], v[208:211], v[16:31]
	ds_read_b128 v[208:211], v149 offset:32
	s_waitcnt lgkmcnt(5)
	v_mfma_f32_32x32x16_bf16 v[64:79], v[168:171], v[212:215], v[64:79]
	v_mfma_f32_32x32x16_bf16 v[0:15], v[172:175], v[212:215], v[0:15]
	ds_read_b128 v[212:215], v149 offset:4640
	s_setprio 0
	global_load_dwordx4 v[168:171], v[140:141], off offset:3200
	global_load_dwordx4 v[172:175], v[142:143], off offset:3200
	s_setprio 1
	s_waitcnt lgkmcnt(1)
	v_mfma_f32_32x32x16_bf16 v[112:127], v[160:163], v[208:211], v[112:127]
	v_mfma_f32_32x32x16_bf16 v[48:63], v[164:167], v[208:211], v[48:63]
	s_waitcnt lgkmcnt(0)
	v_mfma_f32_32x32x16_bf16 v[96:111], v[160:163], v[212:215], v[96:111]
	v_mfma_f32_32x32x16_bf16 v[32:47], v[164:167], v[212:215], v[32:47]
	ds_read_b128 v[208:211], v149 offset:9248
	ds_read_b128 v[212:215], v149 offset:13856
	s_waitcnt vmcnt(7)
	ds_write_b128 v148, v[184:187] offset:18432
	s_waitcnt vmcnt(6)
	ds_write_b128 v148, v[188:191] offset:55296
	ds_read_b128 v[184:187], v150 offset:64
	ds_read_b128 v[188:191], v150 offset:4672
	s_waitcnt lgkmcnt(5)
	v_mfma_f32_32x32x16_bf16 v[80:95], v[160:163], v[208:211], v[80:95]
	v_mfma_f32_32x32x16_bf16 v[16:31], v[164:167], v[208:211], v[16:31]
	ds_read_b128 v[208:211], v149 offset:64
	s_waitcnt lgkmcnt(5)
	v_mfma_f32_32x32x16_bf16 v[64:79], v[160:163], v[212:215], v[64:79]
	v_mfma_f32_32x32x16_bf16 v[0:15], v[164:167], v[212:215], v[0:15]
	ds_read_b128 v[212:215], v149 offset:4672
	s_setprio 0
	global_load_dwordx4 v[160:163], v[132:133], off offset:3200
	global_load_dwordx4 v[164:167], v[134:135], off offset:3200
	s_setprio 1
	s_waitcnt lgkmcnt(1)
	v_mfma_f32_32x32x16_bf16 v[112:127], v[184:187], v[208:211], v[112:127]
	v_mfma_f32_32x32x16_bf16 v[48:63], v[188:191], v[208:211], v[48:63]
	s_waitcnt lgkmcnt(0)
	v_mfma_f32_32x32x16_bf16 v[96:111], v[184:187], v[212:215], v[96:111]
	v_mfma_f32_32x32x16_bf16 v[32:47], v[188:191], v[212:215], v[32:47]
	ds_read_b128 v[208:211], v149 offset:9280
	ds_read_b128 v[212:215], v149 offset:13888
	s_waitcnt vmcnt(7)
	ds_write_b128 v148, v[194:197] offset:27648
	s_waitcnt vmcnt(6)
	ds_write_b128 v148, v[198:201] offset:64512
	ds_read_b128 v[194:197], v150 offset:96
	ds_read_b128 v[198:201], v150 offset:4704
	s_waitcnt lgkmcnt(5)
	v_mfma_f32_32x32x16_bf16 v[80:95], v[184:187], v[208:211], v[80:95]
	v_mfma_f32_32x32x16_bf16 v[16:31], v[188:191], v[208:211], v[16:31]
	ds_read_b128 v[208:211], v149 offset:96
	s_waitcnt lgkmcnt(5)
	v_mfma_f32_32x32x16_bf16 v[64:79], v[184:187], v[212:215], v[64:79]
	v_mfma_f32_32x32x16_bf16 v[0:15], v[188:191], v[212:215], v[0:15]
	ds_read_b128 v[212:215], v149 offset:4704
	s_setprio 0
	global_load_dwordx4 v[184:187], v[144:145], off offset:3200
	global_load_dwordx4 v[188:191], v[146:147], off offset:3200
	s_setprio 1
	s_waitcnt lgkmcnt(1)
	v_mfma_f32_32x32x16_bf16 v[112:127], v[194:197], v[208:211], v[112:127]
	v_mfma_f32_32x32x16_bf16 v[48:63], v[198:201], v[208:211], v[48:63]
	s_waitcnt lgkmcnt(0)
	v_mfma_f32_32x32x16_bf16 v[96:111], v[194:197], v[212:215], v[96:111]
	v_mfma_f32_32x32x16_bf16 v[32:47], v[198:201], v[212:215], v[32:47]
	ds_read_b128 v[208:211], v149 offset:9312
	ds_read_b128 v[212:215], v149 offset:13920
	s_waitcnt lgkmcnt(0)
	s_barrier
; template <bool trans>
; DI void gemm_core(const GTile& tl, const GTile& nx, bool has_next  , bool chain  , bool pre, u32x4 (&ra)[4], u32x4 (&rb)[4], char* smem, f32x16 (&acc)[2][4]) {
;     ...
;   const int nk = K / 64;
;   if (!pre) { G_LOAD(0); G_STORE(0); G_LOAD(1); }
;   for (int kt = 0; kt < nk; ++kt) {
;     __syncthreads();
;     G_COMPUTE(kt & 1, kt);
;   }
	s_waitcnt vmcnt(7)
	ds_write_b128 v192, v[176:179]
	s_waitcnt vmcnt(6)
	ds_write_b128 v159, v[180:183]
	ds_read_b128 v[176:179], v152 offset:36864
	ds_read_b128 v[180:183], v152 offset:41472
	v_mfma_f32_32x32x16_bf16 v[80:95], v[194:197], v[208:211], v[80:95]
	v_mfma_f32_32x32x16_bf16 v[16:31], v[198:201], v[208:211], v[16:31]
	ds_read_b128 v[208:211], v151
	v_mfma_f32_32x32x16_bf16 v[64:79], v[194:197], v[212:215], v[64:79]
	v_mfma_f32_32x32x16_bf16 v[0:15], v[198:201], v[212:215], v[0:15]
	ds_read_b128 v[212:215], v151 offset:4608
	s_setprio 0
	global_load_dwordx4 v[194:197], v[136:137], off offset:3328
	global_load_dwordx4 v[198:201], v[138:139], off offset:3328
	s_setprio 1
	s_waitcnt lgkmcnt(1)
	v_mfma_f32_32x32x16_bf16 v[112:127], v[176:179], v[208:211], v[112:127]
	v_mfma_f32_32x32x16_bf16 v[48:63], v[180:183], v[208:211], v[48:63]
	s_waitcnt lgkmcnt(0)
	v_mfma_f32_32x32x16_bf16 v[96:111], v[176:179], v[212:215], v[96:111]
	v_mfma_f32_32x32x16_bf16 v[32:47], v[180:183], v[212:215], v[32:47]
	ds_read_b128 v[208:211], v151 offset:9216
	ds_read_b128 v[212:215], v151 offset:13824
	s_waitcnt vmcnt(7)
	ds_write_b128 v158, v[168:171]
	s_waitcnt vmcnt(6)
	ds_write_b128 v157, v[172:175]
	ds_read_b128 v[168:171], v152 offset:36896
	ds_read_b128 v[172:175], v152 offset:41504
	s_waitcnt lgkmcnt(5)
	v_mfma_f32_32x32x16_bf16 v[80:95], v[176:179], v[208:211], v[80:95]
	v_mfma_f32_32x32x16_bf16 v[16:31], v[180:183], v[208:211], v[16:31]
	ds_read_b128 v[208:211], v151 offset:32
	s_waitcnt lgkmcnt(5)
	v_mfma_f32_32x32x16_bf16 v[64:79], v[176:179], v[212:215], v[64:79]
	v_mfma_f32_32x32x16_bf16 v[0:15], v[180:183], v[212:215], v[0:15]
	ds_read_b128 v[212:215], v151 offset:4640
	s_setprio 0
	global_load_dwordx4 v[176:179], v[140:141], off offset:3328
	global_load_dwordx4 v[180:183], v[142:143], off offset:3328
	s_setprio 1
	s_waitcnt lgkmcnt(1)
	v_mfma_f32_32x32x16_bf16 v[112:127], v[168:171], v[208:211], v[112:127]
	v_mfma_f32_32x32x16_bf16 v[48:63], v[172:175], v[208:211], v[48:63]
	s_waitcnt lgkmcnt(0)
	v_mfma_f32_32x32x16_bf16 v[96:111], v[168:171], v[212:215], v[96:111]
	v_mfma_f32_32x32x16_bf16 v[32:47], v[172:175], v[212:215], v[32:47]
	ds_read_b128 v[208:211], v151 offset:9248
	ds_read_b128 v[212:215], v151 offset:13856
	s_waitcnt vmcnt(7)
	ds_write_b128 v154, v[160:163]
	s_waitcnt vmcnt(6)
	ds_write_b128 v153, v[164:167]
	ds_read_b128 v[160:163], v152 offset:36928
	ds_read_b128 v[164:167], v152 offset:41536
	s_waitcnt lgkmcnt(5)
	v_mfma_f32_32x32x16_bf16 v[80:95], v[168:171], v[208:211], v[80:95]
	v_mfma_f32_32x32x16_bf16 v[16:31], v[172:175], v[208:211], v[16:31]
	ds_read_b128 v[208:211], v151 offset:64
	s_waitcnt lgkmcnt(5)
	v_mfma_f32_32x32x16_bf16 v[64:79], v[168:171], v[212:215], v[64:79]
	v_mfma_f32_32x32x16_bf16 v[0:15], v[172:175], v[212:215], v[0:15]
	ds_read_b128 v[212:215], v151 offset:4672
	s_setprio 0
	global_load_dwordx4 v[168:171], v[132:133], off offset:3328
	global_load_dwordx4 v[172:175], v[134:135], off offset:3328
	s_setprio 1
	s_waitcnt lgkmcnt(1)
	v_mfma_f32_32x32x16_bf16 v[112:127], v[160:163], v[208:211], v[112:127]
	v_mfma_f32_32x32x16_bf16 v[48:63], v[164:167], v[208:211], v[48:63]
	s_waitcnt lgkmcnt(0)
	v_mfma_f32_32x32x16_bf16 v[96:111], v[160:163], v[212:215], v[96:111]
	v_mfma_f32_32x32x16_bf16 v[32:47], v[164:167], v[212:215], v[32:47]
	ds_read_b128 v[208:211], v151 offset:9280
	ds_read_b128 v[212:215], v151 offset:13888
	s_waitcnt vmcnt(7)
	ds_write_b128 v156, v[184:187]
	s_waitcnt vmcnt(6)
	ds_write_b128 v155, v[188:191]
	ds_read_b128 v[184:187], v152 offset:36960
	ds_read_b128 v[188:191], v152 offset:41568
	s_waitcnt lgkmcnt(5)
	v_mfma_f32_32x32x16_bf16 v[80:95], v[160:163], v[208:211], v[80:95]
	v_mfma_f32_32x32x16_bf16 v[16:31], v[164:167], v[208:211], v[16:31]
	ds_read_b128 v[208:211], v151 offset:96
	s_waitcnt lgkmcnt(5)
	v_mfma_f32_32x32x16_bf16 v[64:79], v[160:163], v[212:215], v[64:79]
	v_mfma_f32_32x32x16_bf16 v[0:15], v[164:167], v[212:215], v[0:15]
	ds_read_b128 v[212:215], v151 offset:4704
	s_setprio 0
	global_load_dwordx4 v[160:163], v[144:145], off offset:3328
	global_load_dwordx4 v[164:167], v[146:147], off offset:3328
	s_setprio 1
	s_waitcnt lgkmcnt(1)
	v_mfma_f32_32x32x16_bf16 v[112:127], v[184:187], v[208:211], v[112:127]
	v_mfma_f32_32x32x16_bf16 v[48:63], v[188:191], v[208:211], v[48:63]
	s_waitcnt lgkmcnt(0)
	v_mfma_f32_32x32x16_bf16 v[96:111], v[184:187], v[212:215], v[96:111]
	v_mfma_f32_32x32x16_bf16 v[32:47], v[188:191], v[212:215], v[32:47]
	ds_read_b128 v[208:211], v151 offset:9312
	ds_read_b128 v[212:215], v151 offset:13920
	s_waitcnt lgkmcnt(0)
	s_barrier
; template <bool trans>
; DI void gemm_core(const GTile& tl, const GTile& nx, bool has_next  , bool chain  , bool pre, u32x4 (&ra)[4], u32x4 (&rb)[4], char* smem, f32x16 (&acc)[2][4]) {
;     ...
;   const int nk = K / 64;
;   if (!pre) { G_LOAD(0); G_STORE(0); G_LOAD(1); }
;   for (int kt = 0; kt < nk; ++kt) {
;     __syncthreads();
;     G_COMPUTE(kt & 1, kt);
;   }
	s_waitcnt vmcnt(7)
	ds_write_b128 v148, v[194:197]
	s_waitcnt vmcnt(6)
	ds_write_b128 v148, v[198:201] offset:36864
	ds_read_b128 v[194:197], v150
	ds_read_b128 v[198:201], v150 offset:4608
	v_mfma_f32_32x32x16_bf16 v[80:95], v[184:187], v[208:211], v[80:95]
	v_mfma_f32_32x32x16_bf16 v[16:31], v[188:191], v[208:211], v[16:31]
	ds_read_b128 v[208:211], v149
	v_mfma_f32_32x32x16_bf16 v[64:79], v[184:187], v[212:215], v[64:79]
	v_mfma_f32_32x32x16_bf16 v[0:15], v[188:191], v[212:215], v[0:15]
	ds_read_b128 v[212:215], v149 offset:4608
	s_setprio 0
	global_load_dwordx4 v[184:187], v[136:137], off offset:3456
	global_load_dwordx4 v[188:191], v[138:139], off offset:3456
	s_setprio 1
	s_waitcnt lgkmcnt(1)
	v_mfma_f32_32x32x16_bf16 v[112:127], v[194:197], v[208:211], v[112:127]
	v_mfma_f32_32x32x16_bf16 v[48:63], v[198:201], v[208:211], v[48:63]
	s_waitcnt lgkmcnt(0)
	v_mfma_f32_32x32x16_bf16 v[96:111], v[194:197], v[212:215], v[96:111]
	v_mfma_f32_32x32x16_bf16 v[32:47], v[198:201], v[212:215], v[32:47]
	ds_read_b128 v[208:211], v149 offset:9216
	ds_read_b128 v[212:215], v149 offset:13824
	s_waitcnt vmcnt(7)
	ds_write_b128 v148, v[176:179] offset:9216
	s_waitcnt vmcnt(6)
	ds_write_b128 v148, v[180:183] offset:46080
	ds_read_b128 v[176:179], v150 offset:32
	ds_read_b128 v[180:183], v150 offset:4640
	s_waitcnt lgkmcnt(5)
	v_mfma_f32_32x32x16_bf16 v[80:95], v[194:197], v[208:211], v[80:95]
	v_mfma_f32_32x32x16_bf16 v[16:31], v[198:201], v[208:211], v[16:31]
	ds_read_b128 v[208:211], v149 offset:32
	s_waitcnt lgkmcnt(5)
	v_mfma_f32_32x32x16_bf16 v[64:79], v[194:197], v[212:215], v[64:79]
	v_mfma_f32_32x32x16_bf16 v[0:15], v[198:201], v[212:215], v[0:15]
	ds_read_b128 v[212:215], v149 offset:4640
	s_setprio 0
	global_load_dwordx4 v[194:197], v[140:141], off offset:3456
	global_load_dwordx4 v[198:201], v[142:143], off offset:3456
	s_setprio 1
	s_waitcnt lgkmcnt(1)
	v_mfma_f32_32x32x16_bf16 v[112:127], v[176:179], v[208:211], v[112:127]
	v_mfma_f32_32x32x16_bf16 v[48:63], v[180:183], v[208:211], v[48:63]
	s_waitcnt lgkmcnt(0)
	v_mfma_f32_32x32x16_bf16 v[96:111], v[176:179], v[212:215], v[96:111]
	v_mfma_f32_32x32x16_bf16 v[32:47], v[180:183], v[212:215], v[32:47]
	ds_read_b128 v[208:211], v149 offset:9248
	ds_read_b128 v[212:215], v149 offset:13856
	s_waitcnt vmcnt(7)
	ds_write_b128 v148, v[168:171] offset:18432
	s_waitcnt vmcnt(6)
	ds_write_b128 v148, v[172:175] offset:55296
	ds_read_b128 v[168:171], v150 offset:64
	ds_read_b128 v[172:175], v150 offset:4672
	s_waitcnt lgkmcnt(5)
	v_mfma_f32_32x32x16_bf16 v[80:95], v[176:179], v[208:211], v[80:95]
	v_mfma_f32_32x32x16_bf16 v[16:31], v[180:183], v[208:211], v[16:31]
	ds_read_b128 v[208:211], v149 offset:64
	s_waitcnt lgkmcnt(5)
	v_mfma_f32_32x32x16_bf16 v[64:79], v[176:179], v[212:215], v[64:79]
	v_mfma_f32_32x32x16_bf16 v[0:15], v[180:183], v[212:215], v[0:15]
	ds_read_b128 v[212:215], v149 offset:4672
	s_setprio 0
	global_load_dwordx4 v[176:179], v[132:133], off offset:3456
	global_load_dwordx4 v[180:183], v[134:135], off offset:3456
	s_setprio 1
	s_waitcnt lgkmcnt(1)
	v_mfma_f32_32x32x16_bf16 v[112:127], v[168:171], v[208:211], v[112:127]
	v_mfma_f32_32x32x16_bf16 v[48:63], v[172:175], v[208:211], v[48:63]
	s_waitcnt lgkmcnt(0)
	v_mfma_f32_32x32x16_bf16 v[96:111], v[168:171], v[212:215], v[96:111]
	v_mfma_f32_32x32x16_bf16 v[32:47], v[172:175], v[212:215], v[32:47]
	ds_read_b128 v[208:211], v149 offset:9280
	ds_read_b128 v[212:215], v149 offset:13888
	s_waitcnt vmcnt(7)
	ds_write_b128 v148, v[160:163] offset:27648
	s_waitcnt vmcnt(6)
	ds_write_b128 v148, v[164:167] offset:64512
	ds_read_b128 v[160:163], v150 offset:96
	ds_read_b128 v[164:167], v150 offset:4704
	s_waitcnt lgkmcnt(5)
	v_mfma_f32_32x32x16_bf16 v[80:95], v[168:171], v[208:211], v[80:95]
	v_mfma_f32_32x32x16_bf16 v[16:31], v[172:175], v[208:211], v[16:31]
	ds_read_b128 v[208:211], v149 offset:96
	s_waitcnt lgkmcnt(5)
	v_mfma_f32_32x32x16_bf16 v[64:79], v[168:171], v[212:215], v[64:79]
	v_mfma_f32_32x32x16_bf16 v[0:15], v[172:175], v[212:215], v[0:15]
	ds_read_b128 v[212:215], v149 offset:4704
	s_setprio 0
	global_load_dwordx4 v[168:171], v[144:145], off offset:3456
	global_load_dwordx4 v[172:175], v[146:147], off offset:3456
	s_setprio 1
	s_waitcnt lgkmcnt(1)
	v_mfma_f32_32x32x16_bf16 v[112:127], v[160:163], v[208:211], v[112:127]
	v_mfma_f32_32x32x16_bf16 v[48:63], v[164:167], v[208:211], v[48:63]
	s_waitcnt lgkmcnt(0)
	v_mfma_f32_32x32x16_bf16 v[96:111], v[160:163], v[212:215], v[96:111]
	v_mfma_f32_32x32x16_bf16 v[32:47], v[164:167], v[212:215], v[32:47]
	ds_read_b128 v[208:211], v149 offset:9312
	ds_read_b128 v[212:215], v149 offset:13920
	s_waitcnt lgkmcnt(0)
	s_barrier
; template <bool trans>
; DI void gemm_core(const GTile& tl, const GTile& nx, bool has_next  , bool chain  , bool pre, u32x4 (&ra)[4], u32x4 (&rb)[4], char* smem, f32x16 (&acc)[2][4]) {
;     ...
;   const int nk = K / 64;
;   if (!pre) { G_LOAD(0); G_STORE(0); G_LOAD(1); }
;   for (int kt = 0; kt < nk; ++kt) {
;     __syncthreads();
;     G_COMPUTE(kt & 1, kt);
;   }
	s_waitcnt vmcnt(7)
	ds_write_b128 v192, v[184:187]
	s_waitcnt vmcnt(6)
	ds_write_b128 v159, v[188:191]
	ds_read_b128 v[184:187], v152 offset:36864
	ds_read_b128 v[188:191], v152 offset:41472
	v_mfma_f32_32x32x16_bf16 v[80:95], v[160:163], v[208:211], v[80:95]
	v_mfma_f32_32x32x16_bf16 v[16:31], v[164:167], v[208:211], v[16:31]
	ds_read_b128 v[208:211], v151
	v_mfma_f32_32x32x16_bf16 v[64:79], v[160:163], v[212:215], v[64:79]
	v_mfma_f32_32x32x16_bf16 v[0:15], v[164:167], v[212:215], v[0:15]
	ds_read_b128 v[212:215], v151 offset:4608
	s_setprio 0
	global_load_dwordx4 v[160:163], v[136:137], off offset:3584
	global_load_dwordx4 v[164:167], v[138:139], off offset:3584
	s_setprio 1
	s_waitcnt lgkmcnt(1)
	v_mfma_f32_32x32x16_bf16 v[112:127], v[184:187], v[208:211], v[112:127]
	v_mfma_f32_32x32x16_bf16 v[48:63], v[188:191], v[208:211], v[48:63]
	s_waitcnt lgkmcnt(0)
	v_mfma_f32_32x32x16_bf16 v[96:111], v[184:187], v[212:215], v[96:111]
	v_mfma_f32_32x32x16_bf16 v[32:47], v[188:191], v[212:215], v[32:47]
	ds_read_b128 v[208:211], v151 offset:9216
	ds_read_b128 v[212:215], v151 offset:13824
	s_waitcnt vmcnt(7)
	ds_write_b128 v158, v[194:197]
	s_waitcnt vmcnt(6)
	ds_write_b128 v157, v[198:201]
	ds_read_b128 v[194:197], v152 offset:36896
	ds_read_b128 v[198:201], v152 offset:41504
	s_waitcnt lgkmcnt(5)
	v_mfma_f32_32x32x16_bf16 v[80:95], v[184:187], v[208:211], v[80:95]
	v_mfma_f32_32x32x16_bf16 v[16:31], v[188:191], v[208:211], v[16:31]
	ds_read_b128 v[208:211], v151 offset:32
	s_waitcnt lgkmcnt(5)
	v_mfma_f32_32x32x16_bf16 v[64:79], v[184:187], v[212:215], v[64:79]
	v_mfma_f32_32x32x16_bf16 v[0:15], v[188:191], v[212:215], v[0:15]
	ds_read_b128 v[212:215], v151 offset:4640
	s_setprio 0
	global_load_dwordx4 v[184:187], v[140:141], off offset:3584
	global_load_dwordx4 v[188:191], v[142:143], off offset:3584
	s_setprio 1
	s_waitcnt lgkmcnt(1)
	v_mfma_f32_32x32x16_bf16 v[112:127], v[194:197], v[208:211], v[112:127]
	v_mfma_f32_32x32x16_bf16 v[48:63], v[198:201], v[208:211], v[48:63]
	s_waitcnt lgkmcnt(0)
	v_mfma_f32_32x32x16_bf16 v[96:111], v[194:197], v[212:215], v[96:111]
	v_mfma_f32_32x32x16_bf16 v[32:47], v[198:201], v[212:215], v[32:47]
	ds_read_b128 v[208:211], v151 offset:9248
	ds_read_b128 v[212:215], v151 offset:13856
	s_waitcnt vmcnt(7)
	ds_write_b128 v154, v[176:179]
	s_waitcnt vmcnt(6)
	ds_write_b128 v153, v[180:183]
	ds_read_b128 v[176:179], v152 offset:36928
	ds_read_b128 v[180:183], v152 offset:41536
	s_waitcnt lgkmcnt(5)
	v_mfma_f32_32x32x16_bf16 v[80:95], v[194:197], v[208:211], v[80:95]
	v_mfma_f32_32x32x16_bf16 v[16:31], v[198:201], v[208:211], v[16:31]
	ds_read_b128 v[208:211], v151 offset:64
	s_waitcnt lgkmcnt(5)
	v_mfma_f32_32x32x16_bf16 v[64:79], v[194:197], v[212:215], v[64:79]
	v_mfma_f32_32x32x16_bf16 v[0:15], v[198:201], v[212:215], v[0:15]
	ds_read_b128 v[212:215], v151 offset:4672
	s_setprio 0
	global_load_dwordx4 v[194:197], v[132:133], off offset:3584
	global_load_dwordx4 v[198:201], v[134:135], off offset:3584
	s_setprio 1
	s_waitcnt lgkmcnt(1)
	v_mfma_f32_32x32x16_bf16 v[112:127], v[176:179], v[208:211], v[112:127]
	v_mfma_f32_32x32x16_bf16 v[48:63], v[180:183], v[208:211], v[48:63]
	s_waitcnt lgkmcnt(0)
	v_mfma_f32_32x32x16_bf16 v[96:111], v[176:179], v[212:215], v[96:111]
	v_mfma_f32_32x32x16_bf16 v[32:47], v[180:183], v[212:215], v[32:47]
	ds_read_b128 v[208:211], v151 offset:9280
	ds_read_b128 v[212:215], v151 offset:13888
	s_waitcnt vmcnt(7)
	ds_write_b128 v156, v[168:171]
	s_waitcnt vmcnt(6)
	ds_write_b128 v155, v[172:175]
	ds_read_b128 v[168:171], v152 offset:36960
	ds_read_b128 v[172:175], v152 offset:41568
	s_waitcnt lgkmcnt(5)
	v_mfma_f32_32x32x16_bf16 v[80:95], v[176:179], v[208:211], v[80:95]
	v_mfma_f32_32x32x16_bf16 v[16:31], v[180:183], v[208:211], v[16:31]
	ds_read_b128 v[208:211], v151 offset:96
	s_waitcnt lgkmcnt(5)
	v_mfma_f32_32x32x16_bf16 v[64:79], v[176:179], v[212:215], v[64:79]
	v_mfma_f32_32x32x16_bf16 v[0:15], v[180:183], v[212:215], v[0:15]
	ds_read_b128 v[212:215], v151 offset:4704
	s_setprio 0
	global_load_dwordx4 v[176:179], v[144:145], off offset:3584
	global_load_dwordx4 v[180:183], v[146:147], off offset:3584
	s_setprio 1
	s_waitcnt lgkmcnt(1)
	v_mfma_f32_32x32x16_bf16 v[112:127], v[168:171], v[208:211], v[112:127]
	v_mfma_f32_32x32x16_bf16 v[48:63], v[172:175], v[208:211], v[48:63]
	s_waitcnt lgkmcnt(0)
	v_mfma_f32_32x32x16_bf16 v[96:111], v[168:171], v[212:215], v[96:111]
	v_mfma_f32_32x32x16_bf16 v[32:47], v[172:175], v[212:215], v[32:47]
	ds_read_b128 v[208:211], v151 offset:9312
	ds_read_b128 v[212:215], v151 offset:13920
	s_waitcnt lgkmcnt(0)
	s_barrier
; template <bool trans>
; DI void gemm_core(const GTile& tl, const GTile& nx, bool has_next  , bool chain  , bool pre, u32x4 (&ra)[4], u32x4 (&rb)[4], char* smem, f32x16 (&acc)[2][4]) {
;     ...
;   const int nk = K / 64;
;   if (!pre) { G_LOAD(0); G_STORE(0); G_LOAD(1); }
;   for (int kt = 0; kt < nk; ++kt) {
;     __syncthreads();
;     G_COMPUTE(kt & 1, kt);
;   }
	s_waitcnt vmcnt(7)
	ds_write_b128 v148, v[160:163]
	s_waitcnt vmcnt(6)
	ds_write_b128 v148, v[164:167] offset:36864
	ds_read_b128 v[160:163], v150
	ds_read_b128 v[164:167], v150 offset:4608
	v_mfma_f32_32x32x16_bf16 v[80:95], v[168:171], v[208:211], v[80:95]
	v_mfma_f32_32x32x16_bf16 v[16:31], v[172:175], v[208:211], v[16:31]
	ds_read_b128 v[208:211], v149
	v_mfma_f32_32x32x16_bf16 v[64:79], v[168:171], v[212:215], v[64:79]
	v_mfma_f32_32x32x16_bf16 v[0:15], v[172:175], v[212:215], v[0:15]
	ds_read_b128 v[212:215], v149 offset:4608
	s_setprio 0
	global_load_dwordx4 v[168:171], v[136:137], off offset:3712
	global_load_dwordx4 v[172:175], v[138:139], off offset:3712
	s_setprio 1
	s_waitcnt lgkmcnt(1)
	v_mfma_f32_32x32x16_bf16 v[112:127], v[160:163], v[208:211], v[112:127]
	v_mfma_f32_32x32x16_bf16 v[48:63], v[164:167], v[208:211], v[48:63]
	s_waitcnt lgkmcnt(0)
	v_mfma_f32_32x32x16_bf16 v[96:111], v[160:163], v[212:215], v[96:111]
	v_mfma_f32_32x32x16_bf16 v[32:47], v[164:167], v[212:215], v[32:47]
	ds_read_b128 v[208:211], v149 offset:9216
	ds_read_b128 v[212:215], v149 offset:13824
	s_waitcnt vmcnt(7)
	ds_write_b128 v148, v[184:187] offset:9216
	s_waitcnt vmcnt(6)
	ds_write_b128 v148, v[188:191] offset:46080
	ds_read_b128 v[184:187], v150 offset:32
	ds_read_b128 v[188:191], v150 offset:4640
	s_waitcnt lgkmcnt(5)
	v_mfma_f32_32x32x16_bf16 v[80:95], v[160:163], v[208:211], v[80:95]
	v_mfma_f32_32x32x16_bf16 v[16:31], v[164:167], v[208:211], v[16:31]
	ds_read_b128 v[208:211], v149 offset:32
	s_waitcnt lgkmcnt(5)
	v_mfma_f32_32x32x16_bf16 v[64:79], v[160:163], v[212:215], v[64:79]
	v_mfma_f32_32x32x16_bf16 v[0:15], v[164:167], v[212:215], v[0:15]
	ds_read_b128 v[212:215], v149 offset:4640
	s_setprio 0
	global_load_dwordx4 v[160:163], v[140:141], off offset:3712
	global_load_dwordx4 v[164:167], v[142:143], off offset:3712
	s_setprio 1
	s_waitcnt lgkmcnt(1)
	v_mfma_f32_32x32x16_bf16 v[112:127], v[184:187], v[208:211], v[112:127]
	v_mfma_f32_32x32x16_bf16 v[48:63], v[188:191], v[208:211], v[48:63]
	s_waitcnt lgkmcnt(0)
	v_mfma_f32_32x32x16_bf16 v[96:111], v[184:187], v[212:215], v[96:111]
	v_mfma_f32_32x32x16_bf16 v[32:47], v[188:191], v[212:215], v[32:47]
	ds_read_b128 v[208:211], v149 offset:9248
	ds_read_b128 v[212:215], v149 offset:13856
	s_waitcnt vmcnt(7)
	ds_write_b128 v148, v[194:197] offset:18432
	s_waitcnt vmcnt(6)
	ds_write_b128 v148, v[198:201] offset:55296
	ds_read_b128 v[194:197], v150 offset:64
	ds_read_b128 v[198:201], v150 offset:4672
	s_waitcnt lgkmcnt(5)
	v_mfma_f32_32x32x16_bf16 v[80:95], v[184:187], v[208:211], v[80:95]
	v_mfma_f32_32x32x16_bf16 v[16:31], v[188:191], v[208:211], v[16:31]
	ds_read_b128 v[208:211], v149 offset:64
	s_waitcnt lgkmcnt(5)
	v_mfma_f32_32x32x16_bf16 v[64:79], v[184:187], v[212:215], v[64:79]
	v_mfma_f32_32x32x16_bf16 v[0:15], v[188:191], v[212:215], v[0:15]
	ds_read_b128 v[212:215], v149 offset:4672
	s_setprio 0
	global_load_dwordx4 v[184:187], v[132:133], off offset:3712
	global_load_dwordx4 v[188:191], v[134:135], off offset:3712
	s_setprio 1
	s_waitcnt lgkmcnt(1)
	v_mfma_f32_32x32x16_bf16 v[112:127], v[194:197], v[208:211], v[112:127]
	v_mfma_f32_32x32x16_bf16 v[48:63], v[198:201], v[208:211], v[48:63]
	s_waitcnt lgkmcnt(0)
	v_mfma_f32_32x32x16_bf16 v[96:111], v[194:197], v[212:215], v[96:111]
	v_mfma_f32_32x32x16_bf16 v[32:47], v[198:201], v[212:215], v[32:47]
	ds_read_b128 v[208:211], v149 offset:9280
	ds_read_b128 v[212:215], v149 offset:13888
	s_waitcnt vmcnt(7)
	ds_write_b128 v148, v[176:179] offset:27648
	s_waitcnt vmcnt(6)
	ds_write_b128 v148, v[180:183] offset:64512
	ds_read_b128 v[176:179], v150 offset:96
	ds_read_b128 v[180:183], v150 offset:4704
	s_waitcnt lgkmcnt(5)
	v_mfma_f32_32x32x16_bf16 v[80:95], v[194:197], v[208:211], v[80:95]
	v_mfma_f32_32x32x16_bf16 v[16:31], v[198:201], v[208:211], v[16:31]
	ds_read_b128 v[208:211], v149 offset:96
	s_waitcnt lgkmcnt(5)
	v_mfma_f32_32x32x16_bf16 v[64:79], v[194:197], v[212:215], v[64:79]
	v_mfma_f32_32x32x16_bf16 v[0:15], v[198:201], v[212:215], v[0:15]
	ds_read_b128 v[212:215], v149 offset:4704
	s_setprio 0
	global_load_dwordx4 v[194:197], v[144:145], off offset:3712
	global_load_dwordx4 v[198:201], v[146:147], off offset:3712
	s_setprio 1
	s_waitcnt lgkmcnt(1)
	v_mfma_f32_32x32x16_bf16 v[112:127], v[176:179], v[208:211], v[112:127]
	v_mfma_f32_32x32x16_bf16 v[48:63], v[180:183], v[208:211], v[48:63]
	s_waitcnt lgkmcnt(0)
	v_mfma_f32_32x32x16_bf16 v[96:111], v[176:179], v[212:215], v[96:111]
	v_mfma_f32_32x32x16_bf16 v[32:47], v[180:183], v[212:215], v[32:47]
	ds_read_b128 v[208:211], v149 offset:9312
	ds_read_b128 v[212:215], v149 offset:13920
	s_waitcnt lgkmcnt(1)
	v_mfma_f32_32x32x16_bf16 v[80:95], v[176:179], v[208:211], v[80:95]
	v_mfma_f32_32x32x16_bf16 v[16:31], v[180:183], v[208:211], v[16:31]
	s_waitcnt lgkmcnt(0)
	v_mfma_f32_32x32x16_bf16 v[64:79], v[176:179], v[212:215], v[64:79]
	v_mfma_f32_32x32x16_bf16 v[0:15], v[180:183], v[212:215], v[0:15]
	s_setprio 0
	global_load_dwordx4 v[176:179], v[136:137], off offset:3840
	global_load_dwordx4 v[180:183], v[138:139], off offset:3840
	s_barrier
; template <bool trans>
; DI void gemm_core(const GTile& tl, const GTile& nx, bool has_next  , bool chain  , bool pre, u32x4 (&ra)[4], u32x4 (&rb)[4], char* smem, f32x16 (&acc)[2][4]) {
;     ...
;   const int nk = K / 64;
;   if (!pre) { G_LOAD(0); G_STORE(0); G_LOAD(1); }
;   for (int kt = 0; kt < nk; ++kt) {
;     __syncthreads();
;     G_COMPUTE(kt & 1, kt);
;   }
	s_waitcnt vmcnt(9)
	ds_write_b128 v192, v[168:171]
	s_waitcnt vmcnt(8)
	ds_write_b128 v159, v[172:175]
	ds_read_b128 v[168:171], v152 offset:36864
	ds_read_b128 v[172:175], v152 offset:41472
	ds_read_b128 v[208:211], v151
	ds_read_b128 v[212:215], v151 offset:4608
	s_setprio 1
	s_waitcnt lgkmcnt(1)
	v_mfma_f32_32x32x16_bf16 v[112:127], v[168:171], v[208:211], v[112:127]
	v_mfma_f32_32x32x16_bf16 v[48:63], v[172:175], v[208:211], v[48:63]
	s_waitcnt lgkmcnt(0)
	v_mfma_f32_32x32x16_bf16 v[96:111], v[168:171], v[212:215], v[96:111]
	v_mfma_f32_32x32x16_bf16 v[32:47], v[172:175], v[212:215], v[32:47]
	ds_read_b128 v[208:211], v151 offset:9216
	ds_read_b128 v[212:215], v151 offset:13824
	s_waitcnt lgkmcnt(1)
	v_mfma_f32_32x32x16_bf16 v[80:95], v[168:171], v[208:211], v[80:95]
	v_mfma_f32_32x32x16_bf16 v[16:31], v[172:175], v[208:211], v[16:31]
	s_waitcnt lgkmcnt(0)
	v_mfma_f32_32x32x16_bf16 v[64:79], v[168:171], v[212:215], v[64:79]
	v_mfma_f32_32x32x16_bf16 v[0:15], v[172:175], v[212:215], v[0:15]
	s_setprio 0
	global_load_dwordx4 v[208:211], v[140:141], off offset:3840
	global_load_dwordx4 v[212:215], v[142:143], off offset:3840
	s_waitcnt vmcnt(9)
	ds_write_b128 v158, v[160:163]
	s_waitcnt vmcnt(8)
	ds_write_b128 v157, v[164:167]
	ds_read_b128 v[160:163], v152 offset:36896
	ds_read_b128 v[164:167], v152 offset:41504
	ds_read_b128 v[168:171], v151 offset:32
	ds_read_b128 v[172:175], v151 offset:4640
	s_setprio 1
	s_waitcnt lgkmcnt(1)
	v_mfma_f32_32x32x16_bf16 v[112:127], v[160:163], v[168:171], v[112:127]
	v_mfma_f32_32x32x16_bf16 v[48:63], v[164:167], v[168:171], v[48:63]
	s_waitcnt lgkmcnt(0)
	v_mfma_f32_32x32x16_bf16 v[96:111], v[160:163], v[172:175], v[96:111]
	v_mfma_f32_32x32x16_bf16 v[32:47], v[164:167], v[172:175], v[32:47]
	ds_read_b128 v[168:171], v151 offset:9248
	ds_read_b128 v[172:175], v151 offset:13856
	s_waitcnt lgkmcnt(1)
	v_mfma_f32_32x32x16_bf16 v[80:95], v[160:163], v[168:171], v[80:95]
	v_mfma_f32_32x32x16_bf16 v[16:31], v[164:167], v[168:171], v[16:31]
	s_waitcnt lgkmcnt(0)
	v_mfma_f32_32x32x16_bf16 v[64:79], v[160:163], v[172:175], v[64:79]
	v_mfma_f32_32x32x16_bf16 v[0:15], v[164:167], v[172:175], v[0:15]
	s_setprio 0
	global_load_dwordx4 v[216:219], v[132:133], off offset:3840
	global_load_dwordx4 v[220:223], v[134:135], off offset:3840
	s_waitcnt vmcnt(9)
	ds_write_b128 v154, v[184:187]
	s_waitcnt vmcnt(8)
	ds_write_b128 v153, v[188:191]
	ds_read_b128 v[160:163], v152 offset:36928
	ds_read_b128 v[164:167], v152 offset:41536
	ds_read_b128 v[168:171], v151 offset:64
	ds_read_b128 v[172:175], v151 offset:4672
	s_setprio 1
	s_waitcnt lgkmcnt(1)
	v_mfma_f32_32x32x16_bf16 v[112:127], v[160:163], v[168:171], v[112:127]
	v_mfma_f32_32x32x16_bf16 v[48:63], v[164:167], v[168:171], v[48:63]
	s_waitcnt lgkmcnt(0)
	v_mfma_f32_32x32x16_bf16 v[96:111], v[160:163], v[172:175], v[96:111]
	v_mfma_f32_32x32x16_bf16 v[32:47], v[164:167], v[172:175], v[32:47]
	ds_read_b128 v[168:171], v151 offset:9280
	ds_read_b128 v[172:175], v151 offset:13888
	s_waitcnt lgkmcnt(1)
	v_mfma_f32_32x32x16_bf16 v[80:95], v[160:163], v[168:171], v[80:95]
	v_mfma_f32_32x32x16_bf16 v[16:31], v[164:167], v[168:171], v[16:31]
	s_waitcnt lgkmcnt(0)
	v_mfma_f32_32x32x16_bf16 v[64:79], v[160:163], v[172:175], v[64:79]
	v_mfma_f32_32x32x16_bf16 v[0:15], v[164:167], v[172:175], v[0:15]
	s_setprio 0
	global_load_dwordx4 v[224:227], v[144:145], off offset:3840
	global_load_dwordx4 v[228:231], v[146:147], off offset:3840
	s_waitcnt vmcnt(9)
	ds_write_b128 v156, v[194:197]
	s_waitcnt vmcnt(8)
	ds_write_b128 v155, v[198:201]
	ds_read_b128 v[160:163], v152 offset:36960
	ds_read_b128 v[164:167], v152 offset:41568
	ds_read_b128 v[168:171], v151 offset:96
	ds_read_b128 v[172:175], v151 offset:4704
	s_setprio 1
	s_waitcnt lgkmcnt(1)
	v_mfma_f32_32x32x16_bf16 v[112:127], v[160:163], v[168:171], v[112:127]
	v_mfma_f32_32x32x16_bf16 v[48:63], v[164:167], v[168:171], v[48:63]
	s_waitcnt lgkmcnt(0)
	v_mfma_f32_32x32x16_bf16 v[96:111], v[160:163], v[172:175], v[96:111]
	v_mfma_f32_32x32x16_bf16 v[32:47], v[164:167], v[172:175], v[32:47]
	ds_read_b128 v[168:171], v151 offset:9312
	ds_read_b128 v[172:175], v151 offset:13920
	s_waitcnt lgkmcnt(1)
	v_mfma_f32_32x32x16_bf16 v[80:95], v[160:163], v[168:171], v[80:95]
	v_mfma_f32_32x32x16_bf16 v[16:31], v[164:167], v[168:171], v[16:31]
	s_waitcnt lgkmcnt(0)
	v_mfma_f32_32x32x16_bf16 v[64:79], v[160:163], v[172:175], v[64:79]
	v_mfma_f32_32x32x16_bf16 v[0:15], v[164:167], v[172:175], v[0:15]
	s_setprio 0
	global_load_dwordx4 v[160:163], v[136:137], off offset:3968
	global_load_dwordx4 v[164:167], v[138:139], off offset:3968
	s_barrier
; template <bool trans>
; DI void gemm_core(const GTile& tl, const GTile& nx, bool has_next  , bool chain  , bool pre, u32x4 (&ra)[4], u32x4 (&rb)[4], char* smem, f32x16 (&acc)[2][4]) {
;     ...
;   const int nk = K / 64;
;   if (!pre) { G_LOAD(0); G_STORE(0); G_LOAD(1); }
;   for (int kt = 0; kt < nk; ++kt) {
;     __syncthreads();
;     G_COMPUTE(kt & 1, kt);
;   }
	s_waitcnt vmcnt(9)
	ds_write_b128 v148, v[176:179]
	s_waitcnt vmcnt(8)
	ds_write_b128 v148, v[180:183] offset:36864
	ds_read_b128 v[136:139], v150
	ds_read_b128 v[168:171], v150 offset:4608
	ds_read_b128 v[172:175], v149
	ds_read_b128 v[176:179], v149 offset:4608
	s_setprio 1
	s_waitcnt lgkmcnt(1)
	v_mfma_f32_32x32x16_bf16 v[112:127], v[136:139], v[172:175], v[112:127]
	v_mfma_f32_32x32x16_bf16 v[48:63], v[168:171], v[172:175], v[48:63]
	s_waitcnt lgkmcnt(0)
	v_mfma_f32_32x32x16_bf16 v[96:111], v[136:139], v[176:179], v[96:111]
	v_mfma_f32_32x32x16_bf16 v[32:47], v[168:171], v[176:179], v[32:47]
	ds_read_b128 v[172:175], v149 offset:9216
	ds_read_b128 v[176:179], v149 offset:13824
	s_waitcnt lgkmcnt(1)
	v_mfma_f32_32x32x16_bf16 v[80:95], v[136:139], v[172:175], v[80:95]
	v_mfma_f32_32x32x16_bf16 v[16:31], v[168:171], v[172:175], v[16:31]
	s_waitcnt lgkmcnt(0)
	v_mfma_f32_32x32x16_bf16 v[64:79], v[136:139], v[176:179], v[64:79]
	v_mfma_f32_32x32x16_bf16 v[0:15], v[168:171], v[176:179], v[0:15]
	s_setprio 0
	global_load_dwordx4 v[168:171], v[140:141], off offset:3968
	global_load_dwordx4 v[172:175], v[142:143], off offset:3968
	s_waitcnt vmcnt(9)
	ds_write_b128 v148, v[208:211] offset:9216
	s_waitcnt vmcnt(8)
	ds_write_b128 v148, v[212:215] offset:46080
	ds_read_b128 v[136:139], v150 offset:32
	ds_read_b128 v[140:143], v150 offset:4640
	ds_read_b128 v[176:179], v149 offset:32
	ds_read_b128 v[180:183], v149 offset:4640
	s_setprio 1
	s_waitcnt lgkmcnt(1)
	v_mfma_f32_32x32x16_bf16 v[112:127], v[136:139], v[176:179], v[112:127]
	v_mfma_f32_32x32x16_bf16 v[48:63], v[140:143], v[176:179], v[48:63]
	s_waitcnt lgkmcnt(0)
	v_mfma_f32_32x32x16_bf16 v[96:111], v[136:139], v[180:183], v[96:111]
	v_mfma_f32_32x32x16_bf16 v[32:47], v[140:143], v[180:183], v[32:47]
	ds_read_b128 v[176:179], v149 offset:9248
	ds_read_b128 v[180:183], v149 offset:13856
	s_waitcnt lgkmcnt(1)
	v_mfma_f32_32x32x16_bf16 v[80:95], v[136:139], v[176:179], v[80:95]
	v_mfma_f32_32x32x16_bf16 v[16:31], v[140:143], v[176:179], v[16:31]
	s_waitcnt lgkmcnt(0)
	v_mfma_f32_32x32x16_bf16 v[64:79], v[136:139], v[180:183], v[64:79]
	v_mfma_f32_32x32x16_bf16 v[0:15], v[140:143], v[180:183], v[0:15]
	s_setprio 0
	global_load_dwordx4 v[176:179], v[132:133], off offset:3968
	global_load_dwordx4 v[180:183], v[134:135], off offset:3968
	s_waitcnt vmcnt(9)
	ds_write_b128 v148, v[216:219] offset:18432
	s_waitcnt vmcnt(8)
	ds_write_b128 v148, v[220:223] offset:55296
	ds_read_b128 v[132:135], v150 offset:64
	ds_read_b128 v[136:139], v150 offset:4672
	ds_read_b128 v[140:143], v149 offset:64
	ds_read_b128 v[184:187], v149 offset:4672
	s_setprio 1
	s_waitcnt lgkmcnt(1)
	v_mfma_f32_32x32x16_bf16 v[112:127], v[132:135], v[140:143], v[112:127]
	v_mfma_f32_32x32x16_bf16 v[48:63], v[136:139], v[140:143], v[48:63]
	s_waitcnt lgkmcnt(0)
	v_mfma_f32_32x32x16_bf16 v[96:111], v[132:135], v[184:187], v[96:111]
	v_mfma_f32_32x32x16_bf16 v[32:47], v[136:139], v[184:187], v[32:47]
	ds_read_b128 v[140:143], v149 offset:9280
	ds_read_b128 v[184:187], v149 offset:13888
	s_waitcnt lgkmcnt(1)
	v_mfma_f32_32x32x16_bf16 v[80:95], v[132:135], v[140:143], v[80:95]
	v_mfma_f32_32x32x16_bf16 v[16:31], v[136:139], v[140:143], v[16:31]
	s_waitcnt lgkmcnt(0)
	v_mfma_f32_32x32x16_bf16 v[64:79], v[132:135], v[184:187], v[64:79]
	v_mfma_f32_32x32x16_bf16 v[0:15], v[136:139], v[184:187], v[0:15]
	s_setprio 0
	global_load_dwordx4 v[184:187], v[144:145], off offset:3968
	global_load_dwordx4 v[188:191], v[146:147], off offset:3968
	s_waitcnt vmcnt(9)
	ds_write_b128 v148, v[224:227] offset:27648
	s_waitcnt vmcnt(8)
	ds_write_b128 v148, v[228:231] offset:64512
	ds_read_b128 v[132:135], v150 offset:96
	ds_read_b128 v[136:139], v150 offset:4704
	ds_read_b128 v[140:143], v149 offset:96
	ds_read_b128 v[144:147], v149 offset:4704
	s_setprio 1
	s_waitcnt lgkmcnt(1)
	v_mfma_f32_32x32x16_bf16 v[112:127], v[132:135], v[140:143], v[112:127]
	v_mfma_f32_32x32x16_bf16 v[48:63], v[136:139], v[140:143], v[48:63]
	s_waitcnt lgkmcnt(0)
	v_mfma_f32_32x32x16_bf16 v[96:111], v[132:135], v[144:147], v[96:111]
	v_mfma_f32_32x32x16_bf16 v[32:47], v[136:139], v[144:147], v[32:47]
	ds_read_b128 v[140:143], v149 offset:9312
	ds_read_b128 v[144:147], v149 offset:13920
	s_waitcnt lgkmcnt(1)
	v_mfma_f32_32x32x16_bf16 v[80:95], v[132:135], v[140:143], v[80:95]
	v_mfma_f32_32x32x16_bf16 v[16:31], v[136:139], v[140:143], v[16:31]
	s_waitcnt lgkmcnt(0)
	v_mfma_f32_32x32x16_bf16 v[64:79], v[132:135], v[144:147], v[64:79]
	v_mfma_f32_32x32x16_bf16 v[0:15], v[136:139], v[144:147], v[0:15]
	s_setprio 0
	v_cndmask_b32_e64 v132, 0, 1, s[52:53]
	v_cmp_ne_u32_e64 s[4:5], 1, v132
	s_andn2_b64 vcc, exec, s[52:53]
	s_barrier
	s_waitcnt vmcnt(7)
	ds_write_b128 v192, v[160:163]
	s_waitcnt vmcnt(6)
	ds_write_b128 v159, v[164:167]
	s_cbranch_vccnz .LBB0_113
	global_load_dwordx4 v[160:163], v[130:131], off
	global_load_dwordx4 v[164:167], v[128:129], off

;   DI bf16_t* h() const { return (bf16_t*)(ws + OFF_H); }
; template <bool trans>
; DI void gemm_core(const GTile& tl, const GTile& nx, bool has_next  , bool chain  , bool pre, u32x4 (&ra)[4], u32x4 (&rb)[4], char* smem, f32x16 (&acc)[2][4]) {
;     ...
;   const int nk = K / 64;
;   if (!pre) { G_LOAD(0); G_STORE(0); G_LOAD(1); }
;   for (int kt = 0; kt < nk; ++kt) {
;     __syncthreads();
;     G_COMPUTE(kt & 1, kt);
;   }
; DI void phase_gemm_out(const Params& p, char* smem, const bf16_t* Wt, const float* R, float* O) {
;     ...
;   for (int t = blockIdx.x; t < 64 * 8; t += gridDim.x) {
;     const int mt = t & 63, nt = t >> 6, tn = t + gridDim.x;
;     const bool has_next = tn < 64 * 8;
;     const GTile tl{p.h(), D, Wt, D, D, mt * 256, nt * 256}, nx{p.h(), D, Wt, D, D, (tn & 63) * 256, (tn >> 6) * 256};
;     WAVE_GEOM;
;     f32x16 acc[2][4];
;     gemm_core<false>(tl, nx, has_next, has_next, pre, ra, rb, smem, acc);
;     const float* Rq = R; asm volatile("" : "+s"(Rq));
;     EpiResid e{Rq, O};
;     e(acc, mt * 256 + wm_ * 128, nt * 256 + wn_ * 64, l32_, g_);
.LBB0_749:
	v_lshl_add_u64 v[128:129], s[2:3], 0, v[184:185]
	v_lshl_add_u64 v[132:133], s[6:7], 0, v[184:185]
	s_waitcnt lgkmcnt(0)
	s_barrier
	global_load_dwordx4 v[198:201], v[128:129], off offset:256
	global_load_dwordx4 v[202:205], v[132:133], off offset:256
	s_add_i32 s38, s38, s96
	s_cmpk_lt_i32 s38, 0x200
	s_cselect_b64 s[14:15], -1, 0
	s_cmpk_gt_i32 s38, 0x1ff
	s_cselect_b64 s[12:13], -1, 0
	s_and_b32 s3, s28, 0x1f80000
	s_add_i32 s24, s25, s24
	s_and_b32 s2, s24, 0xffffff00
	s_and_b32 s40, s33, 0xc0
	s_lshl_b32 s3, s3, 1
	s_add_u32 s6, s18, s3
	s_addc_u32 s7, s19, 0
	s_ashr_i32 s3, s2, 31
	s_lshl_b64 s[2:3], s[2:3], 12
	s_add_u32 s2, s16, s2
	s_addc_u32 s3, s17, s3
	s_lshr_b32 s33, s33, 1
	v_and_b32_e32 v11, 31, v8
	s_and_b32 s33, s33, 0xfffff80
	v_or_b32_e32 v12, s33, v11
	v_or_b32_e32 v11, s40, v11
	v_add3_u32 v191, 16, v10, v9
	v_lshrrev_b32_e32 v8, 1, v8
	v_mul_u32_u24_e32 v131, 0x90, v11
	v_and_b32_e32 v134, 16, v8
	v_add_u32_e32 v195, 0x12000, v191
	v_mul_lo_u32 v130, v12, s35
	v_add3_u32 v192, 16, v131, v134
	v_add_u32_e32 v196, 0x1b000, v191
	ds_write_b128 v195, v[0:3]
	s_waitcnt vmcnt(5)
	ds_write_b128 v196, v[4:7]
	v_lshl_add_u64 v[188:189], s[6:7], 0, v[184:185]
	v_lshl_add_u64 v[186:187], s[2:3], 0, v[184:185]
	v_add3_u32 v184, 16, v130, v134
	ds_read_b128 v[0:3], v192 offset:36864
	ds_read_b128 v[4:7], v192 offset:41472
	ds_read_b128 v[8:11], v184
	ds_read_b128 v[12:15], v184 offset:4608
	v_lshl_add_u64 v[136:137], v[128:129], 0, s[0:1]
	v_lshl_add_u64 v[140:141], v[132:133], 0, s[0:1]
	v_lshl_add_u64 v[144:145], v[128:129], 0, s[8:9]
	v_lshl_add_u64 v[148:149], v[132:133], 0, s[8:9]
	s_setprio 1
	s_waitcnt lgkmcnt(1)
	v_mfma_f32_32x32x16_bf16 v[112:127], v[0:3], v[8:11], 0
	v_mfma_f32_32x32x16_bf16 v[48:63], v[4:7], v[8:11], 0
	s_waitcnt lgkmcnt(0)
	v_mfma_f32_32x32x16_bf16 v[96:111], v[0:3], v[12:15], 0
	v_mfma_f32_32x32x16_bf16 v[32:47], v[4:7], v[12:15], 0
	ds_read_b128 v[8:11], v184 offset:9216
	ds_read_b128 v[12:15], v184 offset:13824
	s_waitcnt lgkmcnt(1)
	v_mfma_f32_32x32x16_bf16 v[80:95], v[0:3], v[8:11], 0
	v_mfma_f32_32x32x16_bf16 v[16:31], v[4:7], v[8:11], 0
	s_waitcnt lgkmcnt(0)
	v_mfma_f32_32x32x16_bf16 v[64:79], v[0:3], v[12:15], 0
	v_mfma_f32_32x32x16_bf16 v[0:15], v[4:7], v[12:15], 0
	s_setprio 0
	global_load_dwordx4 v[208:211], v[136:137], off offset:256
	global_load_dwordx4 v[212:215], v[140:141], off offset:256
	v_add_u32_e32 v194, 0x14400, v191
	v_add_u32_e32 v193, 0x1d400, v191
	ds_write_b128 v194, v[176:179]
	s_waitcnt vmcnt(6)
	ds_write_b128 v193, v[180:183]
	ds_read_b128 v[150:153], v192 offset:36896
	ds_read_b128 v[154:157], v192 offset:41504
	ds_read_b128 v[176:179], v184 offset:32
	ds_read_b128 v[180:183], v184 offset:4640
	s_setprio 1
	s_waitcnt lgkmcnt(1)
	v_mfma_f32_32x32x16_bf16 v[112:127], v[150:153], v[176:179], v[112:127]
	v_mfma_f32_32x32x16_bf16 v[48:63], v[154:157], v[176:179], v[48:63]
	s_waitcnt lgkmcnt(0)
	v_mfma_f32_32x32x16_bf16 v[96:111], v[150:153], v[180:183], v[96:111]
	v_mfma_f32_32x32x16_bf16 v[32:47], v[154:157], v[180:183], v[32:47]
	ds_read_b128 v[176:179], v184 offset:9248
	ds_read_b128 v[180:183], v184 offset:13856
	s_waitcnt lgkmcnt(1)
	v_mfma_f32_32x32x16_bf16 v[80:95], v[150:153], v[176:179], v[80:95]
	v_mfma_f32_32x32x16_bf16 v[16:31], v[154:157], v[176:179], v[16:31]
	s_waitcnt lgkmcnt(0)
	v_mfma_f32_32x32x16_bf16 v[64:79], v[150:153], v[180:183], v[64:79]
	v_mfma_f32_32x32x16_bf16 v[0:15], v[154:157], v[180:183], v[0:15]
	s_setprio 0
	global_load_dwordx4 v[178:181], v[144:145], off offset:256
	global_load_dwordx4 v[216:219], v[148:149], off offset:256
	v_add_u32_e32 v177, 0x16800, v191
	v_add_u32_e32 v176, 0x1f800, v191
	ds_write_b128 v177, v[168:171]
	s_waitcnt vmcnt(7)
	ds_write_b128 v176, v[172:175]
	ds_read_b128 v[150:153], v192 offset:36928
	ds_read_b128 v[154:157], v192 offset:41536
	ds_read_b128 v[168:171], v184 offset:64
	ds_read_b128 v[172:175], v184 offset:4672
	s_setprio 1
	s_waitcnt lgkmcnt(1)
	v_mfma_f32_32x32x16_bf16 v[112:127], v[150:153], v[168:171], v[112:127]
	v_mfma_f32_32x32x16_bf16 v[48:63], v[154:157], v[168:171], v[48:63]
	s_waitcnt lgkmcnt(0)
	v_mfma_f32_32x32x16_bf16 v[96:111], v[150:153], v[172:175], v[96:111]
	v_mfma_f32_32x32x16_bf16 v[32:47], v[154:157], v[172:175], v[32:47]
	ds_read_b128 v[168:171], v184 offset:9280
	ds_read_b128 v[172:175], v184 offset:13888
	s_waitcnt lgkmcnt(1)
	v_mfma_f32_32x32x16_bf16 v[80:95], v[150:153], v[168:171], v[80:95]
	v_mfma_f32_32x32x16_bf16 v[16:31], v[154:157], v[168:171], v[16:31]
	s_waitcnt lgkmcnt(0)
	v_mfma_f32_32x32x16_bf16 v[64:79], v[150:153], v[172:175], v[64:79]
	v_mfma_f32_32x32x16_bf16 v[0:15], v[154:157], v[172:175], v[0:15]
	s_setprio 0
	v_add_co_u32_e32 v152, vcc, s34, v128
	v_add_u32_e32 v171, 0x18c00, v191
	s_nop 0
	v_addc_co_u32_e32 v153, vcc, 0, v129, vcc
	v_add_co_u32_e32 v156, vcc, s34, v132
	v_add_u32_e32 v170, 0x21c00, v191
	s_nop 0
	v_addc_co_u32_e32 v157, vcc, 0, v133, vcc
	global_load_dwordx4 v[172:175], v[152:153], off offset:256
	global_load_dwordx4 v[220:223], v[156:157], off offset:256
	ds_write_b128 v171, v[160:163]
	s_waitcnt vmcnt(8)
	ds_write_b128 v170, v[164:167]
	ds_read_b128 v[158:161], v192 offset:36960
	ds_read_b128 v[162:165], v192 offset:41568
	ds_read_b128 v[166:169], v184 offset:96
	ds_read_b128 v[224:227], v184 offset:4704
	s_setprio 1
	s_waitcnt lgkmcnt(1)
	v_mfma_f32_32x32x16_bf16 v[112:127], v[158:161], v[166:169], v[112:127]
	v_mfma_f32_32x32x16_bf16 v[48:63], v[162:165], v[166:169], v[48:63]
	s_waitcnt lgkmcnt(0)
	v_mfma_f32_32x32x16_bf16 v[96:111], v[158:161], v[224:227], v[96:111]
	v_mfma_f32_32x32x16_bf16 v[32:47], v[162:165], v[224:227], v[32:47]
	ds_read_b128 v[166:169], v184 offset:9312
	ds_read_b128 v[224:227], v184 offset:13920
	s_waitcnt lgkmcnt(1)
	v_mfma_f32_32x32x16_bf16 v[80:95], v[158:161], v[166:169], v[80:95]
	v_mfma_f32_32x32x16_bf16 v[16:31], v[162:165], v[166:169], v[16:31]
	s_waitcnt lgkmcnt(0)
	v_mfma_f32_32x32x16_bf16 v[64:79], v[158:161], v[224:227], v[64:79]
	v_mfma_f32_32x32x16_bf16 v[0:15], v[162:165], v[224:227], v[0:15]
	s_setprio 0
	global_load_dwordx4 v[158:161], v[128:129], off offset:384
	global_load_dwordx4 v[162:165], v[132:133], off offset:384
	s_barrier
; template <bool trans>
; DI void gemm_core(const GTile& tl, const GTile& nx, bool has_next  , bool chain  , bool pre, u32x4 (&ra)[4], u32x4 (&rb)[4], char* smem, f32x16 (&acc)[2][4]) {
;     ...
;   const int nk = K / 64;
;   if (!pre) { G_LOAD(0); G_STORE(0); G_LOAD(1); }
;   for (int kt = 0; kt < nk; ++kt) {
;     __syncthreads();
;     G_COMPUTE(kt & 1, kt);
	v_add3_u32 v169, s37, v131, v134
	s_waitcnt vmcnt(9)
	ds_write_b128 v191, v[198:201]
	s_waitcnt vmcnt(8)
	ds_write_b128 v191, v[202:205] offset:36864
	v_add3_u32 v168, s36, v130, v134
	ds_read_b128 v[198:201], v169
	ds_read_b128 v[202:205], v169 offset:4608
	ds_read_b128 v[224:227], v168
	ds_read_b128 v[228:231], v168 offset:4608
	s_setprio 1
	s_waitcnt lgkmcnt(1)
	v_mfma_f32_32x32x16_bf16 v[112:127], v[198:201], v[224:227], v[112:127]
	v_mfma_f32_32x32x16_bf16 v[48:63], v[202:205], v[224:227], v[48:63]
	s_waitcnt lgkmcnt(0)
	v_mfma_f32_32x32x16_bf16 v[96:111], v[198:201], v[228:231], v[96:111]
	v_mfma_f32_32x32x16_bf16 v[32:47], v[202:205], v[228:231], v[32:47]
	ds_read_b128 v[224:227], v168 offset:9216
	ds_read_b128 v[228:231], v168 offset:13824
	s_waitcnt lgkmcnt(1)
	v_mfma_f32_32x32x16_bf16 v[80:95], v[198:201], v[224:227], v[80:95]
	v_mfma_f32_32x32x16_bf16 v[16:31], v[202:205], v[224:227], v[16:31]
	s_waitcnt lgkmcnt(0)
	v_mfma_f32_32x32x16_bf16 v[64:79], v[198:201], v[228:231], v[64:79]
	v_mfma_f32_32x32x16_bf16 v[0:15], v[202:205], v[228:231], v[0:15]
	s_setprio 0
	global_load_dwordx4 v[198:201], v[136:137], off offset:384
	global_load_dwordx4 v[202:205], v[140:141], off offset:384
	s_waitcnt vmcnt(9)
	ds_write_b128 v191, v[208:211] offset:9216
	s_waitcnt vmcnt(8)
	ds_write_b128 v191, v[212:215] offset:46080
	ds_read_b128 v[208:211], v169 offset:32
	ds_read_b128 v[212:215], v169 offset:4640
	ds_read_b128 v[224:227], v168 offset:32
	ds_read_b128 v[228:231], v168 offset:4640
	s_setprio 1
	s_waitcnt lgkmcnt(1)
	v_mfma_f32_32x32x16_bf16 v[112:127], v[208:211], v[224:227], v[112:127]
	v_mfma_f32_32x32x16_bf16 v[48:63], v[212:215], v[224:227], v[48:63]
	s_waitcnt lgkmcnt(0)
	v_mfma_f32_32x32x16_bf16 v[96:111], v[208:211], v[228:231], v[96:111]
	v_mfma_f32_32x32x16_bf16 v[32:47], v[212:215], v[228:231], v[32:47]
	ds_read_b128 v[224:227], v168 offset:9248
	ds_read_b128 v[228:231], v168 offset:13856
	s_waitcnt lgkmcnt(1)
	v_mfma_f32_32x32x16_bf16 v[80:95], v[208:211], v[224:227], v[80:95]
	v_mfma_f32_32x32x16_bf16 v[16:31], v[212:215], v[224:227], v[16:31]
	s_waitcnt lgkmcnt(0)
	v_mfma_f32_32x32x16_bf16 v[64:79], v[208:211], v[228:231], v[64:79]
	v_mfma_f32_32x32x16_bf16 v[0:15], v[212:215], v[228:231], v[0:15]
	s_setprio 0
	global_load_dwordx4 v[208:211], v[144:145], off offset:384
	global_load_dwordx4 v[212:215], v[148:149], off offset:384
	s_waitcnt vmcnt(9)
	ds_write_b128 v191, v[178:181] offset:18432
	s_waitcnt vmcnt(8)
	ds_write_b128 v191, v[216:219] offset:55296
	ds_read_b128 v[178:181], v169 offset:64
	ds_read_b128 v[216:219], v169 offset:4672
	ds_read_b128 v[224:227], v168 offset:64
	ds_read_b128 v[228:231], v168 offset:4672
	s_setprio 1
	s_waitcnt lgkmcnt(1)
	v_mfma_f32_32x32x16_bf16 v[112:127], v[178:181], v[224:227], v[112:127]
	v_mfma_f32_32x32x16_bf16 v[48:63], v[216:219], v[224:227], v[48:63]
	s_waitcnt lgkmcnt(0)
	v_mfma_f32_32x32x16_bf16 v[96:111], v[178:181], v[228:231], v[96:111]
	v_mfma_f32_32x32x16_bf16 v[32:47], v[216:219], v[228:231], v[32:47]
	ds_read_b128 v[224:227], v168 offset:9280
	ds_read_b128 v[228:231], v168 offset:13888
	s_waitcnt lgkmcnt(1)
	v_mfma_f32_32x32x16_bf16 v[80:95], v[178:181], v[224:227], v[80:95]
	v_mfma_f32_32x32x16_bf16 v[16:31], v[216:219], v[224:227], v[16:31]
	s_waitcnt lgkmcnt(0)
	v_mfma_f32_32x32x16_bf16 v[64:79], v[178:181], v[228:231], v[64:79]
	v_mfma_f32_32x32x16_bf16 v[0:15], v[216:219], v[228:231], v[0:15]
	s_setprio 0
	global_load_dwordx4 v[178:181], v[152:153], off offset:384
	global_load_dwordx4 v[216:219], v[156:157], off offset:384
	s_waitcnt vmcnt(9)
	ds_write_b128 v191, v[172:175] offset:27648
	s_waitcnt vmcnt(8)
	ds_write_b128 v191, v[220:223] offset:64512
	ds_read_b128 v[172:175], v169 offset:96
	ds_read_b128 v[220:223], v169 offset:4704
	ds_read_b128 v[224:227], v168 offset:96
	ds_read_b128 v[228:231], v168 offset:4704
	s_setprio 1
	s_waitcnt lgkmcnt(1)
	v_mfma_f32_32x32x16_bf16 v[112:127], v[172:175], v[224:227], v[112:127]
	v_mfma_f32_32x32x16_bf16 v[48:63], v[220:223], v[224:227], v[48:63]
	s_waitcnt lgkmcnt(0)
	v_mfma_f32_32x32x16_bf16 v[96:111], v[172:175], v[228:231], v[96:111]
	v_mfma_f32_32x32x16_bf16 v[32:47], v[220:223], v[228:231], v[32:47]
	ds_read_b128 v[224:227], v168 offset:9312
	ds_read_b128 v[228:231], v168 offset:13920
	s_waitcnt lgkmcnt(1)
	v_mfma_f32_32x32x16_bf16 v[80:95], v[172:175], v[224:227], v[80:95]
	v_mfma_f32_32x32x16_bf16 v[16:31], v[220:223], v[224:227], v[16:31]
	s_waitcnt lgkmcnt(0)
	v_mfma_f32_32x32x16_bf16 v[64:79], v[172:175], v[228:231], v[64:79]
	v_mfma_f32_32x32x16_bf16 v[0:15], v[220:223], v[228:231], v[0:15]
	s_setprio 0
	global_load_dwordx4 v[172:175], v[128:129], off offset:512
	global_load_dwordx4 v[220:223], v[132:133], off offset:512
	s_barrier
; template <bool trans>
; DI void gemm_core(const GTile& tl, const GTile& nx, bool has_next  , bool chain  , bool pre, u32x4 (&ra)[4], u32x4 (&rb)[4], char* smem, f32x16 (&acc)[2][4]) {
;     ...
;   const int nk = K / 64;
;   if (!pre) { G_LOAD(0); G_STORE(0); G_LOAD(1); }
;   for (int kt = 0; kt < nk; ++kt) {
;     __syncthreads();
;     G_COMPUTE(kt & 1, kt);
	s_waitcnt vmcnt(9)
	ds_write_b128 v195, v[158:161]
	s_waitcnt vmcnt(8)
	ds_write_b128 v196, v[162:165]
	ds_read_b128 v[158:161], v192 offset:36864
	ds_read_b128 v[162:165], v192 offset:41472
	ds_read_b128 v[224:227], v184
	ds_read_b128 v[228:231], v184 offset:4608
	s_setprio 1
	s_waitcnt lgkmcnt(1)
	v_mfma_f32_32x32x16_bf16 v[112:127], v[158:161], v[224:227], v[112:127]
	v_mfma_f32_32x32x16_bf16 v[48:63], v[162:165], v[224:227], v[48:63]
	s_waitcnt lgkmcnt(0)
	v_mfma_f32_32x32x16_bf16 v[96:111], v[158:161], v[228:231], v[96:111]
	v_mfma_f32_32x32x16_bf16 v[32:47], v[162:165], v[228:231], v[32:47]
	ds_read_b128 v[224:227], v184 offset:9216
	ds_read_b128 v[228:231], v184 offset:13824
	s_waitcnt vmcnt(7)
	ds_write_b128 v194, v[198:201]
	s_waitcnt vmcnt(6)
	ds_write_b128 v193, v[202:205]
	ds_read_b128 v[198:201], v192 offset:36896
	ds_read_b128 v[202:205], v192 offset:41504
	s_waitcnt lgkmcnt(5)
	v_mfma_f32_32x32x16_bf16 v[80:95], v[158:161], v[224:227], v[80:95]
	v_mfma_f32_32x32x16_bf16 v[16:31], v[162:165], v[224:227], v[16:31]
	ds_read_b128 v[224:227], v184 offset:32
	s_waitcnt lgkmcnt(5)
	v_mfma_f32_32x32x16_bf16 v[64:79], v[158:161], v[228:231], v[64:79]
	v_mfma_f32_32x32x16_bf16 v[0:15], v[162:165], v[228:231], v[0:15]
	ds_read_b128 v[228:231], v184 offset:4640
	s_setprio 0
	global_load_dwordx4 v[158:161], v[136:137], off offset:512
	global_load_dwordx4 v[162:165], v[140:141], off offset:512
	s_setprio 1
	s_waitcnt lgkmcnt(1)
	v_mfma_f32_32x32x16_bf16 v[112:127], v[198:201], v[224:227], v[112:127]
	v_mfma_f32_32x32x16_bf16 v[48:63], v[202:205], v[224:227], v[48:63]
	s_waitcnt lgkmcnt(0)
	v_mfma_f32_32x32x16_bf16 v[96:111], v[198:201], v[228:231], v[96:111]
	v_mfma_f32_32x32x16_bf16 v[32:47], v[202:205], v[228:231], v[32:47]
	ds_read_b128 v[224:227], v184 offset:9248
	ds_read_b128 v[228:231], v184 offset:13856
	s_waitcnt vmcnt(7)
	ds_write_b128 v177, v[208:211]
	s_waitcnt vmcnt(6)
	ds_write_b128 v176, v[212:215]
	ds_read_b128 v[208:211], v192 offset:36928
	ds_read_b128 v[212:215], v192 offset:41536
	s_waitcnt lgkmcnt(5)
	v_mfma_f32_32x32x16_bf16 v[80:95], v[198:201], v[224:227], v[80:95]
	v_mfma_f32_32x32x16_bf16 v[16:31], v[202:205], v[224:227], v[16:31]
	ds_read_b128 v[224:227], v184 offset:64
	s_waitcnt lgkmcnt(5)
	v_mfma_f32_32x32x16_bf16 v[64:79], v[198:201], v[228:231], v[64:79]
	v_mfma_f32_32x32x16_bf16 v[0:15], v[202:205], v[228:231], v[0:15]
	ds_read_b128 v[228:231], v184 offset:4672
	s_setprio 0
	global_load_dwordx4 v[198:201], v[144:145], off offset:512
	global_load_dwordx4 v[202:205], v[148:149], off offset:512
	s_setprio 1
	s_waitcnt lgkmcnt(1)
	v_mfma_f32_32x32x16_bf16 v[112:127], v[208:211], v[224:227], v[112:127]
	v_mfma_f32_32x32x16_bf16 v[48:63], v[212:215], v[224:227], v[48:63]
	s_waitcnt lgkmcnt(0)
	v_mfma_f32_32x32x16_bf16 v[96:111], v[208:211], v[228:231], v[96:111]
	v_mfma_f32_32x32x16_bf16 v[32:47], v[212:215], v[228:231], v[32:47]
	ds_read_b128 v[224:227], v184 offset:9280
	ds_read_b128 v[228:231], v184 offset:13888
	s_waitcnt vmcnt(7)
	ds_write_b128 v171, v[178:181]
	s_waitcnt vmcnt(6)
	ds_write_b128 v170, v[216:219]
	ds_read_b128 v[178:181], v192 offset:36960
	ds_read_b128 v[216:219], v192 offset:41568
	s_waitcnt lgkmcnt(5)
	v_mfma_f32_32x32x16_bf16 v[80:95], v[208:211], v[224:227], v[80:95]
	v_mfma_f32_32x32x16_bf16 v[16:31], v[212:215], v[224:227], v[16:31]
	ds_read_b128 v[224:227], v184 offset:96
	s_waitcnt lgkmcnt(5)
	v_mfma_f32_32x32x16_bf16 v[64:79], v[208:211], v[228:231], v[64:79]
	v_mfma_f32_32x32x16_bf16 v[0:15], v[212:215], v[228:231], v[0:15]
	ds_read_b128 v[228:231], v184 offset:4704
	s_setprio 0
	global_load_dwordx4 v[208:211], v[152:153], off offset:512
	global_load_dwordx4 v[212:215], v[156:157], off offset:512
	s_setprio 1
	s_waitcnt lgkmcnt(1)
	v_mfma_f32_32x32x16_bf16 v[112:127], v[178:181], v[224:227], v[112:127]
	v_mfma_f32_32x32x16_bf16 v[48:63], v[216:219], v[224:227], v[48:63]
	s_waitcnt lgkmcnt(0)
	v_mfma_f32_32x32x16_bf16 v[96:111], v[178:181], v[228:231], v[96:111]
	v_mfma_f32_32x32x16_bf16 v[32:47], v[216:219], v[228:231], v[32:47]
	ds_read_b128 v[224:227], v184 offset:9312
	ds_read_b128 v[228:231], v184 offset:13920
	s_waitcnt lgkmcnt(0)
	s_barrier
	s_waitcnt vmcnt(7)
	ds_write_b128 v191, v[172:175]
	s_waitcnt vmcnt(6)
	ds_write_b128 v191, v[220:223] offset:36864
	ds_read_b128 v[172:175], v169
	ds_read_b128 v[220:223], v169 offset:4608
	v_mfma_f32_32x32x16_bf16 v[80:95], v[178:181], v[224:227], v[80:95]
	v_mfma_f32_32x32x16_bf16 v[16:31], v[216:219], v[224:227], v[16:31]
	ds_read_b128 v[224:227], v168
	v_mfma_f32_32x32x16_bf16 v[64:79], v[178:181], v[228:231], v[64:79]
	v_mfma_f32_32x32x16_bf16 v[0:15], v[216:219], v[228:231], v[0:15]
	ds_read_b128 v[228:231], v168 offset:4608
	s_setprio 0
	global_load_dwordx4 v[178:181], v[128:129], off offset:640
	global_load_dwordx4 v[216:219], v[132:133], off offset:640
	s_setprio 1
	s_waitcnt lgkmcnt(1)
	v_mfma_f32_32x32x16_bf16 v[112:127], v[172:175], v[224:227], v[112:127]
	v_mfma_f32_32x32x16_bf16 v[48:63], v[220:223], v[224:227], v[48:63]
	s_waitcnt lgkmcnt(0)
	v_mfma_f32_32x32x16_bf16 v[96:111], v[172:175], v[228:231], v[96:111]
	v_mfma_f32_32x32x16_bf16 v[32:47], v[220:223], v[228:231], v[32:47]
	ds_read_b128 v[224:227], v168 offset:9216
	ds_read_b128 v[228:231], v168 offset:13824
	s_waitcnt vmcnt(7)
	ds_write_b128 v191, v[158:161] offset:9216
	s_waitcnt vmcnt(6)
	ds_write_b128 v191, v[162:165] offset:46080
	ds_read_b128 v[158:161], v169 offset:32
	ds_read_b128 v[162:165], v169 offset:4640
	s_waitcnt lgkmcnt(5)
	v_mfma_f32_32x32x16_bf16 v[80:95], v[172:175], v[224:227], v[80:95]
	v_mfma_f32_32x32x16_bf16 v[16:31], v[220:223], v[224:227], v[16:31]
	ds_read_b128 v[224:227], v168 offset:32
	s_waitcnt lgkmcnt(5)
; template <bool trans>
; DI void gemm_core(const GTile& tl, const GTile& nx, bool has_next  , bool chain  , bool pre, u32x4 (&ra)[4], u32x4 (&rb)[4], char* smem, f32x16 (&acc)[2][4]) {
;     ...
;   const int nk = K / 64;
;   if (!pre) { G_LOAD(0); G_STORE(0); G_LOAD(1); }
;   for (int kt = 0; kt < nk; ++kt) {
;     __syncthreads();
;     G_COMPUTE(kt & 1, kt);
	v_mfma_f32_32x32x16_bf16 v[64:79], v[172:175], v[228:231], v[64:79]
	v_mfma_f32_32x32x16_bf16 v[0:15], v[220:223], v[228:231], v[0:15]
	ds_read_b128 v[228:231], v168 offset:4640
	s_setprio 0
	global_load_dwordx4 v[172:175], v[136:137], off offset:640
	global_load_dwordx4 v[220:223], v[140:141], off offset:640
	s_setprio 1
	s_waitcnt lgkmcnt(1)
	v_mfma_f32_32x32x16_bf16 v[112:127], v[158:161], v[224:227], v[112:127]
	v_mfma_f32_32x32x16_bf16 v[48:63], v[162:165], v[224:227], v[48:63]
	s_waitcnt lgkmcnt(0)
	v_mfma_f32_32x32x16_bf16 v[96:111], v[158:161], v[228:231], v[96:111]
	v_mfma_f32_32x32x16_bf16 v[32:47], v[162:165], v[228:231], v[32:47]
	ds_read_b128 v[224:227], v168 offset:9248
	ds_read_b128 v[228:231], v168 offset:13856
	s_waitcnt vmcnt(7)
	ds_write_b128 v191, v[198:201] offset:18432
	s_waitcnt vmcnt(6)
	ds_write_b128 v191, v[202:205] offset:55296
	ds_read_b128 v[198:201], v169 offset:64
	ds_read_b128 v[202:205], v169 offset:4672
	s_waitcnt lgkmcnt(5)
	v_mfma_f32_32x32x16_bf16 v[80:95], v[158:161], v[224:227], v[80:95]
	v_mfma_f32_32x32x16_bf16 v[16:31], v[162:165], v[224:227], v[16:31]
	ds_read_b128 v[224:227], v168 offset:64
	s_waitcnt lgkmcnt(5)
	v_mfma_f32_32x32x16_bf16 v[64:79], v[158:161], v[228:231], v[64:79]
	v_mfma_f32_32x32x16_bf16 v[0:15], v[162:165], v[228:231], v[0:15]
	ds_read_b128 v[228:231], v168 offset:4672
	s_setprio 0
	global_load_dwordx4 v[158:161], v[144:145], off offset:640
	global_load_dwordx4 v[162:165], v[148:149], off offset:640
	s_setprio 1
	s_waitcnt lgkmcnt(1)
	v_mfma_f32_32x32x16_bf16 v[112:127], v[198:201], v[224:227], v[112:127]
	v_mfma_f32_32x32x16_bf16 v[48:63], v[202:205], v[224:227], v[48:63]
	s_waitcnt lgkmcnt(0)
	v_mfma_f32_32x32x16_bf16 v[96:111], v[198:201], v[228:231], v[96:111]
	v_mfma_f32_32x32x16_bf16 v[32:47], v[202:205], v[228:231], v[32:47]
	ds_read_b128 v[224:227], v168 offset:9280
	ds_read_b128 v[228:231], v168 offset:13888
	s_waitcnt vmcnt(7)
	ds_write_b128 v191, v[208:211] offset:27648
	s_waitcnt vmcnt(6)
	ds_write_b128 v191, v[212:215] offset:64512
	ds_read_b128 v[208:211], v169 offset:96
	ds_read_b128 v[212:215], v169 offset:4704
	s_waitcnt lgkmcnt(5)
	v_mfma_f32_32x32x16_bf16 v[80:95], v[198:201], v[224:227], v[80:95]
	v_mfma_f32_32x32x16_bf16 v[16:31], v[202:205], v[224:227], v[16:31]
	ds_read_b128 v[224:227], v168 offset:96
	s_waitcnt lgkmcnt(5)
	v_mfma_f32_32x32x16_bf16 v[64:79], v[198:201], v[228:231], v[64:79]
	v_mfma_f32_32x32x16_bf16 v[0:15], v[202:205], v[228:231], v[0:15]
	ds_read_b128 v[228:231], v168 offset:4704
	s_setprio 0
	global_load_dwordx4 v[198:201], v[152:153], off offset:640
	global_load_dwordx4 v[202:205], v[156:157], off offset:640
	s_setprio 1
	s_waitcnt lgkmcnt(1)
	v_mfma_f32_32x32x16_bf16 v[112:127], v[208:211], v[224:227], v[112:127]
	v_mfma_f32_32x32x16_bf16 v[48:63], v[212:215], v[224:227], v[48:63]
	s_waitcnt lgkmcnt(0)
	v_mfma_f32_32x32x16_bf16 v[96:111], v[208:211], v[228:231], v[96:111]
	v_mfma_f32_32x32x16_bf16 v[32:47], v[212:215], v[228:231], v[32:47]
	ds_read_b128 v[224:227], v168 offset:9312
	ds_read_b128 v[228:231], v168 offset:13920
	s_waitcnt lgkmcnt(0)
	s_barrier
	s_waitcnt vmcnt(7)
	ds_write_b128 v195, v[178:181]
	s_waitcnt vmcnt(6)
	ds_write_b128 v196, v[216:219]
	ds_read_b128 v[178:181], v192 offset:36864
	ds_read_b128 v[216:219], v192 offset:41472
	v_mfma_f32_32x32x16_bf16 v[80:95], v[208:211], v[224:227], v[80:95]
	v_mfma_f32_32x32x16_bf16 v[16:31], v[212:215], v[224:227], v[16:31]
	ds_read_b128 v[224:227], v184
	v_mfma_f32_32x32x16_bf16 v[64:79], v[208:211], v[228:231], v[64:79]
	v_mfma_f32_32x32x16_bf16 v[0:15], v[212:215], v[228:231], v[0:15]
	ds_read_b128 v[228:231], v184 offset:4608
	s_setprio 0
	global_load_dwordx4 v[208:211], v[128:129], off offset:768
	global_load_dwordx4 v[212:215], v[132:133], off offset:768
	s_setprio 1
	s_waitcnt lgkmcnt(1)
	v_mfma_f32_32x32x16_bf16 v[112:127], v[178:181], v[224:227], v[112:127]
	v_mfma_f32_32x32x16_bf16 v[48:63], v[216:219], v[224:227], v[48:63]
	s_waitcnt lgkmcnt(0)
	v_mfma_f32_32x32x16_bf16 v[96:111], v[178:181], v[228:231], v[96:111]
	v_mfma_f32_32x32x16_bf16 v[32:47], v[216:219], v[228:231], v[32:47]
	ds_read_b128 v[224:227], v184 offset:9216
	ds_read_b128 v[228:231], v184 offset:13824
	s_waitcnt vmcnt(7)
	ds_write_b128 v194, v[172:175]
	s_waitcnt vmcnt(6)
	ds_write_b128 v193, v[220:223]
	ds_read_b128 v[172:175], v192 offset:36896
	ds_read_b128 v[220:223], v192 offset:41504
	s_waitcnt lgkmcnt(5)
	v_mfma_f32_32x32x16_bf16 v[80:95], v[178:181], v[224:227], v[80:95]
	v_mfma_f32_32x32x16_bf16 v[16:31], v[216:219], v[224:227], v[16:31]
	ds_read_b128 v[224:227], v184 offset:32
	s_waitcnt lgkmcnt(5)
	v_mfma_f32_32x32x16_bf16 v[64:79], v[178:181], v[228:231], v[64:79]
	v_mfma_f32_32x32x16_bf16 v[0:15], v[216:219], v[228:231], v[0:15]
	ds_read_b128 v[228:231], v184 offset:4640
	s_setprio 0
	global_load_dwordx4 v[178:181], v[136:137], off offset:768
	global_load_dwordx4 v[216:219], v[140:141], off offset:768
	s_setprio 1
	s_waitcnt lgkmcnt(1)
	v_mfma_f32_32x32x16_bf16 v[112:127], v[172:175], v[224:227], v[112:127]
	v_mfma_f32_32x32x16_bf16 v[48:63], v[220:223], v[224:227], v[48:63]
	s_waitcnt lgkmcnt(0)
	v_mfma_f32_32x32x16_bf16 v[96:111], v[172:175], v[228:231], v[96:111]
	v_mfma_f32_32x32x16_bf16 v[32:47], v[220:223], v[228:231], v[32:47]
	ds_read_b128 v[224:227], v184 offset:9248
	ds_read_b128 v[228:231], v184 offset:13856
	s_waitcnt vmcnt(7)
	ds_write_b128 v177, v[158:161]
	s_waitcnt vmcnt(6)
	ds_write_b128 v176, v[162:165]
	ds_read_b128 v[158:161], v192 offset:36928
	ds_read_b128 v[162:165], v192 offset:41536
	s_waitcnt lgkmcnt(5)
; template <bool trans>
; DI void gemm_core(const GTile& tl, const GTile& nx, bool has_next  , bool chain  , bool pre, u32x4 (&ra)[4], u32x4 (&rb)[4], char* smem, f32x16 (&acc)[2][4]) {
;     ...
;   const int nk = K / 64;
;   if (!pre) { G_LOAD(0); G_STORE(0); G_LOAD(1); }
;   for (int kt = 0; kt < nk; ++kt) {
;     __syncthreads();
;     G_COMPUTE(kt & 1, kt);
	v_mfma_f32_32x32x16_bf16 v[80:95], v[172:175], v[224:227], v[80:95]
	v_mfma_f32_32x32x16_bf16 v[16:31], v[220:223], v[224:227], v[16:31]
	ds_read_b128 v[224:227], v184 offset:64
	s_waitcnt lgkmcnt(5)
	v_mfma_f32_32x32x16_bf16 v[64:79], v[172:175], v[228:231], v[64:79]
	v_mfma_f32_32x32x16_bf16 v[0:15], v[220:223], v[228:231], v[0:15]
	ds_read_b128 v[228:231], v184 offset:4672
	s_setprio 0
	global_load_dwordx4 v[172:175], v[144:145], off offset:768
	global_load_dwordx4 v[220:223], v[148:149], off offset:768
	s_setprio 1
	s_waitcnt lgkmcnt(1)
	v_mfma_f32_32x32x16_bf16 v[112:127], v[158:161], v[224:227], v[112:127]
	v_mfma_f32_32x32x16_bf16 v[48:63], v[162:165], v[224:227], v[48:63]
	s_waitcnt lgkmcnt(0)
	v_mfma_f32_32x32x16_bf16 v[96:111], v[158:161], v[228:231], v[96:111]
	v_mfma_f32_32x32x16_bf16 v[32:47], v[162:165], v[228:231], v[32:47]
	ds_read_b128 v[224:227], v184 offset:9280
	ds_read_b128 v[228:231], v184 offset:13888
	s_waitcnt vmcnt(7)
	ds_write_b128 v171, v[198:201]
	s_waitcnt vmcnt(6)
	ds_write_b128 v170, v[202:205]
	ds_read_b128 v[198:201], v192 offset:36960
	ds_read_b128 v[202:205], v192 offset:41568
	s_waitcnt lgkmcnt(5)
	v_mfma_f32_32x32x16_bf16 v[80:95], v[158:161], v[224:227], v[80:95]
	v_mfma_f32_32x32x16_bf16 v[16:31], v[162:165], v[224:227], v[16:31]
	ds_read_b128 v[224:227], v184 offset:96
	s_waitcnt lgkmcnt(5)
	v_mfma_f32_32x32x16_bf16 v[64:79], v[158:161], v[228:231], v[64:79]
	v_mfma_f32_32x32x16_bf16 v[0:15], v[162:165], v[228:231], v[0:15]
	ds_read_b128 v[228:231], v184 offset:4704
	s_setprio 0
	global_load_dwordx4 v[158:161], v[152:153], off offset:768
	global_load_dwordx4 v[162:165], v[156:157], off offset:768
	s_setprio 1
	s_waitcnt lgkmcnt(1)
	v_mfma_f32_32x32x16_bf16 v[112:127], v[198:201], v[224:227], v[112:127]
	v_mfma_f32_32x32x16_bf16 v[48:63], v[202:205], v[224:227], v[48:63]
	s_waitcnt lgkmcnt(0)
	v_mfma_f32_32x32x16_bf16 v[96:111], v[198:201], v[228:231], v[96:111]
	v_mfma_f32_32x32x16_bf16 v[32:47], v[202:205], v[228:231], v[32:47]
	ds_read_b128 v[224:227], v184 offset:9312
	ds_read_b128 v[228:231], v184 offset:13920
	s_waitcnt lgkmcnt(0)
	s_barrier
	s_waitcnt vmcnt(7)
	ds_write_b128 v191, v[208:211]
	s_waitcnt vmcnt(6)
	ds_write_b128 v191, v[212:215] offset:36864
	ds_read_b128 v[208:211], v169
	ds_read_b128 v[212:215], v169 offset:4608
	v_mfma_f32_32x32x16_bf16 v[80:95], v[198:201], v[224:227], v[80:95]
	v_mfma_f32_32x32x16_bf16 v[16:31], v[202:205], v[224:227], v[16:31]
	ds_read_b128 v[224:227], v168
	v_mfma_f32_32x32x16_bf16 v[64:79], v[198:201], v[228:231], v[64:79]
	v_mfma_f32_32x32x16_bf16 v[0:15], v[202:205], v[228:231], v[0:15]
	ds_read_b128 v[228:231], v168 offset:4608
	s_setprio 0
	global_load_dwordx4 v[198:201], v[128:129], off offset:896
	global_load_dwordx4 v[202:205], v[132:133], off offset:896
	s_setprio 1
	s_waitcnt lgkmcnt(1)
	v_mfma_f32_32x32x16_bf16 v[112:127], v[208:211], v[224:227], v[112:127]
	v_mfma_f32_32x32x16_bf16 v[48:63], v[212:215], v[224:227], v[48:63]
	s_waitcnt lgkmcnt(0)
	v_mfma_f32_32x32x16_bf16 v[96:111], v[208:211], v[228:231], v[96:111]
	v_mfma_f32_32x32x16_bf16 v[32:47], v[212:215], v[228:231], v[32:47]
	ds_read_b128 v[224:227], v168 offset:9216
	ds_read_b128 v[228:231], v168 offset:13824
	s_waitcnt vmcnt(7)
	ds_write_b128 v191, v[178:181] offset:9216
	s_waitcnt vmcnt(6)
	ds_write_b128 v191, v[216:219] offset:46080
	ds_read_b128 v[178:181], v169 offset:32
	ds_read_b128 v[216:219], v169 offset:4640
	s_waitcnt lgkmcnt(5)
	v_mfma_f32_32x32x16_bf16 v[80:95], v[208:211], v[224:227], v[80:95]
	v_mfma_f32_32x32x16_bf16 v[16:31], v[212:215], v[224:227], v[16:31]
	ds_read_b128 v[224:227], v168 offset:32
	s_waitcnt lgkmcnt(5)
	v_mfma_f32_32x32x16_bf16 v[64:79], v[208:211], v[228:231], v[64:79]
	v_mfma_f32_32x32x16_bf16 v[0:15], v[212:215], v[228:231], v[0:15]
	ds_read_b128 v[228:231], v168 offset:4640
	s_setprio 0
	global_load_dwordx4 v[208:211], v[136:137], off offset:896
	global_load_dwordx4 v[212:215], v[140:141], off offset:896
	s_setprio 1
	s_waitcnt lgkmcnt(1)
	v_mfma_f32_32x32x16_bf16 v[112:127], v[178:181], v[224:227], v[112:127]
	v_mfma_f32_32x32x16_bf16 v[48:63], v[216:219], v[224:227], v[48:63]
	s_waitcnt lgkmcnt(0)
	v_mfma_f32_32x32x16_bf16 v[96:111], v[178:181], v[228:231], v[96:111]
	v_mfma_f32_32x32x16_bf16 v[32:47], v[216:219], v[228:231], v[32:47]
	ds_read_b128 v[224:227], v168 offset:9248
	ds_read_b128 v[228:231], v168 offset:13856
	s_waitcnt vmcnt(7)
	ds_write_b128 v191, v[172:175] offset:18432
	s_waitcnt vmcnt(6)
	ds_write_b128 v191, v[220:223] offset:55296
	ds_read_b128 v[172:175], v169 offset:64
	ds_read_b128 v[220:223], v169 offset:4672
	s_waitcnt lgkmcnt(5)
	v_mfma_f32_32x32x16_bf16 v[80:95], v[178:181], v[224:227], v[80:95]
	v_mfma_f32_32x32x16_bf16 v[16:31], v[216:219], v[224:227], v[16:31]
	ds_read_b128 v[224:227], v168 offset:64
	s_waitcnt lgkmcnt(5)
	v_mfma_f32_32x32x16_bf16 v[64:79], v[178:181], v[228:231], v[64:79]
	v_mfma_f32_32x32x16_bf16 v[0:15], v[216:219], v[228:231], v[0:15]
	ds_read_b128 v[228:231], v168 offset:4672
	s_setprio 0
	global_load_dwordx4 v[178:181], v[144:145], off offset:896
	global_load_dwordx4 v[216:219], v[148:149], off offset:896
	s_setprio 1
	s_waitcnt lgkmcnt(1)
	v_mfma_f32_32x32x16_bf16 v[112:127], v[172:175], v[224:227], v[112:127]
	v_mfma_f32_32x32x16_bf16 v[48:63], v[220:223], v[224:227], v[48:63]
	s_waitcnt lgkmcnt(0)
	v_mfma_f32_32x32x16_bf16 v[96:111], v[172:175], v[228:231], v[96:111]
	v_mfma_f32_32x32x16_bf16 v[32:47], v[220:223], v[228:231], v[32:47]
	ds_read_b128 v[224:227], v168 offset:9280
	ds_read_b128 v[228:231], v168 offset:13888
	s_waitcnt vmcnt(7)
	ds_write_b128 v191, v[158:161] offset:27648
	s_waitcnt vmcnt(6)
	ds_write_b128 v191, v[162:165] offset:64512
	ds_read_b128 v[158:161], v169 offset:96
	ds_read_b128 v[162:165], v169 offset:4704
	s_waitcnt lgkmcnt(5)
	v_mfma_f32_32x32x16_bf16 v[80:95], v[172:175], v[224:227], v[80:95]
	v_mfma_f32_32x32x16_bf16 v[16:31], v[220:223], v[224:227], v[16:31]
	ds_read_b128 v[224:227], v168 offset:96
	s_waitcnt lgkmcnt(5)
	v_mfma_f32_32x32x16_bf16 v[64:79], v[172:175], v[228:231], v[64:79]
	v_mfma_f32_32x32x16_bf16 v[0:15], v[220:223], v[228:231], v[0:15]
	ds_read_b128 v[228:231], v168 offset:4704
	s_setprio 0
	global_load_dwordx4 v[172:175], v[152:153], off offset:896
	global_load_dwordx4 v[220:223], v[156:157], off offset:896
	s_setprio 1
	s_waitcnt lgkmcnt(1)
	v_mfma_f32_32x32x16_bf16 v[112:127], v[158:161], v[224:227], v[112:127]
	v_mfma_f32_32x32x16_bf16 v[48:63], v[162:165], v[224:227], v[48:63]
	s_waitcnt lgkmcnt(0)
	v_mfma_f32_32x32x16_bf16 v[96:111], v[158:161], v[228:231], v[96:111]
	v_mfma_f32_32x32x16_bf16 v[32:47], v[162:165], v[228:231], v[32:47]
	ds_read_b128 v[224:227], v168 offset:9312
	ds_read_b128 v[228:231], v168 offset:13920
	s_waitcnt lgkmcnt(0)
	s_barrier
; template <bool trans>
; DI void gemm_core(const GTile& tl, const GTile& nx, bool has_next  , bool chain  , bool pre, u32x4 (&ra)[4], u32x4 (&rb)[4], char* smem, f32x16 (&acc)[2][4]) {
;     ...
;   const int nk = K / 64;
;   if (!pre) { G_LOAD(0); G_STORE(0); G_LOAD(1); }
;   for (int kt = 0; kt < nk; ++kt) {
;     __syncthreads();
;     G_COMPUTE(kt & 1, kt);
	s_waitcnt vmcnt(7)
	ds_write_b128 v195, v[198:201]
	s_waitcnt vmcnt(6)
	ds_write_b128 v196, v[202:205]
	ds_read_b128 v[198:201], v192 offset:36864
	ds_read_b128 v[202:205], v192 offset:41472
	v_mfma_f32_32x32x16_bf16 v[80:95], v[158:161], v[224:227], v[80:95]
	v_mfma_f32_32x32x16_bf16 v[16:31], v[162:165], v[224:227], v[16:31]
	ds_read_b128 v[224:227], v184
	v_mfma_f32_32x32x16_bf16 v[64:79], v[158:161], v[228:231], v[64:79]
	v_mfma_f32_32x32x16_bf16 v[0:15], v[162:165], v[228:231], v[0:15]
	ds_read_b128 v[228:231], v184 offset:4608
	s_setprio 0
	global_load_dwordx4 v[158:161], v[128:129], off offset:1024
	global_load_dwordx4 v[162:165], v[132:133], off offset:1024
	s_setprio 1
	s_waitcnt lgkmcnt(1)
	v_mfma_f32_32x32x16_bf16 v[112:127], v[198:201], v[224:227], v[112:127]
	v_mfma_f32_32x32x16_bf16 v[48:63], v[202:205], v[224:227], v[48:63]
	s_waitcnt lgkmcnt(0)
	v_mfma_f32_32x32x16_bf16 v[96:111], v[198:201], v[228:231], v[96:111]
	v_mfma_f32_32x32x16_bf16 v[32:47], v[202:205], v[228:231], v[32:47]
	ds_read_b128 v[224:227], v184 offset:9216
	ds_read_b128 v[228:231], v184 offset:13824
	s_waitcnt vmcnt(7)
	ds_write_b128 v194, v[208:211]
	s_waitcnt vmcnt(6)
	ds_write_b128 v193, v[212:215]
	ds_read_b128 v[208:211], v192 offset:36896
	ds_read_b128 v[212:215], v192 offset:41504
	s_waitcnt lgkmcnt(5)
	v_mfma_f32_32x32x16_bf16 v[80:95], v[198:201], v[224:227], v[80:95]
	v_mfma_f32_32x32x16_bf16 v[16:31], v[202:205], v[224:227], v[16:31]
	ds_read_b128 v[224:227], v184 offset:32
	s_waitcnt lgkmcnt(5)
	v_mfma_f32_32x32x16_bf16 v[64:79], v[198:201], v[228:231], v[64:79]
	v_mfma_f32_32x32x16_bf16 v[0:15], v[202:205], v[228:231], v[0:15]
	ds_read_b128 v[228:231], v184 offset:4640
	s_setprio 0
	global_load_dwordx4 v[198:201], v[136:137], off offset:1024
	global_load_dwordx4 v[202:205], v[140:141], off offset:1024
	s_setprio 1
	s_waitcnt lgkmcnt(1)
	v_mfma_f32_32x32x16_bf16 v[112:127], v[208:211], v[224:227], v[112:127]
	v_mfma_f32_32x32x16_bf16 v[48:63], v[212:215], v[224:227], v[48:63]
	s_waitcnt lgkmcnt(0)
	v_mfma_f32_32x32x16_bf16 v[96:111], v[208:211], v[228:231], v[96:111]
	v_mfma_f32_32x32x16_bf16 v[32:47], v[212:215], v[228:231], v[32:47]
	ds_read_b128 v[224:227], v184 offset:9248
	ds_read_b128 v[228:231], v184 offset:13856
	s_waitcnt vmcnt(7)
	ds_write_b128 v177, v[178:181]
	s_waitcnt vmcnt(6)
	ds_write_b128 v176, v[216:219]
	ds_read_b128 v[178:181], v192 offset:36928
	ds_read_b128 v[216:219], v192 offset:41536
	s_waitcnt lgkmcnt(5)
	v_mfma_f32_32x32x16_bf16 v[80:95], v[208:211], v[224:227], v[80:95]
	v_mfma_f32_32x32x16_bf16 v[16:31], v[212:215], v[224:227], v[16:31]
	ds_read_b128 v[224:227], v184 offset:64
	s_waitcnt lgkmcnt(5)
	v_mfma_f32_32x32x16_bf16 v[64:79], v[208:211], v[228:231], v[64:79]
	v_mfma_f32_32x32x16_bf16 v[0:15], v[212:215], v[228:231], v[0:15]
	ds_read_b128 v[228:231], v184 offset:4672
	s_setprio 0
	global_load_dwordx4 v[208:211], v[144:145], off offset:1024
	global_load_dwordx4 v[212:215], v[148:149], off offset:1024
	s_setprio 1
	s_waitcnt lgkmcnt(1)
	v_mfma_f32_32x32x16_bf16 v[112:127], v[178:181], v[224:227], v[112:127]
	v_mfma_f32_32x32x16_bf16 v[48:63], v[216:219], v[224:227], v[48:63]
	s_waitcnt lgkmcnt(0)
	v_mfma_f32_32x32x16_bf16 v[96:111], v[178:181], v[228:231], v[96:111]
	v_mfma_f32_32x32x16_bf16 v[32:47], v[216:219], v[228:231], v[32:47]
	ds_read_b128 v[224:227], v184 offset:9280
	ds_read_b128 v[228:231], v184 offset:13888
	s_waitcnt vmcnt(7)
	ds_write_b128 v171, v[172:175]
	s_waitcnt vmcnt(6)
	ds_write_b128 v170, v[220:223]
	ds_read_b128 v[172:175], v192 offset:36960
	ds_read_b128 v[220:223], v192 offset:41568
	s_waitcnt lgkmcnt(5)
	v_mfma_f32_32x32x16_bf16 v[80:95], v[178:181], v[224:227], v[80:95]
	v_mfma_f32_32x32x16_bf16 v[16:31], v[216:219], v[224:227], v[16:31]
	ds_read_b128 v[224:227], v184 offset:96
	s_waitcnt lgkmcnt(5)
	v_mfma_f32_32x32x16_bf16 v[64:79], v[178:181], v[228:231], v[64:79]
	v_mfma_f32_32x32x16_bf16 v[0:15], v[216:219], v[228:231], v[0:15]
	ds_read_b128 v[228:231], v184 offset:4704
	s_setprio 0
	global_load_dwordx4 v[178:181], v[152:153], off offset:1024
	global_load_dwordx4 v[216:219], v[156:157], off offset:1024
	s_setprio 1
	s_waitcnt lgkmcnt(1)
	v_mfma_f32_32x32x16_bf16 v[112:127], v[172:175], v[224:227], v[112:127]
	v_mfma_f32_32x32x16_bf16 v[48:63], v[220:223], v[224:227], v[48:63]
	s_waitcnt lgkmcnt(0)
	v_mfma_f32_32x32x16_bf16 v[96:111], v[172:175], v[228:231], v[96:111]
	v_mfma_f32_32x32x16_bf16 v[32:47], v[220:223], v[228:231], v[32:47]
	ds_read_b128 v[224:227], v184 offset:9312
	ds_read_b128 v[228:231], v184 offset:13920
	s_waitcnt lgkmcnt(0)
	s_barrier
; template <bool trans>
; DI void gemm_core(const GTile& tl, const GTile& nx, bool has_next  , bool chain  , bool pre, u32x4 (&ra)[4], u32x4 (&rb)[4], char* smem, f32x16 (&acc)[2][4]) {
;     ...
;   const int nk = K / 64;
;   if (!pre) { G_LOAD(0); G_STORE(0); G_LOAD(1); }
;   for (int kt = 0; kt < nk; ++kt) {
;     __syncthreads();
;     G_COMPUTE(kt & 1, kt);
	s_waitcnt vmcnt(7)
	ds_write_b128 v191, v[158:161]
	s_waitcnt vmcnt(6)
	ds_write_b128 v191, v[162:165] offset:36864
	ds_read_b128 v[158:161], v169
	ds_read_b128 v[162:165], v169 offset:4608
	v_mfma_f32_32x32x16_bf16 v[80:95], v[172:175], v[224:227], v[80:95]
	v_mfma_f32_32x32x16_bf16 v[16:31], v[220:223], v[224:227], v[16:31]
	ds_read_b128 v[224:227], v168
	v_mfma_f32_32x32x16_bf16 v[64:79], v[172:175], v[228:231], v[64:79]
	v_mfma_f32_32x32x16_bf16 v[0:15], v[220:223], v[228:231], v[0:15]
	ds_read_b128 v[228:231], v168 offset:4608
	s_setprio 0
	global_load_dwordx4 v[172:175], v[128:129], off offset:1152
	global_load_dwordx4 v[220:223], v[132:133], off offset:1152
	s_setprio 1
	s_waitcnt lgkmcnt(1)
	v_mfma_f32_32x32x16_bf16 v[112:127], v[158:161], v[224:227], v[112:127]
	v_mfma_f32_32x32x16_bf16 v[48:63], v[162:165], v[224:227], v[48:63]
	s_waitcnt lgkmcnt(0)
	v_mfma_f32_32x32x16_bf16 v[96:111], v[158:161], v[228:231], v[96:111]
	v_mfma_f32_32x32x16_bf16 v[32:47], v[162:165], v[228:231], v[32:47]
	ds_read_b128 v[224:227], v168 offset:9216
	ds_read_b128 v[228:231], v168 offset:13824
	s_waitcnt vmcnt(7)
	ds_write_b128 v191, v[198:201] offset:9216
	s_waitcnt vmcnt(6)
	ds_write_b128 v191, v[202:205] offset:46080
	ds_read_b128 v[198:201], v169 offset:32
	ds_read_b128 v[202:205], v169 offset:4640
	s_waitcnt lgkmcnt(5)
	v_mfma_f32_32x32x16_bf16 v[80:95], v[158:161], v[224:227], v[80:95]
	v_mfma_f32_32x32x16_bf16 v[16:31], v[162:165], v[224:227], v[16:31]
	ds_read_b128 v[224:227], v168 offset:32
	s_waitcnt lgkmcnt(5)
	v_mfma_f32_32x32x16_bf16 v[64:79], v[158:161], v[228:231], v[64:79]
	v_mfma_f32_32x32x16_bf16 v[0:15], v[162:165], v[228:231], v[0:15]
	ds_read_b128 v[228:231], v168 offset:4640
	s_setprio 0
	global_load_dwordx4 v[158:161], v[136:137], off offset:1152
	global_load_dwordx4 v[162:165], v[140:141], off offset:1152
	s_setprio 1
	s_waitcnt lgkmcnt(1)
	v_mfma_f32_32x32x16_bf16 v[112:127], v[198:201], v[224:227], v[112:127]
	v_mfma_f32_32x32x16_bf16 v[48:63], v[202:205], v[224:227], v[48:63]
	s_waitcnt lgkmcnt(0)
	v_mfma_f32_32x32x16_bf16 v[96:111], v[198:201], v[228:231], v[96:111]
	v_mfma_f32_32x32x16_bf16 v[32:47], v[202:205], v[228:231], v[32:47]
	ds_read_b128 v[224:227], v168 offset:9248
	ds_read_b128 v[228:231], v168 offset:13856
	s_waitcnt vmcnt(7)
	ds_write_b128 v191, v[208:211] offset:18432
	s_waitcnt vmcnt(6)
	ds_write_b128 v191, v[212:215] offset:55296
	ds_read_b128 v[208:211], v169 offset:64
	ds_read_b128 v[212:215], v169 offset:4672
	s_waitcnt lgkmcnt(5)
	v_mfma_f32_32x32x16_bf16 v[80:95], v[198:201], v[224:227], v[80:95]
	v_mfma_f32_32x32x16_bf16 v[16:31], v[202:205], v[224:227], v[16:31]
	ds_read_b128 v[224:227], v168 offset:64
	s_waitcnt lgkmcnt(5)
	v_mfma_f32_32x32x16_bf16 v[64:79], v[198:201], v[228:231], v[64:79]
	v_mfma_f32_32x32x16_bf16 v[0:15], v[202:205], v[228:231], v[0:15]
	ds_read_b128 v[228:231], v168 offset:4672
	s_setprio 0
	global_load_dwordx4 v[198:201], v[144:145], off offset:1152
	global_load_dwordx4 v[202:205], v[148:149], off offset:1152
	s_setprio 1
	s_waitcnt lgkmcnt(1)
	v_mfma_f32_32x32x16_bf16 v[112:127], v[208:211], v[224:227], v[112:127]
	v_mfma_f32_32x32x16_bf16 v[48:63], v[212:215], v[224:227], v[48:63]
	s_waitcnt lgkmcnt(0)
	v_mfma_f32_32x32x16_bf16 v[96:111], v[208:211], v[228:231], v[96:111]
	v_mfma_f32_32x32x16_bf16 v[32:47], v[212:215], v[228:231], v[32:47]
	ds_read_b128 v[224:227], v168 offset:9280
	ds_read_b128 v[228:231], v168 offset:13888
	s_waitcnt vmcnt(7)
	ds_write_b128 v191, v[178:181] offset:27648
	s_waitcnt vmcnt(6)
	ds_write_b128 v191, v[216:219] offset:64512
	ds_read_b128 v[178:181], v169 offset:96
	ds_read_b128 v[216:219], v169 offset:4704
	s_waitcnt lgkmcnt(5)
	v_mfma_f32_32x32x16_bf16 v[80:95], v[208:211], v[224:227], v[80:95]
	v_mfma_f32_32x32x16_bf16 v[16:31], v[212:215], v[224:227], v[16:31]
	ds_read_b128 v[224:227], v168 offset:96
	s_waitcnt lgkmcnt(5)
	v_mfma_f32_32x32x16_bf16 v[64:79], v[208:211], v[228:231], v[64:79]
	v_mfma_f32_32x32x16_bf16 v[0:15], v[212:215], v[228:231], v[0:15]
	ds_read_b128 v[228:231], v168 offset:4704
	s_setprio 0
	global_load_dwordx4 v[208:211], v[152:153], off offset:1152
	global_load_dwordx4 v[212:215], v[156:157], off offset:1152
	s_setprio 1
	s_waitcnt lgkmcnt(1)
	v_mfma_f32_32x32x16_bf16 v[112:127], v[178:181], v[224:227], v[112:127]
	v_mfma_f32_32x32x16_bf16 v[48:63], v[216:219], v[224:227], v[48:63]
	s_waitcnt lgkmcnt(0)
	v_mfma_f32_32x32x16_bf16 v[96:111], v[178:181], v[228:231], v[96:111]
	v_mfma_f32_32x32x16_bf16 v[32:47], v[216:219], v[228:231], v[32:47]
	ds_read_b128 v[224:227], v168 offset:9312
	ds_read_b128 v[228:231], v168 offset:13920
	s_waitcnt lgkmcnt(0)
	s_barrier
; template <bool trans>
; DI void gemm_core(const GTile& tl, const GTile& nx, bool has_next  , bool chain  , bool pre, u32x4 (&ra)[4], u32x4 (&rb)[4], char* smem, f32x16 (&acc)[2][4]) {
;     ...
;   const int nk = K / 64;
;   if (!pre) { G_LOAD(0); G_STORE(0); G_LOAD(1); }
;   for (int kt = 0; kt < nk; ++kt) {
;     __syncthreads();
;     G_COMPUTE(kt & 1, kt);
	s_waitcnt vmcnt(7)
	ds_write_b128 v195, v[172:175]
	s_waitcnt vmcnt(6)
	ds_write_b128 v196, v[220:223]
	ds_read_b128 v[172:175], v192 offset:36864
	ds_read_b128 v[220:223], v192 offset:41472
	v_mfma_f32_32x32x16_bf16 v[80:95], v[178:181], v[224:227], v[80:95]
	v_mfma_f32_32x32x16_bf16 v[16:31], v[216:219], v[224:227], v[16:31]
	ds_read_b128 v[224:227], v184
	v_mfma_f32_32x32x16_bf16 v[64:79], v[178:181], v[228:231], v[64:79]
	v_mfma_f32_32x32x16_bf16 v[0:15], v[216:219], v[228:231], v[0:15]
	ds_read_b128 v[228:231], v184 offset:4608
	s_setprio 0
	global_load_dwordx4 v[178:181], v[128:129], off offset:1280
	global_load_dwordx4 v[216:219], v[132:133], off offset:1280
	s_setprio 1
	s_waitcnt lgkmcnt(1)
	v_mfma_f32_32x32x16_bf16 v[112:127], v[172:175], v[224:227], v[112:127]
	v_mfma_f32_32x32x16_bf16 v[48:63], v[220:223], v[224:227], v[48:63]
	s_waitcnt lgkmcnt(0)
	v_mfma_f32_32x32x16_bf16 v[96:111], v[172:175], v[228:231], v[96:111]
	v_mfma_f32_32x32x16_bf16 v[32:47], v[220:223], v[228:231], v[32:47]
	ds_read_b128 v[224:227], v184 offset:9216
	ds_read_b128 v[228:231], v184 offset:13824
	s_waitcnt vmcnt(7)
	ds_write_b128 v194, v[158:161]
	s_waitcnt vmcnt(6)
	ds_write_b128 v193, v[162:165]
	ds_read_b128 v[158:161], v192 offset:36896
	ds_read_b128 v[162:165], v192 offset:41504
	s_waitcnt lgkmcnt(5)
	v_mfma_f32_32x32x16_bf16 v[80:95], v[172:175], v[224:227], v[80:95]
	v_mfma_f32_32x32x16_bf16 v[16:31], v[220:223], v[224:227], v[16:31]
	ds_read_b128 v[224:227], v184 offset:32
	s_waitcnt lgkmcnt(5)
	v_mfma_f32_32x32x16_bf16 v[64:79], v[172:175], v[228:231], v[64:79]
	v_mfma_f32_32x32x16_bf16 v[0:15], v[220:223], v[228:231], v[0:15]
	ds_read_b128 v[228:231], v184 offset:4640
	s_setprio 0
	global_load_dwordx4 v[172:175], v[136:137], off offset:1280
	global_load_dwordx4 v[220:223], v[140:141], off offset:1280
	s_setprio 1
	s_waitcnt lgkmcnt(1)
	v_mfma_f32_32x32x16_bf16 v[112:127], v[158:161], v[224:227], v[112:127]
	v_mfma_f32_32x32x16_bf16 v[48:63], v[162:165], v[224:227], v[48:63]
	s_waitcnt lgkmcnt(0)
	v_mfma_f32_32x32x16_bf16 v[96:111], v[158:161], v[228:231], v[96:111]
	v_mfma_f32_32x32x16_bf16 v[32:47], v[162:165], v[228:231], v[32:47]
	ds_read_b128 v[224:227], v184 offset:9248
	ds_read_b128 v[228:231], v184 offset:13856
	s_waitcnt vmcnt(7)
	ds_write_b128 v177, v[198:201]
	s_waitcnt vmcnt(6)
	ds_write_b128 v176, v[202:205]
	ds_read_b128 v[198:201], v192 offset:36928
	ds_read_b128 v[202:205], v192 offset:41536
	s_waitcnt lgkmcnt(5)
	v_mfma_f32_32x32x16_bf16 v[80:95], v[158:161], v[224:227], v[80:95]
	v_mfma_f32_32x32x16_bf16 v[16:31], v[162:165], v[224:227], v[16:31]
	ds_read_b128 v[224:227], v184 offset:64
	s_waitcnt lgkmcnt(5)
	v_mfma_f32_32x32x16_bf16 v[64:79], v[158:161], v[228:231], v[64:79]
	v_mfma_f32_32x32x16_bf16 v[0:15], v[162:165], v[228:231], v[0:15]
	ds_read_b128 v[228:231], v184 offset:4672
	s_setprio 0
	global_load_dwordx4 v[158:161], v[144:145], off offset:1280
	global_load_dwordx4 v[162:165], v[148:149], off offset:1280
	s_setprio 1
	s_waitcnt lgkmcnt(1)
	v_mfma_f32_32x32x16_bf16 v[112:127], v[198:201], v[224:227], v[112:127]
	v_mfma_f32_32x32x16_bf16 v[48:63], v[202:205], v[224:227], v[48:63]
	s_waitcnt lgkmcnt(0)
	v_mfma_f32_32x32x16_bf16 v[96:111], v[198:201], v[228:231], v[96:111]
	v_mfma_f32_32x32x16_bf16 v[32:47], v[202:205], v[228:231], v[32:47]
	ds_read_b128 v[224:227], v184 offset:9280
	ds_read_b128 v[228:231], v184 offset:13888
	s_waitcnt vmcnt(7)
	ds_write_b128 v171, v[208:211]
	s_waitcnt vmcnt(6)
	ds_write_b128 v170, v[212:215]
	ds_read_b128 v[208:211], v192 offset:36960
	ds_read_b128 v[212:215], v192 offset:41568
	s_waitcnt lgkmcnt(5)
	v_mfma_f32_32x32x16_bf16 v[80:95], v[198:201], v[224:227], v[80:95]
	v_mfma_f32_32x32x16_bf16 v[16:31], v[202:205], v[224:227], v[16:31]
	ds_read_b128 v[224:227], v184 offset:96
	s_waitcnt lgkmcnt(5)
	v_mfma_f32_32x32x16_bf16 v[64:79], v[198:201], v[228:231], v[64:79]
	v_mfma_f32_32x32x16_bf16 v[0:15], v[202:205], v[228:231], v[0:15]
	ds_read_b128 v[228:231], v184 offset:4704
	s_setprio 0
	global_load_dwordx4 v[198:201], v[152:153], off offset:1280
	global_load_dwordx4 v[202:205], v[156:157], off offset:1280
	s_setprio 1
	s_waitcnt lgkmcnt(1)
	v_mfma_f32_32x32x16_bf16 v[112:127], v[208:211], v[224:227], v[112:127]
	v_mfma_f32_32x32x16_bf16 v[48:63], v[212:215], v[224:227], v[48:63]
	s_waitcnt lgkmcnt(0)
	v_mfma_f32_32x32x16_bf16 v[96:111], v[208:211], v[228:231], v[96:111]
	v_mfma_f32_32x32x16_bf16 v[32:47], v[212:215], v[228:231], v[32:47]
	ds_read_b128 v[224:227], v184 offset:9312
	ds_read_b128 v[228:231], v184 offset:13920
	s_waitcnt lgkmcnt(0)
	s_barrier
; template <bool trans>
; DI void gemm_core(const GTile& tl, const GTile& nx, bool has_next  , bool chain  , bool pre, u32x4 (&ra)[4], u32x4 (&rb)[4], char* smem, f32x16 (&acc)[2][4]) {
;     ...
;   const int nk = K / 64;
;   if (!pre) { G_LOAD(0); G_STORE(0); G_LOAD(1); }
;   for (int kt = 0; kt < nk; ++kt) {
;     __syncthreads();
;     G_COMPUTE(kt & 1, kt);
	s_waitcnt vmcnt(7)
	ds_write_b128 v191, v[178:181]
	s_waitcnt vmcnt(6)
	ds_write_b128 v191, v[216:219] offset:36864
	ds_read_b128 v[178:181], v169
	ds_read_b128 v[216:219], v169 offset:4608
	v_mfma_f32_32x32x16_bf16 v[80:95], v[208:211], v[224:227], v[80:95]
	v_mfma_f32_32x32x16_bf16 v[16:31], v[212:215], v[224:227], v[16:31]
	ds_read_b128 v[224:227], v168
	v_mfma_f32_32x32x16_bf16 v[64:79], v[208:211], v[228:231], v[64:79]
	v_mfma_f32_32x32x16_bf16 v[0:15], v[212:215], v[228:231], v[0:15]
	ds_read_b128 v[228:231], v168 offset:4608
	s_setprio 0
	global_load_dwordx4 v[208:211], v[128:129], off offset:1408
	global_load_dwordx4 v[212:215], v[132:133], off offset:1408
	s_setprio 1
	s_waitcnt lgkmcnt(1)
	v_mfma_f32_32x32x16_bf16 v[112:127], v[178:181], v[224:227], v[112:127]
	v_mfma_f32_32x32x16_bf16 v[48:63], v[216:219], v[224:227], v[48:63]
	s_waitcnt lgkmcnt(0)
	v_mfma_f32_32x32x16_bf16 v[96:111], v[178:181], v[228:231], v[96:111]
	v_mfma_f32_32x32x16_bf16 v[32:47], v[216:219], v[228:231], v[32:47]
	ds_read_b128 v[224:227], v168 offset:9216
	ds_read_b128 v[228:231], v168 offset:13824
	s_waitcnt vmcnt(7)
	ds_write_b128 v191, v[172:175] offset:9216
	s_waitcnt vmcnt(6)
	ds_write_b128 v191, v[220:223] offset:46080
	ds_read_b128 v[172:175], v169 offset:32
	ds_read_b128 v[220:223], v169 offset:4640
	s_waitcnt lgkmcnt(5)
	v_mfma_f32_32x32x16_bf16 v[80:95], v[178:181], v[224:227], v[80:95]
	v_mfma_f32_32x32x16_bf16 v[16:31], v[216:219], v[224:227], v[16:31]
	ds_read_b128 v[224:227], v168 offset:32
	s_waitcnt lgkmcnt(5)
	v_mfma_f32_32x32x16_bf16 v[64:79], v[178:181], v[228:231], v[64:79]
	v_mfma_f32_32x32x16_bf16 v[0:15], v[216:219], v[228:231], v[0:15]
	ds_read_b128 v[228:231], v168 offset:4640
	s_setprio 0
	global_load_dwordx4 v[178:181], v[136:137], off offset:1408
	global_load_dwordx4 v[216:219], v[140:141], off offset:1408
	s_setprio 1
	s_waitcnt lgkmcnt(1)
	v_mfma_f32_32x32x16_bf16 v[112:127], v[172:175], v[224:227], v[112:127]
	v_mfma_f32_32x32x16_bf16 v[48:63], v[220:223], v[224:227], v[48:63]
	s_waitcnt lgkmcnt(0)
	v_mfma_f32_32x32x16_bf16 v[96:111], v[172:175], v[228:231], v[96:111]
	v_mfma_f32_32x32x16_bf16 v[32:47], v[220:223], v[228:231], v[32:47]
	ds_read_b128 v[224:227], v168 offset:9248
	ds_read_b128 v[228:231], v168 offset:13856
	s_waitcnt vmcnt(7)
	ds_write_b128 v191, v[158:161] offset:18432
	s_waitcnt vmcnt(6)
	ds_write_b128 v191, v[162:165] offset:55296
	ds_read_b128 v[158:161], v169 offset:64
	ds_read_b128 v[162:165], v169 offset:4672
	s_waitcnt lgkmcnt(5)
	v_mfma_f32_32x32x16_bf16 v[80:95], v[172:175], v[224:227], v[80:95]
	v_mfma_f32_32x32x16_bf16 v[16:31], v[220:223], v[224:227], v[16:31]
	ds_read_b128 v[224:227], v168 offset:64
	s_waitcnt lgkmcnt(5)
	v_mfma_f32_32x32x16_bf16 v[64:79], v[172:175], v[228:231], v[64:79]
	v_mfma_f32_32x32x16_bf16 v[0:15], v[220:223], v[228:231], v[0:15]
	ds_read_b128 v[228:231], v168 offset:4672
	s_setprio 0
	global_load_dwordx4 v[172:175], v[144:145], off offset:1408
	global_load_dwordx4 v[220:223], v[148:149], off offset:1408
	s_setprio 1
	s_waitcnt lgkmcnt(1)
	v_mfma_f32_32x32x16_bf16 v[112:127], v[158:161], v[224:227], v[112:127]
	v_mfma_f32_32x32x16_bf16 v[48:63], v[162:165], v[224:227], v[48:63]
	s_waitcnt lgkmcnt(0)
	v_mfma_f32_32x32x16_bf16 v[96:111], v[158:161], v[228:231], v[96:111]
	v_mfma_f32_32x32x16_bf16 v[32:47], v[162:165], v[228:231], v[32:47]
	ds_read_b128 v[224:227], v168 offset:9280
	ds_read_b128 v[228:231], v168 offset:13888
	s_waitcnt vmcnt(7)
	ds_write_b128 v191, v[198:201] offset:27648
	s_waitcnt vmcnt(6)
	ds_write_b128 v191, v[202:205] offset:64512
	ds_read_b128 v[198:201], v169 offset:96
	ds_read_b128 v[202:205], v169 offset:4704
	s_waitcnt lgkmcnt(5)
	v_mfma_f32_32x32x16_bf16 v[80:95], v[158:161], v[224:227], v[80:95]
	v_mfma_f32_32x32x16_bf16 v[16:31], v[162:165], v[224:227], v[16:31]
	ds_read_b128 v[224:227], v168 offset:96
	s_waitcnt lgkmcnt(5)
	v_mfma_f32_32x32x16_bf16 v[64:79], v[158:161], v[228:231], v[64:79]
	v_mfma_f32_32x32x16_bf16 v[0:15], v[162:165], v[228:231], v[0:15]
	ds_read_b128 v[228:231], v168 offset:4704
	s_setprio 0
	global_load_dwordx4 v[158:161], v[152:153], off offset:1408
	global_load_dwordx4 v[162:165], v[156:157], off offset:1408
	s_setprio 1
	s_waitcnt lgkmcnt(1)
	v_mfma_f32_32x32x16_bf16 v[112:127], v[198:201], v[224:227], v[112:127]
	v_mfma_f32_32x32x16_bf16 v[48:63], v[202:205], v[224:227], v[48:63]
	s_waitcnt lgkmcnt(0)
	v_mfma_f32_32x32x16_bf16 v[96:111], v[198:201], v[228:231], v[96:111]
	v_mfma_f32_32x32x16_bf16 v[32:47], v[202:205], v[228:231], v[32:47]
	ds_read_b128 v[224:227], v168 offset:9312
	ds_read_b128 v[228:231], v168 offset:13920
	s_waitcnt lgkmcnt(0)
	s_barrier
; template <bool trans>
; DI void gemm_core(const GTile& tl, const GTile& nx, bool has_next  , bool chain  , bool pre, u32x4 (&ra)[4], u32x4 (&rb)[4], char* smem, f32x16 (&acc)[2][4]) {
;     ...
;   const int nk = K / 64;
;   if (!pre) { G_LOAD(0); G_STORE(0); G_LOAD(1); }
;   for (int kt = 0; kt < nk; ++kt) {
;     __syncthreads();
;     G_COMPUTE(kt & 1, kt);
	s_waitcnt vmcnt(7)
	ds_write_b128 v195, v[208:211]
	s_waitcnt vmcnt(6)
	ds_write_b128 v196, v[212:215]
	ds_read_b128 v[208:211], v192 offset:36864
	ds_read_b128 v[212:215], v192 offset:41472
	v_mfma_f32_32x32x16_bf16 v[80:95], v[198:201], v[224:227], v[80:95]
	v_mfma_f32_32x32x16_bf16 v[16:31], v[202:205], v[224:227], v[16:31]
	ds_read_b128 v[224:227], v184
	v_mfma_f32_32x32x16_bf16 v[64:79], v[198:201], v[228:231], v[64:79]
	v_mfma_f32_32x32x16_bf16 v[0:15], v[202:205], v[228:231], v[0:15]
	ds_read_b128 v[228:231], v184 offset:4608
	s_setprio 0
	global_load_dwordx4 v[198:201], v[128:129], off offset:1536
	global_load_dwordx4 v[202:205], v[132:133], off offset:1536
	s_setprio 1
	s_waitcnt lgkmcnt(1)
	v_mfma_f32_32x32x16_bf16 v[112:127], v[208:211], v[224:227], v[112:127]
	v_mfma_f32_32x32x16_bf16 v[48:63], v[212:215], v[224:227], v[48:63]
	s_waitcnt lgkmcnt(0)
	v_mfma_f32_32x32x16_bf16 v[96:111], v[208:211], v[228:231], v[96:111]
	v_mfma_f32_32x32x16_bf16 v[32:47], v[212:215], v[228:231], v[32:47]
	ds_read_b128 v[224:227], v184 offset:9216
	ds_read_b128 v[228:231], v184 offset:13824
	s_waitcnt vmcnt(7)
	ds_write_b128 v194, v[178:181]
	s_waitcnt vmcnt(6)
	ds_write_b128 v193, v[216:219]
	ds_read_b128 v[178:181], v192 offset:36896
	ds_read_b128 v[216:219], v192 offset:41504
	s_waitcnt lgkmcnt(5)
	v_mfma_f32_32x32x16_bf16 v[80:95], v[208:211], v[224:227], v[80:95]
	v_mfma_f32_32x32x16_bf16 v[16:31], v[212:215], v[224:227], v[16:31]
	ds_read_b128 v[224:227], v184 offset:32
	s_waitcnt lgkmcnt(5)
	v_mfma_f32_32x32x16_bf16 v[64:79], v[208:211], v[228:231], v[64:79]
	v_mfma_f32_32x32x16_bf16 v[0:15], v[212:215], v[228:231], v[0:15]
	ds_read_b128 v[228:231], v184 offset:4640
	s_setprio 0
	global_load_dwordx4 v[208:211], v[136:137], off offset:1536
	global_load_dwordx4 v[212:215], v[140:141], off offset:1536
	s_setprio 1
	s_waitcnt lgkmcnt(1)
	v_mfma_f32_32x32x16_bf16 v[112:127], v[178:181], v[224:227], v[112:127]
	v_mfma_f32_32x32x16_bf16 v[48:63], v[216:219], v[224:227], v[48:63]
	s_waitcnt lgkmcnt(0)
	v_mfma_f32_32x32x16_bf16 v[96:111], v[178:181], v[228:231], v[96:111]
	v_mfma_f32_32x32x16_bf16 v[32:47], v[216:219], v[228:231], v[32:47]
	ds_read_b128 v[224:227], v184 offset:9248
	ds_read_b128 v[228:231], v184 offset:13856
	s_waitcnt vmcnt(7)
	ds_write_b128 v177, v[172:175]
	s_waitcnt vmcnt(6)
	ds_write_b128 v176, v[220:223]
	ds_read_b128 v[172:175], v192 offset:36928
	ds_read_b128 v[220:223], v192 offset:41536
	s_waitcnt lgkmcnt(5)
	v_mfma_f32_32x32x16_bf16 v[80:95], v[178:181], v[224:227], v[80:95]
	v_mfma_f32_32x32x16_bf16 v[16:31], v[216:219], v[224:227], v[16:31]
	ds_read_b128 v[224:227], v184 offset:64
	s_waitcnt lgkmcnt(5)
	v_mfma_f32_32x32x16_bf16 v[64:79], v[178:181], v[228:231], v[64:79]
	v_mfma_f32_32x32x16_bf16 v[0:15], v[216:219], v[228:231], v[0:15]
	ds_read_b128 v[228:231], v184 offset:4672
	s_setprio 0
	global_load_dwordx4 v[178:181], v[144:145], off offset:1536
	global_load_dwordx4 v[216:219], v[148:149], off offset:1536
	s_setprio 1
	s_waitcnt lgkmcnt(1)
	v_mfma_f32_32x32x16_bf16 v[112:127], v[172:175], v[224:227], v[112:127]
	v_mfma_f32_32x32x16_bf16 v[48:63], v[220:223], v[224:227], v[48:63]
	s_waitcnt lgkmcnt(0)
	v_mfma_f32_32x32x16_bf16 v[96:111], v[172:175], v[228:231], v[96:111]
	v_mfma_f32_32x32x16_bf16 v[32:47], v[220:223], v[228:231], v[32:47]
	ds_read_b128 v[224:227], v184 offset:9280
	ds_read_b128 v[228:231], v184 offset:13888
	s_waitcnt vmcnt(7)
	ds_write_b128 v171, v[158:161]
	s_waitcnt vmcnt(6)
	ds_write_b128 v170, v[162:165]
	ds_read_b128 v[158:161], v192 offset:36960
	ds_read_b128 v[162:165], v192 offset:41568
	s_waitcnt lgkmcnt(5)
	v_mfma_f32_32x32x16_bf16 v[80:95], v[172:175], v[224:227], v[80:95]
	v_mfma_f32_32x32x16_bf16 v[16:31], v[220:223], v[224:227], v[16:31]
	ds_read_b128 v[224:227], v184 offset:96
	s_waitcnt lgkmcnt(5)
	v_mfma_f32_32x32x16_bf16 v[64:79], v[172:175], v[228:231], v[64:79]
	v_mfma_f32_32x32x16_bf16 v[0:15], v[220:223], v[228:231], v[0:15]
	ds_read_b128 v[228:231], v184 offset:4704
	s_setprio 0
	global_load_dwordx4 v[172:175], v[152:153], off offset:1536
	global_load_dwordx4 v[220:223], v[156:157], off offset:1536
	s_setprio 1
	s_waitcnt lgkmcnt(1)
	v_mfma_f32_32x32x16_bf16 v[112:127], v[158:161], v[224:227], v[112:127]
	v_mfma_f32_32x32x16_bf16 v[48:63], v[162:165], v[224:227], v[48:63]
	s_waitcnt lgkmcnt(0)
	v_mfma_f32_32x32x16_bf16 v[96:111], v[158:161], v[228:231], v[96:111]
	v_mfma_f32_32x32x16_bf16 v[32:47], v[162:165], v[228:231], v[32:47]
	ds_read_b128 v[224:227], v184 offset:9312
	ds_read_b128 v[228:231], v184 offset:13920
	s_waitcnt lgkmcnt(0)
	s_barrier
; template <bool trans>
; DI void gemm_core(const GTile& tl, const GTile& nx, bool has_next  , bool chain  , bool pre, u32x4 (&ra)[4], u32x4 (&rb)[4], char* smem, f32x16 (&acc)[2][4]) {
;     ...
;   const int nk = K / 64;
;   if (!pre) { G_LOAD(0); G_STORE(0); G_LOAD(1); }
;   for (int kt = 0; kt < nk; ++kt) {
;     __syncthreads();
;     G_COMPUTE(kt & 1, kt);
	s_waitcnt vmcnt(7)
	ds_write_b128 v191, v[198:201]
	s_waitcnt vmcnt(6)
	ds_write_b128 v191, v[202:205] offset:36864
	ds_read_b128 v[198:201], v169
	ds_read_b128 v[202:205], v169 offset:4608
	v_mfma_f32_32x32x16_bf16 v[80:95], v[158:161], v[224:227], v[80:95]
	v_mfma_f32_32x32x16_bf16 v[16:31], v[162:165], v[224:227], v[16:31]
	ds_read_b128 v[224:227], v168
	v_mfma_f32_32x32x16_bf16 v[64:79], v[158:161], v[228:231], v[64:79]
	v_mfma_f32_32x32x16_bf16 v[0:15], v[162:165], v[228:231], v[0:15]
	ds_read_b128 v[228:231], v168 offset:4608
	s_setprio 0
	global_load_dwordx4 v[158:161], v[128:129], off offset:1664
	global_load_dwordx4 v[162:165], v[132:133], off offset:1664
	s_setprio 1
	s_waitcnt lgkmcnt(1)
	v_mfma_f32_32x32x16_bf16 v[112:127], v[198:201], v[224:227], v[112:127]
	v_mfma_f32_32x32x16_bf16 v[48:63], v[202:205], v[224:227], v[48:63]
	s_waitcnt lgkmcnt(0)
	v_mfma_f32_32x32x16_bf16 v[96:111], v[198:201], v[228:231], v[96:111]
	v_mfma_f32_32x32x16_bf16 v[32:47], v[202:205], v[228:231], v[32:47]
	ds_read_b128 v[224:227], v168 offset:9216
	ds_read_b128 v[228:231], v168 offset:13824
	s_waitcnt vmcnt(7)
	ds_write_b128 v191, v[208:211] offset:9216
	s_waitcnt vmcnt(6)
	ds_write_b128 v191, v[212:215] offset:46080
	ds_read_b128 v[208:211], v169 offset:32
	ds_read_b128 v[212:215], v169 offset:4640
	s_waitcnt lgkmcnt(5)
	v_mfma_f32_32x32x16_bf16 v[80:95], v[198:201], v[224:227], v[80:95]
	v_mfma_f32_32x32x16_bf16 v[16:31], v[202:205], v[224:227], v[16:31]
	ds_read_b128 v[224:227], v168 offset:32
	s_waitcnt lgkmcnt(5)
	v_mfma_f32_32x32x16_bf16 v[64:79], v[198:201], v[228:231], v[64:79]
	v_mfma_f32_32x32x16_bf16 v[0:15], v[202:205], v[228:231], v[0:15]
	ds_read_b128 v[228:231], v168 offset:4640
	s_setprio 0
	global_load_dwordx4 v[198:201], v[136:137], off offset:1664
	global_load_dwordx4 v[202:205], v[140:141], off offset:1664
	s_setprio 1
	s_waitcnt lgkmcnt(1)
	v_mfma_f32_32x32x16_bf16 v[112:127], v[208:211], v[224:227], v[112:127]
	v_mfma_f32_32x32x16_bf16 v[48:63], v[212:215], v[224:227], v[48:63]
	s_waitcnt lgkmcnt(0)
	v_mfma_f32_32x32x16_bf16 v[96:111], v[208:211], v[228:231], v[96:111]
	v_mfma_f32_32x32x16_bf16 v[32:47], v[212:215], v[228:231], v[32:47]
	ds_read_b128 v[224:227], v168 offset:9248
	ds_read_b128 v[228:231], v168 offset:13856
	s_waitcnt vmcnt(7)
	ds_write_b128 v191, v[178:181] offset:18432
	s_waitcnt vmcnt(6)
	ds_write_b128 v191, v[216:219] offset:55296
	ds_read_b128 v[178:181], v169 offset:64
	ds_read_b128 v[216:219], v169 offset:4672
	s_waitcnt lgkmcnt(5)
	v_mfma_f32_32x32x16_bf16 v[80:95], v[208:211], v[224:227], v[80:95]
	v_mfma_f32_32x32x16_bf16 v[16:31], v[212:215], v[224:227], v[16:31]
	ds_read_b128 v[224:227], v168 offset:64
	s_waitcnt lgkmcnt(5)
	v_mfma_f32_32x32x16_bf16 v[64:79], v[208:211], v[228:231], v[64:79]
	v_mfma_f32_32x32x16_bf16 v[0:15], v[212:215], v[228:231], v[0:15]
	ds_read_b128 v[228:231], v168 offset:4672
	s_setprio 0
	global_load_dwordx4 v[208:211], v[144:145], off offset:1664
	global_load_dwordx4 v[212:215], v[148:149], off offset:1664
	s_setprio 1
	s_waitcnt lgkmcnt(1)
	v_mfma_f32_32x32x16_bf16 v[112:127], v[178:181], v[224:227], v[112:127]
	v_mfma_f32_32x32x16_bf16 v[48:63], v[216:219], v[224:227], v[48:63]
	s_waitcnt lgkmcnt(0)
	v_mfma_f32_32x32x16_bf16 v[96:111], v[178:181], v[228:231], v[96:111]
	v_mfma_f32_32x32x16_bf16 v[32:47], v[216:219], v[228:231], v[32:47]
	ds_read_b128 v[224:227], v168 offset:9280
	ds_read_b128 v[228:231], v168 offset:13888
	s_waitcnt vmcnt(7)
	ds_write_b128 v191, v[172:175] offset:27648
	s_waitcnt vmcnt(6)
	ds_write_b128 v191, v[220:223] offset:64512
	ds_read_b128 v[172:175], v169 offset:96
	ds_read_b128 v[220:223], v169 offset:4704
	s_waitcnt lgkmcnt(5)
	v_mfma_f32_32x32x16_bf16 v[80:95], v[178:181], v[224:227], v[80:95]
	v_mfma_f32_32x32x16_bf16 v[16:31], v[216:219], v[224:227], v[16:31]
	ds_read_b128 v[224:227], v168 offset:96
	s_waitcnt lgkmcnt(5)
	v_mfma_f32_32x32x16_bf16 v[64:79], v[178:181], v[228:231], v[64:79]
	v_mfma_f32_32x32x16_bf16 v[0:15], v[216:219], v[228:231], v[0:15]
	ds_read_b128 v[228:231], v168 offset:4704
	s_setprio 0
	global_load_dwordx4 v[178:181], v[152:153], off offset:1664
	global_load_dwordx4 v[216:219], v[156:157], off offset:1664
	s_setprio 1
	s_waitcnt lgkmcnt(1)
	v_mfma_f32_32x32x16_bf16 v[112:127], v[172:175], v[224:227], v[112:127]
	v_mfma_f32_32x32x16_bf16 v[48:63], v[220:223], v[224:227], v[48:63]
	s_waitcnt lgkmcnt(0)
	v_mfma_f32_32x32x16_bf16 v[96:111], v[172:175], v[228:231], v[96:111]
	v_mfma_f32_32x32x16_bf16 v[32:47], v[220:223], v[228:231], v[32:47]
	ds_read_b128 v[224:227], v168 offset:9312
	ds_read_b128 v[228:231], v168 offset:13920
	s_waitcnt lgkmcnt(0)
	s_barrier
; template <bool trans>
; DI void gemm_core(const GTile& tl, const GTile& nx, bool has_next  , bool chain  , bool pre, u32x4 (&ra)[4], u32x4 (&rb)[4], char* smem, f32x16 (&acc)[2][4]) {
;     ...
;   const int nk = K / 64;
;   if (!pre) { G_LOAD(0); G_STORE(0); G_LOAD(1); }
;   for (int kt = 0; kt < nk; ++kt) {
;     __syncthreads();
;     G_COMPUTE(kt & 1, kt);
	s_waitcnt vmcnt(7)
	ds_write_b128 v195, v[158:161]
	s_waitcnt vmcnt(6)
	ds_write_b128 v196, v[162:165]
	ds_read_b128 v[158:161], v192 offset:36864
	ds_read_b128 v[162:165], v192 offset:41472
	v_mfma_f32_32x32x16_bf16 v[80:95], v[172:175], v[224:227], v[80:95]
	v_mfma_f32_32x32x16_bf16 v[16:31], v[220:223], v[224:227], v[16:31]
	ds_read_b128 v[224:227], v184
	v_mfma_f32_32x32x16_bf16 v[64:79], v[172:175], v[228:231], v[64:79]
	v_mfma_f32_32x32x16_bf16 v[0:15], v[220:223], v[228:231], v[0:15]
	ds_read_b128 v[228:231], v184 offset:4608
	s_setprio 0
	global_load_dwordx4 v[172:175], v[128:129], off offset:1792
	global_load_dwordx4 v[220:223], v[132:133], off offset:1792
	s_setprio 1
	s_waitcnt lgkmcnt(1)
	v_mfma_f32_32x32x16_bf16 v[112:127], v[158:161], v[224:227], v[112:127]
	v_mfma_f32_32x32x16_bf16 v[48:63], v[162:165], v[224:227], v[48:63]
	s_waitcnt lgkmcnt(0)
	v_mfma_f32_32x32x16_bf16 v[96:111], v[158:161], v[228:231], v[96:111]
	v_mfma_f32_32x32x16_bf16 v[32:47], v[162:165], v[228:231], v[32:47]
	ds_read_b128 v[224:227], v184 offset:9216
	ds_read_b128 v[228:231], v184 offset:13824
	s_waitcnt vmcnt(7)
	ds_write_b128 v194, v[198:201]
	s_waitcnt vmcnt(6)
	ds_write_b128 v193, v[202:205]
	ds_read_b128 v[198:201], v192 offset:36896
	ds_read_b128 v[202:205], v192 offset:41504
	s_waitcnt lgkmcnt(5)
	v_mfma_f32_32x32x16_bf16 v[80:95], v[158:161], v[224:227], v[80:95]
	v_mfma_f32_32x32x16_bf16 v[16:31], v[162:165], v[224:227], v[16:31]
	ds_read_b128 v[224:227], v184 offset:32
	s_waitcnt lgkmcnt(5)
	v_mfma_f32_32x32x16_bf16 v[64:79], v[158:161], v[228:231], v[64:79]
	v_mfma_f32_32x32x16_bf16 v[0:15], v[162:165], v[228:231], v[0:15]
	ds_read_b128 v[228:231], v184 offset:4640
	s_setprio 0
	global_load_dwordx4 v[158:161], v[136:137], off offset:1792
	global_load_dwordx4 v[162:165], v[140:141], off offset:1792
	s_setprio 1
	s_waitcnt lgkmcnt(1)
	v_mfma_f32_32x32x16_bf16 v[112:127], v[198:201], v[224:227], v[112:127]
	v_mfma_f32_32x32x16_bf16 v[48:63], v[202:205], v[224:227], v[48:63]
	s_waitcnt lgkmcnt(0)
	v_mfma_f32_32x32x16_bf16 v[96:111], v[198:201], v[228:231], v[96:111]
	v_mfma_f32_32x32x16_bf16 v[32:47], v[202:205], v[228:231], v[32:47]
	ds_read_b128 v[224:227], v184 offset:9248
	ds_read_b128 v[228:231], v184 offset:13856
	s_waitcnt vmcnt(7)
	ds_write_b128 v177, v[208:211]
	s_waitcnt vmcnt(6)
	ds_write_b128 v176, v[212:215]
	ds_read_b128 v[208:211], v192 offset:36928
	ds_read_b128 v[212:215], v192 offset:41536
	s_waitcnt lgkmcnt(5)
	v_mfma_f32_32x32x16_bf16 v[80:95], v[198:201], v[224:227], v[80:95]
	v_mfma_f32_32x32x16_bf16 v[16:31], v[202:205], v[224:227], v[16:31]
	ds_read_b128 v[224:227], v184 offset:64
	s_waitcnt lgkmcnt(5)
	v_mfma_f32_32x32x16_bf16 v[64:79], v[198:201], v[228:231], v[64:79]
	v_mfma_f32_32x32x16_bf16 v[0:15], v[202:205], v[228:231], v[0:15]
	ds_read_b128 v[228:231], v184 offset:4672
	s_setprio 0
	global_load_dwordx4 v[198:201], v[144:145], off offset:1792
	global_load_dwordx4 v[202:205], v[148:149], off offset:1792
	s_setprio 1
	s_waitcnt lgkmcnt(1)
	v_mfma_f32_32x32x16_bf16 v[112:127], v[208:211], v[224:227], v[112:127]
	v_mfma_f32_32x32x16_bf16 v[48:63], v[212:215], v[224:227], v[48:63]
	s_waitcnt lgkmcnt(0)
	v_mfma_f32_32x32x16_bf16 v[96:111], v[208:211], v[228:231], v[96:111]
	v_mfma_f32_32x32x16_bf16 v[32:47], v[212:215], v[228:231], v[32:47]
	ds_read_b128 v[224:227], v184 offset:9280
	ds_read_b128 v[228:231], v184 offset:13888
	s_waitcnt vmcnt(7)
	ds_write_b128 v171, v[178:181]
	s_waitcnt vmcnt(6)
	ds_write_b128 v170, v[216:219]
	ds_read_b128 v[178:181], v192 offset:36960
	ds_read_b128 v[216:219], v192 offset:41568
	s_waitcnt lgkmcnt(5)
	v_mfma_f32_32x32x16_bf16 v[80:95], v[208:211], v[224:227], v[80:95]
	v_mfma_f32_32x32x16_bf16 v[16:31], v[212:215], v[224:227], v[16:31]
	ds_read_b128 v[224:227], v184 offset:96
	s_waitcnt lgkmcnt(5)
	v_mfma_f32_32x32x16_bf16 v[64:79], v[208:211], v[228:231], v[64:79]
	v_mfma_f32_32x32x16_bf16 v[0:15], v[212:215], v[228:231], v[0:15]
	ds_read_b128 v[228:231], v184 offset:4704
	s_setprio 0
	global_load_dwordx4 v[208:211], v[152:153], off offset:1792
	global_load_dwordx4 v[212:215], v[156:157], off offset:1792
	s_setprio 1
	s_waitcnt lgkmcnt(1)
	v_mfma_f32_32x32x16_bf16 v[112:127], v[178:181], v[224:227], v[112:127]
	v_mfma_f32_32x32x16_bf16 v[48:63], v[216:219], v[224:227], v[48:63]
	s_waitcnt lgkmcnt(0)
	v_mfma_f32_32x32x16_bf16 v[96:111], v[178:181], v[228:231], v[96:111]
	v_mfma_f32_32x32x16_bf16 v[32:47], v[216:219], v[228:231], v[32:47]
	ds_read_b128 v[224:227], v184 offset:9312
	ds_read_b128 v[228:231], v184 offset:13920
	s_waitcnt lgkmcnt(0)
	s_barrier
; template <bool trans>
; DI void gemm_core(const GTile& tl, const GTile& nx, bool has_next  , bool chain  , bool pre, u32x4 (&ra)[4], u32x4 (&rb)[4], char* smem, f32x16 (&acc)[2][4]) {
;     ...
;   const int nk = K / 64;
;   if (!pre) { G_LOAD(0); G_STORE(0); G_LOAD(1); }
;   for (int kt = 0; kt < nk; ++kt) {
;     __syncthreads();
;     G_COMPUTE(kt & 1, kt);
	s_waitcnt vmcnt(7)
	ds_write_b128 v191, v[172:175]
	s_waitcnt vmcnt(6)
	ds_write_b128 v191, v[220:223] offset:36864
	ds_read_b128 v[172:175], v169
	ds_read_b128 v[220:223], v169 offset:4608
	v_mfma_f32_32x32x16_bf16 v[80:95], v[178:181], v[224:227], v[80:95]
	v_mfma_f32_32x32x16_bf16 v[16:31], v[216:219], v[224:227], v[16:31]
	ds_read_b128 v[224:227], v168
	v_mfma_f32_32x32x16_bf16 v[64:79], v[178:181], v[228:231], v[64:79]
	v_mfma_f32_32x32x16_bf16 v[0:15], v[216:219], v[228:231], v[0:15]
	ds_read_b128 v[228:231], v168 offset:4608
	s_setprio 0
	global_load_dwordx4 v[178:181], v[128:129], off offset:1920
	global_load_dwordx4 v[216:219], v[132:133], off offset:1920
	s_setprio 1
	s_waitcnt lgkmcnt(1)
	v_mfma_f32_32x32x16_bf16 v[112:127], v[172:175], v[224:227], v[112:127]
	v_mfma_f32_32x32x16_bf16 v[48:63], v[220:223], v[224:227], v[48:63]
	s_waitcnt lgkmcnt(0)
	v_mfma_f32_32x32x16_bf16 v[96:111], v[172:175], v[228:231], v[96:111]
	v_mfma_f32_32x32x16_bf16 v[32:47], v[220:223], v[228:231], v[32:47]
	ds_read_b128 v[224:227], v168 offset:9216
	ds_read_b128 v[228:231], v168 offset:13824
	s_waitcnt vmcnt(7)
	ds_write_b128 v191, v[158:161] offset:9216
	s_waitcnt vmcnt(6)
	ds_write_b128 v191, v[162:165] offset:46080
	ds_read_b128 v[158:161], v169 offset:32
	ds_read_b128 v[162:165], v169 offset:4640
	s_waitcnt lgkmcnt(5)
	v_mfma_f32_32x32x16_bf16 v[80:95], v[172:175], v[224:227], v[80:95]
	v_mfma_f32_32x32x16_bf16 v[16:31], v[220:223], v[224:227], v[16:31]
	ds_read_b128 v[224:227], v168 offset:32
	s_waitcnt lgkmcnt(5)
	v_mfma_f32_32x32x16_bf16 v[64:79], v[172:175], v[228:231], v[64:79]
	v_mfma_f32_32x32x16_bf16 v[0:15], v[220:223], v[228:231], v[0:15]
	ds_read_b128 v[228:231], v168 offset:4640
	s_setprio 0
	global_load_dwordx4 v[172:175], v[136:137], off offset:1920
	global_load_dwordx4 v[220:223], v[140:141], off offset:1920
	s_setprio 1
	s_waitcnt lgkmcnt(1)
	v_mfma_f32_32x32x16_bf16 v[112:127], v[158:161], v[224:227], v[112:127]
	v_mfma_f32_32x32x16_bf16 v[48:63], v[162:165], v[224:227], v[48:63]
	s_waitcnt lgkmcnt(0)
	v_mfma_f32_32x32x16_bf16 v[96:111], v[158:161], v[228:231], v[96:111]
	v_mfma_f32_32x32x16_bf16 v[32:47], v[162:165], v[228:231], v[32:47]
	ds_read_b128 v[224:227], v168 offset:9248
	ds_read_b128 v[228:231], v168 offset:13856
	s_waitcnt vmcnt(7)
	ds_write_b128 v191, v[198:201] offset:18432
	s_waitcnt vmcnt(6)
	ds_write_b128 v191, v[202:205] offset:55296
	ds_read_b128 v[198:201], v169 offset:64
	ds_read_b128 v[202:205], v169 offset:4672
	s_waitcnt lgkmcnt(5)
	v_mfma_f32_32x32x16_bf16 v[80:95], v[158:161], v[224:227], v[80:95]
	v_mfma_f32_32x32x16_bf16 v[16:31], v[162:165], v[224:227], v[16:31]
	ds_read_b128 v[224:227], v168 offset:64
	s_waitcnt lgkmcnt(5)
	v_mfma_f32_32x32x16_bf16 v[64:79], v[158:161], v[228:231], v[64:79]
	v_mfma_f32_32x32x16_bf16 v[0:15], v[162:165], v[228:231], v[0:15]
	ds_read_b128 v[228:231], v168 offset:4672
	s_setprio 0
	global_load_dwordx4 v[158:161], v[144:145], off offset:1920
	global_load_dwordx4 v[162:165], v[148:149], off offset:1920
	s_setprio 1
	s_waitcnt lgkmcnt(1)
	v_mfma_f32_32x32x16_bf16 v[112:127], v[198:201], v[224:227], v[112:127]
	v_mfma_f32_32x32x16_bf16 v[48:63], v[202:205], v[224:227], v[48:63]
	s_waitcnt lgkmcnt(0)
	v_mfma_f32_32x32x16_bf16 v[96:111], v[198:201], v[228:231], v[96:111]
	v_mfma_f32_32x32x16_bf16 v[32:47], v[202:205], v[228:231], v[32:47]
	ds_read_b128 v[224:227], v168 offset:9280
	ds_read_b128 v[228:231], v168 offset:13888
	s_waitcnt vmcnt(7)
	ds_write_b128 v191, v[208:211] offset:27648
	s_waitcnt vmcnt(6)
	ds_write_b128 v191, v[212:215] offset:64512
	ds_read_b128 v[208:211], v169 offset:96
	ds_read_b128 v[212:215], v169 offset:4704
	s_waitcnt lgkmcnt(5)
	v_mfma_f32_32x32x16_bf16 v[80:95], v[198:201], v[224:227], v[80:95]
	v_mfma_f32_32x32x16_bf16 v[16:31], v[202:205], v[224:227], v[16:31]
	ds_read_b128 v[224:227], v168 offset:96
	s_waitcnt lgkmcnt(5)
	v_mfma_f32_32x32x16_bf16 v[64:79], v[198:201], v[228:231], v[64:79]
	v_mfma_f32_32x32x16_bf16 v[0:15], v[202:205], v[228:231], v[0:15]
	ds_read_b128 v[228:231], v168 offset:4704
	s_setprio 0
	global_load_dwordx4 v[198:201], v[152:153], off offset:1920
	global_load_dwordx4 v[202:205], v[156:157], off offset:1920
	s_setprio 1
	s_waitcnt lgkmcnt(1)
	v_mfma_f32_32x32x16_bf16 v[112:127], v[208:211], v[224:227], v[112:127]
	v_mfma_f32_32x32x16_bf16 v[48:63], v[212:215], v[224:227], v[48:63]
	s_waitcnt lgkmcnt(0)
	v_mfma_f32_32x32x16_bf16 v[96:111], v[208:211], v[228:231], v[96:111]
	v_mfma_f32_32x32x16_bf16 v[32:47], v[212:215], v[228:231], v[32:47]
	ds_read_b128 v[224:227], v168 offset:9312
	ds_read_b128 v[228:231], v168 offset:13920
	s_waitcnt lgkmcnt(0)
	s_barrier
; template <bool trans>
; DI void gemm_core(const GTile& tl, const GTile& nx, bool has_next  , bool chain  , bool pre, u32x4 (&ra)[4], u32x4 (&rb)[4], char* smem, f32x16 (&acc)[2][4]) {
;     ...
;   const int nk = K / 64;
;   if (!pre) { G_LOAD(0); G_STORE(0); G_LOAD(1); }
;   for (int kt = 0; kt < nk; ++kt) {
;     __syncthreads();
;     G_COMPUTE(kt & 1, kt);
	s_waitcnt vmcnt(7)
	ds_write_b128 v195, v[178:181]
	s_waitcnt vmcnt(6)
	ds_write_b128 v196, v[216:219]
	ds_read_b128 v[178:181], v192 offset:36864
	ds_read_b128 v[216:219], v192 offset:41472
	v_mfma_f32_32x32x16_bf16 v[80:95], v[208:211], v[224:227], v[80:95]
	v_mfma_f32_32x32x16_bf16 v[16:31], v[212:215], v[224:227], v[16:31]
	ds_read_b128 v[224:227], v184
	v_mfma_f32_32x32x16_bf16 v[64:79], v[208:211], v[228:231], v[64:79]
	v_mfma_f32_32x32x16_bf16 v[0:15], v[212:215], v[228:231], v[0:15]
	ds_read_b128 v[228:231], v184 offset:4608
	s_setprio 0
	global_load_dwordx4 v[208:211], v[128:129], off offset:2048
	global_load_dwordx4 v[212:215], v[132:133], off offset:2048
	s_setprio 1
	s_waitcnt lgkmcnt(1)
	v_mfma_f32_32x32x16_bf16 v[112:127], v[178:181], v[224:227], v[112:127]
	v_mfma_f32_32x32x16_bf16 v[48:63], v[216:219], v[224:227], v[48:63]
	s_waitcnt lgkmcnt(0)
	v_mfma_f32_32x32x16_bf16 v[96:111], v[178:181], v[228:231], v[96:111]
	v_mfma_f32_32x32x16_bf16 v[32:47], v[216:219], v[228:231], v[32:47]
	ds_read_b128 v[224:227], v184 offset:9216
	ds_read_b128 v[228:231], v184 offset:13824
	s_waitcnt vmcnt(7)
	ds_write_b128 v194, v[172:175]
	s_waitcnt vmcnt(6)
	ds_write_b128 v193, v[220:223]
	ds_read_b128 v[172:175], v192 offset:36896
	ds_read_b128 v[220:223], v192 offset:41504
	s_waitcnt lgkmcnt(5)
	v_mfma_f32_32x32x16_bf16 v[80:95], v[178:181], v[224:227], v[80:95]
	v_mfma_f32_32x32x16_bf16 v[16:31], v[216:219], v[224:227], v[16:31]
	ds_read_b128 v[224:227], v184 offset:32
	s_waitcnt lgkmcnt(5)
	v_mfma_f32_32x32x16_bf16 v[64:79], v[178:181], v[228:231], v[64:79]
	v_mfma_f32_32x32x16_bf16 v[0:15], v[216:219], v[228:231], v[0:15]
	ds_read_b128 v[228:231], v184 offset:4640
	s_setprio 0
	global_load_dwordx4 v[178:181], v[136:137], off offset:2048
	global_load_dwordx4 v[216:219], v[140:141], off offset:2048
	s_setprio 1
	s_waitcnt lgkmcnt(1)
	v_mfma_f32_32x32x16_bf16 v[112:127], v[172:175], v[224:227], v[112:127]
	v_mfma_f32_32x32x16_bf16 v[48:63], v[220:223], v[224:227], v[48:63]
	s_waitcnt lgkmcnt(0)
	v_mfma_f32_32x32x16_bf16 v[96:111], v[172:175], v[228:231], v[96:111]
	v_mfma_f32_32x32x16_bf16 v[32:47], v[220:223], v[228:231], v[32:47]
	ds_read_b128 v[224:227], v184 offset:9248
	ds_read_b128 v[228:231], v184 offset:13856
	s_waitcnt vmcnt(7)
	ds_write_b128 v177, v[158:161]
	s_waitcnt vmcnt(6)
	ds_write_b128 v176, v[162:165]
	ds_read_b128 v[158:161], v192 offset:36928
	ds_read_b128 v[162:165], v192 offset:41536
	s_waitcnt lgkmcnt(5)
	v_mfma_f32_32x32x16_bf16 v[80:95], v[172:175], v[224:227], v[80:95]
	v_mfma_f32_32x32x16_bf16 v[16:31], v[220:223], v[224:227], v[16:31]
	ds_read_b128 v[224:227], v184 offset:64
	s_waitcnt lgkmcnt(5)
	v_mfma_f32_32x32x16_bf16 v[64:79], v[172:175], v[228:231], v[64:79]
	v_mfma_f32_32x32x16_bf16 v[0:15], v[220:223], v[228:231], v[0:15]
	ds_read_b128 v[228:231], v184 offset:4672
	s_setprio 0
	global_load_dwordx4 v[172:175], v[144:145], off offset:2048
	global_load_dwordx4 v[220:223], v[148:149], off offset:2048
	s_setprio 1
	s_waitcnt lgkmcnt(1)
	v_mfma_f32_32x32x16_bf16 v[112:127], v[158:161], v[224:227], v[112:127]
	v_mfma_f32_32x32x16_bf16 v[48:63], v[162:165], v[224:227], v[48:63]
	s_waitcnt lgkmcnt(0)
	v_mfma_f32_32x32x16_bf16 v[96:111], v[158:161], v[228:231], v[96:111]
	v_mfma_f32_32x32x16_bf16 v[32:47], v[162:165], v[228:231], v[32:47]
	ds_read_b128 v[224:227], v184 offset:9280
	ds_read_b128 v[228:231], v184 offset:13888
	s_waitcnt vmcnt(7)
	ds_write_b128 v171, v[198:201]
	s_waitcnt vmcnt(6)
	ds_write_b128 v170, v[202:205]
	ds_read_b128 v[198:201], v192 offset:36960
	ds_read_b128 v[202:205], v192 offset:41568
	s_waitcnt lgkmcnt(5)
	v_mfma_f32_32x32x16_bf16 v[80:95], v[158:161], v[224:227], v[80:95]
	v_mfma_f32_32x32x16_bf16 v[16:31], v[162:165], v[224:227], v[16:31]
	ds_read_b128 v[224:227], v184 offset:96
	s_waitcnt lgkmcnt(5)
	v_mfma_f32_32x32x16_bf16 v[64:79], v[158:161], v[228:231], v[64:79]
	v_mfma_f32_32x32x16_bf16 v[0:15], v[162:165], v[228:231], v[0:15]
	ds_read_b128 v[228:231], v184 offset:4704
	s_setprio 0
	global_load_dwordx4 v[158:161], v[152:153], off offset:2048
	global_load_dwordx4 v[162:165], v[156:157], off offset:2048
	s_setprio 1
	s_waitcnt lgkmcnt(1)
	v_mfma_f32_32x32x16_bf16 v[112:127], v[198:201], v[224:227], v[112:127]
	v_mfma_f32_32x32x16_bf16 v[48:63], v[202:205], v[224:227], v[48:63]
	s_waitcnt lgkmcnt(0)
	v_mfma_f32_32x32x16_bf16 v[96:111], v[198:201], v[228:231], v[96:111]
	v_mfma_f32_32x32x16_bf16 v[32:47], v[202:205], v[228:231], v[32:47]
	ds_read_b128 v[224:227], v184 offset:9312
	ds_read_b128 v[228:231], v184 offset:13920
	s_waitcnt lgkmcnt(0)
	s_barrier
; template <bool trans>
; DI void gemm_core(const GTile& tl, const GTile& nx, bool has_next  , bool chain  , bool pre, u32x4 (&ra)[4], u32x4 (&rb)[4], char* smem, f32x16 (&acc)[2][4]) {
;     ...
;   const int nk = K / 64;
;   if (!pre) { G_LOAD(0); G_STORE(0); G_LOAD(1); }
;   for (int kt = 0; kt < nk; ++kt) {
;     __syncthreads();
;     G_COMPUTE(kt & 1, kt);
	s_waitcnt vmcnt(7)
	ds_write_b128 v191, v[208:211]
	s_waitcnt vmcnt(6)
	ds_write_b128 v191, v[212:215] offset:36864
	ds_read_b128 v[208:211], v169
	ds_read_b128 v[212:215], v169 offset:4608
	v_mfma_f32_32x32x16_bf16 v[80:95], v[198:201], v[224:227], v[80:95]
	v_mfma_f32_32x32x16_bf16 v[16:31], v[202:205], v[224:227], v[16:31]
	ds_read_b128 v[224:227], v168
	v_mfma_f32_32x32x16_bf16 v[64:79], v[198:201], v[228:231], v[64:79]
	v_mfma_f32_32x32x16_bf16 v[0:15], v[202:205], v[228:231], v[0:15]
	ds_read_b128 v[228:231], v168 offset:4608
	s_setprio 0
	global_load_dwordx4 v[198:201], v[128:129], off offset:2176
	global_load_dwordx4 v[202:205], v[132:133], off offset:2176
	s_setprio 1
	s_waitcnt lgkmcnt(1)
	v_mfma_f32_32x32x16_bf16 v[112:127], v[208:211], v[224:227], v[112:127]
	v_mfma_f32_32x32x16_bf16 v[48:63], v[212:215], v[224:227], v[48:63]
	s_waitcnt lgkmcnt(0)
	v_mfma_f32_32x32x16_bf16 v[96:111], v[208:211], v[228:231], v[96:111]
	v_mfma_f32_32x32x16_bf16 v[32:47], v[212:215], v[228:231], v[32:47]
	ds_read_b128 v[224:227], v168 offset:9216
	ds_read_b128 v[228:231], v168 offset:13824
	s_waitcnt vmcnt(7)
	ds_write_b128 v191, v[178:181] offset:9216
	s_waitcnt vmcnt(6)
	ds_write_b128 v191, v[216:219] offset:46080
	ds_read_b128 v[178:181], v169 offset:32
	ds_read_b128 v[216:219], v169 offset:4640
	s_waitcnt lgkmcnt(5)
	v_mfma_f32_32x32x16_bf16 v[80:95], v[208:211], v[224:227], v[80:95]
	v_mfma_f32_32x32x16_bf16 v[16:31], v[212:215], v[224:227], v[16:31]
	ds_read_b128 v[224:227], v168 offset:32
	s_waitcnt lgkmcnt(5)
	v_mfma_f32_32x32x16_bf16 v[64:79], v[208:211], v[228:231], v[64:79]
	v_mfma_f32_32x32x16_bf16 v[0:15], v[212:215], v[228:231], v[0:15]
	ds_read_b128 v[228:231], v168 offset:4640
	s_setprio 0
	global_load_dwordx4 v[208:211], v[136:137], off offset:2176
	global_load_dwordx4 v[212:215], v[140:141], off offset:2176
	s_setprio 1
	s_waitcnt lgkmcnt(1)
	v_mfma_f32_32x32x16_bf16 v[112:127], v[178:181], v[224:227], v[112:127]
	v_mfma_f32_32x32x16_bf16 v[48:63], v[216:219], v[224:227], v[48:63]
	s_waitcnt lgkmcnt(0)
	v_mfma_f32_32x32x16_bf16 v[96:111], v[178:181], v[228:231], v[96:111]
	v_mfma_f32_32x32x16_bf16 v[32:47], v[216:219], v[228:231], v[32:47]
	ds_read_b128 v[224:227], v168 offset:9248
	ds_read_b128 v[228:231], v168 offset:13856
	s_waitcnt vmcnt(7)
	ds_write_b128 v191, v[172:175] offset:18432
	s_waitcnt vmcnt(6)
	ds_write_b128 v191, v[220:223] offset:55296
	ds_read_b128 v[172:175], v169 offset:64
	ds_read_b128 v[220:223], v169 offset:4672
	s_waitcnt lgkmcnt(5)
	v_mfma_f32_32x32x16_bf16 v[80:95], v[178:181], v[224:227], v[80:95]
	v_mfma_f32_32x32x16_bf16 v[16:31], v[216:219], v[224:227], v[16:31]
	ds_read_b128 v[224:227], v168 offset:64
	s_waitcnt lgkmcnt(5)
	v_mfma_f32_32x32x16_bf16 v[64:79], v[178:181], v[228:231], v[64:79]
	v_mfma_f32_32x32x16_bf16 v[0:15], v[216:219], v[228:231], v[0:15]
	ds_read_b128 v[228:231], v168 offset:4672
	s_setprio 0
	global_load_dwordx4 v[178:181], v[144:145], off offset:2176
	global_load_dwordx4 v[216:219], v[148:149], off offset:2176
	s_setprio 1
	s_waitcnt lgkmcnt(1)
	v_mfma_f32_32x32x16_bf16 v[112:127], v[172:175], v[224:227], v[112:127]
	v_mfma_f32_32x32x16_bf16 v[48:63], v[220:223], v[224:227], v[48:63]
	s_waitcnt lgkmcnt(0)
	v_mfma_f32_32x32x16_bf16 v[96:111], v[172:175], v[228:231], v[96:111]
	v_mfma_f32_32x32x16_bf16 v[32:47], v[220:223], v[228:231], v[32:47]
	ds_read_b128 v[224:227], v168 offset:9280
	ds_read_b128 v[228:231], v168 offset:13888
	s_waitcnt vmcnt(7)
	ds_write_b128 v191, v[158:161] offset:27648
	s_waitcnt vmcnt(6)
	ds_write_b128 v191, v[162:165] offset:64512
	ds_read_b128 v[158:161], v169 offset:96
	ds_read_b128 v[162:165], v169 offset:4704
	s_waitcnt lgkmcnt(5)
	v_mfma_f32_32x32x16_bf16 v[80:95], v[172:175], v[224:227], v[80:95]
	v_mfma_f32_32x32x16_bf16 v[16:31], v[220:223], v[224:227], v[16:31]
	ds_read_b128 v[224:227], v168 offset:96
	s_waitcnt lgkmcnt(5)
	v_mfma_f32_32x32x16_bf16 v[64:79], v[172:175], v[228:231], v[64:79]
	v_mfma_f32_32x32x16_bf16 v[0:15], v[220:223], v[228:231], v[0:15]
	ds_read_b128 v[228:231], v168 offset:4704
	s_setprio 0
	global_load_dwordx4 v[172:175], v[152:153], off offset:2176
	global_load_dwordx4 v[220:223], v[156:157], off offset:2176
	s_setprio 1
	s_waitcnt lgkmcnt(1)
	v_mfma_f32_32x32x16_bf16 v[112:127], v[158:161], v[224:227], v[112:127]
	v_mfma_f32_32x32x16_bf16 v[48:63], v[162:165], v[224:227], v[48:63]
	s_waitcnt lgkmcnt(0)
	v_mfma_f32_32x32x16_bf16 v[96:111], v[158:161], v[228:231], v[96:111]
	v_mfma_f32_32x32x16_bf16 v[32:47], v[162:165], v[228:231], v[32:47]
	ds_read_b128 v[224:227], v168 offset:9312
	ds_read_b128 v[228:231], v168 offset:13920
	s_waitcnt lgkmcnt(0)
	s_barrier
; template <bool trans>
; DI void gemm_core(const GTile& tl, const GTile& nx, bool has_next  , bool chain  , bool pre, u32x4 (&ra)[4], u32x4 (&rb)[4], char* smem, f32x16 (&acc)[2][4]) {
;     ...
;   const int nk = K / 64;
;   if (!pre) { G_LOAD(0); G_STORE(0); G_LOAD(1); }
;   for (int kt = 0; kt < nk; ++kt) {
;     __syncthreads();
;     G_COMPUTE(kt & 1, kt);
	s_waitcnt vmcnt(7)
	ds_write_b128 v195, v[198:201]
	s_waitcnt vmcnt(6)
	ds_write_b128 v196, v[202:205]
	ds_read_b128 v[198:201], v192 offset:36864
	ds_read_b128 v[202:205], v192 offset:41472
	v_mfma_f32_32x32x16_bf16 v[80:95], v[158:161], v[224:227], v[80:95]
	v_mfma_f32_32x32x16_bf16 v[16:31], v[162:165], v[224:227], v[16:31]
	ds_read_b128 v[224:227], v184
	v_mfma_f32_32x32x16_bf16 v[64:79], v[158:161], v[228:231], v[64:79]
	v_mfma_f32_32x32x16_bf16 v[0:15], v[162:165], v[228:231], v[0:15]
	ds_read_b128 v[228:231], v184 offset:4608
	s_setprio 0
	global_load_dwordx4 v[158:161], v[128:129], off offset:2304
	global_load_dwordx4 v[162:165], v[132:133], off offset:2304
	s_setprio 1
	s_waitcnt lgkmcnt(1)
	v_mfma_f32_32x32x16_bf16 v[112:127], v[198:201], v[224:227], v[112:127]
	v_mfma_f32_32x32x16_bf16 v[48:63], v[202:205], v[224:227], v[48:63]
	s_waitcnt lgkmcnt(0)
	v_mfma_f32_32x32x16_bf16 v[96:111], v[198:201], v[228:231], v[96:111]
	v_mfma_f32_32x32x16_bf16 v[32:47], v[202:205], v[228:231], v[32:47]
	ds_read_b128 v[224:227], v184 offset:9216
	ds_read_b128 v[228:231], v184 offset:13824
	s_waitcnt vmcnt(7)
	ds_write_b128 v194, v[208:211]
	s_waitcnt vmcnt(6)
	ds_write_b128 v193, v[212:215]
	ds_read_b128 v[208:211], v192 offset:36896
	ds_read_b128 v[212:215], v192 offset:41504
	s_waitcnt lgkmcnt(5)
	v_mfma_f32_32x32x16_bf16 v[80:95], v[198:201], v[224:227], v[80:95]
	v_mfma_f32_32x32x16_bf16 v[16:31], v[202:205], v[224:227], v[16:31]
	ds_read_b128 v[224:227], v184 offset:32
	s_waitcnt lgkmcnt(5)
	v_mfma_f32_32x32x16_bf16 v[64:79], v[198:201], v[228:231], v[64:79]
	v_mfma_f32_32x32x16_bf16 v[0:15], v[202:205], v[228:231], v[0:15]
	ds_read_b128 v[228:231], v184 offset:4640
	s_setprio 0
	global_load_dwordx4 v[198:201], v[136:137], off offset:2304
	global_load_dwordx4 v[202:205], v[140:141], off offset:2304
	s_setprio 1
	s_waitcnt lgkmcnt(1)
	v_mfma_f32_32x32x16_bf16 v[112:127], v[208:211], v[224:227], v[112:127]
	v_mfma_f32_32x32x16_bf16 v[48:63], v[212:215], v[224:227], v[48:63]
	s_waitcnt lgkmcnt(0)
	v_mfma_f32_32x32x16_bf16 v[96:111], v[208:211], v[228:231], v[96:111]
	v_mfma_f32_32x32x16_bf16 v[32:47], v[212:215], v[228:231], v[32:47]
	ds_read_b128 v[224:227], v184 offset:9248
	ds_read_b128 v[228:231], v184 offset:13856
	s_waitcnt vmcnt(7)
	ds_write_b128 v177, v[178:181]
	s_waitcnt vmcnt(6)
	ds_write_b128 v176, v[216:219]
	ds_read_b128 v[178:181], v192 offset:36928
	ds_read_b128 v[216:219], v192 offset:41536
	s_waitcnt lgkmcnt(5)
	v_mfma_f32_32x32x16_bf16 v[80:95], v[208:211], v[224:227], v[80:95]
	v_mfma_f32_32x32x16_bf16 v[16:31], v[212:215], v[224:227], v[16:31]
	ds_read_b128 v[224:227], v184 offset:64
	s_waitcnt lgkmcnt(5)
	v_mfma_f32_32x32x16_bf16 v[64:79], v[208:211], v[228:231], v[64:79]
	v_mfma_f32_32x32x16_bf16 v[0:15], v[212:215], v[228:231], v[0:15]
	ds_read_b128 v[228:231], v184 offset:4672
	s_setprio 0
	global_load_dwordx4 v[208:211], v[144:145], off offset:2304
	global_load_dwordx4 v[212:215], v[148:149], off offset:2304
	s_setprio 1
	s_waitcnt lgkmcnt(1)
	v_mfma_f32_32x32x16_bf16 v[112:127], v[178:181], v[224:227], v[112:127]
	v_mfma_f32_32x32x16_bf16 v[48:63], v[216:219], v[224:227], v[48:63]
	s_waitcnt lgkmcnt(0)
	v_mfma_f32_32x32x16_bf16 v[96:111], v[178:181], v[228:231], v[96:111]
	v_mfma_f32_32x32x16_bf16 v[32:47], v[216:219], v[228:231], v[32:47]
	ds_read_b128 v[224:227], v184 offset:9280
	ds_read_b128 v[228:231], v184 offset:13888
	s_waitcnt vmcnt(7)
	ds_write_b128 v171, v[172:175]
	s_waitcnt vmcnt(6)
	ds_write_b128 v170, v[220:223]
	ds_read_b128 v[172:175], v192 offset:36960
	ds_read_b128 v[220:223], v192 offset:41568
	s_waitcnt lgkmcnt(5)
	v_mfma_f32_32x32x16_bf16 v[80:95], v[178:181], v[224:227], v[80:95]
	v_mfma_f32_32x32x16_bf16 v[16:31], v[216:219], v[224:227], v[16:31]
	ds_read_b128 v[224:227], v184 offset:96
	s_waitcnt lgkmcnt(5)
	v_mfma_f32_32x32x16_bf16 v[64:79], v[178:181], v[228:231], v[64:79]
	v_mfma_f32_32x32x16_bf16 v[0:15], v[216:219], v[228:231], v[0:15]
	ds_read_b128 v[228:231], v184 offset:4704
	s_setprio 0
	global_load_dwordx4 v[178:181], v[152:153], off offset:2304
	global_load_dwordx4 v[216:219], v[156:157], off offset:2304
	s_setprio 1
	s_waitcnt lgkmcnt(1)
	v_mfma_f32_32x32x16_bf16 v[112:127], v[172:175], v[224:227], v[112:127]
	v_mfma_f32_32x32x16_bf16 v[48:63], v[220:223], v[224:227], v[48:63]
	s_waitcnt lgkmcnt(0)
	v_mfma_f32_32x32x16_bf16 v[96:111], v[172:175], v[228:231], v[96:111]
	v_mfma_f32_32x32x16_bf16 v[32:47], v[220:223], v[228:231], v[32:47]
	ds_read_b128 v[224:227], v184 offset:9312
	ds_read_b128 v[228:231], v184 offset:13920
	s_waitcnt lgkmcnt(0)
	s_barrier
; template <bool trans>
; DI void gemm_core(const GTile& tl, const GTile& nx, bool has_next  , bool chain  , bool pre, u32x4 (&ra)[4], u32x4 (&rb)[4], char* smem, f32x16 (&acc)[2][4]) {
;     ...
;   const int nk = K / 64;
;   if (!pre) { G_LOAD(0); G_STORE(0); G_LOAD(1); }
;   for (int kt = 0; kt < nk; ++kt) {
;     __syncthreads();
;     G_COMPUTE(kt & 1, kt);
	s_waitcnt vmcnt(7)
	ds_write_b128 v191, v[158:161]
	s_waitcnt vmcnt(6)
	ds_write_b128 v191, v[162:165] offset:36864
	ds_read_b128 v[158:161], v169
	ds_read_b128 v[162:165], v169 offset:4608
	v_mfma_f32_32x32x16_bf16 v[80:95], v[172:175], v[224:227], v[80:95]
	v_mfma_f32_32x32x16_bf16 v[16:31], v[220:223], v[224:227], v[16:31]
	ds_read_b128 v[224:227], v168
	v_mfma_f32_32x32x16_bf16 v[64:79], v[172:175], v[228:231], v[64:79]
	v_mfma_f32_32x32x16_bf16 v[0:15], v[220:223], v[228:231], v[0:15]
	ds_read_b128 v[228:231], v168 offset:4608
	s_setprio 0
	global_load_dwordx4 v[172:175], v[128:129], off offset:2432
	global_load_dwordx4 v[220:223], v[132:133], off offset:2432
	s_setprio 1
	s_waitcnt lgkmcnt(1)
	v_mfma_f32_32x32x16_bf16 v[112:127], v[158:161], v[224:227], v[112:127]
	v_mfma_f32_32x32x16_bf16 v[48:63], v[162:165], v[224:227], v[48:63]
	s_waitcnt lgkmcnt(0)
	v_mfma_f32_32x32x16_bf16 v[96:111], v[158:161], v[228:231], v[96:111]
	v_mfma_f32_32x32x16_bf16 v[32:47], v[162:165], v[228:231], v[32:47]
	ds_read_b128 v[224:227], v168 offset:9216
	ds_read_b128 v[228:231], v168 offset:13824
	s_waitcnt vmcnt(7)
	ds_write_b128 v191, v[198:201] offset:9216
	s_waitcnt vmcnt(6)
	ds_write_b128 v191, v[202:205] offset:46080
	ds_read_b128 v[198:201], v169 offset:32
	ds_read_b128 v[202:205], v169 offset:4640
	s_waitcnt lgkmcnt(5)
	v_mfma_f32_32x32x16_bf16 v[80:95], v[158:161], v[224:227], v[80:95]
	v_mfma_f32_32x32x16_bf16 v[16:31], v[162:165], v[224:227], v[16:31]
	ds_read_b128 v[224:227], v168 offset:32
	s_waitcnt lgkmcnt(5)
	v_mfma_f32_32x32x16_bf16 v[64:79], v[158:161], v[228:231], v[64:79]
	v_mfma_f32_32x32x16_bf16 v[0:15], v[162:165], v[228:231], v[0:15]
	ds_read_b128 v[228:231], v168 offset:4640
	s_setprio 0
	global_load_dwordx4 v[158:161], v[136:137], off offset:2432
	global_load_dwordx4 v[162:165], v[140:141], off offset:2432
	s_setprio 1
	s_waitcnt lgkmcnt(1)
	v_mfma_f32_32x32x16_bf16 v[112:127], v[198:201], v[224:227], v[112:127]
	v_mfma_f32_32x32x16_bf16 v[48:63], v[202:205], v[224:227], v[48:63]
	s_waitcnt lgkmcnt(0)
	v_mfma_f32_32x32x16_bf16 v[96:111], v[198:201], v[228:231], v[96:111]
	v_mfma_f32_32x32x16_bf16 v[32:47], v[202:205], v[228:231], v[32:47]
	ds_read_b128 v[224:227], v168 offset:9248
	ds_read_b128 v[228:231], v168 offset:13856
	s_waitcnt vmcnt(7)
	ds_write_b128 v191, v[208:211] offset:18432
	s_waitcnt vmcnt(6)
	ds_write_b128 v191, v[212:215] offset:55296
	ds_read_b128 v[208:211], v169 offset:64
	ds_read_b128 v[212:215], v169 offset:4672
	s_waitcnt lgkmcnt(5)
	v_mfma_f32_32x32x16_bf16 v[80:95], v[198:201], v[224:227], v[80:95]
	v_mfma_f32_32x32x16_bf16 v[16:31], v[202:205], v[224:227], v[16:31]
	ds_read_b128 v[224:227], v168 offset:64
	s_waitcnt lgkmcnt(5)
	v_mfma_f32_32x32x16_bf16 v[64:79], v[198:201], v[228:231], v[64:79]
	v_mfma_f32_32x32x16_bf16 v[0:15], v[202:205], v[228:231], v[0:15]
	ds_read_b128 v[228:231], v168 offset:4672
	s_setprio 0
	global_load_dwordx4 v[198:201], v[144:145], off offset:2432
	global_load_dwordx4 v[202:205], v[148:149], off offset:2432
	s_setprio 1
	s_waitcnt lgkmcnt(1)
	v_mfma_f32_32x32x16_bf16 v[112:127], v[208:211], v[224:227], v[112:127]
	v_mfma_f32_32x32x16_bf16 v[48:63], v[212:215], v[224:227], v[48:63]
	s_waitcnt lgkmcnt(0)
	v_mfma_f32_32x32x16_bf16 v[96:111], v[208:211], v[228:231], v[96:111]
	v_mfma_f32_32x32x16_bf16 v[32:47], v[212:215], v[228:231], v[32:47]
	ds_read_b128 v[224:227], v168 offset:9280
	ds_read_b128 v[228:231], v168 offset:13888
	s_waitcnt vmcnt(7)
	ds_write_b128 v191, v[178:181] offset:27648
	s_waitcnt vmcnt(6)
	ds_write_b128 v191, v[216:219] offset:64512
	ds_read_b128 v[178:181], v169 offset:96
	ds_read_b128 v[216:219], v169 offset:4704
	s_waitcnt lgkmcnt(5)
	v_mfma_f32_32x32x16_bf16 v[80:95], v[208:211], v[224:227], v[80:95]
	v_mfma_f32_32x32x16_bf16 v[16:31], v[212:215], v[224:227], v[16:31]
	ds_read_b128 v[224:227], v168 offset:96
	s_waitcnt lgkmcnt(5)
	v_mfma_f32_32x32x16_bf16 v[64:79], v[208:211], v[228:231], v[64:79]
	v_mfma_f32_32x32x16_bf16 v[0:15], v[212:215], v[228:231], v[0:15]
	ds_read_b128 v[228:231], v168 offset:4704
	s_setprio 0
	global_load_dwordx4 v[208:211], v[152:153], off offset:2432
	global_load_dwordx4 v[212:215], v[156:157], off offset:2432
	s_setprio 1
	s_waitcnt lgkmcnt(1)
	v_mfma_f32_32x32x16_bf16 v[112:127], v[178:181], v[224:227], v[112:127]
	v_mfma_f32_32x32x16_bf16 v[48:63], v[216:219], v[224:227], v[48:63]
	s_waitcnt lgkmcnt(0)
	v_mfma_f32_32x32x16_bf16 v[96:111], v[178:181], v[228:231], v[96:111]
	v_mfma_f32_32x32x16_bf16 v[32:47], v[216:219], v[228:231], v[32:47]
	ds_read_b128 v[224:227], v168 offset:9312
	ds_read_b128 v[228:231], v168 offset:13920
	s_waitcnt lgkmcnt(0)
	s_barrier
; template <bool trans>
; DI void gemm_core(const GTile& tl, const GTile& nx, bool has_next  , bool chain  , bool pre, u32x4 (&ra)[4], u32x4 (&rb)[4], char* smem, f32x16 (&acc)[2][4]) {
;     ...
;   const int nk = K / 64;
;   if (!pre) { G_LOAD(0); G_STORE(0); G_LOAD(1); }
;   for (int kt = 0; kt < nk; ++kt) {
;     __syncthreads();
;     G_COMPUTE(kt & 1, kt);
	s_waitcnt vmcnt(7)
	ds_write_b128 v195, v[172:175]
	s_waitcnt vmcnt(6)
	ds_write_b128 v196, v[220:223]
	ds_read_b128 v[172:175], v192 offset:36864
	ds_read_b128 v[220:223], v192 offset:41472
	v_mfma_f32_32x32x16_bf16 v[80:95], v[178:181], v[224:227], v[80:95]
	v_mfma_f32_32x32x16_bf16 v[16:31], v[216:219], v[224:227], v[16:31]
	ds_read_b128 v[224:227], v184
	v_mfma_f32_32x32x16_bf16 v[64:79], v[178:181], v[228:231], v[64:79]
	v_mfma_f32_32x32x16_bf16 v[0:15], v[216:219], v[228:231], v[0:15]
	ds_read_b128 v[228:231], v184 offset:4608
	s_setprio 0
	global_load_dwordx4 v[178:181], v[128:129], off offset:2560
	global_load_dwordx4 v[216:219], v[132:133], off offset:2560
	s_setprio 1
	s_waitcnt lgkmcnt(1)
	v_mfma_f32_32x32x16_bf16 v[112:127], v[172:175], v[224:227], v[112:127]
	v_mfma_f32_32x32x16_bf16 v[48:63], v[220:223], v[224:227], v[48:63]
	s_waitcnt lgkmcnt(0)
	v_mfma_f32_32x32x16_bf16 v[96:111], v[172:175], v[228:231], v[96:111]
	v_mfma_f32_32x32x16_bf16 v[32:47], v[220:223], v[228:231], v[32:47]
	ds_read_b128 v[224:227], v184 offset:9216
	ds_read_b128 v[228:231], v184 offset:13824
	s_waitcnt vmcnt(7)
	ds_write_b128 v194, v[158:161]
	s_waitcnt vmcnt(6)
	ds_write_b128 v193, v[162:165]
	ds_read_b128 v[158:161], v192 offset:36896
	ds_read_b128 v[162:165], v192 offset:41504
	s_waitcnt lgkmcnt(5)
	v_mfma_f32_32x32x16_bf16 v[80:95], v[172:175], v[224:227], v[80:95]
	v_mfma_f32_32x32x16_bf16 v[16:31], v[220:223], v[224:227], v[16:31]
	ds_read_b128 v[224:227], v184 offset:32
	s_waitcnt lgkmcnt(5)
	v_mfma_f32_32x32x16_bf16 v[64:79], v[172:175], v[228:231], v[64:79]
	v_mfma_f32_32x32x16_bf16 v[0:15], v[220:223], v[228:231], v[0:15]
	ds_read_b128 v[228:231], v184 offset:4640
	s_setprio 0
	global_load_dwordx4 v[172:175], v[136:137], off offset:2560
	global_load_dwordx4 v[220:223], v[140:141], off offset:2560
	s_setprio 1
	s_waitcnt lgkmcnt(1)
	v_mfma_f32_32x32x16_bf16 v[112:127], v[158:161], v[224:227], v[112:127]
	v_mfma_f32_32x32x16_bf16 v[48:63], v[162:165], v[224:227], v[48:63]
	s_waitcnt lgkmcnt(0)
	v_mfma_f32_32x32x16_bf16 v[96:111], v[158:161], v[228:231], v[96:111]
	v_mfma_f32_32x32x16_bf16 v[32:47], v[162:165], v[228:231], v[32:47]
	ds_read_b128 v[224:227], v184 offset:9248
	ds_read_b128 v[228:231], v184 offset:13856
	s_waitcnt vmcnt(7)
	ds_write_b128 v177, v[198:201]
	s_waitcnt vmcnt(6)
	ds_write_b128 v176, v[202:205]
	ds_read_b128 v[198:201], v192 offset:36928
	ds_read_b128 v[202:205], v192 offset:41536
	s_waitcnt lgkmcnt(5)
	v_mfma_f32_32x32x16_bf16 v[80:95], v[158:161], v[224:227], v[80:95]
	v_mfma_f32_32x32x16_bf16 v[16:31], v[162:165], v[224:227], v[16:31]
	ds_read_b128 v[224:227], v184 offset:64
	s_waitcnt lgkmcnt(5)
	v_mfma_f32_32x32x16_bf16 v[64:79], v[158:161], v[228:231], v[64:79]
	v_mfma_f32_32x32x16_bf16 v[0:15], v[162:165], v[228:231], v[0:15]
	ds_read_b128 v[228:231], v184 offset:4672
	s_setprio 0
	global_load_dwordx4 v[158:161], v[144:145], off offset:2560
	global_load_dwordx4 v[162:165], v[148:149], off offset:2560
	s_setprio 1
	s_waitcnt lgkmcnt(1)
	v_mfma_f32_32x32x16_bf16 v[112:127], v[198:201], v[224:227], v[112:127]
	v_mfma_f32_32x32x16_bf16 v[48:63], v[202:205], v[224:227], v[48:63]
	s_waitcnt lgkmcnt(0)
	v_mfma_f32_32x32x16_bf16 v[96:111], v[198:201], v[228:231], v[96:111]
	v_mfma_f32_32x32x16_bf16 v[32:47], v[202:205], v[228:231], v[32:47]
	ds_read_b128 v[224:227], v184 offset:9280
	ds_read_b128 v[228:231], v184 offset:13888
	s_waitcnt vmcnt(7)
	ds_write_b128 v171, v[208:211]
	s_waitcnt vmcnt(6)
	ds_write_b128 v170, v[212:215]
	ds_read_b128 v[208:211], v192 offset:36960
	ds_read_b128 v[212:215], v192 offset:41568
	s_waitcnt lgkmcnt(5)
	v_mfma_f32_32x32x16_bf16 v[80:95], v[198:201], v[224:227], v[80:95]
	v_mfma_f32_32x32x16_bf16 v[16:31], v[202:205], v[224:227], v[16:31]
	ds_read_b128 v[224:227], v184 offset:96
	s_waitcnt lgkmcnt(5)
	v_mfma_f32_32x32x16_bf16 v[64:79], v[198:201], v[228:231], v[64:79]
	v_mfma_f32_32x32x16_bf16 v[0:15], v[202:205], v[228:231], v[0:15]
	ds_read_b128 v[228:231], v184 offset:4704
	s_setprio 0
	global_load_dwordx4 v[198:201], v[152:153], off offset:2560
	global_load_dwordx4 v[202:205], v[156:157], off offset:2560
	s_setprio 1
	s_waitcnt lgkmcnt(1)
	v_mfma_f32_32x32x16_bf16 v[112:127], v[208:211], v[224:227], v[112:127]
	v_mfma_f32_32x32x16_bf16 v[48:63], v[212:215], v[224:227], v[48:63]
	s_waitcnt lgkmcnt(0)
	v_mfma_f32_32x32x16_bf16 v[96:111], v[208:211], v[228:231], v[96:111]
	v_mfma_f32_32x32x16_bf16 v[32:47], v[212:215], v[228:231], v[32:47]
	ds_read_b128 v[224:227], v184 offset:9312
	ds_read_b128 v[228:231], v184 offset:13920
	s_waitcnt lgkmcnt(0)
	s_barrier
; template <bool trans>
; DI void gemm_core(const GTile& tl, const GTile& nx, bool has_next  , bool chain  , bool pre, u32x4 (&ra)[4], u32x4 (&rb)[4], char* smem, f32x16 (&acc)[2][4]) {
;     ...
;   const int nk = K / 64;
;   if (!pre) { G_LOAD(0); G_STORE(0); G_LOAD(1); }
;   for (int kt = 0; kt < nk; ++kt) {
;     __syncthreads();
;     G_COMPUTE(kt & 1, kt);
	s_waitcnt vmcnt(7)
	ds_write_b128 v191, v[178:181]
	s_waitcnt vmcnt(6)
	ds_write_b128 v191, v[216:219] offset:36864
	ds_read_b128 v[178:181], v169
	ds_read_b128 v[216:219], v169 offset:4608
	v_mfma_f32_32x32x16_bf16 v[80:95], v[208:211], v[224:227], v[80:95]
	v_mfma_f32_32x32x16_bf16 v[16:31], v[212:215], v[224:227], v[16:31]
	ds_read_b128 v[224:227], v168
	v_mfma_f32_32x32x16_bf16 v[64:79], v[208:211], v[228:231], v[64:79]
	v_mfma_f32_32x32x16_bf16 v[0:15], v[212:215], v[228:231], v[0:15]
	ds_read_b128 v[228:231], v168 offset:4608
	s_setprio 0
	global_load_dwordx4 v[208:211], v[128:129], off offset:2688
	global_load_dwordx4 v[212:215], v[132:133], off offset:2688
	s_setprio 1
	s_waitcnt lgkmcnt(1)
	v_mfma_f32_32x32x16_bf16 v[112:127], v[178:181], v[224:227], v[112:127]
	v_mfma_f32_32x32x16_bf16 v[48:63], v[216:219], v[224:227], v[48:63]
	s_waitcnt lgkmcnt(0)
	v_mfma_f32_32x32x16_bf16 v[96:111], v[178:181], v[228:231], v[96:111]
	v_mfma_f32_32x32x16_bf16 v[32:47], v[216:219], v[228:231], v[32:47]
	ds_read_b128 v[224:227], v168 offset:9216
	ds_read_b128 v[228:231], v168 offset:13824
	s_waitcnt vmcnt(7)
	ds_write_b128 v191, v[172:175] offset:9216
	s_waitcnt vmcnt(6)
	ds_write_b128 v191, v[220:223] offset:46080
	ds_read_b128 v[172:175], v169 offset:32
	ds_read_b128 v[220:223], v169 offset:4640
	s_waitcnt lgkmcnt(5)
	v_mfma_f32_32x32x16_bf16 v[80:95], v[178:181], v[224:227], v[80:95]
	v_mfma_f32_32x32x16_bf16 v[16:31], v[216:219], v[224:227], v[16:31]
	ds_read_b128 v[224:227], v168 offset:32
	s_waitcnt lgkmcnt(5)
	v_mfma_f32_32x32x16_bf16 v[64:79], v[178:181], v[228:231], v[64:79]
	v_mfma_f32_32x32x16_bf16 v[0:15], v[216:219], v[228:231], v[0:15]
	ds_read_b128 v[228:231], v168 offset:4640
	s_setprio 0
	global_load_dwordx4 v[178:181], v[136:137], off offset:2688
	global_load_dwordx4 v[216:219], v[140:141], off offset:2688
	s_setprio 1
	s_waitcnt lgkmcnt(1)
	v_mfma_f32_32x32x16_bf16 v[112:127], v[172:175], v[224:227], v[112:127]
	v_mfma_f32_32x32x16_bf16 v[48:63], v[220:223], v[224:227], v[48:63]
	s_waitcnt lgkmcnt(0)
	v_mfma_f32_32x32x16_bf16 v[96:111], v[172:175], v[228:231], v[96:111]
	v_mfma_f32_32x32x16_bf16 v[32:47], v[220:223], v[228:231], v[32:47]
	ds_read_b128 v[224:227], v168 offset:9248
	ds_read_b128 v[228:231], v168 offset:13856
	s_waitcnt vmcnt(7)
	ds_write_b128 v191, v[158:161] offset:18432
	s_waitcnt vmcnt(6)
	ds_write_b128 v191, v[162:165] offset:55296
	ds_read_b128 v[158:161], v169 offset:64
	ds_read_b128 v[162:165], v169 offset:4672
	s_waitcnt lgkmcnt(5)
	v_mfma_f32_32x32x16_bf16 v[80:95], v[172:175], v[224:227], v[80:95]
	v_mfma_f32_32x32x16_bf16 v[16:31], v[220:223], v[224:227], v[16:31]
	ds_read_b128 v[224:227], v168 offset:64
	s_waitcnt lgkmcnt(5)
	v_mfma_f32_32x32x16_bf16 v[64:79], v[172:175], v[228:231], v[64:79]
	v_mfma_f32_32x32x16_bf16 v[0:15], v[220:223], v[228:231], v[0:15]
	ds_read_b128 v[228:231], v168 offset:4672
	s_setprio 0
	global_load_dwordx4 v[172:175], v[144:145], off offset:2688
	global_load_dwordx4 v[220:223], v[148:149], off offset:2688
	s_setprio 1
	s_waitcnt lgkmcnt(1)
	v_mfma_f32_32x32x16_bf16 v[112:127], v[158:161], v[224:227], v[112:127]
	v_mfma_f32_32x32x16_bf16 v[48:63], v[162:165], v[224:227], v[48:63]
	s_waitcnt lgkmcnt(0)
	v_mfma_f32_32x32x16_bf16 v[96:111], v[158:161], v[228:231], v[96:111]
	v_mfma_f32_32x32x16_bf16 v[32:47], v[162:165], v[228:231], v[32:47]
	ds_read_b128 v[224:227], v168 offset:9280
	ds_read_b128 v[228:231], v168 offset:13888
	s_waitcnt vmcnt(7)
	ds_write_b128 v191, v[198:201] offset:27648
	s_waitcnt vmcnt(6)
	ds_write_b128 v191, v[202:205] offset:64512
	ds_read_b128 v[198:201], v169 offset:96
	ds_read_b128 v[202:205], v169 offset:4704
	s_waitcnt lgkmcnt(5)
	v_mfma_f32_32x32x16_bf16 v[80:95], v[158:161], v[224:227], v[80:95]
	v_mfma_f32_32x32x16_bf16 v[16:31], v[162:165], v[224:227], v[16:31]
	ds_read_b128 v[224:227], v168 offset:96
	s_waitcnt lgkmcnt(5)
	v_mfma_f32_32x32x16_bf16 v[64:79], v[158:161], v[228:231], v[64:79]
	v_mfma_f32_32x32x16_bf16 v[0:15], v[162:165], v[228:231], v[0:15]
	ds_read_b128 v[228:231], v168 offset:4704
	s_setprio 0
	global_load_dwordx4 v[158:161], v[152:153], off offset:2688
	global_load_dwordx4 v[162:165], v[156:157], off offset:2688
	s_setprio 1
	s_waitcnt lgkmcnt(1)
	v_mfma_f32_32x32x16_bf16 v[112:127], v[198:201], v[224:227], v[112:127]
	v_mfma_f32_32x32x16_bf16 v[48:63], v[202:205], v[224:227], v[48:63]
	s_waitcnt lgkmcnt(0)
	v_mfma_f32_32x32x16_bf16 v[96:111], v[198:201], v[228:231], v[96:111]
	v_mfma_f32_32x32x16_bf16 v[32:47], v[202:205], v[228:231], v[32:47]
	ds_read_b128 v[224:227], v168 offset:9312
	ds_read_b128 v[228:231], v168 offset:13920
	s_waitcnt lgkmcnt(0)
	s_barrier
; template <bool trans>
; DI void gemm_core(const GTile& tl, const GTile& nx, bool has_next  , bool chain  , bool pre, u32x4 (&ra)[4], u32x4 (&rb)[4], char* smem, f32x16 (&acc)[2][4]) {
;     ...
;   const int nk = K / 64;
;   if (!pre) { G_LOAD(0); G_STORE(0); G_LOAD(1); }
;   for (int kt = 0; kt < nk; ++kt) {
;     __syncthreads();
;     G_COMPUTE(kt & 1, kt);
	s_waitcnt vmcnt(7)
	ds_write_b128 v195, v[208:211]
	s_waitcnt vmcnt(6)
	ds_write_b128 v196, v[212:215]
	ds_read_b128 v[208:211], v192 offset:36864
	ds_read_b128 v[212:215], v192 offset:41472
	v_mfma_f32_32x32x16_bf16 v[80:95], v[198:201], v[224:227], v[80:95]
	v_mfma_f32_32x32x16_bf16 v[16:31], v[202:205], v[224:227], v[16:31]
	ds_read_b128 v[224:227], v184
	v_mfma_f32_32x32x16_bf16 v[64:79], v[198:201], v[228:231], v[64:79]
	v_mfma_f32_32x32x16_bf16 v[0:15], v[202:205], v[228:231], v[0:15]
	ds_read_b128 v[228:231], v184 offset:4608
	s_setprio 0
	global_load_dwordx4 v[198:201], v[128:129], off offset:2816
	global_load_dwordx4 v[202:205], v[132:133], off offset:2816
	s_setprio 1
	s_waitcnt lgkmcnt(1)
	v_mfma_f32_32x32x16_bf16 v[112:127], v[208:211], v[224:227], v[112:127]
	v_mfma_f32_32x32x16_bf16 v[48:63], v[212:215], v[224:227], v[48:63]
	s_waitcnt lgkmcnt(0)
	v_mfma_f32_32x32x16_bf16 v[96:111], v[208:211], v[228:231], v[96:111]
	v_mfma_f32_32x32x16_bf16 v[32:47], v[212:215], v[228:231], v[32:47]
	ds_read_b128 v[224:227], v184 offset:9216
	ds_read_b128 v[228:231], v184 offset:13824
	s_waitcnt vmcnt(7)
	ds_write_b128 v194, v[178:181]
	s_waitcnt vmcnt(6)
	ds_write_b128 v193, v[216:219]
	ds_read_b128 v[178:181], v192 offset:36896
	ds_read_b128 v[216:219], v192 offset:41504
	s_waitcnt lgkmcnt(5)
	v_mfma_f32_32x32x16_bf16 v[80:95], v[208:211], v[224:227], v[80:95]
	v_mfma_f32_32x32x16_bf16 v[16:31], v[212:215], v[224:227], v[16:31]
	ds_read_b128 v[224:227], v184 offset:32
	s_waitcnt lgkmcnt(5)
	v_mfma_f32_32x32x16_bf16 v[64:79], v[208:211], v[228:231], v[64:79]
	v_mfma_f32_32x32x16_bf16 v[0:15], v[212:215], v[228:231], v[0:15]
	ds_read_b128 v[228:231], v184 offset:4640
	s_setprio 0
	global_load_dwordx4 v[208:211], v[136:137], off offset:2816
	global_load_dwordx4 v[212:215], v[140:141], off offset:2816
	s_setprio 1
	s_waitcnt lgkmcnt(1)
	v_mfma_f32_32x32x16_bf16 v[112:127], v[178:181], v[224:227], v[112:127]
	v_mfma_f32_32x32x16_bf16 v[48:63], v[216:219], v[224:227], v[48:63]
	s_waitcnt lgkmcnt(0)
	v_mfma_f32_32x32x16_bf16 v[96:111], v[178:181], v[228:231], v[96:111]
	v_mfma_f32_32x32x16_bf16 v[32:47], v[216:219], v[228:231], v[32:47]
	ds_read_b128 v[224:227], v184 offset:9248
	ds_read_b128 v[228:231], v184 offset:13856
	s_waitcnt vmcnt(7)
	ds_write_b128 v177, v[172:175]
	s_waitcnt vmcnt(6)
	ds_write_b128 v176, v[220:223]
	ds_read_b128 v[172:175], v192 offset:36928
	ds_read_b128 v[220:223], v192 offset:41536
	s_waitcnt lgkmcnt(5)
	v_mfma_f32_32x32x16_bf16 v[80:95], v[178:181], v[224:227], v[80:95]
	v_mfma_f32_32x32x16_bf16 v[16:31], v[216:219], v[224:227], v[16:31]
	ds_read_b128 v[224:227], v184 offset:64
	s_waitcnt lgkmcnt(5)
	v_mfma_f32_32x32x16_bf16 v[64:79], v[178:181], v[228:231], v[64:79]
	v_mfma_f32_32x32x16_bf16 v[0:15], v[216:219], v[228:231], v[0:15]
	ds_read_b128 v[228:231], v184 offset:4672
	s_setprio 0
	global_load_dwordx4 v[178:181], v[144:145], off offset:2816
	global_load_dwordx4 v[216:219], v[148:149], off offset:2816
	s_setprio 1
	s_waitcnt lgkmcnt(1)
	v_mfma_f32_32x32x16_bf16 v[112:127], v[172:175], v[224:227], v[112:127]
	v_mfma_f32_32x32x16_bf16 v[48:63], v[220:223], v[224:227], v[48:63]
	s_waitcnt lgkmcnt(0)
	v_mfma_f32_32x32x16_bf16 v[96:111], v[172:175], v[228:231], v[96:111]
	v_mfma_f32_32x32x16_bf16 v[32:47], v[220:223], v[228:231], v[32:47]
	ds_read_b128 v[224:227], v184 offset:9280
	ds_read_b128 v[228:231], v184 offset:13888
	s_waitcnt vmcnt(7)
	ds_write_b128 v171, v[158:161]
	s_waitcnt vmcnt(6)
	ds_write_b128 v170, v[162:165]
	ds_read_b128 v[158:161], v192 offset:36960
	ds_read_b128 v[162:165], v192 offset:41568
	s_waitcnt lgkmcnt(5)
	v_mfma_f32_32x32x16_bf16 v[80:95], v[172:175], v[224:227], v[80:95]
	v_mfma_f32_32x32x16_bf16 v[16:31], v[220:223], v[224:227], v[16:31]
	ds_read_b128 v[224:227], v184 offset:96
	s_waitcnt lgkmcnt(5)
	v_mfma_f32_32x32x16_bf16 v[64:79], v[172:175], v[228:231], v[64:79]
	v_mfma_f32_32x32x16_bf16 v[0:15], v[220:223], v[228:231], v[0:15]
	ds_read_b128 v[228:231], v184 offset:4704
	s_setprio 0
	global_load_dwordx4 v[172:175], v[152:153], off offset:2816
	global_load_dwordx4 v[220:223], v[156:157], off offset:2816
	s_setprio 1
	s_waitcnt lgkmcnt(1)
	v_mfma_f32_32x32x16_bf16 v[112:127], v[158:161], v[224:227], v[112:127]
	v_mfma_f32_32x32x16_bf16 v[48:63], v[162:165], v[224:227], v[48:63]
	s_waitcnt lgkmcnt(0)
	v_mfma_f32_32x32x16_bf16 v[96:111], v[158:161], v[228:231], v[96:111]
	v_mfma_f32_32x32x16_bf16 v[32:47], v[162:165], v[228:231], v[32:47]
	ds_read_b128 v[224:227], v184 offset:9312
	ds_read_b128 v[228:231], v184 offset:13920
	s_waitcnt lgkmcnt(0)
	s_barrier
; template <bool trans>
; DI void gemm_core(const GTile& tl, const GTile& nx, bool has_next  , bool chain  , bool pre, u32x4 (&ra)[4], u32x4 (&rb)[4], char* smem, f32x16 (&acc)[2][4]) {
;     ...
;   const int nk = K / 64;
;   if (!pre) { G_LOAD(0); G_STORE(0); G_LOAD(1); }
;   for (int kt = 0; kt < nk; ++kt) {
;     __syncthreads();
;     G_COMPUTE(kt & 1, kt);
	s_waitcnt vmcnt(7)
	ds_write_b128 v191, v[198:201]
	s_waitcnt vmcnt(6)
	ds_write_b128 v191, v[202:205] offset:36864
	ds_read_b128 v[198:201], v169
	ds_read_b128 v[202:205], v169 offset:4608
	v_mfma_f32_32x32x16_bf16 v[80:95], v[158:161], v[224:227], v[80:95]
	v_mfma_f32_32x32x16_bf16 v[16:31], v[162:165], v[224:227], v[16:31]
	ds_read_b128 v[224:227], v168
	v_mfma_f32_32x32x16_bf16 v[64:79], v[158:161], v[228:231], v[64:79]
	v_mfma_f32_32x32x16_bf16 v[0:15], v[162:165], v[228:231], v[0:15]
	ds_read_b128 v[228:231], v168 offset:4608
	s_setprio 0
	global_load_dwordx4 v[158:161], v[128:129], off offset:2944
	global_load_dwordx4 v[162:165], v[132:133], off offset:2944
	s_setprio 1
	s_waitcnt lgkmcnt(1)
	v_mfma_f32_32x32x16_bf16 v[112:127], v[198:201], v[224:227], v[112:127]
	v_mfma_f32_32x32x16_bf16 v[48:63], v[202:205], v[224:227], v[48:63]
	s_waitcnt lgkmcnt(0)
	v_mfma_f32_32x32x16_bf16 v[96:111], v[198:201], v[228:231], v[96:111]
	v_mfma_f32_32x32x16_bf16 v[32:47], v[202:205], v[228:231], v[32:47]
	ds_read_b128 v[224:227], v168 offset:9216
	ds_read_b128 v[228:231], v168 offset:13824
	s_waitcnt vmcnt(7)
	ds_write_b128 v191, v[208:211] offset:9216
	s_waitcnt vmcnt(6)
	ds_write_b128 v191, v[212:215] offset:46080
	ds_read_b128 v[208:211], v169 offset:32
	ds_read_b128 v[212:215], v169 offset:4640
	s_waitcnt lgkmcnt(5)
	v_mfma_f32_32x32x16_bf16 v[80:95], v[198:201], v[224:227], v[80:95]
	v_mfma_f32_32x32x16_bf16 v[16:31], v[202:205], v[224:227], v[16:31]
	ds_read_b128 v[224:227], v168 offset:32
	s_waitcnt lgkmcnt(5)
	v_mfma_f32_32x32x16_bf16 v[64:79], v[198:201], v[228:231], v[64:79]
	v_mfma_f32_32x32x16_bf16 v[0:15], v[202:205], v[228:231], v[0:15]
	ds_read_b128 v[228:231], v168 offset:4640
	s_setprio 0
	global_load_dwordx4 v[198:201], v[136:137], off offset:2944
	global_load_dwordx4 v[202:205], v[140:141], off offset:2944
	s_setprio 1
	s_waitcnt lgkmcnt(1)
	v_mfma_f32_32x32x16_bf16 v[112:127], v[208:211], v[224:227], v[112:127]
	v_mfma_f32_32x32x16_bf16 v[48:63], v[212:215], v[224:227], v[48:63]
	s_waitcnt lgkmcnt(0)
	v_mfma_f32_32x32x16_bf16 v[96:111], v[208:211], v[228:231], v[96:111]
	v_mfma_f32_32x32x16_bf16 v[32:47], v[212:215], v[228:231], v[32:47]
	ds_read_b128 v[224:227], v168 offset:9248
	ds_read_b128 v[228:231], v168 offset:13856
	s_waitcnt vmcnt(7)
	ds_write_b128 v191, v[178:181] offset:18432
	s_waitcnt vmcnt(6)
	ds_write_b128 v191, v[216:219] offset:55296
	ds_read_b128 v[178:181], v169 offset:64
	ds_read_b128 v[216:219], v169 offset:4672
	s_waitcnt lgkmcnt(5)
	v_mfma_f32_32x32x16_bf16 v[80:95], v[208:211], v[224:227], v[80:95]
	v_mfma_f32_32x32x16_bf16 v[16:31], v[212:215], v[224:227], v[16:31]
	ds_read_b128 v[224:227], v168 offset:64
	s_waitcnt lgkmcnt(5)
	v_mfma_f32_32x32x16_bf16 v[64:79], v[208:211], v[228:231], v[64:79]
	v_mfma_f32_32x32x16_bf16 v[0:15], v[212:215], v[228:231], v[0:15]
	ds_read_b128 v[228:231], v168 offset:4672
	s_setprio 0
	global_load_dwordx4 v[208:211], v[144:145], off offset:2944
	global_load_dwordx4 v[212:215], v[148:149], off offset:2944
	s_setprio 1
	s_waitcnt lgkmcnt(1)
	v_mfma_f32_32x32x16_bf16 v[112:127], v[178:181], v[224:227], v[112:127]
	v_mfma_f32_32x32x16_bf16 v[48:63], v[216:219], v[224:227], v[48:63]
	s_waitcnt lgkmcnt(0)
	v_mfma_f32_32x32x16_bf16 v[96:111], v[178:181], v[228:231], v[96:111]
	v_mfma_f32_32x32x16_bf16 v[32:47], v[216:219], v[228:231], v[32:47]
	ds_read_b128 v[224:227], v168 offset:9280
	ds_read_b128 v[228:231], v168 offset:13888
	s_waitcnt vmcnt(7)
	ds_write_b128 v191, v[172:175] offset:27648
	s_waitcnt vmcnt(6)
	ds_write_b128 v191, v[220:223] offset:64512
	ds_read_b128 v[172:175], v169 offset:96
	ds_read_b128 v[220:223], v169 offset:4704
	s_waitcnt lgkmcnt(5)
	v_mfma_f32_32x32x16_bf16 v[80:95], v[178:181], v[224:227], v[80:95]
	v_mfma_f32_32x32x16_bf16 v[16:31], v[216:219], v[224:227], v[16:31]
	ds_read_b128 v[224:227], v168 offset:96
	s_waitcnt lgkmcnt(5)
	v_mfma_f32_32x32x16_bf16 v[64:79], v[178:181], v[228:231], v[64:79]
	v_mfma_f32_32x32x16_bf16 v[0:15], v[216:219], v[228:231], v[0:15]
	ds_read_b128 v[228:231], v168 offset:4704
	s_setprio 0
	global_load_dwordx4 v[178:181], v[152:153], off offset:2944
	global_load_dwordx4 v[216:219], v[156:157], off offset:2944
	s_setprio 1
	s_waitcnt lgkmcnt(1)
	v_mfma_f32_32x32x16_bf16 v[112:127], v[172:175], v[224:227], v[112:127]
	v_mfma_f32_32x32x16_bf16 v[48:63], v[220:223], v[224:227], v[48:63]
	s_waitcnt lgkmcnt(0)
	v_mfma_f32_32x32x16_bf16 v[96:111], v[172:175], v[228:231], v[96:111]
	v_mfma_f32_32x32x16_bf16 v[32:47], v[220:223], v[228:231], v[32:47]
	ds_read_b128 v[224:227], v168 offset:9312
	ds_read_b128 v[228:231], v168 offset:13920
	s_waitcnt lgkmcnt(0)
	s_barrier
; template <bool trans>
; DI void gemm_core(const GTile& tl, const GTile& nx, bool has_next  , bool chain  , bool pre, u32x4 (&ra)[4], u32x4 (&rb)[4], char* smem, f32x16 (&acc)[2][4]) {
;     ...
;   const int nk = K / 64;
;   if (!pre) { G_LOAD(0); G_STORE(0); G_LOAD(1); }
;   for (int kt = 0; kt < nk; ++kt) {
;     __syncthreads();
;     G_COMPUTE(kt & 1, kt);
	s_waitcnt vmcnt(7)
	ds_write_b128 v195, v[158:161]
	s_waitcnt vmcnt(6)
	ds_write_b128 v196, v[162:165]
	ds_read_b128 v[158:161], v192 offset:36864
	ds_read_b128 v[162:165], v192 offset:41472
	v_mfma_f32_32x32x16_bf16 v[80:95], v[172:175], v[224:227], v[80:95]
	v_mfma_f32_32x32x16_bf16 v[16:31], v[220:223], v[224:227], v[16:31]
	ds_read_b128 v[224:227], v184
	v_mfma_f32_32x32x16_bf16 v[64:79], v[172:175], v[228:231], v[64:79]
	v_mfma_f32_32x32x16_bf16 v[0:15], v[220:223], v[228:231], v[0:15]
	ds_read_b128 v[228:231], v184 offset:4608
	s_setprio 0
	global_load_dwordx4 v[172:175], v[128:129], off offset:3072
	global_load_dwordx4 v[220:223], v[132:133], off offset:3072
	s_setprio 1
	s_waitcnt lgkmcnt(1)
	v_mfma_f32_32x32x16_bf16 v[112:127], v[158:161], v[224:227], v[112:127]
	v_mfma_f32_32x32x16_bf16 v[48:63], v[162:165], v[224:227], v[48:63]
	s_waitcnt lgkmcnt(0)
	v_mfma_f32_32x32x16_bf16 v[96:111], v[158:161], v[228:231], v[96:111]
	v_mfma_f32_32x32x16_bf16 v[32:47], v[162:165], v[228:231], v[32:47]
	ds_read_b128 v[224:227], v184 offset:9216
	ds_read_b128 v[228:231], v184 offset:13824
	s_waitcnt vmcnt(7)
	ds_write_b128 v194, v[198:201]
	s_waitcnt vmcnt(6)
	ds_write_b128 v193, v[202:205]
	ds_read_b128 v[198:201], v192 offset:36896
	ds_read_b128 v[202:205], v192 offset:41504
	s_waitcnt lgkmcnt(5)
	v_mfma_f32_32x32x16_bf16 v[80:95], v[158:161], v[224:227], v[80:95]
	v_mfma_f32_32x32x16_bf16 v[16:31], v[162:165], v[224:227], v[16:31]
	ds_read_b128 v[224:227], v184 offset:32
	s_waitcnt lgkmcnt(5)
	v_mfma_f32_32x32x16_bf16 v[64:79], v[158:161], v[228:231], v[64:79]
	v_mfma_f32_32x32x16_bf16 v[0:15], v[162:165], v[228:231], v[0:15]
	ds_read_b128 v[228:231], v184 offset:4640
	s_setprio 0
	global_load_dwordx4 v[158:161], v[136:137], off offset:3072
	global_load_dwordx4 v[162:165], v[140:141], off offset:3072
	s_setprio 1
	s_waitcnt lgkmcnt(1)
	v_mfma_f32_32x32x16_bf16 v[112:127], v[198:201], v[224:227], v[112:127]
	v_mfma_f32_32x32x16_bf16 v[48:63], v[202:205], v[224:227], v[48:63]
	s_waitcnt lgkmcnt(0)
	v_mfma_f32_32x32x16_bf16 v[96:111], v[198:201], v[228:231], v[96:111]
	v_mfma_f32_32x32x16_bf16 v[32:47], v[202:205], v[228:231], v[32:47]
	ds_read_b128 v[224:227], v184 offset:9248
	ds_read_b128 v[228:231], v184 offset:13856
	s_waitcnt vmcnt(7)
	ds_write_b128 v177, v[208:211]
	s_waitcnt vmcnt(6)
	ds_write_b128 v176, v[212:215]
	ds_read_b128 v[208:211], v192 offset:36928
	ds_read_b128 v[212:215], v192 offset:41536
	s_waitcnt lgkmcnt(5)
	v_mfma_f32_32x32x16_bf16 v[80:95], v[198:201], v[224:227], v[80:95]
	v_mfma_f32_32x32x16_bf16 v[16:31], v[202:205], v[224:227], v[16:31]
	ds_read_b128 v[224:227], v184 offset:64
	s_waitcnt lgkmcnt(5)
	v_mfma_f32_32x32x16_bf16 v[64:79], v[198:201], v[228:231], v[64:79]
	v_mfma_f32_32x32x16_bf16 v[0:15], v[202:205], v[228:231], v[0:15]
	ds_read_b128 v[228:231], v184 offset:4672
	s_setprio 0
	global_load_dwordx4 v[198:201], v[144:145], off offset:3072
	global_load_dwordx4 v[202:205], v[148:149], off offset:3072
	s_setprio 1
	s_waitcnt lgkmcnt(1)
	v_mfma_f32_32x32x16_bf16 v[112:127], v[208:211], v[224:227], v[112:127]
	v_mfma_f32_32x32x16_bf16 v[48:63], v[212:215], v[224:227], v[48:63]
	s_waitcnt lgkmcnt(0)
	v_mfma_f32_32x32x16_bf16 v[96:111], v[208:211], v[228:231], v[96:111]
	v_mfma_f32_32x32x16_bf16 v[32:47], v[212:215], v[228:231], v[32:47]
	ds_read_b128 v[224:227], v184 offset:9280
	ds_read_b128 v[228:231], v184 offset:13888
	s_waitcnt vmcnt(7)
	ds_write_b128 v171, v[178:181]
	s_waitcnt vmcnt(6)
	ds_write_b128 v170, v[216:219]
	ds_read_b128 v[178:181], v192 offset:36960
	ds_read_b128 v[216:219], v192 offset:41568
	s_waitcnt lgkmcnt(5)
	v_mfma_f32_32x32x16_bf16 v[80:95], v[208:211], v[224:227], v[80:95]
	v_mfma_f32_32x32x16_bf16 v[16:31], v[212:215], v[224:227], v[16:31]
	ds_read_b128 v[224:227], v184 offset:96
	s_waitcnt lgkmcnt(5)
	v_mfma_f32_32x32x16_bf16 v[64:79], v[208:211], v[228:231], v[64:79]
	v_mfma_f32_32x32x16_bf16 v[0:15], v[212:215], v[228:231], v[0:15]
	ds_read_b128 v[228:231], v184 offset:4704
	s_setprio 0
	global_load_dwordx4 v[208:211], v[152:153], off offset:3072
	global_load_dwordx4 v[212:215], v[156:157], off offset:3072
	s_setprio 1
	s_waitcnt lgkmcnt(1)
	v_mfma_f32_32x32x16_bf16 v[112:127], v[178:181], v[224:227], v[112:127]
	v_mfma_f32_32x32x16_bf16 v[48:63], v[216:219], v[224:227], v[48:63]
	s_waitcnt lgkmcnt(0)
	v_mfma_f32_32x32x16_bf16 v[96:111], v[178:181], v[228:231], v[96:111]
	v_mfma_f32_32x32x16_bf16 v[32:47], v[216:219], v[228:231], v[32:47]
	ds_read_b128 v[224:227], v184 offset:9312
	ds_read_b128 v[228:231], v184 offset:13920
	s_waitcnt lgkmcnt(0)
	s_barrier
; template <bool trans>
; DI void gemm_core(const GTile& tl, const GTile& nx, bool has_next  , bool chain  , bool pre, u32x4 (&ra)[4], u32x4 (&rb)[4], char* smem, f32x16 (&acc)[2][4]) {
;     ...
;   const int nk = K / 64;
;   if (!pre) { G_LOAD(0); G_STORE(0); G_LOAD(1); }
;   for (int kt = 0; kt < nk; ++kt) {
;     __syncthreads();
;     G_COMPUTE(kt & 1, kt);
	s_waitcnt vmcnt(7)
	ds_write_b128 v191, v[172:175]
	s_waitcnt vmcnt(6)
	ds_write_b128 v191, v[220:223] offset:36864
	ds_read_b128 v[172:175], v169
	ds_read_b128 v[220:223], v169 offset:4608
	v_mfma_f32_32x32x16_bf16 v[80:95], v[178:181], v[224:227], v[80:95]
	v_mfma_f32_32x32x16_bf16 v[16:31], v[216:219], v[224:227], v[16:31]
	ds_read_b128 v[224:227], v168
	v_mfma_f32_32x32x16_bf16 v[64:79], v[178:181], v[228:231], v[64:79]
	v_mfma_f32_32x32x16_bf16 v[0:15], v[216:219], v[228:231], v[0:15]
	ds_read_b128 v[228:231], v168 offset:4608
	s_setprio 0
	global_load_dwordx4 v[178:181], v[128:129], off offset:3200
	global_load_dwordx4 v[216:219], v[132:133], off offset:3200
	s_setprio 1
	s_waitcnt lgkmcnt(1)
	v_mfma_f32_32x32x16_bf16 v[112:127], v[172:175], v[224:227], v[112:127]
	v_mfma_f32_32x32x16_bf16 v[48:63], v[220:223], v[224:227], v[48:63]
	s_waitcnt lgkmcnt(0)
	v_mfma_f32_32x32x16_bf16 v[96:111], v[172:175], v[228:231], v[96:111]
	v_mfma_f32_32x32x16_bf16 v[32:47], v[220:223], v[228:231], v[32:47]
	ds_read_b128 v[224:227], v168 offset:9216
	ds_read_b128 v[228:231], v168 offset:13824
	s_waitcnt vmcnt(7)
	ds_write_b128 v191, v[158:161] offset:9216
	s_waitcnt vmcnt(6)
	ds_write_b128 v191, v[162:165] offset:46080
	ds_read_b128 v[158:161], v169 offset:32
	ds_read_b128 v[162:165], v169 offset:4640
	s_waitcnt lgkmcnt(5)
	v_mfma_f32_32x32x16_bf16 v[80:95], v[172:175], v[224:227], v[80:95]
	v_mfma_f32_32x32x16_bf16 v[16:31], v[220:223], v[224:227], v[16:31]
	ds_read_b128 v[224:227], v168 offset:32
	s_waitcnt lgkmcnt(5)
	v_mfma_f32_32x32x16_bf16 v[64:79], v[172:175], v[228:231], v[64:79]
	v_mfma_f32_32x32x16_bf16 v[0:15], v[220:223], v[228:231], v[0:15]
	ds_read_b128 v[228:231], v168 offset:4640
	s_setprio 0
	global_load_dwordx4 v[172:175], v[136:137], off offset:3200
	global_load_dwordx4 v[220:223], v[140:141], off offset:3200
	s_setprio 1
	s_waitcnt lgkmcnt(1)
	v_mfma_f32_32x32x16_bf16 v[112:127], v[158:161], v[224:227], v[112:127]
	v_mfma_f32_32x32x16_bf16 v[48:63], v[162:165], v[224:227], v[48:63]
	s_waitcnt lgkmcnt(0)
	v_mfma_f32_32x32x16_bf16 v[96:111], v[158:161], v[228:231], v[96:111]
	v_mfma_f32_32x32x16_bf16 v[32:47], v[162:165], v[228:231], v[32:47]
	ds_read_b128 v[224:227], v168 offset:9248
	ds_read_b128 v[228:231], v168 offset:13856
	s_waitcnt vmcnt(7)
	ds_write_b128 v191, v[198:201] offset:18432
	s_waitcnt vmcnt(6)
	ds_write_b128 v191, v[202:205] offset:55296
	ds_read_b128 v[198:201], v169 offset:64
	ds_read_b128 v[202:205], v169 offset:4672
	s_waitcnt lgkmcnt(5)
	v_mfma_f32_32x32x16_bf16 v[80:95], v[158:161], v[224:227], v[80:95]
	v_mfma_f32_32x32x16_bf16 v[16:31], v[162:165], v[224:227], v[16:31]
	ds_read_b128 v[224:227], v168 offset:64
	s_waitcnt lgkmcnt(5)
	v_mfma_f32_32x32x16_bf16 v[64:79], v[158:161], v[228:231], v[64:79]
	v_mfma_f32_32x32x16_bf16 v[0:15], v[162:165], v[228:231], v[0:15]
	ds_read_b128 v[228:231], v168 offset:4672
	s_setprio 0
	global_load_dwordx4 v[158:161], v[144:145], off offset:3200
	global_load_dwordx4 v[162:165], v[148:149], off offset:3200
	s_setprio 1
	s_waitcnt lgkmcnt(1)
	v_mfma_f32_32x32x16_bf16 v[112:127], v[198:201], v[224:227], v[112:127]
	v_mfma_f32_32x32x16_bf16 v[48:63], v[202:205], v[224:227], v[48:63]
	s_waitcnt lgkmcnt(0)
	v_mfma_f32_32x32x16_bf16 v[96:111], v[198:201], v[228:231], v[96:111]
	v_mfma_f32_32x32x16_bf16 v[32:47], v[202:205], v[228:231], v[32:47]
	ds_read_b128 v[224:227], v168 offset:9280
	ds_read_b128 v[228:231], v168 offset:13888
	s_waitcnt vmcnt(7)
	ds_write_b128 v191, v[208:211] offset:27648
	s_waitcnt vmcnt(6)
	ds_write_b128 v191, v[212:215] offset:64512
	ds_read_b128 v[208:211], v169 offset:96
	ds_read_b128 v[212:215], v169 offset:4704
	s_waitcnt lgkmcnt(5)
	v_mfma_f32_32x32x16_bf16 v[80:95], v[198:201], v[224:227], v[80:95]
	v_mfma_f32_32x32x16_bf16 v[16:31], v[202:205], v[224:227], v[16:31]
	ds_read_b128 v[224:227], v168 offset:96
	s_waitcnt lgkmcnt(5)
	v_mfma_f32_32x32x16_bf16 v[64:79], v[198:201], v[228:231], v[64:79]
	v_mfma_f32_32x32x16_bf16 v[0:15], v[202:205], v[228:231], v[0:15]
	ds_read_b128 v[228:231], v168 offset:4704
	s_setprio 0
	global_load_dwordx4 v[198:201], v[152:153], off offset:3200
	global_load_dwordx4 v[202:205], v[156:157], off offset:3200
	s_setprio 1
	s_waitcnt lgkmcnt(1)
	v_mfma_f32_32x32x16_bf16 v[112:127], v[208:211], v[224:227], v[112:127]
	v_mfma_f32_32x32x16_bf16 v[48:63], v[212:215], v[224:227], v[48:63]
	s_waitcnt lgkmcnt(0)
	v_mfma_f32_32x32x16_bf16 v[96:111], v[208:211], v[228:231], v[96:111]
	v_mfma_f32_32x32x16_bf16 v[32:47], v[212:215], v[228:231], v[32:47]
	ds_read_b128 v[224:227], v168 offset:9312
	ds_read_b128 v[228:231], v168 offset:13920
	s_waitcnt lgkmcnt(0)
	s_barrier
; template <bool trans>
; DI void gemm_core(const GTile& tl, const GTile& nx, bool has_next  , bool chain  , bool pre, u32x4 (&ra)[4], u32x4 (&rb)[4], char* smem, f32x16 (&acc)[2][4]) {
;     ...
;   const int nk = K / 64;
;   if (!pre) { G_LOAD(0); G_STORE(0); G_LOAD(1); }
;   for (int kt = 0; kt < nk; ++kt) {
;     __syncthreads();
;     G_COMPUTE(kt & 1, kt);
	s_waitcnt vmcnt(7)
	ds_write_b128 v195, v[178:181]
	s_waitcnt vmcnt(6)
	ds_write_b128 v196, v[216:219]
	ds_read_b128 v[178:181], v192 offset:36864
	ds_read_b128 v[216:219], v192 offset:41472
	v_mfma_f32_32x32x16_bf16 v[80:95], v[208:211], v[224:227], v[80:95]
	v_mfma_f32_32x32x16_bf16 v[16:31], v[212:215], v[224:227], v[16:31]
	ds_read_b128 v[224:227], v184
	v_mfma_f32_32x32x16_bf16 v[64:79], v[208:211], v[228:231], v[64:79]
	v_mfma_f32_32x32x16_bf16 v[0:15], v[212:215], v[228:231], v[0:15]
	ds_read_b128 v[228:231], v184 offset:4608
	s_setprio 0
	global_load_dwordx4 v[208:211], v[128:129], off offset:3328
	global_load_dwordx4 v[212:215], v[132:133], off offset:3328
	s_setprio 1
	s_waitcnt lgkmcnt(1)
	v_mfma_f32_32x32x16_bf16 v[112:127], v[178:181], v[224:227], v[112:127]
	v_mfma_f32_32x32x16_bf16 v[48:63], v[216:219], v[224:227], v[48:63]
	s_waitcnt lgkmcnt(0)
	v_mfma_f32_32x32x16_bf16 v[96:111], v[178:181], v[228:231], v[96:111]
	v_mfma_f32_32x32x16_bf16 v[32:47], v[216:219], v[228:231], v[32:47]
	ds_read_b128 v[224:227], v184 offset:9216
	ds_read_b128 v[228:231], v184 offset:13824
	s_waitcnt vmcnt(7)
	ds_write_b128 v194, v[172:175]
	s_waitcnt vmcnt(6)
	ds_write_b128 v193, v[220:223]
	ds_read_b128 v[172:175], v192 offset:36896
	ds_read_b128 v[220:223], v192 offset:41504
	s_waitcnt lgkmcnt(5)
	v_mfma_f32_32x32x16_bf16 v[80:95], v[178:181], v[224:227], v[80:95]
	v_mfma_f32_32x32x16_bf16 v[16:31], v[216:219], v[224:227], v[16:31]
	ds_read_b128 v[224:227], v184 offset:32
	s_waitcnt lgkmcnt(5)
	v_mfma_f32_32x32x16_bf16 v[64:79], v[178:181], v[228:231], v[64:79]
	v_mfma_f32_32x32x16_bf16 v[0:15], v[216:219], v[228:231], v[0:15]
	ds_read_b128 v[228:231], v184 offset:4640
	s_setprio 0
	global_load_dwordx4 v[178:181], v[136:137], off offset:3328
	global_load_dwordx4 v[216:219], v[140:141], off offset:3328
	s_setprio 1
	s_waitcnt lgkmcnt(1)
	v_mfma_f32_32x32x16_bf16 v[112:127], v[172:175], v[224:227], v[112:127]
	v_mfma_f32_32x32x16_bf16 v[48:63], v[220:223], v[224:227], v[48:63]
	s_waitcnt lgkmcnt(0)
	v_mfma_f32_32x32x16_bf16 v[96:111], v[172:175], v[228:231], v[96:111]
	v_mfma_f32_32x32x16_bf16 v[32:47], v[220:223], v[228:231], v[32:47]
	ds_read_b128 v[224:227], v184 offset:9248
	ds_read_b128 v[228:231], v184 offset:13856
	s_waitcnt vmcnt(7)
	ds_write_b128 v177, v[158:161]
	s_waitcnt vmcnt(6)
	ds_write_b128 v176, v[162:165]
	ds_read_b128 v[158:161], v192 offset:36928
	ds_read_b128 v[162:165], v192 offset:41536
	s_waitcnt lgkmcnt(5)
	v_mfma_f32_32x32x16_bf16 v[80:95], v[172:175], v[224:227], v[80:95]
	v_mfma_f32_32x32x16_bf16 v[16:31], v[220:223], v[224:227], v[16:31]
	ds_read_b128 v[224:227], v184 offset:64
	s_waitcnt lgkmcnt(5)
	v_mfma_f32_32x32x16_bf16 v[64:79], v[172:175], v[228:231], v[64:79]
	v_mfma_f32_32x32x16_bf16 v[0:15], v[220:223], v[228:231], v[0:15]
	ds_read_b128 v[228:231], v184 offset:4672
	s_setprio 0
	global_load_dwordx4 v[172:175], v[144:145], off offset:3328
	global_load_dwordx4 v[220:223], v[148:149], off offset:3328
	s_setprio 1
	s_waitcnt lgkmcnt(1)
	v_mfma_f32_32x32x16_bf16 v[112:127], v[158:161], v[224:227], v[112:127]
	v_mfma_f32_32x32x16_bf16 v[48:63], v[162:165], v[224:227], v[48:63]
	s_waitcnt lgkmcnt(0)
	v_mfma_f32_32x32x16_bf16 v[96:111], v[158:161], v[228:231], v[96:111]
	v_mfma_f32_32x32x16_bf16 v[32:47], v[162:165], v[228:231], v[32:47]
	ds_read_b128 v[224:227], v184 offset:9280
	ds_read_b128 v[228:231], v184 offset:13888
	s_waitcnt vmcnt(7)
	ds_write_b128 v171, v[198:201]
	s_waitcnt vmcnt(6)
	ds_write_b128 v170, v[202:205]
	ds_read_b128 v[198:201], v192 offset:36960
	ds_read_b128 v[202:205], v192 offset:41568
	s_waitcnt lgkmcnt(5)
	v_mfma_f32_32x32x16_bf16 v[80:95], v[158:161], v[224:227], v[80:95]
	v_mfma_f32_32x32x16_bf16 v[16:31], v[162:165], v[224:227], v[16:31]
	ds_read_b128 v[224:227], v184 offset:96
	s_waitcnt lgkmcnt(5)
	v_mfma_f32_32x32x16_bf16 v[64:79], v[158:161], v[228:231], v[64:79]
	v_mfma_f32_32x32x16_bf16 v[0:15], v[162:165], v[228:231], v[0:15]
	ds_read_b128 v[228:231], v184 offset:4704
	s_setprio 0
	global_load_dwordx4 v[158:161], v[152:153], off offset:3328
	global_load_dwordx4 v[162:165], v[156:157], off offset:3328
	s_setprio 1
	s_waitcnt lgkmcnt(1)
	v_mfma_f32_32x32x16_bf16 v[112:127], v[198:201], v[224:227], v[112:127]
	v_mfma_f32_32x32x16_bf16 v[48:63], v[202:205], v[224:227], v[48:63]
	s_waitcnt lgkmcnt(0)
	v_mfma_f32_32x32x16_bf16 v[96:111], v[198:201], v[228:231], v[96:111]
	v_mfma_f32_32x32x16_bf16 v[32:47], v[202:205], v[228:231], v[32:47]
	ds_read_b128 v[224:227], v184 offset:9312
	ds_read_b128 v[228:231], v184 offset:13920
	s_waitcnt lgkmcnt(0)
	s_barrier
; template <bool trans>
; DI void gemm_core(const GTile& tl, const GTile& nx, bool has_next  , bool chain  , bool pre, u32x4 (&ra)[4], u32x4 (&rb)[4], char* smem, f32x16 (&acc)[2][4]) {
;     ...
;   const int nk = K / 64;
;   if (!pre) { G_LOAD(0); G_STORE(0); G_LOAD(1); }
;   for (int kt = 0; kt < nk; ++kt) {
;     __syncthreads();
;     G_COMPUTE(kt & 1, kt);
	s_waitcnt vmcnt(7)
	ds_write_b128 v191, v[208:211]
	s_waitcnt vmcnt(6)
	ds_write_b128 v191, v[212:215] offset:36864
	ds_read_b128 v[208:211], v169
	ds_read_b128 v[212:215], v169 offset:4608
	v_mfma_f32_32x32x16_bf16 v[80:95], v[198:201], v[224:227], v[80:95]
	v_mfma_f32_32x32x16_bf16 v[16:31], v[202:205], v[224:227], v[16:31]
	ds_read_b128 v[224:227], v168
	v_mfma_f32_32x32x16_bf16 v[64:79], v[198:201], v[228:231], v[64:79]
	v_mfma_f32_32x32x16_bf16 v[0:15], v[202:205], v[228:231], v[0:15]
	ds_read_b128 v[228:231], v168 offset:4608
	s_setprio 0
	global_load_dwordx4 v[198:201], v[128:129], off offset:3456
	global_load_dwordx4 v[202:205], v[132:133], off offset:3456
	s_setprio 1
	s_waitcnt lgkmcnt(1)
	v_mfma_f32_32x32x16_bf16 v[112:127], v[208:211], v[224:227], v[112:127]
	v_mfma_f32_32x32x16_bf16 v[48:63], v[212:215], v[224:227], v[48:63]
	s_waitcnt lgkmcnt(0)
	v_mfma_f32_32x32x16_bf16 v[96:111], v[208:211], v[228:231], v[96:111]
	v_mfma_f32_32x32x16_bf16 v[32:47], v[212:215], v[228:231], v[32:47]
	ds_read_b128 v[224:227], v168 offset:9216
	ds_read_b128 v[228:231], v168 offset:13824
	s_waitcnt vmcnt(7)
	ds_write_b128 v191, v[178:181] offset:9216
	s_waitcnt vmcnt(6)
	ds_write_b128 v191, v[216:219] offset:46080
	ds_read_b128 v[178:181], v169 offset:32
	ds_read_b128 v[216:219], v169 offset:4640
	s_waitcnt lgkmcnt(5)
	v_mfma_f32_32x32x16_bf16 v[80:95], v[208:211], v[224:227], v[80:95]
	v_mfma_f32_32x32x16_bf16 v[16:31], v[212:215], v[224:227], v[16:31]
	ds_read_b128 v[224:227], v168 offset:32
	s_waitcnt lgkmcnt(5)
	v_mfma_f32_32x32x16_bf16 v[64:79], v[208:211], v[228:231], v[64:79]
	v_mfma_f32_32x32x16_bf16 v[0:15], v[212:215], v[228:231], v[0:15]
	ds_read_b128 v[228:231], v168 offset:4640
	s_setprio 0
	global_load_dwordx4 v[208:211], v[136:137], off offset:3456
	global_load_dwordx4 v[212:215], v[140:141], off offset:3456
	s_setprio 1
	s_waitcnt lgkmcnt(1)
	v_mfma_f32_32x32x16_bf16 v[112:127], v[178:181], v[224:227], v[112:127]
	v_mfma_f32_32x32x16_bf16 v[48:63], v[216:219], v[224:227], v[48:63]
	s_waitcnt lgkmcnt(0)
	v_mfma_f32_32x32x16_bf16 v[96:111], v[178:181], v[228:231], v[96:111]
	v_mfma_f32_32x32x16_bf16 v[32:47], v[216:219], v[228:231], v[32:47]
	ds_read_b128 v[224:227], v168 offset:9248
	ds_read_b128 v[228:231], v168 offset:13856
	s_waitcnt vmcnt(7)
	ds_write_b128 v191, v[172:175] offset:18432
	s_waitcnt vmcnt(6)
	ds_write_b128 v191, v[220:223] offset:55296
	ds_read_b128 v[172:175], v169 offset:64
	ds_read_b128 v[220:223], v169 offset:4672
	s_waitcnt lgkmcnt(5)
	v_mfma_f32_32x32x16_bf16 v[80:95], v[178:181], v[224:227], v[80:95]
	v_mfma_f32_32x32x16_bf16 v[16:31], v[216:219], v[224:227], v[16:31]
	ds_read_b128 v[224:227], v168 offset:64
	s_waitcnt lgkmcnt(5)
	v_mfma_f32_32x32x16_bf16 v[64:79], v[178:181], v[228:231], v[64:79]
	v_mfma_f32_32x32x16_bf16 v[0:15], v[216:219], v[228:231], v[0:15]
	ds_read_b128 v[228:231], v168 offset:4672
	s_setprio 0
	global_load_dwordx4 v[178:181], v[144:145], off offset:3456
	global_load_dwordx4 v[216:219], v[148:149], off offset:3456
	s_setprio 1
	s_waitcnt lgkmcnt(1)
	v_mfma_f32_32x32x16_bf16 v[112:127], v[172:175], v[224:227], v[112:127]
	v_mfma_f32_32x32x16_bf16 v[48:63], v[220:223], v[224:227], v[48:63]
	s_waitcnt lgkmcnt(0)
	v_mfma_f32_32x32x16_bf16 v[96:111], v[172:175], v[228:231], v[96:111]
	v_mfma_f32_32x32x16_bf16 v[32:47], v[220:223], v[228:231], v[32:47]
	ds_read_b128 v[224:227], v168 offset:9280
	ds_read_b128 v[228:231], v168 offset:13888
	s_waitcnt vmcnt(7)
	ds_write_b128 v191, v[158:161] offset:27648
	s_waitcnt vmcnt(6)
	ds_write_b128 v191, v[162:165] offset:64512
	ds_read_b128 v[158:161], v169 offset:96
	ds_read_b128 v[162:165], v169 offset:4704
	s_waitcnt lgkmcnt(5)
	v_mfma_f32_32x32x16_bf16 v[80:95], v[172:175], v[224:227], v[80:95]
	v_mfma_f32_32x32x16_bf16 v[16:31], v[220:223], v[224:227], v[16:31]
	ds_read_b128 v[224:227], v168 offset:96
	s_waitcnt lgkmcnt(5)
	v_mfma_f32_32x32x16_bf16 v[64:79], v[172:175], v[228:231], v[64:79]
	v_mfma_f32_32x32x16_bf16 v[0:15], v[220:223], v[228:231], v[0:15]
	ds_read_b128 v[228:231], v168 offset:4704
	s_setprio 0
	global_load_dwordx4 v[172:175], v[152:153], off offset:3456
	global_load_dwordx4 v[220:223], v[156:157], off offset:3456
	s_setprio 1
	s_waitcnt lgkmcnt(1)
	v_mfma_f32_32x32x16_bf16 v[112:127], v[158:161], v[224:227], v[112:127]
	v_mfma_f32_32x32x16_bf16 v[48:63], v[162:165], v[224:227], v[48:63]
	s_waitcnt lgkmcnt(0)
	v_mfma_f32_32x32x16_bf16 v[96:111], v[158:161], v[228:231], v[96:111]
	v_mfma_f32_32x32x16_bf16 v[32:47], v[162:165], v[228:231], v[32:47]
	ds_read_b128 v[224:227], v168 offset:9312
	ds_read_b128 v[228:231], v168 offset:13920
	s_waitcnt lgkmcnt(0)
	s_barrier
; template <bool trans>
; DI void gemm_core(const GTile& tl, const GTile& nx, bool has_next  , bool chain  , bool pre, u32x4 (&ra)[4], u32x4 (&rb)[4], char* smem, f32x16 (&acc)[2][4]) {
;     ...
;   const int nk = K / 64;
;   if (!pre) { G_LOAD(0); G_STORE(0); G_LOAD(1); }
;   for (int kt = 0; kt < nk; ++kt) {
;     __syncthreads();
;     G_COMPUTE(kt & 1, kt);
	s_waitcnt vmcnt(7)
	ds_write_b128 v195, v[198:201]
	s_waitcnt vmcnt(6)
	ds_write_b128 v196, v[202:205]
	ds_read_b128 v[198:201], v192 offset:36864
	ds_read_b128 v[202:205], v192 offset:41472
	v_mfma_f32_32x32x16_bf16 v[80:95], v[158:161], v[224:227], v[80:95]
	v_mfma_f32_32x32x16_bf16 v[16:31], v[162:165], v[224:227], v[16:31]
	ds_read_b128 v[224:227], v184
	v_mfma_f32_32x32x16_bf16 v[64:79], v[158:161], v[228:231], v[64:79]
	v_mfma_f32_32x32x16_bf16 v[0:15], v[162:165], v[228:231], v[0:15]
	ds_read_b128 v[228:231], v184 offset:4608
	s_setprio 0
	global_load_dwordx4 v[158:161], v[128:129], off offset:3584
	global_load_dwordx4 v[162:165], v[132:133], off offset:3584
	s_setprio 1
	s_waitcnt lgkmcnt(1)
	v_mfma_f32_32x32x16_bf16 v[112:127], v[198:201], v[224:227], v[112:127]
	v_mfma_f32_32x32x16_bf16 v[48:63], v[202:205], v[224:227], v[48:63]
	s_waitcnt lgkmcnt(0)
	v_mfma_f32_32x32x16_bf16 v[96:111], v[198:201], v[228:231], v[96:111]
	v_mfma_f32_32x32x16_bf16 v[32:47], v[202:205], v[228:231], v[32:47]
	ds_read_b128 v[224:227], v184 offset:9216
	ds_read_b128 v[228:231], v184 offset:13824
	s_waitcnt vmcnt(7)
	ds_write_b128 v194, v[208:211]
	s_waitcnt vmcnt(6)
	ds_write_b128 v193, v[212:215]
	ds_read_b128 v[208:211], v192 offset:36896
	ds_read_b128 v[212:215], v192 offset:41504
	s_waitcnt lgkmcnt(5)
	v_mfma_f32_32x32x16_bf16 v[80:95], v[198:201], v[224:227], v[80:95]
	v_mfma_f32_32x32x16_bf16 v[16:31], v[202:205], v[224:227], v[16:31]
	ds_read_b128 v[224:227], v184 offset:32
	s_waitcnt lgkmcnt(5)
	v_mfma_f32_32x32x16_bf16 v[64:79], v[198:201], v[228:231], v[64:79]
	v_mfma_f32_32x32x16_bf16 v[0:15], v[202:205], v[228:231], v[0:15]
	ds_read_b128 v[228:231], v184 offset:4640
	s_setprio 0
	global_load_dwordx4 v[198:201], v[136:137], off offset:3584
	global_load_dwordx4 v[202:205], v[140:141], off offset:3584
	s_setprio 1
	s_waitcnt lgkmcnt(1)
	v_mfma_f32_32x32x16_bf16 v[112:127], v[208:211], v[224:227], v[112:127]
	v_mfma_f32_32x32x16_bf16 v[48:63], v[212:215], v[224:227], v[48:63]
	s_waitcnt lgkmcnt(0)
	v_mfma_f32_32x32x16_bf16 v[96:111], v[208:211], v[228:231], v[96:111]
	v_mfma_f32_32x32x16_bf16 v[32:47], v[212:215], v[228:231], v[32:47]
	ds_read_b128 v[224:227], v184 offset:9248
	ds_read_b128 v[228:231], v184 offset:13856
	s_waitcnt vmcnt(7)
	ds_write_b128 v177, v[178:181]
	s_waitcnt vmcnt(6)
	ds_write_b128 v176, v[216:219]
	ds_read_b128 v[178:181], v192 offset:36928
	ds_read_b128 v[216:219], v192 offset:41536
	s_waitcnt lgkmcnt(5)
	v_mfma_f32_32x32x16_bf16 v[80:95], v[208:211], v[224:227], v[80:95]
	v_mfma_f32_32x32x16_bf16 v[16:31], v[212:215], v[224:227], v[16:31]
	ds_read_b128 v[224:227], v184 offset:64
	s_waitcnt lgkmcnt(5)
	v_mfma_f32_32x32x16_bf16 v[64:79], v[208:211], v[228:231], v[64:79]
	v_mfma_f32_32x32x16_bf16 v[0:15], v[212:215], v[228:231], v[0:15]
	ds_read_b128 v[228:231], v184 offset:4672
	s_setprio 0
	global_load_dwordx4 v[208:211], v[144:145], off offset:3584
	global_load_dwordx4 v[212:215], v[148:149], off offset:3584
	s_setprio 1
	s_waitcnt lgkmcnt(1)
	v_mfma_f32_32x32x16_bf16 v[112:127], v[178:181], v[224:227], v[112:127]
	v_mfma_f32_32x32x16_bf16 v[48:63], v[216:219], v[224:227], v[48:63]
	s_waitcnt lgkmcnt(0)
	v_mfma_f32_32x32x16_bf16 v[96:111], v[178:181], v[228:231], v[96:111]
	v_mfma_f32_32x32x16_bf16 v[32:47], v[216:219], v[228:231], v[32:47]
	ds_read_b128 v[224:227], v184 offset:9280
	ds_read_b128 v[228:231], v184 offset:13888
	s_waitcnt vmcnt(7)
	ds_write_b128 v171, v[172:175]
	s_waitcnt vmcnt(6)
	ds_write_b128 v170, v[220:223]
	ds_read_b128 v[172:175], v192 offset:36960
	ds_read_b128 v[220:223], v192 offset:41568
	s_waitcnt lgkmcnt(5)
	v_mfma_f32_32x32x16_bf16 v[80:95], v[178:181], v[224:227], v[80:95]
	v_mfma_f32_32x32x16_bf16 v[16:31], v[216:219], v[224:227], v[16:31]
	ds_read_b128 v[224:227], v184 offset:96
	s_waitcnt lgkmcnt(5)
	v_mfma_f32_32x32x16_bf16 v[64:79], v[178:181], v[228:231], v[64:79]
	v_mfma_f32_32x32x16_bf16 v[0:15], v[216:219], v[228:231], v[0:15]
	ds_read_b128 v[228:231], v184 offset:4704
	s_setprio 0
	global_load_dwordx4 v[178:181], v[152:153], off offset:3584
	global_load_dwordx4 v[216:219], v[156:157], off offset:3584
	s_setprio 1
	s_waitcnt lgkmcnt(1)
	v_mfma_f32_32x32x16_bf16 v[112:127], v[172:175], v[224:227], v[112:127]
	v_mfma_f32_32x32x16_bf16 v[48:63], v[220:223], v[224:227], v[48:63]
	s_waitcnt lgkmcnt(0)
	v_mfma_f32_32x32x16_bf16 v[96:111], v[172:175], v[228:231], v[96:111]
	v_mfma_f32_32x32x16_bf16 v[32:47], v[220:223], v[228:231], v[32:47]
	ds_read_b128 v[224:227], v184 offset:9312
	ds_read_b128 v[228:231], v184 offset:13920
	s_waitcnt lgkmcnt(0)
	s_barrier
; template <bool trans>
; DI void gemm_core(const GTile& tl, const GTile& nx, bool has_next  , bool chain  , bool pre, u32x4 (&ra)[4], u32x4 (&rb)[4], char* smem, f32x16 (&acc)[2][4]) {
;     ...
;   const int nk = K / 64;
;   if (!pre) { G_LOAD(0); G_STORE(0); G_LOAD(1); }
;   for (int kt = 0; kt < nk; ++kt) {
;     __syncthreads();
;     G_COMPUTE(kt & 1, kt);
	s_waitcnt vmcnt(7)
	ds_write_b128 v191, v[158:161]
	s_waitcnt vmcnt(6)
	ds_write_b128 v191, v[162:165] offset:36864
	ds_read_b128 v[158:161], v169
	ds_read_b128 v[162:165], v169 offset:4608
	v_mfma_f32_32x32x16_bf16 v[80:95], v[172:175], v[224:227], v[80:95]
	v_mfma_f32_32x32x16_bf16 v[16:31], v[220:223], v[224:227], v[16:31]
	ds_read_b128 v[224:227], v168
	v_mfma_f32_32x32x16_bf16 v[64:79], v[172:175], v[228:231], v[64:79]
	v_mfma_f32_32x32x16_bf16 v[0:15], v[220:223], v[228:231], v[0:15]
	ds_read_b128 v[228:231], v168 offset:4608
	s_setprio 0
	global_load_dwordx4 v[172:175], v[128:129], off offset:3712
	global_load_dwordx4 v[220:223], v[132:133], off offset:3712
	s_setprio 1
	s_waitcnt lgkmcnt(1)
	v_mfma_f32_32x32x16_bf16 v[112:127], v[158:161], v[224:227], v[112:127]
	v_mfma_f32_32x32x16_bf16 v[48:63], v[162:165], v[224:227], v[48:63]
	s_waitcnt lgkmcnt(0)
	v_mfma_f32_32x32x16_bf16 v[96:111], v[158:161], v[228:231], v[96:111]
	v_mfma_f32_32x32x16_bf16 v[32:47], v[162:165], v[228:231], v[32:47]
	ds_read_b128 v[224:227], v168 offset:9216
	ds_read_b128 v[228:231], v168 offset:13824
	s_waitcnt vmcnt(7)
	ds_write_b128 v191, v[198:201] offset:9216
	s_waitcnt vmcnt(6)
	ds_write_b128 v191, v[202:205] offset:46080
	ds_read_b128 v[198:201], v169 offset:32
	ds_read_b128 v[202:205], v169 offset:4640
	s_waitcnt lgkmcnt(5)
	v_mfma_f32_32x32x16_bf16 v[80:95], v[158:161], v[224:227], v[80:95]
	v_mfma_f32_32x32x16_bf16 v[16:31], v[162:165], v[224:227], v[16:31]
	ds_read_b128 v[224:227], v168 offset:32
	s_waitcnt lgkmcnt(5)
	v_mfma_f32_32x32x16_bf16 v[64:79], v[158:161], v[228:231], v[64:79]
	v_mfma_f32_32x32x16_bf16 v[0:15], v[162:165], v[228:231], v[0:15]
	ds_read_b128 v[228:231], v168 offset:4640
	s_setprio 0
	global_load_dwordx4 v[158:161], v[136:137], off offset:3712
	global_load_dwordx4 v[162:165], v[140:141], off offset:3712
	s_setprio 1
	s_waitcnt lgkmcnt(1)
	v_mfma_f32_32x32x16_bf16 v[112:127], v[198:201], v[224:227], v[112:127]
	v_mfma_f32_32x32x16_bf16 v[48:63], v[202:205], v[224:227], v[48:63]
	s_waitcnt lgkmcnt(0)
	v_mfma_f32_32x32x16_bf16 v[96:111], v[198:201], v[228:231], v[96:111]
	v_mfma_f32_32x32x16_bf16 v[32:47], v[202:205], v[228:231], v[32:47]
	ds_read_b128 v[224:227], v168 offset:9248
	ds_read_b128 v[228:231], v168 offset:13856
	s_waitcnt vmcnt(7)
	ds_write_b128 v191, v[208:211] offset:18432
	s_waitcnt vmcnt(6)
	ds_write_b128 v191, v[212:215] offset:55296
	ds_read_b128 v[208:211], v169 offset:64
	ds_read_b128 v[212:215], v169 offset:4672
	s_waitcnt lgkmcnt(5)
	v_mfma_f32_32x32x16_bf16 v[80:95], v[198:201], v[224:227], v[80:95]
	v_mfma_f32_32x32x16_bf16 v[16:31], v[202:205], v[224:227], v[16:31]
	ds_read_b128 v[224:227], v168 offset:64
	s_waitcnt lgkmcnt(5)
	v_mfma_f32_32x32x16_bf16 v[64:79], v[198:201], v[228:231], v[64:79]
	v_mfma_f32_32x32x16_bf16 v[0:15], v[202:205], v[228:231], v[0:15]
	ds_read_b128 v[228:231], v168 offset:4672
	s_setprio 0
	global_load_dwordx4 v[198:201], v[144:145], off offset:3712
	global_load_dwordx4 v[202:205], v[148:149], off offset:3712
	s_setprio 1
	s_waitcnt lgkmcnt(1)
	v_mfma_f32_32x32x16_bf16 v[112:127], v[208:211], v[224:227], v[112:127]
	v_mfma_f32_32x32x16_bf16 v[48:63], v[212:215], v[224:227], v[48:63]
	s_waitcnt lgkmcnt(0)
	v_mfma_f32_32x32x16_bf16 v[96:111], v[208:211], v[228:231], v[96:111]
	v_mfma_f32_32x32x16_bf16 v[32:47], v[212:215], v[228:231], v[32:47]
	ds_read_b128 v[224:227], v168 offset:9280
	ds_read_b128 v[228:231], v168 offset:13888
	s_waitcnt vmcnt(7)
	ds_write_b128 v191, v[178:181] offset:27648
	s_waitcnt vmcnt(6)
	ds_write_b128 v191, v[216:219] offset:64512
	ds_read_b128 v[178:181], v169 offset:96
	ds_read_b128 v[216:219], v169 offset:4704
	s_waitcnt lgkmcnt(5)
	v_mfma_f32_32x32x16_bf16 v[80:95], v[208:211], v[224:227], v[80:95]
	v_mfma_f32_32x32x16_bf16 v[16:31], v[212:215], v[224:227], v[16:31]
	ds_read_b128 v[224:227], v168 offset:96
	s_waitcnt lgkmcnt(5)
	v_mfma_f32_32x32x16_bf16 v[64:79], v[208:211], v[228:231], v[64:79]
	v_mfma_f32_32x32x16_bf16 v[0:15], v[212:215], v[228:231], v[0:15]
	ds_read_b128 v[228:231], v168 offset:4704
	s_setprio 0
	global_load_dwordx4 v[208:211], v[152:153], off offset:3712
	global_load_dwordx4 v[212:215], v[156:157], off offset:3712
	s_setprio 1
	s_waitcnt lgkmcnt(1)
	v_mfma_f32_32x32x16_bf16 v[112:127], v[178:181], v[224:227], v[112:127]
	v_mfma_f32_32x32x16_bf16 v[48:63], v[216:219], v[224:227], v[48:63]
	s_waitcnt lgkmcnt(0)
	v_mfma_f32_32x32x16_bf16 v[96:111], v[178:181], v[228:231], v[96:111]
	v_mfma_f32_32x32x16_bf16 v[32:47], v[216:219], v[228:231], v[32:47]
	ds_read_b128 v[224:227], v168 offset:9312
	ds_read_b128 v[228:231], v168 offset:13920
	s_waitcnt lgkmcnt(0)
	s_barrier
; template <bool trans>
; DI void gemm_core(const GTile& tl, const GTile& nx, bool has_next  , bool chain  , bool pre, u32x4 (&ra)[4], u32x4 (&rb)[4], char* smem, f32x16 (&acc)[2][4]) {
;     ...
;   const int nk = K / 64;
;   if (!pre) { G_LOAD(0); G_STORE(0); G_LOAD(1); }
;   for (int kt = 0; kt < nk; ++kt) {
;     __syncthreads();
;     G_COMPUTE(kt & 1, kt);
	s_waitcnt vmcnt(7)
	ds_write_b128 v195, v[172:175]
	s_waitcnt vmcnt(6)
	ds_write_b128 v196, v[220:223]
	ds_read_b128 v[172:175], v192 offset:36864
	ds_read_b128 v[220:223], v192 offset:41472
	v_mfma_f32_32x32x16_bf16 v[80:95], v[178:181], v[224:227], v[80:95]
	v_mfma_f32_32x32x16_bf16 v[16:31], v[216:219], v[224:227], v[16:31]
	ds_read_b128 v[224:227], v184
	v_mfma_f32_32x32x16_bf16 v[64:79], v[178:181], v[228:231], v[64:79]
	v_mfma_f32_32x32x16_bf16 v[0:15], v[216:219], v[228:231], v[0:15]
	ds_read_b128 v[228:231], v184 offset:4608
	s_setprio 0
	global_load_dwordx4 v[178:181], v[128:129], off offset:3840
	global_load_dwordx4 v[216:219], v[132:133], off offset:3840
	s_setprio 1
	s_waitcnt lgkmcnt(1)
	v_mfma_f32_32x32x16_bf16 v[112:127], v[172:175], v[224:227], v[112:127]
	v_mfma_f32_32x32x16_bf16 v[48:63], v[220:223], v[224:227], v[48:63]
	s_waitcnt lgkmcnt(0)
	v_mfma_f32_32x32x16_bf16 v[96:111], v[172:175], v[228:231], v[96:111]
	v_mfma_f32_32x32x16_bf16 v[32:47], v[220:223], v[228:231], v[32:47]
	ds_read_b128 v[224:227], v184 offset:9216
	ds_read_b128 v[228:231], v184 offset:13824
	s_waitcnt vmcnt(7)
	ds_write_b128 v194, v[158:161]
	s_waitcnt vmcnt(6)
	ds_write_b128 v193, v[162:165]
	ds_read_b128 v[158:161], v192 offset:36896
	ds_read_b128 v[162:165], v192 offset:41504
	s_waitcnt lgkmcnt(5)
	v_mfma_f32_32x32x16_bf16 v[80:95], v[172:175], v[224:227], v[80:95]
	v_mfma_f32_32x32x16_bf16 v[16:31], v[220:223], v[224:227], v[16:31]
	ds_read_b128 v[224:227], v184 offset:32
	s_waitcnt lgkmcnt(5)
	v_mfma_f32_32x32x16_bf16 v[64:79], v[172:175], v[228:231], v[64:79]
	v_mfma_f32_32x32x16_bf16 v[0:15], v[220:223], v[228:231], v[0:15]
	ds_read_b128 v[228:231], v184 offset:4640
	s_setprio 0
	global_load_dwordx4 v[172:175], v[136:137], off offset:3840
	global_load_dwordx4 v[220:223], v[140:141], off offset:3840
	s_setprio 1
	s_waitcnt lgkmcnt(1)
	v_mfma_f32_32x32x16_bf16 v[112:127], v[158:161], v[224:227], v[112:127]
	v_mfma_f32_32x32x16_bf16 v[48:63], v[162:165], v[224:227], v[48:63]
	s_waitcnt lgkmcnt(0)
	v_mfma_f32_32x32x16_bf16 v[96:111], v[158:161], v[228:231], v[96:111]
	v_mfma_f32_32x32x16_bf16 v[32:47], v[162:165], v[228:231], v[32:47]
	ds_read_b128 v[224:227], v184 offset:9248
	ds_read_b128 v[228:231], v184 offset:13856
	s_waitcnt vmcnt(7)
	ds_write_b128 v177, v[198:201]
	s_waitcnt vmcnt(6)
	ds_write_b128 v176, v[202:205]
	ds_read_b128 v[198:201], v192 offset:36928
	ds_read_b128 v[202:205], v192 offset:41536
	s_waitcnt lgkmcnt(5)
	v_mfma_f32_32x32x16_bf16 v[80:95], v[158:161], v[224:227], v[80:95]
	v_mfma_f32_32x32x16_bf16 v[16:31], v[162:165], v[224:227], v[16:31]
	ds_read_b128 v[224:227], v184 offset:64
	s_waitcnt lgkmcnt(5)
	v_mfma_f32_32x32x16_bf16 v[64:79], v[158:161], v[228:231], v[64:79]
	v_mfma_f32_32x32x16_bf16 v[0:15], v[162:165], v[228:231], v[0:15]
	ds_read_b128 v[228:231], v184 offset:4672
	s_setprio 0
	global_load_dwordx4 v[158:161], v[144:145], off offset:3840
	global_load_dwordx4 v[162:165], v[148:149], off offset:3840
	s_setprio 1
	s_waitcnt lgkmcnt(1)
	v_mfma_f32_32x32x16_bf16 v[112:127], v[198:201], v[224:227], v[112:127]
	v_mfma_f32_32x32x16_bf16 v[48:63], v[202:205], v[224:227], v[48:63]
	s_waitcnt lgkmcnt(0)
	v_mfma_f32_32x32x16_bf16 v[96:111], v[198:201], v[228:231], v[96:111]
	v_mfma_f32_32x32x16_bf16 v[32:47], v[202:205], v[228:231], v[32:47]
	ds_read_b128 v[224:227], v184 offset:9280
	ds_read_b128 v[228:231], v184 offset:13888
	s_waitcnt vmcnt(7)
	ds_write_b128 v171, v[208:211]
	s_waitcnt vmcnt(6)
	ds_write_b128 v170, v[212:215]
	ds_read_b128 v[208:211], v192 offset:36960
	ds_read_b128 v[212:215], v192 offset:41568
	s_waitcnt lgkmcnt(5)
	v_mfma_f32_32x32x16_bf16 v[80:95], v[198:201], v[224:227], v[80:95]
	v_mfma_f32_32x32x16_bf16 v[16:31], v[202:205], v[224:227], v[16:31]
	ds_read_b128 v[224:227], v184 offset:96
	s_waitcnt lgkmcnt(5)
	v_mfma_f32_32x32x16_bf16 v[64:79], v[198:201], v[228:231], v[64:79]
	v_mfma_f32_32x32x16_bf16 v[0:15], v[202:205], v[228:231], v[0:15]
	ds_read_b128 v[228:231], v184 offset:4704
	s_setprio 0
	global_load_dwordx4 v[198:201], v[152:153], off offset:3840
	global_load_dwordx4 v[202:205], v[156:157], off offset:3840
	s_setprio 1
	s_waitcnt lgkmcnt(1)
	v_mfma_f32_32x32x16_bf16 v[112:127], v[208:211], v[224:227], v[112:127]
	v_mfma_f32_32x32x16_bf16 v[48:63], v[212:215], v[224:227], v[48:63]
	s_waitcnt lgkmcnt(0)
	v_mfma_f32_32x32x16_bf16 v[96:111], v[208:211], v[228:231], v[96:111]
	v_mfma_f32_32x32x16_bf16 v[32:47], v[212:215], v[228:231], v[32:47]
	ds_read_b128 v[224:227], v184 offset:9312
	ds_read_b128 v[228:231], v184 offset:13920
	s_waitcnt lgkmcnt(1)
	v_mfma_f32_32x32x16_bf16 v[80:95], v[208:211], v[224:227], v[80:95]
	v_mfma_f32_32x32x16_bf16 v[16:31], v[212:215], v[224:227], v[16:31]
	s_waitcnt lgkmcnt(0)
	v_mfma_f32_32x32x16_bf16 v[64:79], v[208:211], v[228:231], v[64:79]
	v_mfma_f32_32x32x16_bf16 v[0:15], v[212:215], v[228:231], v[0:15]
	s_setprio 0
	s_barrier
; template <bool trans>
; DI void gemm_core(const GTile& tl, const GTile& nx, bool has_next  , bool chain  , bool pre, u32x4 (&ra)[4], u32x4 (&rb)[4], char* smem, f32x16 (&acc)[2][4]) {
;     ...
;   const int nk = K / 64;
;   if (!pre) { G_LOAD(0); G_STORE(0); G_LOAD(1); }
;   for (int kt = 0; kt < nk; ++kt) {
;     __syncthreads();
;     G_COMPUTE(kt & 1, kt);
;   }
	global_load_dwordx4 v[128:131], v[128:129], off offset:3968
	s_nop 0
	global_load_dwordx4 v[132:135], v[132:133], off offset:3968
	s_waitcnt vmcnt(9)
	ds_write_b128 v191, v[178:181]
	s_waitcnt vmcnt(8)
	ds_write_b128 v191, v[216:219] offset:36864
	ds_read_b128 v[178:181], v169
	ds_read_b128 v[208:211], v169 offset:4608
	ds_read_b128 v[212:215], v168
	ds_read_b128 v[216:219], v168 offset:4608
	s_setprio 1
	s_waitcnt lgkmcnt(1)
	v_mfma_f32_32x32x16_bf16 v[112:127], v[178:181], v[212:215], v[112:127]
	v_mfma_f32_32x32x16_bf16 v[48:63], v[208:211], v[212:215], v[48:63]
	s_waitcnt lgkmcnt(0)
	v_mfma_f32_32x32x16_bf16 v[96:111], v[178:181], v[216:219], v[96:111]
	v_mfma_f32_32x32x16_bf16 v[32:47], v[208:211], v[216:219], v[32:47]
	ds_read_b128 v[212:215], v168 offset:9216
	ds_read_b128 v[216:219], v168 offset:13824
	s_waitcnt lgkmcnt(1)
	v_mfma_f32_32x32x16_bf16 v[80:95], v[178:181], v[212:215], v[80:95]
	v_mfma_f32_32x32x16_bf16 v[16:31], v[208:211], v[212:215], v[16:31]
	s_waitcnt lgkmcnt(0)
	v_mfma_f32_32x32x16_bf16 v[64:79], v[178:181], v[216:219], v[64:79]
	v_mfma_f32_32x32x16_bf16 v[0:15], v[208:211], v[216:219], v[0:15]
	s_setprio 0
	global_load_dwordx4 v[136:139], v[136:137], off offset:3968
	s_nop 0
	global_load_dwordx4 v[140:143], v[140:141], off offset:3968
	s_waitcnt vmcnt(9)
	ds_write_b128 v191, v[172:175] offset:9216
	s_waitcnt vmcnt(8)
	ds_write_b128 v191, v[220:223] offset:46080
	ds_read_b128 v[172:175], v169 offset:32
	ds_read_b128 v[178:181], v169 offset:4640
	ds_read_b128 v[208:211], v168 offset:32
	ds_read_b128 v[212:215], v168 offset:4640
	s_setprio 1
	s_waitcnt lgkmcnt(1)
	v_mfma_f32_32x32x16_bf16 v[112:127], v[172:175], v[208:211], v[112:127]
	v_mfma_f32_32x32x16_bf16 v[48:63], v[178:181], v[208:211], v[48:63]
	s_waitcnt lgkmcnt(0)
	v_mfma_f32_32x32x16_bf16 v[96:111], v[172:175], v[212:215], v[96:111]
	v_mfma_f32_32x32x16_bf16 v[32:47], v[178:181], v[212:215], v[32:47]
	ds_read_b128 v[208:211], v168 offset:9248
	ds_read_b128 v[212:215], v168 offset:13856
	s_waitcnt lgkmcnt(1)
	v_mfma_f32_32x32x16_bf16 v[80:95], v[172:175], v[208:211], v[80:95]
	v_mfma_f32_32x32x16_bf16 v[16:31], v[178:181], v[208:211], v[16:31]
	s_waitcnt lgkmcnt(0)
	v_mfma_f32_32x32x16_bf16 v[64:79], v[172:175], v[212:215], v[64:79]
	v_mfma_f32_32x32x16_bf16 v[0:15], v[178:181], v[212:215], v[0:15]
	s_setprio 0
	global_load_dwordx4 v[144:147], v[144:145], off offset:3968
	s_nop 0
	global_load_dwordx4 v[148:151], v[148:149], off offset:3968
	s_waitcnt vmcnt(9)
	ds_write_b128 v191, v[158:161] offset:18432
	s_waitcnt vmcnt(8)
	ds_write_b128 v191, v[162:165] offset:55296
	ds_read_b128 v[158:161], v169 offset:64
	ds_read_b128 v[162:165], v169 offset:4672
	ds_read_b128 v[172:175], v168 offset:64
	ds_read_b128 v[178:181], v168 offset:4672
	s_setprio 1
	s_waitcnt lgkmcnt(1)
	v_mfma_f32_32x32x16_bf16 v[112:127], v[158:161], v[172:175], v[112:127]
	v_mfma_f32_32x32x16_bf16 v[48:63], v[162:165], v[172:175], v[48:63]
	s_waitcnt lgkmcnt(0)
	v_mfma_f32_32x32x16_bf16 v[96:111], v[158:161], v[178:181], v[96:111]
	v_mfma_f32_32x32x16_bf16 v[32:47], v[162:165], v[178:181], v[32:47]
	ds_read_b128 v[172:175], v168 offset:9280
	ds_read_b128 v[178:181], v168 offset:13888
	s_waitcnt lgkmcnt(1)
	v_mfma_f32_32x32x16_bf16 v[80:95], v[158:161], v[172:175], v[80:95]
	v_mfma_f32_32x32x16_bf16 v[16:31], v[162:165], v[172:175], v[16:31]
	s_waitcnt lgkmcnt(0)
	v_mfma_f32_32x32x16_bf16 v[64:79], v[158:161], v[178:181], v[64:79]
	v_mfma_f32_32x32x16_bf16 v[0:15], v[162:165], v[178:181], v[0:15]
	s_setprio 0
	global_load_dwordx4 v[152:155], v[152:153], off offset:3968
	s_nop 0
	global_load_dwordx4 v[156:159], v[156:157], off offset:3968
	s_waitcnt vmcnt(9)
	ds_write_b128 v191, v[198:201] offset:27648
	s_waitcnt vmcnt(8)
	ds_write_b128 v191, v[202:205] offset:64512
	ds_read_b128 v[160:163], v169 offset:96
	ds_read_b128 v[164:167], v169 offset:4704
	ds_read_b128 v[172:175], v168 offset:96
	ds_read_b128 v[178:181], v168 offset:4704
	s_setprio 1
	s_waitcnt lgkmcnt(1)
	v_mfma_f32_32x32x16_bf16 v[112:127], v[160:163], v[172:175], v[112:127]
	v_mfma_f32_32x32x16_bf16 v[48:63], v[164:167], v[172:175], v[48:63]
	s_waitcnt lgkmcnt(0)
	v_mfma_f32_32x32x16_bf16 v[96:111], v[160:163], v[178:181], v[96:111]
	v_mfma_f32_32x32x16_bf16 v[32:47], v[164:167], v[178:181], v[32:47]
	ds_read_b128 v[172:175], v168 offset:9312
	ds_read_b128 v[178:181], v168 offset:13920
	s_waitcnt lgkmcnt(1)
	v_mfma_f32_32x32x16_bf16 v[80:95], v[160:163], v[172:175], v[80:95]
	v_mfma_f32_32x32x16_bf16 v[16:31], v[164:167], v[172:175], v[16:31]
	s_waitcnt lgkmcnt(0)
	v_mfma_f32_32x32x16_bf16 v[64:79], v[160:163], v[178:181], v[64:79]
	v_mfma_f32_32x32x16_bf16 v[0:15], v[164:167], v[178:181], v[0:15]
	s_setprio 0
	s_and_b64 vcc, exec, s[12:13]
	s_barrier
	s_waitcnt vmcnt(7)
	ds_write_b128 v195, v[128:131]
	s_waitcnt vmcnt(6)
	ds_write_b128 v196, v[132:135]
	s_cbranch_vccnz .LBB0_751
	global_load_dwordx4 v[128:131], v[188:189], off
	global_load_dwordx4 v[132:135], v[186:187], off

; template <bool trans>
; DI void gemm_core(const GTile& tl, const GTile& nx, bool has_next  , bool chain  , bool pre, u32x4 (&ra)[4], u32x4 (&rb)[4], char* smem, f32x16 (&acc)[2][4]) {
;     ...
;   const int nk = K / 64;
;   if (!pre) { G_LOAD(0); G_STORE(0); G_LOAD(1); }
;   for (int kt = 0; kt < nk; ++kt) {
;     __syncthreads();
;     G_COMPUTE(kt & 1, kt);
.LBB0_882:
	v_lshl_add_u64 v[190:191], s[2:3], 0, v[192:193]
	v_lshl_add_u64 v[188:189], s[16:17], 0, v[192:193]
	s_waitcnt lgkmcnt(0)
	s_barrier
	global_load_dwordx4 v[218:221], v[190:191], off offset:256
	global_load_dwordx4 v[222:225], v[188:189], off offset:256
	s_lshr_b32 s3, s33, 1
	s_and_b32 s2, s33, 0xc0
	v_and_b32_e32 v10, 31, v8
	s_and_b32 s3, s3, 0xfffff80
	v_or_b32_e32 v12, s3, v10
	v_or_b32_e32 v10, s2, v10
	v_add3_u32 v215, 16, v11, v9
	v_lshrrev_b32_e32 v8, 1, v8
	v_mul_u32_u24_e32 v208, 0x90, v10
	v_and_b32_e32 v242, 16, v8
	v_add_u32_e32 v209, 0x12000, v215
	v_mul_lo_u32 v205, v12, s54
	v_add3_u32 v204, 16, v208, v242
	v_add_u32_e32 v210, 0x1b000, v215
	ds_write_b128 v209, v[0:3]
	s_waitcnt vmcnt(5)
	ds_write_b128 v210, v[4:7]
	v_add3_u32 v192, 16, v205, v242
	ds_read_b128 v[0:3], v204 offset:36864
	ds_read_b128 v[4:7], v204 offset:41472
	ds_read_b128 v[8:11], v192
	ds_read_b128 v[12:15], v192 offset:4608
	v_lshl_add_u64 v[184:185], v[190:191], 0, s[14:15]
	v_lshl_add_u64 v[186:187], v[188:189], 0, s[14:15]
	v_lshl_add_u64 v[194:195], v[190:191], 0, s[12:13]
	v_lshl_add_u64 v[196:197], v[188:189], 0, s[12:13]
	s_setprio 1
	s_waitcnt lgkmcnt(1)
	v_mfma_f32_32x32x16_bf16 v[112:127], v[8:11], v[0:3], 0
	v_mfma_f32_32x32x16_bf16 v[48:63], v[8:11], v[4:7], 0
	s_waitcnt lgkmcnt(0)
	v_mfma_f32_32x32x16_bf16 v[96:111], v[12:15], v[0:3], 0
	v_mfma_f32_32x32x16_bf16 v[32:47], v[12:15], v[4:7], 0
	ds_read_b128 v[8:11], v192 offset:9216
	ds_read_b128 v[12:15], v192 offset:13824
	s_waitcnt lgkmcnt(1)
	v_mfma_f32_32x32x16_bf16 v[80:95], v[8:11], v[0:3], 0
	v_mfma_f32_32x32x16_bf16 v[16:31], v[8:11], v[4:7], 0
	s_waitcnt lgkmcnt(0)
	v_mfma_f32_32x32x16_bf16 v[64:79], v[12:15], v[0:3], 0
	v_mfma_f32_32x32x16_bf16 v[0:15], v[12:15], v[4:7], 0
	s_setprio 0
	global_load_dwordx4 v[226:229], v[194:195], off offset:256
	global_load_dwordx4 v[230:233], v[196:197], off offset:256
	v_add_u32_e32 v212, 0x14400, v215
	v_add_u32_e32 v211, 0x1d400, v215
	ds_write_b128 v212, v[176:179]
	s_waitcnt vmcnt(6)
	ds_write_b128 v211, v[180:183]
	ds_read_b128 v[176:179], v204 offset:36896
	ds_read_b128 v[180:183], v204 offset:41504
	ds_read_b128 v[198:201], v192 offset:32
	ds_read_b128 v[234:237], v192 offset:4640
	s_setprio 1
	s_waitcnt lgkmcnt(1)
	v_mfma_f32_32x32x16_bf16 v[112:127], v[198:201], v[176:179], v[112:127]
	v_mfma_f32_32x32x16_bf16 v[48:63], v[198:201], v[180:183], v[48:63]
	s_waitcnt lgkmcnt(0)
	v_mfma_f32_32x32x16_bf16 v[96:111], v[234:237], v[176:179], v[96:111]
	v_mfma_f32_32x32x16_bf16 v[32:47], v[234:237], v[180:183], v[32:47]
	ds_read_b128 v[198:201], v192 offset:9248
	ds_read_b128 v[234:237], v192 offset:13856
	s_waitcnt lgkmcnt(1)
	v_mfma_f32_32x32x16_bf16 v[80:95], v[198:201], v[176:179], v[80:95]
	v_mfma_f32_32x32x16_bf16 v[16:31], v[198:201], v[180:183], v[16:31]
	s_waitcnt lgkmcnt(0)
	v_mfma_f32_32x32x16_bf16 v[64:79], v[234:237], v[176:179], v[64:79]
	v_mfma_f32_32x32x16_bf16 v[0:15], v[234:237], v[180:183], v[0:15]
	s_setprio 0
	global_load_dwordx4 v[176:179], v[184:185], off offset:256
	global_load_dwordx4 v[180:183], v[186:187], off offset:256
	v_add_u32_e32 v214, 0x16800, v215
	v_add_u32_e32 v213, 0x1f800, v215
	ds_write_b128 v214, v[168:171]
	s_waitcnt vmcnt(7)
	ds_write_b128 v213, v[172:175]
	ds_read_b128 v[168:171], v204 offset:36928
	ds_read_b128 v[172:175], v204 offset:41536
	ds_read_b128 v[198:201], v192 offset:64
	ds_read_b128 v[234:237], v192 offset:4672
	s_setprio 1
	s_waitcnt lgkmcnt(1)
	v_mfma_f32_32x32x16_bf16 v[112:127], v[198:201], v[168:171], v[112:127]
	v_mfma_f32_32x32x16_bf16 v[48:63], v[198:201], v[172:175], v[48:63]
	s_waitcnt lgkmcnt(0)
	v_mfma_f32_32x32x16_bf16 v[96:111], v[234:237], v[168:171], v[96:111]
	v_mfma_f32_32x32x16_bf16 v[32:47], v[234:237], v[172:175], v[32:47]
	ds_read_b128 v[198:201], v192 offset:9280
	ds_read_b128 v[234:237], v192 offset:13888
	s_waitcnt lgkmcnt(1)
	v_mfma_f32_32x32x16_bf16 v[80:95], v[198:201], v[168:171], v[80:95]
	v_mfma_f32_32x32x16_bf16 v[16:31], v[198:201], v[172:175], v[16:31]
	s_waitcnt lgkmcnt(0)
	v_mfma_f32_32x32x16_bf16 v[64:79], v[234:237], v[168:171], v[64:79]
	v_mfma_f32_32x32x16_bf16 v[0:15], v[234:237], v[172:175], v[0:15]
	s_setprio 0
	v_add_co_u32_e32 v198, vcc, s53, v190
	v_add_u32_e32 v217, 0x18c00, v215
	s_nop 0
	v_addc_co_u32_e32 v199, vcc, 0, v191, vcc
	v_add_co_u32_e32 v200, vcc, s53, v188
	v_add_u32_e32 v216, 0x21c00, v215
	s_nop 0
	v_addc_co_u32_e32 v201, vcc, 0, v189, vcc
	global_load_dwordx4 v[168:171], v[198:199], off offset:256
	global_load_dwordx4 v[172:175], v[200:201], off offset:256
	ds_write_b128 v217, v[160:163]
	s_waitcnt vmcnt(8)
	ds_write_b128 v216, v[164:167]
	ds_read_b128 v[160:163], v204 offset:36960
	ds_read_b128 v[164:167], v204 offset:41568
	ds_read_b128 v[234:237], v192 offset:96
	ds_read_b128 v[238:241], v192 offset:4704
	s_setprio 1
	s_waitcnt lgkmcnt(1)
	v_mfma_f32_32x32x16_bf16 v[112:127], v[234:237], v[160:163], v[112:127]
	v_mfma_f32_32x32x16_bf16 v[48:63], v[234:237], v[164:167], v[48:63]
	s_waitcnt lgkmcnt(0)
	v_mfma_f32_32x32x16_bf16 v[96:111], v[238:241], v[160:163], v[96:111]
	v_mfma_f32_32x32x16_bf16 v[32:47], v[238:241], v[164:167], v[32:47]
	ds_read_b128 v[234:237], v192 offset:9312
	ds_read_b128 v[238:241], v192 offset:13920
	s_waitcnt lgkmcnt(1)
	v_mfma_f32_32x32x16_bf16 v[80:95], v[234:237], v[160:163], v[80:95]
	v_mfma_f32_32x32x16_bf16 v[16:31], v[234:237], v[164:167], v[16:31]
	s_waitcnt lgkmcnt(0)
	v_mfma_f32_32x32x16_bf16 v[64:79], v[238:241], v[160:163], v[64:79]
	v_mfma_f32_32x32x16_bf16 v[0:15], v[238:241], v[164:167], v[0:15]
	s_setprio 0
	global_load_dwordx4 v[160:163], v[190:191], off offset:384
	global_load_dwordx4 v[164:167], v[188:189], off offset:384
	s_barrier
; template <bool trans>
; DI void gemm_core(const GTile& tl, const GTile& nx, bool has_next  , bool chain  , bool pre, u32x4 (&ra)[4], u32x4 (&rb)[4], char* smem, f32x16 (&acc)[2][4]) {
;     ...
;   const int nk = K / 64;
;   if (!pre) { G_LOAD(0); G_STORE(0); G_LOAD(1); }
;   for (int kt = 0; kt < nk; ++kt) {
;     __syncthreads();
;     G_COMPUTE(kt & 1, kt);
	s_add_i32 s2, 16, 0x12000
	v_add3_u32 v205, s2, v205, v242
	s_add_i32 s2, 16, 0x1b000
	v_add3_u32 v208, s2, v208, v242
	s_waitcnt vmcnt(9)
	ds_write_b128 v215, v[218:221]
	s_waitcnt vmcnt(8)
	ds_write_b128 v215, v[222:225] offset:36864
	ds_read_b128 v[218:221], v208
	ds_read_b128 v[222:225], v208 offset:4608
	ds_read_b128 v[234:237], v205
	ds_read_b128 v[238:241], v205 offset:4608
	s_setprio 1
	s_waitcnt lgkmcnt(1)
	v_mfma_f32_32x32x16_bf16 v[112:127], v[234:237], v[218:221], v[112:127]
	v_mfma_f32_32x32x16_bf16 v[48:63], v[234:237], v[222:225], v[48:63]
	s_waitcnt lgkmcnt(0)
	v_mfma_f32_32x32x16_bf16 v[96:111], v[238:241], v[218:221], v[96:111]
	v_mfma_f32_32x32x16_bf16 v[32:47], v[238:241], v[222:225], v[32:47]
	ds_read_b128 v[234:237], v205 offset:9216
	ds_read_b128 v[238:241], v205 offset:13824
	s_waitcnt lgkmcnt(1)
	v_mfma_f32_32x32x16_bf16 v[80:95], v[234:237], v[218:221], v[80:95]
	v_mfma_f32_32x32x16_bf16 v[16:31], v[234:237], v[222:225], v[16:31]
	s_waitcnt lgkmcnt(0)
	v_mfma_f32_32x32x16_bf16 v[64:79], v[238:241], v[218:221], v[64:79]
	v_mfma_f32_32x32x16_bf16 v[0:15], v[238:241], v[222:225], v[0:15]
	s_setprio 0
	global_load_dwordx4 v[218:221], v[194:195], off offset:384
	global_load_dwordx4 v[222:225], v[196:197], off offset:384
	s_waitcnt vmcnt(9)
	ds_write_b128 v215, v[226:229] offset:9216
	s_waitcnt vmcnt(8)
	ds_write_b128 v215, v[230:233] offset:46080
	ds_read_b128 v[226:229], v208 offset:32
	ds_read_b128 v[230:233], v208 offset:4640
	ds_read_b128 v[234:237], v205 offset:32
	ds_read_b128 v[238:241], v205 offset:4640
	s_setprio 1
	s_waitcnt lgkmcnt(1)
	v_mfma_f32_32x32x16_bf16 v[112:127], v[234:237], v[226:229], v[112:127]
	v_mfma_f32_32x32x16_bf16 v[48:63], v[234:237], v[230:233], v[48:63]
	s_waitcnt lgkmcnt(0)
	v_mfma_f32_32x32x16_bf16 v[96:111], v[238:241], v[226:229], v[96:111]
	v_mfma_f32_32x32x16_bf16 v[32:47], v[238:241], v[230:233], v[32:47]
	ds_read_b128 v[234:237], v205 offset:9248
	ds_read_b128 v[238:241], v205 offset:13856
	s_waitcnt lgkmcnt(1)
	v_mfma_f32_32x32x16_bf16 v[80:95], v[234:237], v[226:229], v[80:95]
	v_mfma_f32_32x32x16_bf16 v[16:31], v[234:237], v[230:233], v[16:31]
	s_waitcnt lgkmcnt(0)
	v_mfma_f32_32x32x16_bf16 v[64:79], v[238:241], v[226:229], v[64:79]
	v_mfma_f32_32x32x16_bf16 v[0:15], v[238:241], v[230:233], v[0:15]
	s_setprio 0
	global_load_dwordx4 v[226:229], v[184:185], off offset:384
	global_load_dwordx4 v[230:233], v[186:187], off offset:384
	s_waitcnt vmcnt(9)
	ds_write_b128 v215, v[176:179] offset:18432
	s_waitcnt vmcnt(8)
	ds_write_b128 v215, v[180:183] offset:55296
	ds_read_b128 v[176:179], v208 offset:64
	ds_read_b128 v[180:183], v208 offset:4672
	ds_read_b128 v[234:237], v205 offset:64
	ds_read_b128 v[238:241], v205 offset:4672
	s_setprio 1
	s_waitcnt lgkmcnt(1)
	v_mfma_f32_32x32x16_bf16 v[112:127], v[234:237], v[176:179], v[112:127]
	v_mfma_f32_32x32x16_bf16 v[48:63], v[234:237], v[180:183], v[48:63]
	s_waitcnt lgkmcnt(0)
	v_mfma_f32_32x32x16_bf16 v[96:111], v[238:241], v[176:179], v[96:111]
	v_mfma_f32_32x32x16_bf16 v[32:47], v[238:241], v[180:183], v[32:47]
	ds_read_b128 v[234:237], v205 offset:9280
	ds_read_b128 v[238:241], v205 offset:13888
	s_waitcnt lgkmcnt(1)
	v_mfma_f32_32x32x16_bf16 v[80:95], v[234:237], v[176:179], v[80:95]
	v_mfma_f32_32x32x16_bf16 v[16:31], v[234:237], v[180:183], v[16:31]
	s_waitcnt lgkmcnt(0)
	v_mfma_f32_32x32x16_bf16 v[64:79], v[238:241], v[176:179], v[64:79]
	v_mfma_f32_32x32x16_bf16 v[0:15], v[238:241], v[180:183], v[0:15]
	s_setprio 0
	global_load_dwordx4 v[176:179], v[198:199], off offset:384
	global_load_dwordx4 v[180:183], v[200:201], off offset:384
	s_waitcnt vmcnt(9)
	ds_write_b128 v215, v[168:171] offset:27648
	s_waitcnt vmcnt(8)
	ds_write_b128 v215, v[172:175] offset:64512
	ds_read_b128 v[168:171], v208 offset:96
	ds_read_b128 v[172:175], v208 offset:4704
	ds_read_b128 v[234:237], v205 offset:96
	ds_read_b128 v[238:241], v205 offset:4704
	s_setprio 1
	s_waitcnt lgkmcnt(1)
	v_mfma_f32_32x32x16_bf16 v[112:127], v[234:237], v[168:171], v[112:127]
	v_mfma_f32_32x32x16_bf16 v[48:63], v[234:237], v[172:175], v[48:63]
	s_waitcnt lgkmcnt(0)
	v_mfma_f32_32x32x16_bf16 v[96:111], v[238:241], v[168:171], v[96:111]
	v_mfma_f32_32x32x16_bf16 v[32:47], v[238:241], v[172:175], v[32:47]
	ds_read_b128 v[234:237], v205 offset:9312
	ds_read_b128 v[238:241], v205 offset:13920
	s_waitcnt lgkmcnt(1)
	v_mfma_f32_32x32x16_bf16 v[80:95], v[234:237], v[168:171], v[80:95]
	v_mfma_f32_32x32x16_bf16 v[16:31], v[234:237], v[172:175], v[16:31]
	s_waitcnt lgkmcnt(0)
	v_mfma_f32_32x32x16_bf16 v[64:79], v[238:241], v[168:171], v[64:79]
	v_mfma_f32_32x32x16_bf16 v[0:15], v[238:241], v[172:175], v[0:15]
	s_setprio 0
	global_load_dwordx4 v[168:171], v[190:191], off offset:512
	global_load_dwordx4 v[172:175], v[188:189], off offset:512
	s_barrier
; template <bool trans>
; DI void gemm_core(const GTile& tl, const GTile& nx, bool has_next  , bool chain  , bool pre, u32x4 (&ra)[4], u32x4 (&rb)[4], char* smem, f32x16 (&acc)[2][4]) {
;     ...
;   const int nk = K / 64;
;   if (!pre) { G_LOAD(0); G_STORE(0); G_LOAD(1); }
;   for (int kt = 0; kt < nk; ++kt) {
;     __syncthreads();
;     G_COMPUTE(kt & 1, kt);
	s_waitcnt vmcnt(9)
	ds_write_b128 v209, v[160:163]
	s_waitcnt vmcnt(8)
	ds_write_b128 v210, v[164:167]
	ds_read_b128 v[160:163], v204 offset:36864
	ds_read_b128 v[164:167], v204 offset:41472
	ds_read_b128 v[234:237], v192
	ds_read_b128 v[238:241], v192 offset:4608
	s_setprio 1
	s_waitcnt lgkmcnt(1)
	v_mfma_f32_32x32x16_bf16 v[112:127], v[234:237], v[160:163], v[112:127]
	v_mfma_f32_32x32x16_bf16 v[48:63], v[234:237], v[164:167], v[48:63]
	s_waitcnt lgkmcnt(0)
	v_mfma_f32_32x32x16_bf16 v[96:111], v[238:241], v[160:163], v[96:111]
	v_mfma_f32_32x32x16_bf16 v[32:47], v[238:241], v[164:167], v[32:47]
	ds_read_b128 v[234:237], v192 offset:9216
	ds_read_b128 v[238:241], v192 offset:13824
	s_waitcnt vmcnt(7)
	ds_write_b128 v212, v[218:221]
	s_waitcnt vmcnt(6)
	ds_write_b128 v211, v[222:225]
	ds_read_b128 v[218:221], v204 offset:36896
	ds_read_b128 v[222:225], v204 offset:41504
	s_waitcnt lgkmcnt(5)
	v_mfma_f32_32x32x16_bf16 v[80:95], v[234:237], v[160:163], v[80:95]
	v_mfma_f32_32x32x16_bf16 v[16:31], v[234:237], v[164:167], v[16:31]
	ds_read_b128 v[234:237], v192 offset:32
	s_waitcnt lgkmcnt(5)
	v_mfma_f32_32x32x16_bf16 v[64:79], v[238:241], v[160:163], v[64:79]
	v_mfma_f32_32x32x16_bf16 v[0:15], v[238:241], v[164:167], v[0:15]
	ds_read_b128 v[238:241], v192 offset:4640
	s_setprio 0
	global_load_dwordx4 v[160:163], v[194:195], off offset:512
	global_load_dwordx4 v[164:167], v[196:197], off offset:512
	s_setprio 1
	s_waitcnt lgkmcnt(1)
	v_mfma_f32_32x32x16_bf16 v[112:127], v[234:237], v[218:221], v[112:127]
	v_mfma_f32_32x32x16_bf16 v[48:63], v[234:237], v[222:225], v[48:63]
	s_waitcnt lgkmcnt(0)
	v_mfma_f32_32x32x16_bf16 v[96:111], v[238:241], v[218:221], v[96:111]
	v_mfma_f32_32x32x16_bf16 v[32:47], v[238:241], v[222:225], v[32:47]
	ds_read_b128 v[234:237], v192 offset:9248
	ds_read_b128 v[238:241], v192 offset:13856
	s_waitcnt vmcnt(7)
	ds_write_b128 v214, v[226:229]
	s_waitcnt vmcnt(6)
	ds_write_b128 v213, v[230:233]
	ds_read_b128 v[226:229], v204 offset:36928
	ds_read_b128 v[230:233], v204 offset:41536
	s_waitcnt lgkmcnt(5)
	v_mfma_f32_32x32x16_bf16 v[80:95], v[234:237], v[218:221], v[80:95]
	v_mfma_f32_32x32x16_bf16 v[16:31], v[234:237], v[222:225], v[16:31]
	ds_read_b128 v[234:237], v192 offset:64
	s_waitcnt lgkmcnt(5)
	v_mfma_f32_32x32x16_bf16 v[64:79], v[238:241], v[218:221], v[64:79]
	v_mfma_f32_32x32x16_bf16 v[0:15], v[238:241], v[222:225], v[0:15]
	ds_read_b128 v[238:241], v192 offset:4672
	s_setprio 0
	global_load_dwordx4 v[218:221], v[184:185], off offset:512
	global_load_dwordx4 v[222:225], v[186:187], off offset:512
	s_setprio 1
	s_waitcnt lgkmcnt(1)
	v_mfma_f32_32x32x16_bf16 v[112:127], v[234:237], v[226:229], v[112:127]
	v_mfma_f32_32x32x16_bf16 v[48:63], v[234:237], v[230:233], v[48:63]
	s_waitcnt lgkmcnt(0)
	v_mfma_f32_32x32x16_bf16 v[96:111], v[238:241], v[226:229], v[96:111]
	v_mfma_f32_32x32x16_bf16 v[32:47], v[238:241], v[230:233], v[32:47]
	ds_read_b128 v[234:237], v192 offset:9280
	ds_read_b128 v[238:241], v192 offset:13888
	s_waitcnt vmcnt(7)
	ds_write_b128 v217, v[176:179]
	s_waitcnt vmcnt(6)
	ds_write_b128 v216, v[180:183]
	ds_read_b128 v[176:179], v204 offset:36960
	ds_read_b128 v[180:183], v204 offset:41568
	s_waitcnt lgkmcnt(5)
	v_mfma_f32_32x32x16_bf16 v[80:95], v[234:237], v[226:229], v[80:95]
	v_mfma_f32_32x32x16_bf16 v[16:31], v[234:237], v[230:233], v[16:31]
	ds_read_b128 v[234:237], v192 offset:96
	s_waitcnt lgkmcnt(5)
	v_mfma_f32_32x32x16_bf16 v[64:79], v[238:241], v[226:229], v[64:79]
	v_mfma_f32_32x32x16_bf16 v[0:15], v[238:241], v[230:233], v[0:15]
	ds_read_b128 v[238:241], v192 offset:4704
	s_setprio 0
	global_load_dwordx4 v[226:229], v[198:199], off offset:512
	global_load_dwordx4 v[230:233], v[200:201], off offset:512
	s_setprio 1
	s_waitcnt lgkmcnt(1)
	v_mfma_f32_32x32x16_bf16 v[112:127], v[234:237], v[176:179], v[112:127]
	v_mfma_f32_32x32x16_bf16 v[48:63], v[234:237], v[180:183], v[48:63]
	s_waitcnt lgkmcnt(0)
	v_mfma_f32_32x32x16_bf16 v[96:111], v[238:241], v[176:179], v[96:111]
	v_mfma_f32_32x32x16_bf16 v[32:47], v[238:241], v[180:183], v[32:47]
	ds_read_b128 v[234:237], v192 offset:9312
	ds_read_b128 v[238:241], v192 offset:13920
	s_waitcnt lgkmcnt(0)
	s_barrier
	s_waitcnt vmcnt(7)
	ds_write_b128 v215, v[168:171]
	s_waitcnt vmcnt(6)
	ds_write_b128 v215, v[172:175] offset:36864
	ds_read_b128 v[168:171], v208
	ds_read_b128 v[172:175], v208 offset:4608
	v_mfma_f32_32x32x16_bf16 v[80:95], v[234:237], v[176:179], v[80:95]
	v_mfma_f32_32x32x16_bf16 v[16:31], v[234:237], v[180:183], v[16:31]
	ds_read_b128 v[234:237], v205
	v_mfma_f32_32x32x16_bf16 v[64:79], v[238:241], v[176:179], v[64:79]
	v_mfma_f32_32x32x16_bf16 v[0:15], v[238:241], v[180:183], v[0:15]
	ds_read_b128 v[238:241], v205 offset:4608
	s_setprio 0
	global_load_dwordx4 v[176:179], v[190:191], off offset:640
	global_load_dwordx4 v[180:183], v[188:189], off offset:640
	s_setprio 1
	s_waitcnt lgkmcnt(1)
	v_mfma_f32_32x32x16_bf16 v[112:127], v[234:237], v[168:171], v[112:127]
	v_mfma_f32_32x32x16_bf16 v[48:63], v[234:237], v[172:175], v[48:63]
	s_waitcnt lgkmcnt(0)
	v_mfma_f32_32x32x16_bf16 v[96:111], v[238:241], v[168:171], v[96:111]
	v_mfma_f32_32x32x16_bf16 v[32:47], v[238:241], v[172:175], v[32:47]
	ds_read_b128 v[234:237], v205 offset:9216
	ds_read_b128 v[238:241], v205 offset:13824
	s_waitcnt vmcnt(7)
	ds_write_b128 v215, v[160:163] offset:9216
	s_waitcnt vmcnt(6)
	ds_write_b128 v215, v[164:167] offset:46080
	ds_read_b128 v[160:163], v208 offset:32
	ds_read_b128 v[164:167], v208 offset:4640
	s_waitcnt lgkmcnt(5)
	v_mfma_f32_32x32x16_bf16 v[80:95], v[234:237], v[168:171], v[80:95]
	v_mfma_f32_32x32x16_bf16 v[16:31], v[234:237], v[172:175], v[16:31]
	ds_read_b128 v[234:237], v205 offset:32
	s_waitcnt lgkmcnt(5)
; template <bool trans>
; DI void gemm_core(const GTile& tl, const GTile& nx, bool has_next  , bool chain  , bool pre, u32x4 (&ra)[4], u32x4 (&rb)[4], char* smem, f32x16 (&acc)[2][4]) {
;     ...
;   const int nk = K / 64;
;   if (!pre) { G_LOAD(0); G_STORE(0); G_LOAD(1); }
;   for (int kt = 0; kt < nk; ++kt) {
;     __syncthreads();
;     G_COMPUTE(kt & 1, kt);
	v_mfma_f32_32x32x16_bf16 v[64:79], v[238:241], v[168:171], v[64:79]
	v_mfma_f32_32x32x16_bf16 v[0:15], v[238:241], v[172:175], v[0:15]
	ds_read_b128 v[238:241], v205 offset:4640
	s_setprio 0
	global_load_dwordx4 v[168:171], v[194:195], off offset:640
	global_load_dwordx4 v[172:175], v[196:197], off offset:640
	s_setprio 1
	s_waitcnt lgkmcnt(1)
	v_mfma_f32_32x32x16_bf16 v[112:127], v[234:237], v[160:163], v[112:127]
	v_mfma_f32_32x32x16_bf16 v[48:63], v[234:237], v[164:167], v[48:63]
	s_waitcnt lgkmcnt(0)
	v_mfma_f32_32x32x16_bf16 v[96:111], v[238:241], v[160:163], v[96:111]
	v_mfma_f32_32x32x16_bf16 v[32:47], v[238:241], v[164:167], v[32:47]
	ds_read_b128 v[234:237], v205 offset:9248
	ds_read_b128 v[238:241], v205 offset:13856
	s_waitcnt vmcnt(7)
	ds_write_b128 v215, v[218:221] offset:18432
	s_waitcnt vmcnt(6)
	ds_write_b128 v215, v[222:225] offset:55296
	ds_read_b128 v[218:221], v208 offset:64
	ds_read_b128 v[222:225], v208 offset:4672
	s_waitcnt lgkmcnt(5)
	v_mfma_f32_32x32x16_bf16 v[80:95], v[234:237], v[160:163], v[80:95]
	v_mfma_f32_32x32x16_bf16 v[16:31], v[234:237], v[164:167], v[16:31]
	ds_read_b128 v[234:237], v205 offset:64
	s_waitcnt lgkmcnt(5)
	v_mfma_f32_32x32x16_bf16 v[64:79], v[238:241], v[160:163], v[64:79]
	v_mfma_f32_32x32x16_bf16 v[0:15], v[238:241], v[164:167], v[0:15]
	ds_read_b128 v[238:241], v205 offset:4672
	s_setprio 0
	global_load_dwordx4 v[160:163], v[184:185], off offset:640
	global_load_dwordx4 v[164:167], v[186:187], off offset:640
	s_setprio 1
	s_waitcnt lgkmcnt(1)
	v_mfma_f32_32x32x16_bf16 v[112:127], v[234:237], v[218:221], v[112:127]
	v_mfma_f32_32x32x16_bf16 v[48:63], v[234:237], v[222:225], v[48:63]
	s_waitcnt lgkmcnt(0)
	v_mfma_f32_32x32x16_bf16 v[96:111], v[238:241], v[218:221], v[96:111]
	v_mfma_f32_32x32x16_bf16 v[32:47], v[238:241], v[222:225], v[32:47]
	ds_read_b128 v[234:237], v205 offset:9280
	ds_read_b128 v[238:241], v205 offset:13888
	s_waitcnt vmcnt(7)
	ds_write_b128 v215, v[226:229] offset:27648
	s_waitcnt vmcnt(6)
	ds_write_b128 v215, v[230:233] offset:64512
	ds_read_b128 v[226:229], v208 offset:96
	ds_read_b128 v[230:233], v208 offset:4704
	s_waitcnt lgkmcnt(5)
	v_mfma_f32_32x32x16_bf16 v[80:95], v[234:237], v[218:221], v[80:95]
	v_mfma_f32_32x32x16_bf16 v[16:31], v[234:237], v[222:225], v[16:31]
	ds_read_b128 v[234:237], v205 offset:96
	s_waitcnt lgkmcnt(5)
	v_mfma_f32_32x32x16_bf16 v[64:79], v[238:241], v[218:221], v[64:79]
	v_mfma_f32_32x32x16_bf16 v[0:15], v[238:241], v[222:225], v[0:15]
	ds_read_b128 v[238:241], v205 offset:4704
	s_setprio 0
	global_load_dwordx4 v[218:221], v[198:199], off offset:640
	global_load_dwordx4 v[222:225], v[200:201], off offset:640
	s_setprio 1
	s_waitcnt lgkmcnt(1)
	v_mfma_f32_32x32x16_bf16 v[112:127], v[234:237], v[226:229], v[112:127]
	v_mfma_f32_32x32x16_bf16 v[48:63], v[234:237], v[230:233], v[48:63]
	s_waitcnt lgkmcnt(0)
	v_mfma_f32_32x32x16_bf16 v[96:111], v[238:241], v[226:229], v[96:111]
	v_mfma_f32_32x32x16_bf16 v[32:47], v[238:241], v[230:233], v[32:47]
	ds_read_b128 v[234:237], v205 offset:9312
	ds_read_b128 v[238:241], v205 offset:13920
	s_waitcnt lgkmcnt(0)
	s_barrier
	s_waitcnt vmcnt(7)
	ds_write_b128 v209, v[176:179]
	s_waitcnt vmcnt(6)
	ds_write_b128 v210, v[180:183]
	ds_read_b128 v[176:179], v204 offset:36864
	ds_read_b128 v[180:183], v204 offset:41472
	v_mfma_f32_32x32x16_bf16 v[80:95], v[234:237], v[226:229], v[80:95]
	v_mfma_f32_32x32x16_bf16 v[16:31], v[234:237], v[230:233], v[16:31]
	ds_read_b128 v[234:237], v192
	v_mfma_f32_32x32x16_bf16 v[64:79], v[238:241], v[226:229], v[64:79]
	v_mfma_f32_32x32x16_bf16 v[0:15], v[238:241], v[230:233], v[0:15]
	ds_read_b128 v[238:241], v192 offset:4608
	s_setprio 0
	global_load_dwordx4 v[226:229], v[190:191], off offset:768
	global_load_dwordx4 v[230:233], v[188:189], off offset:768
	s_setprio 1
	s_waitcnt lgkmcnt(1)
	v_mfma_f32_32x32x16_bf16 v[112:127], v[234:237], v[176:179], v[112:127]
	v_mfma_f32_32x32x16_bf16 v[48:63], v[234:237], v[180:183], v[48:63]
	s_waitcnt lgkmcnt(0)
	v_mfma_f32_32x32x16_bf16 v[96:111], v[238:241], v[176:179], v[96:111]
	v_mfma_f32_32x32x16_bf16 v[32:47], v[238:241], v[180:183], v[32:47]
	ds_read_b128 v[234:237], v192 offset:9216
	ds_read_b128 v[238:241], v192 offset:13824
	s_waitcnt vmcnt(7)
	ds_write_b128 v212, v[168:171]
	s_waitcnt vmcnt(6)
	ds_write_b128 v211, v[172:175]
	ds_read_b128 v[168:171], v204 offset:36896
	ds_read_b128 v[172:175], v204 offset:41504
	s_waitcnt lgkmcnt(5)
	v_mfma_f32_32x32x16_bf16 v[80:95], v[234:237], v[176:179], v[80:95]
	v_mfma_f32_32x32x16_bf16 v[16:31], v[234:237], v[180:183], v[16:31]
	ds_read_b128 v[234:237], v192 offset:32
	s_waitcnt lgkmcnt(5)
	v_mfma_f32_32x32x16_bf16 v[64:79], v[238:241], v[176:179], v[64:79]
	v_mfma_f32_32x32x16_bf16 v[0:15], v[238:241], v[180:183], v[0:15]
	ds_read_b128 v[238:241], v192 offset:4640
	s_setprio 0
	global_load_dwordx4 v[176:179], v[194:195], off offset:768
	global_load_dwordx4 v[180:183], v[196:197], off offset:768
	s_setprio 1
	s_waitcnt lgkmcnt(1)
	v_mfma_f32_32x32x16_bf16 v[112:127], v[234:237], v[168:171], v[112:127]
	v_mfma_f32_32x32x16_bf16 v[48:63], v[234:237], v[172:175], v[48:63]
	s_waitcnt lgkmcnt(0)
	v_mfma_f32_32x32x16_bf16 v[96:111], v[238:241], v[168:171], v[96:111]
	v_mfma_f32_32x32x16_bf16 v[32:47], v[238:241], v[172:175], v[32:47]
	ds_read_b128 v[234:237], v192 offset:9248
	ds_read_b128 v[238:241], v192 offset:13856
	s_waitcnt vmcnt(7)
	ds_write_b128 v214, v[160:163]
	s_waitcnt vmcnt(6)
	ds_write_b128 v213, v[164:167]
	ds_read_b128 v[160:163], v204 offset:36928
	ds_read_b128 v[164:167], v204 offset:41536
	s_waitcnt lgkmcnt(5)
; template <bool trans>
; DI void gemm_core(const GTile& tl, const GTile& nx, bool has_next  , bool chain  , bool pre, u32x4 (&ra)[4], u32x4 (&rb)[4], char* smem, f32x16 (&acc)[2][4]) {
;     ...
;   const int nk = K / 64;
;   if (!pre) { G_LOAD(0); G_STORE(0); G_LOAD(1); }
;   for (int kt = 0; kt < nk; ++kt) {
;     __syncthreads();
;     G_COMPUTE(kt & 1, kt);
	v_mfma_f32_32x32x16_bf16 v[80:95], v[234:237], v[168:171], v[80:95]
	v_mfma_f32_32x32x16_bf16 v[16:31], v[234:237], v[172:175], v[16:31]
	ds_read_b128 v[234:237], v192 offset:64
	s_waitcnt lgkmcnt(5)
	v_mfma_f32_32x32x16_bf16 v[64:79], v[238:241], v[168:171], v[64:79]
	v_mfma_f32_32x32x16_bf16 v[0:15], v[238:241], v[172:175], v[0:15]
	ds_read_b128 v[238:241], v192 offset:4672
	s_setprio 0
	global_load_dwordx4 v[168:171], v[184:185], off offset:768
	global_load_dwordx4 v[172:175], v[186:187], off offset:768
	s_setprio 1
	s_waitcnt lgkmcnt(1)
	v_mfma_f32_32x32x16_bf16 v[112:127], v[234:237], v[160:163], v[112:127]
	v_mfma_f32_32x32x16_bf16 v[48:63], v[234:237], v[164:167], v[48:63]
	s_waitcnt lgkmcnt(0)
	v_mfma_f32_32x32x16_bf16 v[96:111], v[238:241], v[160:163], v[96:111]
	v_mfma_f32_32x32x16_bf16 v[32:47], v[238:241], v[164:167], v[32:47]
	ds_read_b128 v[234:237], v192 offset:9280
	ds_read_b128 v[238:241], v192 offset:13888
	s_waitcnt vmcnt(7)
	ds_write_b128 v217, v[218:221]
	s_waitcnt vmcnt(6)
	ds_write_b128 v216, v[222:225]
	ds_read_b128 v[218:221], v204 offset:36960
	ds_read_b128 v[222:225], v204 offset:41568
	s_waitcnt lgkmcnt(5)
	v_mfma_f32_32x32x16_bf16 v[80:95], v[234:237], v[160:163], v[80:95]
	v_mfma_f32_32x32x16_bf16 v[16:31], v[234:237], v[164:167], v[16:31]
	ds_read_b128 v[234:237], v192 offset:96
	s_waitcnt lgkmcnt(5)
	v_mfma_f32_32x32x16_bf16 v[64:79], v[238:241], v[160:163], v[64:79]
	v_mfma_f32_32x32x16_bf16 v[0:15], v[238:241], v[164:167], v[0:15]
	ds_read_b128 v[238:241], v192 offset:4704
	s_setprio 0
	global_load_dwordx4 v[160:163], v[198:199], off offset:768
	global_load_dwordx4 v[164:167], v[200:201], off offset:768
	s_setprio 1
	s_waitcnt lgkmcnt(1)
	v_mfma_f32_32x32x16_bf16 v[112:127], v[234:237], v[218:221], v[112:127]
	v_mfma_f32_32x32x16_bf16 v[48:63], v[234:237], v[222:225], v[48:63]
	s_waitcnt lgkmcnt(0)
	v_mfma_f32_32x32x16_bf16 v[96:111], v[238:241], v[218:221], v[96:111]
	v_mfma_f32_32x32x16_bf16 v[32:47], v[238:241], v[222:225], v[32:47]
	ds_read_b128 v[234:237], v192 offset:9312
	ds_read_b128 v[238:241], v192 offset:13920
	s_waitcnt lgkmcnt(0)
	s_barrier
	s_waitcnt vmcnt(7)
	ds_write_b128 v215, v[226:229]
	s_waitcnt vmcnt(6)
	ds_write_b128 v215, v[230:233] offset:36864
	ds_read_b128 v[226:229], v208
	ds_read_b128 v[230:233], v208 offset:4608
	v_mfma_f32_32x32x16_bf16 v[80:95], v[234:237], v[218:221], v[80:95]
	v_mfma_f32_32x32x16_bf16 v[16:31], v[234:237], v[222:225], v[16:31]
	ds_read_b128 v[234:237], v205
	v_mfma_f32_32x32x16_bf16 v[64:79], v[238:241], v[218:221], v[64:79]
	v_mfma_f32_32x32x16_bf16 v[0:15], v[238:241], v[222:225], v[0:15]
	ds_read_b128 v[238:241], v205 offset:4608
	s_setprio 0
	global_load_dwordx4 v[218:221], v[190:191], off offset:896
	global_load_dwordx4 v[222:225], v[188:189], off offset:896
	s_setprio 1
	s_waitcnt lgkmcnt(1)
	v_mfma_f32_32x32x16_bf16 v[112:127], v[234:237], v[226:229], v[112:127]
	v_mfma_f32_32x32x16_bf16 v[48:63], v[234:237], v[230:233], v[48:63]
	s_waitcnt lgkmcnt(0)
	v_mfma_f32_32x32x16_bf16 v[96:111], v[238:241], v[226:229], v[96:111]
	v_mfma_f32_32x32x16_bf16 v[32:47], v[238:241], v[230:233], v[32:47]
	ds_read_b128 v[234:237], v205 offset:9216
	ds_read_b128 v[238:241], v205 offset:13824
	s_waitcnt vmcnt(7)
	ds_write_b128 v215, v[176:179] offset:9216
	s_waitcnt vmcnt(6)
	ds_write_b128 v215, v[180:183] offset:46080
	ds_read_b128 v[176:179], v208 offset:32
	ds_read_b128 v[180:183], v208 offset:4640
	s_waitcnt lgkmcnt(5)
	v_mfma_f32_32x32x16_bf16 v[80:95], v[234:237], v[226:229], v[80:95]
	v_mfma_f32_32x32x16_bf16 v[16:31], v[234:237], v[230:233], v[16:31]
	ds_read_b128 v[234:237], v205 offset:32
	s_waitcnt lgkmcnt(5)
	v_mfma_f32_32x32x16_bf16 v[64:79], v[238:241], v[226:229], v[64:79]
	v_mfma_f32_32x32x16_bf16 v[0:15], v[238:241], v[230:233], v[0:15]
	ds_read_b128 v[238:241], v205 offset:4640
	s_setprio 0
	global_load_dwordx4 v[226:229], v[194:195], off offset:896
	global_load_dwordx4 v[230:233], v[196:197], off offset:896
	s_setprio 1
	s_waitcnt lgkmcnt(1)
	v_mfma_f32_32x32x16_bf16 v[112:127], v[234:237], v[176:179], v[112:127]
	v_mfma_f32_32x32x16_bf16 v[48:63], v[234:237], v[180:183], v[48:63]
	s_waitcnt lgkmcnt(0)
	v_mfma_f32_32x32x16_bf16 v[96:111], v[238:241], v[176:179], v[96:111]
	v_mfma_f32_32x32x16_bf16 v[32:47], v[238:241], v[180:183], v[32:47]
	ds_read_b128 v[234:237], v205 offset:9248
	ds_read_b128 v[238:241], v205 offset:13856
	s_waitcnt vmcnt(7)
	ds_write_b128 v215, v[168:171] offset:18432
	s_waitcnt vmcnt(6)
	ds_write_b128 v215, v[172:175] offset:55296
	ds_read_b128 v[168:171], v208 offset:64
	ds_read_b128 v[172:175], v208 offset:4672
	s_waitcnt lgkmcnt(5)
	v_mfma_f32_32x32x16_bf16 v[80:95], v[234:237], v[176:179], v[80:95]
	v_mfma_f32_32x32x16_bf16 v[16:31], v[234:237], v[180:183], v[16:31]
	ds_read_b128 v[234:237], v205 offset:64
	s_waitcnt lgkmcnt(5)
	v_mfma_f32_32x32x16_bf16 v[64:79], v[238:241], v[176:179], v[64:79]
	v_mfma_f32_32x32x16_bf16 v[0:15], v[238:241], v[180:183], v[0:15]
	ds_read_b128 v[238:241], v205 offset:4672
	s_setprio 0
	global_load_dwordx4 v[176:179], v[184:185], off offset:896
	global_load_dwordx4 v[180:183], v[186:187], off offset:896
	s_setprio 1
	s_waitcnt lgkmcnt(1)
	v_mfma_f32_32x32x16_bf16 v[112:127], v[234:237], v[168:171], v[112:127]
	v_mfma_f32_32x32x16_bf16 v[48:63], v[234:237], v[172:175], v[48:63]
	s_waitcnt lgkmcnt(0)
	v_mfma_f32_32x32x16_bf16 v[96:111], v[238:241], v[168:171], v[96:111]
	v_mfma_f32_32x32x16_bf16 v[32:47], v[238:241], v[172:175], v[32:47]
	ds_read_b128 v[234:237], v205 offset:9280
	ds_read_b128 v[238:241], v205 offset:13888
	s_waitcnt vmcnt(7)
	ds_write_b128 v215, v[160:163] offset:27648
	s_waitcnt vmcnt(6)
	ds_write_b128 v215, v[164:167] offset:64512
	ds_read_b128 v[160:163], v208 offset:96
	ds_read_b128 v[164:167], v208 offset:4704
	s_waitcnt lgkmcnt(5)
	v_mfma_f32_32x32x16_bf16 v[80:95], v[234:237], v[168:171], v[80:95]
	v_mfma_f32_32x32x16_bf16 v[16:31], v[234:237], v[172:175], v[16:31]
	ds_read_b128 v[234:237], v205 offset:96
	s_waitcnt lgkmcnt(5)
	v_mfma_f32_32x32x16_bf16 v[64:79], v[238:241], v[168:171], v[64:79]
	v_mfma_f32_32x32x16_bf16 v[0:15], v[238:241], v[172:175], v[0:15]
	ds_read_b128 v[238:241], v205 offset:4704
	s_setprio 0
	global_load_dwordx4 v[168:171], v[198:199], off offset:896
	global_load_dwordx4 v[172:175], v[200:201], off offset:896
	s_setprio 1
	s_waitcnt lgkmcnt(1)
	v_mfma_f32_32x32x16_bf16 v[112:127], v[234:237], v[160:163], v[112:127]
	v_mfma_f32_32x32x16_bf16 v[48:63], v[234:237], v[164:167], v[48:63]
	s_waitcnt lgkmcnt(0)
	v_mfma_f32_32x32x16_bf16 v[96:111], v[238:241], v[160:163], v[96:111]
	v_mfma_f32_32x32x16_bf16 v[32:47], v[238:241], v[164:167], v[32:47]
	ds_read_b128 v[234:237], v205 offset:9312
	ds_read_b128 v[238:241], v205 offset:13920
	s_waitcnt lgkmcnt(0)
	s_barrier
; template <bool trans>
; DI void gemm_core(const GTile& tl, const GTile& nx, bool has_next  , bool chain  , bool pre, u32x4 (&ra)[4], u32x4 (&rb)[4], char* smem, f32x16 (&acc)[2][4]) {
;     ...
;   const int nk = K / 64;
;   if (!pre) { G_LOAD(0); G_STORE(0); G_LOAD(1); }
;   for (int kt = 0; kt < nk; ++kt) {
;     __syncthreads();
;     G_COMPUTE(kt & 1, kt);
	s_waitcnt vmcnt(7)
	ds_write_b128 v209, v[218:221]
	s_waitcnt vmcnt(6)
	ds_write_b128 v210, v[222:225]
	ds_read_b128 v[218:221], v204 offset:36864
	ds_read_b128 v[222:225], v204 offset:41472
	v_mfma_f32_32x32x16_bf16 v[80:95], v[234:237], v[160:163], v[80:95]
	v_mfma_f32_32x32x16_bf16 v[16:31], v[234:237], v[164:167], v[16:31]
	ds_read_b128 v[234:237], v192
	v_mfma_f32_32x32x16_bf16 v[64:79], v[238:241], v[160:163], v[64:79]
	v_mfma_f32_32x32x16_bf16 v[0:15], v[238:241], v[164:167], v[0:15]
	ds_read_b128 v[238:241], v192 offset:4608
	s_setprio 0
	global_load_dwordx4 v[160:163], v[190:191], off offset:1024
	global_load_dwordx4 v[164:167], v[188:189], off offset:1024
	s_setprio 1
	s_waitcnt lgkmcnt(1)
	v_mfma_f32_32x32x16_bf16 v[112:127], v[234:237], v[218:221], v[112:127]
	v_mfma_f32_32x32x16_bf16 v[48:63], v[234:237], v[222:225], v[48:63]
	s_waitcnt lgkmcnt(0)
	v_mfma_f32_32x32x16_bf16 v[96:111], v[238:241], v[218:221], v[96:111]
	v_mfma_f32_32x32x16_bf16 v[32:47], v[238:241], v[222:225], v[32:47]
	ds_read_b128 v[234:237], v192 offset:9216
	ds_read_b128 v[238:241], v192 offset:13824
	s_waitcnt vmcnt(7)
	ds_write_b128 v212, v[226:229]
	s_waitcnt vmcnt(6)
	ds_write_b128 v211, v[230:233]
	ds_read_b128 v[226:229], v204 offset:36896
	ds_read_b128 v[230:233], v204 offset:41504
	s_waitcnt lgkmcnt(5)
	v_mfma_f32_32x32x16_bf16 v[80:95], v[234:237], v[218:221], v[80:95]
	v_mfma_f32_32x32x16_bf16 v[16:31], v[234:237], v[222:225], v[16:31]
	ds_read_b128 v[234:237], v192 offset:32
	s_waitcnt lgkmcnt(5)
	v_mfma_f32_32x32x16_bf16 v[64:79], v[238:241], v[218:221], v[64:79]
	v_mfma_f32_32x32x16_bf16 v[0:15], v[238:241], v[222:225], v[0:15]
	ds_read_b128 v[238:241], v192 offset:4640
	s_setprio 0
	global_load_dwordx4 v[218:221], v[194:195], off offset:1024
	global_load_dwordx4 v[222:225], v[196:197], off offset:1024
	s_setprio 1
	s_waitcnt lgkmcnt(1)
	v_mfma_f32_32x32x16_bf16 v[112:127], v[234:237], v[226:229], v[112:127]
	v_mfma_f32_32x32x16_bf16 v[48:63], v[234:237], v[230:233], v[48:63]
	s_waitcnt lgkmcnt(0)
	v_mfma_f32_32x32x16_bf16 v[96:111], v[238:241], v[226:229], v[96:111]
	v_mfma_f32_32x32x16_bf16 v[32:47], v[238:241], v[230:233], v[32:47]
	ds_read_b128 v[234:237], v192 offset:9248
	ds_read_b128 v[238:241], v192 offset:13856
	s_waitcnt vmcnt(7)
	ds_write_b128 v214, v[176:179]
	s_waitcnt vmcnt(6)
	ds_write_b128 v213, v[180:183]
	ds_read_b128 v[176:179], v204 offset:36928
	ds_read_b128 v[180:183], v204 offset:41536
	s_waitcnt lgkmcnt(5)
	v_mfma_f32_32x32x16_bf16 v[80:95], v[234:237], v[226:229], v[80:95]
	v_mfma_f32_32x32x16_bf16 v[16:31], v[234:237], v[230:233], v[16:31]
	ds_read_b128 v[234:237], v192 offset:64
	s_waitcnt lgkmcnt(5)
	v_mfma_f32_32x32x16_bf16 v[64:79], v[238:241], v[226:229], v[64:79]
	v_mfma_f32_32x32x16_bf16 v[0:15], v[238:241], v[230:233], v[0:15]
	ds_read_b128 v[238:241], v192 offset:4672
	s_setprio 0
	global_load_dwordx4 v[226:229], v[184:185], off offset:1024
	global_load_dwordx4 v[230:233], v[186:187], off offset:1024
	s_setprio 1
	s_waitcnt lgkmcnt(1)
	v_mfma_f32_32x32x16_bf16 v[112:127], v[234:237], v[176:179], v[112:127]
	v_mfma_f32_32x32x16_bf16 v[48:63], v[234:237], v[180:183], v[48:63]
	s_waitcnt lgkmcnt(0)
	v_mfma_f32_32x32x16_bf16 v[96:111], v[238:241], v[176:179], v[96:111]
	v_mfma_f32_32x32x16_bf16 v[32:47], v[238:241], v[180:183], v[32:47]
	ds_read_b128 v[234:237], v192 offset:9280
	ds_read_b128 v[238:241], v192 offset:13888
	s_waitcnt vmcnt(7)
	ds_write_b128 v217, v[168:171]
	s_waitcnt vmcnt(6)
	ds_write_b128 v216, v[172:175]
	ds_read_b128 v[168:171], v204 offset:36960
	ds_read_b128 v[172:175], v204 offset:41568
	s_waitcnt lgkmcnt(5)
	v_mfma_f32_32x32x16_bf16 v[80:95], v[234:237], v[176:179], v[80:95]
	v_mfma_f32_32x32x16_bf16 v[16:31], v[234:237], v[180:183], v[16:31]
	ds_read_b128 v[234:237], v192 offset:96
	s_waitcnt lgkmcnt(5)
	v_mfma_f32_32x32x16_bf16 v[64:79], v[238:241], v[176:179], v[64:79]
	v_mfma_f32_32x32x16_bf16 v[0:15], v[238:241], v[180:183], v[0:15]
	ds_read_b128 v[238:241], v192 offset:4704
	s_setprio 0
	global_load_dwordx4 v[176:179], v[198:199], off offset:1024
	global_load_dwordx4 v[180:183], v[200:201], off offset:1024
	s_setprio 1
	s_waitcnt lgkmcnt(1)
	v_mfma_f32_32x32x16_bf16 v[112:127], v[234:237], v[168:171], v[112:127]
	v_mfma_f32_32x32x16_bf16 v[48:63], v[234:237], v[172:175], v[48:63]
	s_waitcnt lgkmcnt(0)
	v_mfma_f32_32x32x16_bf16 v[96:111], v[238:241], v[168:171], v[96:111]
	v_mfma_f32_32x32x16_bf16 v[32:47], v[238:241], v[172:175], v[32:47]
	ds_read_b128 v[234:237], v192 offset:9312
	ds_read_b128 v[238:241], v192 offset:13920
	s_waitcnt lgkmcnt(0)
	s_barrier
; template <bool trans>
; DI void gemm_core(const GTile& tl, const GTile& nx, bool has_next  , bool chain  , bool pre, u32x4 (&ra)[4], u32x4 (&rb)[4], char* smem, f32x16 (&acc)[2][4]) {
;     ...
;   const int nk = K / 64;
;   if (!pre) { G_LOAD(0); G_STORE(0); G_LOAD(1); }
;   for (int kt = 0; kt < nk; ++kt) {
;     __syncthreads();
;     G_COMPUTE(kt & 1, kt);
	s_waitcnt vmcnt(7)
	ds_write_b128 v215, v[160:163]
	s_waitcnt vmcnt(6)
	ds_write_b128 v215, v[164:167] offset:36864
	ds_read_b128 v[160:163], v208
	ds_read_b128 v[164:167], v208 offset:4608
	v_mfma_f32_32x32x16_bf16 v[80:95], v[234:237], v[168:171], v[80:95]
	v_mfma_f32_32x32x16_bf16 v[16:31], v[234:237], v[172:175], v[16:31]
	ds_read_b128 v[234:237], v205
	v_mfma_f32_32x32x16_bf16 v[64:79], v[238:241], v[168:171], v[64:79]
	v_mfma_f32_32x32x16_bf16 v[0:15], v[238:241], v[172:175], v[0:15]
	ds_read_b128 v[238:241], v205 offset:4608
	s_setprio 0
	global_load_dwordx4 v[168:171], v[190:191], off offset:1152
	global_load_dwordx4 v[172:175], v[188:189], off offset:1152
	s_setprio 1
	s_waitcnt lgkmcnt(1)
	v_mfma_f32_32x32x16_bf16 v[112:127], v[234:237], v[160:163], v[112:127]
	v_mfma_f32_32x32x16_bf16 v[48:63], v[234:237], v[164:167], v[48:63]
	s_waitcnt lgkmcnt(0)
	v_mfma_f32_32x32x16_bf16 v[96:111], v[238:241], v[160:163], v[96:111]
	v_mfma_f32_32x32x16_bf16 v[32:47], v[238:241], v[164:167], v[32:47]
	ds_read_b128 v[234:237], v205 offset:9216
	ds_read_b128 v[238:241], v205 offset:13824
	s_waitcnt vmcnt(7)
	ds_write_b128 v215, v[218:221] offset:9216
	s_waitcnt vmcnt(6)
	ds_write_b128 v215, v[222:225] offset:46080
	ds_read_b128 v[218:221], v208 offset:32
	ds_read_b128 v[222:225], v208 offset:4640
	s_waitcnt lgkmcnt(5)
	v_mfma_f32_32x32x16_bf16 v[80:95], v[234:237], v[160:163], v[80:95]
	v_mfma_f32_32x32x16_bf16 v[16:31], v[234:237], v[164:167], v[16:31]
	ds_read_b128 v[234:237], v205 offset:32
	s_waitcnt lgkmcnt(5)
	v_mfma_f32_32x32x16_bf16 v[64:79], v[238:241], v[160:163], v[64:79]
	v_mfma_f32_32x32x16_bf16 v[0:15], v[238:241], v[164:167], v[0:15]
	ds_read_b128 v[238:241], v205 offset:4640
	s_setprio 0
	global_load_dwordx4 v[160:163], v[194:195], off offset:1152
	global_load_dwordx4 v[164:167], v[196:197], off offset:1152
	s_setprio 1
	s_waitcnt lgkmcnt(1)
	v_mfma_f32_32x32x16_bf16 v[112:127], v[234:237], v[218:221], v[112:127]
	v_mfma_f32_32x32x16_bf16 v[48:63], v[234:237], v[222:225], v[48:63]
	s_waitcnt lgkmcnt(0)
	v_mfma_f32_32x32x16_bf16 v[96:111], v[238:241], v[218:221], v[96:111]
	v_mfma_f32_32x32x16_bf16 v[32:47], v[238:241], v[222:225], v[32:47]
	ds_read_b128 v[234:237], v205 offset:9248
	ds_read_b128 v[238:241], v205 offset:13856
	s_waitcnt vmcnt(7)
	ds_write_b128 v215, v[226:229] offset:18432
	s_waitcnt vmcnt(6)
	ds_write_b128 v215, v[230:233] offset:55296
	ds_read_b128 v[226:229], v208 offset:64
	ds_read_b128 v[230:233], v208 offset:4672
	s_waitcnt lgkmcnt(5)
	v_mfma_f32_32x32x16_bf16 v[80:95], v[234:237], v[218:221], v[80:95]
	v_mfma_f32_32x32x16_bf16 v[16:31], v[234:237], v[222:225], v[16:31]
	ds_read_b128 v[234:237], v205 offset:64
	s_waitcnt lgkmcnt(5)
	v_mfma_f32_32x32x16_bf16 v[64:79], v[238:241], v[218:221], v[64:79]
	v_mfma_f32_32x32x16_bf16 v[0:15], v[238:241], v[222:225], v[0:15]
	ds_read_b128 v[238:241], v205 offset:4672
	s_setprio 0
	global_load_dwordx4 v[218:221], v[184:185], off offset:1152
	global_load_dwordx4 v[222:225], v[186:187], off offset:1152
	s_setprio 1
	s_waitcnt lgkmcnt(1)
	v_mfma_f32_32x32x16_bf16 v[112:127], v[234:237], v[226:229], v[112:127]
	v_mfma_f32_32x32x16_bf16 v[48:63], v[234:237], v[230:233], v[48:63]
	s_waitcnt lgkmcnt(0)
	v_mfma_f32_32x32x16_bf16 v[96:111], v[238:241], v[226:229], v[96:111]
	v_mfma_f32_32x32x16_bf16 v[32:47], v[238:241], v[230:233], v[32:47]
	ds_read_b128 v[234:237], v205 offset:9280
	ds_read_b128 v[238:241], v205 offset:13888
	s_waitcnt vmcnt(7)
	ds_write_b128 v215, v[176:179] offset:27648
	s_waitcnt vmcnt(6)
	ds_write_b128 v215, v[180:183] offset:64512
	ds_read_b128 v[176:179], v208 offset:96
	ds_read_b128 v[180:183], v208 offset:4704
	s_waitcnt lgkmcnt(5)
	v_mfma_f32_32x32x16_bf16 v[80:95], v[234:237], v[226:229], v[80:95]
	v_mfma_f32_32x32x16_bf16 v[16:31], v[234:237], v[230:233], v[16:31]
	ds_read_b128 v[234:237], v205 offset:96
	s_waitcnt lgkmcnt(5)
	v_mfma_f32_32x32x16_bf16 v[64:79], v[238:241], v[226:229], v[64:79]
	v_mfma_f32_32x32x16_bf16 v[0:15], v[238:241], v[230:233], v[0:15]
	ds_read_b128 v[238:241], v205 offset:4704
	s_setprio 0
	global_load_dwordx4 v[226:229], v[198:199], off offset:1152
	global_load_dwordx4 v[230:233], v[200:201], off offset:1152
	s_setprio 1
	s_waitcnt lgkmcnt(1)
	v_mfma_f32_32x32x16_bf16 v[112:127], v[234:237], v[176:179], v[112:127]
	v_mfma_f32_32x32x16_bf16 v[48:63], v[234:237], v[180:183], v[48:63]
	s_waitcnt lgkmcnt(0)
	v_mfma_f32_32x32x16_bf16 v[96:111], v[238:241], v[176:179], v[96:111]
	v_mfma_f32_32x32x16_bf16 v[32:47], v[238:241], v[180:183], v[32:47]
	ds_read_b128 v[234:237], v205 offset:9312
	ds_read_b128 v[238:241], v205 offset:13920
	s_waitcnt lgkmcnt(0)
	s_barrier
; template <bool trans>
; DI void gemm_core(const GTile& tl, const GTile& nx, bool has_next  , bool chain  , bool pre, u32x4 (&ra)[4], u32x4 (&rb)[4], char* smem, f32x16 (&acc)[2][4]) {
;     ...
;   const int nk = K / 64;
;   if (!pre) { G_LOAD(0); G_STORE(0); G_LOAD(1); }
;   for (int kt = 0; kt < nk; ++kt) {
;     __syncthreads();
;     G_COMPUTE(kt & 1, kt);
	s_waitcnt vmcnt(7)
	ds_write_b128 v209, v[168:171]
	s_waitcnt vmcnt(6)
	ds_write_b128 v210, v[172:175]
	ds_read_b128 v[168:171], v204 offset:36864
	ds_read_b128 v[172:175], v204 offset:41472
	v_mfma_f32_32x32x16_bf16 v[80:95], v[234:237], v[176:179], v[80:95]
	v_mfma_f32_32x32x16_bf16 v[16:31], v[234:237], v[180:183], v[16:31]
	ds_read_b128 v[234:237], v192
	v_mfma_f32_32x32x16_bf16 v[64:79], v[238:241], v[176:179], v[64:79]
	v_mfma_f32_32x32x16_bf16 v[0:15], v[238:241], v[180:183], v[0:15]
	ds_read_b128 v[238:241], v192 offset:4608
	s_setprio 0
	global_load_dwordx4 v[176:179], v[190:191], off offset:1280
	global_load_dwordx4 v[180:183], v[188:189], off offset:1280
	s_setprio 1
	s_waitcnt lgkmcnt(1)
	v_mfma_f32_32x32x16_bf16 v[112:127], v[234:237], v[168:171], v[112:127]
	v_mfma_f32_32x32x16_bf16 v[48:63], v[234:237], v[172:175], v[48:63]
	s_waitcnt lgkmcnt(0)
	v_mfma_f32_32x32x16_bf16 v[96:111], v[238:241], v[168:171], v[96:111]
	v_mfma_f32_32x32x16_bf16 v[32:47], v[238:241], v[172:175], v[32:47]
	ds_read_b128 v[234:237], v192 offset:9216
	ds_read_b128 v[238:241], v192 offset:13824
	s_waitcnt vmcnt(7)
	ds_write_b128 v212, v[160:163]
	s_waitcnt vmcnt(6)
	ds_write_b128 v211, v[164:167]
	ds_read_b128 v[160:163], v204 offset:36896
	ds_read_b128 v[164:167], v204 offset:41504
	s_waitcnt lgkmcnt(5)
	v_mfma_f32_32x32x16_bf16 v[80:95], v[234:237], v[168:171], v[80:95]
	v_mfma_f32_32x32x16_bf16 v[16:31], v[234:237], v[172:175], v[16:31]
	ds_read_b128 v[234:237], v192 offset:32
	s_waitcnt lgkmcnt(5)
	v_mfma_f32_32x32x16_bf16 v[64:79], v[238:241], v[168:171], v[64:79]
	v_mfma_f32_32x32x16_bf16 v[0:15], v[238:241], v[172:175], v[0:15]
	ds_read_b128 v[238:241], v192 offset:4640
	s_setprio 0
	global_load_dwordx4 v[168:171], v[194:195], off offset:1280
	global_load_dwordx4 v[172:175], v[196:197], off offset:1280
	s_setprio 1
	s_waitcnt lgkmcnt(1)
	v_mfma_f32_32x32x16_bf16 v[112:127], v[234:237], v[160:163], v[112:127]
	v_mfma_f32_32x32x16_bf16 v[48:63], v[234:237], v[164:167], v[48:63]
	s_waitcnt lgkmcnt(0)
	v_mfma_f32_32x32x16_bf16 v[96:111], v[238:241], v[160:163], v[96:111]
	v_mfma_f32_32x32x16_bf16 v[32:47], v[238:241], v[164:167], v[32:47]
	ds_read_b128 v[234:237], v192 offset:9248
	ds_read_b128 v[238:241], v192 offset:13856
	s_waitcnt vmcnt(7)
	ds_write_b128 v214, v[218:221]
	s_waitcnt vmcnt(6)
	ds_write_b128 v213, v[222:225]
	ds_read_b128 v[218:221], v204 offset:36928
	ds_read_b128 v[222:225], v204 offset:41536
	s_waitcnt lgkmcnt(5)
	v_mfma_f32_32x32x16_bf16 v[80:95], v[234:237], v[160:163], v[80:95]
	v_mfma_f32_32x32x16_bf16 v[16:31], v[234:237], v[164:167], v[16:31]
	ds_read_b128 v[234:237], v192 offset:64
	s_waitcnt lgkmcnt(5)
	v_mfma_f32_32x32x16_bf16 v[64:79], v[238:241], v[160:163], v[64:79]
	v_mfma_f32_32x32x16_bf16 v[0:15], v[238:241], v[164:167], v[0:15]
	ds_read_b128 v[238:241], v192 offset:4672
	s_setprio 0
	global_load_dwordx4 v[160:163], v[184:185], off offset:1280
	global_load_dwordx4 v[164:167], v[186:187], off offset:1280
	s_setprio 1
	s_waitcnt lgkmcnt(1)
	v_mfma_f32_32x32x16_bf16 v[112:127], v[234:237], v[218:221], v[112:127]
	v_mfma_f32_32x32x16_bf16 v[48:63], v[234:237], v[222:225], v[48:63]
	s_waitcnt lgkmcnt(0)
	v_mfma_f32_32x32x16_bf16 v[96:111], v[238:241], v[218:221], v[96:111]
	v_mfma_f32_32x32x16_bf16 v[32:47], v[238:241], v[222:225], v[32:47]
	ds_read_b128 v[234:237], v192 offset:9280
	ds_read_b128 v[238:241], v192 offset:13888
	s_waitcnt vmcnt(7)
	ds_write_b128 v217, v[226:229]
	s_waitcnt vmcnt(6)
	ds_write_b128 v216, v[230:233]
	ds_read_b128 v[226:229], v204 offset:36960
	ds_read_b128 v[230:233], v204 offset:41568
	s_waitcnt lgkmcnt(5)
	v_mfma_f32_32x32x16_bf16 v[80:95], v[234:237], v[218:221], v[80:95]
	v_mfma_f32_32x32x16_bf16 v[16:31], v[234:237], v[222:225], v[16:31]
	ds_read_b128 v[234:237], v192 offset:96
	s_waitcnt lgkmcnt(5)
	v_mfma_f32_32x32x16_bf16 v[64:79], v[238:241], v[218:221], v[64:79]
	v_mfma_f32_32x32x16_bf16 v[0:15], v[238:241], v[222:225], v[0:15]
	ds_read_b128 v[238:241], v192 offset:4704
	s_setprio 0
	global_load_dwordx4 v[218:221], v[198:199], off offset:1280
	global_load_dwordx4 v[222:225], v[200:201], off offset:1280
	s_setprio 1
	s_waitcnt lgkmcnt(1)
	v_mfma_f32_32x32x16_bf16 v[112:127], v[234:237], v[226:229], v[112:127]
	v_mfma_f32_32x32x16_bf16 v[48:63], v[234:237], v[230:233], v[48:63]
	s_waitcnt lgkmcnt(0)
	v_mfma_f32_32x32x16_bf16 v[96:111], v[238:241], v[226:229], v[96:111]
	v_mfma_f32_32x32x16_bf16 v[32:47], v[238:241], v[230:233], v[32:47]
	ds_read_b128 v[234:237], v192 offset:9312
	ds_read_b128 v[238:241], v192 offset:13920
	s_waitcnt lgkmcnt(0)
	s_barrier
; template <bool trans>
; DI void gemm_core(const GTile& tl, const GTile& nx, bool has_next  , bool chain  , bool pre, u32x4 (&ra)[4], u32x4 (&rb)[4], char* smem, f32x16 (&acc)[2][4]) {
;     ...
;   const int nk = K / 64;
;   if (!pre) { G_LOAD(0); G_STORE(0); G_LOAD(1); }
;   for (int kt = 0; kt < nk; ++kt) {
;     __syncthreads();
;     G_COMPUTE(kt & 1, kt);
	s_waitcnt vmcnt(7)
	ds_write_b128 v215, v[176:179]
	s_waitcnt vmcnt(6)
	ds_write_b128 v215, v[180:183] offset:36864
	ds_read_b128 v[176:179], v208
	ds_read_b128 v[180:183], v208 offset:4608
	v_mfma_f32_32x32x16_bf16 v[80:95], v[234:237], v[226:229], v[80:95]
	v_mfma_f32_32x32x16_bf16 v[16:31], v[234:237], v[230:233], v[16:31]
	ds_read_b128 v[234:237], v205
	v_mfma_f32_32x32x16_bf16 v[64:79], v[238:241], v[226:229], v[64:79]
	v_mfma_f32_32x32x16_bf16 v[0:15], v[238:241], v[230:233], v[0:15]
	ds_read_b128 v[238:241], v205 offset:4608
	s_setprio 0
	global_load_dwordx4 v[226:229], v[190:191], off offset:1408
	global_load_dwordx4 v[230:233], v[188:189], off offset:1408
	s_setprio 1
	s_waitcnt lgkmcnt(1)
	v_mfma_f32_32x32x16_bf16 v[112:127], v[234:237], v[176:179], v[112:127]
	v_mfma_f32_32x32x16_bf16 v[48:63], v[234:237], v[180:183], v[48:63]
	s_waitcnt lgkmcnt(0)
	v_mfma_f32_32x32x16_bf16 v[96:111], v[238:241], v[176:179], v[96:111]
	v_mfma_f32_32x32x16_bf16 v[32:47], v[238:241], v[180:183], v[32:47]
	ds_read_b128 v[234:237], v205 offset:9216
	ds_read_b128 v[238:241], v205 offset:13824
	s_waitcnt vmcnt(7)
	ds_write_b128 v215, v[168:171] offset:9216
	s_waitcnt vmcnt(6)
	ds_write_b128 v215, v[172:175] offset:46080
	ds_read_b128 v[168:171], v208 offset:32
	ds_read_b128 v[172:175], v208 offset:4640
	s_waitcnt lgkmcnt(5)
	v_mfma_f32_32x32x16_bf16 v[80:95], v[234:237], v[176:179], v[80:95]
	v_mfma_f32_32x32x16_bf16 v[16:31], v[234:237], v[180:183], v[16:31]
	ds_read_b128 v[234:237], v205 offset:32
	s_waitcnt lgkmcnt(5)
	v_mfma_f32_32x32x16_bf16 v[64:79], v[238:241], v[176:179], v[64:79]
	v_mfma_f32_32x32x16_bf16 v[0:15], v[238:241], v[180:183], v[0:15]
	ds_read_b128 v[238:241], v205 offset:4640
	s_setprio 0
	global_load_dwordx4 v[176:179], v[194:195], off offset:1408
	global_load_dwordx4 v[180:183], v[196:197], off offset:1408
	s_setprio 1
	s_waitcnt lgkmcnt(1)
	v_mfma_f32_32x32x16_bf16 v[112:127], v[234:237], v[168:171], v[112:127]
	v_mfma_f32_32x32x16_bf16 v[48:63], v[234:237], v[172:175], v[48:63]
	s_waitcnt lgkmcnt(0)
	v_mfma_f32_32x32x16_bf16 v[96:111], v[238:241], v[168:171], v[96:111]
	v_mfma_f32_32x32x16_bf16 v[32:47], v[238:241], v[172:175], v[32:47]
	ds_read_b128 v[234:237], v205 offset:9248
	ds_read_b128 v[238:241], v205 offset:13856
	s_waitcnt vmcnt(7)
	ds_write_b128 v215, v[160:163] offset:18432
	s_waitcnt vmcnt(6)
	ds_write_b128 v215, v[164:167] offset:55296
	ds_read_b128 v[160:163], v208 offset:64
	ds_read_b128 v[164:167], v208 offset:4672
	s_waitcnt lgkmcnt(5)
	v_mfma_f32_32x32x16_bf16 v[80:95], v[234:237], v[168:171], v[80:95]
	v_mfma_f32_32x32x16_bf16 v[16:31], v[234:237], v[172:175], v[16:31]
	ds_read_b128 v[234:237], v205 offset:64
	s_waitcnt lgkmcnt(5)
	v_mfma_f32_32x32x16_bf16 v[64:79], v[238:241], v[168:171], v[64:79]
	v_mfma_f32_32x32x16_bf16 v[0:15], v[238:241], v[172:175], v[0:15]
	ds_read_b128 v[238:241], v205 offset:4672
	s_setprio 0
	global_load_dwordx4 v[168:171], v[184:185], off offset:1408
	global_load_dwordx4 v[172:175], v[186:187], off offset:1408
	s_setprio 1
	s_waitcnt lgkmcnt(1)
	v_mfma_f32_32x32x16_bf16 v[112:127], v[234:237], v[160:163], v[112:127]
	v_mfma_f32_32x32x16_bf16 v[48:63], v[234:237], v[164:167], v[48:63]
	s_waitcnt lgkmcnt(0)
	v_mfma_f32_32x32x16_bf16 v[96:111], v[238:241], v[160:163], v[96:111]
	v_mfma_f32_32x32x16_bf16 v[32:47], v[238:241], v[164:167], v[32:47]
	ds_read_b128 v[234:237], v205 offset:9280
	ds_read_b128 v[238:241], v205 offset:13888
	s_waitcnt vmcnt(7)
	ds_write_b128 v215, v[218:221] offset:27648
	s_waitcnt vmcnt(6)
	ds_write_b128 v215, v[222:225] offset:64512
	ds_read_b128 v[218:221], v208 offset:96
	ds_read_b128 v[222:225], v208 offset:4704
	s_waitcnt lgkmcnt(5)
	v_mfma_f32_32x32x16_bf16 v[80:95], v[234:237], v[160:163], v[80:95]
	v_mfma_f32_32x32x16_bf16 v[16:31], v[234:237], v[164:167], v[16:31]
	ds_read_b128 v[234:237], v205 offset:96
	s_waitcnt lgkmcnt(5)
	v_mfma_f32_32x32x16_bf16 v[64:79], v[238:241], v[160:163], v[64:79]
	v_mfma_f32_32x32x16_bf16 v[0:15], v[238:241], v[164:167], v[0:15]
	ds_read_b128 v[238:241], v205 offset:4704
	s_setprio 0
	global_load_dwordx4 v[160:163], v[198:199], off offset:1408
	global_load_dwordx4 v[164:167], v[200:201], off offset:1408
	s_setprio 1
	s_waitcnt lgkmcnt(1)
	v_mfma_f32_32x32x16_bf16 v[112:127], v[234:237], v[218:221], v[112:127]
	v_mfma_f32_32x32x16_bf16 v[48:63], v[234:237], v[222:225], v[48:63]
	s_waitcnt lgkmcnt(0)
	v_mfma_f32_32x32x16_bf16 v[96:111], v[238:241], v[218:221], v[96:111]
	v_mfma_f32_32x32x16_bf16 v[32:47], v[238:241], v[222:225], v[32:47]
	ds_read_b128 v[234:237], v205 offset:9312
	ds_read_b128 v[238:241], v205 offset:13920
	s_waitcnt lgkmcnt(0)
	s_barrier
; template <bool trans>
; DI void gemm_core(const GTile& tl, const GTile& nx, bool has_next  , bool chain  , bool pre, u32x4 (&ra)[4], u32x4 (&rb)[4], char* smem, f32x16 (&acc)[2][4]) {
;     ...
;   const int nk = K / 64;
;   if (!pre) { G_LOAD(0); G_STORE(0); G_LOAD(1); }
;   for (int kt = 0; kt < nk; ++kt) {
;     __syncthreads();
;     G_COMPUTE(kt & 1, kt);
	s_waitcnt vmcnt(7)
	ds_write_b128 v209, v[226:229]
	s_waitcnt vmcnt(6)
	ds_write_b128 v210, v[230:233]
	ds_read_b128 v[226:229], v204 offset:36864
	ds_read_b128 v[230:233], v204 offset:41472
	v_mfma_f32_32x32x16_bf16 v[80:95], v[234:237], v[218:221], v[80:95]
	v_mfma_f32_32x32x16_bf16 v[16:31], v[234:237], v[222:225], v[16:31]
	ds_read_b128 v[234:237], v192
	v_mfma_f32_32x32x16_bf16 v[64:79], v[238:241], v[218:221], v[64:79]
	v_mfma_f32_32x32x16_bf16 v[0:15], v[238:241], v[222:225], v[0:15]
	ds_read_b128 v[238:241], v192 offset:4608
	s_setprio 0
	global_load_dwordx4 v[218:221], v[190:191], off offset:1536
	global_load_dwordx4 v[222:225], v[188:189], off offset:1536
	s_setprio 1
	s_waitcnt lgkmcnt(1)
	v_mfma_f32_32x32x16_bf16 v[112:127], v[234:237], v[226:229], v[112:127]
	v_mfma_f32_32x32x16_bf16 v[48:63], v[234:237], v[230:233], v[48:63]
	s_waitcnt lgkmcnt(0)
	v_mfma_f32_32x32x16_bf16 v[96:111], v[238:241], v[226:229], v[96:111]
	v_mfma_f32_32x32x16_bf16 v[32:47], v[238:241], v[230:233], v[32:47]
	ds_read_b128 v[234:237], v192 offset:9216
	ds_read_b128 v[238:241], v192 offset:13824
	s_waitcnt vmcnt(7)
	ds_write_b128 v212, v[176:179]
	s_waitcnt vmcnt(6)
	ds_write_b128 v211, v[180:183]
	ds_read_b128 v[176:179], v204 offset:36896
	ds_read_b128 v[180:183], v204 offset:41504
	s_waitcnt lgkmcnt(5)
	v_mfma_f32_32x32x16_bf16 v[80:95], v[234:237], v[226:229], v[80:95]
	v_mfma_f32_32x32x16_bf16 v[16:31], v[234:237], v[230:233], v[16:31]
	ds_read_b128 v[234:237], v192 offset:32
	s_waitcnt lgkmcnt(5)
	v_mfma_f32_32x32x16_bf16 v[64:79], v[238:241], v[226:229], v[64:79]
	v_mfma_f32_32x32x16_bf16 v[0:15], v[238:241], v[230:233], v[0:15]
	ds_read_b128 v[238:241], v192 offset:4640
	s_setprio 0
	global_load_dwordx4 v[226:229], v[194:195], off offset:1536
	global_load_dwordx4 v[230:233], v[196:197], off offset:1536
	s_setprio 1
	s_waitcnt lgkmcnt(1)
	v_mfma_f32_32x32x16_bf16 v[112:127], v[234:237], v[176:179], v[112:127]
	v_mfma_f32_32x32x16_bf16 v[48:63], v[234:237], v[180:183], v[48:63]
	s_waitcnt lgkmcnt(0)
	v_mfma_f32_32x32x16_bf16 v[96:111], v[238:241], v[176:179], v[96:111]
	v_mfma_f32_32x32x16_bf16 v[32:47], v[238:241], v[180:183], v[32:47]
	ds_read_b128 v[234:237], v192 offset:9248
	ds_read_b128 v[238:241], v192 offset:13856
	s_waitcnt vmcnt(7)
	ds_write_b128 v214, v[168:171]
	s_waitcnt vmcnt(6)
	ds_write_b128 v213, v[172:175]
	ds_read_b128 v[168:171], v204 offset:36928
	ds_read_b128 v[172:175], v204 offset:41536
	s_waitcnt lgkmcnt(5)
	v_mfma_f32_32x32x16_bf16 v[80:95], v[234:237], v[176:179], v[80:95]
	v_mfma_f32_32x32x16_bf16 v[16:31], v[234:237], v[180:183], v[16:31]
	ds_read_b128 v[234:237], v192 offset:64
	s_waitcnt lgkmcnt(5)
	v_mfma_f32_32x32x16_bf16 v[64:79], v[238:241], v[176:179], v[64:79]
	v_mfma_f32_32x32x16_bf16 v[0:15], v[238:241], v[180:183], v[0:15]
	ds_read_b128 v[238:241], v192 offset:4672
	s_setprio 0
	global_load_dwordx4 v[176:179], v[184:185], off offset:1536
	global_load_dwordx4 v[180:183], v[186:187], off offset:1536
	s_setprio 1
	s_waitcnt lgkmcnt(1)
	v_mfma_f32_32x32x16_bf16 v[112:127], v[234:237], v[168:171], v[112:127]
	v_mfma_f32_32x32x16_bf16 v[48:63], v[234:237], v[172:175], v[48:63]
	s_waitcnt lgkmcnt(0)
	v_mfma_f32_32x32x16_bf16 v[96:111], v[238:241], v[168:171], v[96:111]
	v_mfma_f32_32x32x16_bf16 v[32:47], v[238:241], v[172:175], v[32:47]
	ds_read_b128 v[234:237], v192 offset:9280
	ds_read_b128 v[238:241], v192 offset:13888
	s_waitcnt vmcnt(7)
	ds_write_b128 v217, v[160:163]
	s_waitcnt vmcnt(6)
	ds_write_b128 v216, v[164:167]
	ds_read_b128 v[160:163], v204 offset:36960
	ds_read_b128 v[164:167], v204 offset:41568
	s_waitcnt lgkmcnt(5)
	v_mfma_f32_32x32x16_bf16 v[80:95], v[234:237], v[168:171], v[80:95]
	v_mfma_f32_32x32x16_bf16 v[16:31], v[234:237], v[172:175], v[16:31]
	ds_read_b128 v[234:237], v192 offset:96
	s_waitcnt lgkmcnt(5)
	v_mfma_f32_32x32x16_bf16 v[64:79], v[238:241], v[168:171], v[64:79]
	v_mfma_f32_32x32x16_bf16 v[0:15], v[238:241], v[172:175], v[0:15]
	ds_read_b128 v[238:241], v192 offset:4704
	s_setprio 0
	global_load_dwordx4 v[168:171], v[198:199], off offset:1536
	global_load_dwordx4 v[172:175], v[200:201], off offset:1536
	s_setprio 1
	s_waitcnt lgkmcnt(1)
	v_mfma_f32_32x32x16_bf16 v[112:127], v[234:237], v[160:163], v[112:127]
	v_mfma_f32_32x32x16_bf16 v[48:63], v[234:237], v[164:167], v[48:63]
	s_waitcnt lgkmcnt(0)
	v_mfma_f32_32x32x16_bf16 v[96:111], v[238:241], v[160:163], v[96:111]
	v_mfma_f32_32x32x16_bf16 v[32:47], v[238:241], v[164:167], v[32:47]
	ds_read_b128 v[234:237], v192 offset:9312
	ds_read_b128 v[238:241], v192 offset:13920
	s_waitcnt lgkmcnt(0)
	s_barrier
; template <bool trans>
; DI void gemm_core(const GTile& tl, const GTile& nx, bool has_next  , bool chain  , bool pre, u32x4 (&ra)[4], u32x4 (&rb)[4], char* smem, f32x16 (&acc)[2][4]) {
;     ...
;   const int nk = K / 64;
;   if (!pre) { G_LOAD(0); G_STORE(0); G_LOAD(1); }
;   for (int kt = 0; kt < nk; ++kt) {
;     __syncthreads();
;     G_COMPUTE(kt & 1, kt);
	s_waitcnt vmcnt(7)
	ds_write_b128 v215, v[218:221]
	s_waitcnt vmcnt(6)
	ds_write_b128 v215, v[222:225] offset:36864
	ds_read_b128 v[218:221], v208
	ds_read_b128 v[222:225], v208 offset:4608
	v_mfma_f32_32x32x16_bf16 v[80:95], v[234:237], v[160:163], v[80:95]
	v_mfma_f32_32x32x16_bf16 v[16:31], v[234:237], v[164:167], v[16:31]
	ds_read_b128 v[234:237], v205
	v_mfma_f32_32x32x16_bf16 v[64:79], v[238:241], v[160:163], v[64:79]
	v_mfma_f32_32x32x16_bf16 v[0:15], v[238:241], v[164:167], v[0:15]
	ds_read_b128 v[238:241], v205 offset:4608
	s_setprio 0
	global_load_dwordx4 v[160:163], v[190:191], off offset:1664
	global_load_dwordx4 v[164:167], v[188:189], off offset:1664
	s_setprio 1
	s_waitcnt lgkmcnt(1)
	v_mfma_f32_32x32x16_bf16 v[112:127], v[234:237], v[218:221], v[112:127]
	v_mfma_f32_32x32x16_bf16 v[48:63], v[234:237], v[222:225], v[48:63]
	s_waitcnt lgkmcnt(0)
	v_mfma_f32_32x32x16_bf16 v[96:111], v[238:241], v[218:221], v[96:111]
	v_mfma_f32_32x32x16_bf16 v[32:47], v[238:241], v[222:225], v[32:47]
	ds_read_b128 v[234:237], v205 offset:9216
	ds_read_b128 v[238:241], v205 offset:13824
	s_waitcnt vmcnt(7)
	ds_write_b128 v215, v[226:229] offset:9216
	s_waitcnt vmcnt(6)
	ds_write_b128 v215, v[230:233] offset:46080
	ds_read_b128 v[226:229], v208 offset:32
	ds_read_b128 v[230:233], v208 offset:4640
	s_waitcnt lgkmcnt(5)
	v_mfma_f32_32x32x16_bf16 v[80:95], v[234:237], v[218:221], v[80:95]
	v_mfma_f32_32x32x16_bf16 v[16:31], v[234:237], v[222:225], v[16:31]
	ds_read_b128 v[234:237], v205 offset:32
	s_waitcnt lgkmcnt(5)
	v_mfma_f32_32x32x16_bf16 v[64:79], v[238:241], v[218:221], v[64:79]
	v_mfma_f32_32x32x16_bf16 v[0:15], v[238:241], v[222:225], v[0:15]
	ds_read_b128 v[238:241], v205 offset:4640
	s_setprio 0
	global_load_dwordx4 v[218:221], v[194:195], off offset:1664
	global_load_dwordx4 v[222:225], v[196:197], off offset:1664
	s_setprio 1
	s_waitcnt lgkmcnt(1)
	v_mfma_f32_32x32x16_bf16 v[112:127], v[234:237], v[226:229], v[112:127]
	v_mfma_f32_32x32x16_bf16 v[48:63], v[234:237], v[230:233], v[48:63]
	s_waitcnt lgkmcnt(0)
	v_mfma_f32_32x32x16_bf16 v[96:111], v[238:241], v[226:229], v[96:111]
	v_mfma_f32_32x32x16_bf16 v[32:47], v[238:241], v[230:233], v[32:47]
	ds_read_b128 v[234:237], v205 offset:9248
	ds_read_b128 v[238:241], v205 offset:13856
	s_waitcnt vmcnt(7)
	ds_write_b128 v215, v[176:179] offset:18432
	s_waitcnt vmcnt(6)
	ds_write_b128 v215, v[180:183] offset:55296
	ds_read_b128 v[176:179], v208 offset:64
	ds_read_b128 v[180:183], v208 offset:4672
	s_waitcnt lgkmcnt(5)
	v_mfma_f32_32x32x16_bf16 v[80:95], v[234:237], v[226:229], v[80:95]
	v_mfma_f32_32x32x16_bf16 v[16:31], v[234:237], v[230:233], v[16:31]
	ds_read_b128 v[234:237], v205 offset:64
	s_waitcnt lgkmcnt(5)
	v_mfma_f32_32x32x16_bf16 v[64:79], v[238:241], v[226:229], v[64:79]
	v_mfma_f32_32x32x16_bf16 v[0:15], v[238:241], v[230:233], v[0:15]
	ds_read_b128 v[238:241], v205 offset:4672
	s_setprio 0
	global_load_dwordx4 v[226:229], v[184:185], off offset:1664
	global_load_dwordx4 v[230:233], v[186:187], off offset:1664
	s_setprio 1
	s_waitcnt lgkmcnt(1)
	v_mfma_f32_32x32x16_bf16 v[112:127], v[234:237], v[176:179], v[112:127]
	v_mfma_f32_32x32x16_bf16 v[48:63], v[234:237], v[180:183], v[48:63]
	s_waitcnt lgkmcnt(0)
	v_mfma_f32_32x32x16_bf16 v[96:111], v[238:241], v[176:179], v[96:111]
	v_mfma_f32_32x32x16_bf16 v[32:47], v[238:241], v[180:183], v[32:47]
	ds_read_b128 v[234:237], v205 offset:9280
	ds_read_b128 v[238:241], v205 offset:13888
	s_waitcnt vmcnt(7)
	ds_write_b128 v215, v[168:171] offset:27648
	s_waitcnt vmcnt(6)
	ds_write_b128 v215, v[172:175] offset:64512
	ds_read_b128 v[168:171], v208 offset:96
	ds_read_b128 v[172:175], v208 offset:4704
	s_waitcnt lgkmcnt(5)
	v_mfma_f32_32x32x16_bf16 v[80:95], v[234:237], v[176:179], v[80:95]
	v_mfma_f32_32x32x16_bf16 v[16:31], v[234:237], v[180:183], v[16:31]
	ds_read_b128 v[234:237], v205 offset:96
	s_waitcnt lgkmcnt(5)
	v_mfma_f32_32x32x16_bf16 v[64:79], v[238:241], v[176:179], v[64:79]
	v_mfma_f32_32x32x16_bf16 v[0:15], v[238:241], v[180:183], v[0:15]
	ds_read_b128 v[238:241], v205 offset:4704
	s_setprio 0
	global_load_dwordx4 v[176:179], v[198:199], off offset:1664
	global_load_dwordx4 v[180:183], v[200:201], off offset:1664
	s_setprio 1
	s_waitcnt lgkmcnt(1)
	v_mfma_f32_32x32x16_bf16 v[112:127], v[234:237], v[168:171], v[112:127]
	v_mfma_f32_32x32x16_bf16 v[48:63], v[234:237], v[172:175], v[48:63]
	s_waitcnt lgkmcnt(0)
	v_mfma_f32_32x32x16_bf16 v[96:111], v[238:241], v[168:171], v[96:111]
	v_mfma_f32_32x32x16_bf16 v[32:47], v[238:241], v[172:175], v[32:47]
	ds_read_b128 v[234:237], v205 offset:9312
	ds_read_b128 v[238:241], v205 offset:13920
	s_waitcnt lgkmcnt(0)
	s_barrier
; template <bool trans>
; DI void gemm_core(const GTile& tl, const GTile& nx, bool has_next  , bool chain  , bool pre, u32x4 (&ra)[4], u32x4 (&rb)[4], char* smem, f32x16 (&acc)[2][4]) {
;     ...
;   const int nk = K / 64;
;   if (!pre) { G_LOAD(0); G_STORE(0); G_LOAD(1); }
;   for (int kt = 0; kt < nk; ++kt) {
;     __syncthreads();
;     G_COMPUTE(kt & 1, kt);
	s_waitcnt vmcnt(7)
	ds_write_b128 v209, v[160:163]
	s_waitcnt vmcnt(6)
	ds_write_b128 v210, v[164:167]
	ds_read_b128 v[160:163], v204 offset:36864
	ds_read_b128 v[164:167], v204 offset:41472
	v_mfma_f32_32x32x16_bf16 v[80:95], v[234:237], v[168:171], v[80:95]
	v_mfma_f32_32x32x16_bf16 v[16:31], v[234:237], v[172:175], v[16:31]
	ds_read_b128 v[234:237], v192
	v_mfma_f32_32x32x16_bf16 v[64:79], v[238:241], v[168:171], v[64:79]
	v_mfma_f32_32x32x16_bf16 v[0:15], v[238:241], v[172:175], v[0:15]
	ds_read_b128 v[238:241], v192 offset:4608
	s_setprio 0
	global_load_dwordx4 v[168:171], v[190:191], off offset:1792
	global_load_dwordx4 v[172:175], v[188:189], off offset:1792
	s_setprio 1
	s_waitcnt lgkmcnt(1)
	v_mfma_f32_32x32x16_bf16 v[112:127], v[234:237], v[160:163], v[112:127]
	v_mfma_f32_32x32x16_bf16 v[48:63], v[234:237], v[164:167], v[48:63]
	s_waitcnt lgkmcnt(0)
	v_mfma_f32_32x32x16_bf16 v[96:111], v[238:241], v[160:163], v[96:111]
	v_mfma_f32_32x32x16_bf16 v[32:47], v[238:241], v[164:167], v[32:47]
	ds_read_b128 v[234:237], v192 offset:9216
	ds_read_b128 v[238:241], v192 offset:13824
	s_waitcnt vmcnt(7)
	ds_write_b128 v212, v[218:221]
	s_waitcnt vmcnt(6)
	ds_write_b128 v211, v[222:225]
	ds_read_b128 v[218:221], v204 offset:36896
	ds_read_b128 v[222:225], v204 offset:41504
	s_waitcnt lgkmcnt(5)
	v_mfma_f32_32x32x16_bf16 v[80:95], v[234:237], v[160:163], v[80:95]
	v_mfma_f32_32x32x16_bf16 v[16:31], v[234:237], v[164:167], v[16:31]
	ds_read_b128 v[234:237], v192 offset:32
	s_waitcnt lgkmcnt(5)
	v_mfma_f32_32x32x16_bf16 v[64:79], v[238:241], v[160:163], v[64:79]
	v_mfma_f32_32x32x16_bf16 v[0:15], v[238:241], v[164:167], v[0:15]
	ds_read_b128 v[238:241], v192 offset:4640
	s_setprio 0
	global_load_dwordx4 v[160:163], v[194:195], off offset:1792
	global_load_dwordx4 v[164:167], v[196:197], off offset:1792
	s_setprio 1
	s_waitcnt lgkmcnt(1)
	v_mfma_f32_32x32x16_bf16 v[112:127], v[234:237], v[218:221], v[112:127]
	v_mfma_f32_32x32x16_bf16 v[48:63], v[234:237], v[222:225], v[48:63]
	s_waitcnt lgkmcnt(0)
	v_mfma_f32_32x32x16_bf16 v[96:111], v[238:241], v[218:221], v[96:111]
	v_mfma_f32_32x32x16_bf16 v[32:47], v[238:241], v[222:225], v[32:47]
	ds_read_b128 v[234:237], v192 offset:9248
	ds_read_b128 v[238:241], v192 offset:13856
	s_waitcnt vmcnt(7)
	ds_write_b128 v214, v[226:229]
	s_waitcnt vmcnt(6)
	ds_write_b128 v213, v[230:233]
	ds_read_b128 v[226:229], v204 offset:36928
	ds_read_b128 v[230:233], v204 offset:41536
	s_waitcnt lgkmcnt(5)
	v_mfma_f32_32x32x16_bf16 v[80:95], v[234:237], v[218:221], v[80:95]
	v_mfma_f32_32x32x16_bf16 v[16:31], v[234:237], v[222:225], v[16:31]
	ds_read_b128 v[234:237], v192 offset:64
	s_waitcnt lgkmcnt(5)
	v_mfma_f32_32x32x16_bf16 v[64:79], v[238:241], v[218:221], v[64:79]
	v_mfma_f32_32x32x16_bf16 v[0:15], v[238:241], v[222:225], v[0:15]
	ds_read_b128 v[238:241], v192 offset:4672
	s_setprio 0
	global_load_dwordx4 v[218:221], v[184:185], off offset:1792
	global_load_dwordx4 v[222:225], v[186:187], off offset:1792
	s_setprio 1
	s_waitcnt lgkmcnt(1)
	v_mfma_f32_32x32x16_bf16 v[112:127], v[234:237], v[226:229], v[112:127]
	v_mfma_f32_32x32x16_bf16 v[48:63], v[234:237], v[230:233], v[48:63]
	s_waitcnt lgkmcnt(0)
	v_mfma_f32_32x32x16_bf16 v[96:111], v[238:241], v[226:229], v[96:111]
	v_mfma_f32_32x32x16_bf16 v[32:47], v[238:241], v[230:233], v[32:47]
	ds_read_b128 v[234:237], v192 offset:9280
	ds_read_b128 v[238:241], v192 offset:13888
	s_waitcnt vmcnt(7)
	ds_write_b128 v217, v[176:179]
	s_waitcnt vmcnt(6)
	ds_write_b128 v216, v[180:183]
	ds_read_b128 v[176:179], v204 offset:36960
	ds_read_b128 v[180:183], v204 offset:41568
	s_waitcnt lgkmcnt(5)
	v_mfma_f32_32x32x16_bf16 v[80:95], v[234:237], v[226:229], v[80:95]
	v_mfma_f32_32x32x16_bf16 v[16:31], v[234:237], v[230:233], v[16:31]
	ds_read_b128 v[234:237], v192 offset:96
	s_waitcnt lgkmcnt(5)
	v_mfma_f32_32x32x16_bf16 v[64:79], v[238:241], v[226:229], v[64:79]
	v_mfma_f32_32x32x16_bf16 v[0:15], v[238:241], v[230:233], v[0:15]
	ds_read_b128 v[238:241], v192 offset:4704
	s_setprio 0
	global_load_dwordx4 v[226:229], v[198:199], off offset:1792
	global_load_dwordx4 v[230:233], v[200:201], off offset:1792
	s_setprio 1
	s_waitcnt lgkmcnt(1)
	v_mfma_f32_32x32x16_bf16 v[112:127], v[234:237], v[176:179], v[112:127]
	v_mfma_f32_32x32x16_bf16 v[48:63], v[234:237], v[180:183], v[48:63]
	s_waitcnt lgkmcnt(0)
	v_mfma_f32_32x32x16_bf16 v[96:111], v[238:241], v[176:179], v[96:111]
	v_mfma_f32_32x32x16_bf16 v[32:47], v[238:241], v[180:183], v[32:47]
	ds_read_b128 v[234:237], v192 offset:9312
	ds_read_b128 v[238:241], v192 offset:13920
	s_waitcnt lgkmcnt(0)
	s_barrier
; template <bool trans>
; DI void gemm_core(const GTile& tl, const GTile& nx, bool has_next  , bool chain  , bool pre, u32x4 (&ra)[4], u32x4 (&rb)[4], char* smem, f32x16 (&acc)[2][4]) {
;     ...
;   const int nk = K / 64;
;   if (!pre) { G_LOAD(0); G_STORE(0); G_LOAD(1); }
;   for (int kt = 0; kt < nk; ++kt) {
;     __syncthreads();
;     G_COMPUTE(kt & 1, kt);
	s_waitcnt vmcnt(7)
	ds_write_b128 v215, v[168:171]
	s_waitcnt vmcnt(6)
	ds_write_b128 v215, v[172:175] offset:36864
	ds_read_b128 v[168:171], v208
	ds_read_b128 v[172:175], v208 offset:4608
	v_mfma_f32_32x32x16_bf16 v[80:95], v[234:237], v[176:179], v[80:95]
	v_mfma_f32_32x32x16_bf16 v[16:31], v[234:237], v[180:183], v[16:31]
	ds_read_b128 v[234:237], v205
	v_mfma_f32_32x32x16_bf16 v[64:79], v[238:241], v[176:179], v[64:79]
	v_mfma_f32_32x32x16_bf16 v[0:15], v[238:241], v[180:183], v[0:15]
	ds_read_b128 v[238:241], v205 offset:4608
	s_setprio 0
	global_load_dwordx4 v[176:179], v[190:191], off offset:1920
	global_load_dwordx4 v[180:183], v[188:189], off offset:1920
	s_setprio 1
	s_waitcnt lgkmcnt(1)
	v_mfma_f32_32x32x16_bf16 v[112:127], v[234:237], v[168:171], v[112:127]
	v_mfma_f32_32x32x16_bf16 v[48:63], v[234:237], v[172:175], v[48:63]
	s_waitcnt lgkmcnt(0)
	v_mfma_f32_32x32x16_bf16 v[96:111], v[238:241], v[168:171], v[96:111]
	v_mfma_f32_32x32x16_bf16 v[32:47], v[238:241], v[172:175], v[32:47]
	ds_read_b128 v[234:237], v205 offset:9216
	ds_read_b128 v[238:241], v205 offset:13824
	s_waitcnt vmcnt(7)
	ds_write_b128 v215, v[160:163] offset:9216
	s_waitcnt vmcnt(6)
	ds_write_b128 v215, v[164:167] offset:46080
	ds_read_b128 v[160:163], v208 offset:32
	ds_read_b128 v[164:167], v208 offset:4640
	s_waitcnt lgkmcnt(5)
	v_mfma_f32_32x32x16_bf16 v[80:95], v[234:237], v[168:171], v[80:95]
	v_mfma_f32_32x32x16_bf16 v[16:31], v[234:237], v[172:175], v[16:31]
	ds_read_b128 v[234:237], v205 offset:32
	s_waitcnt lgkmcnt(5)
	v_mfma_f32_32x32x16_bf16 v[64:79], v[238:241], v[168:171], v[64:79]
	v_mfma_f32_32x32x16_bf16 v[0:15], v[238:241], v[172:175], v[0:15]
	ds_read_b128 v[238:241], v205 offset:4640
	s_setprio 0
	global_load_dwordx4 v[168:171], v[194:195], off offset:1920
	global_load_dwordx4 v[172:175], v[196:197], off offset:1920
	s_setprio 1
	s_waitcnt lgkmcnt(1)
	v_mfma_f32_32x32x16_bf16 v[112:127], v[234:237], v[160:163], v[112:127]
	v_mfma_f32_32x32x16_bf16 v[48:63], v[234:237], v[164:167], v[48:63]
	s_waitcnt lgkmcnt(0)
	v_mfma_f32_32x32x16_bf16 v[96:111], v[238:241], v[160:163], v[96:111]
	v_mfma_f32_32x32x16_bf16 v[32:47], v[238:241], v[164:167], v[32:47]
	ds_read_b128 v[234:237], v205 offset:9248
	ds_read_b128 v[238:241], v205 offset:13856
	s_waitcnt vmcnt(7)
	ds_write_b128 v215, v[218:221] offset:18432
	s_waitcnt vmcnt(6)
	ds_write_b128 v215, v[222:225] offset:55296
	ds_read_b128 v[218:221], v208 offset:64
	ds_read_b128 v[222:225], v208 offset:4672
	s_waitcnt lgkmcnt(5)
	v_mfma_f32_32x32x16_bf16 v[80:95], v[234:237], v[160:163], v[80:95]
	v_mfma_f32_32x32x16_bf16 v[16:31], v[234:237], v[164:167], v[16:31]
	ds_read_b128 v[234:237], v205 offset:64
	s_waitcnt lgkmcnt(5)
	v_mfma_f32_32x32x16_bf16 v[64:79], v[238:241], v[160:163], v[64:79]
	v_mfma_f32_32x32x16_bf16 v[0:15], v[238:241], v[164:167], v[0:15]
	ds_read_b128 v[238:241], v205 offset:4672
	s_setprio 0
	global_load_dwordx4 v[160:163], v[184:185], off offset:1920
	global_load_dwordx4 v[164:167], v[186:187], off offset:1920
	s_setprio 1
	s_waitcnt lgkmcnt(1)
	v_mfma_f32_32x32x16_bf16 v[112:127], v[234:237], v[218:221], v[112:127]
	v_mfma_f32_32x32x16_bf16 v[48:63], v[234:237], v[222:225], v[48:63]
	s_waitcnt lgkmcnt(0)
	v_mfma_f32_32x32x16_bf16 v[96:111], v[238:241], v[218:221], v[96:111]
	v_mfma_f32_32x32x16_bf16 v[32:47], v[238:241], v[222:225], v[32:47]
	ds_read_b128 v[234:237], v205 offset:9280
	ds_read_b128 v[238:241], v205 offset:13888
	s_waitcnt vmcnt(7)
	ds_write_b128 v215, v[226:229] offset:27648
	s_waitcnt vmcnt(6)
	ds_write_b128 v215, v[230:233] offset:64512
	ds_read_b128 v[226:229], v208 offset:96
	ds_read_b128 v[230:233], v208 offset:4704
	s_waitcnt lgkmcnt(5)
	v_mfma_f32_32x32x16_bf16 v[80:95], v[234:237], v[218:221], v[80:95]
	v_mfma_f32_32x32x16_bf16 v[16:31], v[234:237], v[222:225], v[16:31]
	ds_read_b128 v[234:237], v205 offset:96
	s_waitcnt lgkmcnt(5)
	v_mfma_f32_32x32x16_bf16 v[64:79], v[238:241], v[218:221], v[64:79]
	v_mfma_f32_32x32x16_bf16 v[0:15], v[238:241], v[222:225], v[0:15]
	ds_read_b128 v[238:241], v205 offset:4704
	s_setprio 0
	global_load_dwordx4 v[218:221], v[198:199], off offset:1920
	global_load_dwordx4 v[222:225], v[200:201], off offset:1920
	s_setprio 1
	s_waitcnt lgkmcnt(1)
	v_mfma_f32_32x32x16_bf16 v[112:127], v[234:237], v[226:229], v[112:127]
	v_mfma_f32_32x32x16_bf16 v[48:63], v[234:237], v[230:233], v[48:63]
	s_waitcnt lgkmcnt(0)
	v_mfma_f32_32x32x16_bf16 v[96:111], v[238:241], v[226:229], v[96:111]
	v_mfma_f32_32x32x16_bf16 v[32:47], v[238:241], v[230:233], v[32:47]
	ds_read_b128 v[234:237], v205 offset:9312
	ds_read_b128 v[238:241], v205 offset:13920
	s_waitcnt lgkmcnt(0)
	s_barrier
; template <bool trans>
; DI void gemm_core(const GTile& tl, const GTile& nx, bool has_next  , bool chain  , bool pre, u32x4 (&ra)[4], u32x4 (&rb)[4], char* smem, f32x16 (&acc)[2][4]) {
;     ...
;   const int nk = K / 64;
;   if (!pre) { G_LOAD(0); G_STORE(0); G_LOAD(1); }
;   for (int kt = 0; kt < nk; ++kt) {
;     __syncthreads();
;     G_COMPUTE(kt & 1, kt);
	s_waitcnt vmcnt(7)
	ds_write_b128 v209, v[176:179]
	s_waitcnt vmcnt(6)
	ds_write_b128 v210, v[180:183]
	ds_read_b128 v[176:179], v204 offset:36864
	ds_read_b128 v[180:183], v204 offset:41472
	v_mfma_f32_32x32x16_bf16 v[80:95], v[234:237], v[226:229], v[80:95]
	v_mfma_f32_32x32x16_bf16 v[16:31], v[234:237], v[230:233], v[16:31]
	ds_read_b128 v[234:237], v192
	v_mfma_f32_32x32x16_bf16 v[64:79], v[238:241], v[226:229], v[64:79]
	v_mfma_f32_32x32x16_bf16 v[0:15], v[238:241], v[230:233], v[0:15]
	ds_read_b128 v[238:241], v192 offset:4608
	s_setprio 0
	global_load_dwordx4 v[226:229], v[190:191], off offset:2048
	global_load_dwordx4 v[230:233], v[188:189], off offset:2048
	s_setprio 1
	s_waitcnt lgkmcnt(1)
	v_mfma_f32_32x32x16_bf16 v[112:127], v[234:237], v[176:179], v[112:127]
	v_mfma_f32_32x32x16_bf16 v[48:63], v[234:237], v[180:183], v[48:63]
	s_waitcnt lgkmcnt(0)
	v_mfma_f32_32x32x16_bf16 v[96:111], v[238:241], v[176:179], v[96:111]
	v_mfma_f32_32x32x16_bf16 v[32:47], v[238:241], v[180:183], v[32:47]
	ds_read_b128 v[234:237], v192 offset:9216
	ds_read_b128 v[238:241], v192 offset:13824
	s_waitcnt vmcnt(7)
	ds_write_b128 v212, v[168:171]
	s_waitcnt vmcnt(6)
	ds_write_b128 v211, v[172:175]
	ds_read_b128 v[168:171], v204 offset:36896
	ds_read_b128 v[172:175], v204 offset:41504
	s_waitcnt lgkmcnt(5)
	v_mfma_f32_32x32x16_bf16 v[80:95], v[234:237], v[176:179], v[80:95]
	v_mfma_f32_32x32x16_bf16 v[16:31], v[234:237], v[180:183], v[16:31]
	ds_read_b128 v[234:237], v192 offset:32
	s_waitcnt lgkmcnt(5)
	v_mfma_f32_32x32x16_bf16 v[64:79], v[238:241], v[176:179], v[64:79]
	v_mfma_f32_32x32x16_bf16 v[0:15], v[238:241], v[180:183], v[0:15]
	ds_read_b128 v[238:241], v192 offset:4640
	s_setprio 0
	global_load_dwordx4 v[176:179], v[194:195], off offset:2048
	global_load_dwordx4 v[180:183], v[196:197], off offset:2048
	s_setprio 1
	s_waitcnt lgkmcnt(1)
	v_mfma_f32_32x32x16_bf16 v[112:127], v[234:237], v[168:171], v[112:127]
	v_mfma_f32_32x32x16_bf16 v[48:63], v[234:237], v[172:175], v[48:63]
	s_waitcnt lgkmcnt(0)
	v_mfma_f32_32x32x16_bf16 v[96:111], v[238:241], v[168:171], v[96:111]
	v_mfma_f32_32x32x16_bf16 v[32:47], v[238:241], v[172:175], v[32:47]
	ds_read_b128 v[234:237], v192 offset:9248
	ds_read_b128 v[238:241], v192 offset:13856
	s_waitcnt vmcnt(7)
	ds_write_b128 v214, v[160:163]
	s_waitcnt vmcnt(6)
	ds_write_b128 v213, v[164:167]
	ds_read_b128 v[160:163], v204 offset:36928
	ds_read_b128 v[164:167], v204 offset:41536
	s_waitcnt lgkmcnt(5)
	v_mfma_f32_32x32x16_bf16 v[80:95], v[234:237], v[168:171], v[80:95]
	v_mfma_f32_32x32x16_bf16 v[16:31], v[234:237], v[172:175], v[16:31]
	ds_read_b128 v[234:237], v192 offset:64
	s_waitcnt lgkmcnt(5)
	v_mfma_f32_32x32x16_bf16 v[64:79], v[238:241], v[168:171], v[64:79]
	v_mfma_f32_32x32x16_bf16 v[0:15], v[238:241], v[172:175], v[0:15]
	ds_read_b128 v[238:241], v192 offset:4672
	s_setprio 0
	global_load_dwordx4 v[168:171], v[184:185], off offset:2048
	global_load_dwordx4 v[172:175], v[186:187], off offset:2048
	s_setprio 1
	s_waitcnt lgkmcnt(1)
	v_mfma_f32_32x32x16_bf16 v[112:127], v[234:237], v[160:163], v[112:127]
	v_mfma_f32_32x32x16_bf16 v[48:63], v[234:237], v[164:167], v[48:63]
	s_waitcnt lgkmcnt(0)
	v_mfma_f32_32x32x16_bf16 v[96:111], v[238:241], v[160:163], v[96:111]
	v_mfma_f32_32x32x16_bf16 v[32:47], v[238:241], v[164:167], v[32:47]
	ds_read_b128 v[234:237], v192 offset:9280
	ds_read_b128 v[238:241], v192 offset:13888
	s_waitcnt vmcnt(7)
	ds_write_b128 v217, v[218:221]
	s_waitcnt vmcnt(6)
	ds_write_b128 v216, v[222:225]
	ds_read_b128 v[218:221], v204 offset:36960
	ds_read_b128 v[222:225], v204 offset:41568
	s_waitcnt lgkmcnt(5)
	v_mfma_f32_32x32x16_bf16 v[80:95], v[234:237], v[160:163], v[80:95]
	v_mfma_f32_32x32x16_bf16 v[16:31], v[234:237], v[164:167], v[16:31]
	ds_read_b128 v[234:237], v192 offset:96
	s_waitcnt lgkmcnt(5)
	v_mfma_f32_32x32x16_bf16 v[64:79], v[238:241], v[160:163], v[64:79]
	v_mfma_f32_32x32x16_bf16 v[0:15], v[238:241], v[164:167], v[0:15]
	ds_read_b128 v[238:241], v192 offset:4704
	s_setprio 0
	global_load_dwordx4 v[160:163], v[198:199], off offset:2048
	global_load_dwordx4 v[164:167], v[200:201], off offset:2048
	s_setprio 1
	s_waitcnt lgkmcnt(1)
	v_mfma_f32_32x32x16_bf16 v[112:127], v[234:237], v[218:221], v[112:127]
	v_mfma_f32_32x32x16_bf16 v[48:63], v[234:237], v[222:225], v[48:63]
	s_waitcnt lgkmcnt(0)
	v_mfma_f32_32x32x16_bf16 v[96:111], v[238:241], v[218:221], v[96:111]
	v_mfma_f32_32x32x16_bf16 v[32:47], v[238:241], v[222:225], v[32:47]
	ds_read_b128 v[234:237], v192 offset:9312
	ds_read_b128 v[238:241], v192 offset:13920
	s_waitcnt lgkmcnt(0)
	s_barrier
; template <bool trans>
; DI void gemm_core(const GTile& tl, const GTile& nx, bool has_next  , bool chain  , bool pre, u32x4 (&ra)[4], u32x4 (&rb)[4], char* smem, f32x16 (&acc)[2][4]) {
;     ...
;   const int nk = K / 64;
;   if (!pre) { G_LOAD(0); G_STORE(0); G_LOAD(1); }
;   for (int kt = 0; kt < nk; ++kt) {
;     __syncthreads();
;     G_COMPUTE(kt & 1, kt);
	s_waitcnt vmcnt(7)
	ds_write_b128 v215, v[226:229]
	s_waitcnt vmcnt(6)
	ds_write_b128 v215, v[230:233] offset:36864
	ds_read_b128 v[226:229], v208
	ds_read_b128 v[230:233], v208 offset:4608
	v_mfma_f32_32x32x16_bf16 v[80:95], v[234:237], v[218:221], v[80:95]
	v_mfma_f32_32x32x16_bf16 v[16:31], v[234:237], v[222:225], v[16:31]
	ds_read_b128 v[234:237], v205
	v_mfma_f32_32x32x16_bf16 v[64:79], v[238:241], v[218:221], v[64:79]
	v_mfma_f32_32x32x16_bf16 v[0:15], v[238:241], v[222:225], v[0:15]
	ds_read_b128 v[238:241], v205 offset:4608
	s_setprio 0
	global_load_dwordx4 v[218:221], v[190:191], off offset:2176
	global_load_dwordx4 v[222:225], v[188:189], off offset:2176
	s_setprio 1
	s_waitcnt lgkmcnt(1)
	v_mfma_f32_32x32x16_bf16 v[112:127], v[234:237], v[226:229], v[112:127]
	v_mfma_f32_32x32x16_bf16 v[48:63], v[234:237], v[230:233], v[48:63]
	s_waitcnt lgkmcnt(0)
	v_mfma_f32_32x32x16_bf16 v[96:111], v[238:241], v[226:229], v[96:111]
	v_mfma_f32_32x32x16_bf16 v[32:47], v[238:241], v[230:233], v[32:47]
	ds_read_b128 v[234:237], v205 offset:9216
	ds_read_b128 v[238:241], v205 offset:13824
	s_waitcnt vmcnt(7)
	ds_write_b128 v215, v[176:179] offset:9216
	s_waitcnt vmcnt(6)
	ds_write_b128 v215, v[180:183] offset:46080
	ds_read_b128 v[176:179], v208 offset:32
	ds_read_b128 v[180:183], v208 offset:4640
	s_waitcnt lgkmcnt(5)
	v_mfma_f32_32x32x16_bf16 v[80:95], v[234:237], v[226:229], v[80:95]
	v_mfma_f32_32x32x16_bf16 v[16:31], v[234:237], v[230:233], v[16:31]
	ds_read_b128 v[234:237], v205 offset:32
	s_waitcnt lgkmcnt(5)
	v_mfma_f32_32x32x16_bf16 v[64:79], v[238:241], v[226:229], v[64:79]
	v_mfma_f32_32x32x16_bf16 v[0:15], v[238:241], v[230:233], v[0:15]
	ds_read_b128 v[238:241], v205 offset:4640
	s_setprio 0
	global_load_dwordx4 v[226:229], v[194:195], off offset:2176
	global_load_dwordx4 v[230:233], v[196:197], off offset:2176
	s_setprio 1
	s_waitcnt lgkmcnt(1)
	v_mfma_f32_32x32x16_bf16 v[112:127], v[234:237], v[176:179], v[112:127]
	v_mfma_f32_32x32x16_bf16 v[48:63], v[234:237], v[180:183], v[48:63]
	s_waitcnt lgkmcnt(0)
	v_mfma_f32_32x32x16_bf16 v[96:111], v[238:241], v[176:179], v[96:111]
	v_mfma_f32_32x32x16_bf16 v[32:47], v[238:241], v[180:183], v[32:47]
	ds_read_b128 v[234:237], v205 offset:9248
	ds_read_b128 v[238:241], v205 offset:13856
	s_waitcnt vmcnt(7)
	ds_write_b128 v215, v[168:171] offset:18432
	s_waitcnt vmcnt(6)
	ds_write_b128 v215, v[172:175] offset:55296
	ds_read_b128 v[168:171], v208 offset:64
	ds_read_b128 v[172:175], v208 offset:4672
	s_waitcnt lgkmcnt(5)
	v_mfma_f32_32x32x16_bf16 v[80:95], v[234:237], v[176:179], v[80:95]
	v_mfma_f32_32x32x16_bf16 v[16:31], v[234:237], v[180:183], v[16:31]
	ds_read_b128 v[234:237], v205 offset:64
	s_waitcnt lgkmcnt(5)
	v_mfma_f32_32x32x16_bf16 v[64:79], v[238:241], v[176:179], v[64:79]
	v_mfma_f32_32x32x16_bf16 v[0:15], v[238:241], v[180:183], v[0:15]
	ds_read_b128 v[238:241], v205 offset:4672
	s_setprio 0
	global_load_dwordx4 v[176:179], v[184:185], off offset:2176
	global_load_dwordx4 v[180:183], v[186:187], off offset:2176
	s_setprio 1
	s_waitcnt lgkmcnt(1)
	v_mfma_f32_32x32x16_bf16 v[112:127], v[234:237], v[168:171], v[112:127]
	v_mfma_f32_32x32x16_bf16 v[48:63], v[234:237], v[172:175], v[48:63]
	s_waitcnt lgkmcnt(0)
	v_mfma_f32_32x32x16_bf16 v[96:111], v[238:241], v[168:171], v[96:111]
	v_mfma_f32_32x32x16_bf16 v[32:47], v[238:241], v[172:175], v[32:47]
	ds_read_b128 v[234:237], v205 offset:9280
	ds_read_b128 v[238:241], v205 offset:13888
	s_waitcnt vmcnt(7)
	ds_write_b128 v215, v[160:163] offset:27648
	s_waitcnt vmcnt(6)
	ds_write_b128 v215, v[164:167] offset:64512
	ds_read_b128 v[160:163], v208 offset:96
	ds_read_b128 v[164:167], v208 offset:4704
	s_waitcnt lgkmcnt(5)
	v_mfma_f32_32x32x16_bf16 v[80:95], v[234:237], v[168:171], v[80:95]
	v_mfma_f32_32x32x16_bf16 v[16:31], v[234:237], v[172:175], v[16:31]
	ds_read_b128 v[234:237], v205 offset:96
	s_waitcnt lgkmcnt(5)
	v_mfma_f32_32x32x16_bf16 v[64:79], v[238:241], v[168:171], v[64:79]
	v_mfma_f32_32x32x16_bf16 v[0:15], v[238:241], v[172:175], v[0:15]
	ds_read_b128 v[238:241], v205 offset:4704
	s_setprio 0
	global_load_dwordx4 v[168:171], v[198:199], off offset:2176
	global_load_dwordx4 v[172:175], v[200:201], off offset:2176
	s_setprio 1
	s_waitcnt lgkmcnt(1)
	v_mfma_f32_32x32x16_bf16 v[112:127], v[234:237], v[160:163], v[112:127]
	v_mfma_f32_32x32x16_bf16 v[48:63], v[234:237], v[164:167], v[48:63]
	s_waitcnt lgkmcnt(0)
	v_mfma_f32_32x32x16_bf16 v[96:111], v[238:241], v[160:163], v[96:111]
	v_mfma_f32_32x32x16_bf16 v[32:47], v[238:241], v[164:167], v[32:47]
	ds_read_b128 v[234:237], v205 offset:9312
	ds_read_b128 v[238:241], v205 offset:13920
	s_waitcnt lgkmcnt(0)
	s_barrier
; template <bool trans>
; DI void gemm_core(const GTile& tl, const GTile& nx, bool has_next  , bool chain  , bool pre, u32x4 (&ra)[4], u32x4 (&rb)[4], char* smem, f32x16 (&acc)[2][4]) {
;     ...
;   const int nk = K / 64;
;   if (!pre) { G_LOAD(0); G_STORE(0); G_LOAD(1); }
;   for (int kt = 0; kt < nk; ++kt) {
;     __syncthreads();
;     G_COMPUTE(kt & 1, kt);
	s_waitcnt vmcnt(7)
	ds_write_b128 v209, v[218:221]
	s_waitcnt vmcnt(6)
	ds_write_b128 v210, v[222:225]
	ds_read_b128 v[218:221], v204 offset:36864
	ds_read_b128 v[222:225], v204 offset:41472
	v_mfma_f32_32x32x16_bf16 v[80:95], v[234:237], v[160:163], v[80:95]
	v_mfma_f32_32x32x16_bf16 v[16:31], v[234:237], v[164:167], v[16:31]
	ds_read_b128 v[234:237], v192
	v_mfma_f32_32x32x16_bf16 v[64:79], v[238:241], v[160:163], v[64:79]
	v_mfma_f32_32x32x16_bf16 v[0:15], v[238:241], v[164:167], v[0:15]
	ds_read_b128 v[238:241], v192 offset:4608
	s_setprio 0
	global_load_dwordx4 v[160:163], v[190:191], off offset:2304
	global_load_dwordx4 v[164:167], v[188:189], off offset:2304
	s_setprio 1
	s_waitcnt lgkmcnt(1)
	v_mfma_f32_32x32x16_bf16 v[112:127], v[234:237], v[218:221], v[112:127]
	v_mfma_f32_32x32x16_bf16 v[48:63], v[234:237], v[222:225], v[48:63]
	s_waitcnt lgkmcnt(0)
	v_mfma_f32_32x32x16_bf16 v[96:111], v[238:241], v[218:221], v[96:111]
	v_mfma_f32_32x32x16_bf16 v[32:47], v[238:241], v[222:225], v[32:47]
	ds_read_b128 v[234:237], v192 offset:9216
	ds_read_b128 v[238:241], v192 offset:13824
	s_waitcnt vmcnt(7)
	ds_write_b128 v212, v[226:229]
	s_waitcnt vmcnt(6)
	ds_write_b128 v211, v[230:233]
	ds_read_b128 v[226:229], v204 offset:36896
	ds_read_b128 v[230:233], v204 offset:41504
	s_waitcnt lgkmcnt(5)
	v_mfma_f32_32x32x16_bf16 v[80:95], v[234:237], v[218:221], v[80:95]
	v_mfma_f32_32x32x16_bf16 v[16:31], v[234:237], v[222:225], v[16:31]
	ds_read_b128 v[234:237], v192 offset:32
	s_waitcnt lgkmcnt(5)
	v_mfma_f32_32x32x16_bf16 v[64:79], v[238:241], v[218:221], v[64:79]
	v_mfma_f32_32x32x16_bf16 v[0:15], v[238:241], v[222:225], v[0:15]
	ds_read_b128 v[238:241], v192 offset:4640
	s_setprio 0
	global_load_dwordx4 v[218:221], v[194:195], off offset:2304
	global_load_dwordx4 v[222:225], v[196:197], off offset:2304
	s_setprio 1
	s_waitcnt lgkmcnt(1)
	v_mfma_f32_32x32x16_bf16 v[112:127], v[234:237], v[226:229], v[112:127]
	v_mfma_f32_32x32x16_bf16 v[48:63], v[234:237], v[230:233], v[48:63]
	s_waitcnt lgkmcnt(0)
	v_mfma_f32_32x32x16_bf16 v[96:111], v[238:241], v[226:229], v[96:111]
	v_mfma_f32_32x32x16_bf16 v[32:47], v[238:241], v[230:233], v[32:47]
	ds_read_b128 v[234:237], v192 offset:9248
	ds_read_b128 v[238:241], v192 offset:13856
	s_waitcnt vmcnt(7)
	ds_write_b128 v214, v[176:179]
	s_waitcnt vmcnt(6)
	ds_write_b128 v213, v[180:183]
	ds_read_b128 v[176:179], v204 offset:36928
	ds_read_b128 v[180:183], v204 offset:41536
	s_waitcnt lgkmcnt(5)
	v_mfma_f32_32x32x16_bf16 v[80:95], v[234:237], v[226:229], v[80:95]
	v_mfma_f32_32x32x16_bf16 v[16:31], v[234:237], v[230:233], v[16:31]
	ds_read_b128 v[234:237], v192 offset:64
	s_waitcnt lgkmcnt(5)
	v_mfma_f32_32x32x16_bf16 v[64:79], v[238:241], v[226:229], v[64:79]
	v_mfma_f32_32x32x16_bf16 v[0:15], v[238:241], v[230:233], v[0:15]
	ds_read_b128 v[238:241], v192 offset:4672
	s_setprio 0
	global_load_dwordx4 v[226:229], v[184:185], off offset:2304
	global_load_dwordx4 v[230:233], v[186:187], off offset:2304
	s_setprio 1
	s_waitcnt lgkmcnt(1)
	v_mfma_f32_32x32x16_bf16 v[112:127], v[234:237], v[176:179], v[112:127]
	v_mfma_f32_32x32x16_bf16 v[48:63], v[234:237], v[180:183], v[48:63]
	s_waitcnt lgkmcnt(0)
	v_mfma_f32_32x32x16_bf16 v[96:111], v[238:241], v[176:179], v[96:111]
	v_mfma_f32_32x32x16_bf16 v[32:47], v[238:241], v[180:183], v[32:47]
	ds_read_b128 v[234:237], v192 offset:9280
	ds_read_b128 v[238:241], v192 offset:13888
	s_waitcnt vmcnt(7)
	ds_write_b128 v217, v[168:171]
	s_waitcnt vmcnt(6)
	ds_write_b128 v216, v[172:175]
	ds_read_b128 v[168:171], v204 offset:36960
	ds_read_b128 v[172:175], v204 offset:41568
	s_waitcnt lgkmcnt(5)
	v_mfma_f32_32x32x16_bf16 v[80:95], v[234:237], v[176:179], v[80:95]
	v_mfma_f32_32x32x16_bf16 v[16:31], v[234:237], v[180:183], v[16:31]
	ds_read_b128 v[234:237], v192 offset:96
	s_waitcnt lgkmcnt(5)
	v_mfma_f32_32x32x16_bf16 v[64:79], v[238:241], v[176:179], v[64:79]
	v_mfma_f32_32x32x16_bf16 v[0:15], v[238:241], v[180:183], v[0:15]
	ds_read_b128 v[238:241], v192 offset:4704
	s_setprio 0
	global_load_dwordx4 v[176:179], v[198:199], off offset:2304
	global_load_dwordx4 v[180:183], v[200:201], off offset:2304
	s_setprio 1
	s_waitcnt lgkmcnt(1)
	v_mfma_f32_32x32x16_bf16 v[112:127], v[234:237], v[168:171], v[112:127]
	v_mfma_f32_32x32x16_bf16 v[48:63], v[234:237], v[172:175], v[48:63]
	s_waitcnt lgkmcnt(0)
	v_mfma_f32_32x32x16_bf16 v[96:111], v[238:241], v[168:171], v[96:111]
	v_mfma_f32_32x32x16_bf16 v[32:47], v[238:241], v[172:175], v[32:47]
	ds_read_b128 v[234:237], v192 offset:9312
	ds_read_b128 v[238:241], v192 offset:13920
	s_waitcnt lgkmcnt(0)
	s_barrier
; template <bool trans>
; DI void gemm_core(const GTile& tl, const GTile& nx, bool has_next  , bool chain  , bool pre, u32x4 (&ra)[4], u32x4 (&rb)[4], char* smem, f32x16 (&acc)[2][4]) {
;     ...
;   const int nk = K / 64;
;   if (!pre) { G_LOAD(0); G_STORE(0); G_LOAD(1); }
;   for (int kt = 0; kt < nk; ++kt) {
;     __syncthreads();
;     G_COMPUTE(kt & 1, kt);
	s_waitcnt vmcnt(7)
	ds_write_b128 v215, v[160:163]
	s_waitcnt vmcnt(6)
	ds_write_b128 v215, v[164:167] offset:36864
	ds_read_b128 v[160:163], v208
	ds_read_b128 v[164:167], v208 offset:4608
	v_mfma_f32_32x32x16_bf16 v[80:95], v[234:237], v[168:171], v[80:95]
	v_mfma_f32_32x32x16_bf16 v[16:31], v[234:237], v[172:175], v[16:31]
	ds_read_b128 v[234:237], v205
	v_mfma_f32_32x32x16_bf16 v[64:79], v[238:241], v[168:171], v[64:79]
	v_mfma_f32_32x32x16_bf16 v[0:15], v[238:241], v[172:175], v[0:15]
	ds_read_b128 v[238:241], v205 offset:4608
	s_setprio 0
	global_load_dwordx4 v[168:171], v[190:191], off offset:2432
	global_load_dwordx4 v[172:175], v[188:189], off offset:2432
	s_setprio 1
	s_waitcnt lgkmcnt(1)
	v_mfma_f32_32x32x16_bf16 v[112:127], v[234:237], v[160:163], v[112:127]
	v_mfma_f32_32x32x16_bf16 v[48:63], v[234:237], v[164:167], v[48:63]
	s_waitcnt lgkmcnt(0)
	v_mfma_f32_32x32x16_bf16 v[96:111], v[238:241], v[160:163], v[96:111]
	v_mfma_f32_32x32x16_bf16 v[32:47], v[238:241], v[164:167], v[32:47]
	ds_read_b128 v[234:237], v205 offset:9216
	ds_read_b128 v[238:241], v205 offset:13824
	s_waitcnt vmcnt(7)
	ds_write_b128 v215, v[218:221] offset:9216
	s_waitcnt vmcnt(6)
	ds_write_b128 v215, v[222:225] offset:46080
	ds_read_b128 v[218:221], v208 offset:32
	ds_read_b128 v[222:225], v208 offset:4640
	s_waitcnt lgkmcnt(5)
	v_mfma_f32_32x32x16_bf16 v[80:95], v[234:237], v[160:163], v[80:95]
	v_mfma_f32_32x32x16_bf16 v[16:31], v[234:237], v[164:167], v[16:31]
	ds_read_b128 v[234:237], v205 offset:32
	s_waitcnt lgkmcnt(5)
	v_mfma_f32_32x32x16_bf16 v[64:79], v[238:241], v[160:163], v[64:79]
	v_mfma_f32_32x32x16_bf16 v[0:15], v[238:241], v[164:167], v[0:15]
	ds_read_b128 v[238:241], v205 offset:4640
	s_setprio 0
	global_load_dwordx4 v[160:163], v[194:195], off offset:2432
	global_load_dwordx4 v[164:167], v[196:197], off offset:2432
	s_setprio 1
	s_waitcnt lgkmcnt(1)
	v_mfma_f32_32x32x16_bf16 v[112:127], v[234:237], v[218:221], v[112:127]
	v_mfma_f32_32x32x16_bf16 v[48:63], v[234:237], v[222:225], v[48:63]
	s_waitcnt lgkmcnt(0)
	v_mfma_f32_32x32x16_bf16 v[96:111], v[238:241], v[218:221], v[96:111]
	v_mfma_f32_32x32x16_bf16 v[32:47], v[238:241], v[222:225], v[32:47]
	ds_read_b128 v[234:237], v205 offset:9248
	ds_read_b128 v[238:241], v205 offset:13856
	s_waitcnt vmcnt(7)
	ds_write_b128 v215, v[226:229] offset:18432
	s_waitcnt vmcnt(6)
	ds_write_b128 v215, v[230:233] offset:55296
	ds_read_b128 v[226:229], v208 offset:64
	ds_read_b128 v[230:233], v208 offset:4672
	s_waitcnt lgkmcnt(5)
	v_mfma_f32_32x32x16_bf16 v[80:95], v[234:237], v[218:221], v[80:95]
	v_mfma_f32_32x32x16_bf16 v[16:31], v[234:237], v[222:225], v[16:31]
	ds_read_b128 v[234:237], v205 offset:64
	s_waitcnt lgkmcnt(5)
	v_mfma_f32_32x32x16_bf16 v[64:79], v[238:241], v[218:221], v[64:79]
	v_mfma_f32_32x32x16_bf16 v[0:15], v[238:241], v[222:225], v[0:15]
	ds_read_b128 v[238:241], v205 offset:4672
	s_setprio 0
	global_load_dwordx4 v[218:221], v[184:185], off offset:2432
	global_load_dwordx4 v[222:225], v[186:187], off offset:2432
	s_setprio 1
	s_waitcnt lgkmcnt(1)
	v_mfma_f32_32x32x16_bf16 v[112:127], v[234:237], v[226:229], v[112:127]
	v_mfma_f32_32x32x16_bf16 v[48:63], v[234:237], v[230:233], v[48:63]
	s_waitcnt lgkmcnt(0)
	v_mfma_f32_32x32x16_bf16 v[96:111], v[238:241], v[226:229], v[96:111]
	v_mfma_f32_32x32x16_bf16 v[32:47], v[238:241], v[230:233], v[32:47]
	ds_read_b128 v[234:237], v205 offset:9280
	ds_read_b128 v[238:241], v205 offset:13888
	s_waitcnt vmcnt(7)
	ds_write_b128 v215, v[176:179] offset:27648
	s_waitcnt vmcnt(6)
	ds_write_b128 v215, v[180:183] offset:64512
	ds_read_b128 v[176:179], v208 offset:96
	ds_read_b128 v[180:183], v208 offset:4704
	s_waitcnt lgkmcnt(5)
	v_mfma_f32_32x32x16_bf16 v[80:95], v[234:237], v[226:229], v[80:95]
	v_mfma_f32_32x32x16_bf16 v[16:31], v[234:237], v[230:233], v[16:31]
	ds_read_b128 v[234:237], v205 offset:96
	s_waitcnt lgkmcnt(5)
	v_mfma_f32_32x32x16_bf16 v[64:79], v[238:241], v[226:229], v[64:79]
	v_mfma_f32_32x32x16_bf16 v[0:15], v[238:241], v[230:233], v[0:15]
	ds_read_b128 v[238:241], v205 offset:4704
	s_setprio 0
	global_load_dwordx4 v[226:229], v[198:199], off offset:2432
	global_load_dwordx4 v[230:233], v[200:201], off offset:2432
	s_setprio 1
	s_waitcnt lgkmcnt(1)
	v_mfma_f32_32x32x16_bf16 v[112:127], v[234:237], v[176:179], v[112:127]
	v_mfma_f32_32x32x16_bf16 v[48:63], v[234:237], v[180:183], v[48:63]
	s_waitcnt lgkmcnt(0)
	v_mfma_f32_32x32x16_bf16 v[96:111], v[238:241], v[176:179], v[96:111]
	v_mfma_f32_32x32x16_bf16 v[32:47], v[238:241], v[180:183], v[32:47]
	ds_read_b128 v[234:237], v205 offset:9312
	ds_read_b128 v[238:241], v205 offset:13920
	s_waitcnt lgkmcnt(0)
	s_barrier
; template <bool trans>
; DI void gemm_core(const GTile& tl, const GTile& nx, bool has_next  , bool chain  , bool pre, u32x4 (&ra)[4], u32x4 (&rb)[4], char* smem, f32x16 (&acc)[2][4]) {
;     ...
;   const int nk = K / 64;
;   if (!pre) { G_LOAD(0); G_STORE(0); G_LOAD(1); }
;   for (int kt = 0; kt < nk; ++kt) {
;     __syncthreads();
;     G_COMPUTE(kt & 1, kt);
;   }
	s_waitcnt vmcnt(7)
	ds_write_b128 v209, v[168:171]
	s_waitcnt vmcnt(6)
	ds_write_b128 v210, v[172:175]
	ds_read_b128 v[168:171], v204 offset:36864
	ds_read_b128 v[172:175], v204 offset:41472
	v_mfma_f32_32x32x16_bf16 v[80:95], v[234:237], v[176:179], v[80:95]
	v_mfma_f32_32x32x16_bf16 v[16:31], v[234:237], v[180:183], v[16:31]
	ds_read_b128 v[234:237], v192
	v_mfma_f32_32x32x16_bf16 v[64:79], v[238:241], v[176:179], v[64:79]
	v_mfma_f32_32x32x16_bf16 v[0:15], v[238:241], v[180:183], v[0:15]
	ds_read_b128 v[238:241], v192 offset:4608
	s_setprio 0
	global_load_dwordx4 v[176:179], v[190:191], off offset:2560
	global_load_dwordx4 v[180:183], v[188:189], off offset:2560
	s_setprio 1
	s_waitcnt lgkmcnt(1)
	v_mfma_f32_32x32x16_bf16 v[112:127], v[234:237], v[168:171], v[112:127]
	v_mfma_f32_32x32x16_bf16 v[48:63], v[234:237], v[172:175], v[48:63]
	s_waitcnt lgkmcnt(0)
	v_mfma_f32_32x32x16_bf16 v[96:111], v[238:241], v[168:171], v[96:111]
	v_mfma_f32_32x32x16_bf16 v[32:47], v[238:241], v[172:175], v[32:47]
	ds_read_b128 v[234:237], v192 offset:9216
	ds_read_b128 v[238:241], v192 offset:13824
	s_waitcnt vmcnt(7)
	ds_write_b128 v212, v[160:163]
	s_waitcnt vmcnt(6)
	ds_write_b128 v211, v[164:167]
	ds_read_b128 v[160:163], v204 offset:36896
	ds_read_b128 v[164:167], v204 offset:41504
	s_waitcnt lgkmcnt(5)
	v_mfma_f32_32x32x16_bf16 v[80:95], v[234:237], v[168:171], v[80:95]
	v_mfma_f32_32x32x16_bf16 v[16:31], v[234:237], v[172:175], v[16:31]
	ds_read_b128 v[234:237], v192 offset:32
	s_waitcnt lgkmcnt(5)
	v_mfma_f32_32x32x16_bf16 v[64:79], v[238:241], v[168:171], v[64:79]
	v_mfma_f32_32x32x16_bf16 v[0:15], v[238:241], v[172:175], v[0:15]
	ds_read_b128 v[238:241], v192 offset:4640
	s_setprio 0
	global_load_dwordx4 v[168:171], v[194:195], off offset:2560
	global_load_dwordx4 v[172:175], v[196:197], off offset:2560
	s_setprio 1
	s_waitcnt lgkmcnt(1)
	v_mfma_f32_32x32x16_bf16 v[112:127], v[234:237], v[160:163], v[112:127]
	v_mfma_f32_32x32x16_bf16 v[48:63], v[234:237], v[164:167], v[48:63]
	s_waitcnt lgkmcnt(0)
	v_mfma_f32_32x32x16_bf16 v[96:111], v[238:241], v[160:163], v[96:111]
	v_mfma_f32_32x32x16_bf16 v[32:47], v[238:241], v[164:167], v[32:47]
	ds_read_b128 v[234:237], v192 offset:9248
	ds_read_b128 v[238:241], v192 offset:13856
	s_waitcnt vmcnt(7)
	ds_write_b128 v214, v[218:221]
	s_waitcnt vmcnt(6)
	ds_write_b128 v213, v[222:225]
	ds_read_b128 v[218:221], v204 offset:36928
	ds_read_b128 v[222:225], v204 offset:41536
	s_waitcnt lgkmcnt(5)
	v_mfma_f32_32x32x16_bf16 v[80:95], v[234:237], v[160:163], v[80:95]
	v_mfma_f32_32x32x16_bf16 v[16:31], v[234:237], v[164:167], v[16:31]
	ds_read_b128 v[234:237], v192 offset:64
	s_waitcnt lgkmcnt(5)
	v_mfma_f32_32x32x16_bf16 v[64:79], v[238:241], v[160:163], v[64:79]
	v_mfma_f32_32x32x16_bf16 v[0:15], v[238:241], v[164:167], v[0:15]
	ds_read_b128 v[238:241], v192 offset:4672
	s_setprio 0
	global_load_dwordx4 v[160:163], v[184:185], off offset:2560
	global_load_dwordx4 v[164:167], v[186:187], off offset:2560
	s_setprio 1
	s_waitcnt lgkmcnt(1)
	v_mfma_f32_32x32x16_bf16 v[112:127], v[234:237], v[218:221], v[112:127]
	v_mfma_f32_32x32x16_bf16 v[48:63], v[234:237], v[222:225], v[48:63]
	s_waitcnt lgkmcnt(0)
	v_mfma_f32_32x32x16_bf16 v[96:111], v[238:241], v[218:221], v[96:111]
	v_mfma_f32_32x32x16_bf16 v[32:47], v[238:241], v[222:225], v[32:47]
	ds_read_b128 v[234:237], v192 offset:9280
	ds_read_b128 v[238:241], v192 offset:13888
	s_waitcnt vmcnt(7)
	ds_write_b128 v217, v[226:229]
	s_waitcnt vmcnt(6)
	ds_write_b128 v216, v[230:233]
	ds_read_b128 v[226:229], v204 offset:36960
	ds_read_b128 v[230:233], v204 offset:41568
	s_waitcnt lgkmcnt(5)
	v_mfma_f32_32x32x16_bf16 v[80:95], v[234:237], v[218:221], v[80:95]
	v_mfma_f32_32x32x16_bf16 v[16:31], v[234:237], v[222:225], v[16:31]
	ds_read_b128 v[234:237], v192 offset:96
	s_waitcnt lgkmcnt(5)
	v_mfma_f32_32x32x16_bf16 v[64:79], v[238:241], v[218:221], v[64:79]
	v_mfma_f32_32x32x16_bf16 v[0:15], v[238:241], v[222:225], v[0:15]
	ds_read_b128 v[238:241], v192 offset:4704
	s_setprio 0
	global_load_dwordx4 v[218:221], v[198:199], off offset:2560
	global_load_dwordx4 v[222:225], v[200:201], off offset:2560
	s_setprio 1
	s_waitcnt lgkmcnt(1)
	v_mfma_f32_32x32x16_bf16 v[112:127], v[234:237], v[226:229], v[112:127]
	v_mfma_f32_32x32x16_bf16 v[48:63], v[234:237], v[230:233], v[48:63]
	s_waitcnt lgkmcnt(0)
	v_mfma_f32_32x32x16_bf16 v[96:111], v[238:241], v[226:229], v[96:111]
	v_mfma_f32_32x32x16_bf16 v[32:47], v[238:241], v[230:233], v[32:47]
	ds_read_b128 v[234:237], v192 offset:9312
	ds_read_b128 v[238:241], v192 offset:13920
	s_waitcnt lgkmcnt(0)
	s_barrier
; template <bool trans>
; DI void gemm_core(const GTile& tl, const GTile& nx, bool has_next  , bool chain  , bool pre, u32x4 (&ra)[4], u32x4 (&rb)[4], char* smem, f32x16 (&acc)[2][4]) {
;     ...
;   const int nk = K / 64;
;   if (!pre) { G_LOAD(0); G_STORE(0); G_LOAD(1); }
;   for (int kt = 0; kt < nk; ++kt) {
;     __syncthreads();
;     G_COMPUTE(kt & 1, kt);
;   }
	s_waitcnt vmcnt(7)
	ds_write_b128 v215, v[176:179]
	s_waitcnt vmcnt(6)
	ds_write_b128 v215, v[180:183] offset:36864
	ds_read_b128 v[176:179], v208
	ds_read_b128 v[180:183], v208 offset:4608
	v_mfma_f32_32x32x16_bf16 v[80:95], v[234:237], v[226:229], v[80:95]
	v_mfma_f32_32x32x16_bf16 v[16:31], v[234:237], v[230:233], v[16:31]
	ds_read_b128 v[234:237], v205
	v_mfma_f32_32x32x16_bf16 v[64:79], v[238:241], v[226:229], v[64:79]
	v_mfma_f32_32x32x16_bf16 v[0:15], v[238:241], v[230:233], v[0:15]
	ds_read_b128 v[238:241], v205 offset:4608
	s_setprio 0
	global_load_dwordx4 v[226:229], v[190:191], off offset:2688
	global_load_dwordx4 v[230:233], v[188:189], off offset:2688
	s_setprio 1
	s_waitcnt lgkmcnt(1)
	v_mfma_f32_32x32x16_bf16 v[112:127], v[234:237], v[176:179], v[112:127]
	v_mfma_f32_32x32x16_bf16 v[48:63], v[234:237], v[180:183], v[48:63]
	s_waitcnt lgkmcnt(0)
	v_mfma_f32_32x32x16_bf16 v[96:111], v[238:241], v[176:179], v[96:111]
	v_mfma_f32_32x32x16_bf16 v[32:47], v[238:241], v[180:183], v[32:47]
	ds_read_b128 v[234:237], v205 offset:9216
	ds_read_b128 v[238:241], v205 offset:13824
	s_waitcnt vmcnt(7)
	ds_write_b128 v215, v[168:171] offset:9216
	s_waitcnt vmcnt(6)
	ds_write_b128 v215, v[172:175] offset:46080
	ds_read_b128 v[168:171], v208 offset:32
	ds_read_b128 v[172:175], v208 offset:4640
	s_waitcnt lgkmcnt(5)
	v_mfma_f32_32x32x16_bf16 v[80:95], v[234:237], v[176:179], v[80:95]
	v_mfma_f32_32x32x16_bf16 v[16:31], v[234:237], v[180:183], v[16:31]
	ds_read_b128 v[234:237], v205 offset:32
	s_waitcnt lgkmcnt(5)
	v_mfma_f32_32x32x16_bf16 v[64:79], v[238:241], v[176:179], v[64:79]
	v_mfma_f32_32x32x16_bf16 v[0:15], v[238:241], v[180:183], v[0:15]
	ds_read_b128 v[238:241], v205 offset:4640
	s_setprio 0
	global_load_dwordx4 v[176:179], v[194:195], off offset:2688
	global_load_dwordx4 v[180:183], v[196:197], off offset:2688
	s_setprio 1
	s_waitcnt lgkmcnt(1)
	v_mfma_f32_32x32x16_bf16 v[112:127], v[234:237], v[168:171], v[112:127]
	v_mfma_f32_32x32x16_bf16 v[48:63], v[234:237], v[172:175], v[48:63]
	s_waitcnt lgkmcnt(0)
	v_mfma_f32_32x32x16_bf16 v[96:111], v[238:241], v[168:171], v[96:111]
	v_mfma_f32_32x32x16_bf16 v[32:47], v[238:241], v[172:175], v[32:47]
	ds_read_b128 v[234:237], v205 offset:9248
	ds_read_b128 v[238:241], v205 offset:13856
	s_waitcnt vmcnt(7)
	ds_write_b128 v215, v[160:163] offset:18432
	s_waitcnt vmcnt(6)
	ds_write_b128 v215, v[164:167] offset:55296
	ds_read_b128 v[160:163], v208 offset:64
	ds_read_b128 v[164:167], v208 offset:4672
	s_waitcnt lgkmcnt(5)
	v_mfma_f32_32x32x16_bf16 v[80:95], v[234:237], v[168:171], v[80:95]
	v_mfma_f32_32x32x16_bf16 v[16:31], v[234:237], v[172:175], v[16:31]
	ds_read_b128 v[234:237], v205 offset:64
	s_waitcnt lgkmcnt(5)
	v_mfma_f32_32x32x16_bf16 v[64:79], v[238:241], v[168:171], v[64:79]
	v_mfma_f32_32x32x16_bf16 v[0:15], v[238:241], v[172:175], v[0:15]
	ds_read_b128 v[238:241], v205 offset:4672
	s_setprio 0
	global_load_dwordx4 v[168:171], v[184:185], off offset:2688
	global_load_dwordx4 v[172:175], v[186:187], off offset:2688
	s_setprio 1
	s_waitcnt lgkmcnt(1)
	v_mfma_f32_32x32x16_bf16 v[112:127], v[234:237], v[160:163], v[112:127]
	v_mfma_f32_32x32x16_bf16 v[48:63], v[234:237], v[164:167], v[48:63]
	s_waitcnt lgkmcnt(0)
	v_mfma_f32_32x32x16_bf16 v[96:111], v[238:241], v[160:163], v[96:111]
	v_mfma_f32_32x32x16_bf16 v[32:47], v[238:241], v[164:167], v[32:47]
	ds_read_b128 v[234:237], v205 offset:9280
	ds_read_b128 v[238:241], v205 offset:13888
	s_waitcnt vmcnt(7)
	ds_write_b128 v215, v[218:221] offset:27648
	s_waitcnt vmcnt(6)
	ds_write_b128 v215, v[222:225] offset:64512
	ds_read_b128 v[218:221], v208 offset:96
	ds_read_b128 v[222:225], v208 offset:4704
	s_waitcnt lgkmcnt(5)
	v_mfma_f32_32x32x16_bf16 v[80:95], v[234:237], v[160:163], v[80:95]
	v_mfma_f32_32x32x16_bf16 v[16:31], v[234:237], v[164:167], v[16:31]
	ds_read_b128 v[234:237], v205 offset:96
	s_waitcnt lgkmcnt(5)
	v_mfma_f32_32x32x16_bf16 v[64:79], v[238:241], v[160:163], v[64:79]
	v_mfma_f32_32x32x16_bf16 v[0:15], v[238:241], v[164:167], v[0:15]
	ds_read_b128 v[238:241], v205 offset:4704
	s_setprio 0
	global_load_dwordx4 v[160:163], v[198:199], off offset:2688
	global_load_dwordx4 v[164:167], v[200:201], off offset:2688
	s_setprio 1
	s_waitcnt lgkmcnt(1)
	v_mfma_f32_32x32x16_bf16 v[112:127], v[234:237], v[218:221], v[112:127]
	v_mfma_f32_32x32x16_bf16 v[48:63], v[234:237], v[222:225], v[48:63]
	s_waitcnt lgkmcnt(0)
	v_mfma_f32_32x32x16_bf16 v[96:111], v[238:241], v[218:221], v[96:111]
	v_mfma_f32_32x32x16_bf16 v[32:47], v[238:241], v[222:225], v[32:47]
	ds_read_b128 v[234:237], v205 offset:9312
	ds_read_b128 v[238:241], v205 offset:13920
	s_waitcnt lgkmcnt(0)
	s_barrier
; template <bool trans>
; DI void gemm_core(const GTile& tl, const GTile& nx, bool has_next  , bool chain  , bool pre, u32x4 (&ra)[4], u32x4 (&rb)[4], char* smem, f32x16 (&acc)[2][4]) {
;     ...
;   const int nk = K / 64;
;   if (!pre) { G_LOAD(0); G_STORE(0); G_LOAD(1); }
;   for (int kt = 0; kt < nk; ++kt) {
;     __syncthreads();
;     G_COMPUTE(kt & 1, kt);
;   }
	s_waitcnt vmcnt(7)
	ds_write_b128 v209, v[226:229]
	s_waitcnt vmcnt(6)
	ds_write_b128 v210, v[230:233]
	ds_read_b128 v[226:229], v204 offset:36864
	ds_read_b128 v[230:233], v204 offset:41472
	v_mfma_f32_32x32x16_bf16 v[80:95], v[234:237], v[218:221], v[80:95]
	v_mfma_f32_32x32x16_bf16 v[16:31], v[234:237], v[222:225], v[16:31]
	ds_read_b128 v[234:237], v192
	v_mfma_f32_32x32x16_bf16 v[64:79], v[238:241], v[218:221], v[64:79]
	v_mfma_f32_32x32x16_bf16 v[0:15], v[238:241], v[222:225], v[0:15]
	ds_read_b128 v[238:241], v192 offset:4608
	s_setprio 0
	global_load_dwordx4 v[218:221], v[190:191], off offset:2816
	global_load_dwordx4 v[222:225], v[188:189], off offset:2816
	s_setprio 1
	s_waitcnt lgkmcnt(1)
	v_mfma_f32_32x32x16_bf16 v[112:127], v[234:237], v[226:229], v[112:127]
	v_mfma_f32_32x32x16_bf16 v[48:63], v[234:237], v[230:233], v[48:63]
	s_waitcnt lgkmcnt(0)
	v_mfma_f32_32x32x16_bf16 v[96:111], v[238:241], v[226:229], v[96:111]
	v_mfma_f32_32x32x16_bf16 v[32:47], v[238:241], v[230:233], v[32:47]
	ds_read_b128 v[234:237], v192 offset:9216
	ds_read_b128 v[238:241], v192 offset:13824
	s_waitcnt vmcnt(7)
	ds_write_b128 v212, v[176:179]
	s_waitcnt vmcnt(6)
	ds_write_b128 v211, v[180:183]
	ds_read_b128 v[176:179], v204 offset:36896
	ds_read_b128 v[180:183], v204 offset:41504
	s_waitcnt lgkmcnt(5)
	v_mfma_f32_32x32x16_bf16 v[80:95], v[234:237], v[226:229], v[80:95]
	v_mfma_f32_32x32x16_bf16 v[16:31], v[234:237], v[230:233], v[16:31]
	ds_read_b128 v[234:237], v192 offset:32
	s_waitcnt lgkmcnt(5)
	v_mfma_f32_32x32x16_bf16 v[64:79], v[238:241], v[226:229], v[64:79]
	v_mfma_f32_32x32x16_bf16 v[0:15], v[238:241], v[230:233], v[0:15]
	ds_read_b128 v[238:241], v192 offset:4640
	s_setprio 0
	global_load_dwordx4 v[226:229], v[194:195], off offset:2816
	global_load_dwordx4 v[230:233], v[196:197], off offset:2816
	s_setprio 1
	s_waitcnt lgkmcnt(1)
	v_mfma_f32_32x32x16_bf16 v[112:127], v[234:237], v[176:179], v[112:127]
	v_mfma_f32_32x32x16_bf16 v[48:63], v[234:237], v[180:183], v[48:63]
	s_waitcnt lgkmcnt(0)
	v_mfma_f32_32x32x16_bf16 v[96:111], v[238:241], v[176:179], v[96:111]
	v_mfma_f32_32x32x16_bf16 v[32:47], v[238:241], v[180:183], v[32:47]
	ds_read_b128 v[234:237], v192 offset:9248
	ds_read_b128 v[238:241], v192 offset:13856
	s_waitcnt vmcnt(7)
	ds_write_b128 v214, v[168:171]
	s_waitcnt vmcnt(6)
	ds_write_b128 v213, v[172:175]
	ds_read_b128 v[168:171], v204 offset:36928
	ds_read_b128 v[172:175], v204 offset:41536
	s_waitcnt lgkmcnt(5)
	v_mfma_f32_32x32x16_bf16 v[80:95], v[234:237], v[176:179], v[80:95]
	v_mfma_f32_32x32x16_bf16 v[16:31], v[234:237], v[180:183], v[16:31]
	ds_read_b128 v[234:237], v192 offset:64
	s_waitcnt lgkmcnt(5)
	v_mfma_f32_32x32x16_bf16 v[64:79], v[238:241], v[176:179], v[64:79]
	v_mfma_f32_32x32x16_bf16 v[0:15], v[238:241], v[180:183], v[0:15]
	ds_read_b128 v[238:241], v192 offset:4672
	s_setprio 0
	global_load_dwordx4 v[176:179], v[184:185], off offset:2816
	global_load_dwordx4 v[180:183], v[186:187], off offset:2816
	s_setprio 1
	s_waitcnt lgkmcnt(1)
	v_mfma_f32_32x32x16_bf16 v[112:127], v[234:237], v[168:171], v[112:127]
	v_mfma_f32_32x32x16_bf16 v[48:63], v[234:237], v[172:175], v[48:63]
	s_waitcnt lgkmcnt(0)
	v_mfma_f32_32x32x16_bf16 v[96:111], v[238:241], v[168:171], v[96:111]
	v_mfma_f32_32x32x16_bf16 v[32:47], v[238:241], v[172:175], v[32:47]
	ds_read_b128 v[234:237], v192 offset:9280
	ds_read_b128 v[238:241], v192 offset:13888
	s_waitcnt vmcnt(7)
	ds_write_b128 v217, v[160:163]
	s_waitcnt vmcnt(6)
	ds_write_b128 v216, v[164:167]
	ds_read_b128 v[160:163], v204 offset:36960
	ds_read_b128 v[164:167], v204 offset:41568
	s_waitcnt lgkmcnt(5)
	v_mfma_f32_32x32x16_bf16 v[80:95], v[234:237], v[168:171], v[80:95]
	v_mfma_f32_32x32x16_bf16 v[16:31], v[234:237], v[172:175], v[16:31]
	ds_read_b128 v[234:237], v192 offset:96
	s_waitcnt lgkmcnt(5)
	v_mfma_f32_32x32x16_bf16 v[64:79], v[238:241], v[168:171], v[64:79]
	v_mfma_f32_32x32x16_bf16 v[0:15], v[238:241], v[172:175], v[0:15]
	ds_read_b128 v[238:241], v192 offset:4704
	s_setprio 0
	global_load_dwordx4 v[168:171], v[198:199], off offset:2816
	global_load_dwordx4 v[172:175], v[200:201], off offset:2816
	s_setprio 1
	s_waitcnt lgkmcnt(1)
	v_mfma_f32_32x32x16_bf16 v[112:127], v[234:237], v[160:163], v[112:127]
	v_mfma_f32_32x32x16_bf16 v[48:63], v[234:237], v[164:167], v[48:63]
	s_waitcnt lgkmcnt(0)
	v_mfma_f32_32x32x16_bf16 v[96:111], v[238:241], v[160:163], v[96:111]
	v_mfma_f32_32x32x16_bf16 v[32:47], v[238:241], v[164:167], v[32:47]
	ds_read_b128 v[234:237], v192 offset:9312
	ds_read_b128 v[238:241], v192 offset:13920
	s_waitcnt lgkmcnt(0)
	s_barrier
; template <bool trans>
; DI void gemm_core(const GTile& tl, const GTile& nx, bool has_next  , bool chain  , bool pre, u32x4 (&ra)[4], u32x4 (&rb)[4], char* smem, f32x16 (&acc)[2][4]) {
;     ...
;   const int nk = K / 64;
;   if (!pre) { G_LOAD(0); G_STORE(0); G_LOAD(1); }
;   for (int kt = 0; kt < nk; ++kt) {
;     __syncthreads();
;     G_COMPUTE(kt & 1, kt);
;   }
	s_waitcnt vmcnt(7)
	ds_write_b128 v215, v[218:221]
	s_waitcnt vmcnt(6)
	ds_write_b128 v215, v[222:225] offset:36864
	ds_read_b128 v[218:221], v208
	ds_read_b128 v[222:225], v208 offset:4608
	v_mfma_f32_32x32x16_bf16 v[80:95], v[234:237], v[160:163], v[80:95]
	v_mfma_f32_32x32x16_bf16 v[16:31], v[234:237], v[164:167], v[16:31]
	ds_read_b128 v[234:237], v205
	v_mfma_f32_32x32x16_bf16 v[64:79], v[238:241], v[160:163], v[64:79]
	v_mfma_f32_32x32x16_bf16 v[0:15], v[238:241], v[164:167], v[0:15]
	ds_read_b128 v[238:241], v205 offset:4608
	s_setprio 0
	global_load_dwordx4 v[160:163], v[190:191], off offset:2944
	global_load_dwordx4 v[164:167], v[188:189], off offset:2944
	s_setprio 1
	s_waitcnt lgkmcnt(1)
	v_mfma_f32_32x32x16_bf16 v[112:127], v[234:237], v[218:221], v[112:127]
	v_mfma_f32_32x32x16_bf16 v[48:63], v[234:237], v[222:225], v[48:63]
	s_waitcnt lgkmcnt(0)
	v_mfma_f32_32x32x16_bf16 v[96:111], v[238:241], v[218:221], v[96:111]
	v_mfma_f32_32x32x16_bf16 v[32:47], v[238:241], v[222:225], v[32:47]
	ds_read_b128 v[234:237], v205 offset:9216
	ds_read_b128 v[238:241], v205 offset:13824
	s_waitcnt vmcnt(7)
	ds_write_b128 v215, v[226:229] offset:9216
	s_waitcnt vmcnt(6)
	ds_write_b128 v215, v[230:233] offset:46080
	ds_read_b128 v[226:229], v208 offset:32
	ds_read_b128 v[230:233], v208 offset:4640
	s_waitcnt lgkmcnt(5)
	v_mfma_f32_32x32x16_bf16 v[80:95], v[234:237], v[218:221], v[80:95]
	v_mfma_f32_32x32x16_bf16 v[16:31], v[234:237], v[222:225], v[16:31]
	ds_read_b128 v[234:237], v205 offset:32
	s_waitcnt lgkmcnt(5)
	v_mfma_f32_32x32x16_bf16 v[64:79], v[238:241], v[218:221], v[64:79]
	v_mfma_f32_32x32x16_bf16 v[0:15], v[238:241], v[222:225], v[0:15]
	ds_read_b128 v[238:241], v205 offset:4640
	s_setprio 0
	global_load_dwordx4 v[218:221], v[194:195], off offset:2944
	global_load_dwordx4 v[222:225], v[196:197], off offset:2944
	s_setprio 1
	s_waitcnt lgkmcnt(1)
	v_mfma_f32_32x32x16_bf16 v[112:127], v[234:237], v[226:229], v[112:127]
	v_mfma_f32_32x32x16_bf16 v[48:63], v[234:237], v[230:233], v[48:63]
	s_waitcnt lgkmcnt(0)
	v_mfma_f32_32x32x16_bf16 v[96:111], v[238:241], v[226:229], v[96:111]
	v_mfma_f32_32x32x16_bf16 v[32:47], v[238:241], v[230:233], v[32:47]
	ds_read_b128 v[234:237], v205 offset:9248
	ds_read_b128 v[238:241], v205 offset:13856
	s_waitcnt vmcnt(7)
	ds_write_b128 v215, v[176:179] offset:18432
	s_waitcnt vmcnt(6)
	ds_write_b128 v215, v[180:183] offset:55296
	ds_read_b128 v[176:179], v208 offset:64
	ds_read_b128 v[180:183], v208 offset:4672
	s_waitcnt lgkmcnt(5)
	v_mfma_f32_32x32x16_bf16 v[80:95], v[234:237], v[226:229], v[80:95]
	v_mfma_f32_32x32x16_bf16 v[16:31], v[234:237], v[230:233], v[16:31]
	ds_read_b128 v[234:237], v205 offset:64
	s_waitcnt lgkmcnt(5)
	v_mfma_f32_32x32x16_bf16 v[64:79], v[238:241], v[226:229], v[64:79]
	v_mfma_f32_32x32x16_bf16 v[0:15], v[238:241], v[230:233], v[0:15]
	ds_read_b128 v[238:241], v205 offset:4672
	s_setprio 0
	global_load_dwordx4 v[226:229], v[184:185], off offset:2944
	global_load_dwordx4 v[230:233], v[186:187], off offset:2944
	s_setprio 1
	s_waitcnt lgkmcnt(1)
	v_mfma_f32_32x32x16_bf16 v[112:127], v[234:237], v[176:179], v[112:127]
	v_mfma_f32_32x32x16_bf16 v[48:63], v[234:237], v[180:183], v[48:63]
	s_waitcnt lgkmcnt(0)
	v_mfma_f32_32x32x16_bf16 v[96:111], v[238:241], v[176:179], v[96:111]
	v_mfma_f32_32x32x16_bf16 v[32:47], v[238:241], v[180:183], v[32:47]
	ds_read_b128 v[234:237], v205 offset:9280
	ds_read_b128 v[238:241], v205 offset:13888
	s_waitcnt vmcnt(7)
	ds_write_b128 v215, v[168:171] offset:27648
	s_waitcnt vmcnt(6)
	ds_write_b128 v215, v[172:175] offset:64512
	ds_read_b128 v[168:171], v208 offset:96
	ds_read_b128 v[172:175], v208 offset:4704
	s_waitcnt lgkmcnt(5)
	v_mfma_f32_32x32x16_bf16 v[80:95], v[234:237], v[176:179], v[80:95]
	v_mfma_f32_32x32x16_bf16 v[16:31], v[234:237], v[180:183], v[16:31]
	ds_read_b128 v[234:237], v205 offset:96
	s_waitcnt lgkmcnt(5)
	v_mfma_f32_32x32x16_bf16 v[64:79], v[238:241], v[176:179], v[64:79]
	v_mfma_f32_32x32x16_bf16 v[0:15], v[238:241], v[180:183], v[0:15]
	ds_read_b128 v[238:241], v205 offset:4704
	s_setprio 0
	global_load_dwordx4 v[176:179], v[198:199], off offset:2944
	global_load_dwordx4 v[180:183], v[200:201], off offset:2944
	s_setprio 1
	s_waitcnt lgkmcnt(1)
	v_mfma_f32_32x32x16_bf16 v[112:127], v[234:237], v[168:171], v[112:127]
	v_mfma_f32_32x32x16_bf16 v[48:63], v[234:237], v[172:175], v[48:63]
	s_waitcnt lgkmcnt(0)
	v_mfma_f32_32x32x16_bf16 v[96:111], v[238:241], v[168:171], v[96:111]
	v_mfma_f32_32x32x16_bf16 v[32:47], v[238:241], v[172:175], v[32:47]
	ds_read_b128 v[234:237], v205 offset:9312
	ds_read_b128 v[238:241], v205 offset:13920
	s_waitcnt lgkmcnt(0)
	s_barrier
; template <bool trans>
; DI void gemm_core(const GTile& tl, const GTile& nx, bool has_next  , bool chain  , bool pre, u32x4 (&ra)[4], u32x4 (&rb)[4], char* smem, f32x16 (&acc)[2][4]) {
;     ...
;   const int nk = K / 64;
;   if (!pre) { G_LOAD(0); G_STORE(0); G_LOAD(1); }
;   for (int kt = 0; kt < nk; ++kt) {
;     __syncthreads();
;     G_COMPUTE(kt & 1, kt);
;   }
	s_waitcnt vmcnt(7)
	ds_write_b128 v209, v[160:163]
	s_waitcnt vmcnt(6)
	ds_write_b128 v210, v[164:167]
	ds_read_b128 v[160:163], v204 offset:36864
	ds_read_b128 v[164:167], v204 offset:41472
	v_mfma_f32_32x32x16_bf16 v[80:95], v[234:237], v[168:171], v[80:95]
	v_mfma_f32_32x32x16_bf16 v[16:31], v[234:237], v[172:175], v[16:31]
	ds_read_b128 v[234:237], v192
	v_mfma_f32_32x32x16_bf16 v[64:79], v[238:241], v[168:171], v[64:79]
	v_mfma_f32_32x32x16_bf16 v[0:15], v[238:241], v[172:175], v[0:15]
	ds_read_b128 v[238:241], v192 offset:4608
	s_setprio 0
	global_load_dwordx4 v[168:171], v[190:191], off offset:3072
	global_load_dwordx4 v[172:175], v[188:189], off offset:3072
	s_setprio 1
	s_waitcnt lgkmcnt(1)
	v_mfma_f32_32x32x16_bf16 v[112:127], v[234:237], v[160:163], v[112:127]
	v_mfma_f32_32x32x16_bf16 v[48:63], v[234:237], v[164:167], v[48:63]
	s_waitcnt lgkmcnt(0)
	v_mfma_f32_32x32x16_bf16 v[96:111], v[238:241], v[160:163], v[96:111]
	v_mfma_f32_32x32x16_bf16 v[32:47], v[238:241], v[164:167], v[32:47]
	ds_read_b128 v[234:237], v192 offset:9216
	ds_read_b128 v[238:241], v192 offset:13824
	s_waitcnt vmcnt(7)
	ds_write_b128 v212, v[218:221]
	s_waitcnt vmcnt(6)
	ds_write_b128 v211, v[222:225]
	ds_read_b128 v[218:221], v204 offset:36896
	ds_read_b128 v[222:225], v204 offset:41504
	s_waitcnt lgkmcnt(5)
	v_mfma_f32_32x32x16_bf16 v[80:95], v[234:237], v[160:163], v[80:95]
	v_mfma_f32_32x32x16_bf16 v[16:31], v[234:237], v[164:167], v[16:31]
	ds_read_b128 v[234:237], v192 offset:32
	s_waitcnt lgkmcnt(5)
	v_mfma_f32_32x32x16_bf16 v[64:79], v[238:241], v[160:163], v[64:79]
	v_mfma_f32_32x32x16_bf16 v[0:15], v[238:241], v[164:167], v[0:15]
	ds_read_b128 v[238:241], v192 offset:4640
	s_setprio 0
	global_load_dwordx4 v[160:163], v[194:195], off offset:3072
	global_load_dwordx4 v[164:167], v[196:197], off offset:3072
	s_setprio 1
	s_waitcnt lgkmcnt(1)
	v_mfma_f32_32x32x16_bf16 v[112:127], v[234:237], v[218:221], v[112:127]
	v_mfma_f32_32x32x16_bf16 v[48:63], v[234:237], v[222:225], v[48:63]
	s_waitcnt lgkmcnt(0)
	v_mfma_f32_32x32x16_bf16 v[96:111], v[238:241], v[218:221], v[96:111]
	v_mfma_f32_32x32x16_bf16 v[32:47], v[238:241], v[222:225], v[32:47]
	ds_read_b128 v[234:237], v192 offset:9248
	ds_read_b128 v[238:241], v192 offset:13856
	s_waitcnt vmcnt(7)
	ds_write_b128 v214, v[226:229]
	s_waitcnt vmcnt(6)
	ds_write_b128 v213, v[230:233]
	ds_read_b128 v[226:229], v204 offset:36928
	ds_read_b128 v[230:233], v204 offset:41536
	s_waitcnt lgkmcnt(5)
	v_mfma_f32_32x32x16_bf16 v[80:95], v[234:237], v[218:221], v[80:95]
	v_mfma_f32_32x32x16_bf16 v[16:31], v[234:237], v[222:225], v[16:31]
	ds_read_b128 v[234:237], v192 offset:64
	s_waitcnt lgkmcnt(5)
	v_mfma_f32_32x32x16_bf16 v[64:79], v[238:241], v[218:221], v[64:79]
	v_mfma_f32_32x32x16_bf16 v[0:15], v[238:241], v[222:225], v[0:15]
	ds_read_b128 v[238:241], v192 offset:4672
	s_setprio 0
	global_load_dwordx4 v[218:221], v[184:185], off offset:3072
	global_load_dwordx4 v[222:225], v[186:187], off offset:3072
	s_setprio 1
	s_waitcnt lgkmcnt(1)
	v_mfma_f32_32x32x16_bf16 v[112:127], v[234:237], v[226:229], v[112:127]
	v_mfma_f32_32x32x16_bf16 v[48:63], v[234:237], v[230:233], v[48:63]
	s_waitcnt lgkmcnt(0)
	v_mfma_f32_32x32x16_bf16 v[96:111], v[238:241], v[226:229], v[96:111]
	v_mfma_f32_32x32x16_bf16 v[32:47], v[238:241], v[230:233], v[32:47]
	ds_read_b128 v[234:237], v192 offset:9280
	ds_read_b128 v[238:241], v192 offset:13888
	s_waitcnt vmcnt(7)
	ds_write_b128 v217, v[176:179]
	s_waitcnt vmcnt(6)
	ds_write_b128 v216, v[180:183]
	ds_read_b128 v[176:179], v204 offset:36960
	ds_read_b128 v[180:183], v204 offset:41568
	s_waitcnt lgkmcnt(5)
	v_mfma_f32_32x32x16_bf16 v[80:95], v[234:237], v[226:229], v[80:95]
	v_mfma_f32_32x32x16_bf16 v[16:31], v[234:237], v[230:233], v[16:31]
	ds_read_b128 v[234:237], v192 offset:96
	s_waitcnt lgkmcnt(5)
	v_mfma_f32_32x32x16_bf16 v[64:79], v[238:241], v[226:229], v[64:79]
	v_mfma_f32_32x32x16_bf16 v[0:15], v[238:241], v[230:233], v[0:15]
	ds_read_b128 v[238:241], v192 offset:4704
	s_setprio 0
	global_load_dwordx4 v[226:229], v[198:199], off offset:3072
	global_load_dwordx4 v[230:233], v[200:201], off offset:3072
	s_setprio 1
	s_waitcnt lgkmcnt(1)
	v_mfma_f32_32x32x16_bf16 v[112:127], v[234:237], v[176:179], v[112:127]
	v_mfma_f32_32x32x16_bf16 v[48:63], v[234:237], v[180:183], v[48:63]
	s_waitcnt lgkmcnt(0)
	v_mfma_f32_32x32x16_bf16 v[96:111], v[238:241], v[176:179], v[96:111]
	v_mfma_f32_32x32x16_bf16 v[32:47], v[238:241], v[180:183], v[32:47]
	ds_read_b128 v[234:237], v192 offset:9312
	ds_read_b128 v[238:241], v192 offset:13920
	s_waitcnt lgkmcnt(0)
	s_barrier
; template <bool trans>
; DI void gemm_core(const GTile& tl, const GTile& nx, bool has_next  , bool chain  , bool pre, u32x4 (&ra)[4], u32x4 (&rb)[4], char* smem, f32x16 (&acc)[2][4]) {
;     ...
;   const int nk = K / 64;
;   if (!pre) { G_LOAD(0); G_STORE(0); G_LOAD(1); }
;   for (int kt = 0; kt < nk; ++kt) {
;     __syncthreads();
;     G_COMPUTE(kt & 1, kt);
;   }
	s_waitcnt vmcnt(7)
	ds_write_b128 v215, v[168:171]
	s_waitcnt vmcnt(6)
	ds_write_b128 v215, v[172:175] offset:36864
	ds_read_b128 v[168:171], v208
	ds_read_b128 v[172:175], v208 offset:4608
	v_mfma_f32_32x32x16_bf16 v[80:95], v[234:237], v[176:179], v[80:95]
	v_mfma_f32_32x32x16_bf16 v[16:31], v[234:237], v[180:183], v[16:31]
	ds_read_b128 v[234:237], v205
	v_mfma_f32_32x32x16_bf16 v[64:79], v[238:241], v[176:179], v[64:79]
	v_mfma_f32_32x32x16_bf16 v[0:15], v[238:241], v[180:183], v[0:15]
	ds_read_b128 v[238:241], v205 offset:4608
	s_setprio 0
	global_load_dwordx4 v[176:179], v[190:191], off offset:3200
	global_load_dwordx4 v[180:183], v[188:189], off offset:3200
	s_setprio 1
	s_waitcnt lgkmcnt(1)
	v_mfma_f32_32x32x16_bf16 v[112:127], v[234:237], v[168:171], v[112:127]
	v_mfma_f32_32x32x16_bf16 v[48:63], v[234:237], v[172:175], v[48:63]
	s_waitcnt lgkmcnt(0)
	v_mfma_f32_32x32x16_bf16 v[96:111], v[238:241], v[168:171], v[96:111]
	v_mfma_f32_32x32x16_bf16 v[32:47], v[238:241], v[172:175], v[32:47]
	ds_read_b128 v[234:237], v205 offset:9216
	ds_read_b128 v[238:241], v205 offset:13824
	s_waitcnt vmcnt(7)
	ds_write_b128 v215, v[160:163] offset:9216
	s_waitcnt vmcnt(6)
	ds_write_b128 v215, v[164:167] offset:46080
	ds_read_b128 v[160:163], v208 offset:32
	ds_read_b128 v[164:167], v208 offset:4640
	s_waitcnt lgkmcnt(5)
	v_mfma_f32_32x32x16_bf16 v[80:95], v[234:237], v[168:171], v[80:95]
	v_mfma_f32_32x32x16_bf16 v[16:31], v[234:237], v[172:175], v[16:31]
	ds_read_b128 v[234:237], v205 offset:32
	s_waitcnt lgkmcnt(5)
	v_mfma_f32_32x32x16_bf16 v[64:79], v[238:241], v[168:171], v[64:79]
	v_mfma_f32_32x32x16_bf16 v[0:15], v[238:241], v[172:175], v[0:15]
	ds_read_b128 v[238:241], v205 offset:4640
	s_setprio 0
	global_load_dwordx4 v[168:171], v[194:195], off offset:3200
	global_load_dwordx4 v[172:175], v[196:197], off offset:3200
	s_setprio 1
	s_waitcnt lgkmcnt(1)
	v_mfma_f32_32x32x16_bf16 v[112:127], v[234:237], v[160:163], v[112:127]
	v_mfma_f32_32x32x16_bf16 v[48:63], v[234:237], v[164:167], v[48:63]
	s_waitcnt lgkmcnt(0)
	v_mfma_f32_32x32x16_bf16 v[96:111], v[238:241], v[160:163], v[96:111]
	v_mfma_f32_32x32x16_bf16 v[32:47], v[238:241], v[164:167], v[32:47]
	ds_read_b128 v[234:237], v205 offset:9248
	ds_read_b128 v[238:241], v205 offset:13856
	s_waitcnt vmcnt(7)
	ds_write_b128 v215, v[218:221] offset:18432
	s_waitcnt vmcnt(6)
	ds_write_b128 v215, v[222:225] offset:55296
	ds_read_b128 v[218:221], v208 offset:64
	ds_read_b128 v[222:225], v208 offset:4672
	s_waitcnt lgkmcnt(5)
	v_mfma_f32_32x32x16_bf16 v[80:95], v[234:237], v[160:163], v[80:95]
	v_mfma_f32_32x32x16_bf16 v[16:31], v[234:237], v[164:167], v[16:31]
	ds_read_b128 v[234:237], v205 offset:64
	s_waitcnt lgkmcnt(5)
	v_mfma_f32_32x32x16_bf16 v[64:79], v[238:241], v[160:163], v[64:79]
	v_mfma_f32_32x32x16_bf16 v[0:15], v[238:241], v[164:167], v[0:15]
	ds_read_b128 v[238:241], v205 offset:4672
	s_setprio 0
	global_load_dwordx4 v[160:163], v[184:185], off offset:3200
	global_load_dwordx4 v[164:167], v[186:187], off offset:3200
	s_setprio 1
	s_waitcnt lgkmcnt(1)
	v_mfma_f32_32x32x16_bf16 v[112:127], v[234:237], v[218:221], v[112:127]
	v_mfma_f32_32x32x16_bf16 v[48:63], v[234:237], v[222:225], v[48:63]
	s_waitcnt lgkmcnt(0)
	v_mfma_f32_32x32x16_bf16 v[96:111], v[238:241], v[218:221], v[96:111]
	v_mfma_f32_32x32x16_bf16 v[32:47], v[238:241], v[222:225], v[32:47]
	ds_read_b128 v[234:237], v205 offset:9280
	ds_read_b128 v[238:241], v205 offset:13888
	s_waitcnt vmcnt(7)
	ds_write_b128 v215, v[226:229] offset:27648
	s_waitcnt vmcnt(6)
	ds_write_b128 v215, v[230:233] offset:64512
	ds_read_b128 v[226:229], v208 offset:96
	ds_read_b128 v[230:233], v208 offset:4704
	s_waitcnt lgkmcnt(5)
	v_mfma_f32_32x32x16_bf16 v[80:95], v[234:237], v[218:221], v[80:95]
	v_mfma_f32_32x32x16_bf16 v[16:31], v[234:237], v[222:225], v[16:31]
	ds_read_b128 v[234:237], v205 offset:96
	s_waitcnt lgkmcnt(5)
	v_mfma_f32_32x32x16_bf16 v[64:79], v[238:241], v[218:221], v[64:79]
	v_mfma_f32_32x32x16_bf16 v[0:15], v[238:241], v[222:225], v[0:15]
	ds_read_b128 v[238:241], v205 offset:4704
	s_setprio 0
	global_load_dwordx4 v[218:221], v[198:199], off offset:3200
	global_load_dwordx4 v[222:225], v[200:201], off offset:3200
	s_setprio 1
	s_waitcnt lgkmcnt(1)
	v_mfma_f32_32x32x16_bf16 v[112:127], v[234:237], v[226:229], v[112:127]
	v_mfma_f32_32x32x16_bf16 v[48:63], v[234:237], v[230:233], v[48:63]
	s_waitcnt lgkmcnt(0)
	v_mfma_f32_32x32x16_bf16 v[96:111], v[238:241], v[226:229], v[96:111]
	v_mfma_f32_32x32x16_bf16 v[32:47], v[238:241], v[230:233], v[32:47]
	ds_read_b128 v[234:237], v205 offset:9312
	ds_read_b128 v[238:241], v205 offset:13920
	s_waitcnt lgkmcnt(0)
	s_barrier
; template <bool trans>
; DI void gemm_core(const GTile& tl, const GTile& nx, bool has_next  , bool chain  , bool pre, u32x4 (&ra)[4], u32x4 (&rb)[4], char* smem, f32x16 (&acc)[2][4]) {
;     ...
;   const int nk = K / 64;
;   if (!pre) { G_LOAD(0); G_STORE(0); G_LOAD(1); }
;   for (int kt = 0; kt < nk; ++kt) {
;     __syncthreads();
;     G_COMPUTE(kt & 1, kt);
;   }
	s_waitcnt vmcnt(7)
	ds_write_b128 v209, v[176:179]
	s_waitcnt vmcnt(6)
	ds_write_b128 v210, v[180:183]
	ds_read_b128 v[176:179], v204 offset:36864
	ds_read_b128 v[180:183], v204 offset:41472
	v_mfma_f32_32x32x16_bf16 v[80:95], v[234:237], v[226:229], v[80:95]
	v_mfma_f32_32x32x16_bf16 v[16:31], v[234:237], v[230:233], v[16:31]
	ds_read_b128 v[234:237], v192
	v_mfma_f32_32x32x16_bf16 v[64:79], v[238:241], v[226:229], v[64:79]
	v_mfma_f32_32x32x16_bf16 v[0:15], v[238:241], v[230:233], v[0:15]
	ds_read_b128 v[238:241], v192 offset:4608
	s_setprio 0
	global_load_dwordx4 v[226:229], v[190:191], off offset:3328
	global_load_dwordx4 v[230:233], v[188:189], off offset:3328
	s_setprio 1
	s_waitcnt lgkmcnt(1)
	v_mfma_f32_32x32x16_bf16 v[112:127], v[234:237], v[176:179], v[112:127]
	v_mfma_f32_32x32x16_bf16 v[48:63], v[234:237], v[180:183], v[48:63]
	s_waitcnt lgkmcnt(0)
	v_mfma_f32_32x32x16_bf16 v[96:111], v[238:241], v[176:179], v[96:111]
	v_mfma_f32_32x32x16_bf16 v[32:47], v[238:241], v[180:183], v[32:47]
	ds_read_b128 v[234:237], v192 offset:9216
	ds_read_b128 v[238:241], v192 offset:13824
	s_waitcnt vmcnt(7)
	ds_write_b128 v212, v[168:171]
	s_waitcnt vmcnt(6)
	ds_write_b128 v211, v[172:175]
	ds_read_b128 v[168:171], v204 offset:36896
	ds_read_b128 v[172:175], v204 offset:41504
	s_waitcnt lgkmcnt(5)
	v_mfma_f32_32x32x16_bf16 v[80:95], v[234:237], v[176:179], v[80:95]
	v_mfma_f32_32x32x16_bf16 v[16:31], v[234:237], v[180:183], v[16:31]
	ds_read_b128 v[234:237], v192 offset:32
	s_waitcnt lgkmcnt(5)
	v_mfma_f32_32x32x16_bf16 v[64:79], v[238:241], v[176:179], v[64:79]
	v_mfma_f32_32x32x16_bf16 v[0:15], v[238:241], v[180:183], v[0:15]
	ds_read_b128 v[238:241], v192 offset:4640
	s_setprio 0
	global_load_dwordx4 v[176:179], v[194:195], off offset:3328
	global_load_dwordx4 v[180:183], v[196:197], off offset:3328
	s_setprio 1
	s_waitcnt lgkmcnt(1)
	v_mfma_f32_32x32x16_bf16 v[112:127], v[234:237], v[168:171], v[112:127]
	v_mfma_f32_32x32x16_bf16 v[48:63], v[234:237], v[172:175], v[48:63]
	s_waitcnt lgkmcnt(0)
	v_mfma_f32_32x32x16_bf16 v[96:111], v[238:241], v[168:171], v[96:111]
	v_mfma_f32_32x32x16_bf16 v[32:47], v[238:241], v[172:175], v[32:47]
	ds_read_b128 v[234:237], v192 offset:9248
	ds_read_b128 v[238:241], v192 offset:13856
	s_waitcnt vmcnt(7)
	ds_write_b128 v214, v[160:163]
	s_waitcnt vmcnt(6)
	ds_write_b128 v213, v[164:167]
	ds_read_b128 v[160:163], v204 offset:36928
	ds_read_b128 v[164:167], v204 offset:41536
	s_waitcnt lgkmcnt(5)
	v_mfma_f32_32x32x16_bf16 v[80:95], v[234:237], v[168:171], v[80:95]
	v_mfma_f32_32x32x16_bf16 v[16:31], v[234:237], v[172:175], v[16:31]
	ds_read_b128 v[234:237], v192 offset:64
	s_waitcnt lgkmcnt(5)
	v_mfma_f32_32x32x16_bf16 v[64:79], v[238:241], v[168:171], v[64:79]
	v_mfma_f32_32x32x16_bf16 v[0:15], v[238:241], v[172:175], v[0:15]
	ds_read_b128 v[238:241], v192 offset:4672
	s_setprio 0
	global_load_dwordx4 v[168:171], v[184:185], off offset:3328
	global_load_dwordx4 v[172:175], v[186:187], off offset:3328
	s_setprio 1
	s_waitcnt lgkmcnt(1)
	v_mfma_f32_32x32x16_bf16 v[112:127], v[234:237], v[160:163], v[112:127]
	v_mfma_f32_32x32x16_bf16 v[48:63], v[234:237], v[164:167], v[48:63]
	s_waitcnt lgkmcnt(0)
	v_mfma_f32_32x32x16_bf16 v[96:111], v[238:241], v[160:163], v[96:111]
	v_mfma_f32_32x32x16_bf16 v[32:47], v[238:241], v[164:167], v[32:47]
	ds_read_b128 v[234:237], v192 offset:9280
	ds_read_b128 v[238:241], v192 offset:13888
	s_waitcnt vmcnt(7)
	ds_write_b128 v217, v[218:221]
	s_waitcnt vmcnt(6)
	ds_write_b128 v216, v[222:225]
	ds_read_b128 v[218:221], v204 offset:36960
	ds_read_b128 v[222:225], v204 offset:41568
	s_waitcnt lgkmcnt(5)
	v_mfma_f32_32x32x16_bf16 v[80:95], v[234:237], v[160:163], v[80:95]
	v_mfma_f32_32x32x16_bf16 v[16:31], v[234:237], v[164:167], v[16:31]
	ds_read_b128 v[234:237], v192 offset:96
	s_waitcnt lgkmcnt(5)
	v_mfma_f32_32x32x16_bf16 v[64:79], v[238:241], v[160:163], v[64:79]
	v_mfma_f32_32x32x16_bf16 v[0:15], v[238:241], v[164:167], v[0:15]
	ds_read_b128 v[238:241], v192 offset:4704
	s_setprio 0
	global_load_dwordx4 v[160:163], v[198:199], off offset:3328
	global_load_dwordx4 v[164:167], v[200:201], off offset:3328
	s_setprio 1
	s_waitcnt lgkmcnt(1)
	v_mfma_f32_32x32x16_bf16 v[112:127], v[234:237], v[218:221], v[112:127]
	v_mfma_f32_32x32x16_bf16 v[48:63], v[234:237], v[222:225], v[48:63]
	s_waitcnt lgkmcnt(0)
	v_mfma_f32_32x32x16_bf16 v[96:111], v[238:241], v[218:221], v[96:111]
	v_mfma_f32_32x32x16_bf16 v[32:47], v[238:241], v[222:225], v[32:47]
	ds_read_b128 v[234:237], v192 offset:9312
	ds_read_b128 v[238:241], v192 offset:13920
	s_waitcnt lgkmcnt(0)
	s_barrier
; template <bool trans>
; DI void gemm_core(const GTile& tl, const GTile& nx, bool has_next  , bool chain  , bool pre, u32x4 (&ra)[4], u32x4 (&rb)[4], char* smem, f32x16 (&acc)[2][4]) {
;     ...
;   const int nk = K / 64;
;   if (!pre) { G_LOAD(0); G_STORE(0); G_LOAD(1); }
;   for (int kt = 0; kt < nk; ++kt) {
;     __syncthreads();
;     G_COMPUTE(kt & 1, kt);
;   }
	s_waitcnt vmcnt(7)
	ds_write_b128 v215, v[226:229]
	s_waitcnt vmcnt(6)
	ds_write_b128 v215, v[230:233] offset:36864
	ds_read_b128 v[226:229], v208
	ds_read_b128 v[230:233], v208 offset:4608
	v_mfma_f32_32x32x16_bf16 v[80:95], v[234:237], v[218:221], v[80:95]
	v_mfma_f32_32x32x16_bf16 v[16:31], v[234:237], v[222:225], v[16:31]
	ds_read_b128 v[234:237], v205
	v_mfma_f32_32x32x16_bf16 v[64:79], v[238:241], v[218:221], v[64:79]
	v_mfma_f32_32x32x16_bf16 v[0:15], v[238:241], v[222:225], v[0:15]
	ds_read_b128 v[238:241], v205 offset:4608
	s_setprio 0
	global_load_dwordx4 v[218:221], v[190:191], off offset:3456
	global_load_dwordx4 v[222:225], v[188:189], off offset:3456
	s_setprio 1
	s_waitcnt lgkmcnt(1)
	v_mfma_f32_32x32x16_bf16 v[112:127], v[234:237], v[226:229], v[112:127]
	v_mfma_f32_32x32x16_bf16 v[48:63], v[234:237], v[230:233], v[48:63]
	s_waitcnt lgkmcnt(0)
	v_mfma_f32_32x32x16_bf16 v[96:111], v[238:241], v[226:229], v[96:111]
	v_mfma_f32_32x32x16_bf16 v[32:47], v[238:241], v[230:233], v[32:47]
	ds_read_b128 v[234:237], v205 offset:9216
	ds_read_b128 v[238:241], v205 offset:13824
	s_waitcnt vmcnt(7)
	ds_write_b128 v215, v[176:179] offset:9216
	s_waitcnt vmcnt(6)
	ds_write_b128 v215, v[180:183] offset:46080
	ds_read_b128 v[176:179], v208 offset:32
	ds_read_b128 v[180:183], v208 offset:4640
	s_waitcnt lgkmcnt(5)
	v_mfma_f32_32x32x16_bf16 v[80:95], v[234:237], v[226:229], v[80:95]
	v_mfma_f32_32x32x16_bf16 v[16:31], v[234:237], v[230:233], v[16:31]
	ds_read_b128 v[234:237], v205 offset:32
	s_waitcnt lgkmcnt(5)
	v_mfma_f32_32x32x16_bf16 v[64:79], v[238:241], v[226:229], v[64:79]
	v_mfma_f32_32x32x16_bf16 v[0:15], v[238:241], v[230:233], v[0:15]
	ds_read_b128 v[238:241], v205 offset:4640
	s_setprio 0
	global_load_dwordx4 v[226:229], v[194:195], off offset:3456
	global_load_dwordx4 v[230:233], v[196:197], off offset:3456
	s_setprio 1
	s_waitcnt lgkmcnt(1)
	v_mfma_f32_32x32x16_bf16 v[112:127], v[234:237], v[176:179], v[112:127]
	v_mfma_f32_32x32x16_bf16 v[48:63], v[234:237], v[180:183], v[48:63]
	s_waitcnt lgkmcnt(0)
	v_mfma_f32_32x32x16_bf16 v[96:111], v[238:241], v[176:179], v[96:111]
	v_mfma_f32_32x32x16_bf16 v[32:47], v[238:241], v[180:183], v[32:47]
	ds_read_b128 v[234:237], v205 offset:9248
	ds_read_b128 v[238:241], v205 offset:13856
	s_waitcnt vmcnt(7)
	ds_write_b128 v215, v[168:171] offset:18432
	s_waitcnt vmcnt(6)
	ds_write_b128 v215, v[172:175] offset:55296
	ds_read_b128 v[168:171], v208 offset:64
	ds_read_b128 v[172:175], v208 offset:4672
	s_waitcnt lgkmcnt(5)
	v_mfma_f32_32x32x16_bf16 v[80:95], v[234:237], v[176:179], v[80:95]
	v_mfma_f32_32x32x16_bf16 v[16:31], v[234:237], v[180:183], v[16:31]
	ds_read_b128 v[234:237], v205 offset:64
	s_waitcnt lgkmcnt(5)
	v_mfma_f32_32x32x16_bf16 v[64:79], v[238:241], v[176:179], v[64:79]
	v_mfma_f32_32x32x16_bf16 v[0:15], v[238:241], v[180:183], v[0:15]
	ds_read_b128 v[238:241], v205 offset:4672
	s_setprio 0
	global_load_dwordx4 v[176:179], v[184:185], off offset:3456
	global_load_dwordx4 v[180:183], v[186:187], off offset:3456
	s_setprio 1
	s_waitcnt lgkmcnt(1)
	v_mfma_f32_32x32x16_bf16 v[112:127], v[234:237], v[168:171], v[112:127]
	v_mfma_f32_32x32x16_bf16 v[48:63], v[234:237], v[172:175], v[48:63]
	s_waitcnt lgkmcnt(0)
	v_mfma_f32_32x32x16_bf16 v[96:111], v[238:241], v[168:171], v[96:111]
	v_mfma_f32_32x32x16_bf16 v[32:47], v[238:241], v[172:175], v[32:47]
	ds_read_b128 v[234:237], v205 offset:9280
	ds_read_b128 v[238:241], v205 offset:13888
	s_waitcnt vmcnt(7)
	ds_write_b128 v215, v[160:163] offset:27648
	s_waitcnt vmcnt(6)
	ds_write_b128 v215, v[164:167] offset:64512
	ds_read_b128 v[160:163], v208 offset:96
	ds_read_b128 v[164:167], v208 offset:4704
	s_waitcnt lgkmcnt(5)
	v_mfma_f32_32x32x16_bf16 v[80:95], v[234:237], v[168:171], v[80:95]
	v_mfma_f32_32x32x16_bf16 v[16:31], v[234:237], v[172:175], v[16:31]
	ds_read_b128 v[234:237], v205 offset:96
	s_waitcnt lgkmcnt(5)
	v_mfma_f32_32x32x16_bf16 v[64:79], v[238:241], v[168:171], v[64:79]
	v_mfma_f32_32x32x16_bf16 v[0:15], v[238:241], v[172:175], v[0:15]
	ds_read_b128 v[238:241], v205 offset:4704
	s_setprio 0
	global_load_dwordx4 v[168:171], v[198:199], off offset:3456
	global_load_dwordx4 v[172:175], v[200:201], off offset:3456
	s_setprio 1
	s_waitcnt lgkmcnt(1)
	v_mfma_f32_32x32x16_bf16 v[112:127], v[234:237], v[160:163], v[112:127]
	v_mfma_f32_32x32x16_bf16 v[48:63], v[234:237], v[164:167], v[48:63]
	s_waitcnt lgkmcnt(0)
	v_mfma_f32_32x32x16_bf16 v[96:111], v[238:241], v[160:163], v[96:111]
	v_mfma_f32_32x32x16_bf16 v[32:47], v[238:241], v[164:167], v[32:47]
	ds_read_b128 v[234:237], v205 offset:9312
	ds_read_b128 v[238:241], v205 offset:13920
	s_waitcnt lgkmcnt(0)
	s_barrier
; template <bool trans>
; DI void gemm_core(const GTile& tl, const GTile& nx, bool has_next  , bool chain  , bool pre, u32x4 (&ra)[4], u32x4 (&rb)[4], char* smem, f32x16 (&acc)[2][4]) {
;     ...
;   const int nk = K / 64;
;   if (!pre) { G_LOAD(0); G_STORE(0); G_LOAD(1); }
;   for (int kt = 0; kt < nk; ++kt) {
;     __syncthreads();
;     G_COMPUTE(kt & 1, kt);
;   }
	s_waitcnt vmcnt(7)
	ds_write_b128 v209, v[218:221]
	s_waitcnt vmcnt(6)
	ds_write_b128 v210, v[222:225]
	ds_read_b128 v[218:221], v204 offset:36864
	ds_read_b128 v[222:225], v204 offset:41472
	v_mfma_f32_32x32x16_bf16 v[80:95], v[234:237], v[160:163], v[80:95]
	v_mfma_f32_32x32x16_bf16 v[16:31], v[234:237], v[164:167], v[16:31]
	ds_read_b128 v[234:237], v192
	v_mfma_f32_32x32x16_bf16 v[64:79], v[238:241], v[160:163], v[64:79]
	v_mfma_f32_32x32x16_bf16 v[0:15], v[238:241], v[164:167], v[0:15]
	ds_read_b128 v[238:241], v192 offset:4608
	s_setprio 0
	global_load_dwordx4 v[160:163], v[190:191], off offset:3584
	global_load_dwordx4 v[164:167], v[188:189], off offset:3584
	s_setprio 1
	s_waitcnt lgkmcnt(1)
	v_mfma_f32_32x32x16_bf16 v[112:127], v[234:237], v[218:221], v[112:127]
	v_mfma_f32_32x32x16_bf16 v[48:63], v[234:237], v[222:225], v[48:63]
	s_waitcnt lgkmcnt(0)
	v_mfma_f32_32x32x16_bf16 v[96:111], v[238:241], v[218:221], v[96:111]
	v_mfma_f32_32x32x16_bf16 v[32:47], v[238:241], v[222:225], v[32:47]
	ds_read_b128 v[234:237], v192 offset:9216
	ds_read_b128 v[238:241], v192 offset:13824
	s_waitcnt vmcnt(7)
	ds_write_b128 v212, v[226:229]
	s_waitcnt vmcnt(6)
	ds_write_b128 v211, v[230:233]
	ds_read_b128 v[226:229], v204 offset:36896
	ds_read_b128 v[230:233], v204 offset:41504
	s_waitcnt lgkmcnt(5)
	v_mfma_f32_32x32x16_bf16 v[80:95], v[234:237], v[218:221], v[80:95]
	v_mfma_f32_32x32x16_bf16 v[16:31], v[234:237], v[222:225], v[16:31]
	ds_read_b128 v[234:237], v192 offset:32
	s_waitcnt lgkmcnt(5)
	v_mfma_f32_32x32x16_bf16 v[64:79], v[238:241], v[218:221], v[64:79]
	v_mfma_f32_32x32x16_bf16 v[0:15], v[238:241], v[222:225], v[0:15]
	ds_read_b128 v[238:241], v192 offset:4640
	s_setprio 0
	global_load_dwordx4 v[218:221], v[194:195], off offset:3584
	global_load_dwordx4 v[222:225], v[196:197], off offset:3584
	s_setprio 1
	s_waitcnt lgkmcnt(1)
	v_mfma_f32_32x32x16_bf16 v[112:127], v[234:237], v[226:229], v[112:127]
	v_mfma_f32_32x32x16_bf16 v[48:63], v[234:237], v[230:233], v[48:63]
	s_waitcnt lgkmcnt(0)
	v_mfma_f32_32x32x16_bf16 v[96:111], v[238:241], v[226:229], v[96:111]
	v_mfma_f32_32x32x16_bf16 v[32:47], v[238:241], v[230:233], v[32:47]
	ds_read_b128 v[234:237], v192 offset:9248
	ds_read_b128 v[238:241], v192 offset:13856
	s_waitcnt vmcnt(7)
	ds_write_b128 v214, v[176:179]
	s_waitcnt vmcnt(6)
	ds_write_b128 v213, v[180:183]
	ds_read_b128 v[176:179], v204 offset:36928
	ds_read_b128 v[180:183], v204 offset:41536
	s_waitcnt lgkmcnt(5)
	v_mfma_f32_32x32x16_bf16 v[80:95], v[234:237], v[226:229], v[80:95]
	v_mfma_f32_32x32x16_bf16 v[16:31], v[234:237], v[230:233], v[16:31]
	ds_read_b128 v[234:237], v192 offset:64
	s_waitcnt lgkmcnt(5)
	v_mfma_f32_32x32x16_bf16 v[64:79], v[238:241], v[226:229], v[64:79]
	v_mfma_f32_32x32x16_bf16 v[0:15], v[238:241], v[230:233], v[0:15]
	ds_read_b128 v[238:241], v192 offset:4672
	s_setprio 0
	global_load_dwordx4 v[226:229], v[184:185], off offset:3584
	global_load_dwordx4 v[230:233], v[186:187], off offset:3584
	s_setprio 1
	s_waitcnt lgkmcnt(1)
	v_mfma_f32_32x32x16_bf16 v[112:127], v[234:237], v[176:179], v[112:127]
	v_mfma_f32_32x32x16_bf16 v[48:63], v[234:237], v[180:183], v[48:63]
	s_waitcnt lgkmcnt(0)
	v_mfma_f32_32x32x16_bf16 v[96:111], v[238:241], v[176:179], v[96:111]
	v_mfma_f32_32x32x16_bf16 v[32:47], v[238:241], v[180:183], v[32:47]
	ds_read_b128 v[234:237], v192 offset:9280
	ds_read_b128 v[238:241], v192 offset:13888
	s_waitcnt vmcnt(7)
	ds_write_b128 v217, v[168:171]
	s_waitcnt vmcnt(6)
	ds_write_b128 v216, v[172:175]
	ds_read_b128 v[168:171], v204 offset:36960
	ds_read_b128 v[172:175], v204 offset:41568
	s_waitcnt lgkmcnt(5)
	v_mfma_f32_32x32x16_bf16 v[80:95], v[234:237], v[176:179], v[80:95]
	v_mfma_f32_32x32x16_bf16 v[16:31], v[234:237], v[180:183], v[16:31]
	ds_read_b128 v[234:237], v192 offset:96
	s_waitcnt lgkmcnt(5)
	v_mfma_f32_32x32x16_bf16 v[64:79], v[238:241], v[176:179], v[64:79]
	v_mfma_f32_32x32x16_bf16 v[0:15], v[238:241], v[180:183], v[0:15]
	ds_read_b128 v[238:241], v192 offset:4704
	s_setprio 0
	global_load_dwordx4 v[176:179], v[198:199], off offset:3584
	global_load_dwordx4 v[180:183], v[200:201], off offset:3584
	s_setprio 1
	s_waitcnt lgkmcnt(1)
	v_mfma_f32_32x32x16_bf16 v[112:127], v[234:237], v[168:171], v[112:127]
	v_mfma_f32_32x32x16_bf16 v[48:63], v[234:237], v[172:175], v[48:63]
	s_waitcnt lgkmcnt(0)
	v_mfma_f32_32x32x16_bf16 v[96:111], v[238:241], v[168:171], v[96:111]
	v_mfma_f32_32x32x16_bf16 v[32:47], v[238:241], v[172:175], v[32:47]
	ds_read_b128 v[234:237], v192 offset:9312
	ds_read_b128 v[238:241], v192 offset:13920
	s_waitcnt lgkmcnt(0)
	s_barrier
; template <bool trans>
; DI void gemm_core(const GTile& tl, const GTile& nx, bool has_next  , bool chain  , bool pre, u32x4 (&ra)[4], u32x4 (&rb)[4], char* smem, f32x16 (&acc)[2][4]) {
;     ...
;   const int nk = K / 64;
;   if (!pre) { G_LOAD(0); G_STORE(0); G_LOAD(1); }
;   for (int kt = 0; kt < nk; ++kt) {
;     __syncthreads();
;     G_COMPUTE(kt & 1, kt);
;   }
	s_waitcnt vmcnt(7)
	ds_write_b128 v215, v[160:163]
	s_waitcnt vmcnt(6)
	ds_write_b128 v215, v[164:167] offset:36864
	ds_read_b128 v[160:163], v208
	ds_read_b128 v[164:167], v208 offset:4608
	v_mfma_f32_32x32x16_bf16 v[80:95], v[234:237], v[168:171], v[80:95]
	v_mfma_f32_32x32x16_bf16 v[16:31], v[234:237], v[172:175], v[16:31]
	ds_read_b128 v[234:237], v205
	v_mfma_f32_32x32x16_bf16 v[64:79], v[238:241], v[168:171], v[64:79]
	v_mfma_f32_32x32x16_bf16 v[0:15], v[238:241], v[172:175], v[0:15]
	ds_read_b128 v[238:241], v205 offset:4608
	s_setprio 0
	global_load_dwordx4 v[168:171], v[190:191], off offset:3712
	global_load_dwordx4 v[172:175], v[188:189], off offset:3712
	s_setprio 1
	s_waitcnt lgkmcnt(1)
	v_mfma_f32_32x32x16_bf16 v[112:127], v[234:237], v[160:163], v[112:127]
	v_mfma_f32_32x32x16_bf16 v[48:63], v[234:237], v[164:167], v[48:63]
	s_waitcnt lgkmcnt(0)
	v_mfma_f32_32x32x16_bf16 v[96:111], v[238:241], v[160:163], v[96:111]
	v_mfma_f32_32x32x16_bf16 v[32:47], v[238:241], v[164:167], v[32:47]
	ds_read_b128 v[234:237], v205 offset:9216
	ds_read_b128 v[238:241], v205 offset:13824
	s_waitcnt vmcnt(7)
	ds_write_b128 v215, v[218:221] offset:9216
	s_waitcnt vmcnt(6)
	ds_write_b128 v215, v[222:225] offset:46080
	ds_read_b128 v[218:221], v208 offset:32
	ds_read_b128 v[222:225], v208 offset:4640
	s_waitcnt lgkmcnt(5)
	v_mfma_f32_32x32x16_bf16 v[80:95], v[234:237], v[160:163], v[80:95]
	v_mfma_f32_32x32x16_bf16 v[16:31], v[234:237], v[164:167], v[16:31]
	ds_read_b128 v[234:237], v205 offset:32
	s_waitcnt lgkmcnt(5)
	v_mfma_f32_32x32x16_bf16 v[64:79], v[238:241], v[160:163], v[64:79]
	v_mfma_f32_32x32x16_bf16 v[0:15], v[238:241], v[164:167], v[0:15]
	ds_read_b128 v[238:241], v205 offset:4640
	s_setprio 0
	global_load_dwordx4 v[160:163], v[194:195], off offset:3712
	global_load_dwordx4 v[164:167], v[196:197], off offset:3712
	s_setprio 1
	s_waitcnt lgkmcnt(1)
	v_mfma_f32_32x32x16_bf16 v[112:127], v[234:237], v[218:221], v[112:127]
	v_mfma_f32_32x32x16_bf16 v[48:63], v[234:237], v[222:225], v[48:63]
	s_waitcnt lgkmcnt(0)
	v_mfma_f32_32x32x16_bf16 v[96:111], v[238:241], v[218:221], v[96:111]
	v_mfma_f32_32x32x16_bf16 v[32:47], v[238:241], v[222:225], v[32:47]
	ds_read_b128 v[234:237], v205 offset:9248
	ds_read_b128 v[238:241], v205 offset:13856
	s_waitcnt vmcnt(7)
	ds_write_b128 v215, v[226:229] offset:18432
	s_waitcnt vmcnt(6)
	ds_write_b128 v215, v[230:233] offset:55296
	ds_read_b128 v[226:229], v208 offset:64
	ds_read_b128 v[230:233], v208 offset:4672
	s_waitcnt lgkmcnt(5)
	v_mfma_f32_32x32x16_bf16 v[80:95], v[234:237], v[218:221], v[80:95]
	v_mfma_f32_32x32x16_bf16 v[16:31], v[234:237], v[222:225], v[16:31]
	ds_read_b128 v[234:237], v205 offset:64
	s_waitcnt lgkmcnt(5)
	v_mfma_f32_32x32x16_bf16 v[64:79], v[238:241], v[218:221], v[64:79]
	v_mfma_f32_32x32x16_bf16 v[0:15], v[238:241], v[222:225], v[0:15]
	ds_read_b128 v[238:241], v205 offset:4672
	s_setprio 0
	global_load_dwordx4 v[218:221], v[184:185], off offset:3712
	global_load_dwordx4 v[222:225], v[186:187], off offset:3712
	s_setprio 1
	s_waitcnt lgkmcnt(1)
	v_mfma_f32_32x32x16_bf16 v[112:127], v[234:237], v[226:229], v[112:127]
	v_mfma_f32_32x32x16_bf16 v[48:63], v[234:237], v[230:233], v[48:63]
	s_waitcnt lgkmcnt(0)
	v_mfma_f32_32x32x16_bf16 v[96:111], v[238:241], v[226:229], v[96:111]
	v_mfma_f32_32x32x16_bf16 v[32:47], v[238:241], v[230:233], v[32:47]
	ds_read_b128 v[234:237], v205 offset:9280
	ds_read_b128 v[238:241], v205 offset:13888
	s_waitcnt vmcnt(7)
	ds_write_b128 v215, v[176:179] offset:27648
	s_waitcnt vmcnt(6)
	ds_write_b128 v215, v[180:183] offset:64512
	ds_read_b128 v[176:179], v208 offset:96
	ds_read_b128 v[180:183], v208 offset:4704
	s_waitcnt lgkmcnt(5)
	v_mfma_f32_32x32x16_bf16 v[80:95], v[234:237], v[226:229], v[80:95]
	v_mfma_f32_32x32x16_bf16 v[16:31], v[234:237], v[230:233], v[16:31]
	ds_read_b128 v[234:237], v205 offset:96
	s_waitcnt lgkmcnt(5)
	v_mfma_f32_32x32x16_bf16 v[64:79], v[238:241], v[226:229], v[64:79]
	v_mfma_f32_32x32x16_bf16 v[0:15], v[238:241], v[230:233], v[0:15]
	ds_read_b128 v[238:241], v205 offset:4704
	s_setprio 0
	global_load_dwordx4 v[226:229], v[198:199], off offset:3712
	global_load_dwordx4 v[230:233], v[200:201], off offset:3712
	s_setprio 1
	s_waitcnt lgkmcnt(1)
	v_mfma_f32_32x32x16_bf16 v[112:127], v[234:237], v[176:179], v[112:127]
	v_mfma_f32_32x32x16_bf16 v[48:63], v[234:237], v[180:183], v[48:63]
	s_waitcnt lgkmcnt(0)
	v_mfma_f32_32x32x16_bf16 v[96:111], v[238:241], v[176:179], v[96:111]
	v_mfma_f32_32x32x16_bf16 v[32:47], v[238:241], v[180:183], v[32:47]
	ds_read_b128 v[234:237], v205 offset:9312
	ds_read_b128 v[238:241], v205 offset:13920
	s_waitcnt lgkmcnt(1)
	v_mfma_f32_32x32x16_bf16 v[80:95], v[234:237], v[176:179], v[80:95]
	v_mfma_f32_32x32x16_bf16 v[16:31], v[234:237], v[180:183], v[16:31]
	s_waitcnt lgkmcnt(0)
	v_mfma_f32_32x32x16_bf16 v[64:79], v[238:241], v[176:179], v[64:79]
	v_mfma_f32_32x32x16_bf16 v[0:15], v[238:241], v[180:183], v[0:15]
	s_setprio 0
	global_load_dwordx4 v[176:179], v[190:191], off offset:3840
	global_load_dwordx4 v[180:183], v[188:189], off offset:3840
	s_barrier
; template <bool trans>
; DI void gemm_core(const GTile& tl, const GTile& nx, bool has_next  , bool chain  , bool pre, u32x4 (&ra)[4], u32x4 (&rb)[4], char* smem, f32x16 (&acc)[2][4]) {
;     ...
;   const int nk = K / 64;
;   if (!pre) { G_LOAD(0); G_STORE(0); G_LOAD(1); }
;   for (int kt = 0; kt < nk; ++kt) {
;     __syncthreads();
;     G_COMPUTE(kt & 1, kt);
;   }
	s_waitcnt vmcnt(9)
	ds_write_b128 v209, v[168:171]
	s_waitcnt vmcnt(8)
	ds_write_b128 v210, v[172:175]
	ds_read_b128 v[168:171], v204 offset:36864
	ds_read_b128 v[172:175], v204 offset:41472
	ds_read_b128 v[234:237], v192
	ds_read_b128 v[238:241], v192 offset:4608
	s_setprio 1
	s_waitcnt lgkmcnt(1)
	v_mfma_f32_32x32x16_bf16 v[112:127], v[234:237], v[168:171], v[112:127]
	v_mfma_f32_32x32x16_bf16 v[48:63], v[234:237], v[172:175], v[48:63]
	s_waitcnt lgkmcnt(0)
	v_mfma_f32_32x32x16_bf16 v[96:111], v[238:241], v[168:171], v[96:111]
	v_mfma_f32_32x32x16_bf16 v[32:47], v[238:241], v[172:175], v[32:47]
	ds_read_b128 v[234:237], v192 offset:9216
	ds_read_b128 v[238:241], v192 offset:13824
	s_waitcnt lgkmcnt(1)
	v_mfma_f32_32x32x16_bf16 v[80:95], v[234:237], v[168:171], v[80:95]
	v_mfma_f32_32x32x16_bf16 v[16:31], v[234:237], v[172:175], v[16:31]
	s_waitcnt lgkmcnt(0)
	v_mfma_f32_32x32x16_bf16 v[64:79], v[238:241], v[168:171], v[64:79]
	v_mfma_f32_32x32x16_bf16 v[0:15], v[238:241], v[172:175], v[0:15]
	s_setprio 0
	global_load_dwordx4 v[234:237], v[194:195], off offset:3840
	global_load_dwordx4 v[238:241], v[196:197], off offset:3840
	s_waitcnt vmcnt(9)
	ds_write_b128 v212, v[160:163]
	s_waitcnt vmcnt(8)
	ds_write_b128 v211, v[164:167]
	ds_read_b128 v[160:163], v204 offset:36896
	ds_read_b128 v[164:167], v204 offset:41504
	ds_read_b128 v[168:171], v192 offset:32
	ds_read_b128 v[172:175], v192 offset:4640
	s_setprio 1
	s_waitcnt lgkmcnt(1)
	v_mfma_f32_32x32x16_bf16 v[112:127], v[168:171], v[160:163], v[112:127]
	v_mfma_f32_32x32x16_bf16 v[48:63], v[168:171], v[164:167], v[48:63]
	s_waitcnt lgkmcnt(0)
	v_mfma_f32_32x32x16_bf16 v[96:111], v[172:175], v[160:163], v[96:111]
	v_mfma_f32_32x32x16_bf16 v[32:47], v[172:175], v[164:167], v[32:47]
	ds_read_b128 v[168:171], v192 offset:9248
	ds_read_b128 v[172:175], v192 offset:13856
	s_waitcnt lgkmcnt(1)
	v_mfma_f32_32x32x16_bf16 v[80:95], v[168:171], v[160:163], v[80:95]
	v_mfma_f32_32x32x16_bf16 v[16:31], v[168:171], v[164:167], v[16:31]
	s_waitcnt lgkmcnt(0)
	v_mfma_f32_32x32x16_bf16 v[64:79], v[172:175], v[160:163], v[64:79]
	v_mfma_f32_32x32x16_bf16 v[0:15], v[172:175], v[164:167], v[0:15]
	s_setprio 0
	global_load_dwordx4 v[242:245], v[184:185], off offset:3840
	global_load_dwordx4 v[246:249], v[186:187], off offset:3840
	s_waitcnt vmcnt(9)
	ds_write_b128 v214, v[218:221]
	s_waitcnt vmcnt(8)
	ds_write_b128 v213, v[222:225]
	ds_read_b128 v[160:163], v204 offset:36928
	ds_read_b128 v[164:167], v204 offset:41536
	ds_read_b128 v[168:171], v192 offset:64
	ds_read_b128 v[172:175], v192 offset:4672
	s_setprio 1
	s_waitcnt lgkmcnt(1)
	v_mfma_f32_32x32x16_bf16 v[112:127], v[168:171], v[160:163], v[112:127]
	v_mfma_f32_32x32x16_bf16 v[48:63], v[168:171], v[164:167], v[48:63]
	s_waitcnt lgkmcnt(0)
	v_mfma_f32_32x32x16_bf16 v[96:111], v[172:175], v[160:163], v[96:111]
	v_mfma_f32_32x32x16_bf16 v[32:47], v[172:175], v[164:167], v[32:47]
	ds_read_b128 v[168:171], v192 offset:9280
	ds_read_b128 v[172:175], v192 offset:13888
	s_waitcnt lgkmcnt(1)
	v_mfma_f32_32x32x16_bf16 v[80:95], v[168:171], v[160:163], v[80:95]
	v_mfma_f32_32x32x16_bf16 v[16:31], v[168:171], v[164:167], v[16:31]
	s_waitcnt lgkmcnt(0)
	v_mfma_f32_32x32x16_bf16 v[64:79], v[172:175], v[160:163], v[64:79]
	v_mfma_f32_32x32x16_bf16 v[0:15], v[172:175], v[164:167], v[0:15]
	s_setprio 0
	global_load_dwordx4 v[218:221], v[198:199], off offset:3840
	global_load_dwordx4 v[222:225], v[200:201], off offset:3840
	s_waitcnt vmcnt(9)
	ds_write_b128 v217, v[226:229]
	s_waitcnt vmcnt(8)
	ds_write_b128 v216, v[230:233]
	ds_read_b128 v[160:163], v204 offset:36960
	ds_read_b128 v[164:167], v204 offset:41568
	ds_read_b128 v[168:171], v192 offset:96
	ds_read_b128 v[172:175], v192 offset:4704
	s_setprio 1
	s_waitcnt lgkmcnt(1)
	v_mfma_f32_32x32x16_bf16 v[112:127], v[168:171], v[160:163], v[112:127]
	v_mfma_f32_32x32x16_bf16 v[48:63], v[168:171], v[164:167], v[48:63]
	s_waitcnt lgkmcnt(0)
	v_mfma_f32_32x32x16_bf16 v[96:111], v[172:175], v[160:163], v[96:111]
	v_mfma_f32_32x32x16_bf16 v[32:47], v[172:175], v[164:167], v[32:47]
	ds_read_b128 v[168:171], v192 offset:9312
	ds_read_b128 v[172:175], v192 offset:13920
	s_waitcnt lgkmcnt(1)
	v_mfma_f32_32x32x16_bf16 v[80:95], v[168:171], v[160:163], v[80:95]
	v_mfma_f32_32x32x16_bf16 v[16:31], v[168:171], v[164:167], v[16:31]
	s_waitcnt lgkmcnt(0)
	v_mfma_f32_32x32x16_bf16 v[64:79], v[172:175], v[160:163], v[64:79]
	v_mfma_f32_32x32x16_bf16 v[0:15], v[172:175], v[164:167], v[0:15]
	s_setprio 0
	global_load_dwordx4 v[160:163], v[190:191], off offset:3968
	global_load_dwordx4 v[164:167], v[188:189], off offset:3968
	s_barrier
; template <bool trans>
; DI void gemm_core(const GTile& tl, const GTile& nx, bool has_next  , bool chain  , bool pre, u32x4 (&ra)[4], u32x4 (&rb)[4], char* smem, f32x16 (&acc)[2][4]) {
;     ...
;   const int nk = K / 64;
;   if (!pre) { G_LOAD(0); G_STORE(0); G_LOAD(1); }
;   for (int kt = 0; kt < nk; ++kt) {
;     __syncthreads();
;     G_COMPUTE(kt & 1, kt);
;   }
	s_waitcnt vmcnt(9)
	ds_write_b128 v215, v[176:179]
	s_waitcnt vmcnt(8)
	ds_write_b128 v215, v[180:183] offset:36864
	ds_read_b128 v[168:171], v208
	ds_read_b128 v[172:175], v208 offset:4608
	ds_read_b128 v[176:179], v205
	ds_read_b128 v[180:183], v205 offset:4608
	s_setprio 1
	s_waitcnt lgkmcnt(1)
	v_mfma_f32_32x32x16_bf16 v[112:127], v[176:179], v[168:171], v[112:127]
	v_mfma_f32_32x32x16_bf16 v[48:63], v[176:179], v[172:175], v[48:63]
	s_waitcnt lgkmcnt(0)
	v_mfma_f32_32x32x16_bf16 v[96:111], v[180:183], v[168:171], v[96:111]
	v_mfma_f32_32x32x16_bf16 v[32:47], v[180:183], v[172:175], v[32:47]
	ds_read_b128 v[176:179], v205 offset:9216
	ds_read_b128 v[180:183], v205 offset:13824
	s_waitcnt lgkmcnt(1)
	v_mfma_f32_32x32x16_bf16 v[80:95], v[176:179], v[168:171], v[80:95]
	v_mfma_f32_32x32x16_bf16 v[16:31], v[176:179], v[172:175], v[16:31]
	s_waitcnt lgkmcnt(0)
	v_mfma_f32_32x32x16_bf16 v[64:79], v[180:183], v[168:171], v[64:79]
	v_mfma_f32_32x32x16_bf16 v[0:15], v[180:183], v[172:175], v[0:15]
	s_setprio 0
	global_load_dwordx4 v[168:171], v[194:195], off offset:3968
	global_load_dwordx4 v[172:175], v[196:197], off offset:3968
	s_waitcnt vmcnt(9)
	ds_write_b128 v215, v[234:237] offset:9216
	s_waitcnt vmcnt(8)
	ds_write_b128 v215, v[238:241] offset:46080
	ds_read_b128 v[176:179], v208 offset:32
	ds_read_b128 v[180:183], v208 offset:4640
	ds_read_b128 v[188:191], v205 offset:32
	ds_read_b128 v[194:197], v205 offset:4640
	s_setprio 1
	s_waitcnt lgkmcnt(1)
	v_mfma_f32_32x32x16_bf16 v[112:127], v[188:191], v[176:179], v[112:127]
	v_mfma_f32_32x32x16_bf16 v[48:63], v[188:191], v[180:183], v[48:63]
	s_waitcnt lgkmcnt(0)
	v_mfma_f32_32x32x16_bf16 v[96:111], v[194:197], v[176:179], v[96:111]
	v_mfma_f32_32x32x16_bf16 v[32:47], v[194:197], v[180:183], v[32:47]
	ds_read_b128 v[188:191], v205 offset:9248
	ds_read_b128 v[194:197], v205 offset:13856
	s_waitcnt lgkmcnt(1)
	v_mfma_f32_32x32x16_bf16 v[80:95], v[188:191], v[176:179], v[80:95]
	v_mfma_f32_32x32x16_bf16 v[16:31], v[188:191], v[180:183], v[16:31]
	s_waitcnt lgkmcnt(0)
	v_mfma_f32_32x32x16_bf16 v[64:79], v[194:197], v[176:179], v[64:79]
	v_mfma_f32_32x32x16_bf16 v[0:15], v[194:197], v[180:183], v[0:15]
	s_setprio 0
	global_load_dwordx4 v[176:179], v[184:185], off offset:3968
	global_load_dwordx4 v[180:183], v[186:187], off offset:3968
	s_waitcnt vmcnt(9)
	ds_write_b128 v215, v[242:245] offset:18432
	s_waitcnt vmcnt(8)
	ds_write_b128 v215, v[246:249] offset:55296
	ds_read_b128 v[184:187], v208 offset:64
	ds_read_b128 v[188:191], v208 offset:4672
	ds_read_b128 v[194:197], v205 offset:64
	ds_read_b128 v[226:229], v205 offset:4672
	s_setprio 1
	s_waitcnt lgkmcnt(1)
	v_mfma_f32_32x32x16_bf16 v[112:127], v[194:197], v[184:187], v[112:127]
	v_mfma_f32_32x32x16_bf16 v[48:63], v[194:197], v[188:191], v[48:63]
	s_waitcnt lgkmcnt(0)
	v_mfma_f32_32x32x16_bf16 v[96:111], v[226:229], v[184:187], v[96:111]
	v_mfma_f32_32x32x16_bf16 v[32:47], v[226:229], v[188:191], v[32:47]
	ds_read_b128 v[194:197], v205 offset:9280
	ds_read_b128 v[226:229], v205 offset:13888
	s_waitcnt lgkmcnt(1)
	v_mfma_f32_32x32x16_bf16 v[80:95], v[194:197], v[184:187], v[80:95]
	v_mfma_f32_32x32x16_bf16 v[16:31], v[194:197], v[188:191], v[16:31]
	s_waitcnt lgkmcnt(0)
	v_mfma_f32_32x32x16_bf16 v[64:79], v[226:229], v[184:187], v[64:79]
	v_mfma_f32_32x32x16_bf16 v[0:15], v[226:229], v[188:191], v[0:15]
	s_setprio 0
	global_load_dwordx4 v[184:187], v[198:199], off offset:3968
	global_load_dwordx4 v[188:191], v[200:201], off offset:3968
	s_waitcnt vmcnt(9)
	ds_write_b128 v215, v[218:221] offset:27648
	s_waitcnt vmcnt(8)
	ds_write_b128 v215, v[222:225] offset:64512
	ds_read_b128 v[194:197], v208 offset:96
	ds_read_b128 v[198:201], v208 offset:4704
	ds_read_b128 v[218:221], v205 offset:96
	ds_read_b128 v[222:225], v205 offset:4704
	s_setprio 1
	s_waitcnt lgkmcnt(1)
	v_mfma_f32_32x32x16_bf16 v[112:127], v[218:221], v[194:197], v[112:127]
	v_mfma_f32_32x32x16_bf16 v[48:63], v[218:221], v[198:201], v[48:63]
	s_waitcnt lgkmcnt(0)
	v_mfma_f32_32x32x16_bf16 v[96:111], v[222:225], v[194:197], v[96:111]
	v_mfma_f32_32x32x16_bf16 v[32:47], v[222:225], v[198:201], v[32:47]
	ds_read_b128 v[218:221], v205 offset:9312
	ds_read_b128 v[222:225], v205 offset:13920
	s_waitcnt lgkmcnt(1)
	v_mfma_f32_32x32x16_bf16 v[80:95], v[218:221], v[194:197], v[80:95]
	v_mfma_f32_32x32x16_bf16 v[16:31], v[218:221], v[198:201], v[16:31]
	s_waitcnt lgkmcnt(0)
	v_mfma_f32_32x32x16_bf16 v[64:79], v[222:225], v[194:197], v[64:79]
	v_mfma_f32_32x32x16_bf16 v[0:15], v[222:225], v[198:201], v[0:15]
	s_setprio 0
	s_barrier
; template <bool trans>
; DI void gemm_core(const GTile& tl, const GTile& nx, bool has_next  , bool chain  , bool pre, u32x4 (&ra)[4], u32x4 (&rb)[4], char* smem, f32x16 (&acc)[2][4]) {
;     ...
;   const int nk = K / 64;
;   if (!pre) { G_LOAD(0); G_STORE(0); G_LOAD(1); }
;   for (int kt = 0; kt < nk; ++kt) {
;     __syncthreads();
;     G_COMPUTE(kt & 1, kt);
;   }
	s_waitcnt vmcnt(7)
	ds_write_b128 v209, v[160:163]
	s_waitcnt vmcnt(6)
	ds_write_b128 v210, v[164:167]
	ds_read_b128 v[194:197], v204 offset:36864
	ds_read_b128 v[198:201], v204 offset:41472
	ds_read_b128 v[218:221], v192
	ds_read_b128 v[222:225], v192 offset:4608
	s_setprio 1
	s_waitcnt lgkmcnt(1)
	v_mfma_f32_32x32x16_bf16 v[112:127], v[218:221], v[194:197], v[112:127]
	v_mfma_f32_32x32x16_bf16 v[48:63], v[218:221], v[198:201], v[48:63]
	s_waitcnt lgkmcnt(0)
	v_mfma_f32_32x32x16_bf16 v[96:111], v[222:225], v[194:197], v[96:111]
	v_mfma_f32_32x32x16_bf16 v[32:47], v[222:225], v[198:201], v[32:47]
	ds_read_b128 v[218:221], v192 offset:9216
	ds_read_b128 v[222:225], v192 offset:13824
	s_waitcnt lgkmcnt(1)
	v_mfma_f32_32x32x16_bf16 v[80:95], v[218:221], v[194:197], v[80:95]
	v_mfma_f32_32x32x16_bf16 v[16:31], v[218:221], v[198:201], v[16:31]
	s_waitcnt lgkmcnt(0)
	v_mfma_f32_32x32x16_bf16 v[64:79], v[222:225], v[194:197], v[64:79]
	v_mfma_f32_32x32x16_bf16 v[0:15], v[222:225], v[198:201], v[0:15]
	s_setprio 0
	s_waitcnt vmcnt(5)
	ds_write_b128 v212, v[168:171]
	s_waitcnt vmcnt(4)
	ds_write_b128 v211, v[172:175]
	ds_read_b128 v[194:197], v204 offset:36896
	ds_read_b128 v[198:201], v204 offset:41504
	ds_read_b128 v[218:221], v192 offset:32
	ds_read_b128 v[222:225], v192 offset:4640
	s_setprio 1
	s_waitcnt lgkmcnt(1)
	v_mfma_f32_32x32x16_bf16 v[112:127], v[218:221], v[194:197], v[112:127]
	v_mfma_f32_32x32x16_bf16 v[48:63], v[218:221], v[198:201], v[48:63]
	s_waitcnt lgkmcnt(0)
	v_mfma_f32_32x32x16_bf16 v[96:111], v[222:225], v[194:197], v[96:111]
	v_mfma_f32_32x32x16_bf16 v[32:47], v[222:225], v[198:201], v[32:47]
	ds_read_b128 v[218:221], v192 offset:9248
	ds_read_b128 v[222:225], v192 offset:13856
	s_waitcnt lgkmcnt(1)
	v_mfma_f32_32x32x16_bf16 v[80:95], v[218:221], v[194:197], v[80:95]
	v_mfma_f32_32x32x16_bf16 v[16:31], v[218:221], v[198:201], v[16:31]
	s_waitcnt lgkmcnt(0)
	v_mfma_f32_32x32x16_bf16 v[64:79], v[222:225], v[194:197], v[64:79]
	v_mfma_f32_32x32x16_bf16 v[0:15], v[222:225], v[198:201], v[0:15]
	s_setprio 0
	s_waitcnt vmcnt(3)
	ds_write_b128 v214, v[176:179]
	s_waitcnt vmcnt(2)
	ds_write_b128 v213, v[180:183]
	ds_read_b128 v[194:197], v204 offset:36928
	ds_read_b128 v[198:201], v204 offset:41536
	ds_read_b128 v[210:213], v192 offset:64
	ds_read_b128 v[218:221], v192 offset:4672
	s_setprio 1
	s_waitcnt lgkmcnt(1)
	v_mfma_f32_32x32x16_bf16 v[112:127], v[210:213], v[194:197], v[112:127]
	v_mfma_f32_32x32x16_bf16 v[48:63], v[210:213], v[198:201], v[48:63]
	s_waitcnt lgkmcnt(0)
	v_mfma_f32_32x32x16_bf16 v[96:111], v[218:221], v[194:197], v[96:111]
	v_mfma_f32_32x32x16_bf16 v[32:47], v[218:221], v[198:201], v[32:47]
	ds_read_b128 v[210:213], v192 offset:9280
	ds_read_b128 v[218:221], v192 offset:13888
	s_waitcnt lgkmcnt(1)
	v_mfma_f32_32x32x16_bf16 v[80:95], v[210:213], v[194:197], v[80:95]
	v_mfma_f32_32x32x16_bf16 v[16:31], v[210:213], v[198:201], v[16:31]
	s_waitcnt lgkmcnt(0)
	v_mfma_f32_32x32x16_bf16 v[64:79], v[218:221], v[194:197], v[64:79]
	v_mfma_f32_32x32x16_bf16 v[0:15], v[218:221], v[198:201], v[0:15]
	s_setprio 0
	s_waitcnt vmcnt(1)
	ds_write_b128 v217, v[184:187]
	s_waitcnt vmcnt(0)
	ds_write_b128 v216, v[188:191]
	ds_read_b128 v[194:197], v204 offset:36960
	ds_read_b128 v[198:201], v204 offset:41568
	ds_read_b128 v[210:213], v192 offset:96
	ds_read_b128 v[214:217], v192 offset:4704
	s_setprio 1
	s_waitcnt lgkmcnt(1)
	v_mfma_f32_32x32x16_bf16 v[112:127], v[210:213], v[194:197], v[112:127]
	v_mfma_f32_32x32x16_bf16 v[48:63], v[210:213], v[198:201], v[48:63]
	s_waitcnt lgkmcnt(0)
	v_mfma_f32_32x32x16_bf16 v[96:111], v[214:217], v[194:197], v[96:111]
	v_mfma_f32_32x32x16_bf16 v[32:47], v[214:217], v[198:201], v[32:47]
	ds_read_b128 v[210:213], v192 offset:9312
	ds_read_b128 v[214:217], v192 offset:13920
	s_waitcnt lgkmcnt(1)
	v_mfma_f32_32x32x16_bf16 v[80:95], v[210:213], v[194:197], v[80:95]
	v_mfma_f32_32x32x16_bf16 v[16:31], v[210:213], v[198:201], v[16:31]
	s_waitcnt lgkmcnt(0)
	v_mfma_f32_32x32x16_bf16 v[64:79], v[214:217], v[194:197], v[64:79]
	v_mfma_f32_32x32x16_bf16 v[0:15], v[214:217], v[198:201], v[0:15]
	s_setprio 0
	s_barrier
; template <bool trans>
; DI void gemm_core(const GTile& tl, const GTile& nx, bool has_next  , bool chain  , bool pre, u32x4 (&ra)[4], u32x4 (&rb)[4], char* smem, f32x16 (&acc)[2][4]) {
;     ...
;   const int nk = K / 64;
;   if (!pre) { G_LOAD(0); G_STORE(0); G_LOAD(1); }
;   for (int kt = 0; kt < nk; ++kt) {
;     __syncthreads();
;     G_COMPUTE(kt & 1, kt);
;   }
;   if (!has_next) __syncthreads();
	ds_read_b128 v[194:197], v208
	ds_read_b128 v[198:201], v208 offset:4608
	ds_read_b128 v[210:213], v205
	ds_read_b128 v[214:217], v205 offset:4608
	s_setprio 1
	s_waitcnt lgkmcnt(1)
	v_mfma_f32_32x32x16_bf16 v[112:127], v[210:213], v[194:197], v[112:127]
	v_mfma_f32_32x32x16_bf16 v[48:63], v[210:213], v[198:201], v[48:63]
	s_waitcnt lgkmcnt(0)
	v_mfma_f32_32x32x16_bf16 v[96:111], v[214:217], v[194:197], v[96:111]
	v_mfma_f32_32x32x16_bf16 v[32:47], v[214:217], v[198:201], v[32:47]
	ds_read_b128 v[210:213], v205 offset:9216
	ds_read_b128 v[214:217], v205 offset:13824
	s_waitcnt lgkmcnt(1)
	v_mfma_f32_32x32x16_bf16 v[80:95], v[210:213], v[194:197], v[80:95]
	v_mfma_f32_32x32x16_bf16 v[16:31], v[210:213], v[198:201], v[16:31]
	s_waitcnt lgkmcnt(0)
	v_mfma_f32_32x32x16_bf16 v[64:79], v[214:217], v[194:197], v[64:79]
	v_mfma_f32_32x32x16_bf16 v[0:15], v[214:217], v[198:201], v[0:15]
	s_setprio 0
	ds_read_b128 v[194:197], v208 offset:32
	ds_read_b128 v[198:201], v208 offset:4640
	ds_read_b128 v[210:213], v205 offset:32
	ds_read_b128 v[214:217], v205 offset:4640
	s_setprio 1
	s_waitcnt lgkmcnt(1)
	v_mfma_f32_32x32x16_bf16 v[112:127], v[210:213], v[194:197], v[112:127]
	v_mfma_f32_32x32x16_bf16 v[48:63], v[210:213], v[198:201], v[48:63]
	s_waitcnt lgkmcnt(0)
	v_mfma_f32_32x32x16_bf16 v[96:111], v[214:217], v[194:197], v[96:111]
	v_mfma_f32_32x32x16_bf16 v[32:47], v[214:217], v[198:201], v[32:47]
	ds_read_b128 v[210:213], v205 offset:9248
	ds_read_b128 v[214:217], v205 offset:13856
	s_waitcnt lgkmcnt(1)
	v_mfma_f32_32x32x16_bf16 v[80:95], v[210:213], v[194:197], v[80:95]
	v_mfma_f32_32x32x16_bf16 v[16:31], v[210:213], v[198:201], v[16:31]
	s_waitcnt lgkmcnt(0)
	v_mfma_f32_32x32x16_bf16 v[64:79], v[214:217], v[194:197], v[64:79]
	v_mfma_f32_32x32x16_bf16 v[0:15], v[214:217], v[198:201], v[0:15]
	s_setprio 0
	ds_read_b128 v[194:197], v208 offset:64
	ds_read_b128 v[198:201], v208 offset:4672
	ds_read_b128 v[210:213], v205 offset:64
	ds_read_b128 v[214:217], v205 offset:4672
	s_setprio 1
	s_waitcnt lgkmcnt(1)
	v_mfma_f32_32x32x16_bf16 v[112:127], v[210:213], v[194:197], v[112:127]
	v_mfma_f32_32x32x16_bf16 v[48:63], v[210:213], v[198:201], v[48:63]
	s_waitcnt lgkmcnt(0)
	v_mfma_f32_32x32x16_bf16 v[96:111], v[214:217], v[194:197], v[96:111]
	v_mfma_f32_32x32x16_bf16 v[32:47], v[214:217], v[198:201], v[32:47]
	ds_read_b128 v[210:213], v205 offset:9280
	ds_read_b128 v[214:217], v205 offset:13888
	s_waitcnt lgkmcnt(1)
	v_mfma_f32_32x32x16_bf16 v[80:95], v[210:213], v[194:197], v[80:95]
	v_mfma_f32_32x32x16_bf16 v[16:31], v[210:213], v[198:201], v[16:31]
	s_waitcnt lgkmcnt(0)
	v_mfma_f32_32x32x16_bf16 v[64:79], v[214:217], v[194:197], v[64:79]
	v_mfma_f32_32x32x16_bf16 v[0:15], v[214:217], v[198:201], v[0:15]
	s_setprio 0
	ds_read_b128 v[194:197], v208 offset:96
	ds_read_b128 v[198:201], v208 offset:4704
	ds_read_b128 v[208:211], v205 offset:96
	ds_read_b128 v[212:215], v205 offset:4704
	s_setprio 1
	s_waitcnt lgkmcnt(1)
	v_mfma_f32_32x32x16_bf16 v[112:127], v[208:211], v[194:197], v[112:127]
	v_mfma_f32_32x32x16_bf16 v[48:63], v[208:211], v[198:201], v[48:63]
	s_waitcnt lgkmcnt(0)
	v_mfma_f32_32x32x16_bf16 v[96:111], v[212:215], v[194:197], v[96:111]
	v_mfma_f32_32x32x16_bf16 v[32:47], v[212:215], v[198:201], v[32:47]
	ds_read_b128 v[208:211], v205 offset:9312
	ds_read_b128 v[212:215], v205 offset:13920
	s_waitcnt lgkmcnt(1)
	v_mfma_f32_32x32x16_bf16 v[80:95], v[208:211], v[194:197], v[80:95]
	v_mfma_f32_32x32x16_bf16 v[16:31], v[208:211], v[198:201], v[16:31]
	s_waitcnt lgkmcnt(0)
	v_mfma_f32_32x32x16_bf16 v[64:79], v[212:215], v[194:197], v[64:79]
	v_mfma_f32_32x32x16_bf16 v[0:15], v[212:215], v[198:201], v[0:15]
	s_setprio 0
	s_andn2_b64 vcc, exec, s[30:31]
	s_cbranch_vccnz .LBB0_884
	s_barrier

;   DI bf16_t* wt_in1() const { return (bf16_t*)(ws + OFF_WT_IN1); }
;   DI bf16_t* h() const { return (bf16_t*)(ws + OFF_H); }
;   DI bf16_t* vtd() const { return (bf16_t*)(ws + OFF_VTD); }
; DI int in1_nt(int t) { return (t >> 6) < 23 ? (t >> 6) : 25; }
; template <bool trans>
; DI void gemm_core(const GTile& tl, const GTile& nx, bool has_next  , bool chain  , bool pre, u32x4 (&ra)[4], u32x4 (&rb)[4], char* smem, f32x16 (&acc)[2][4]) {
;     ...
;   const int nk = K / 64;
;   if (!pre) { G_LOAD(0); G_STORE(0); G_LOAD(1); }
;   for (int kt = 0; kt < nk; ++kt) {
;     __syncthreads();
;     G_COMPUTE(kt & 1, kt);
;   }
; DI void phase_gemm_in1(const Params& p, char* smem) {
;     ...
;     const int mt = t & 63, nt = in1_nt(t), tn = t + gridDim.x;
;     const bool has_next = tn < 64 * 24;
;     const GTile tl{p.h(), D, p.wt_in1(), D, D, mt * 256, nt * 256}, nx{p.h(), D, p.wt_in1(), D, D, (tn & 63) * 256, in1_nt(tn) * 256};
;     WAVE_GEOM;
;     const bool trans = nt >= 17 && nt < 21;
;     const int mbase = mt * 256 + wm_ * 128, nbase = nt * 256 + wn_ * 64;
;     if (trans) { f32x16 acc[2][4]; gemm_core<true>(tl, nx, has_next, false, pre, ra, rb, smem, acc); EpiVt e{p.vtd(), 8, 128, 4352, nullptr, 0}; e(acc, mbase, nbase, l32_, g_); }
;     else { f32x16 acc[2][4]; gemm_core<false>(tl, nx, has_next, has_next, pre, ra, rb, smem, acc);
.LBB0_890:
	v_lshl_add_u64 v[136:137], s[2:3], 0, v[192:193]
	v_lshl_add_u64 v[138:139], s[16:17], 0, v[192:193]
	s_waitcnt lgkmcnt(0)
	s_barrier
	global_load_dwordx4 v[184:187], v[136:137], off offset:256
	global_load_dwordx4 v[188:191], v[138:139], off offset:256
	s_ashr_i32 s2, s56, 6
	s_lshl_b32 s3, s2, 8
	s_cmp_lt_i32 s2, 23
	s_cselect_b32 s2, s3, 0x1900
	s_and_b32 s3, s49, 0x1f80000
	s_and_b32 s16, s18, 0xc0
	s_lshl_b32 s3, s3, 1
	s_add_u32 s6, s24, s3
	s_addc_u32 s7, s25, 0
	s_ashr_i32 s3, s2, 31
	s_lshl_b64 s[2:3], s[2:3], 12
	s_add_u32 s2, s27, s2
	s_addc_u32 s3, s40, s3
	s_lshr_b32 s17, s18, 1
	v_and_b32_e32 v11, 31, v8
	s_and_b32 s17, s17, 0xfffff80
	v_or_b32_e32 v12, s17, v11
	v_or_b32_e32 v11, s16, v11
	v_add3_u32 v148, 16, v10, v9
	v_lshrrev_b32_e32 v8, 1, v8
	v_mul_u32_u24_e32 v150, 0x90, v11
	v_lshl_add_u64 v[130:131], s[6:7], 0, v[192:193]
	v_lshl_add_u64 v[128:129], s[2:3], 0, v[192:193]
	v_and_b32_e32 v204, 16, v8
	v_add_u32_e32 v192, 0x12000, v148
	v_mul_lo_u32 v149, v12, s54
	v_add3_u32 v152, 16, v150, v204
	v_add_u32_e32 v159, 0x1b000, v148
	ds_write_b128 v192, v[0:3]
	s_waitcnt vmcnt(5)
	ds_write_b128 v159, v[4:7]
	v_add3_u32 v151, 16, v149, v204
	ds_read_b128 v[0:3], v152 offset:36864
	ds_read_b128 v[16:19], v152 offset:41472
	ds_read_b128 v[4:7], v151
	ds_read_b128 v[8:11], v151 offset:4608
	v_lshl_add_u64 v[140:141], v[136:137], 0, s[12:13]
	v_lshl_add_u64 v[142:143], v[138:139], 0, s[12:13]
	v_lshl_add_u64 v[132:133], v[136:137], 0, s[14:15]
	v_lshl_add_u64 v[134:135], v[138:139], 0, s[14:15]
	s_setprio 1
	s_waitcnt lgkmcnt(1)
	v_mfma_f32_32x32x16_bf16 v[96:111], v[0:3], v[4:7], 0
	v_mfma_f32_32x32x16_bf16 v[112:127], v[16:19], v[4:7], 0
	ds_read_b128 v[4:7], v151 offset:9216
	ds_read_b128 v[20:23], v151 offset:13824
	s_waitcnt lgkmcnt(2)
	v_mfma_f32_32x32x16_bf16 v[64:79], v[0:3], v[8:11], 0
	v_mfma_f32_32x32x16_bf16 v[80:95], v[16:19], v[8:11], 0
	s_waitcnt lgkmcnt(1)
	v_mfma_f32_32x32x16_bf16 v[32:47], v[0:3], v[4:7], 0
	v_mfma_f32_32x32x16_bf16 v[48:63], v[16:19], v[4:7], 0
	s_waitcnt lgkmcnt(0)
	v_mfma_f32_32x32x16_bf16 v[0:15], v[0:3], v[20:23], 0
	v_mfma_f32_32x32x16_bf16 v[16:31], v[16:19], v[20:23], 0
	s_setprio 0
	global_load_dwordx4 v[194:197], v[140:141], off offset:256
	global_load_dwordx4 v[198:201], v[142:143], off offset:256
	v_add_u32_e32 v158, 0x14400, v148
	v_add_u32_e32 v157, 0x1d400, v148
	ds_write_b128 v158, v[176:179]
	s_waitcnt vmcnt(6)
	ds_write_b128 v157, v[180:183]
	ds_read_b128 v[144:147], v152 offset:36896
	ds_read_b128 v[176:179], v152 offset:41504
	ds_read_b128 v[180:183], v151 offset:32
	ds_read_b128 v[208:211], v151 offset:4640
	s_setprio 1
	s_waitcnt lgkmcnt(1)
	v_mfma_f32_32x32x16_bf16 v[96:111], v[144:147], v[180:183], v[96:111]
	v_mfma_f32_32x32x16_bf16 v[112:127], v[176:179], v[180:183], v[112:127]
	s_waitcnt lgkmcnt(0)
	v_mfma_f32_32x32x16_bf16 v[64:79], v[144:147], v[208:211], v[64:79]
	v_mfma_f32_32x32x16_bf16 v[80:95], v[176:179], v[208:211], v[80:95]
	ds_read_b128 v[180:183], v151 offset:9248
	ds_read_b128 v[208:211], v151 offset:13856
	s_waitcnt lgkmcnt(1)
	v_mfma_f32_32x32x16_bf16 v[32:47], v[144:147], v[180:183], v[32:47]
	v_mfma_f32_32x32x16_bf16 v[48:63], v[176:179], v[180:183], v[48:63]
	s_waitcnt lgkmcnt(0)
	v_mfma_f32_32x32x16_bf16 v[0:15], v[144:147], v[208:211], v[0:15]
	v_mfma_f32_32x32x16_bf16 v[16:31], v[176:179], v[208:211], v[16:31]
	s_setprio 0
	global_load_dwordx4 v[176:179], v[132:133], off offset:256
	global_load_dwordx4 v[180:183], v[134:135], off offset:256
	v_add_u32_e32 v154, 0x16800, v148
	v_add_u32_e32 v153, 0x1f800, v148
	ds_write_b128 v154, v[168:171]
	s_waitcnt vmcnt(7)
	ds_write_b128 v153, v[172:175]
	ds_read_b128 v[144:147], v152 offset:36928
	ds_read_b128 v[168:171], v152 offset:41536
	ds_read_b128 v[172:175], v151 offset:64
	ds_read_b128 v[208:211], v151 offset:4672
	s_setprio 1
	s_waitcnt lgkmcnt(1)
	v_mfma_f32_32x32x16_bf16 v[96:111], v[144:147], v[172:175], v[96:111]
	v_mfma_f32_32x32x16_bf16 v[112:127], v[168:171], v[172:175], v[112:127]
	s_waitcnt lgkmcnt(0)
	v_mfma_f32_32x32x16_bf16 v[64:79], v[144:147], v[208:211], v[64:79]
	v_mfma_f32_32x32x16_bf16 v[80:95], v[168:171], v[208:211], v[80:95]
	ds_read_b128 v[172:175], v151 offset:9280
	ds_read_b128 v[208:211], v151 offset:13888
	s_waitcnt lgkmcnt(1)
	v_mfma_f32_32x32x16_bf16 v[32:47], v[144:147], v[172:175], v[32:47]
	v_mfma_f32_32x32x16_bf16 v[48:63], v[168:171], v[172:175], v[48:63]
	s_waitcnt lgkmcnt(0)
	v_mfma_f32_32x32x16_bf16 v[0:15], v[144:147], v[208:211], v[0:15]
	v_mfma_f32_32x32x16_bf16 v[16:31], v[168:171], v[208:211], v[16:31]
	s_setprio 0
	v_add_co_u32_e32 v144, vcc, s53, v136
	v_add_u32_e32 v156, 0x18c00, v148
	s_nop 0
	v_addc_co_u32_e32 v145, vcc, 0, v137, vcc
	v_add_co_u32_e32 v146, vcc, s53, v138
	v_add_u32_e32 v155, 0x21c00, v148
	s_nop 0
	v_addc_co_u32_e32 v147, vcc, 0, v139, vcc
	global_load_dwordx4 v[168:171], v[144:145], off offset:256
	global_load_dwordx4 v[172:175], v[146:147], off offset:256
	ds_write_b128 v156, v[160:163]
	s_waitcnt vmcnt(8)
	ds_write_b128 v155, v[164:167]
	ds_read_b128 v[160:163], v152 offset:36960
	ds_read_b128 v[164:167], v152 offset:41568
	ds_read_b128 v[208:211], v151 offset:96
	ds_read_b128 v[212:215], v151 offset:4704
	s_setprio 1
	s_waitcnt lgkmcnt(1)
	v_mfma_f32_32x32x16_bf16 v[96:111], v[160:163], v[208:211], v[96:111]
	v_mfma_f32_32x32x16_bf16 v[112:127], v[164:167], v[208:211], v[112:127]
	s_waitcnt lgkmcnt(0)
	v_mfma_f32_32x32x16_bf16 v[64:79], v[160:163], v[212:215], v[64:79]
	v_mfma_f32_32x32x16_bf16 v[80:95], v[164:167], v[212:215], v[80:95]
	ds_read_b128 v[208:211], v151 offset:9312
	ds_read_b128 v[212:215], v151 offset:13920
	s_waitcnt lgkmcnt(1)
	v_mfma_f32_32x32x16_bf16 v[32:47], v[160:163], v[208:211], v[32:47]
	v_mfma_f32_32x32x16_bf16 v[48:63], v[164:167], v[208:211], v[48:63]
	s_waitcnt lgkmcnt(0)
	v_mfma_f32_32x32x16_bf16 v[0:15], v[160:163], v[212:215], v[0:15]
	v_mfma_f32_32x32x16_bf16 v[16:31], v[164:167], v[212:215], v[16:31]
	s_setprio 0
	global_load_dwordx4 v[160:163], v[136:137], off offset:384
	global_load_dwordx4 v[164:167], v[138:139], off offset:384
	s_barrier
; template <bool trans>
; DI void gemm_core(const GTile& tl, const GTile& nx, bool has_next  , bool chain  , bool pre, u32x4 (&ra)[4], u32x4 (&rb)[4], char* smem, f32x16 (&acc)[2][4]) {
;     ...
;   const int nk = K / 64;
;   if (!pre) { G_LOAD(0); G_STORE(0); G_LOAD(1); }
;   for (int kt = 0; kt < nk; ++kt) {
;     __syncthreads();
;     G_COMPUTE(kt & 1, kt);
;   }
	s_add_i32 s2, 16, 0x12000
	v_add3_u32 v149, s2, v149, v204
	s_add_i32 s2, 16, 0x1b000
	v_add3_u32 v150, s2, v150, v204
	s_waitcnt vmcnt(9)
	ds_write_b128 v148, v[184:187]
	s_waitcnt vmcnt(8)
	ds_write_b128 v148, v[188:191] offset:36864
	ds_read_b128 v[184:187], v150
	ds_read_b128 v[188:191], v150 offset:4608
	ds_read_b128 v[208:211], v149
	ds_read_b128 v[212:215], v149 offset:4608
	s_setprio 1
	s_waitcnt lgkmcnt(1)
	v_mfma_f32_32x32x16_bf16 v[96:111], v[184:187], v[208:211], v[96:111]
	v_mfma_f32_32x32x16_bf16 v[112:127], v[188:191], v[208:211], v[112:127]
	s_waitcnt lgkmcnt(0)
	v_mfma_f32_32x32x16_bf16 v[64:79], v[184:187], v[212:215], v[64:79]
	v_mfma_f32_32x32x16_bf16 v[80:95], v[188:191], v[212:215], v[80:95]
	ds_read_b128 v[208:211], v149 offset:9216
	ds_read_b128 v[212:215], v149 offset:13824
	s_waitcnt lgkmcnt(1)
	v_mfma_f32_32x32x16_bf16 v[32:47], v[184:187], v[208:211], v[32:47]
	v_mfma_f32_32x32x16_bf16 v[48:63], v[188:191], v[208:211], v[48:63]
	s_waitcnt lgkmcnt(0)
	v_mfma_f32_32x32x16_bf16 v[0:15], v[184:187], v[212:215], v[0:15]
	v_mfma_f32_32x32x16_bf16 v[16:31], v[188:191], v[212:215], v[16:31]
	s_setprio 0
	global_load_dwordx4 v[184:187], v[140:141], off offset:384
	global_load_dwordx4 v[188:191], v[142:143], off offset:384
	s_waitcnt vmcnt(9)
	ds_write_b128 v148, v[194:197] offset:9216
	s_waitcnt vmcnt(8)
	ds_write_b128 v148, v[198:201] offset:46080
	ds_read_b128 v[194:197], v150 offset:32
	ds_read_b128 v[198:201], v150 offset:4640
	ds_read_b128 v[208:211], v149 offset:32
	ds_read_b128 v[212:215], v149 offset:4640
	s_setprio 1
	s_waitcnt lgkmcnt(1)
	v_mfma_f32_32x32x16_bf16 v[96:111], v[194:197], v[208:211], v[96:111]
	v_mfma_f32_32x32x16_bf16 v[112:127], v[198:201], v[208:211], v[112:127]
	s_waitcnt lgkmcnt(0)
	v_mfma_f32_32x32x16_bf16 v[64:79], v[194:197], v[212:215], v[64:79]
	v_mfma_f32_32x32x16_bf16 v[80:95], v[198:201], v[212:215], v[80:95]
	ds_read_b128 v[208:211], v149 offset:9248
	ds_read_b128 v[212:215], v149 offset:13856
	s_waitcnt lgkmcnt(1)
	v_mfma_f32_32x32x16_bf16 v[32:47], v[194:197], v[208:211], v[32:47]
	v_mfma_f32_32x32x16_bf16 v[48:63], v[198:201], v[208:211], v[48:63]
	s_waitcnt lgkmcnt(0)
	v_mfma_f32_32x32x16_bf16 v[0:15], v[194:197], v[212:215], v[0:15]
	v_mfma_f32_32x32x16_bf16 v[16:31], v[198:201], v[212:215], v[16:31]
	s_setprio 0
	global_load_dwordx4 v[194:197], v[132:133], off offset:384
	global_load_dwordx4 v[198:201], v[134:135], off offset:384
	s_waitcnt vmcnt(9)
	ds_write_b128 v148, v[176:179] offset:18432
	s_waitcnt vmcnt(8)
	ds_write_b128 v148, v[180:183] offset:55296
	ds_read_b128 v[176:179], v150 offset:64
	ds_read_b128 v[180:183], v150 offset:4672
	ds_read_b128 v[208:211], v149 offset:64
	ds_read_b128 v[212:215], v149 offset:4672
	s_setprio 1
	s_waitcnt lgkmcnt(1)
	v_mfma_f32_32x32x16_bf16 v[96:111], v[176:179], v[208:211], v[96:111]
	v_mfma_f32_32x32x16_bf16 v[112:127], v[180:183], v[208:211], v[112:127]
	s_waitcnt lgkmcnt(0)
	v_mfma_f32_32x32x16_bf16 v[64:79], v[176:179], v[212:215], v[64:79]
	v_mfma_f32_32x32x16_bf16 v[80:95], v[180:183], v[212:215], v[80:95]
	ds_read_b128 v[208:211], v149 offset:9280
	ds_read_b128 v[212:215], v149 offset:13888
	s_waitcnt lgkmcnt(1)
	v_mfma_f32_32x32x16_bf16 v[32:47], v[176:179], v[208:211], v[32:47]
	v_mfma_f32_32x32x16_bf16 v[48:63], v[180:183], v[208:211], v[48:63]
	s_waitcnt lgkmcnt(0)
	v_mfma_f32_32x32x16_bf16 v[0:15], v[176:179], v[212:215], v[0:15]
	v_mfma_f32_32x32x16_bf16 v[16:31], v[180:183], v[212:215], v[16:31]
	s_setprio 0
	global_load_dwordx4 v[176:179], v[144:145], off offset:384
	global_load_dwordx4 v[180:183], v[146:147], off offset:384
	s_waitcnt vmcnt(9)
	ds_write_b128 v148, v[168:171] offset:27648
	s_waitcnt vmcnt(8)
	ds_write_b128 v148, v[172:175] offset:64512
	ds_read_b128 v[168:171], v150 offset:96
	ds_read_b128 v[172:175], v150 offset:4704
	ds_read_b128 v[208:211], v149 offset:96
	ds_read_b128 v[212:215], v149 offset:4704
	s_setprio 1
	s_waitcnt lgkmcnt(1)
	v_mfma_f32_32x32x16_bf16 v[96:111], v[168:171], v[208:211], v[96:111]
	v_mfma_f32_32x32x16_bf16 v[112:127], v[172:175], v[208:211], v[112:127]
	s_waitcnt lgkmcnt(0)
	v_mfma_f32_32x32x16_bf16 v[64:79], v[168:171], v[212:215], v[64:79]
	v_mfma_f32_32x32x16_bf16 v[80:95], v[172:175], v[212:215], v[80:95]
	ds_read_b128 v[208:211], v149 offset:9312
	ds_read_b128 v[212:215], v149 offset:13920
	s_waitcnt lgkmcnt(1)
	v_mfma_f32_32x32x16_bf16 v[32:47], v[168:171], v[208:211], v[32:47]
	v_mfma_f32_32x32x16_bf16 v[48:63], v[172:175], v[208:211], v[48:63]
	s_waitcnt lgkmcnt(0)
	v_mfma_f32_32x32x16_bf16 v[0:15], v[168:171], v[212:215], v[0:15]
	v_mfma_f32_32x32x16_bf16 v[16:31], v[172:175], v[212:215], v[16:31]
	s_setprio 0
	global_load_dwordx4 v[168:171], v[136:137], off offset:512
	global_load_dwordx4 v[172:175], v[138:139], off offset:512
	s_barrier
; template <bool trans>
; DI void gemm_core(const GTile& tl, const GTile& nx, bool has_next  , bool chain  , bool pre, u32x4 (&ra)[4], u32x4 (&rb)[4], char* smem, f32x16 (&acc)[2][4]) {
;     ...
;   const int nk = K / 64;
;   if (!pre) { G_LOAD(0); G_STORE(0); G_LOAD(1); }
;   for (int kt = 0; kt < nk; ++kt) {
;     __syncthreads();
;     G_COMPUTE(kt & 1, kt);
;   }
	s_waitcnt vmcnt(9)
	ds_write_b128 v192, v[160:163]
	s_waitcnt vmcnt(8)
	ds_write_b128 v159, v[164:167]
	ds_read_b128 v[160:163], v152 offset:36864
	ds_read_b128 v[164:167], v152 offset:41472
	ds_read_b128 v[208:211], v151
	ds_read_b128 v[212:215], v151 offset:4608
	s_setprio 1
	s_waitcnt lgkmcnt(1)
	v_mfma_f32_32x32x16_bf16 v[96:111], v[160:163], v[208:211], v[96:111]
	v_mfma_f32_32x32x16_bf16 v[112:127], v[164:167], v[208:211], v[112:127]
	s_waitcnt lgkmcnt(0)
	v_mfma_f32_32x32x16_bf16 v[64:79], v[160:163], v[212:215], v[64:79]
	v_mfma_f32_32x32x16_bf16 v[80:95], v[164:167], v[212:215], v[80:95]
	ds_read_b128 v[208:211], v151 offset:9216
	ds_read_b128 v[212:215], v151 offset:13824
	s_waitcnt vmcnt(7)
	ds_write_b128 v158, v[184:187]
	s_waitcnt vmcnt(6)
	ds_write_b128 v157, v[188:191]
	ds_read_b128 v[184:187], v152 offset:36896
	ds_read_b128 v[188:191], v152 offset:41504
	s_waitcnt lgkmcnt(5)
	v_mfma_f32_32x32x16_bf16 v[32:47], v[160:163], v[208:211], v[32:47]
	v_mfma_f32_32x32x16_bf16 v[48:63], v[164:167], v[208:211], v[48:63]
	ds_read_b128 v[208:211], v151 offset:32
	s_waitcnt lgkmcnt(5)
	v_mfma_f32_32x32x16_bf16 v[0:15], v[160:163], v[212:215], v[0:15]
	v_mfma_f32_32x32x16_bf16 v[16:31], v[164:167], v[212:215], v[16:31]
	ds_read_b128 v[212:215], v151 offset:4640
	s_setprio 0
	global_load_dwordx4 v[160:163], v[140:141], off offset:512
	global_load_dwordx4 v[164:167], v[142:143], off offset:512
	s_setprio 1
	s_waitcnt lgkmcnt(1)
	v_mfma_f32_32x32x16_bf16 v[96:111], v[184:187], v[208:211], v[96:111]
	v_mfma_f32_32x32x16_bf16 v[112:127], v[188:191], v[208:211], v[112:127]
	s_waitcnt lgkmcnt(0)
	v_mfma_f32_32x32x16_bf16 v[64:79], v[184:187], v[212:215], v[64:79]
	v_mfma_f32_32x32x16_bf16 v[80:95], v[188:191], v[212:215], v[80:95]
	ds_read_b128 v[208:211], v151 offset:9248
	ds_read_b128 v[212:215], v151 offset:13856
	s_waitcnt vmcnt(7)
	ds_write_b128 v154, v[194:197]
	s_waitcnt vmcnt(6)
	ds_write_b128 v153, v[198:201]
	ds_read_b128 v[194:197], v152 offset:36928
	ds_read_b128 v[198:201], v152 offset:41536
	s_waitcnt lgkmcnt(5)
	v_mfma_f32_32x32x16_bf16 v[32:47], v[184:187], v[208:211], v[32:47]
	v_mfma_f32_32x32x16_bf16 v[48:63], v[188:191], v[208:211], v[48:63]
	ds_read_b128 v[208:211], v151 offset:64
	s_waitcnt lgkmcnt(5)
	v_mfma_f32_32x32x16_bf16 v[0:15], v[184:187], v[212:215], v[0:15]
	v_mfma_f32_32x32x16_bf16 v[16:31], v[188:191], v[212:215], v[16:31]
	ds_read_b128 v[212:215], v151 offset:4672
	s_setprio 0
	global_load_dwordx4 v[184:187], v[132:133], off offset:512
	global_load_dwordx4 v[188:191], v[134:135], off offset:512
	s_setprio 1
	s_waitcnt lgkmcnt(1)
	v_mfma_f32_32x32x16_bf16 v[96:111], v[194:197], v[208:211], v[96:111]
	v_mfma_f32_32x32x16_bf16 v[112:127], v[198:201], v[208:211], v[112:127]
	s_waitcnt lgkmcnt(0)
	v_mfma_f32_32x32x16_bf16 v[64:79], v[194:197], v[212:215], v[64:79]
	v_mfma_f32_32x32x16_bf16 v[80:95], v[198:201], v[212:215], v[80:95]
	ds_read_b128 v[208:211], v151 offset:9280
	ds_read_b128 v[212:215], v151 offset:13888
	s_waitcnt vmcnt(7)
	ds_write_b128 v156, v[176:179]
	s_waitcnt vmcnt(6)
	ds_write_b128 v155, v[180:183]
	ds_read_b128 v[176:179], v152 offset:36960
	ds_read_b128 v[180:183], v152 offset:41568
	s_waitcnt lgkmcnt(5)
	v_mfma_f32_32x32x16_bf16 v[32:47], v[194:197], v[208:211], v[32:47]
	v_mfma_f32_32x32x16_bf16 v[48:63], v[198:201], v[208:211], v[48:63]
	ds_read_b128 v[208:211], v151 offset:96
	s_waitcnt lgkmcnt(5)
	v_mfma_f32_32x32x16_bf16 v[0:15], v[194:197], v[212:215], v[0:15]
	v_mfma_f32_32x32x16_bf16 v[16:31], v[198:201], v[212:215], v[16:31]
	ds_read_b128 v[212:215], v151 offset:4704
	s_setprio 0
	global_load_dwordx4 v[194:197], v[144:145], off offset:512
	global_load_dwordx4 v[198:201], v[146:147], off offset:512
	s_setprio 1
	s_waitcnt lgkmcnt(1)
	v_mfma_f32_32x32x16_bf16 v[96:111], v[176:179], v[208:211], v[96:111]
	v_mfma_f32_32x32x16_bf16 v[112:127], v[180:183], v[208:211], v[112:127]
	s_waitcnt lgkmcnt(0)
	v_mfma_f32_32x32x16_bf16 v[64:79], v[176:179], v[212:215], v[64:79]
	v_mfma_f32_32x32x16_bf16 v[80:95], v[180:183], v[212:215], v[80:95]
	ds_read_b128 v[208:211], v151 offset:9312
	ds_read_b128 v[212:215], v151 offset:13920
	s_waitcnt lgkmcnt(0)
	s_barrier
	s_waitcnt vmcnt(7)
	ds_write_b128 v148, v[168:171]
	s_waitcnt vmcnt(6)
	ds_write_b128 v148, v[172:175] offset:36864
	ds_read_b128 v[168:171], v150
	ds_read_b128 v[172:175], v150 offset:4608
	v_mfma_f32_32x32x16_bf16 v[32:47], v[176:179], v[208:211], v[32:47]
	v_mfma_f32_32x32x16_bf16 v[48:63], v[180:183], v[208:211], v[48:63]
	ds_read_b128 v[208:211], v149
	v_mfma_f32_32x32x16_bf16 v[0:15], v[176:179], v[212:215], v[0:15]
	v_mfma_f32_32x32x16_bf16 v[16:31], v[180:183], v[212:215], v[16:31]
	ds_read_b128 v[212:215], v149 offset:4608
	s_setprio 0
	global_load_dwordx4 v[176:179], v[136:137], off offset:640
	global_load_dwordx4 v[180:183], v[138:139], off offset:640
	s_setprio 1
	s_waitcnt lgkmcnt(1)
	v_mfma_f32_32x32x16_bf16 v[96:111], v[168:171], v[208:211], v[96:111]
	v_mfma_f32_32x32x16_bf16 v[112:127], v[172:175], v[208:211], v[112:127]
	s_waitcnt lgkmcnt(0)
	v_mfma_f32_32x32x16_bf16 v[64:79], v[168:171], v[212:215], v[64:79]
	v_mfma_f32_32x32x16_bf16 v[80:95], v[172:175], v[212:215], v[80:95]
	ds_read_b128 v[208:211], v149 offset:9216
	ds_read_b128 v[212:215], v149 offset:13824
	s_waitcnt vmcnt(7)
	ds_write_b128 v148, v[160:163] offset:9216
	s_waitcnt vmcnt(6)
	ds_write_b128 v148, v[164:167] offset:46080
	ds_read_b128 v[160:163], v150 offset:32
	ds_read_b128 v[164:167], v150 offset:4640
	s_waitcnt lgkmcnt(5)
	v_mfma_f32_32x32x16_bf16 v[32:47], v[168:171], v[208:211], v[32:47]
	v_mfma_f32_32x32x16_bf16 v[48:63], v[172:175], v[208:211], v[48:63]
	ds_read_b128 v[208:211], v149 offset:32
	s_waitcnt lgkmcnt(5)
; template <bool trans>
; DI void gemm_core(const GTile& tl, const GTile& nx, bool has_next  , bool chain  , bool pre, u32x4 (&ra)[4], u32x4 (&rb)[4], char* smem, f32x16 (&acc)[2][4]) {
;     ...
;   const int nk = K / 64;
;   if (!pre) { G_LOAD(0); G_STORE(0); G_LOAD(1); }
;   for (int kt = 0; kt < nk; ++kt) {
;     __syncthreads();
;     G_COMPUTE(kt & 1, kt);
;   }
	v_mfma_f32_32x32x16_bf16 v[0:15], v[168:171], v[212:215], v[0:15]
	v_mfma_f32_32x32x16_bf16 v[16:31], v[172:175], v[212:215], v[16:31]
	ds_read_b128 v[212:215], v149 offset:4640
	s_setprio 0
	global_load_dwordx4 v[168:171], v[140:141], off offset:640
	global_load_dwordx4 v[172:175], v[142:143], off offset:640
	s_setprio 1
	s_waitcnt lgkmcnt(1)
	v_mfma_f32_32x32x16_bf16 v[96:111], v[160:163], v[208:211], v[96:111]
	v_mfma_f32_32x32x16_bf16 v[112:127], v[164:167], v[208:211], v[112:127]
	s_waitcnt lgkmcnt(0)
	v_mfma_f32_32x32x16_bf16 v[64:79], v[160:163], v[212:215], v[64:79]
	v_mfma_f32_32x32x16_bf16 v[80:95], v[164:167], v[212:215], v[80:95]
	ds_read_b128 v[208:211], v149 offset:9248
	ds_read_b128 v[212:215], v149 offset:13856
	s_waitcnt vmcnt(7)
	ds_write_b128 v148, v[184:187] offset:18432
	s_waitcnt vmcnt(6)
	ds_write_b128 v148, v[188:191] offset:55296
	ds_read_b128 v[184:187], v150 offset:64
	ds_read_b128 v[188:191], v150 offset:4672
	s_waitcnt lgkmcnt(5)
	v_mfma_f32_32x32x16_bf16 v[32:47], v[160:163], v[208:211], v[32:47]
	v_mfma_f32_32x32x16_bf16 v[48:63], v[164:167], v[208:211], v[48:63]
	ds_read_b128 v[208:211], v149 offset:64
	s_waitcnt lgkmcnt(5)
	v_mfma_f32_32x32x16_bf16 v[0:15], v[160:163], v[212:215], v[0:15]
	v_mfma_f32_32x32x16_bf16 v[16:31], v[164:167], v[212:215], v[16:31]
	ds_read_b128 v[212:215], v149 offset:4672
	s_setprio 0
	global_load_dwordx4 v[160:163], v[132:133], off offset:640
	global_load_dwordx4 v[164:167], v[134:135], off offset:640
	s_setprio 1
	s_waitcnt lgkmcnt(1)
	v_mfma_f32_32x32x16_bf16 v[96:111], v[184:187], v[208:211], v[96:111]
	v_mfma_f32_32x32x16_bf16 v[112:127], v[188:191], v[208:211], v[112:127]
	s_waitcnt lgkmcnt(0)
	v_mfma_f32_32x32x16_bf16 v[64:79], v[184:187], v[212:215], v[64:79]
	v_mfma_f32_32x32x16_bf16 v[80:95], v[188:191], v[212:215], v[80:95]
	ds_read_b128 v[208:211], v149 offset:9280
	ds_read_b128 v[212:215], v149 offset:13888
	s_waitcnt vmcnt(7)
	ds_write_b128 v148, v[194:197] offset:27648
	s_waitcnt vmcnt(6)
	ds_write_b128 v148, v[198:201] offset:64512
	ds_read_b128 v[194:197], v150 offset:96
	ds_read_b128 v[198:201], v150 offset:4704
	s_waitcnt lgkmcnt(5)
	v_mfma_f32_32x32x16_bf16 v[32:47], v[184:187], v[208:211], v[32:47]
	v_mfma_f32_32x32x16_bf16 v[48:63], v[188:191], v[208:211], v[48:63]
	ds_read_b128 v[208:211], v149 offset:96
	s_waitcnt lgkmcnt(5)
	v_mfma_f32_32x32x16_bf16 v[0:15], v[184:187], v[212:215], v[0:15]
	v_mfma_f32_32x32x16_bf16 v[16:31], v[188:191], v[212:215], v[16:31]
	ds_read_b128 v[212:215], v149 offset:4704
	s_setprio 0
	global_load_dwordx4 v[184:187], v[144:145], off offset:640
	global_load_dwordx4 v[188:191], v[146:147], off offset:640
	s_setprio 1
	s_waitcnt lgkmcnt(1)
	v_mfma_f32_32x32x16_bf16 v[96:111], v[194:197], v[208:211], v[96:111]
	v_mfma_f32_32x32x16_bf16 v[112:127], v[198:201], v[208:211], v[112:127]
	s_waitcnt lgkmcnt(0)
	v_mfma_f32_32x32x16_bf16 v[64:79], v[194:197], v[212:215], v[64:79]
	v_mfma_f32_32x32x16_bf16 v[80:95], v[198:201], v[212:215], v[80:95]
	ds_read_b128 v[208:211], v149 offset:9312
	ds_read_b128 v[212:215], v149 offset:13920
	s_waitcnt lgkmcnt(0)
	s_barrier
	s_waitcnt vmcnt(7)
	ds_write_b128 v192, v[176:179]
	s_waitcnt vmcnt(6)
	ds_write_b128 v159, v[180:183]
	ds_read_b128 v[176:179], v152 offset:36864
	ds_read_b128 v[180:183], v152 offset:41472
	v_mfma_f32_32x32x16_bf16 v[32:47], v[194:197], v[208:211], v[32:47]
	v_mfma_f32_32x32x16_bf16 v[48:63], v[198:201], v[208:211], v[48:63]
	ds_read_b128 v[208:211], v151
	v_mfma_f32_32x32x16_bf16 v[0:15], v[194:197], v[212:215], v[0:15]
	v_mfma_f32_32x32x16_bf16 v[16:31], v[198:201], v[212:215], v[16:31]
	ds_read_b128 v[212:215], v151 offset:4608
	s_setprio 0
	global_load_dwordx4 v[194:197], v[136:137], off offset:768
	global_load_dwordx4 v[198:201], v[138:139], off offset:768
	s_setprio 1
	s_waitcnt lgkmcnt(1)
	v_mfma_f32_32x32x16_bf16 v[96:111], v[176:179], v[208:211], v[96:111]
	v_mfma_f32_32x32x16_bf16 v[112:127], v[180:183], v[208:211], v[112:127]
	s_waitcnt lgkmcnt(0)
	v_mfma_f32_32x32x16_bf16 v[64:79], v[176:179], v[212:215], v[64:79]
	v_mfma_f32_32x32x16_bf16 v[80:95], v[180:183], v[212:215], v[80:95]
	ds_read_b128 v[208:211], v151 offset:9216
	ds_read_b128 v[212:215], v151 offset:13824
	s_waitcnt vmcnt(7)
	ds_write_b128 v158, v[168:171]
	s_waitcnt vmcnt(6)
	ds_write_b128 v157, v[172:175]
	ds_read_b128 v[168:171], v152 offset:36896
	ds_read_b128 v[172:175], v152 offset:41504
	s_waitcnt lgkmcnt(5)
	v_mfma_f32_32x32x16_bf16 v[32:47], v[176:179], v[208:211], v[32:47]
	v_mfma_f32_32x32x16_bf16 v[48:63], v[180:183], v[208:211], v[48:63]
	ds_read_b128 v[208:211], v151 offset:32
	s_waitcnt lgkmcnt(5)
	v_mfma_f32_32x32x16_bf16 v[0:15], v[176:179], v[212:215], v[0:15]
	v_mfma_f32_32x32x16_bf16 v[16:31], v[180:183], v[212:215], v[16:31]
	ds_read_b128 v[212:215], v151 offset:4640
	s_setprio 0
	global_load_dwordx4 v[176:179], v[140:141], off offset:768
	global_load_dwordx4 v[180:183], v[142:143], off offset:768
	s_setprio 1
	s_waitcnt lgkmcnt(1)
	v_mfma_f32_32x32x16_bf16 v[96:111], v[168:171], v[208:211], v[96:111]
	v_mfma_f32_32x32x16_bf16 v[112:127], v[172:175], v[208:211], v[112:127]
	s_waitcnt lgkmcnt(0)
	v_mfma_f32_32x32x16_bf16 v[64:79], v[168:171], v[212:215], v[64:79]
	v_mfma_f32_32x32x16_bf16 v[80:95], v[172:175], v[212:215], v[80:95]
	ds_read_b128 v[208:211], v151 offset:9248
	ds_read_b128 v[212:215], v151 offset:13856
	s_waitcnt vmcnt(7)
	ds_write_b128 v154, v[160:163]
	s_waitcnt vmcnt(6)
	ds_write_b128 v153, v[164:167]
	ds_read_b128 v[160:163], v152 offset:36928
	ds_read_b128 v[164:167], v152 offset:41536
	s_waitcnt lgkmcnt(5)
; template <bool trans>
; DI void gemm_core(const GTile& tl, const GTile& nx, bool has_next  , bool chain  , bool pre, u32x4 (&ra)[4], u32x4 (&rb)[4], char* smem, f32x16 (&acc)[2][4]) {
;     ...
;   const int nk = K / 64;
;   if (!pre) { G_LOAD(0); G_STORE(0); G_LOAD(1); }
;   for (int kt = 0; kt < nk; ++kt) {
;     __syncthreads();
;     G_COMPUTE(kt & 1, kt);
;   }
	v_mfma_f32_32x32x16_bf16 v[32:47], v[168:171], v[208:211], v[32:47]
	v_mfma_f32_32x32x16_bf16 v[48:63], v[172:175], v[208:211], v[48:63]
	ds_read_b128 v[208:211], v151 offset:64
	s_waitcnt lgkmcnt(5)
	v_mfma_f32_32x32x16_bf16 v[0:15], v[168:171], v[212:215], v[0:15]
	v_mfma_f32_32x32x16_bf16 v[16:31], v[172:175], v[212:215], v[16:31]
	ds_read_b128 v[212:215], v151 offset:4672
	s_setprio 0
	global_load_dwordx4 v[168:171], v[132:133], off offset:768
	global_load_dwordx4 v[172:175], v[134:135], off offset:768
	s_setprio 1
	s_waitcnt lgkmcnt(1)
	v_mfma_f32_32x32x16_bf16 v[96:111], v[160:163], v[208:211], v[96:111]
	v_mfma_f32_32x32x16_bf16 v[112:127], v[164:167], v[208:211], v[112:127]
	s_waitcnt lgkmcnt(0)
	v_mfma_f32_32x32x16_bf16 v[64:79], v[160:163], v[212:215], v[64:79]
	v_mfma_f32_32x32x16_bf16 v[80:95], v[164:167], v[212:215], v[80:95]
	ds_read_b128 v[208:211], v151 offset:9280
	ds_read_b128 v[212:215], v151 offset:13888
	s_waitcnt vmcnt(7)
	ds_write_b128 v156, v[184:187]
	s_waitcnt vmcnt(6)
	ds_write_b128 v155, v[188:191]
	ds_read_b128 v[184:187], v152 offset:36960
	ds_read_b128 v[188:191], v152 offset:41568
	s_waitcnt lgkmcnt(5)
	v_mfma_f32_32x32x16_bf16 v[32:47], v[160:163], v[208:211], v[32:47]
	v_mfma_f32_32x32x16_bf16 v[48:63], v[164:167], v[208:211], v[48:63]
	ds_read_b128 v[208:211], v151 offset:96
	s_waitcnt lgkmcnt(5)
	v_mfma_f32_32x32x16_bf16 v[0:15], v[160:163], v[212:215], v[0:15]
	v_mfma_f32_32x32x16_bf16 v[16:31], v[164:167], v[212:215], v[16:31]
	ds_read_b128 v[212:215], v151 offset:4704
	s_setprio 0
	global_load_dwordx4 v[160:163], v[144:145], off offset:768
	global_load_dwordx4 v[164:167], v[146:147], off offset:768
	s_setprio 1
	s_waitcnt lgkmcnt(1)
	v_mfma_f32_32x32x16_bf16 v[96:111], v[184:187], v[208:211], v[96:111]
	v_mfma_f32_32x32x16_bf16 v[112:127], v[188:191], v[208:211], v[112:127]
	s_waitcnt lgkmcnt(0)
	v_mfma_f32_32x32x16_bf16 v[64:79], v[184:187], v[212:215], v[64:79]
	v_mfma_f32_32x32x16_bf16 v[80:95], v[188:191], v[212:215], v[80:95]
	ds_read_b128 v[208:211], v151 offset:9312
	ds_read_b128 v[212:215], v151 offset:13920
	s_waitcnt lgkmcnt(0)
	s_barrier
	s_waitcnt vmcnt(7)
	ds_write_b128 v148, v[194:197]
	s_waitcnt vmcnt(6)
	ds_write_b128 v148, v[198:201] offset:36864
	ds_read_b128 v[194:197], v150
	ds_read_b128 v[198:201], v150 offset:4608
	v_mfma_f32_32x32x16_bf16 v[32:47], v[184:187], v[208:211], v[32:47]
	v_mfma_f32_32x32x16_bf16 v[48:63], v[188:191], v[208:211], v[48:63]
	ds_read_b128 v[208:211], v149
	v_mfma_f32_32x32x16_bf16 v[0:15], v[184:187], v[212:215], v[0:15]
	v_mfma_f32_32x32x16_bf16 v[16:31], v[188:191], v[212:215], v[16:31]
	ds_read_b128 v[212:215], v149 offset:4608
	s_setprio 0
	global_load_dwordx4 v[184:187], v[136:137], off offset:896
	global_load_dwordx4 v[188:191], v[138:139], off offset:896
	s_setprio 1
	s_waitcnt lgkmcnt(1)
	v_mfma_f32_32x32x16_bf16 v[96:111], v[194:197], v[208:211], v[96:111]
	v_mfma_f32_32x32x16_bf16 v[112:127], v[198:201], v[208:211], v[112:127]
	s_waitcnt lgkmcnt(0)
	v_mfma_f32_32x32x16_bf16 v[64:79], v[194:197], v[212:215], v[64:79]
	v_mfma_f32_32x32x16_bf16 v[80:95], v[198:201], v[212:215], v[80:95]
	ds_read_b128 v[208:211], v149 offset:9216
	ds_read_b128 v[212:215], v149 offset:13824
	s_waitcnt vmcnt(7)
	ds_write_b128 v148, v[176:179] offset:9216
	s_waitcnt vmcnt(6)
	ds_write_b128 v148, v[180:183] offset:46080
	ds_read_b128 v[176:179], v150 offset:32
	ds_read_b128 v[180:183], v150 offset:4640
	s_waitcnt lgkmcnt(5)
	v_mfma_f32_32x32x16_bf16 v[32:47], v[194:197], v[208:211], v[32:47]
	v_mfma_f32_32x32x16_bf16 v[48:63], v[198:201], v[208:211], v[48:63]
	ds_read_b128 v[208:211], v149 offset:32
	s_waitcnt lgkmcnt(5)
	v_mfma_f32_32x32x16_bf16 v[0:15], v[194:197], v[212:215], v[0:15]
	v_mfma_f32_32x32x16_bf16 v[16:31], v[198:201], v[212:215], v[16:31]
	ds_read_b128 v[212:215], v149 offset:4640
	s_setprio 0
	global_load_dwordx4 v[194:197], v[140:141], off offset:896
	global_load_dwordx4 v[198:201], v[142:143], off offset:896
	s_setprio 1
	s_waitcnt lgkmcnt(1)
	v_mfma_f32_32x32x16_bf16 v[96:111], v[176:179], v[208:211], v[96:111]
	v_mfma_f32_32x32x16_bf16 v[112:127], v[180:183], v[208:211], v[112:127]
	s_waitcnt lgkmcnt(0)
	v_mfma_f32_32x32x16_bf16 v[64:79], v[176:179], v[212:215], v[64:79]
	v_mfma_f32_32x32x16_bf16 v[80:95], v[180:183], v[212:215], v[80:95]
	ds_read_b128 v[208:211], v149 offset:9248
	ds_read_b128 v[212:215], v149 offset:13856
	s_waitcnt vmcnt(7)
	ds_write_b128 v148, v[168:171] offset:18432
	s_waitcnt vmcnt(6)
	ds_write_b128 v148, v[172:175] offset:55296
	ds_read_b128 v[168:171], v150 offset:64
	ds_read_b128 v[172:175], v150 offset:4672
	s_waitcnt lgkmcnt(5)
	v_mfma_f32_32x32x16_bf16 v[32:47], v[176:179], v[208:211], v[32:47]
	v_mfma_f32_32x32x16_bf16 v[48:63], v[180:183], v[208:211], v[48:63]
	ds_read_b128 v[208:211], v149 offset:64
	s_waitcnt lgkmcnt(5)
	v_mfma_f32_32x32x16_bf16 v[0:15], v[176:179], v[212:215], v[0:15]
	v_mfma_f32_32x32x16_bf16 v[16:31], v[180:183], v[212:215], v[16:31]
	ds_read_b128 v[212:215], v149 offset:4672
	s_setprio 0
	global_load_dwordx4 v[176:179], v[132:133], off offset:896
	global_load_dwordx4 v[180:183], v[134:135], off offset:896
	s_setprio 1
	s_waitcnt lgkmcnt(1)
	v_mfma_f32_32x32x16_bf16 v[96:111], v[168:171], v[208:211], v[96:111]
	v_mfma_f32_32x32x16_bf16 v[112:127], v[172:175], v[208:211], v[112:127]
	s_waitcnt lgkmcnt(0)
	v_mfma_f32_32x32x16_bf16 v[64:79], v[168:171], v[212:215], v[64:79]
	v_mfma_f32_32x32x16_bf16 v[80:95], v[172:175], v[212:215], v[80:95]
	ds_read_b128 v[208:211], v149 offset:9280
	ds_read_b128 v[212:215], v149 offset:13888
	s_waitcnt vmcnt(7)
	ds_write_b128 v148, v[160:163] offset:27648
	s_waitcnt vmcnt(6)
	ds_write_b128 v148, v[164:167] offset:64512
	ds_read_b128 v[160:163], v150 offset:96
	ds_read_b128 v[164:167], v150 offset:4704
	s_waitcnt lgkmcnt(5)
	v_mfma_f32_32x32x16_bf16 v[32:47], v[168:171], v[208:211], v[32:47]
	v_mfma_f32_32x32x16_bf16 v[48:63], v[172:175], v[208:211], v[48:63]
	ds_read_b128 v[208:211], v149 offset:96
	s_waitcnt lgkmcnt(5)
	v_mfma_f32_32x32x16_bf16 v[0:15], v[168:171], v[212:215], v[0:15]
	v_mfma_f32_32x32x16_bf16 v[16:31], v[172:175], v[212:215], v[16:31]
	ds_read_b128 v[212:215], v149 offset:4704
	s_setprio 0
	global_load_dwordx4 v[168:171], v[144:145], off offset:896
	global_load_dwordx4 v[172:175], v[146:147], off offset:896
	s_setprio 1
	s_waitcnt lgkmcnt(1)
	v_mfma_f32_32x32x16_bf16 v[96:111], v[160:163], v[208:211], v[96:111]
	v_mfma_f32_32x32x16_bf16 v[112:127], v[164:167], v[208:211], v[112:127]
	s_waitcnt lgkmcnt(0)
	v_mfma_f32_32x32x16_bf16 v[64:79], v[160:163], v[212:215], v[64:79]
	v_mfma_f32_32x32x16_bf16 v[80:95], v[164:167], v[212:215], v[80:95]
	ds_read_b128 v[208:211], v149 offset:9312
	ds_read_b128 v[212:215], v149 offset:13920
	s_waitcnt lgkmcnt(0)
	s_barrier
; template <bool trans>
; DI void gemm_core(const GTile& tl, const GTile& nx, bool has_next  , bool chain  , bool pre, u32x4 (&ra)[4], u32x4 (&rb)[4], char* smem, f32x16 (&acc)[2][4]) {
;     ...
;   const int nk = K / 64;
;   if (!pre) { G_LOAD(0); G_STORE(0); G_LOAD(1); }
;   for (int kt = 0; kt < nk; ++kt) {
;     __syncthreads();
;     G_COMPUTE(kt & 1, kt);
;   }
	s_waitcnt vmcnt(7)
	ds_write_b128 v192, v[184:187]
	s_waitcnt vmcnt(6)
	ds_write_b128 v159, v[188:191]
	ds_read_b128 v[184:187], v152 offset:36864
	ds_read_b128 v[188:191], v152 offset:41472
	v_mfma_f32_32x32x16_bf16 v[32:47], v[160:163], v[208:211], v[32:47]
	v_mfma_f32_32x32x16_bf16 v[48:63], v[164:167], v[208:211], v[48:63]
	ds_read_b128 v[208:211], v151
	v_mfma_f32_32x32x16_bf16 v[0:15], v[160:163], v[212:215], v[0:15]
	v_mfma_f32_32x32x16_bf16 v[16:31], v[164:167], v[212:215], v[16:31]
	ds_read_b128 v[212:215], v151 offset:4608
	s_setprio 0
	global_load_dwordx4 v[160:163], v[136:137], off offset:1024
	global_load_dwordx4 v[164:167], v[138:139], off offset:1024
	s_setprio 1
	s_waitcnt lgkmcnt(1)
	v_mfma_f32_32x32x16_bf16 v[96:111], v[184:187], v[208:211], v[96:111]
	v_mfma_f32_32x32x16_bf16 v[112:127], v[188:191], v[208:211], v[112:127]
	s_waitcnt lgkmcnt(0)
	v_mfma_f32_32x32x16_bf16 v[64:79], v[184:187], v[212:215], v[64:79]
	v_mfma_f32_32x32x16_bf16 v[80:95], v[188:191], v[212:215], v[80:95]
	ds_read_b128 v[208:211], v151 offset:9216
	ds_read_b128 v[212:215], v151 offset:13824
	s_waitcnt vmcnt(7)
	ds_write_b128 v158, v[194:197]
	s_waitcnt vmcnt(6)
	ds_write_b128 v157, v[198:201]
	ds_read_b128 v[194:197], v152 offset:36896
	ds_read_b128 v[198:201], v152 offset:41504
	s_waitcnt lgkmcnt(5)
	v_mfma_f32_32x32x16_bf16 v[32:47], v[184:187], v[208:211], v[32:47]
	v_mfma_f32_32x32x16_bf16 v[48:63], v[188:191], v[208:211], v[48:63]
	ds_read_b128 v[208:211], v151 offset:32
	s_waitcnt lgkmcnt(5)
	v_mfma_f32_32x32x16_bf16 v[0:15], v[184:187], v[212:215], v[0:15]
	v_mfma_f32_32x32x16_bf16 v[16:31], v[188:191], v[212:215], v[16:31]
	ds_read_b128 v[212:215], v151 offset:4640
	s_setprio 0
	global_load_dwordx4 v[184:187], v[140:141], off offset:1024
	global_load_dwordx4 v[188:191], v[142:143], off offset:1024
	s_setprio 1
	s_waitcnt lgkmcnt(1)
	v_mfma_f32_32x32x16_bf16 v[96:111], v[194:197], v[208:211], v[96:111]
	v_mfma_f32_32x32x16_bf16 v[112:127], v[198:201], v[208:211], v[112:127]
	s_waitcnt lgkmcnt(0)
	v_mfma_f32_32x32x16_bf16 v[64:79], v[194:197], v[212:215], v[64:79]
	v_mfma_f32_32x32x16_bf16 v[80:95], v[198:201], v[212:215], v[80:95]
	ds_read_b128 v[208:211], v151 offset:9248
	ds_read_b128 v[212:215], v151 offset:13856
	s_waitcnt vmcnt(7)
	ds_write_b128 v154, v[176:179]
	s_waitcnt vmcnt(6)
	ds_write_b128 v153, v[180:183]
	ds_read_b128 v[176:179], v152 offset:36928
	ds_read_b128 v[180:183], v152 offset:41536
	s_waitcnt lgkmcnt(5)
	v_mfma_f32_32x32x16_bf16 v[32:47], v[194:197], v[208:211], v[32:47]
	v_mfma_f32_32x32x16_bf16 v[48:63], v[198:201], v[208:211], v[48:63]
	ds_read_b128 v[208:211], v151 offset:64
	s_waitcnt lgkmcnt(5)
	v_mfma_f32_32x32x16_bf16 v[0:15], v[194:197], v[212:215], v[0:15]
	v_mfma_f32_32x32x16_bf16 v[16:31], v[198:201], v[212:215], v[16:31]
	ds_read_b128 v[212:215], v151 offset:4672
	s_setprio 0
	global_load_dwordx4 v[194:197], v[132:133], off offset:1024
	global_load_dwordx4 v[198:201], v[134:135], off offset:1024
	s_setprio 1
	s_waitcnt lgkmcnt(1)
	v_mfma_f32_32x32x16_bf16 v[96:111], v[176:179], v[208:211], v[96:111]
	v_mfma_f32_32x32x16_bf16 v[112:127], v[180:183], v[208:211], v[112:127]
	s_waitcnt lgkmcnt(0)
	v_mfma_f32_32x32x16_bf16 v[64:79], v[176:179], v[212:215], v[64:79]
	v_mfma_f32_32x32x16_bf16 v[80:95], v[180:183], v[212:215], v[80:95]
	ds_read_b128 v[208:211], v151 offset:9280
	ds_read_b128 v[212:215], v151 offset:13888
	s_waitcnt vmcnt(7)
	ds_write_b128 v156, v[168:171]
	s_waitcnt vmcnt(6)
	ds_write_b128 v155, v[172:175]
	ds_read_b128 v[168:171], v152 offset:36960
	ds_read_b128 v[172:175], v152 offset:41568
	s_waitcnt lgkmcnt(5)
	v_mfma_f32_32x32x16_bf16 v[32:47], v[176:179], v[208:211], v[32:47]
	v_mfma_f32_32x32x16_bf16 v[48:63], v[180:183], v[208:211], v[48:63]
	ds_read_b128 v[208:211], v151 offset:96
	s_waitcnt lgkmcnt(5)
	v_mfma_f32_32x32x16_bf16 v[0:15], v[176:179], v[212:215], v[0:15]
	v_mfma_f32_32x32x16_bf16 v[16:31], v[180:183], v[212:215], v[16:31]
	ds_read_b128 v[212:215], v151 offset:4704
	s_setprio 0
	global_load_dwordx4 v[176:179], v[144:145], off offset:1024
	global_load_dwordx4 v[180:183], v[146:147], off offset:1024
	s_setprio 1
	s_waitcnt lgkmcnt(1)
	v_mfma_f32_32x32x16_bf16 v[96:111], v[168:171], v[208:211], v[96:111]
	v_mfma_f32_32x32x16_bf16 v[112:127], v[172:175], v[208:211], v[112:127]
	s_waitcnt lgkmcnt(0)
	v_mfma_f32_32x32x16_bf16 v[64:79], v[168:171], v[212:215], v[64:79]
	v_mfma_f32_32x32x16_bf16 v[80:95], v[172:175], v[212:215], v[80:95]
	ds_read_b128 v[208:211], v151 offset:9312
	ds_read_b128 v[212:215], v151 offset:13920
	s_waitcnt lgkmcnt(0)
	s_barrier
; template <bool trans>
; DI void gemm_core(const GTile& tl, const GTile& nx, bool has_next  , bool chain  , bool pre, u32x4 (&ra)[4], u32x4 (&rb)[4], char* smem, f32x16 (&acc)[2][4]) {
;     ...
;   const int nk = K / 64;
;   if (!pre) { G_LOAD(0); G_STORE(0); G_LOAD(1); }
;   for (int kt = 0; kt < nk; ++kt) {
;     __syncthreads();
;     G_COMPUTE(kt & 1, kt);
;   }
	s_waitcnt vmcnt(7)
	ds_write_b128 v148, v[160:163]
	s_waitcnt vmcnt(6)
	ds_write_b128 v148, v[164:167] offset:36864
	ds_read_b128 v[160:163], v150
	ds_read_b128 v[164:167], v150 offset:4608
	v_mfma_f32_32x32x16_bf16 v[32:47], v[168:171], v[208:211], v[32:47]
	v_mfma_f32_32x32x16_bf16 v[48:63], v[172:175], v[208:211], v[48:63]
	ds_read_b128 v[208:211], v149
	v_mfma_f32_32x32x16_bf16 v[0:15], v[168:171], v[212:215], v[0:15]
	v_mfma_f32_32x32x16_bf16 v[16:31], v[172:175], v[212:215], v[16:31]
	ds_read_b128 v[212:215], v149 offset:4608
	s_setprio 0
	global_load_dwordx4 v[168:171], v[136:137], off offset:1152
	global_load_dwordx4 v[172:175], v[138:139], off offset:1152
	s_setprio 1
	s_waitcnt lgkmcnt(1)
	v_mfma_f32_32x32x16_bf16 v[96:111], v[160:163], v[208:211], v[96:111]
	v_mfma_f32_32x32x16_bf16 v[112:127], v[164:167], v[208:211], v[112:127]
	s_waitcnt lgkmcnt(0)
	v_mfma_f32_32x32x16_bf16 v[64:79], v[160:163], v[212:215], v[64:79]
	v_mfma_f32_32x32x16_bf16 v[80:95], v[164:167], v[212:215], v[80:95]
	ds_read_b128 v[208:211], v149 offset:9216
	ds_read_b128 v[212:215], v149 offset:13824
	s_waitcnt vmcnt(7)
	ds_write_b128 v148, v[184:187] offset:9216
	s_waitcnt vmcnt(6)
	ds_write_b128 v148, v[188:191] offset:46080
	ds_read_b128 v[184:187], v150 offset:32
	ds_read_b128 v[188:191], v150 offset:4640
	s_waitcnt lgkmcnt(5)
	v_mfma_f32_32x32x16_bf16 v[32:47], v[160:163], v[208:211], v[32:47]
	v_mfma_f32_32x32x16_bf16 v[48:63], v[164:167], v[208:211], v[48:63]
	ds_read_b128 v[208:211], v149 offset:32
	s_waitcnt lgkmcnt(5)
	v_mfma_f32_32x32x16_bf16 v[0:15], v[160:163], v[212:215], v[0:15]
	v_mfma_f32_32x32x16_bf16 v[16:31], v[164:167], v[212:215], v[16:31]
	ds_read_b128 v[212:215], v149 offset:4640
	s_setprio 0
	global_load_dwordx4 v[160:163], v[140:141], off offset:1152
	global_load_dwordx4 v[164:167], v[142:143], off offset:1152
	s_setprio 1
	s_waitcnt lgkmcnt(1)
	v_mfma_f32_32x32x16_bf16 v[96:111], v[184:187], v[208:211], v[96:111]
	v_mfma_f32_32x32x16_bf16 v[112:127], v[188:191], v[208:211], v[112:127]
	s_waitcnt lgkmcnt(0)
	v_mfma_f32_32x32x16_bf16 v[64:79], v[184:187], v[212:215], v[64:79]
	v_mfma_f32_32x32x16_bf16 v[80:95], v[188:191], v[212:215], v[80:95]
	ds_read_b128 v[208:211], v149 offset:9248
	ds_read_b128 v[212:215], v149 offset:13856
	s_waitcnt vmcnt(7)
	ds_write_b128 v148, v[194:197] offset:18432
	s_waitcnt vmcnt(6)
	ds_write_b128 v148, v[198:201] offset:55296
	ds_read_b128 v[194:197], v150 offset:64
	ds_read_b128 v[198:201], v150 offset:4672
	s_waitcnt lgkmcnt(5)
	v_mfma_f32_32x32x16_bf16 v[32:47], v[184:187], v[208:211], v[32:47]
	v_mfma_f32_32x32x16_bf16 v[48:63], v[188:191], v[208:211], v[48:63]
	ds_read_b128 v[208:211], v149 offset:64
	s_waitcnt lgkmcnt(5)
	v_mfma_f32_32x32x16_bf16 v[0:15], v[184:187], v[212:215], v[0:15]
	v_mfma_f32_32x32x16_bf16 v[16:31], v[188:191], v[212:215], v[16:31]
	ds_read_b128 v[212:215], v149 offset:4672
	s_setprio 0
	global_load_dwordx4 v[184:187], v[132:133], off offset:1152
	global_load_dwordx4 v[188:191], v[134:135], off offset:1152
	s_setprio 1
	s_waitcnt lgkmcnt(1)
	v_mfma_f32_32x32x16_bf16 v[96:111], v[194:197], v[208:211], v[96:111]
	v_mfma_f32_32x32x16_bf16 v[112:127], v[198:201], v[208:211], v[112:127]
	s_waitcnt lgkmcnt(0)
	v_mfma_f32_32x32x16_bf16 v[64:79], v[194:197], v[212:215], v[64:79]
	v_mfma_f32_32x32x16_bf16 v[80:95], v[198:201], v[212:215], v[80:95]
	ds_read_b128 v[208:211], v149 offset:9280
	ds_read_b128 v[212:215], v149 offset:13888
	s_waitcnt vmcnt(7)
	ds_write_b128 v148, v[176:179] offset:27648
	s_waitcnt vmcnt(6)
	ds_write_b128 v148, v[180:183] offset:64512
	ds_read_b128 v[176:179], v150 offset:96
	ds_read_b128 v[180:183], v150 offset:4704
	s_waitcnt lgkmcnt(5)
	v_mfma_f32_32x32x16_bf16 v[32:47], v[194:197], v[208:211], v[32:47]
	v_mfma_f32_32x32x16_bf16 v[48:63], v[198:201], v[208:211], v[48:63]
	ds_read_b128 v[208:211], v149 offset:96
	s_waitcnt lgkmcnt(5)
	v_mfma_f32_32x32x16_bf16 v[0:15], v[194:197], v[212:215], v[0:15]
	v_mfma_f32_32x32x16_bf16 v[16:31], v[198:201], v[212:215], v[16:31]
	ds_read_b128 v[212:215], v149 offset:4704
	s_setprio 0
	global_load_dwordx4 v[194:197], v[144:145], off offset:1152
	global_load_dwordx4 v[198:201], v[146:147], off offset:1152
	s_setprio 1
	s_waitcnt lgkmcnt(1)
	v_mfma_f32_32x32x16_bf16 v[96:111], v[176:179], v[208:211], v[96:111]
	v_mfma_f32_32x32x16_bf16 v[112:127], v[180:183], v[208:211], v[112:127]
	s_waitcnt lgkmcnt(0)
	v_mfma_f32_32x32x16_bf16 v[64:79], v[176:179], v[212:215], v[64:79]
	v_mfma_f32_32x32x16_bf16 v[80:95], v[180:183], v[212:215], v[80:95]
	ds_read_b128 v[208:211], v149 offset:9312
	ds_read_b128 v[212:215], v149 offset:13920
	s_waitcnt lgkmcnt(0)
	s_barrier
; template <bool trans>
; DI void gemm_core(const GTile& tl, const GTile& nx, bool has_next  , bool chain  , bool pre, u32x4 (&ra)[4], u32x4 (&rb)[4], char* smem, f32x16 (&acc)[2][4]) {
;     ...
;   const int nk = K / 64;
;   if (!pre) { G_LOAD(0); G_STORE(0); G_LOAD(1); }
;   for (int kt = 0; kt < nk; ++kt) {
;     __syncthreads();
;     G_COMPUTE(kt & 1, kt);
;   }
	s_waitcnt vmcnt(7)
	ds_write_b128 v192, v[168:171]
	s_waitcnt vmcnt(6)
	ds_write_b128 v159, v[172:175]
	ds_read_b128 v[168:171], v152 offset:36864
	ds_read_b128 v[172:175], v152 offset:41472
	v_mfma_f32_32x32x16_bf16 v[32:47], v[176:179], v[208:211], v[32:47]
	v_mfma_f32_32x32x16_bf16 v[48:63], v[180:183], v[208:211], v[48:63]
	ds_read_b128 v[208:211], v151
	v_mfma_f32_32x32x16_bf16 v[0:15], v[176:179], v[212:215], v[0:15]
	v_mfma_f32_32x32x16_bf16 v[16:31], v[180:183], v[212:215], v[16:31]
	ds_read_b128 v[212:215], v151 offset:4608
	s_setprio 0
	global_load_dwordx4 v[176:179], v[136:137], off offset:1280
	global_load_dwordx4 v[180:183], v[138:139], off offset:1280
	s_setprio 1
	s_waitcnt lgkmcnt(1)
	v_mfma_f32_32x32x16_bf16 v[96:111], v[168:171], v[208:211], v[96:111]
	v_mfma_f32_32x32x16_bf16 v[112:127], v[172:175], v[208:211], v[112:127]
	s_waitcnt lgkmcnt(0)
	v_mfma_f32_32x32x16_bf16 v[64:79], v[168:171], v[212:215], v[64:79]
	v_mfma_f32_32x32x16_bf16 v[80:95], v[172:175], v[212:215], v[80:95]
	ds_read_b128 v[208:211], v151 offset:9216
	ds_read_b128 v[212:215], v151 offset:13824
	s_waitcnt vmcnt(7)
	ds_write_b128 v158, v[160:163]
	s_waitcnt vmcnt(6)
	ds_write_b128 v157, v[164:167]
	ds_read_b128 v[160:163], v152 offset:36896
	ds_read_b128 v[164:167], v152 offset:41504
	s_waitcnt lgkmcnt(5)
	v_mfma_f32_32x32x16_bf16 v[32:47], v[168:171], v[208:211], v[32:47]
	v_mfma_f32_32x32x16_bf16 v[48:63], v[172:175], v[208:211], v[48:63]
	ds_read_b128 v[208:211], v151 offset:32
	s_waitcnt lgkmcnt(5)
	v_mfma_f32_32x32x16_bf16 v[0:15], v[168:171], v[212:215], v[0:15]
	v_mfma_f32_32x32x16_bf16 v[16:31], v[172:175], v[212:215], v[16:31]
	ds_read_b128 v[212:215], v151 offset:4640
	s_setprio 0
	global_load_dwordx4 v[168:171], v[140:141], off offset:1280
	global_load_dwordx4 v[172:175], v[142:143], off offset:1280
	s_setprio 1
	s_waitcnt lgkmcnt(1)
	v_mfma_f32_32x32x16_bf16 v[96:111], v[160:163], v[208:211], v[96:111]
	v_mfma_f32_32x32x16_bf16 v[112:127], v[164:167], v[208:211], v[112:127]
	s_waitcnt lgkmcnt(0)
	v_mfma_f32_32x32x16_bf16 v[64:79], v[160:163], v[212:215], v[64:79]
	v_mfma_f32_32x32x16_bf16 v[80:95], v[164:167], v[212:215], v[80:95]
	ds_read_b128 v[208:211], v151 offset:9248
	ds_read_b128 v[212:215], v151 offset:13856
	s_waitcnt vmcnt(7)
	ds_write_b128 v154, v[184:187]
	s_waitcnt vmcnt(6)
	ds_write_b128 v153, v[188:191]
	ds_read_b128 v[184:187], v152 offset:36928
	ds_read_b128 v[188:191], v152 offset:41536
	s_waitcnt lgkmcnt(5)
	v_mfma_f32_32x32x16_bf16 v[32:47], v[160:163], v[208:211], v[32:47]
	v_mfma_f32_32x32x16_bf16 v[48:63], v[164:167], v[208:211], v[48:63]
	ds_read_b128 v[208:211], v151 offset:64
	s_waitcnt lgkmcnt(5)
	v_mfma_f32_32x32x16_bf16 v[0:15], v[160:163], v[212:215], v[0:15]
	v_mfma_f32_32x32x16_bf16 v[16:31], v[164:167], v[212:215], v[16:31]
	ds_read_b128 v[212:215], v151 offset:4672
	s_setprio 0
	global_load_dwordx4 v[160:163], v[132:133], off offset:1280
	global_load_dwordx4 v[164:167], v[134:135], off offset:1280
	s_setprio 1
	s_waitcnt lgkmcnt(1)
	v_mfma_f32_32x32x16_bf16 v[96:111], v[184:187], v[208:211], v[96:111]
	v_mfma_f32_32x32x16_bf16 v[112:127], v[188:191], v[208:211], v[112:127]
	s_waitcnt lgkmcnt(0)
	v_mfma_f32_32x32x16_bf16 v[64:79], v[184:187], v[212:215], v[64:79]
	v_mfma_f32_32x32x16_bf16 v[80:95], v[188:191], v[212:215], v[80:95]
	ds_read_b128 v[208:211], v151 offset:9280
	ds_read_b128 v[212:215], v151 offset:13888
	s_waitcnt vmcnt(7)
	ds_write_b128 v156, v[194:197]
	s_waitcnt vmcnt(6)
	ds_write_b128 v155, v[198:201]
	ds_read_b128 v[194:197], v152 offset:36960
	ds_read_b128 v[198:201], v152 offset:41568
	s_waitcnt lgkmcnt(5)
	v_mfma_f32_32x32x16_bf16 v[32:47], v[184:187], v[208:211], v[32:47]
	v_mfma_f32_32x32x16_bf16 v[48:63], v[188:191], v[208:211], v[48:63]
	ds_read_b128 v[208:211], v151 offset:96
	s_waitcnt lgkmcnt(5)
	v_mfma_f32_32x32x16_bf16 v[0:15], v[184:187], v[212:215], v[0:15]
	v_mfma_f32_32x32x16_bf16 v[16:31], v[188:191], v[212:215], v[16:31]
	ds_read_b128 v[212:215], v151 offset:4704
	s_setprio 0
	global_load_dwordx4 v[184:187], v[144:145], off offset:1280
	global_load_dwordx4 v[188:191], v[146:147], off offset:1280
	s_setprio 1
	s_waitcnt lgkmcnt(1)
	v_mfma_f32_32x32x16_bf16 v[96:111], v[194:197], v[208:211], v[96:111]
	v_mfma_f32_32x32x16_bf16 v[112:127], v[198:201], v[208:211], v[112:127]
	s_waitcnt lgkmcnt(0)
	v_mfma_f32_32x32x16_bf16 v[64:79], v[194:197], v[212:215], v[64:79]
	v_mfma_f32_32x32x16_bf16 v[80:95], v[198:201], v[212:215], v[80:95]
	ds_read_b128 v[208:211], v151 offset:9312
	ds_read_b128 v[212:215], v151 offset:13920
	s_waitcnt lgkmcnt(0)
	s_barrier
; template <bool trans>
; DI void gemm_core(const GTile& tl, const GTile& nx, bool has_next  , bool chain  , bool pre, u32x4 (&ra)[4], u32x4 (&rb)[4], char* smem, f32x16 (&acc)[2][4]) {
;     ...
;   const int nk = K / 64;
;   if (!pre) { G_LOAD(0); G_STORE(0); G_LOAD(1); }
;   for (int kt = 0; kt < nk; ++kt) {
;     __syncthreads();
;     G_COMPUTE(kt & 1, kt);
;   }
	s_waitcnt vmcnt(7)
	ds_write_b128 v148, v[176:179]
	s_waitcnt vmcnt(6)
	ds_write_b128 v148, v[180:183] offset:36864
	ds_read_b128 v[176:179], v150
	ds_read_b128 v[180:183], v150 offset:4608
	v_mfma_f32_32x32x16_bf16 v[32:47], v[194:197], v[208:211], v[32:47]
	v_mfma_f32_32x32x16_bf16 v[48:63], v[198:201], v[208:211], v[48:63]
	ds_read_b128 v[208:211], v149
	v_mfma_f32_32x32x16_bf16 v[0:15], v[194:197], v[212:215], v[0:15]
	v_mfma_f32_32x32x16_bf16 v[16:31], v[198:201], v[212:215], v[16:31]
	ds_read_b128 v[212:215], v149 offset:4608
	s_setprio 0
	global_load_dwordx4 v[194:197], v[136:137], off offset:1408
	global_load_dwordx4 v[198:201], v[138:139], off offset:1408
	s_setprio 1
	s_waitcnt lgkmcnt(1)
	v_mfma_f32_32x32x16_bf16 v[96:111], v[176:179], v[208:211], v[96:111]
	v_mfma_f32_32x32x16_bf16 v[112:127], v[180:183], v[208:211], v[112:127]
	s_waitcnt lgkmcnt(0)
	v_mfma_f32_32x32x16_bf16 v[64:79], v[176:179], v[212:215], v[64:79]
	v_mfma_f32_32x32x16_bf16 v[80:95], v[180:183], v[212:215], v[80:95]
	ds_read_b128 v[208:211], v149 offset:9216
	ds_read_b128 v[212:215], v149 offset:13824
	s_waitcnt vmcnt(7)
	ds_write_b128 v148, v[168:171] offset:9216
	s_waitcnt vmcnt(6)
	ds_write_b128 v148, v[172:175] offset:46080
	ds_read_b128 v[168:171], v150 offset:32
	ds_read_b128 v[172:175], v150 offset:4640
	s_waitcnt lgkmcnt(5)
	v_mfma_f32_32x32x16_bf16 v[32:47], v[176:179], v[208:211], v[32:47]
	v_mfma_f32_32x32x16_bf16 v[48:63], v[180:183], v[208:211], v[48:63]
	ds_read_b128 v[208:211], v149 offset:32
	s_waitcnt lgkmcnt(5)
	v_mfma_f32_32x32x16_bf16 v[0:15], v[176:179], v[212:215], v[0:15]
	v_mfma_f32_32x32x16_bf16 v[16:31], v[180:183], v[212:215], v[16:31]
	ds_read_b128 v[212:215], v149 offset:4640
	s_setprio 0
	global_load_dwordx4 v[176:179], v[140:141], off offset:1408
	global_load_dwordx4 v[180:183], v[142:143], off offset:1408
	s_setprio 1
	s_waitcnt lgkmcnt(1)
	v_mfma_f32_32x32x16_bf16 v[96:111], v[168:171], v[208:211], v[96:111]
	v_mfma_f32_32x32x16_bf16 v[112:127], v[172:175], v[208:211], v[112:127]
	s_waitcnt lgkmcnt(0)
	v_mfma_f32_32x32x16_bf16 v[64:79], v[168:171], v[212:215], v[64:79]
	v_mfma_f32_32x32x16_bf16 v[80:95], v[172:175], v[212:215], v[80:95]
	ds_read_b128 v[208:211], v149 offset:9248
	ds_read_b128 v[212:215], v149 offset:13856
	s_waitcnt vmcnt(7)
	ds_write_b128 v148, v[160:163] offset:18432
	s_waitcnt vmcnt(6)
	ds_write_b128 v148, v[164:167] offset:55296
	ds_read_b128 v[160:163], v150 offset:64
	ds_read_b128 v[164:167], v150 offset:4672
	s_waitcnt lgkmcnt(5)
	v_mfma_f32_32x32x16_bf16 v[32:47], v[168:171], v[208:211], v[32:47]
	v_mfma_f32_32x32x16_bf16 v[48:63], v[172:175], v[208:211], v[48:63]
	ds_read_b128 v[208:211], v149 offset:64
	s_waitcnt lgkmcnt(5)
	v_mfma_f32_32x32x16_bf16 v[0:15], v[168:171], v[212:215], v[0:15]
	v_mfma_f32_32x32x16_bf16 v[16:31], v[172:175], v[212:215], v[16:31]
	ds_read_b128 v[212:215], v149 offset:4672
	s_setprio 0
	global_load_dwordx4 v[168:171], v[132:133], off offset:1408
	global_load_dwordx4 v[172:175], v[134:135], off offset:1408
	s_setprio 1
	s_waitcnt lgkmcnt(1)
	v_mfma_f32_32x32x16_bf16 v[96:111], v[160:163], v[208:211], v[96:111]
	v_mfma_f32_32x32x16_bf16 v[112:127], v[164:167], v[208:211], v[112:127]
	s_waitcnt lgkmcnt(0)
	v_mfma_f32_32x32x16_bf16 v[64:79], v[160:163], v[212:215], v[64:79]
	v_mfma_f32_32x32x16_bf16 v[80:95], v[164:167], v[212:215], v[80:95]
	ds_read_b128 v[208:211], v149 offset:9280
	ds_read_b128 v[212:215], v149 offset:13888
	s_waitcnt vmcnt(7)
	ds_write_b128 v148, v[184:187] offset:27648
	s_waitcnt vmcnt(6)
	ds_write_b128 v148, v[188:191] offset:64512
	ds_read_b128 v[184:187], v150 offset:96
	ds_read_b128 v[188:191], v150 offset:4704
	s_waitcnt lgkmcnt(5)
	v_mfma_f32_32x32x16_bf16 v[32:47], v[160:163], v[208:211], v[32:47]
	v_mfma_f32_32x32x16_bf16 v[48:63], v[164:167], v[208:211], v[48:63]
	ds_read_b128 v[208:211], v149 offset:96
	s_waitcnt lgkmcnt(5)
	v_mfma_f32_32x32x16_bf16 v[0:15], v[160:163], v[212:215], v[0:15]
	v_mfma_f32_32x32x16_bf16 v[16:31], v[164:167], v[212:215], v[16:31]
	ds_read_b128 v[212:215], v149 offset:4704
	s_setprio 0
	global_load_dwordx4 v[160:163], v[144:145], off offset:1408
	global_load_dwordx4 v[164:167], v[146:147], off offset:1408
	s_setprio 1
	s_waitcnt lgkmcnt(1)
	v_mfma_f32_32x32x16_bf16 v[96:111], v[184:187], v[208:211], v[96:111]
	v_mfma_f32_32x32x16_bf16 v[112:127], v[188:191], v[208:211], v[112:127]
	s_waitcnt lgkmcnt(0)
	v_mfma_f32_32x32x16_bf16 v[64:79], v[184:187], v[212:215], v[64:79]
	v_mfma_f32_32x32x16_bf16 v[80:95], v[188:191], v[212:215], v[80:95]
	ds_read_b128 v[208:211], v149 offset:9312
	ds_read_b128 v[212:215], v149 offset:13920
	s_waitcnt lgkmcnt(0)
	s_barrier
; template <bool trans>
; DI void gemm_core(const GTile& tl, const GTile& nx, bool has_next  , bool chain  , bool pre, u32x4 (&ra)[4], u32x4 (&rb)[4], char* smem, f32x16 (&acc)[2][4]) {
;     ...
;   const int nk = K / 64;
;   if (!pre) { G_LOAD(0); G_STORE(0); G_LOAD(1); }
;   for (int kt = 0; kt < nk; ++kt) {
;     __syncthreads();
;     G_COMPUTE(kt & 1, kt);
;   }
	s_waitcnt vmcnt(7)
	ds_write_b128 v192, v[194:197]
	s_waitcnt vmcnt(6)
	ds_write_b128 v159, v[198:201]
	ds_read_b128 v[194:197], v152 offset:36864
	ds_read_b128 v[198:201], v152 offset:41472
	v_mfma_f32_32x32x16_bf16 v[32:47], v[184:187], v[208:211], v[32:47]
	v_mfma_f32_32x32x16_bf16 v[48:63], v[188:191], v[208:211], v[48:63]
	ds_read_b128 v[208:211], v151
	v_mfma_f32_32x32x16_bf16 v[0:15], v[184:187], v[212:215], v[0:15]
	v_mfma_f32_32x32x16_bf16 v[16:31], v[188:191], v[212:215], v[16:31]
	ds_read_b128 v[212:215], v151 offset:4608
	s_setprio 0
	global_load_dwordx4 v[184:187], v[136:137], off offset:1536
	global_load_dwordx4 v[188:191], v[138:139], off offset:1536
	s_setprio 1
	s_waitcnt lgkmcnt(1)
	v_mfma_f32_32x32x16_bf16 v[96:111], v[194:197], v[208:211], v[96:111]
	v_mfma_f32_32x32x16_bf16 v[112:127], v[198:201], v[208:211], v[112:127]
	s_waitcnt lgkmcnt(0)
	v_mfma_f32_32x32x16_bf16 v[64:79], v[194:197], v[212:215], v[64:79]
	v_mfma_f32_32x32x16_bf16 v[80:95], v[198:201], v[212:215], v[80:95]
	ds_read_b128 v[208:211], v151 offset:9216
	ds_read_b128 v[212:215], v151 offset:13824
	s_waitcnt vmcnt(7)
	ds_write_b128 v158, v[176:179]
	s_waitcnt vmcnt(6)
	ds_write_b128 v157, v[180:183]
	ds_read_b128 v[176:179], v152 offset:36896
	ds_read_b128 v[180:183], v152 offset:41504
	s_waitcnt lgkmcnt(5)
	v_mfma_f32_32x32x16_bf16 v[32:47], v[194:197], v[208:211], v[32:47]
	v_mfma_f32_32x32x16_bf16 v[48:63], v[198:201], v[208:211], v[48:63]
	ds_read_b128 v[208:211], v151 offset:32
	s_waitcnt lgkmcnt(5)
	v_mfma_f32_32x32x16_bf16 v[0:15], v[194:197], v[212:215], v[0:15]
	v_mfma_f32_32x32x16_bf16 v[16:31], v[198:201], v[212:215], v[16:31]
	ds_read_b128 v[212:215], v151 offset:4640
	s_setprio 0
	global_load_dwordx4 v[194:197], v[140:141], off offset:1536
	global_load_dwordx4 v[198:201], v[142:143], off offset:1536
	s_setprio 1
	s_waitcnt lgkmcnt(1)
	v_mfma_f32_32x32x16_bf16 v[96:111], v[176:179], v[208:211], v[96:111]
	v_mfma_f32_32x32x16_bf16 v[112:127], v[180:183], v[208:211], v[112:127]
	s_waitcnt lgkmcnt(0)
	v_mfma_f32_32x32x16_bf16 v[64:79], v[176:179], v[212:215], v[64:79]
	v_mfma_f32_32x32x16_bf16 v[80:95], v[180:183], v[212:215], v[80:95]
	ds_read_b128 v[208:211], v151 offset:9248
	ds_read_b128 v[212:215], v151 offset:13856
	s_waitcnt vmcnt(7)
	ds_write_b128 v154, v[168:171]
	s_waitcnt vmcnt(6)
	ds_write_b128 v153, v[172:175]
	ds_read_b128 v[168:171], v152 offset:36928
	ds_read_b128 v[172:175], v152 offset:41536
	s_waitcnt lgkmcnt(5)
	v_mfma_f32_32x32x16_bf16 v[32:47], v[176:179], v[208:211], v[32:47]
	v_mfma_f32_32x32x16_bf16 v[48:63], v[180:183], v[208:211], v[48:63]
	ds_read_b128 v[208:211], v151 offset:64
	s_waitcnt lgkmcnt(5)
	v_mfma_f32_32x32x16_bf16 v[0:15], v[176:179], v[212:215], v[0:15]
	v_mfma_f32_32x32x16_bf16 v[16:31], v[180:183], v[212:215], v[16:31]
	ds_read_b128 v[212:215], v151 offset:4672
	s_setprio 0
	global_load_dwordx4 v[176:179], v[132:133], off offset:1536
	global_load_dwordx4 v[180:183], v[134:135], off offset:1536
	s_setprio 1
	s_waitcnt lgkmcnt(1)
	v_mfma_f32_32x32x16_bf16 v[96:111], v[168:171], v[208:211], v[96:111]
	v_mfma_f32_32x32x16_bf16 v[112:127], v[172:175], v[208:211], v[112:127]
	s_waitcnt lgkmcnt(0)
	v_mfma_f32_32x32x16_bf16 v[64:79], v[168:171], v[212:215], v[64:79]
	v_mfma_f32_32x32x16_bf16 v[80:95], v[172:175], v[212:215], v[80:95]
	ds_read_b128 v[208:211], v151 offset:9280
	ds_read_b128 v[212:215], v151 offset:13888
	s_waitcnt vmcnt(7)
	ds_write_b128 v156, v[160:163]
	s_waitcnt vmcnt(6)
	ds_write_b128 v155, v[164:167]
	ds_read_b128 v[160:163], v152 offset:36960
	ds_read_b128 v[164:167], v152 offset:41568
	s_waitcnt lgkmcnt(5)
	v_mfma_f32_32x32x16_bf16 v[32:47], v[168:171], v[208:211], v[32:47]
	v_mfma_f32_32x32x16_bf16 v[48:63], v[172:175], v[208:211], v[48:63]
	ds_read_b128 v[208:211], v151 offset:96
	s_waitcnt lgkmcnt(5)
	v_mfma_f32_32x32x16_bf16 v[0:15], v[168:171], v[212:215], v[0:15]
	v_mfma_f32_32x32x16_bf16 v[16:31], v[172:175], v[212:215], v[16:31]
	ds_read_b128 v[212:215], v151 offset:4704
	s_setprio 0
	global_load_dwordx4 v[168:171], v[144:145], off offset:1536
	global_load_dwordx4 v[172:175], v[146:147], off offset:1536
	s_setprio 1
	s_waitcnt lgkmcnt(1)
	v_mfma_f32_32x32x16_bf16 v[96:111], v[160:163], v[208:211], v[96:111]
	v_mfma_f32_32x32x16_bf16 v[112:127], v[164:167], v[208:211], v[112:127]
	s_waitcnt lgkmcnt(0)
	v_mfma_f32_32x32x16_bf16 v[64:79], v[160:163], v[212:215], v[64:79]
	v_mfma_f32_32x32x16_bf16 v[80:95], v[164:167], v[212:215], v[80:95]
	ds_read_b128 v[208:211], v151 offset:9312
	ds_read_b128 v[212:215], v151 offset:13920
	s_waitcnt lgkmcnt(0)
	s_barrier
; template <bool trans>
; DI void gemm_core(const GTile& tl, const GTile& nx, bool has_next  , bool chain  , bool pre, u32x4 (&ra)[4], u32x4 (&rb)[4], char* smem, f32x16 (&acc)[2][4]) {
;     ...
;   const int nk = K / 64;
;   if (!pre) { G_LOAD(0); G_STORE(0); G_LOAD(1); }
;   for (int kt = 0; kt < nk; ++kt) {
;     __syncthreads();
;     G_COMPUTE(kt & 1, kt);
;   }
	s_waitcnt vmcnt(7)
	ds_write_b128 v148, v[184:187]
	s_waitcnt vmcnt(6)
	ds_write_b128 v148, v[188:191] offset:36864
	ds_read_b128 v[184:187], v150
	ds_read_b128 v[188:191], v150 offset:4608
	v_mfma_f32_32x32x16_bf16 v[32:47], v[160:163], v[208:211], v[32:47]
	v_mfma_f32_32x32x16_bf16 v[48:63], v[164:167], v[208:211], v[48:63]
	ds_read_b128 v[208:211], v149
	v_mfma_f32_32x32x16_bf16 v[0:15], v[160:163], v[212:215], v[0:15]
	v_mfma_f32_32x32x16_bf16 v[16:31], v[164:167], v[212:215], v[16:31]
	ds_read_b128 v[212:215], v149 offset:4608
	s_setprio 0
	global_load_dwordx4 v[160:163], v[136:137], off offset:1664
	global_load_dwordx4 v[164:167], v[138:139], off offset:1664
	s_setprio 1
	s_waitcnt lgkmcnt(1)
	v_mfma_f32_32x32x16_bf16 v[96:111], v[184:187], v[208:211], v[96:111]
	v_mfma_f32_32x32x16_bf16 v[112:127], v[188:191], v[208:211], v[112:127]
	s_waitcnt lgkmcnt(0)
	v_mfma_f32_32x32x16_bf16 v[64:79], v[184:187], v[212:215], v[64:79]
	v_mfma_f32_32x32x16_bf16 v[80:95], v[188:191], v[212:215], v[80:95]
	ds_read_b128 v[208:211], v149 offset:9216
	ds_read_b128 v[212:215], v149 offset:13824
	s_waitcnt vmcnt(7)
	ds_write_b128 v148, v[194:197] offset:9216
	s_waitcnt vmcnt(6)
	ds_write_b128 v148, v[198:201] offset:46080
	ds_read_b128 v[194:197], v150 offset:32
	ds_read_b128 v[198:201], v150 offset:4640
	s_waitcnt lgkmcnt(5)
	v_mfma_f32_32x32x16_bf16 v[32:47], v[184:187], v[208:211], v[32:47]
	v_mfma_f32_32x32x16_bf16 v[48:63], v[188:191], v[208:211], v[48:63]
	ds_read_b128 v[208:211], v149 offset:32
	s_waitcnt lgkmcnt(5)
	v_mfma_f32_32x32x16_bf16 v[0:15], v[184:187], v[212:215], v[0:15]
	v_mfma_f32_32x32x16_bf16 v[16:31], v[188:191], v[212:215], v[16:31]
	ds_read_b128 v[212:215], v149 offset:4640
	s_setprio 0
	global_load_dwordx4 v[184:187], v[140:141], off offset:1664
	global_load_dwordx4 v[188:191], v[142:143], off offset:1664
	s_setprio 1
	s_waitcnt lgkmcnt(1)
	v_mfma_f32_32x32x16_bf16 v[96:111], v[194:197], v[208:211], v[96:111]
	v_mfma_f32_32x32x16_bf16 v[112:127], v[198:201], v[208:211], v[112:127]
	s_waitcnt lgkmcnt(0)
	v_mfma_f32_32x32x16_bf16 v[64:79], v[194:197], v[212:215], v[64:79]
	v_mfma_f32_32x32x16_bf16 v[80:95], v[198:201], v[212:215], v[80:95]
	ds_read_b128 v[208:211], v149 offset:9248
	ds_read_b128 v[212:215], v149 offset:13856
	s_waitcnt vmcnt(7)
	ds_write_b128 v148, v[176:179] offset:18432
	s_waitcnt vmcnt(6)
	ds_write_b128 v148, v[180:183] offset:55296
	ds_read_b128 v[176:179], v150 offset:64
	ds_read_b128 v[180:183], v150 offset:4672
	s_waitcnt lgkmcnt(5)
	v_mfma_f32_32x32x16_bf16 v[32:47], v[194:197], v[208:211], v[32:47]
	v_mfma_f32_32x32x16_bf16 v[48:63], v[198:201], v[208:211], v[48:63]
	ds_read_b128 v[208:211], v149 offset:64
	s_waitcnt lgkmcnt(5)
	v_mfma_f32_32x32x16_bf16 v[0:15], v[194:197], v[212:215], v[0:15]
	v_mfma_f32_32x32x16_bf16 v[16:31], v[198:201], v[212:215], v[16:31]
	ds_read_b128 v[212:215], v149 offset:4672
	s_setprio 0
	global_load_dwordx4 v[194:197], v[132:133], off offset:1664
	global_load_dwordx4 v[198:201], v[134:135], off offset:1664
	s_setprio 1
	s_waitcnt lgkmcnt(1)
	v_mfma_f32_32x32x16_bf16 v[96:111], v[176:179], v[208:211], v[96:111]
	v_mfma_f32_32x32x16_bf16 v[112:127], v[180:183], v[208:211], v[112:127]
	s_waitcnt lgkmcnt(0)
	v_mfma_f32_32x32x16_bf16 v[64:79], v[176:179], v[212:215], v[64:79]
	v_mfma_f32_32x32x16_bf16 v[80:95], v[180:183], v[212:215], v[80:95]
	ds_read_b128 v[208:211], v149 offset:9280
	ds_read_b128 v[212:215], v149 offset:13888
	s_waitcnt vmcnt(7)
	ds_write_b128 v148, v[168:171] offset:27648
	s_waitcnt vmcnt(6)
	ds_write_b128 v148, v[172:175] offset:64512
	ds_read_b128 v[168:171], v150 offset:96
	ds_read_b128 v[172:175], v150 offset:4704
	s_waitcnt lgkmcnt(5)
	v_mfma_f32_32x32x16_bf16 v[32:47], v[176:179], v[208:211], v[32:47]
	v_mfma_f32_32x32x16_bf16 v[48:63], v[180:183], v[208:211], v[48:63]
	ds_read_b128 v[208:211], v149 offset:96
	s_waitcnt lgkmcnt(5)
	v_mfma_f32_32x32x16_bf16 v[0:15], v[176:179], v[212:215], v[0:15]
	v_mfma_f32_32x32x16_bf16 v[16:31], v[180:183], v[212:215], v[16:31]
	ds_read_b128 v[212:215], v149 offset:4704
	s_setprio 0
	global_load_dwordx4 v[176:179], v[144:145], off offset:1664
	global_load_dwordx4 v[180:183], v[146:147], off offset:1664
	s_setprio 1
	s_waitcnt lgkmcnt(1)
	v_mfma_f32_32x32x16_bf16 v[96:111], v[168:171], v[208:211], v[96:111]
	v_mfma_f32_32x32x16_bf16 v[112:127], v[172:175], v[208:211], v[112:127]
	s_waitcnt lgkmcnt(0)
	v_mfma_f32_32x32x16_bf16 v[64:79], v[168:171], v[212:215], v[64:79]
	v_mfma_f32_32x32x16_bf16 v[80:95], v[172:175], v[212:215], v[80:95]
	ds_read_b128 v[208:211], v149 offset:9312
	ds_read_b128 v[212:215], v149 offset:13920
	s_waitcnt lgkmcnt(0)
	s_barrier
; template <bool trans>
; DI void gemm_core(const GTile& tl, const GTile& nx, bool has_next  , bool chain  , bool pre, u32x4 (&ra)[4], u32x4 (&rb)[4], char* smem, f32x16 (&acc)[2][4]) {
;     ...
;   const int nk = K / 64;
;   if (!pre) { G_LOAD(0); G_STORE(0); G_LOAD(1); }
;   for (int kt = 0; kt < nk; ++kt) {
;     __syncthreads();
;     G_COMPUTE(kt & 1, kt);
;   }
	s_waitcnt vmcnt(7)
	ds_write_b128 v192, v[160:163]
	s_waitcnt vmcnt(6)
	ds_write_b128 v159, v[164:167]
	ds_read_b128 v[160:163], v152 offset:36864
	ds_read_b128 v[164:167], v152 offset:41472
	v_mfma_f32_32x32x16_bf16 v[32:47], v[168:171], v[208:211], v[32:47]
	v_mfma_f32_32x32x16_bf16 v[48:63], v[172:175], v[208:211], v[48:63]
	ds_read_b128 v[208:211], v151
	v_mfma_f32_32x32x16_bf16 v[0:15], v[168:171], v[212:215], v[0:15]
	v_mfma_f32_32x32x16_bf16 v[16:31], v[172:175], v[212:215], v[16:31]
	ds_read_b128 v[212:215], v151 offset:4608
	s_setprio 0
	global_load_dwordx4 v[168:171], v[136:137], off offset:1792
	global_load_dwordx4 v[172:175], v[138:139], off offset:1792
	s_setprio 1
	s_waitcnt lgkmcnt(1)
	v_mfma_f32_32x32x16_bf16 v[96:111], v[160:163], v[208:211], v[96:111]
	v_mfma_f32_32x32x16_bf16 v[112:127], v[164:167], v[208:211], v[112:127]
	s_waitcnt lgkmcnt(0)
	v_mfma_f32_32x32x16_bf16 v[64:79], v[160:163], v[212:215], v[64:79]
	v_mfma_f32_32x32x16_bf16 v[80:95], v[164:167], v[212:215], v[80:95]
	ds_read_b128 v[208:211], v151 offset:9216
	ds_read_b128 v[212:215], v151 offset:13824
	s_waitcnt vmcnt(7)
	ds_write_b128 v158, v[184:187]
	s_waitcnt vmcnt(6)
	ds_write_b128 v157, v[188:191]
	ds_read_b128 v[184:187], v152 offset:36896
	ds_read_b128 v[188:191], v152 offset:41504
	s_waitcnt lgkmcnt(5)
	v_mfma_f32_32x32x16_bf16 v[32:47], v[160:163], v[208:211], v[32:47]
	v_mfma_f32_32x32x16_bf16 v[48:63], v[164:167], v[208:211], v[48:63]
	ds_read_b128 v[208:211], v151 offset:32
	s_waitcnt lgkmcnt(5)
	v_mfma_f32_32x32x16_bf16 v[0:15], v[160:163], v[212:215], v[0:15]
	v_mfma_f32_32x32x16_bf16 v[16:31], v[164:167], v[212:215], v[16:31]
	ds_read_b128 v[212:215], v151 offset:4640
	s_setprio 0
	global_load_dwordx4 v[160:163], v[140:141], off offset:1792
	global_load_dwordx4 v[164:167], v[142:143], off offset:1792
	s_setprio 1
	s_waitcnt lgkmcnt(1)
	v_mfma_f32_32x32x16_bf16 v[96:111], v[184:187], v[208:211], v[96:111]
	v_mfma_f32_32x32x16_bf16 v[112:127], v[188:191], v[208:211], v[112:127]
	s_waitcnt lgkmcnt(0)
	v_mfma_f32_32x32x16_bf16 v[64:79], v[184:187], v[212:215], v[64:79]
	v_mfma_f32_32x32x16_bf16 v[80:95], v[188:191], v[212:215], v[80:95]
	ds_read_b128 v[208:211], v151 offset:9248
	ds_read_b128 v[212:215], v151 offset:13856
	s_waitcnt vmcnt(7)
	ds_write_b128 v154, v[194:197]
	s_waitcnt vmcnt(6)
	ds_write_b128 v153, v[198:201]
	ds_read_b128 v[194:197], v152 offset:36928
	ds_read_b128 v[198:201], v152 offset:41536
	s_waitcnt lgkmcnt(5)
	v_mfma_f32_32x32x16_bf16 v[32:47], v[184:187], v[208:211], v[32:47]
	v_mfma_f32_32x32x16_bf16 v[48:63], v[188:191], v[208:211], v[48:63]
	ds_read_b128 v[208:211], v151 offset:64
	s_waitcnt lgkmcnt(5)
	v_mfma_f32_32x32x16_bf16 v[0:15], v[184:187], v[212:215], v[0:15]
	v_mfma_f32_32x32x16_bf16 v[16:31], v[188:191], v[212:215], v[16:31]
	ds_read_b128 v[212:215], v151 offset:4672
	s_setprio 0
	global_load_dwordx4 v[184:187], v[132:133], off offset:1792
	global_load_dwordx4 v[188:191], v[134:135], off offset:1792
	s_setprio 1
	s_waitcnt lgkmcnt(1)
	v_mfma_f32_32x32x16_bf16 v[96:111], v[194:197], v[208:211], v[96:111]
	v_mfma_f32_32x32x16_bf16 v[112:127], v[198:201], v[208:211], v[112:127]
	s_waitcnt lgkmcnt(0)
	v_mfma_f32_32x32x16_bf16 v[64:79], v[194:197], v[212:215], v[64:79]
	v_mfma_f32_32x32x16_bf16 v[80:95], v[198:201], v[212:215], v[80:95]
	ds_read_b128 v[208:211], v151 offset:9280
	ds_read_b128 v[212:215], v151 offset:13888
	s_waitcnt vmcnt(7)
	ds_write_b128 v156, v[176:179]
	s_waitcnt vmcnt(6)
	ds_write_b128 v155, v[180:183]
	ds_read_b128 v[176:179], v152 offset:36960
	ds_read_b128 v[180:183], v152 offset:41568
	s_waitcnt lgkmcnt(5)
	v_mfma_f32_32x32x16_bf16 v[32:47], v[194:197], v[208:211], v[32:47]
	v_mfma_f32_32x32x16_bf16 v[48:63], v[198:201], v[208:211], v[48:63]
	ds_read_b128 v[208:211], v151 offset:96
	s_waitcnt lgkmcnt(5)
	v_mfma_f32_32x32x16_bf16 v[0:15], v[194:197], v[212:215], v[0:15]
	v_mfma_f32_32x32x16_bf16 v[16:31], v[198:201], v[212:215], v[16:31]
	ds_read_b128 v[212:215], v151 offset:4704
	s_setprio 0
	global_load_dwordx4 v[194:197], v[144:145], off offset:1792
	global_load_dwordx4 v[198:201], v[146:147], off offset:1792
	s_setprio 1
	s_waitcnt lgkmcnt(1)
	v_mfma_f32_32x32x16_bf16 v[96:111], v[176:179], v[208:211], v[96:111]
	v_mfma_f32_32x32x16_bf16 v[112:127], v[180:183], v[208:211], v[112:127]
	s_waitcnt lgkmcnt(0)
	v_mfma_f32_32x32x16_bf16 v[64:79], v[176:179], v[212:215], v[64:79]
	v_mfma_f32_32x32x16_bf16 v[80:95], v[180:183], v[212:215], v[80:95]
	ds_read_b128 v[208:211], v151 offset:9312
	ds_read_b128 v[212:215], v151 offset:13920
	s_waitcnt lgkmcnt(0)
	s_barrier
; template <bool trans>
; DI void gemm_core(const GTile& tl, const GTile& nx, bool has_next  , bool chain  , bool pre, u32x4 (&ra)[4], u32x4 (&rb)[4], char* smem, f32x16 (&acc)[2][4]) {
;     ...
;   const int nk = K / 64;
;   if (!pre) { G_LOAD(0); G_STORE(0); G_LOAD(1); }
;   for (int kt = 0; kt < nk; ++kt) {
;     __syncthreads();
;     G_COMPUTE(kt & 1, kt);
;   }
	s_waitcnt vmcnt(7)
	ds_write_b128 v148, v[168:171]
	s_waitcnt vmcnt(6)
	ds_write_b128 v148, v[172:175] offset:36864
	ds_read_b128 v[168:171], v150
	ds_read_b128 v[172:175], v150 offset:4608
	v_mfma_f32_32x32x16_bf16 v[32:47], v[176:179], v[208:211], v[32:47]
	v_mfma_f32_32x32x16_bf16 v[48:63], v[180:183], v[208:211], v[48:63]
	ds_read_b128 v[208:211], v149
	v_mfma_f32_32x32x16_bf16 v[0:15], v[176:179], v[212:215], v[0:15]
	v_mfma_f32_32x32x16_bf16 v[16:31], v[180:183], v[212:215], v[16:31]
	ds_read_b128 v[212:215], v149 offset:4608
	s_setprio 0
	global_load_dwordx4 v[176:179], v[136:137], off offset:1920
	global_load_dwordx4 v[180:183], v[138:139], off offset:1920
	s_setprio 1
	s_waitcnt lgkmcnt(1)
	v_mfma_f32_32x32x16_bf16 v[96:111], v[168:171], v[208:211], v[96:111]
	v_mfma_f32_32x32x16_bf16 v[112:127], v[172:175], v[208:211], v[112:127]
	s_waitcnt lgkmcnt(0)
	v_mfma_f32_32x32x16_bf16 v[64:79], v[168:171], v[212:215], v[64:79]
	v_mfma_f32_32x32x16_bf16 v[80:95], v[172:175], v[212:215], v[80:95]
	ds_read_b128 v[208:211], v149 offset:9216
	ds_read_b128 v[212:215], v149 offset:13824
	s_waitcnt vmcnt(7)
	ds_write_b128 v148, v[160:163] offset:9216
	s_waitcnt vmcnt(6)
	ds_write_b128 v148, v[164:167] offset:46080
	ds_read_b128 v[160:163], v150 offset:32
	ds_read_b128 v[164:167], v150 offset:4640
	s_waitcnt lgkmcnt(5)
	v_mfma_f32_32x32x16_bf16 v[32:47], v[168:171], v[208:211], v[32:47]
	v_mfma_f32_32x32x16_bf16 v[48:63], v[172:175], v[208:211], v[48:63]
	ds_read_b128 v[208:211], v149 offset:32
	s_waitcnt lgkmcnt(5)
	v_mfma_f32_32x32x16_bf16 v[0:15], v[168:171], v[212:215], v[0:15]
	v_mfma_f32_32x32x16_bf16 v[16:31], v[172:175], v[212:215], v[16:31]
	ds_read_b128 v[212:215], v149 offset:4640
	s_setprio 0
	global_load_dwordx4 v[168:171], v[140:141], off offset:1920
	global_load_dwordx4 v[172:175], v[142:143], off offset:1920
	s_setprio 1
	s_waitcnt lgkmcnt(1)
	v_mfma_f32_32x32x16_bf16 v[96:111], v[160:163], v[208:211], v[96:111]
	v_mfma_f32_32x32x16_bf16 v[112:127], v[164:167], v[208:211], v[112:127]
	s_waitcnt lgkmcnt(0)
	v_mfma_f32_32x32x16_bf16 v[64:79], v[160:163], v[212:215], v[64:79]
	v_mfma_f32_32x32x16_bf16 v[80:95], v[164:167], v[212:215], v[80:95]
	ds_read_b128 v[208:211], v149 offset:9248
	ds_read_b128 v[212:215], v149 offset:13856
	s_waitcnt vmcnt(7)
	ds_write_b128 v148, v[184:187] offset:18432
	s_waitcnt vmcnt(6)
	ds_write_b128 v148, v[188:191] offset:55296
	ds_read_b128 v[184:187], v150 offset:64
	ds_read_b128 v[188:191], v150 offset:4672
	s_waitcnt lgkmcnt(5)
	v_mfma_f32_32x32x16_bf16 v[32:47], v[160:163], v[208:211], v[32:47]
	v_mfma_f32_32x32x16_bf16 v[48:63], v[164:167], v[208:211], v[48:63]
	ds_read_b128 v[208:211], v149 offset:64
	s_waitcnt lgkmcnt(5)
	v_mfma_f32_32x32x16_bf16 v[0:15], v[160:163], v[212:215], v[0:15]
	v_mfma_f32_32x32x16_bf16 v[16:31], v[164:167], v[212:215], v[16:31]
	ds_read_b128 v[212:215], v149 offset:4672
	s_setprio 0
	global_load_dwordx4 v[160:163], v[132:133], off offset:1920
	global_load_dwordx4 v[164:167], v[134:135], off offset:1920
	s_setprio 1
	s_waitcnt lgkmcnt(1)
	v_mfma_f32_32x32x16_bf16 v[96:111], v[184:187], v[208:211], v[96:111]
	v_mfma_f32_32x32x16_bf16 v[112:127], v[188:191], v[208:211], v[112:127]
	s_waitcnt lgkmcnt(0)
	v_mfma_f32_32x32x16_bf16 v[64:79], v[184:187], v[212:215], v[64:79]
	v_mfma_f32_32x32x16_bf16 v[80:95], v[188:191], v[212:215], v[80:95]
	ds_read_b128 v[208:211], v149 offset:9280
	ds_read_b128 v[212:215], v149 offset:13888
	s_waitcnt vmcnt(7)
	ds_write_b128 v148, v[194:197] offset:27648
	s_waitcnt vmcnt(6)
	ds_write_b128 v148, v[198:201] offset:64512
	ds_read_b128 v[194:197], v150 offset:96
	ds_read_b128 v[198:201], v150 offset:4704
	s_waitcnt lgkmcnt(5)
	v_mfma_f32_32x32x16_bf16 v[32:47], v[184:187], v[208:211], v[32:47]
	v_mfma_f32_32x32x16_bf16 v[48:63], v[188:191], v[208:211], v[48:63]
	ds_read_b128 v[208:211], v149 offset:96
	s_waitcnt lgkmcnt(5)
	v_mfma_f32_32x32x16_bf16 v[0:15], v[184:187], v[212:215], v[0:15]
	v_mfma_f32_32x32x16_bf16 v[16:31], v[188:191], v[212:215], v[16:31]
	ds_read_b128 v[212:215], v149 offset:4704
	s_setprio 0
	global_load_dwordx4 v[184:187], v[144:145], off offset:1920
	global_load_dwordx4 v[188:191], v[146:147], off offset:1920
	s_setprio 1
	s_waitcnt lgkmcnt(1)
	v_mfma_f32_32x32x16_bf16 v[96:111], v[194:197], v[208:211], v[96:111]
	v_mfma_f32_32x32x16_bf16 v[112:127], v[198:201], v[208:211], v[112:127]
	s_waitcnt lgkmcnt(0)
	v_mfma_f32_32x32x16_bf16 v[64:79], v[194:197], v[212:215], v[64:79]
	v_mfma_f32_32x32x16_bf16 v[80:95], v[198:201], v[212:215], v[80:95]
	ds_read_b128 v[208:211], v149 offset:9312
	ds_read_b128 v[212:215], v149 offset:13920
	s_waitcnt lgkmcnt(0)
	s_barrier
; template <bool trans>
; DI void gemm_core(const GTile& tl, const GTile& nx, bool has_next  , bool chain  , bool pre, u32x4 (&ra)[4], u32x4 (&rb)[4], char* smem, f32x16 (&acc)[2][4]) {
;     ...
;   const int nk = K / 64;
;   if (!pre) { G_LOAD(0); G_STORE(0); G_LOAD(1); }
;   for (int kt = 0; kt < nk; ++kt) {
;     __syncthreads();
;     G_COMPUTE(kt & 1, kt);
;   }
	s_waitcnt vmcnt(7)
	ds_write_b128 v192, v[176:179]
	s_waitcnt vmcnt(6)
	ds_write_b128 v159, v[180:183]
	ds_read_b128 v[176:179], v152 offset:36864
	ds_read_b128 v[180:183], v152 offset:41472
	v_mfma_f32_32x32x16_bf16 v[32:47], v[194:197], v[208:211], v[32:47]
	v_mfma_f32_32x32x16_bf16 v[48:63], v[198:201], v[208:211], v[48:63]
	ds_read_b128 v[208:211], v151
	v_mfma_f32_32x32x16_bf16 v[0:15], v[194:197], v[212:215], v[0:15]
	v_mfma_f32_32x32x16_bf16 v[16:31], v[198:201], v[212:215], v[16:31]
	ds_read_b128 v[212:215], v151 offset:4608
	s_setprio 0
	global_load_dwordx4 v[194:197], v[136:137], off offset:2048
	global_load_dwordx4 v[198:201], v[138:139], off offset:2048
	s_setprio 1
	s_waitcnt lgkmcnt(1)
	v_mfma_f32_32x32x16_bf16 v[96:111], v[176:179], v[208:211], v[96:111]
	v_mfma_f32_32x32x16_bf16 v[112:127], v[180:183], v[208:211], v[112:127]
	s_waitcnt lgkmcnt(0)
	v_mfma_f32_32x32x16_bf16 v[64:79], v[176:179], v[212:215], v[64:79]
	v_mfma_f32_32x32x16_bf16 v[80:95], v[180:183], v[212:215], v[80:95]
	ds_read_b128 v[208:211], v151 offset:9216
	ds_read_b128 v[212:215], v151 offset:13824
	s_waitcnt vmcnt(7)
	ds_write_b128 v158, v[168:171]
	s_waitcnt vmcnt(6)
	ds_write_b128 v157, v[172:175]
	ds_read_b128 v[168:171], v152 offset:36896
	ds_read_b128 v[172:175], v152 offset:41504
	s_waitcnt lgkmcnt(5)
	v_mfma_f32_32x32x16_bf16 v[32:47], v[176:179], v[208:211], v[32:47]
	v_mfma_f32_32x32x16_bf16 v[48:63], v[180:183], v[208:211], v[48:63]
	ds_read_b128 v[208:211], v151 offset:32
	s_waitcnt lgkmcnt(5)
	v_mfma_f32_32x32x16_bf16 v[0:15], v[176:179], v[212:215], v[0:15]
	v_mfma_f32_32x32x16_bf16 v[16:31], v[180:183], v[212:215], v[16:31]
	ds_read_b128 v[212:215], v151 offset:4640
	s_setprio 0
	global_load_dwordx4 v[176:179], v[140:141], off offset:2048
	global_load_dwordx4 v[180:183], v[142:143], off offset:2048
	s_setprio 1
	s_waitcnt lgkmcnt(1)
	v_mfma_f32_32x32x16_bf16 v[96:111], v[168:171], v[208:211], v[96:111]
	v_mfma_f32_32x32x16_bf16 v[112:127], v[172:175], v[208:211], v[112:127]
	s_waitcnt lgkmcnt(0)
	v_mfma_f32_32x32x16_bf16 v[64:79], v[168:171], v[212:215], v[64:79]
	v_mfma_f32_32x32x16_bf16 v[80:95], v[172:175], v[212:215], v[80:95]
	ds_read_b128 v[208:211], v151 offset:9248
	ds_read_b128 v[212:215], v151 offset:13856
	s_waitcnt vmcnt(7)
	ds_write_b128 v154, v[160:163]
	s_waitcnt vmcnt(6)
	ds_write_b128 v153, v[164:167]
	ds_read_b128 v[160:163], v152 offset:36928
	ds_read_b128 v[164:167], v152 offset:41536
	s_waitcnt lgkmcnt(5)
	v_mfma_f32_32x32x16_bf16 v[32:47], v[168:171], v[208:211], v[32:47]
	v_mfma_f32_32x32x16_bf16 v[48:63], v[172:175], v[208:211], v[48:63]
	ds_read_b128 v[208:211], v151 offset:64
	s_waitcnt lgkmcnt(5)
	v_mfma_f32_32x32x16_bf16 v[0:15], v[168:171], v[212:215], v[0:15]
	v_mfma_f32_32x32x16_bf16 v[16:31], v[172:175], v[212:215], v[16:31]
	ds_read_b128 v[212:215], v151 offset:4672
	s_setprio 0
	global_load_dwordx4 v[168:171], v[132:133], off offset:2048
	global_load_dwordx4 v[172:175], v[134:135], off offset:2048
	s_setprio 1
	s_waitcnt lgkmcnt(1)
	v_mfma_f32_32x32x16_bf16 v[96:111], v[160:163], v[208:211], v[96:111]
	v_mfma_f32_32x32x16_bf16 v[112:127], v[164:167], v[208:211], v[112:127]
	s_waitcnt lgkmcnt(0)
	v_mfma_f32_32x32x16_bf16 v[64:79], v[160:163], v[212:215], v[64:79]
	v_mfma_f32_32x32x16_bf16 v[80:95], v[164:167], v[212:215], v[80:95]
	ds_read_b128 v[208:211], v151 offset:9280
	ds_read_b128 v[212:215], v151 offset:13888
	s_waitcnt vmcnt(7)
	ds_write_b128 v156, v[184:187]
	s_waitcnt vmcnt(6)
	ds_write_b128 v155, v[188:191]
	ds_read_b128 v[184:187], v152 offset:36960
	ds_read_b128 v[188:191], v152 offset:41568
	s_waitcnt lgkmcnt(5)
	v_mfma_f32_32x32x16_bf16 v[32:47], v[160:163], v[208:211], v[32:47]
	v_mfma_f32_32x32x16_bf16 v[48:63], v[164:167], v[208:211], v[48:63]
	ds_read_b128 v[208:211], v151 offset:96
	s_waitcnt lgkmcnt(5)
	v_mfma_f32_32x32x16_bf16 v[0:15], v[160:163], v[212:215], v[0:15]
	v_mfma_f32_32x32x16_bf16 v[16:31], v[164:167], v[212:215], v[16:31]
	ds_read_b128 v[212:215], v151 offset:4704
	s_setprio 0
	global_load_dwordx4 v[160:163], v[144:145], off offset:2048
	global_load_dwordx4 v[164:167], v[146:147], off offset:2048
	s_setprio 1
	s_waitcnt lgkmcnt(1)
	v_mfma_f32_32x32x16_bf16 v[96:111], v[184:187], v[208:211], v[96:111]
	v_mfma_f32_32x32x16_bf16 v[112:127], v[188:191], v[208:211], v[112:127]
	s_waitcnt lgkmcnt(0)
	v_mfma_f32_32x32x16_bf16 v[64:79], v[184:187], v[212:215], v[64:79]
	v_mfma_f32_32x32x16_bf16 v[80:95], v[188:191], v[212:215], v[80:95]
	ds_read_b128 v[208:211], v151 offset:9312
	ds_read_b128 v[212:215], v151 offset:13920
	s_waitcnt lgkmcnt(0)
	s_barrier
; template <bool trans>
; DI void gemm_core(const GTile& tl, const GTile& nx, bool has_next  , bool chain  , bool pre, u32x4 (&ra)[4], u32x4 (&rb)[4], char* smem, f32x16 (&acc)[2][4]) {
;     ...
;   const int nk = K / 64;
;   if (!pre) { G_LOAD(0); G_STORE(0); G_LOAD(1); }
;   for (int kt = 0; kt < nk; ++kt) {
;     __syncthreads();
;     G_COMPUTE(kt & 1, kt);
;   }
	s_waitcnt vmcnt(7)
	ds_write_b128 v148, v[194:197]
	s_waitcnt vmcnt(6)
	ds_write_b128 v148, v[198:201] offset:36864
	ds_read_b128 v[194:197], v150
	ds_read_b128 v[198:201], v150 offset:4608
	v_mfma_f32_32x32x16_bf16 v[32:47], v[184:187], v[208:211], v[32:47]
	v_mfma_f32_32x32x16_bf16 v[48:63], v[188:191], v[208:211], v[48:63]
	ds_read_b128 v[208:211], v149
	v_mfma_f32_32x32x16_bf16 v[0:15], v[184:187], v[212:215], v[0:15]
	v_mfma_f32_32x32x16_bf16 v[16:31], v[188:191], v[212:215], v[16:31]
	ds_read_b128 v[212:215], v149 offset:4608
	s_setprio 0
	global_load_dwordx4 v[184:187], v[136:137], off offset:2176
	global_load_dwordx4 v[188:191], v[138:139], off offset:2176
	s_setprio 1
	s_waitcnt lgkmcnt(1)
	v_mfma_f32_32x32x16_bf16 v[96:111], v[194:197], v[208:211], v[96:111]
	v_mfma_f32_32x32x16_bf16 v[112:127], v[198:201], v[208:211], v[112:127]
	s_waitcnt lgkmcnt(0)
	v_mfma_f32_32x32x16_bf16 v[64:79], v[194:197], v[212:215], v[64:79]
	v_mfma_f32_32x32x16_bf16 v[80:95], v[198:201], v[212:215], v[80:95]
	ds_read_b128 v[208:211], v149 offset:9216
	ds_read_b128 v[212:215], v149 offset:13824
	s_waitcnt vmcnt(7)
	ds_write_b128 v148, v[176:179] offset:9216
	s_waitcnt vmcnt(6)
	ds_write_b128 v148, v[180:183] offset:46080
	ds_read_b128 v[176:179], v150 offset:32
	ds_read_b128 v[180:183], v150 offset:4640
	s_waitcnt lgkmcnt(5)
	v_mfma_f32_32x32x16_bf16 v[32:47], v[194:197], v[208:211], v[32:47]
	v_mfma_f32_32x32x16_bf16 v[48:63], v[198:201], v[208:211], v[48:63]
	ds_read_b128 v[208:211], v149 offset:32
	s_waitcnt lgkmcnt(5)
	v_mfma_f32_32x32x16_bf16 v[0:15], v[194:197], v[212:215], v[0:15]
	v_mfma_f32_32x32x16_bf16 v[16:31], v[198:201], v[212:215], v[16:31]
	ds_read_b128 v[212:215], v149 offset:4640
	s_setprio 0
	global_load_dwordx4 v[194:197], v[140:141], off offset:2176
	global_load_dwordx4 v[198:201], v[142:143], off offset:2176
	s_setprio 1
	s_waitcnt lgkmcnt(1)
	v_mfma_f32_32x32x16_bf16 v[96:111], v[176:179], v[208:211], v[96:111]
	v_mfma_f32_32x32x16_bf16 v[112:127], v[180:183], v[208:211], v[112:127]
	s_waitcnt lgkmcnt(0)
	v_mfma_f32_32x32x16_bf16 v[64:79], v[176:179], v[212:215], v[64:79]
	v_mfma_f32_32x32x16_bf16 v[80:95], v[180:183], v[212:215], v[80:95]
	ds_read_b128 v[208:211], v149 offset:9248
	ds_read_b128 v[212:215], v149 offset:13856
	s_waitcnt vmcnt(7)
	ds_write_b128 v148, v[168:171] offset:18432
	s_waitcnt vmcnt(6)
	ds_write_b128 v148, v[172:175] offset:55296
	ds_read_b128 v[168:171], v150 offset:64
	ds_read_b128 v[172:175], v150 offset:4672
	s_waitcnt lgkmcnt(5)
	v_mfma_f32_32x32x16_bf16 v[32:47], v[176:179], v[208:211], v[32:47]
	v_mfma_f32_32x32x16_bf16 v[48:63], v[180:183], v[208:211], v[48:63]
	ds_read_b128 v[208:211], v149 offset:64
	s_waitcnt lgkmcnt(5)
	v_mfma_f32_32x32x16_bf16 v[0:15], v[176:179], v[212:215], v[0:15]
	v_mfma_f32_32x32x16_bf16 v[16:31], v[180:183], v[212:215], v[16:31]
	ds_read_b128 v[212:215], v149 offset:4672
	s_setprio 0
	global_load_dwordx4 v[176:179], v[132:133], off offset:2176
	global_load_dwordx4 v[180:183], v[134:135], off offset:2176
	s_setprio 1
	s_waitcnt lgkmcnt(1)
	v_mfma_f32_32x32x16_bf16 v[96:111], v[168:171], v[208:211], v[96:111]
	v_mfma_f32_32x32x16_bf16 v[112:127], v[172:175], v[208:211], v[112:127]
	s_waitcnt lgkmcnt(0)
	v_mfma_f32_32x32x16_bf16 v[64:79], v[168:171], v[212:215], v[64:79]
	v_mfma_f32_32x32x16_bf16 v[80:95], v[172:175], v[212:215], v[80:95]
	ds_read_b128 v[208:211], v149 offset:9280
	ds_read_b128 v[212:215], v149 offset:13888
	s_waitcnt vmcnt(7)
	ds_write_b128 v148, v[160:163] offset:27648
	s_waitcnt vmcnt(6)
	ds_write_b128 v148, v[164:167] offset:64512
	ds_read_b128 v[160:163], v150 offset:96
	ds_read_b128 v[164:167], v150 offset:4704
	s_waitcnt lgkmcnt(5)
	v_mfma_f32_32x32x16_bf16 v[32:47], v[168:171], v[208:211], v[32:47]
	v_mfma_f32_32x32x16_bf16 v[48:63], v[172:175], v[208:211], v[48:63]
	ds_read_b128 v[208:211], v149 offset:96
	s_waitcnt lgkmcnt(5)
	v_mfma_f32_32x32x16_bf16 v[0:15], v[168:171], v[212:215], v[0:15]
	v_mfma_f32_32x32x16_bf16 v[16:31], v[172:175], v[212:215], v[16:31]
	ds_read_b128 v[212:215], v149 offset:4704
	s_setprio 0
	global_load_dwordx4 v[168:171], v[144:145], off offset:2176
	global_load_dwordx4 v[172:175], v[146:147], off offset:2176
	s_setprio 1
	s_waitcnt lgkmcnt(1)
	v_mfma_f32_32x32x16_bf16 v[96:111], v[160:163], v[208:211], v[96:111]
	v_mfma_f32_32x32x16_bf16 v[112:127], v[164:167], v[208:211], v[112:127]
	s_waitcnt lgkmcnt(0)
	v_mfma_f32_32x32x16_bf16 v[64:79], v[160:163], v[212:215], v[64:79]
	v_mfma_f32_32x32x16_bf16 v[80:95], v[164:167], v[212:215], v[80:95]
	ds_read_b128 v[208:211], v149 offset:9312
	ds_read_b128 v[212:215], v149 offset:13920
	s_waitcnt lgkmcnt(0)
	s_barrier
; template <bool trans>
; DI void gemm_core(const GTile& tl, const GTile& nx, bool has_next  , bool chain  , bool pre, u32x4 (&ra)[4], u32x4 (&rb)[4], char* smem, f32x16 (&acc)[2][4]) {
;     ...
;   const int nk = K / 64;
;   if (!pre) { G_LOAD(0); G_STORE(0); G_LOAD(1); }
;   for (int kt = 0; kt < nk; ++kt) {
;     __syncthreads();
;     G_COMPUTE(kt & 1, kt);
;   }
	s_waitcnt vmcnt(7)
	ds_write_b128 v192, v[184:187]
	s_waitcnt vmcnt(6)
	ds_write_b128 v159, v[188:191]
	ds_read_b128 v[184:187], v152 offset:36864
	ds_read_b128 v[188:191], v152 offset:41472
	v_mfma_f32_32x32x16_bf16 v[32:47], v[160:163], v[208:211], v[32:47]
	v_mfma_f32_32x32x16_bf16 v[48:63], v[164:167], v[208:211], v[48:63]
	ds_read_b128 v[208:211], v151
	v_mfma_f32_32x32x16_bf16 v[0:15], v[160:163], v[212:215], v[0:15]
	v_mfma_f32_32x32x16_bf16 v[16:31], v[164:167], v[212:215], v[16:31]
	ds_read_b128 v[212:215], v151 offset:4608
	s_setprio 0
	global_load_dwordx4 v[160:163], v[136:137], off offset:2304
	global_load_dwordx4 v[164:167], v[138:139], off offset:2304
	s_setprio 1
	s_waitcnt lgkmcnt(1)
	v_mfma_f32_32x32x16_bf16 v[96:111], v[184:187], v[208:211], v[96:111]
	v_mfma_f32_32x32x16_bf16 v[112:127], v[188:191], v[208:211], v[112:127]
	s_waitcnt lgkmcnt(0)
	v_mfma_f32_32x32x16_bf16 v[64:79], v[184:187], v[212:215], v[64:79]
	v_mfma_f32_32x32x16_bf16 v[80:95], v[188:191], v[212:215], v[80:95]
	ds_read_b128 v[208:211], v151 offset:9216
	ds_read_b128 v[212:215], v151 offset:13824
	s_waitcnt vmcnt(7)
	ds_write_b128 v158, v[194:197]
	s_waitcnt vmcnt(6)
	ds_write_b128 v157, v[198:201]
	ds_read_b128 v[194:197], v152 offset:36896
	ds_read_b128 v[198:201], v152 offset:41504
	s_waitcnt lgkmcnt(5)
	v_mfma_f32_32x32x16_bf16 v[32:47], v[184:187], v[208:211], v[32:47]
	v_mfma_f32_32x32x16_bf16 v[48:63], v[188:191], v[208:211], v[48:63]
	ds_read_b128 v[208:211], v151 offset:32
	s_waitcnt lgkmcnt(5)
	v_mfma_f32_32x32x16_bf16 v[0:15], v[184:187], v[212:215], v[0:15]
	v_mfma_f32_32x32x16_bf16 v[16:31], v[188:191], v[212:215], v[16:31]
	ds_read_b128 v[212:215], v151 offset:4640
	s_setprio 0
	global_load_dwordx4 v[184:187], v[140:141], off offset:2304
	global_load_dwordx4 v[188:191], v[142:143], off offset:2304
	s_setprio 1
	s_waitcnt lgkmcnt(1)
	v_mfma_f32_32x32x16_bf16 v[96:111], v[194:197], v[208:211], v[96:111]
	v_mfma_f32_32x32x16_bf16 v[112:127], v[198:201], v[208:211], v[112:127]
	s_waitcnt lgkmcnt(0)
	v_mfma_f32_32x32x16_bf16 v[64:79], v[194:197], v[212:215], v[64:79]
	v_mfma_f32_32x32x16_bf16 v[80:95], v[198:201], v[212:215], v[80:95]
	ds_read_b128 v[208:211], v151 offset:9248
	ds_read_b128 v[212:215], v151 offset:13856
	s_waitcnt vmcnt(7)
	ds_write_b128 v154, v[176:179]
	s_waitcnt vmcnt(6)
	ds_write_b128 v153, v[180:183]
	ds_read_b128 v[176:179], v152 offset:36928
	ds_read_b128 v[180:183], v152 offset:41536
	s_waitcnt lgkmcnt(5)
	v_mfma_f32_32x32x16_bf16 v[32:47], v[194:197], v[208:211], v[32:47]
	v_mfma_f32_32x32x16_bf16 v[48:63], v[198:201], v[208:211], v[48:63]
	ds_read_b128 v[208:211], v151 offset:64
	s_waitcnt lgkmcnt(5)
	v_mfma_f32_32x32x16_bf16 v[0:15], v[194:197], v[212:215], v[0:15]
	v_mfma_f32_32x32x16_bf16 v[16:31], v[198:201], v[212:215], v[16:31]
	ds_read_b128 v[212:215], v151 offset:4672
	s_setprio 0
	global_load_dwordx4 v[194:197], v[132:133], off offset:2304
	global_load_dwordx4 v[198:201], v[134:135], off offset:2304
	s_setprio 1
	s_waitcnt lgkmcnt(1)
	v_mfma_f32_32x32x16_bf16 v[96:111], v[176:179], v[208:211], v[96:111]
	v_mfma_f32_32x32x16_bf16 v[112:127], v[180:183], v[208:211], v[112:127]
	s_waitcnt lgkmcnt(0)
	v_mfma_f32_32x32x16_bf16 v[64:79], v[176:179], v[212:215], v[64:79]
	v_mfma_f32_32x32x16_bf16 v[80:95], v[180:183], v[212:215], v[80:95]
	ds_read_b128 v[208:211], v151 offset:9280
	ds_read_b128 v[212:215], v151 offset:13888
	s_waitcnt vmcnt(7)
	ds_write_b128 v156, v[168:171]
	s_waitcnt vmcnt(6)
	ds_write_b128 v155, v[172:175]
	ds_read_b128 v[168:171], v152 offset:36960
	ds_read_b128 v[172:175], v152 offset:41568
	s_waitcnt lgkmcnt(5)
	v_mfma_f32_32x32x16_bf16 v[32:47], v[176:179], v[208:211], v[32:47]
	v_mfma_f32_32x32x16_bf16 v[48:63], v[180:183], v[208:211], v[48:63]
	ds_read_b128 v[208:211], v151 offset:96
	s_waitcnt lgkmcnt(5)
	v_mfma_f32_32x32x16_bf16 v[0:15], v[176:179], v[212:215], v[0:15]
	v_mfma_f32_32x32x16_bf16 v[16:31], v[180:183], v[212:215], v[16:31]
	ds_read_b128 v[212:215], v151 offset:4704
	s_setprio 0
	global_load_dwordx4 v[176:179], v[144:145], off offset:2304
	global_load_dwordx4 v[180:183], v[146:147], off offset:2304
	s_setprio 1
	s_waitcnt lgkmcnt(1)
	v_mfma_f32_32x32x16_bf16 v[96:111], v[168:171], v[208:211], v[96:111]
	v_mfma_f32_32x32x16_bf16 v[112:127], v[172:175], v[208:211], v[112:127]
	s_waitcnt lgkmcnt(0)
	v_mfma_f32_32x32x16_bf16 v[64:79], v[168:171], v[212:215], v[64:79]
	v_mfma_f32_32x32x16_bf16 v[80:95], v[172:175], v[212:215], v[80:95]
	ds_read_b128 v[208:211], v151 offset:9312
	ds_read_b128 v[212:215], v151 offset:13920
	s_waitcnt lgkmcnt(0)
	s_barrier
; template <bool trans>
; DI void gemm_core(const GTile& tl, const GTile& nx, bool has_next  , bool chain  , bool pre, u32x4 (&ra)[4], u32x4 (&rb)[4], char* smem, f32x16 (&acc)[2][4]) {
;     ...
;   const int nk = K / 64;
;   if (!pre) { G_LOAD(0); G_STORE(0); G_LOAD(1); }
;   for (int kt = 0; kt < nk; ++kt) {
;     __syncthreads();
;     G_COMPUTE(kt & 1, kt);
;   }
	s_waitcnt vmcnt(7)
	ds_write_b128 v148, v[160:163]
	s_waitcnt vmcnt(6)
	ds_write_b128 v148, v[164:167] offset:36864
	ds_read_b128 v[160:163], v150
	ds_read_b128 v[164:167], v150 offset:4608
	v_mfma_f32_32x32x16_bf16 v[32:47], v[168:171], v[208:211], v[32:47]
	v_mfma_f32_32x32x16_bf16 v[48:63], v[172:175], v[208:211], v[48:63]
	ds_read_b128 v[208:211], v149
	v_mfma_f32_32x32x16_bf16 v[0:15], v[168:171], v[212:215], v[0:15]
	v_mfma_f32_32x32x16_bf16 v[16:31], v[172:175], v[212:215], v[16:31]
	ds_read_b128 v[212:215], v149 offset:4608
	s_setprio 0
	global_load_dwordx4 v[168:171], v[136:137], off offset:2432
	global_load_dwordx4 v[172:175], v[138:139], off offset:2432
	s_setprio 1
	s_waitcnt lgkmcnt(1)
	v_mfma_f32_32x32x16_bf16 v[96:111], v[160:163], v[208:211], v[96:111]
	v_mfma_f32_32x32x16_bf16 v[112:127], v[164:167], v[208:211], v[112:127]
	s_waitcnt lgkmcnt(0)
	v_mfma_f32_32x32x16_bf16 v[64:79], v[160:163], v[212:215], v[64:79]
	v_mfma_f32_32x32x16_bf16 v[80:95], v[164:167], v[212:215], v[80:95]
	ds_read_b128 v[208:211], v149 offset:9216
	ds_read_b128 v[212:215], v149 offset:13824
	s_waitcnt vmcnt(7)
	ds_write_b128 v148, v[184:187] offset:9216
	s_waitcnt vmcnt(6)
	ds_write_b128 v148, v[188:191] offset:46080
	ds_read_b128 v[184:187], v150 offset:32
	ds_read_b128 v[188:191], v150 offset:4640
	s_waitcnt lgkmcnt(5)
	v_mfma_f32_32x32x16_bf16 v[32:47], v[160:163], v[208:211], v[32:47]
	v_mfma_f32_32x32x16_bf16 v[48:63], v[164:167], v[208:211], v[48:63]
	ds_read_b128 v[208:211], v149 offset:32
	s_waitcnt lgkmcnt(5)
	v_mfma_f32_32x32x16_bf16 v[0:15], v[160:163], v[212:215], v[0:15]
	v_mfma_f32_32x32x16_bf16 v[16:31], v[164:167], v[212:215], v[16:31]
	ds_read_b128 v[212:215], v149 offset:4640
	s_setprio 0
	global_load_dwordx4 v[160:163], v[140:141], off offset:2432
	global_load_dwordx4 v[164:167], v[142:143], off offset:2432
	s_setprio 1
	s_waitcnt lgkmcnt(1)
	v_mfma_f32_32x32x16_bf16 v[96:111], v[184:187], v[208:211], v[96:111]
	v_mfma_f32_32x32x16_bf16 v[112:127], v[188:191], v[208:211], v[112:127]
	s_waitcnt lgkmcnt(0)
	v_mfma_f32_32x32x16_bf16 v[64:79], v[184:187], v[212:215], v[64:79]
	v_mfma_f32_32x32x16_bf16 v[80:95], v[188:191], v[212:215], v[80:95]
	ds_read_b128 v[208:211], v149 offset:9248
	ds_read_b128 v[212:215], v149 offset:13856
	s_waitcnt vmcnt(7)
	ds_write_b128 v148, v[194:197] offset:18432
	s_waitcnt vmcnt(6)
	ds_write_b128 v148, v[198:201] offset:55296
	ds_read_b128 v[194:197], v150 offset:64
	ds_read_b128 v[198:201], v150 offset:4672
	s_waitcnt lgkmcnt(5)
	v_mfma_f32_32x32x16_bf16 v[32:47], v[184:187], v[208:211], v[32:47]
	v_mfma_f32_32x32x16_bf16 v[48:63], v[188:191], v[208:211], v[48:63]
	ds_read_b128 v[208:211], v149 offset:64
	s_waitcnt lgkmcnt(5)
	v_mfma_f32_32x32x16_bf16 v[0:15], v[184:187], v[212:215], v[0:15]
	v_mfma_f32_32x32x16_bf16 v[16:31], v[188:191], v[212:215], v[16:31]
	ds_read_b128 v[212:215], v149 offset:4672
	s_setprio 0
	global_load_dwordx4 v[184:187], v[132:133], off offset:2432
	global_load_dwordx4 v[188:191], v[134:135], off offset:2432
	s_setprio 1
	s_waitcnt lgkmcnt(1)
	v_mfma_f32_32x32x16_bf16 v[96:111], v[194:197], v[208:211], v[96:111]
	v_mfma_f32_32x32x16_bf16 v[112:127], v[198:201], v[208:211], v[112:127]
	s_waitcnt lgkmcnt(0)
	v_mfma_f32_32x32x16_bf16 v[64:79], v[194:197], v[212:215], v[64:79]
	v_mfma_f32_32x32x16_bf16 v[80:95], v[198:201], v[212:215], v[80:95]
	ds_read_b128 v[208:211], v149 offset:9280
	ds_read_b128 v[212:215], v149 offset:13888
	s_waitcnt vmcnt(7)
	ds_write_b128 v148, v[176:179] offset:27648
	s_waitcnt vmcnt(6)
	ds_write_b128 v148, v[180:183] offset:64512
	ds_read_b128 v[176:179], v150 offset:96
	ds_read_b128 v[180:183], v150 offset:4704
	s_waitcnt lgkmcnt(5)
	v_mfma_f32_32x32x16_bf16 v[32:47], v[194:197], v[208:211], v[32:47]
	v_mfma_f32_32x32x16_bf16 v[48:63], v[198:201], v[208:211], v[48:63]
	ds_read_b128 v[208:211], v149 offset:96
	s_waitcnt lgkmcnt(5)
	v_mfma_f32_32x32x16_bf16 v[0:15], v[194:197], v[212:215], v[0:15]
	v_mfma_f32_32x32x16_bf16 v[16:31], v[198:201], v[212:215], v[16:31]
	ds_read_b128 v[212:215], v149 offset:4704
	s_setprio 0
	global_load_dwordx4 v[194:197], v[144:145], off offset:2432
	global_load_dwordx4 v[198:201], v[146:147], off offset:2432
	s_setprio 1
	s_waitcnt lgkmcnt(1)
	v_mfma_f32_32x32x16_bf16 v[96:111], v[176:179], v[208:211], v[96:111]
	v_mfma_f32_32x32x16_bf16 v[112:127], v[180:183], v[208:211], v[112:127]
	s_waitcnt lgkmcnt(0)
	v_mfma_f32_32x32x16_bf16 v[64:79], v[176:179], v[212:215], v[64:79]
	v_mfma_f32_32x32x16_bf16 v[80:95], v[180:183], v[212:215], v[80:95]
	ds_read_b128 v[208:211], v149 offset:9312
	ds_read_b128 v[212:215], v149 offset:13920
	s_waitcnt lgkmcnt(0)
	s_barrier
; template <bool trans>
; DI void gemm_core(const GTile& tl, const GTile& nx, bool has_next  , bool chain  , bool pre, u32x4 (&ra)[4], u32x4 (&rb)[4], char* smem, f32x16 (&acc)[2][4]) {
;     ...
;   const int nk = K / 64;
;   if (!pre) { G_LOAD(0); G_STORE(0); G_LOAD(1); }
;   for (int kt = 0; kt < nk; ++kt) {
;     __syncthreads();
;     G_COMPUTE(kt & 1, kt);
;   }
	s_waitcnt vmcnt(7)
	ds_write_b128 v192, v[168:171]
	s_waitcnt vmcnt(6)
	ds_write_b128 v159, v[172:175]
	ds_read_b128 v[168:171], v152 offset:36864
	ds_read_b128 v[172:175], v152 offset:41472
	v_mfma_f32_32x32x16_bf16 v[32:47], v[176:179], v[208:211], v[32:47]
	v_mfma_f32_32x32x16_bf16 v[48:63], v[180:183], v[208:211], v[48:63]
	ds_read_b128 v[208:211], v151
	v_mfma_f32_32x32x16_bf16 v[0:15], v[176:179], v[212:215], v[0:15]
	v_mfma_f32_32x32x16_bf16 v[16:31], v[180:183], v[212:215], v[16:31]
	ds_read_b128 v[212:215], v151 offset:4608
	s_setprio 0
	global_load_dwordx4 v[176:179], v[136:137], off offset:2560
	global_load_dwordx4 v[180:183], v[138:139], off offset:2560
	s_setprio 1
	s_waitcnt lgkmcnt(1)
	v_mfma_f32_32x32x16_bf16 v[96:111], v[168:171], v[208:211], v[96:111]
	v_mfma_f32_32x32x16_bf16 v[112:127], v[172:175], v[208:211], v[112:127]
	s_waitcnt lgkmcnt(0)
	v_mfma_f32_32x32x16_bf16 v[64:79], v[168:171], v[212:215], v[64:79]
	v_mfma_f32_32x32x16_bf16 v[80:95], v[172:175], v[212:215], v[80:95]
	ds_read_b128 v[208:211], v151 offset:9216
	ds_read_b128 v[212:215], v151 offset:13824
	s_waitcnt vmcnt(7)
	ds_write_b128 v158, v[160:163]
	s_waitcnt vmcnt(6)
	ds_write_b128 v157, v[164:167]
	ds_read_b128 v[160:163], v152 offset:36896
	ds_read_b128 v[164:167], v152 offset:41504
	s_waitcnt lgkmcnt(5)
	v_mfma_f32_32x32x16_bf16 v[32:47], v[168:171], v[208:211], v[32:47]
	v_mfma_f32_32x32x16_bf16 v[48:63], v[172:175], v[208:211], v[48:63]
	ds_read_b128 v[208:211], v151 offset:32
	s_waitcnt lgkmcnt(5)
	v_mfma_f32_32x32x16_bf16 v[0:15], v[168:171], v[212:215], v[0:15]
	v_mfma_f32_32x32x16_bf16 v[16:31], v[172:175], v[212:215], v[16:31]
	ds_read_b128 v[212:215], v151 offset:4640
	s_setprio 0
	global_load_dwordx4 v[168:171], v[140:141], off offset:2560
	global_load_dwordx4 v[172:175], v[142:143], off offset:2560
	s_setprio 1
	s_waitcnt lgkmcnt(1)
	v_mfma_f32_32x32x16_bf16 v[96:111], v[160:163], v[208:211], v[96:111]
	v_mfma_f32_32x32x16_bf16 v[112:127], v[164:167], v[208:211], v[112:127]
	s_waitcnt lgkmcnt(0)
	v_mfma_f32_32x32x16_bf16 v[64:79], v[160:163], v[212:215], v[64:79]
	v_mfma_f32_32x32x16_bf16 v[80:95], v[164:167], v[212:215], v[80:95]
	ds_read_b128 v[208:211], v151 offset:9248
	ds_read_b128 v[212:215], v151 offset:13856
	s_waitcnt vmcnt(7)
	ds_write_b128 v154, v[184:187]
	s_waitcnt vmcnt(6)
	ds_write_b128 v153, v[188:191]
	ds_read_b128 v[184:187], v152 offset:36928
	ds_read_b128 v[188:191], v152 offset:41536
	s_waitcnt lgkmcnt(5)
	v_mfma_f32_32x32x16_bf16 v[32:47], v[160:163], v[208:211], v[32:47]
	v_mfma_f32_32x32x16_bf16 v[48:63], v[164:167], v[208:211], v[48:63]
	ds_read_b128 v[208:211], v151 offset:64
	s_waitcnt lgkmcnt(5)
	v_mfma_f32_32x32x16_bf16 v[0:15], v[160:163], v[212:215], v[0:15]
	v_mfma_f32_32x32x16_bf16 v[16:31], v[164:167], v[212:215], v[16:31]
	ds_read_b128 v[212:215], v151 offset:4672
	s_setprio 0
	global_load_dwordx4 v[160:163], v[132:133], off offset:2560
	global_load_dwordx4 v[164:167], v[134:135], off offset:2560
	s_setprio 1
	s_waitcnt lgkmcnt(1)
	v_mfma_f32_32x32x16_bf16 v[96:111], v[184:187], v[208:211], v[96:111]
	v_mfma_f32_32x32x16_bf16 v[112:127], v[188:191], v[208:211], v[112:127]
	s_waitcnt lgkmcnt(0)
	v_mfma_f32_32x32x16_bf16 v[64:79], v[184:187], v[212:215], v[64:79]
	v_mfma_f32_32x32x16_bf16 v[80:95], v[188:191], v[212:215], v[80:95]
	ds_read_b128 v[208:211], v151 offset:9280
	ds_read_b128 v[212:215], v151 offset:13888
	s_waitcnt vmcnt(7)
	ds_write_b128 v156, v[194:197]
	s_waitcnt vmcnt(6)
	ds_write_b128 v155, v[198:201]
	ds_read_b128 v[194:197], v152 offset:36960
	ds_read_b128 v[198:201], v152 offset:41568
	s_waitcnt lgkmcnt(5)
	v_mfma_f32_32x32x16_bf16 v[32:47], v[184:187], v[208:211], v[32:47]
	v_mfma_f32_32x32x16_bf16 v[48:63], v[188:191], v[208:211], v[48:63]
	ds_read_b128 v[208:211], v151 offset:96
	s_waitcnt lgkmcnt(5)
	v_mfma_f32_32x32x16_bf16 v[0:15], v[184:187], v[212:215], v[0:15]
	v_mfma_f32_32x32x16_bf16 v[16:31], v[188:191], v[212:215], v[16:31]
	ds_read_b128 v[212:215], v151 offset:4704
	s_setprio 0
	global_load_dwordx4 v[184:187], v[144:145], off offset:2560
	global_load_dwordx4 v[188:191], v[146:147], off offset:2560
	s_setprio 1
	s_waitcnt lgkmcnt(1)
	v_mfma_f32_32x32x16_bf16 v[96:111], v[194:197], v[208:211], v[96:111]
	v_mfma_f32_32x32x16_bf16 v[112:127], v[198:201], v[208:211], v[112:127]
	s_waitcnt lgkmcnt(0)
	v_mfma_f32_32x32x16_bf16 v[64:79], v[194:197], v[212:215], v[64:79]
	v_mfma_f32_32x32x16_bf16 v[80:95], v[198:201], v[212:215], v[80:95]
	ds_read_b128 v[208:211], v151 offset:9312
	ds_read_b128 v[212:215], v151 offset:13920
	s_waitcnt lgkmcnt(0)
	s_barrier
; template <bool trans>
; DI void gemm_core(const GTile& tl, const GTile& nx, bool has_next  , bool chain  , bool pre, u32x4 (&ra)[4], u32x4 (&rb)[4], char* smem, f32x16 (&acc)[2][4]) {
;     ...
;   const int nk = K / 64;
;   if (!pre) { G_LOAD(0); G_STORE(0); G_LOAD(1); }
;   for (int kt = 0; kt < nk; ++kt) {
;     __syncthreads();
;     G_COMPUTE(kt & 1, kt);
;   }
	s_waitcnt vmcnt(7)
	ds_write_b128 v148, v[176:179]
	s_waitcnt vmcnt(6)
	ds_write_b128 v148, v[180:183] offset:36864
	ds_read_b128 v[176:179], v150
	ds_read_b128 v[180:183], v150 offset:4608
	v_mfma_f32_32x32x16_bf16 v[32:47], v[194:197], v[208:211], v[32:47]
	v_mfma_f32_32x32x16_bf16 v[48:63], v[198:201], v[208:211], v[48:63]
	ds_read_b128 v[208:211], v149
	v_mfma_f32_32x32x16_bf16 v[0:15], v[194:197], v[212:215], v[0:15]
	v_mfma_f32_32x32x16_bf16 v[16:31], v[198:201], v[212:215], v[16:31]
	ds_read_b128 v[212:215], v149 offset:4608
	s_setprio 0
	global_load_dwordx4 v[194:197], v[136:137], off offset:2688
	global_load_dwordx4 v[198:201], v[138:139], off offset:2688
	s_setprio 1
	s_waitcnt lgkmcnt(1)
	v_mfma_f32_32x32x16_bf16 v[96:111], v[176:179], v[208:211], v[96:111]
	v_mfma_f32_32x32x16_bf16 v[112:127], v[180:183], v[208:211], v[112:127]
	s_waitcnt lgkmcnt(0)
	v_mfma_f32_32x32x16_bf16 v[64:79], v[176:179], v[212:215], v[64:79]
	v_mfma_f32_32x32x16_bf16 v[80:95], v[180:183], v[212:215], v[80:95]
	ds_read_b128 v[208:211], v149 offset:9216
	ds_read_b128 v[212:215], v149 offset:13824
	s_waitcnt vmcnt(7)
	ds_write_b128 v148, v[168:171] offset:9216
	s_waitcnt vmcnt(6)
	ds_write_b128 v148, v[172:175] offset:46080
	ds_read_b128 v[168:171], v150 offset:32
	ds_read_b128 v[172:175], v150 offset:4640
	s_waitcnt lgkmcnt(5)
	v_mfma_f32_32x32x16_bf16 v[32:47], v[176:179], v[208:211], v[32:47]
	v_mfma_f32_32x32x16_bf16 v[48:63], v[180:183], v[208:211], v[48:63]
	ds_read_b128 v[208:211], v149 offset:32
	s_waitcnt lgkmcnt(5)
	v_mfma_f32_32x32x16_bf16 v[0:15], v[176:179], v[212:215], v[0:15]
	v_mfma_f32_32x32x16_bf16 v[16:31], v[180:183], v[212:215], v[16:31]
	ds_read_b128 v[212:215], v149 offset:4640
	s_setprio 0
	global_load_dwordx4 v[176:179], v[140:141], off offset:2688
	global_load_dwordx4 v[180:183], v[142:143], off offset:2688
	s_setprio 1
	s_waitcnt lgkmcnt(1)
	v_mfma_f32_32x32x16_bf16 v[96:111], v[168:171], v[208:211], v[96:111]
	v_mfma_f32_32x32x16_bf16 v[112:127], v[172:175], v[208:211], v[112:127]
	s_waitcnt lgkmcnt(0)
	v_mfma_f32_32x32x16_bf16 v[64:79], v[168:171], v[212:215], v[64:79]
	v_mfma_f32_32x32x16_bf16 v[80:95], v[172:175], v[212:215], v[80:95]
	ds_read_b128 v[208:211], v149 offset:9248
	ds_read_b128 v[212:215], v149 offset:13856
	s_waitcnt vmcnt(7)
	ds_write_b128 v148, v[160:163] offset:18432
	s_waitcnt vmcnt(6)
	ds_write_b128 v148, v[164:167] offset:55296
	ds_read_b128 v[160:163], v150 offset:64
	ds_read_b128 v[164:167], v150 offset:4672
	s_waitcnt lgkmcnt(5)
	v_mfma_f32_32x32x16_bf16 v[32:47], v[168:171], v[208:211], v[32:47]
	v_mfma_f32_32x32x16_bf16 v[48:63], v[172:175], v[208:211], v[48:63]
	ds_read_b128 v[208:211], v149 offset:64
	s_waitcnt lgkmcnt(5)
	v_mfma_f32_32x32x16_bf16 v[0:15], v[168:171], v[212:215], v[0:15]
	v_mfma_f32_32x32x16_bf16 v[16:31], v[172:175], v[212:215], v[16:31]
	ds_read_b128 v[212:215], v149 offset:4672
	s_setprio 0
	global_load_dwordx4 v[168:171], v[132:133], off offset:2688
	global_load_dwordx4 v[172:175], v[134:135], off offset:2688
	s_setprio 1
	s_waitcnt lgkmcnt(1)
	v_mfma_f32_32x32x16_bf16 v[96:111], v[160:163], v[208:211], v[96:111]
	v_mfma_f32_32x32x16_bf16 v[112:127], v[164:167], v[208:211], v[112:127]
	s_waitcnt lgkmcnt(0)
	v_mfma_f32_32x32x16_bf16 v[64:79], v[160:163], v[212:215], v[64:79]
	v_mfma_f32_32x32x16_bf16 v[80:95], v[164:167], v[212:215], v[80:95]
	ds_read_b128 v[208:211], v149 offset:9280
	ds_read_b128 v[212:215], v149 offset:13888
	s_waitcnt vmcnt(7)
	ds_write_b128 v148, v[184:187] offset:27648
	s_waitcnt vmcnt(6)
	ds_write_b128 v148, v[188:191] offset:64512
	ds_read_b128 v[184:187], v150 offset:96
	ds_read_b128 v[188:191], v150 offset:4704
	s_waitcnt lgkmcnt(5)
	v_mfma_f32_32x32x16_bf16 v[32:47], v[160:163], v[208:211], v[32:47]
	v_mfma_f32_32x32x16_bf16 v[48:63], v[164:167], v[208:211], v[48:63]
	ds_read_b128 v[208:211], v149 offset:96
	s_waitcnt lgkmcnt(5)
	v_mfma_f32_32x32x16_bf16 v[0:15], v[160:163], v[212:215], v[0:15]
	v_mfma_f32_32x32x16_bf16 v[16:31], v[164:167], v[212:215], v[16:31]
	ds_read_b128 v[212:215], v149 offset:4704
	s_setprio 0
	global_load_dwordx4 v[160:163], v[144:145], off offset:2688
	global_load_dwordx4 v[164:167], v[146:147], off offset:2688
	s_setprio 1
	s_waitcnt lgkmcnt(1)
	v_mfma_f32_32x32x16_bf16 v[96:111], v[184:187], v[208:211], v[96:111]
	v_mfma_f32_32x32x16_bf16 v[112:127], v[188:191], v[208:211], v[112:127]
	s_waitcnt lgkmcnt(0)
	v_mfma_f32_32x32x16_bf16 v[64:79], v[184:187], v[212:215], v[64:79]
	v_mfma_f32_32x32x16_bf16 v[80:95], v[188:191], v[212:215], v[80:95]
	ds_read_b128 v[208:211], v149 offset:9312
	ds_read_b128 v[212:215], v149 offset:13920
	s_waitcnt lgkmcnt(0)
	s_barrier
; template <bool trans>
; DI void gemm_core(const GTile& tl, const GTile& nx, bool has_next  , bool chain  , bool pre, u32x4 (&ra)[4], u32x4 (&rb)[4], char* smem, f32x16 (&acc)[2][4]) {
;     ...
;   const int nk = K / 64;
;   if (!pre) { G_LOAD(0); G_STORE(0); G_LOAD(1); }
;   for (int kt = 0; kt < nk; ++kt) {
;     __syncthreads();
;     G_COMPUTE(kt & 1, kt);
;   }
	s_waitcnt vmcnt(7)
	ds_write_b128 v192, v[194:197]
	s_waitcnt vmcnt(6)
	ds_write_b128 v159, v[198:201]
	ds_read_b128 v[194:197], v152 offset:36864
	ds_read_b128 v[198:201], v152 offset:41472
	v_mfma_f32_32x32x16_bf16 v[32:47], v[184:187], v[208:211], v[32:47]
	v_mfma_f32_32x32x16_bf16 v[48:63], v[188:191], v[208:211], v[48:63]
	ds_read_b128 v[208:211], v151
	v_mfma_f32_32x32x16_bf16 v[0:15], v[184:187], v[212:215], v[0:15]
	v_mfma_f32_32x32x16_bf16 v[16:31], v[188:191], v[212:215], v[16:31]
	ds_read_b128 v[212:215], v151 offset:4608
	s_setprio 0
	global_load_dwordx4 v[184:187], v[136:137], off offset:2816
	global_load_dwordx4 v[188:191], v[138:139], off offset:2816
	s_setprio 1
	s_waitcnt lgkmcnt(1)
	v_mfma_f32_32x32x16_bf16 v[96:111], v[194:197], v[208:211], v[96:111]
	v_mfma_f32_32x32x16_bf16 v[112:127], v[198:201], v[208:211], v[112:127]
	s_waitcnt lgkmcnt(0)
	v_mfma_f32_32x32x16_bf16 v[64:79], v[194:197], v[212:215], v[64:79]
	v_mfma_f32_32x32x16_bf16 v[80:95], v[198:201], v[212:215], v[80:95]
	ds_read_b128 v[208:211], v151 offset:9216
	ds_read_b128 v[212:215], v151 offset:13824
	s_waitcnt vmcnt(7)
	ds_write_b128 v158, v[176:179]
	s_waitcnt vmcnt(6)
	ds_write_b128 v157, v[180:183]
	ds_read_b128 v[176:179], v152 offset:36896
	ds_read_b128 v[180:183], v152 offset:41504
	s_waitcnt lgkmcnt(5)
	v_mfma_f32_32x32x16_bf16 v[32:47], v[194:197], v[208:211], v[32:47]
	v_mfma_f32_32x32x16_bf16 v[48:63], v[198:201], v[208:211], v[48:63]
	ds_read_b128 v[208:211], v151 offset:32
	s_waitcnt lgkmcnt(5)
	v_mfma_f32_32x32x16_bf16 v[0:15], v[194:197], v[212:215], v[0:15]
	v_mfma_f32_32x32x16_bf16 v[16:31], v[198:201], v[212:215], v[16:31]
	ds_read_b128 v[212:215], v151 offset:4640
	s_setprio 0
	global_load_dwordx4 v[194:197], v[140:141], off offset:2816
	global_load_dwordx4 v[198:201], v[142:143], off offset:2816
	s_setprio 1
	s_waitcnt lgkmcnt(1)
	v_mfma_f32_32x32x16_bf16 v[96:111], v[176:179], v[208:211], v[96:111]
	v_mfma_f32_32x32x16_bf16 v[112:127], v[180:183], v[208:211], v[112:127]
	s_waitcnt lgkmcnt(0)
	v_mfma_f32_32x32x16_bf16 v[64:79], v[176:179], v[212:215], v[64:79]
	v_mfma_f32_32x32x16_bf16 v[80:95], v[180:183], v[212:215], v[80:95]
	ds_read_b128 v[208:211], v151 offset:9248
	ds_read_b128 v[212:215], v151 offset:13856
	s_waitcnt vmcnt(7)
	ds_write_b128 v154, v[168:171]
	s_waitcnt vmcnt(6)
	ds_write_b128 v153, v[172:175]
	ds_read_b128 v[168:171], v152 offset:36928
	ds_read_b128 v[172:175], v152 offset:41536
	s_waitcnt lgkmcnt(5)
	v_mfma_f32_32x32x16_bf16 v[32:47], v[176:179], v[208:211], v[32:47]
	v_mfma_f32_32x32x16_bf16 v[48:63], v[180:183], v[208:211], v[48:63]
	ds_read_b128 v[208:211], v151 offset:64
	s_waitcnt lgkmcnt(5)
	v_mfma_f32_32x32x16_bf16 v[0:15], v[176:179], v[212:215], v[0:15]
	v_mfma_f32_32x32x16_bf16 v[16:31], v[180:183], v[212:215], v[16:31]
	ds_read_b128 v[212:215], v151 offset:4672
	s_setprio 0
	global_load_dwordx4 v[176:179], v[132:133], off offset:2816
	global_load_dwordx4 v[180:183], v[134:135], off offset:2816
	s_setprio 1
	s_waitcnt lgkmcnt(1)
	v_mfma_f32_32x32x16_bf16 v[96:111], v[168:171], v[208:211], v[96:111]
	v_mfma_f32_32x32x16_bf16 v[112:127], v[172:175], v[208:211], v[112:127]
	s_waitcnt lgkmcnt(0)
	v_mfma_f32_32x32x16_bf16 v[64:79], v[168:171], v[212:215], v[64:79]
	v_mfma_f32_32x32x16_bf16 v[80:95], v[172:175], v[212:215], v[80:95]
	ds_read_b128 v[208:211], v151 offset:9280
	ds_read_b128 v[212:215], v151 offset:13888
	s_waitcnt vmcnt(7)
	ds_write_b128 v156, v[160:163]
	s_waitcnt vmcnt(6)
	ds_write_b128 v155, v[164:167]
	ds_read_b128 v[160:163], v152 offset:36960
	ds_read_b128 v[164:167], v152 offset:41568
	s_waitcnt lgkmcnt(5)
	v_mfma_f32_32x32x16_bf16 v[32:47], v[168:171], v[208:211], v[32:47]
	v_mfma_f32_32x32x16_bf16 v[48:63], v[172:175], v[208:211], v[48:63]
	ds_read_b128 v[208:211], v151 offset:96
	s_waitcnt lgkmcnt(5)
	v_mfma_f32_32x32x16_bf16 v[0:15], v[168:171], v[212:215], v[0:15]
	v_mfma_f32_32x32x16_bf16 v[16:31], v[172:175], v[212:215], v[16:31]
	ds_read_b128 v[212:215], v151 offset:4704
	s_setprio 0
	global_load_dwordx4 v[168:171], v[144:145], off offset:2816
	global_load_dwordx4 v[172:175], v[146:147], off offset:2816
	s_setprio 1
	s_waitcnt lgkmcnt(1)
	v_mfma_f32_32x32x16_bf16 v[96:111], v[160:163], v[208:211], v[96:111]
	v_mfma_f32_32x32x16_bf16 v[112:127], v[164:167], v[208:211], v[112:127]
	s_waitcnt lgkmcnt(0)
	v_mfma_f32_32x32x16_bf16 v[64:79], v[160:163], v[212:215], v[64:79]
	v_mfma_f32_32x32x16_bf16 v[80:95], v[164:167], v[212:215], v[80:95]
	ds_read_b128 v[208:211], v151 offset:9312
	ds_read_b128 v[212:215], v151 offset:13920
	s_waitcnt lgkmcnt(0)
	s_barrier
; template <bool trans>
; DI void gemm_core(const GTile& tl, const GTile& nx, bool has_next  , bool chain  , bool pre, u32x4 (&ra)[4], u32x4 (&rb)[4], char* smem, f32x16 (&acc)[2][4]) {
;     ...
;   const int nk = K / 64;
;   if (!pre) { G_LOAD(0); G_STORE(0); G_LOAD(1); }
;   for (int kt = 0; kt < nk; ++kt) {
;     __syncthreads();
;     G_COMPUTE(kt & 1, kt);
;   }
	s_waitcnt vmcnt(7)
	ds_write_b128 v148, v[184:187]
	s_waitcnt vmcnt(6)
	ds_write_b128 v148, v[188:191] offset:36864
	ds_read_b128 v[184:187], v150
	ds_read_b128 v[188:191], v150 offset:4608
	v_mfma_f32_32x32x16_bf16 v[32:47], v[160:163], v[208:211], v[32:47]
	v_mfma_f32_32x32x16_bf16 v[48:63], v[164:167], v[208:211], v[48:63]
	ds_read_b128 v[208:211], v149
	v_mfma_f32_32x32x16_bf16 v[0:15], v[160:163], v[212:215], v[0:15]
	v_mfma_f32_32x32x16_bf16 v[16:31], v[164:167], v[212:215], v[16:31]
	ds_read_b128 v[212:215], v149 offset:4608
	s_setprio 0
	global_load_dwordx4 v[160:163], v[136:137], off offset:2944
	global_load_dwordx4 v[164:167], v[138:139], off offset:2944
	s_setprio 1
	s_waitcnt lgkmcnt(1)
	v_mfma_f32_32x32x16_bf16 v[96:111], v[184:187], v[208:211], v[96:111]
	v_mfma_f32_32x32x16_bf16 v[112:127], v[188:191], v[208:211], v[112:127]
	s_waitcnt lgkmcnt(0)
	v_mfma_f32_32x32x16_bf16 v[64:79], v[184:187], v[212:215], v[64:79]
	v_mfma_f32_32x32x16_bf16 v[80:95], v[188:191], v[212:215], v[80:95]
	ds_read_b128 v[208:211], v149 offset:9216
	ds_read_b128 v[212:215], v149 offset:13824
	s_waitcnt vmcnt(7)
	ds_write_b128 v148, v[194:197] offset:9216
	s_waitcnt vmcnt(6)
	ds_write_b128 v148, v[198:201] offset:46080
	ds_read_b128 v[194:197], v150 offset:32
	ds_read_b128 v[198:201], v150 offset:4640
	s_waitcnt lgkmcnt(5)
	v_mfma_f32_32x32x16_bf16 v[32:47], v[184:187], v[208:211], v[32:47]
	v_mfma_f32_32x32x16_bf16 v[48:63], v[188:191], v[208:211], v[48:63]
	ds_read_b128 v[208:211], v149 offset:32
	s_waitcnt lgkmcnt(5)
	v_mfma_f32_32x32x16_bf16 v[0:15], v[184:187], v[212:215], v[0:15]
	v_mfma_f32_32x32x16_bf16 v[16:31], v[188:191], v[212:215], v[16:31]
	ds_read_b128 v[212:215], v149 offset:4640
	s_setprio 0
	global_load_dwordx4 v[184:187], v[140:141], off offset:2944
	global_load_dwordx4 v[188:191], v[142:143], off offset:2944
	s_setprio 1
	s_waitcnt lgkmcnt(1)
	v_mfma_f32_32x32x16_bf16 v[96:111], v[194:197], v[208:211], v[96:111]
	v_mfma_f32_32x32x16_bf16 v[112:127], v[198:201], v[208:211], v[112:127]
	s_waitcnt lgkmcnt(0)
	v_mfma_f32_32x32x16_bf16 v[64:79], v[194:197], v[212:215], v[64:79]
	v_mfma_f32_32x32x16_bf16 v[80:95], v[198:201], v[212:215], v[80:95]
	ds_read_b128 v[208:211], v149 offset:9248
	ds_read_b128 v[212:215], v149 offset:13856
	s_waitcnt vmcnt(7)
	ds_write_b128 v148, v[176:179] offset:18432
	s_waitcnt vmcnt(6)
	ds_write_b128 v148, v[180:183] offset:55296
	ds_read_b128 v[176:179], v150 offset:64
	ds_read_b128 v[180:183], v150 offset:4672
	s_waitcnt lgkmcnt(5)
	v_mfma_f32_32x32x16_bf16 v[32:47], v[194:197], v[208:211], v[32:47]
	v_mfma_f32_32x32x16_bf16 v[48:63], v[198:201], v[208:211], v[48:63]
	ds_read_b128 v[208:211], v149 offset:64
	s_waitcnt lgkmcnt(5)
	v_mfma_f32_32x32x16_bf16 v[0:15], v[194:197], v[212:215], v[0:15]
	v_mfma_f32_32x32x16_bf16 v[16:31], v[198:201], v[212:215], v[16:31]
	ds_read_b128 v[212:215], v149 offset:4672
	s_setprio 0
	global_load_dwordx4 v[194:197], v[132:133], off offset:2944
	global_load_dwordx4 v[198:201], v[134:135], off offset:2944
	s_setprio 1
	s_waitcnt lgkmcnt(1)
	v_mfma_f32_32x32x16_bf16 v[96:111], v[176:179], v[208:211], v[96:111]
	v_mfma_f32_32x32x16_bf16 v[112:127], v[180:183], v[208:211], v[112:127]
	s_waitcnt lgkmcnt(0)
	v_mfma_f32_32x32x16_bf16 v[64:79], v[176:179], v[212:215], v[64:79]
	v_mfma_f32_32x32x16_bf16 v[80:95], v[180:183], v[212:215], v[80:95]
	ds_read_b128 v[208:211], v149 offset:9280
	ds_read_b128 v[212:215], v149 offset:13888
	s_waitcnt vmcnt(7)
	ds_write_b128 v148, v[168:171] offset:27648
	s_waitcnt vmcnt(6)
	ds_write_b128 v148, v[172:175] offset:64512
	ds_read_b128 v[168:171], v150 offset:96
	ds_read_b128 v[172:175], v150 offset:4704
	s_waitcnt lgkmcnt(5)
	v_mfma_f32_32x32x16_bf16 v[32:47], v[176:179], v[208:211], v[32:47]
	v_mfma_f32_32x32x16_bf16 v[48:63], v[180:183], v[208:211], v[48:63]
	ds_read_b128 v[208:211], v149 offset:96
	s_waitcnt lgkmcnt(5)
	v_mfma_f32_32x32x16_bf16 v[0:15], v[176:179], v[212:215], v[0:15]
	v_mfma_f32_32x32x16_bf16 v[16:31], v[180:183], v[212:215], v[16:31]
	ds_read_b128 v[212:215], v149 offset:4704
	s_setprio 0
	global_load_dwordx4 v[176:179], v[144:145], off offset:2944
	global_load_dwordx4 v[180:183], v[146:147], off offset:2944
	s_setprio 1
	s_waitcnt lgkmcnt(1)
	v_mfma_f32_32x32x16_bf16 v[96:111], v[168:171], v[208:211], v[96:111]
	v_mfma_f32_32x32x16_bf16 v[112:127], v[172:175], v[208:211], v[112:127]
	s_waitcnt lgkmcnt(0)
	v_mfma_f32_32x32x16_bf16 v[64:79], v[168:171], v[212:215], v[64:79]
	v_mfma_f32_32x32x16_bf16 v[80:95], v[172:175], v[212:215], v[80:95]
	ds_read_b128 v[208:211], v149 offset:9312
	ds_read_b128 v[212:215], v149 offset:13920
	s_waitcnt lgkmcnt(0)
	s_barrier
; template <bool trans>
; DI void gemm_core(const GTile& tl, const GTile& nx, bool has_next  , bool chain  , bool pre, u32x4 (&ra)[4], u32x4 (&rb)[4], char* smem, f32x16 (&acc)[2][4]) {
;     ...
;   const int nk = K / 64;
;   if (!pre) { G_LOAD(0); G_STORE(0); G_LOAD(1); }
;   for (int kt = 0; kt < nk; ++kt) {
;     __syncthreads();
;     G_COMPUTE(kt & 1, kt);
;   }
	s_waitcnt vmcnt(7)
	ds_write_b128 v192, v[160:163]
	s_waitcnt vmcnt(6)
	ds_write_b128 v159, v[164:167]
	ds_read_b128 v[160:163], v152 offset:36864
	ds_read_b128 v[164:167], v152 offset:41472
	v_mfma_f32_32x32x16_bf16 v[32:47], v[168:171], v[208:211], v[32:47]
	v_mfma_f32_32x32x16_bf16 v[48:63], v[172:175], v[208:211], v[48:63]
	ds_read_b128 v[208:211], v151
	v_mfma_f32_32x32x16_bf16 v[0:15], v[168:171], v[212:215], v[0:15]
	v_mfma_f32_32x32x16_bf16 v[16:31], v[172:175], v[212:215], v[16:31]
	ds_read_b128 v[212:215], v151 offset:4608
	s_setprio 0
	global_load_dwordx4 v[168:171], v[136:137], off offset:3072
	global_load_dwordx4 v[172:175], v[138:139], off offset:3072
	s_setprio 1
	s_waitcnt lgkmcnt(1)
	v_mfma_f32_32x32x16_bf16 v[96:111], v[160:163], v[208:211], v[96:111]
	v_mfma_f32_32x32x16_bf16 v[112:127], v[164:167], v[208:211], v[112:127]
	s_waitcnt lgkmcnt(0)
	v_mfma_f32_32x32x16_bf16 v[64:79], v[160:163], v[212:215], v[64:79]
	v_mfma_f32_32x32x16_bf16 v[80:95], v[164:167], v[212:215], v[80:95]
	ds_read_b128 v[208:211], v151 offset:9216
	ds_read_b128 v[212:215], v151 offset:13824
	s_waitcnt vmcnt(7)
	ds_write_b128 v158, v[184:187]
	s_waitcnt vmcnt(6)
	ds_write_b128 v157, v[188:191]
	ds_read_b128 v[184:187], v152 offset:36896
	ds_read_b128 v[188:191], v152 offset:41504
	s_waitcnt lgkmcnt(5)
	v_mfma_f32_32x32x16_bf16 v[32:47], v[160:163], v[208:211], v[32:47]
	v_mfma_f32_32x32x16_bf16 v[48:63], v[164:167], v[208:211], v[48:63]
	ds_read_b128 v[208:211], v151 offset:32
	s_waitcnt lgkmcnt(5)
	v_mfma_f32_32x32x16_bf16 v[0:15], v[160:163], v[212:215], v[0:15]
	v_mfma_f32_32x32x16_bf16 v[16:31], v[164:167], v[212:215], v[16:31]
	ds_read_b128 v[212:215], v151 offset:4640
	s_setprio 0
	global_load_dwordx4 v[160:163], v[140:141], off offset:3072
	global_load_dwordx4 v[164:167], v[142:143], off offset:3072
	s_setprio 1
	s_waitcnt lgkmcnt(1)
	v_mfma_f32_32x32x16_bf16 v[96:111], v[184:187], v[208:211], v[96:111]
	v_mfma_f32_32x32x16_bf16 v[112:127], v[188:191], v[208:211], v[112:127]
	s_waitcnt lgkmcnt(0)
	v_mfma_f32_32x32x16_bf16 v[64:79], v[184:187], v[212:215], v[64:79]
	v_mfma_f32_32x32x16_bf16 v[80:95], v[188:191], v[212:215], v[80:95]
	ds_read_b128 v[208:211], v151 offset:9248
	ds_read_b128 v[212:215], v151 offset:13856
	s_waitcnt vmcnt(7)
	ds_write_b128 v154, v[194:197]
	s_waitcnt vmcnt(6)
	ds_write_b128 v153, v[198:201]
	ds_read_b128 v[194:197], v152 offset:36928
	ds_read_b128 v[198:201], v152 offset:41536
	s_waitcnt lgkmcnt(5)
	v_mfma_f32_32x32x16_bf16 v[32:47], v[184:187], v[208:211], v[32:47]
	v_mfma_f32_32x32x16_bf16 v[48:63], v[188:191], v[208:211], v[48:63]
	ds_read_b128 v[208:211], v151 offset:64
	s_waitcnt lgkmcnt(5)
	v_mfma_f32_32x32x16_bf16 v[0:15], v[184:187], v[212:215], v[0:15]
	v_mfma_f32_32x32x16_bf16 v[16:31], v[188:191], v[212:215], v[16:31]
	ds_read_b128 v[212:215], v151 offset:4672
	s_setprio 0
	global_load_dwordx4 v[184:187], v[132:133], off offset:3072
	global_load_dwordx4 v[188:191], v[134:135], off offset:3072
	s_setprio 1
	s_waitcnt lgkmcnt(1)
	v_mfma_f32_32x32x16_bf16 v[96:111], v[194:197], v[208:211], v[96:111]
	v_mfma_f32_32x32x16_bf16 v[112:127], v[198:201], v[208:211], v[112:127]
	s_waitcnt lgkmcnt(0)
	v_mfma_f32_32x32x16_bf16 v[64:79], v[194:197], v[212:215], v[64:79]
	v_mfma_f32_32x32x16_bf16 v[80:95], v[198:201], v[212:215], v[80:95]
	ds_read_b128 v[208:211], v151 offset:9280
	ds_read_b128 v[212:215], v151 offset:13888
	s_waitcnt vmcnt(7)
	ds_write_b128 v156, v[176:179]
	s_waitcnt vmcnt(6)
	ds_write_b128 v155, v[180:183]
	ds_read_b128 v[176:179], v152 offset:36960
	ds_read_b128 v[180:183], v152 offset:41568
	s_waitcnt lgkmcnt(5)
	v_mfma_f32_32x32x16_bf16 v[32:47], v[194:197], v[208:211], v[32:47]
	v_mfma_f32_32x32x16_bf16 v[48:63], v[198:201], v[208:211], v[48:63]
	ds_read_b128 v[208:211], v151 offset:96
	s_waitcnt lgkmcnt(5)
	v_mfma_f32_32x32x16_bf16 v[0:15], v[194:197], v[212:215], v[0:15]
	v_mfma_f32_32x32x16_bf16 v[16:31], v[198:201], v[212:215], v[16:31]
	ds_read_b128 v[212:215], v151 offset:4704
	s_setprio 0
	global_load_dwordx4 v[194:197], v[144:145], off offset:3072
	global_load_dwordx4 v[198:201], v[146:147], off offset:3072
	s_setprio 1
	s_waitcnt lgkmcnt(1)
	v_mfma_f32_32x32x16_bf16 v[96:111], v[176:179], v[208:211], v[96:111]
	v_mfma_f32_32x32x16_bf16 v[112:127], v[180:183], v[208:211], v[112:127]
	s_waitcnt lgkmcnt(0)
	v_mfma_f32_32x32x16_bf16 v[64:79], v[176:179], v[212:215], v[64:79]
	v_mfma_f32_32x32x16_bf16 v[80:95], v[180:183], v[212:215], v[80:95]
	ds_read_b128 v[208:211], v151 offset:9312
	ds_read_b128 v[212:215], v151 offset:13920
	s_waitcnt lgkmcnt(0)
	s_barrier
; template <bool trans>
; DI void gemm_core(const GTile& tl, const GTile& nx, bool has_next  , bool chain  , bool pre, u32x4 (&ra)[4], u32x4 (&rb)[4], char* smem, f32x16 (&acc)[2][4]) {
;     ...
;   const int nk = K / 64;
;   if (!pre) { G_LOAD(0); G_STORE(0); G_LOAD(1); }
;   for (int kt = 0; kt < nk; ++kt) {
;     __syncthreads();
;     G_COMPUTE(kt & 1, kt);
;   }
	s_waitcnt vmcnt(7)
	ds_write_b128 v148, v[168:171]
	s_waitcnt vmcnt(6)
	ds_write_b128 v148, v[172:175] offset:36864
	ds_read_b128 v[168:171], v150
	ds_read_b128 v[172:175], v150 offset:4608
	v_mfma_f32_32x32x16_bf16 v[32:47], v[176:179], v[208:211], v[32:47]
	v_mfma_f32_32x32x16_bf16 v[48:63], v[180:183], v[208:211], v[48:63]
	ds_read_b128 v[208:211], v149
	v_mfma_f32_32x32x16_bf16 v[0:15], v[176:179], v[212:215], v[0:15]
	v_mfma_f32_32x32x16_bf16 v[16:31], v[180:183], v[212:215], v[16:31]
	ds_read_b128 v[212:215], v149 offset:4608
	s_setprio 0
	global_load_dwordx4 v[176:179], v[136:137], off offset:3200
	global_load_dwordx4 v[180:183], v[138:139], off offset:3200
	s_setprio 1
	s_waitcnt lgkmcnt(1)
	v_mfma_f32_32x32x16_bf16 v[96:111], v[168:171], v[208:211], v[96:111]
	v_mfma_f32_32x32x16_bf16 v[112:127], v[172:175], v[208:211], v[112:127]
	s_waitcnt lgkmcnt(0)
	v_mfma_f32_32x32x16_bf16 v[64:79], v[168:171], v[212:215], v[64:79]
	v_mfma_f32_32x32x16_bf16 v[80:95], v[172:175], v[212:215], v[80:95]
	ds_read_b128 v[208:211], v149 offset:9216
	ds_read_b128 v[212:215], v149 offset:13824
	s_waitcnt vmcnt(7)
	ds_write_b128 v148, v[160:163] offset:9216
	s_waitcnt vmcnt(6)
	ds_write_b128 v148, v[164:167] offset:46080
	ds_read_b128 v[160:163], v150 offset:32
	ds_read_b128 v[164:167], v150 offset:4640
	s_waitcnt lgkmcnt(5)
	v_mfma_f32_32x32x16_bf16 v[32:47], v[168:171], v[208:211], v[32:47]
	v_mfma_f32_32x32x16_bf16 v[48:63], v[172:175], v[208:211], v[48:63]
	ds_read_b128 v[208:211], v149 offset:32
	s_waitcnt lgkmcnt(5)
	v_mfma_f32_32x32x16_bf16 v[0:15], v[168:171], v[212:215], v[0:15]
	v_mfma_f32_32x32x16_bf16 v[16:31], v[172:175], v[212:215], v[16:31]
	ds_read_b128 v[212:215], v149 offset:4640
	s_setprio 0
	global_load_dwordx4 v[168:171], v[140:141], off offset:3200
	global_load_dwordx4 v[172:175], v[142:143], off offset:3200
	s_setprio 1
	s_waitcnt lgkmcnt(1)
	v_mfma_f32_32x32x16_bf16 v[96:111], v[160:163], v[208:211], v[96:111]
	v_mfma_f32_32x32x16_bf16 v[112:127], v[164:167], v[208:211], v[112:127]
	s_waitcnt lgkmcnt(0)
	v_mfma_f32_32x32x16_bf16 v[64:79], v[160:163], v[212:215], v[64:79]
	v_mfma_f32_32x32x16_bf16 v[80:95], v[164:167], v[212:215], v[80:95]
	ds_read_b128 v[208:211], v149 offset:9248
	ds_read_b128 v[212:215], v149 offset:13856
	s_waitcnt vmcnt(7)
	ds_write_b128 v148, v[184:187] offset:18432
	s_waitcnt vmcnt(6)
	ds_write_b128 v148, v[188:191] offset:55296
	ds_read_b128 v[184:187], v150 offset:64
	ds_read_b128 v[188:191], v150 offset:4672
	s_waitcnt lgkmcnt(5)
	v_mfma_f32_32x32x16_bf16 v[32:47], v[160:163], v[208:211], v[32:47]
	v_mfma_f32_32x32x16_bf16 v[48:63], v[164:167], v[208:211], v[48:63]
	ds_read_b128 v[208:211], v149 offset:64
	s_waitcnt lgkmcnt(5)
	v_mfma_f32_32x32x16_bf16 v[0:15], v[160:163], v[212:215], v[0:15]
	v_mfma_f32_32x32x16_bf16 v[16:31], v[164:167], v[212:215], v[16:31]
	ds_read_b128 v[212:215], v149 offset:4672
	s_setprio 0
	global_load_dwordx4 v[160:163], v[132:133], off offset:3200
	global_load_dwordx4 v[164:167], v[134:135], off offset:3200
	s_setprio 1
	s_waitcnt lgkmcnt(1)
	v_mfma_f32_32x32x16_bf16 v[96:111], v[184:187], v[208:211], v[96:111]
	v_mfma_f32_32x32x16_bf16 v[112:127], v[188:191], v[208:211], v[112:127]
	s_waitcnt lgkmcnt(0)
	v_mfma_f32_32x32x16_bf16 v[64:79], v[184:187], v[212:215], v[64:79]
	v_mfma_f32_32x32x16_bf16 v[80:95], v[188:191], v[212:215], v[80:95]
	ds_read_b128 v[208:211], v149 offset:9280
	ds_read_b128 v[212:215], v149 offset:13888
	s_waitcnt vmcnt(7)
	ds_write_b128 v148, v[194:197] offset:27648
	s_waitcnt vmcnt(6)
	ds_write_b128 v148, v[198:201] offset:64512
	ds_read_b128 v[194:197], v150 offset:96
	ds_read_b128 v[198:201], v150 offset:4704
	s_waitcnt lgkmcnt(5)
	v_mfma_f32_32x32x16_bf16 v[32:47], v[184:187], v[208:211], v[32:47]
	v_mfma_f32_32x32x16_bf16 v[48:63], v[188:191], v[208:211], v[48:63]
	ds_read_b128 v[208:211], v149 offset:96
	s_waitcnt lgkmcnt(5)
	v_mfma_f32_32x32x16_bf16 v[0:15], v[184:187], v[212:215], v[0:15]
	v_mfma_f32_32x32x16_bf16 v[16:31], v[188:191], v[212:215], v[16:31]
	ds_read_b128 v[212:215], v149 offset:4704
	s_setprio 0
	global_load_dwordx4 v[184:187], v[144:145], off offset:3200
	global_load_dwordx4 v[188:191], v[146:147], off offset:3200
	s_setprio 1
	s_waitcnt lgkmcnt(1)
	v_mfma_f32_32x32x16_bf16 v[96:111], v[194:197], v[208:211], v[96:111]
	v_mfma_f32_32x32x16_bf16 v[112:127], v[198:201], v[208:211], v[112:127]
	s_waitcnt lgkmcnt(0)
	v_mfma_f32_32x32x16_bf16 v[64:79], v[194:197], v[212:215], v[64:79]
	v_mfma_f32_32x32x16_bf16 v[80:95], v[198:201], v[212:215], v[80:95]
	ds_read_b128 v[208:211], v149 offset:9312
	ds_read_b128 v[212:215], v149 offset:13920
	s_waitcnt lgkmcnt(0)
	s_barrier
; template <bool trans>
; DI void gemm_core(const GTile& tl, const GTile& nx, bool has_next  , bool chain  , bool pre, u32x4 (&ra)[4], u32x4 (&rb)[4], char* smem, f32x16 (&acc)[2][4]) {
;     ...
;   const int nk = K / 64;
;   if (!pre) { G_LOAD(0); G_STORE(0); G_LOAD(1); }
;   for (int kt = 0; kt < nk; ++kt) {
;     __syncthreads();
;     G_COMPUTE(kt & 1, kt);
;   }
	s_waitcnt vmcnt(7)
	ds_write_b128 v192, v[176:179]
	s_waitcnt vmcnt(6)
	ds_write_b128 v159, v[180:183]
	ds_read_b128 v[176:179], v152 offset:36864
	ds_read_b128 v[180:183], v152 offset:41472
	v_mfma_f32_32x32x16_bf16 v[32:47], v[194:197], v[208:211], v[32:47]
	v_mfma_f32_32x32x16_bf16 v[48:63], v[198:201], v[208:211], v[48:63]
	ds_read_b128 v[208:211], v151
	v_mfma_f32_32x32x16_bf16 v[0:15], v[194:197], v[212:215], v[0:15]
	v_mfma_f32_32x32x16_bf16 v[16:31], v[198:201], v[212:215], v[16:31]
	ds_read_b128 v[212:215], v151 offset:4608
	s_setprio 0
	global_load_dwordx4 v[194:197], v[136:137], off offset:3328
	global_load_dwordx4 v[198:201], v[138:139], off offset:3328
	s_setprio 1
	s_waitcnt lgkmcnt(1)
	v_mfma_f32_32x32x16_bf16 v[96:111], v[176:179], v[208:211], v[96:111]
	v_mfma_f32_32x32x16_bf16 v[112:127], v[180:183], v[208:211], v[112:127]
	s_waitcnt lgkmcnt(0)
	v_mfma_f32_32x32x16_bf16 v[64:79], v[176:179], v[212:215], v[64:79]
	v_mfma_f32_32x32x16_bf16 v[80:95], v[180:183], v[212:215], v[80:95]
	ds_read_b128 v[208:211], v151 offset:9216
	ds_read_b128 v[212:215], v151 offset:13824
	s_waitcnt vmcnt(7)
	ds_write_b128 v158, v[168:171]
	s_waitcnt vmcnt(6)
	ds_write_b128 v157, v[172:175]
	ds_read_b128 v[168:171], v152 offset:36896
	ds_read_b128 v[172:175], v152 offset:41504
	s_waitcnt lgkmcnt(5)
	v_mfma_f32_32x32x16_bf16 v[32:47], v[176:179], v[208:211], v[32:47]
	v_mfma_f32_32x32x16_bf16 v[48:63], v[180:183], v[208:211], v[48:63]
	ds_read_b128 v[208:211], v151 offset:32
	s_waitcnt lgkmcnt(5)
	v_mfma_f32_32x32x16_bf16 v[0:15], v[176:179], v[212:215], v[0:15]
	v_mfma_f32_32x32x16_bf16 v[16:31], v[180:183], v[212:215], v[16:31]
	ds_read_b128 v[212:215], v151 offset:4640
	s_setprio 0
	global_load_dwordx4 v[176:179], v[140:141], off offset:3328
	global_load_dwordx4 v[180:183], v[142:143], off offset:3328
	s_setprio 1
	s_waitcnt lgkmcnt(1)
	v_mfma_f32_32x32x16_bf16 v[96:111], v[168:171], v[208:211], v[96:111]
	v_mfma_f32_32x32x16_bf16 v[112:127], v[172:175], v[208:211], v[112:127]
	s_waitcnt lgkmcnt(0)
	v_mfma_f32_32x32x16_bf16 v[64:79], v[168:171], v[212:215], v[64:79]
	v_mfma_f32_32x32x16_bf16 v[80:95], v[172:175], v[212:215], v[80:95]
	ds_read_b128 v[208:211], v151 offset:9248
	ds_read_b128 v[212:215], v151 offset:13856
	s_waitcnt vmcnt(7)
	ds_write_b128 v154, v[160:163]
	s_waitcnt vmcnt(6)
	ds_write_b128 v153, v[164:167]
	ds_read_b128 v[160:163], v152 offset:36928
	ds_read_b128 v[164:167], v152 offset:41536
	s_waitcnt lgkmcnt(5)
	v_mfma_f32_32x32x16_bf16 v[32:47], v[168:171], v[208:211], v[32:47]
	v_mfma_f32_32x32x16_bf16 v[48:63], v[172:175], v[208:211], v[48:63]
	ds_read_b128 v[208:211], v151 offset:64
	s_waitcnt lgkmcnt(5)
	v_mfma_f32_32x32x16_bf16 v[0:15], v[168:171], v[212:215], v[0:15]
	v_mfma_f32_32x32x16_bf16 v[16:31], v[172:175], v[212:215], v[16:31]
	ds_read_b128 v[212:215], v151 offset:4672
	s_setprio 0
	global_load_dwordx4 v[168:171], v[132:133], off offset:3328
	global_load_dwordx4 v[172:175], v[134:135], off offset:3328
	s_setprio 1
	s_waitcnt lgkmcnt(1)
	v_mfma_f32_32x32x16_bf16 v[96:111], v[160:163], v[208:211], v[96:111]
	v_mfma_f32_32x32x16_bf16 v[112:127], v[164:167], v[208:211], v[112:127]
	s_waitcnt lgkmcnt(0)
	v_mfma_f32_32x32x16_bf16 v[64:79], v[160:163], v[212:215], v[64:79]
	v_mfma_f32_32x32x16_bf16 v[80:95], v[164:167], v[212:215], v[80:95]
	ds_read_b128 v[208:211], v151 offset:9280
	ds_read_b128 v[212:215], v151 offset:13888
	s_waitcnt vmcnt(7)
	ds_write_b128 v156, v[184:187]
	s_waitcnt vmcnt(6)
	ds_write_b128 v155, v[188:191]
	ds_read_b128 v[184:187], v152 offset:36960
	ds_read_b128 v[188:191], v152 offset:41568
	s_waitcnt lgkmcnt(5)
	v_mfma_f32_32x32x16_bf16 v[32:47], v[160:163], v[208:211], v[32:47]
	v_mfma_f32_32x32x16_bf16 v[48:63], v[164:167], v[208:211], v[48:63]
	ds_read_b128 v[208:211], v151 offset:96
	s_waitcnt lgkmcnt(5)
	v_mfma_f32_32x32x16_bf16 v[0:15], v[160:163], v[212:215], v[0:15]
	v_mfma_f32_32x32x16_bf16 v[16:31], v[164:167], v[212:215], v[16:31]
	ds_read_b128 v[212:215], v151 offset:4704
	s_setprio 0
	global_load_dwordx4 v[160:163], v[144:145], off offset:3328
	global_load_dwordx4 v[164:167], v[146:147], off offset:3328
	s_setprio 1
	s_waitcnt lgkmcnt(1)
	v_mfma_f32_32x32x16_bf16 v[96:111], v[184:187], v[208:211], v[96:111]
	v_mfma_f32_32x32x16_bf16 v[112:127], v[188:191], v[208:211], v[112:127]
	s_waitcnt lgkmcnt(0)
	v_mfma_f32_32x32x16_bf16 v[64:79], v[184:187], v[212:215], v[64:79]
	v_mfma_f32_32x32x16_bf16 v[80:95], v[188:191], v[212:215], v[80:95]
	ds_read_b128 v[208:211], v151 offset:9312
	ds_read_b128 v[212:215], v151 offset:13920
	s_waitcnt lgkmcnt(0)
	s_barrier
; template <bool trans>
; DI void gemm_core(const GTile& tl, const GTile& nx, bool has_next  , bool chain  , bool pre, u32x4 (&ra)[4], u32x4 (&rb)[4], char* smem, f32x16 (&acc)[2][4]) {
;     ...
;   const int nk = K / 64;
;   if (!pre) { G_LOAD(0); G_STORE(0); G_LOAD(1); }
;   for (int kt = 0; kt < nk; ++kt) {
;     __syncthreads();
;     G_COMPUTE(kt & 1, kt);
;   }
	s_waitcnt vmcnt(7)
	ds_write_b128 v148, v[194:197]
	s_waitcnt vmcnt(6)
	ds_write_b128 v148, v[198:201] offset:36864
	ds_read_b128 v[194:197], v150
	ds_read_b128 v[198:201], v150 offset:4608
	v_mfma_f32_32x32x16_bf16 v[32:47], v[184:187], v[208:211], v[32:47]
	v_mfma_f32_32x32x16_bf16 v[48:63], v[188:191], v[208:211], v[48:63]
	ds_read_b128 v[208:211], v149
	v_mfma_f32_32x32x16_bf16 v[0:15], v[184:187], v[212:215], v[0:15]
	v_mfma_f32_32x32x16_bf16 v[16:31], v[188:191], v[212:215], v[16:31]
	ds_read_b128 v[212:215], v149 offset:4608
	s_setprio 0
	global_load_dwordx4 v[184:187], v[136:137], off offset:3456
	global_load_dwordx4 v[188:191], v[138:139], off offset:3456
	s_setprio 1
	s_waitcnt lgkmcnt(1)
	v_mfma_f32_32x32x16_bf16 v[96:111], v[194:197], v[208:211], v[96:111]
	v_mfma_f32_32x32x16_bf16 v[112:127], v[198:201], v[208:211], v[112:127]
	s_waitcnt lgkmcnt(0)
	v_mfma_f32_32x32x16_bf16 v[64:79], v[194:197], v[212:215], v[64:79]
	v_mfma_f32_32x32x16_bf16 v[80:95], v[198:201], v[212:215], v[80:95]
	ds_read_b128 v[208:211], v149 offset:9216
	ds_read_b128 v[212:215], v149 offset:13824
	s_waitcnt vmcnt(7)
	ds_write_b128 v148, v[176:179] offset:9216
	s_waitcnt vmcnt(6)
	ds_write_b128 v148, v[180:183] offset:46080
	ds_read_b128 v[176:179], v150 offset:32
	ds_read_b128 v[180:183], v150 offset:4640
	s_waitcnt lgkmcnt(5)
	v_mfma_f32_32x32x16_bf16 v[32:47], v[194:197], v[208:211], v[32:47]
	v_mfma_f32_32x32x16_bf16 v[48:63], v[198:201], v[208:211], v[48:63]
	ds_read_b128 v[208:211], v149 offset:32
	s_waitcnt lgkmcnt(5)
	v_mfma_f32_32x32x16_bf16 v[0:15], v[194:197], v[212:215], v[0:15]
	v_mfma_f32_32x32x16_bf16 v[16:31], v[198:201], v[212:215], v[16:31]
	ds_read_b128 v[212:215], v149 offset:4640
	s_setprio 0
	global_load_dwordx4 v[194:197], v[140:141], off offset:3456
	global_load_dwordx4 v[198:201], v[142:143], off offset:3456
	s_setprio 1
	s_waitcnt lgkmcnt(1)
	v_mfma_f32_32x32x16_bf16 v[96:111], v[176:179], v[208:211], v[96:111]
	v_mfma_f32_32x32x16_bf16 v[112:127], v[180:183], v[208:211], v[112:127]
	s_waitcnt lgkmcnt(0)
	v_mfma_f32_32x32x16_bf16 v[64:79], v[176:179], v[212:215], v[64:79]
	v_mfma_f32_32x32x16_bf16 v[80:95], v[180:183], v[212:215], v[80:95]
	ds_read_b128 v[208:211], v149 offset:9248
	ds_read_b128 v[212:215], v149 offset:13856
	s_waitcnt vmcnt(7)
	ds_write_b128 v148, v[168:171] offset:18432
	s_waitcnt vmcnt(6)
	ds_write_b128 v148, v[172:175] offset:55296
	ds_read_b128 v[168:171], v150 offset:64
	ds_read_b128 v[172:175], v150 offset:4672
	s_waitcnt lgkmcnt(5)
	v_mfma_f32_32x32x16_bf16 v[32:47], v[176:179], v[208:211], v[32:47]
	v_mfma_f32_32x32x16_bf16 v[48:63], v[180:183], v[208:211], v[48:63]
	ds_read_b128 v[208:211], v149 offset:64
	s_waitcnt lgkmcnt(5)
	v_mfma_f32_32x32x16_bf16 v[0:15], v[176:179], v[212:215], v[0:15]
	v_mfma_f32_32x32x16_bf16 v[16:31], v[180:183], v[212:215], v[16:31]
	ds_read_b128 v[212:215], v149 offset:4672
	s_setprio 0
	global_load_dwordx4 v[176:179], v[132:133], off offset:3456
	global_load_dwordx4 v[180:183], v[134:135], off offset:3456
	s_setprio 1
	s_waitcnt lgkmcnt(1)
	v_mfma_f32_32x32x16_bf16 v[96:111], v[168:171], v[208:211], v[96:111]
	v_mfma_f32_32x32x16_bf16 v[112:127], v[172:175], v[208:211], v[112:127]
	s_waitcnt lgkmcnt(0)
	v_mfma_f32_32x32x16_bf16 v[64:79], v[168:171], v[212:215], v[64:79]
	v_mfma_f32_32x32x16_bf16 v[80:95], v[172:175], v[212:215], v[80:95]
	ds_read_b128 v[208:211], v149 offset:9280
	ds_read_b128 v[212:215], v149 offset:13888
	s_waitcnt vmcnt(7)
	ds_write_b128 v148, v[160:163] offset:27648
	s_waitcnt vmcnt(6)
	ds_write_b128 v148, v[164:167] offset:64512
	ds_read_b128 v[160:163], v150 offset:96
	ds_read_b128 v[164:167], v150 offset:4704
	s_waitcnt lgkmcnt(5)
	v_mfma_f32_32x32x16_bf16 v[32:47], v[168:171], v[208:211], v[32:47]
	v_mfma_f32_32x32x16_bf16 v[48:63], v[172:175], v[208:211], v[48:63]
	ds_read_b128 v[208:211], v149 offset:96
	s_waitcnt lgkmcnt(5)
	v_mfma_f32_32x32x16_bf16 v[0:15], v[168:171], v[212:215], v[0:15]
	v_mfma_f32_32x32x16_bf16 v[16:31], v[172:175], v[212:215], v[16:31]
	ds_read_b128 v[212:215], v149 offset:4704
	s_setprio 0
	global_load_dwordx4 v[168:171], v[144:145], off offset:3456
	global_load_dwordx4 v[172:175], v[146:147], off offset:3456
	s_setprio 1
	s_waitcnt lgkmcnt(1)
	v_mfma_f32_32x32x16_bf16 v[96:111], v[160:163], v[208:211], v[96:111]
	v_mfma_f32_32x32x16_bf16 v[112:127], v[164:167], v[208:211], v[112:127]
	s_waitcnt lgkmcnt(0)
	v_mfma_f32_32x32x16_bf16 v[64:79], v[160:163], v[212:215], v[64:79]
	v_mfma_f32_32x32x16_bf16 v[80:95], v[164:167], v[212:215], v[80:95]
	ds_read_b128 v[208:211], v149 offset:9312
	ds_read_b128 v[212:215], v149 offset:13920
	s_waitcnt lgkmcnt(0)
	s_barrier
; template <bool trans>
; DI void gemm_core(const GTile& tl, const GTile& nx, bool has_next  , bool chain  , bool pre, u32x4 (&ra)[4], u32x4 (&rb)[4], char* smem, f32x16 (&acc)[2][4]) {
;     ...
;   const int nk = K / 64;
;   if (!pre) { G_LOAD(0); G_STORE(0); G_LOAD(1); }
;   for (int kt = 0; kt < nk; ++kt) {
;     __syncthreads();
;     G_COMPUTE(kt & 1, kt);
;   }
	s_waitcnt vmcnt(7)
	ds_write_b128 v192, v[184:187]
	s_waitcnt vmcnt(6)
	ds_write_b128 v159, v[188:191]
	ds_read_b128 v[184:187], v152 offset:36864
	ds_read_b128 v[188:191], v152 offset:41472
	v_mfma_f32_32x32x16_bf16 v[32:47], v[160:163], v[208:211], v[32:47]
	v_mfma_f32_32x32x16_bf16 v[48:63], v[164:167], v[208:211], v[48:63]
	ds_read_b128 v[208:211], v151
	v_mfma_f32_32x32x16_bf16 v[0:15], v[160:163], v[212:215], v[0:15]
	v_mfma_f32_32x32x16_bf16 v[16:31], v[164:167], v[212:215], v[16:31]
	ds_read_b128 v[212:215], v151 offset:4608
	s_setprio 0
	global_load_dwordx4 v[160:163], v[136:137], off offset:3584
	global_load_dwordx4 v[164:167], v[138:139], off offset:3584
	s_setprio 1
	s_waitcnt lgkmcnt(1)
	v_mfma_f32_32x32x16_bf16 v[96:111], v[184:187], v[208:211], v[96:111]
	v_mfma_f32_32x32x16_bf16 v[112:127], v[188:191], v[208:211], v[112:127]
	s_waitcnt lgkmcnt(0)
	v_mfma_f32_32x32x16_bf16 v[64:79], v[184:187], v[212:215], v[64:79]
	v_mfma_f32_32x32x16_bf16 v[80:95], v[188:191], v[212:215], v[80:95]
	ds_read_b128 v[208:211], v151 offset:9216
	ds_read_b128 v[212:215], v151 offset:13824
	s_waitcnt vmcnt(7)
	ds_write_b128 v158, v[194:197]
	s_waitcnt vmcnt(6)
	ds_write_b128 v157, v[198:201]
	ds_read_b128 v[194:197], v152 offset:36896
	ds_read_b128 v[198:201], v152 offset:41504
	s_waitcnt lgkmcnt(5)
	v_mfma_f32_32x32x16_bf16 v[32:47], v[184:187], v[208:211], v[32:47]
	v_mfma_f32_32x32x16_bf16 v[48:63], v[188:191], v[208:211], v[48:63]
	ds_read_b128 v[208:211], v151 offset:32
	s_waitcnt lgkmcnt(5)
	v_mfma_f32_32x32x16_bf16 v[0:15], v[184:187], v[212:215], v[0:15]
	v_mfma_f32_32x32x16_bf16 v[16:31], v[188:191], v[212:215], v[16:31]
	ds_read_b128 v[212:215], v151 offset:4640
	s_setprio 0
	global_load_dwordx4 v[184:187], v[140:141], off offset:3584
	global_load_dwordx4 v[188:191], v[142:143], off offset:3584
	s_setprio 1
	s_waitcnt lgkmcnt(1)
	v_mfma_f32_32x32x16_bf16 v[96:111], v[194:197], v[208:211], v[96:111]
	v_mfma_f32_32x32x16_bf16 v[112:127], v[198:201], v[208:211], v[112:127]
	s_waitcnt lgkmcnt(0)
	v_mfma_f32_32x32x16_bf16 v[64:79], v[194:197], v[212:215], v[64:79]
	v_mfma_f32_32x32x16_bf16 v[80:95], v[198:201], v[212:215], v[80:95]
	ds_read_b128 v[208:211], v151 offset:9248
	ds_read_b128 v[212:215], v151 offset:13856
	s_waitcnt vmcnt(7)
	ds_write_b128 v154, v[176:179]
	s_waitcnt vmcnt(6)
	ds_write_b128 v153, v[180:183]
	ds_read_b128 v[176:179], v152 offset:36928
	ds_read_b128 v[180:183], v152 offset:41536
	s_waitcnt lgkmcnt(5)
	v_mfma_f32_32x32x16_bf16 v[32:47], v[194:197], v[208:211], v[32:47]
	v_mfma_f32_32x32x16_bf16 v[48:63], v[198:201], v[208:211], v[48:63]
	ds_read_b128 v[208:211], v151 offset:64
	s_waitcnt lgkmcnt(5)
	v_mfma_f32_32x32x16_bf16 v[0:15], v[194:197], v[212:215], v[0:15]
	v_mfma_f32_32x32x16_bf16 v[16:31], v[198:201], v[212:215], v[16:31]
	ds_read_b128 v[212:215], v151 offset:4672
	s_setprio 0
	global_load_dwordx4 v[194:197], v[132:133], off offset:3584
	global_load_dwordx4 v[198:201], v[134:135], off offset:3584
	s_setprio 1
	s_waitcnt lgkmcnt(1)
	v_mfma_f32_32x32x16_bf16 v[96:111], v[176:179], v[208:211], v[96:111]
	v_mfma_f32_32x32x16_bf16 v[112:127], v[180:183], v[208:211], v[112:127]
	s_waitcnt lgkmcnt(0)
	v_mfma_f32_32x32x16_bf16 v[64:79], v[176:179], v[212:215], v[64:79]
	v_mfma_f32_32x32x16_bf16 v[80:95], v[180:183], v[212:215], v[80:95]
	ds_read_b128 v[208:211], v151 offset:9280
	ds_read_b128 v[212:215], v151 offset:13888
	s_waitcnt vmcnt(7)
	ds_write_b128 v156, v[168:171]
	s_waitcnt vmcnt(6)
	ds_write_b128 v155, v[172:175]
	ds_read_b128 v[168:171], v152 offset:36960
	ds_read_b128 v[172:175], v152 offset:41568
	s_waitcnt lgkmcnt(5)
	v_mfma_f32_32x32x16_bf16 v[32:47], v[176:179], v[208:211], v[32:47]
	v_mfma_f32_32x32x16_bf16 v[48:63], v[180:183], v[208:211], v[48:63]
	ds_read_b128 v[208:211], v151 offset:96
	s_waitcnt lgkmcnt(5)
	v_mfma_f32_32x32x16_bf16 v[0:15], v[176:179], v[212:215], v[0:15]
	v_mfma_f32_32x32x16_bf16 v[16:31], v[180:183], v[212:215], v[16:31]
	ds_read_b128 v[212:215], v151 offset:4704
	s_setprio 0
	global_load_dwordx4 v[176:179], v[144:145], off offset:3584
	global_load_dwordx4 v[180:183], v[146:147], off offset:3584
	s_setprio 1
	s_waitcnt lgkmcnt(1)
	v_mfma_f32_32x32x16_bf16 v[96:111], v[168:171], v[208:211], v[96:111]
	v_mfma_f32_32x32x16_bf16 v[112:127], v[172:175], v[208:211], v[112:127]
	s_waitcnt lgkmcnt(0)
	v_mfma_f32_32x32x16_bf16 v[64:79], v[168:171], v[212:215], v[64:79]
	v_mfma_f32_32x32x16_bf16 v[80:95], v[172:175], v[212:215], v[80:95]
	ds_read_b128 v[208:211], v151 offset:9312
	ds_read_b128 v[212:215], v151 offset:13920
	s_waitcnt lgkmcnt(0)
	s_barrier
; template <bool trans>
; DI void gemm_core(const GTile& tl, const GTile& nx, bool has_next  , bool chain  , bool pre, u32x4 (&ra)[4], u32x4 (&rb)[4], char* smem, f32x16 (&acc)[2][4]) {
;     ...
;   const int nk = K / 64;
;   if (!pre) { G_LOAD(0); G_STORE(0); G_LOAD(1); }
;   for (int kt = 0; kt < nk; ++kt) {
;     __syncthreads();
;     G_COMPUTE(kt & 1, kt);
;   }
	s_waitcnt vmcnt(7)
	ds_write_b128 v148, v[160:163]
	s_waitcnt vmcnt(6)
	ds_write_b128 v148, v[164:167] offset:36864
	ds_read_b128 v[160:163], v150
	ds_read_b128 v[164:167], v150 offset:4608
	v_mfma_f32_32x32x16_bf16 v[32:47], v[168:171], v[208:211], v[32:47]
	v_mfma_f32_32x32x16_bf16 v[48:63], v[172:175], v[208:211], v[48:63]
	ds_read_b128 v[208:211], v149
	v_mfma_f32_32x32x16_bf16 v[0:15], v[168:171], v[212:215], v[0:15]
	v_mfma_f32_32x32x16_bf16 v[16:31], v[172:175], v[212:215], v[16:31]
	ds_read_b128 v[212:215], v149 offset:4608
	s_setprio 0
	global_load_dwordx4 v[168:171], v[136:137], off offset:3712
	global_load_dwordx4 v[172:175], v[138:139], off offset:3712
	s_setprio 1
	s_waitcnt lgkmcnt(1)
	v_mfma_f32_32x32x16_bf16 v[96:111], v[160:163], v[208:211], v[96:111]
	v_mfma_f32_32x32x16_bf16 v[112:127], v[164:167], v[208:211], v[112:127]
	s_waitcnt lgkmcnt(0)
	v_mfma_f32_32x32x16_bf16 v[64:79], v[160:163], v[212:215], v[64:79]
	v_mfma_f32_32x32x16_bf16 v[80:95], v[164:167], v[212:215], v[80:95]
	ds_read_b128 v[208:211], v149 offset:9216
	ds_read_b128 v[212:215], v149 offset:13824
	s_waitcnt vmcnt(7)
	ds_write_b128 v148, v[184:187] offset:9216
	s_waitcnt vmcnt(6)
	ds_write_b128 v148, v[188:191] offset:46080
	ds_read_b128 v[184:187], v150 offset:32
	ds_read_b128 v[188:191], v150 offset:4640
	s_waitcnt lgkmcnt(5)
	v_mfma_f32_32x32x16_bf16 v[32:47], v[160:163], v[208:211], v[32:47]
	v_mfma_f32_32x32x16_bf16 v[48:63], v[164:167], v[208:211], v[48:63]
	ds_read_b128 v[208:211], v149 offset:32
	s_waitcnt lgkmcnt(5)
	v_mfma_f32_32x32x16_bf16 v[0:15], v[160:163], v[212:215], v[0:15]
	v_mfma_f32_32x32x16_bf16 v[16:31], v[164:167], v[212:215], v[16:31]
	ds_read_b128 v[212:215], v149 offset:4640
	s_setprio 0
	global_load_dwordx4 v[160:163], v[140:141], off offset:3712
	global_load_dwordx4 v[164:167], v[142:143], off offset:3712
	s_setprio 1
	s_waitcnt lgkmcnt(1)
	v_mfma_f32_32x32x16_bf16 v[96:111], v[184:187], v[208:211], v[96:111]
	v_mfma_f32_32x32x16_bf16 v[112:127], v[188:191], v[208:211], v[112:127]
	s_waitcnt lgkmcnt(0)
	v_mfma_f32_32x32x16_bf16 v[64:79], v[184:187], v[212:215], v[64:79]
	v_mfma_f32_32x32x16_bf16 v[80:95], v[188:191], v[212:215], v[80:95]
	ds_read_b128 v[208:211], v149 offset:9248
	ds_read_b128 v[212:215], v149 offset:13856
	s_waitcnt vmcnt(7)
	ds_write_b128 v148, v[194:197] offset:18432
	s_waitcnt vmcnt(6)
	ds_write_b128 v148, v[198:201] offset:55296
	ds_read_b128 v[194:197], v150 offset:64
	ds_read_b128 v[198:201], v150 offset:4672
	s_waitcnt lgkmcnt(5)
	v_mfma_f32_32x32x16_bf16 v[32:47], v[184:187], v[208:211], v[32:47]
	v_mfma_f32_32x32x16_bf16 v[48:63], v[188:191], v[208:211], v[48:63]
	ds_read_b128 v[208:211], v149 offset:64
	s_waitcnt lgkmcnt(5)
	v_mfma_f32_32x32x16_bf16 v[0:15], v[184:187], v[212:215], v[0:15]
	v_mfma_f32_32x32x16_bf16 v[16:31], v[188:191], v[212:215], v[16:31]
	ds_read_b128 v[212:215], v149 offset:4672
	s_setprio 0
	global_load_dwordx4 v[184:187], v[132:133], off offset:3712
	global_load_dwordx4 v[188:191], v[134:135], off offset:3712
	s_setprio 1
	s_waitcnt lgkmcnt(1)
	v_mfma_f32_32x32x16_bf16 v[96:111], v[194:197], v[208:211], v[96:111]
	v_mfma_f32_32x32x16_bf16 v[112:127], v[198:201], v[208:211], v[112:127]
	s_waitcnt lgkmcnt(0)
	v_mfma_f32_32x32x16_bf16 v[64:79], v[194:197], v[212:215], v[64:79]
	v_mfma_f32_32x32x16_bf16 v[80:95], v[198:201], v[212:215], v[80:95]
	ds_read_b128 v[208:211], v149 offset:9280
	ds_read_b128 v[212:215], v149 offset:13888
	s_waitcnt vmcnt(7)
	ds_write_b128 v148, v[176:179] offset:27648
	s_waitcnt vmcnt(6)
	ds_write_b128 v148, v[180:183] offset:64512
	ds_read_b128 v[176:179], v150 offset:96
	ds_read_b128 v[180:183], v150 offset:4704
	s_waitcnt lgkmcnt(5)
	v_mfma_f32_32x32x16_bf16 v[32:47], v[194:197], v[208:211], v[32:47]
	v_mfma_f32_32x32x16_bf16 v[48:63], v[198:201], v[208:211], v[48:63]
	ds_read_b128 v[208:211], v149 offset:96
	s_waitcnt lgkmcnt(5)
	v_mfma_f32_32x32x16_bf16 v[0:15], v[194:197], v[212:215], v[0:15]
	v_mfma_f32_32x32x16_bf16 v[16:31], v[198:201], v[212:215], v[16:31]
	ds_read_b128 v[212:215], v149 offset:4704
	s_setprio 0
	global_load_dwordx4 v[194:197], v[144:145], off offset:3712
	global_load_dwordx4 v[198:201], v[146:147], off offset:3712
	s_setprio 1
	s_waitcnt lgkmcnt(1)
	v_mfma_f32_32x32x16_bf16 v[96:111], v[176:179], v[208:211], v[96:111]
	v_mfma_f32_32x32x16_bf16 v[112:127], v[180:183], v[208:211], v[112:127]
	s_waitcnt lgkmcnt(0)
	v_mfma_f32_32x32x16_bf16 v[64:79], v[176:179], v[212:215], v[64:79]
	v_mfma_f32_32x32x16_bf16 v[80:95], v[180:183], v[212:215], v[80:95]
	ds_read_b128 v[208:211], v149 offset:9312
	ds_read_b128 v[212:215], v149 offset:13920
	s_waitcnt lgkmcnt(1)
	v_mfma_f32_32x32x16_bf16 v[32:47], v[176:179], v[208:211], v[32:47]
	v_mfma_f32_32x32x16_bf16 v[48:63], v[180:183], v[208:211], v[48:63]
	s_waitcnt lgkmcnt(0)
	v_mfma_f32_32x32x16_bf16 v[0:15], v[176:179], v[212:215], v[0:15]
	v_mfma_f32_32x32x16_bf16 v[16:31], v[180:183], v[212:215], v[16:31]
	s_setprio 0
	global_load_dwordx4 v[176:179], v[136:137], off offset:3840
	global_load_dwordx4 v[180:183], v[138:139], off offset:3840
	s_barrier
; template <bool trans>
; DI void gemm_core(const GTile& tl, const GTile& nx, bool has_next  , bool chain  , bool pre, u32x4 (&ra)[4], u32x4 (&rb)[4], char* smem, f32x16 (&acc)[2][4]) {
;     ...
;   const int nk = K / 64;
;   if (!pre) { G_LOAD(0); G_STORE(0); G_LOAD(1); }
;   for (int kt = 0; kt < nk; ++kt) {
;     __syncthreads();
;     G_COMPUTE(kt & 1, kt);
;   }
	s_waitcnt vmcnt(9)
	ds_write_b128 v192, v[168:171]
	s_waitcnt vmcnt(8)
	ds_write_b128 v159, v[172:175]
	ds_read_b128 v[168:171], v152 offset:36864
	ds_read_b128 v[172:175], v152 offset:41472
	ds_read_b128 v[208:211], v151
	ds_read_b128 v[212:215], v151 offset:4608
	s_setprio 1
	s_waitcnt lgkmcnt(1)
	v_mfma_f32_32x32x16_bf16 v[96:111], v[168:171], v[208:211], v[96:111]
	v_mfma_f32_32x32x16_bf16 v[112:127], v[172:175], v[208:211], v[112:127]
	s_waitcnt lgkmcnt(0)
	v_mfma_f32_32x32x16_bf16 v[64:79], v[168:171], v[212:215], v[64:79]
	v_mfma_f32_32x32x16_bf16 v[80:95], v[172:175], v[212:215], v[80:95]
	ds_read_b128 v[208:211], v151 offset:9216
	ds_read_b128 v[212:215], v151 offset:13824
	s_waitcnt lgkmcnt(1)
	v_mfma_f32_32x32x16_bf16 v[32:47], v[168:171], v[208:211], v[32:47]
	v_mfma_f32_32x32x16_bf16 v[48:63], v[172:175], v[208:211], v[48:63]
	s_waitcnt lgkmcnt(0)
	v_mfma_f32_32x32x16_bf16 v[0:15], v[168:171], v[212:215], v[0:15]
	v_mfma_f32_32x32x16_bf16 v[16:31], v[172:175], v[212:215], v[16:31]
	s_setprio 0
	global_load_dwordx4 v[208:211], v[140:141], off offset:3840
	global_load_dwordx4 v[212:215], v[142:143], off offset:3840
	s_waitcnt vmcnt(9)
	ds_write_b128 v158, v[160:163]
	s_waitcnt vmcnt(8)
	ds_write_b128 v157, v[164:167]
	ds_read_b128 v[160:163], v152 offset:36896
	ds_read_b128 v[164:167], v152 offset:41504
	ds_read_b128 v[168:171], v151 offset:32
	ds_read_b128 v[172:175], v151 offset:4640
	s_setprio 1
	s_waitcnt lgkmcnt(1)
	v_mfma_f32_32x32x16_bf16 v[96:111], v[160:163], v[168:171], v[96:111]
	v_mfma_f32_32x32x16_bf16 v[112:127], v[164:167], v[168:171], v[112:127]
	s_waitcnt lgkmcnt(0)
	v_mfma_f32_32x32x16_bf16 v[64:79], v[160:163], v[172:175], v[64:79]
	v_mfma_f32_32x32x16_bf16 v[80:95], v[164:167], v[172:175], v[80:95]
	ds_read_b128 v[168:171], v151 offset:9248
	ds_read_b128 v[172:175], v151 offset:13856
	s_waitcnt lgkmcnt(1)
	v_mfma_f32_32x32x16_bf16 v[32:47], v[160:163], v[168:171], v[32:47]
	v_mfma_f32_32x32x16_bf16 v[48:63], v[164:167], v[168:171], v[48:63]
	s_waitcnt lgkmcnt(0)
	v_mfma_f32_32x32x16_bf16 v[0:15], v[160:163], v[172:175], v[0:15]
	v_mfma_f32_32x32x16_bf16 v[16:31], v[164:167], v[172:175], v[16:31]
	s_setprio 0
	global_load_dwordx4 v[216:219], v[132:133], off offset:3840
	global_load_dwordx4 v[220:223], v[134:135], off offset:3840
	s_waitcnt vmcnt(9)
	ds_write_b128 v154, v[184:187]
	s_waitcnt vmcnt(8)
	ds_write_b128 v153, v[188:191]
	ds_read_b128 v[160:163], v152 offset:36928
	ds_read_b128 v[164:167], v152 offset:41536
	ds_read_b128 v[168:171], v151 offset:64
	ds_read_b128 v[172:175], v151 offset:4672
	s_setprio 1
	s_waitcnt lgkmcnt(1)
	v_mfma_f32_32x32x16_bf16 v[96:111], v[160:163], v[168:171], v[96:111]
	v_mfma_f32_32x32x16_bf16 v[112:127], v[164:167], v[168:171], v[112:127]
	s_waitcnt lgkmcnt(0)
	v_mfma_f32_32x32x16_bf16 v[64:79], v[160:163], v[172:175], v[64:79]
	v_mfma_f32_32x32x16_bf16 v[80:95], v[164:167], v[172:175], v[80:95]
	ds_read_b128 v[168:171], v151 offset:9280
	ds_read_b128 v[172:175], v151 offset:13888
	s_waitcnt lgkmcnt(1)
	v_mfma_f32_32x32x16_bf16 v[32:47], v[160:163], v[168:171], v[32:47]
	v_mfma_f32_32x32x16_bf16 v[48:63], v[164:167], v[168:171], v[48:63]
	s_waitcnt lgkmcnt(0)
	v_mfma_f32_32x32x16_bf16 v[0:15], v[160:163], v[172:175], v[0:15]
	v_mfma_f32_32x32x16_bf16 v[16:31], v[164:167], v[172:175], v[16:31]
	s_setprio 0
	global_load_dwordx4 v[224:227], v[144:145], off offset:3840
	global_load_dwordx4 v[228:231], v[146:147], off offset:3840
	s_waitcnt vmcnt(9)
	ds_write_b128 v156, v[194:197]
	s_waitcnt vmcnt(8)
	ds_write_b128 v155, v[198:201]
	ds_read_b128 v[160:163], v152 offset:36960
	ds_read_b128 v[164:167], v152 offset:41568
	ds_read_b128 v[168:171], v151 offset:96
	ds_read_b128 v[172:175], v151 offset:4704
	s_setprio 1
	s_waitcnt lgkmcnt(1)
	v_mfma_f32_32x32x16_bf16 v[96:111], v[160:163], v[168:171], v[96:111]
	v_mfma_f32_32x32x16_bf16 v[112:127], v[164:167], v[168:171], v[112:127]
	s_waitcnt lgkmcnt(0)
	v_mfma_f32_32x32x16_bf16 v[64:79], v[160:163], v[172:175], v[64:79]
	v_mfma_f32_32x32x16_bf16 v[80:95], v[164:167], v[172:175], v[80:95]
	ds_read_b128 v[168:171], v151 offset:9312
	ds_read_b128 v[172:175], v151 offset:13920
	s_waitcnt lgkmcnt(1)
	v_mfma_f32_32x32x16_bf16 v[32:47], v[160:163], v[168:171], v[32:47]
	v_mfma_f32_32x32x16_bf16 v[48:63], v[164:167], v[168:171], v[48:63]
	s_waitcnt lgkmcnt(0)
	v_mfma_f32_32x32x16_bf16 v[0:15], v[160:163], v[172:175], v[0:15]
	v_mfma_f32_32x32x16_bf16 v[16:31], v[164:167], v[172:175], v[16:31]
	s_setprio 0
	global_load_dwordx4 v[160:163], v[136:137], off offset:3968
	global_load_dwordx4 v[164:167], v[138:139], off offset:3968
	s_barrier
; template <bool trans>
; DI void gemm_core(const GTile& tl, const GTile& nx, bool has_next  , bool chain  , bool pre, u32x4 (&ra)[4], u32x4 (&rb)[4], char* smem, f32x16 (&acc)[2][4]) {
;     ...
;   const int nk = K / 64;
;   if (!pre) { G_LOAD(0); G_STORE(0); G_LOAD(1); }
;   for (int kt = 0; kt < nk; ++kt) {
;     __syncthreads();
;     G_COMPUTE(kt & 1, kt);
;   }
	s_waitcnt vmcnt(9)
	ds_write_b128 v148, v[176:179]
	s_waitcnt vmcnt(8)
	ds_write_b128 v148, v[180:183] offset:36864
	ds_read_b128 v[136:139], v150
	ds_read_b128 v[168:171], v150 offset:4608
	ds_read_b128 v[172:175], v149
	ds_read_b128 v[176:179], v149 offset:4608
	s_setprio 1
	s_waitcnt lgkmcnt(1)
	v_mfma_f32_32x32x16_bf16 v[96:111], v[136:139], v[172:175], v[96:111]
	v_mfma_f32_32x32x16_bf16 v[112:127], v[168:171], v[172:175], v[112:127]
	s_waitcnt lgkmcnt(0)
	v_mfma_f32_32x32x16_bf16 v[64:79], v[136:139], v[176:179], v[64:79]
	v_mfma_f32_32x32x16_bf16 v[80:95], v[168:171], v[176:179], v[80:95]
	ds_read_b128 v[172:175], v149 offset:9216
	ds_read_b128 v[176:179], v149 offset:13824
	s_waitcnt lgkmcnt(1)
	v_mfma_f32_32x32x16_bf16 v[32:47], v[136:139], v[172:175], v[32:47]
	v_mfma_f32_32x32x16_bf16 v[48:63], v[168:171], v[172:175], v[48:63]
	s_waitcnt lgkmcnt(0)
	v_mfma_f32_32x32x16_bf16 v[0:15], v[136:139], v[176:179], v[0:15]
	v_mfma_f32_32x32x16_bf16 v[16:31], v[168:171], v[176:179], v[16:31]
	s_setprio 0
	global_load_dwordx4 v[168:171], v[140:141], off offset:3968
	global_load_dwordx4 v[172:175], v[142:143], off offset:3968
	s_waitcnt vmcnt(9)
	ds_write_b128 v148, v[208:211] offset:9216
	s_waitcnt vmcnt(8)
	ds_write_b128 v148, v[212:215] offset:46080
	ds_read_b128 v[136:139], v150 offset:32
	ds_read_b128 v[140:143], v150 offset:4640
	ds_read_b128 v[176:179], v149 offset:32
	ds_read_b128 v[180:183], v149 offset:4640
	s_setprio 1
	s_waitcnt lgkmcnt(1)
	v_mfma_f32_32x32x16_bf16 v[96:111], v[136:139], v[176:179], v[96:111]
	v_mfma_f32_32x32x16_bf16 v[112:127], v[140:143], v[176:179], v[112:127]
	s_waitcnt lgkmcnt(0)
	v_mfma_f32_32x32x16_bf16 v[64:79], v[136:139], v[180:183], v[64:79]
	v_mfma_f32_32x32x16_bf16 v[80:95], v[140:143], v[180:183], v[80:95]
	ds_read_b128 v[176:179], v149 offset:9248
	ds_read_b128 v[180:183], v149 offset:13856
	s_waitcnt lgkmcnt(1)
	v_mfma_f32_32x32x16_bf16 v[32:47], v[136:139], v[176:179], v[32:47]
	v_mfma_f32_32x32x16_bf16 v[48:63], v[140:143], v[176:179], v[48:63]
	s_waitcnt lgkmcnt(0)
	v_mfma_f32_32x32x16_bf16 v[0:15], v[136:139], v[180:183], v[0:15]
	v_mfma_f32_32x32x16_bf16 v[16:31], v[140:143], v[180:183], v[16:31]
	s_setprio 0
	global_load_dwordx4 v[176:179], v[132:133], off offset:3968
	global_load_dwordx4 v[180:183], v[134:135], off offset:3968
	s_waitcnt vmcnt(9)
	ds_write_b128 v148, v[216:219] offset:18432
	s_waitcnt vmcnt(8)
	ds_write_b128 v148, v[220:223] offset:55296
	ds_read_b128 v[132:135], v150 offset:64
	ds_read_b128 v[136:139], v150 offset:4672
	ds_read_b128 v[140:143], v149 offset:64
	ds_read_b128 v[184:187], v149 offset:4672
	s_setprio 1
	s_waitcnt lgkmcnt(1)
	v_mfma_f32_32x32x16_bf16 v[96:111], v[132:135], v[140:143], v[96:111]
	v_mfma_f32_32x32x16_bf16 v[112:127], v[136:139], v[140:143], v[112:127]
	s_waitcnt lgkmcnt(0)
	v_mfma_f32_32x32x16_bf16 v[64:79], v[132:135], v[184:187], v[64:79]
	v_mfma_f32_32x32x16_bf16 v[80:95], v[136:139], v[184:187], v[80:95]
	ds_read_b128 v[140:143], v149 offset:9280
	ds_read_b128 v[184:187], v149 offset:13888
	s_waitcnt lgkmcnt(1)
	v_mfma_f32_32x32x16_bf16 v[32:47], v[132:135], v[140:143], v[32:47]
	v_mfma_f32_32x32x16_bf16 v[48:63], v[136:139], v[140:143], v[48:63]
	s_waitcnt lgkmcnt(0)
	v_mfma_f32_32x32x16_bf16 v[0:15], v[132:135], v[184:187], v[0:15]
	v_mfma_f32_32x32x16_bf16 v[16:31], v[136:139], v[184:187], v[16:31]
	s_setprio 0
	global_load_dwordx4 v[184:187], v[144:145], off offset:3968
	global_load_dwordx4 v[188:191], v[146:147], off offset:3968
	s_waitcnt vmcnt(9)
	ds_write_b128 v148, v[224:227] offset:27648
	s_waitcnt vmcnt(8)
	ds_write_b128 v148, v[228:231] offset:64512
	ds_read_b128 v[132:135], v150 offset:96
	ds_read_b128 v[136:139], v150 offset:4704
	ds_read_b128 v[140:143], v149 offset:96
	ds_read_b128 v[144:147], v149 offset:4704
	s_setprio 1
	s_waitcnt lgkmcnt(1)
	v_mfma_f32_32x32x16_bf16 v[96:111], v[132:135], v[140:143], v[96:111]
	v_mfma_f32_32x32x16_bf16 v[112:127], v[136:139], v[140:143], v[112:127]
	s_waitcnt lgkmcnt(0)
	v_mfma_f32_32x32x16_bf16 v[64:79], v[132:135], v[144:147], v[64:79]
	v_mfma_f32_32x32x16_bf16 v[80:95], v[136:139], v[144:147], v[80:95]
	ds_read_b128 v[140:143], v149 offset:9312
	ds_read_b128 v[144:147], v149 offset:13920
	s_waitcnt lgkmcnt(1)
	v_mfma_f32_32x32x16_bf16 v[32:47], v[132:135], v[140:143], v[32:47]
	v_mfma_f32_32x32x16_bf16 v[48:63], v[136:139], v[140:143], v[48:63]
	s_waitcnt lgkmcnt(0)
	v_mfma_f32_32x32x16_bf16 v[0:15], v[132:135], v[144:147], v[0:15]
	v_mfma_f32_32x32x16_bf16 v[16:31], v[136:139], v[144:147], v[16:31]
	s_setprio 0
	v_cndmask_b32_e64 v132, 0, 1, s[34:35]
	v_cmp_ne_u32_e64 s[6:7], 1, v132
	s_andn2_b64 vcc, exec, s[34:35]
	s_barrier
	s_waitcnt vmcnt(7)
	ds_write_b128 v192, v[160:163]
	s_waitcnt vmcnt(6)
	ds_write_b128 v159, v[164:167]
	s_cbranch_vccnz .LBB0_892
	global_load_dwordx4 v[160:163], v[130:131], off
	global_load_dwordx4 v[164:167], v[128:129], off

;   DI bf16_t* h() const { return (bf16_t*)(ws + OFF_H); }
; template <bool trans>
; DI void gemm_core(const GTile& tl, const GTile& nx, bool has_next  , bool chain  , bool pre, u32x4 (&ra)[4], u32x4 (&rb)[4], char* smem, f32x16 (&acc)[2][4]) {
;     ...
;   const int nk = K / 64;
;   if (!pre) { G_LOAD(0); G_STORE(0); G_LOAD(1); }
;   for (int kt = 0; kt < nk; ++kt) {
;     __syncthreads();
;     G_COMPUTE(kt & 1, kt);
;   }
; DI void phase_gemm_out(const Params& p, char* smem, const bf16_t* Wt, const float* R, float* O) {
;     ...
;   for (int t = blockIdx.x; t < 64 * 8; t += gridDim.x) {
;     const int mt = t & 63, nt = t >> 6, tn = t + gridDim.x;
;     const bool has_next = tn < 64 * 8;
;     const GTile tl{p.h(), D, Wt, D, D, mt * 256, nt * 256}, nx{p.h(), D, Wt, D, D, (tn & 63) * 256, (tn >> 6) * 256};
;     WAVE_GEOM;
;     f32x16 acc[2][4];
;     gemm_core<false>(tl, nx, has_next, has_next, pre, ra, rb, smem, acc);
.LBB0_1637:
	v_lshl_add_u64 v[128:129], s[2:3], 0, v[184:185]
	v_lshl_add_u64 v[132:133], s[4:5], 0, v[184:185]
	s_waitcnt lgkmcnt(0)
	s_barrier
	global_load_dwordx4 v[200:203], v[128:129], off offset:256
	global_load_dwordx4 v[208:211], v[132:133], off offset:256
	s_add_i32 s84, s84, s96
	s_cmpk_lt_i32 s84, 0x200
	s_cselect_b64 s[12:13], -1, 0
	s_cmpk_gt_i32 s84, 0x1ff
	s_cselect_b64 s[10:11], -1, 0
	s_and_b32 s3, s24, 0x1f80000
	s_add_i32 s16, s17, s16
	s_and_b32 s2, s16, 0xffffff00
	s_and_b32 s38, s37, 0xc0
	s_lshl_b32 s3, s3, 1
	s_add_u32 s4, s28, s3
	s_addc_u32 s5, s29, 0
	s_ashr_i32 s3, s2, 31
	s_lshl_b64 s[2:3], s[2:3], 12
	s_add_u32 s2, s14, s2
	s_addc_u32 s3, s15, s3
	s_lshr_b32 s37, s37, 1
	v_and_b32_e32 v11, 31, v8
	s_and_b32 s37, s37, 0xfffff80
	v_or_b32_e32 v12, s37, v11
	v_or_b32_e32 v11, s38, v11
	v_add3_u32 v191, 16, v10, v9
	v_lshrrev_b32_e32 v8, 1, v8
	v_mul_u32_u24_e32 v131, 0x90, v11
	v_and_b32_e32 v134, 16, v8
	v_add_u32_e32 v195, 0x12000, v191
	v_mul_lo_u32 v130, v12, s33
	v_add3_u32 v192, 16, v131, v134
	v_add_u32_e32 v196, 0x1b000, v191
	ds_write_b128 v195, v[0:3]
	s_waitcnt vmcnt(5)
	ds_write_b128 v196, v[4:7]
	v_lshl_add_u64 v[188:189], s[4:5], 0, v[184:185]
	v_lshl_add_u64 v[186:187], s[2:3], 0, v[184:185]
	v_add3_u32 v184, 16, v130, v134
	ds_read_b128 v[0:3], v192 offset:36864
	ds_read_b128 v[4:7], v192 offset:41472
	ds_read_b128 v[8:11], v184
	ds_read_b128 v[12:15], v184 offset:4608
	v_lshl_add_u64 v[136:137], v[128:129], 0, s[0:1]
	v_lshl_add_u64 v[140:141], v[132:133], 0, s[0:1]
	v_lshl_add_u64 v[144:145], v[128:129], 0, s[6:7]
	v_lshl_add_u64 v[148:149], v[132:133], 0, s[6:7]
	s_setprio 1
	s_waitcnt lgkmcnt(1)
	v_mfma_f32_32x32x16_bf16 v[112:127], v[0:3], v[8:11], 0
	v_mfma_f32_32x32x16_bf16 v[48:63], v[4:7], v[8:11], 0
	s_waitcnt lgkmcnt(0)
	v_mfma_f32_32x32x16_bf16 v[96:111], v[0:3], v[12:15], 0
	v_mfma_f32_32x32x16_bf16 v[32:47], v[4:7], v[12:15], 0
	ds_read_b128 v[8:11], v184 offset:9216
	ds_read_b128 v[12:15], v184 offset:13824
	s_waitcnt lgkmcnt(1)
	v_mfma_f32_32x32x16_bf16 v[80:95], v[0:3], v[8:11], 0
	v_mfma_f32_32x32x16_bf16 v[16:31], v[4:7], v[8:11], 0
	s_waitcnt lgkmcnt(0)
	v_mfma_f32_32x32x16_bf16 v[64:79], v[0:3], v[12:15], 0
	v_mfma_f32_32x32x16_bf16 v[0:15], v[4:7], v[12:15], 0
	s_setprio 0
	global_load_dwordx4 v[212:215], v[136:137], off offset:256
	global_load_dwordx4 v[216:219], v[140:141], off offset:256
	v_add_u32_e32 v194, 0x14400, v191
	v_add_u32_e32 v193, 0x1d400, v191
	ds_write_b128 v194, v[176:179]
	s_waitcnt vmcnt(6)
	ds_write_b128 v193, v[180:183]
	ds_read_b128 v[150:153], v192 offset:36896
	ds_read_b128 v[154:157], v192 offset:41504
	ds_read_b128 v[176:179], v184 offset:32
	ds_read_b128 v[180:183], v184 offset:4640
	s_setprio 1
	s_waitcnt lgkmcnt(1)
	v_mfma_f32_32x32x16_bf16 v[112:127], v[150:153], v[176:179], v[112:127]
	v_mfma_f32_32x32x16_bf16 v[48:63], v[154:157], v[176:179], v[48:63]
	s_waitcnt lgkmcnt(0)
	v_mfma_f32_32x32x16_bf16 v[96:111], v[150:153], v[180:183], v[96:111]
	v_mfma_f32_32x32x16_bf16 v[32:47], v[154:157], v[180:183], v[32:47]
	ds_read_b128 v[176:179], v184 offset:9248
	ds_read_b128 v[180:183], v184 offset:13856
	s_waitcnt lgkmcnt(1)
	v_mfma_f32_32x32x16_bf16 v[80:95], v[150:153], v[176:179], v[80:95]
	v_mfma_f32_32x32x16_bf16 v[16:31], v[154:157], v[176:179], v[16:31]
	s_waitcnt lgkmcnt(0)
	v_mfma_f32_32x32x16_bf16 v[64:79], v[150:153], v[180:183], v[64:79]
	v_mfma_f32_32x32x16_bf16 v[0:15], v[154:157], v[180:183], v[0:15]
	s_setprio 0
	global_load_dwordx4 v[178:181], v[144:145], off offset:256
	global_load_dwordx4 v[220:223], v[148:149], off offset:256
	v_add_u32_e32 v177, 0x16800, v191
	v_add_u32_e32 v176, 0x1f800, v191
	ds_write_b128 v177, v[168:171]
	s_waitcnt vmcnt(7)
	ds_write_b128 v176, v[172:175]
	ds_read_b128 v[150:153], v192 offset:36928
	ds_read_b128 v[154:157], v192 offset:41536
	ds_read_b128 v[168:171], v184 offset:64
	ds_read_b128 v[172:175], v184 offset:4672
	s_setprio 1
	s_waitcnt lgkmcnt(1)
	v_mfma_f32_32x32x16_bf16 v[112:127], v[150:153], v[168:171], v[112:127]
	v_mfma_f32_32x32x16_bf16 v[48:63], v[154:157], v[168:171], v[48:63]
	s_waitcnt lgkmcnt(0)
	v_mfma_f32_32x32x16_bf16 v[96:111], v[150:153], v[172:175], v[96:111]
	v_mfma_f32_32x32x16_bf16 v[32:47], v[154:157], v[172:175], v[32:47]
	ds_read_b128 v[168:171], v184 offset:9280
	ds_read_b128 v[172:175], v184 offset:13888
	s_waitcnt lgkmcnt(1)
	v_mfma_f32_32x32x16_bf16 v[80:95], v[150:153], v[168:171], v[80:95]
	v_mfma_f32_32x32x16_bf16 v[16:31], v[154:157], v[168:171], v[16:31]
	s_waitcnt lgkmcnt(0)
	v_mfma_f32_32x32x16_bf16 v[64:79], v[150:153], v[172:175], v[64:79]
	v_mfma_f32_32x32x16_bf16 v[0:15], v[154:157], v[172:175], v[0:15]
	s_setprio 0
	v_add_co_u32_e32 v152, vcc, s31, v128
	v_add_u32_e32 v171, 0x18c00, v191
	s_nop 0
	v_addc_co_u32_e32 v153, vcc, 0, v129, vcc
	v_add_co_u32_e32 v156, vcc, s31, v132
	v_add_u32_e32 v170, 0x21c00, v191
	s_nop 0
	v_addc_co_u32_e32 v157, vcc, 0, v133, vcc
	global_load_dwordx4 v[172:175], v[152:153], off offset:256
	global_load_dwordx4 v[224:227], v[156:157], off offset:256
	ds_write_b128 v171, v[160:163]
	s_waitcnt vmcnt(8)
	ds_write_b128 v170, v[164:167]
	ds_read_b128 v[158:161], v192 offset:36960
	ds_read_b128 v[162:165], v192 offset:41568
	ds_read_b128 v[166:169], v184 offset:96
	ds_read_b128 v[228:231], v184 offset:4704
	s_setprio 1
	s_waitcnt lgkmcnt(1)
	v_mfma_f32_32x32x16_bf16 v[112:127], v[158:161], v[166:169], v[112:127]
	v_mfma_f32_32x32x16_bf16 v[48:63], v[162:165], v[166:169], v[48:63]
	s_waitcnt lgkmcnt(0)
	v_mfma_f32_32x32x16_bf16 v[96:111], v[158:161], v[228:231], v[96:111]
	v_mfma_f32_32x32x16_bf16 v[32:47], v[162:165], v[228:231], v[32:47]
	ds_read_b128 v[166:169], v184 offset:9312
	ds_read_b128 v[228:231], v184 offset:13920
	s_waitcnt lgkmcnt(1)
	v_mfma_f32_32x32x16_bf16 v[80:95], v[158:161], v[166:169], v[80:95]
	v_mfma_f32_32x32x16_bf16 v[16:31], v[162:165], v[166:169], v[16:31]
	s_waitcnt lgkmcnt(0)
	v_mfma_f32_32x32x16_bf16 v[64:79], v[158:161], v[228:231], v[64:79]
	v_mfma_f32_32x32x16_bf16 v[0:15], v[162:165], v[228:231], v[0:15]
	s_setprio 0
	global_load_dwordx4 v[158:161], v[128:129], off offset:384
	global_load_dwordx4 v[162:165], v[132:133], off offset:384
	s_barrier
; template <bool trans>
; DI void gemm_core(const GTile& tl, const GTile& nx, bool has_next  , bool chain  , bool pre, u32x4 (&ra)[4], u32x4 (&rb)[4], char* smem, f32x16 (&acc)[2][4]) {
;     ...
;   const int nk = K / 64;
;   if (!pre) { G_LOAD(0); G_STORE(0); G_LOAD(1); }
;   for (int kt = 0; kt < nk; ++kt) {
;     __syncthreads();
;     G_COMPUTE(kt & 1, kt);
;   }
	v_add3_u32 v169, s35, v131, v134
	s_waitcnt vmcnt(9)
	ds_write_b128 v191, v[200:203]
	s_waitcnt vmcnt(8)
	ds_write_b128 v191, v[208:211] offset:36864
	v_add3_u32 v168, s34, v130, v134
	ds_read_b128 v[200:203], v169
	ds_read_b128 v[208:211], v169 offset:4608
	ds_read_b128 v[228:231], v168
	ds_read_b128 v[232:235], v168 offset:4608
	s_setprio 1
	s_waitcnt lgkmcnt(1)
	v_mfma_f32_32x32x16_bf16 v[112:127], v[200:203], v[228:231], v[112:127]
	v_mfma_f32_32x32x16_bf16 v[48:63], v[208:211], v[228:231], v[48:63]
	s_waitcnt lgkmcnt(0)
	v_mfma_f32_32x32x16_bf16 v[96:111], v[200:203], v[232:235], v[96:111]
	v_mfma_f32_32x32x16_bf16 v[32:47], v[208:211], v[232:235], v[32:47]
	ds_read_b128 v[228:231], v168 offset:9216
	ds_read_b128 v[232:235], v168 offset:13824
	s_waitcnt lgkmcnt(1)
	v_mfma_f32_32x32x16_bf16 v[80:95], v[200:203], v[228:231], v[80:95]
	v_mfma_f32_32x32x16_bf16 v[16:31], v[208:211], v[228:231], v[16:31]
	s_waitcnt lgkmcnt(0)
	v_mfma_f32_32x32x16_bf16 v[64:79], v[200:203], v[232:235], v[64:79]
	v_mfma_f32_32x32x16_bf16 v[0:15], v[208:211], v[232:235], v[0:15]
	s_setprio 0
	global_load_dwordx4 v[200:203], v[136:137], off offset:384
	global_load_dwordx4 v[208:211], v[140:141], off offset:384
	s_waitcnt vmcnt(9)
	ds_write_b128 v191, v[212:215] offset:9216
	s_waitcnt vmcnt(8)
	ds_write_b128 v191, v[216:219] offset:46080
	ds_read_b128 v[212:215], v169 offset:32
	ds_read_b128 v[216:219], v169 offset:4640
	ds_read_b128 v[228:231], v168 offset:32
	ds_read_b128 v[232:235], v168 offset:4640
	s_setprio 1
	s_waitcnt lgkmcnt(1)
	v_mfma_f32_32x32x16_bf16 v[112:127], v[212:215], v[228:231], v[112:127]
	v_mfma_f32_32x32x16_bf16 v[48:63], v[216:219], v[228:231], v[48:63]
	s_waitcnt lgkmcnt(0)
	v_mfma_f32_32x32x16_bf16 v[96:111], v[212:215], v[232:235], v[96:111]
	v_mfma_f32_32x32x16_bf16 v[32:47], v[216:219], v[232:235], v[32:47]
	ds_read_b128 v[228:231], v168 offset:9248
	ds_read_b128 v[232:235], v168 offset:13856
	s_waitcnt lgkmcnt(1)
	v_mfma_f32_32x32x16_bf16 v[80:95], v[212:215], v[228:231], v[80:95]
	v_mfma_f32_32x32x16_bf16 v[16:31], v[216:219], v[228:231], v[16:31]
	s_waitcnt lgkmcnt(0)
	v_mfma_f32_32x32x16_bf16 v[64:79], v[212:215], v[232:235], v[64:79]
	v_mfma_f32_32x32x16_bf16 v[0:15], v[216:219], v[232:235], v[0:15]
	s_setprio 0
	global_load_dwordx4 v[212:215], v[144:145], off offset:384
	global_load_dwordx4 v[216:219], v[148:149], off offset:384
	s_waitcnt vmcnt(9)
	ds_write_b128 v191, v[178:181] offset:18432
	s_waitcnt vmcnt(8)
	ds_write_b128 v191, v[220:223] offset:55296
	ds_read_b128 v[178:181], v169 offset:64
	ds_read_b128 v[220:223], v169 offset:4672
	ds_read_b128 v[228:231], v168 offset:64
	ds_read_b128 v[232:235], v168 offset:4672
	s_setprio 1
	s_waitcnt lgkmcnt(1)
	v_mfma_f32_32x32x16_bf16 v[112:127], v[178:181], v[228:231], v[112:127]
	v_mfma_f32_32x32x16_bf16 v[48:63], v[220:223], v[228:231], v[48:63]
	s_waitcnt lgkmcnt(0)
	v_mfma_f32_32x32x16_bf16 v[96:111], v[178:181], v[232:235], v[96:111]
	v_mfma_f32_32x32x16_bf16 v[32:47], v[220:223], v[232:235], v[32:47]
	ds_read_b128 v[228:231], v168 offset:9280
	ds_read_b128 v[232:235], v168 offset:13888
	s_waitcnt lgkmcnt(1)
	v_mfma_f32_32x32x16_bf16 v[80:95], v[178:181], v[228:231], v[80:95]
	v_mfma_f32_32x32x16_bf16 v[16:31], v[220:223], v[228:231], v[16:31]
	s_waitcnt lgkmcnt(0)
	v_mfma_f32_32x32x16_bf16 v[64:79], v[178:181], v[232:235], v[64:79]
	v_mfma_f32_32x32x16_bf16 v[0:15], v[220:223], v[232:235], v[0:15]
	s_setprio 0
	global_load_dwordx4 v[178:181], v[152:153], off offset:384
	global_load_dwordx4 v[220:223], v[156:157], off offset:384
	s_waitcnt vmcnt(9)
	ds_write_b128 v191, v[172:175] offset:27648
	s_waitcnt vmcnt(8)
	ds_write_b128 v191, v[224:227] offset:64512
	ds_read_b128 v[172:175], v169 offset:96
	ds_read_b128 v[224:227], v169 offset:4704
	ds_read_b128 v[228:231], v168 offset:96
	ds_read_b128 v[232:235], v168 offset:4704
	s_setprio 1
	s_waitcnt lgkmcnt(1)
	v_mfma_f32_32x32x16_bf16 v[112:127], v[172:175], v[228:231], v[112:127]
	v_mfma_f32_32x32x16_bf16 v[48:63], v[224:227], v[228:231], v[48:63]
	s_waitcnt lgkmcnt(0)
	v_mfma_f32_32x32x16_bf16 v[96:111], v[172:175], v[232:235], v[96:111]
	v_mfma_f32_32x32x16_bf16 v[32:47], v[224:227], v[232:235], v[32:47]
	ds_read_b128 v[228:231], v168 offset:9312
	ds_read_b128 v[232:235], v168 offset:13920
	s_waitcnt lgkmcnt(1)
	v_mfma_f32_32x32x16_bf16 v[80:95], v[172:175], v[228:231], v[80:95]
	v_mfma_f32_32x32x16_bf16 v[16:31], v[224:227], v[228:231], v[16:31]
	s_waitcnt lgkmcnt(0)
	v_mfma_f32_32x32x16_bf16 v[64:79], v[172:175], v[232:235], v[64:79]
	v_mfma_f32_32x32x16_bf16 v[0:15], v[224:227], v[232:235], v[0:15]
	s_setprio 0
	global_load_dwordx4 v[172:175], v[128:129], off offset:512
	global_load_dwordx4 v[224:227], v[132:133], off offset:512
	s_barrier
; template <bool trans>
; DI void gemm_core(const GTile& tl, const GTile& nx, bool has_next  , bool chain  , bool pre, u32x4 (&ra)[4], u32x4 (&rb)[4], char* smem, f32x16 (&acc)[2][4]) {
;     ...
;   const int nk = K / 64;
;   if (!pre) { G_LOAD(0); G_STORE(0); G_LOAD(1); }
;   for (int kt = 0; kt < nk; ++kt) {
;     __syncthreads();
;     G_COMPUTE(kt & 1, kt);
;   }
	s_waitcnt vmcnt(9)
	ds_write_b128 v195, v[158:161]
	s_waitcnt vmcnt(8)
	ds_write_b128 v196, v[162:165]
	ds_read_b128 v[158:161], v192 offset:36864
	ds_read_b128 v[162:165], v192 offset:41472
	ds_read_b128 v[228:231], v184
	ds_read_b128 v[232:235], v184 offset:4608
	s_setprio 1
	s_waitcnt lgkmcnt(1)
	v_mfma_f32_32x32x16_bf16 v[112:127], v[158:161], v[228:231], v[112:127]
	v_mfma_f32_32x32x16_bf16 v[48:63], v[162:165], v[228:231], v[48:63]
	s_waitcnt lgkmcnt(0)
	v_mfma_f32_32x32x16_bf16 v[96:111], v[158:161], v[232:235], v[96:111]
	v_mfma_f32_32x32x16_bf16 v[32:47], v[162:165], v[232:235], v[32:47]
	ds_read_b128 v[228:231], v184 offset:9216
	ds_read_b128 v[232:235], v184 offset:13824
	s_waitcnt vmcnt(7)
	ds_write_b128 v194, v[200:203]
	s_waitcnt vmcnt(6)
	ds_write_b128 v193, v[208:211]
	ds_read_b128 v[200:203], v192 offset:36896
	ds_read_b128 v[208:211], v192 offset:41504
	s_waitcnt lgkmcnt(5)
	v_mfma_f32_32x32x16_bf16 v[80:95], v[158:161], v[228:231], v[80:95]
	v_mfma_f32_32x32x16_bf16 v[16:31], v[162:165], v[228:231], v[16:31]
	ds_read_b128 v[228:231], v184 offset:32
	s_waitcnt lgkmcnt(5)
	v_mfma_f32_32x32x16_bf16 v[64:79], v[158:161], v[232:235], v[64:79]
	v_mfma_f32_32x32x16_bf16 v[0:15], v[162:165], v[232:235], v[0:15]
	ds_read_b128 v[232:235], v184 offset:4640
	s_setprio 0
	global_load_dwordx4 v[158:161], v[136:137], off offset:512
	global_load_dwordx4 v[162:165], v[140:141], off offset:512
	s_setprio 1
	s_waitcnt lgkmcnt(1)
	v_mfma_f32_32x32x16_bf16 v[112:127], v[200:203], v[228:231], v[112:127]
	v_mfma_f32_32x32x16_bf16 v[48:63], v[208:211], v[228:231], v[48:63]
	s_waitcnt lgkmcnt(0)
	v_mfma_f32_32x32x16_bf16 v[96:111], v[200:203], v[232:235], v[96:111]
	v_mfma_f32_32x32x16_bf16 v[32:47], v[208:211], v[232:235], v[32:47]
	ds_read_b128 v[228:231], v184 offset:9248
	ds_read_b128 v[232:235], v184 offset:13856
	s_waitcnt vmcnt(7)
	ds_write_b128 v177, v[212:215]
	s_waitcnt vmcnt(6)
	ds_write_b128 v176, v[216:219]
	ds_read_b128 v[212:215], v192 offset:36928
	ds_read_b128 v[216:219], v192 offset:41536
	s_waitcnt lgkmcnt(5)
	v_mfma_f32_32x32x16_bf16 v[80:95], v[200:203], v[228:231], v[80:95]
	v_mfma_f32_32x32x16_bf16 v[16:31], v[208:211], v[228:231], v[16:31]
	ds_read_b128 v[228:231], v184 offset:64
	s_waitcnt lgkmcnt(5)
	v_mfma_f32_32x32x16_bf16 v[64:79], v[200:203], v[232:235], v[64:79]
	v_mfma_f32_32x32x16_bf16 v[0:15], v[208:211], v[232:235], v[0:15]
	ds_read_b128 v[232:235], v184 offset:4672
	s_setprio 0
	global_load_dwordx4 v[200:203], v[144:145], off offset:512
	global_load_dwordx4 v[208:211], v[148:149], off offset:512
	s_setprio 1
	s_waitcnt lgkmcnt(1)
	v_mfma_f32_32x32x16_bf16 v[112:127], v[212:215], v[228:231], v[112:127]
	v_mfma_f32_32x32x16_bf16 v[48:63], v[216:219], v[228:231], v[48:63]
	s_waitcnt lgkmcnt(0)
	v_mfma_f32_32x32x16_bf16 v[96:111], v[212:215], v[232:235], v[96:111]
	v_mfma_f32_32x32x16_bf16 v[32:47], v[216:219], v[232:235], v[32:47]
	ds_read_b128 v[228:231], v184 offset:9280
	ds_read_b128 v[232:235], v184 offset:13888
	s_waitcnt vmcnt(7)
	ds_write_b128 v171, v[178:181]
	s_waitcnt vmcnt(6)
	ds_write_b128 v170, v[220:223]
	ds_read_b128 v[178:181], v192 offset:36960
	ds_read_b128 v[220:223], v192 offset:41568
	s_waitcnt lgkmcnt(5)
	v_mfma_f32_32x32x16_bf16 v[80:95], v[212:215], v[228:231], v[80:95]
	v_mfma_f32_32x32x16_bf16 v[16:31], v[216:219], v[228:231], v[16:31]
	ds_read_b128 v[228:231], v184 offset:96
	s_waitcnt lgkmcnt(5)
	v_mfma_f32_32x32x16_bf16 v[64:79], v[212:215], v[232:235], v[64:79]
	v_mfma_f32_32x32x16_bf16 v[0:15], v[216:219], v[232:235], v[0:15]
	ds_read_b128 v[232:235], v184 offset:4704
	s_setprio 0
	global_load_dwordx4 v[212:215], v[152:153], off offset:512
	global_load_dwordx4 v[216:219], v[156:157], off offset:512
	s_setprio 1
	s_waitcnt lgkmcnt(1)
	v_mfma_f32_32x32x16_bf16 v[112:127], v[178:181], v[228:231], v[112:127]
	v_mfma_f32_32x32x16_bf16 v[48:63], v[220:223], v[228:231], v[48:63]
	s_waitcnt lgkmcnt(0)
	v_mfma_f32_32x32x16_bf16 v[96:111], v[178:181], v[232:235], v[96:111]
	v_mfma_f32_32x32x16_bf16 v[32:47], v[220:223], v[232:235], v[32:47]
	ds_read_b128 v[228:231], v184 offset:9312
	ds_read_b128 v[232:235], v184 offset:13920
	s_waitcnt lgkmcnt(0)
	s_barrier
	s_waitcnt vmcnt(7)
	ds_write_b128 v191, v[172:175]
	s_waitcnt vmcnt(6)
	ds_write_b128 v191, v[224:227] offset:36864
	ds_read_b128 v[172:175], v169
	ds_read_b128 v[224:227], v169 offset:4608
	v_mfma_f32_32x32x16_bf16 v[80:95], v[178:181], v[228:231], v[80:95]
	v_mfma_f32_32x32x16_bf16 v[16:31], v[220:223], v[228:231], v[16:31]
	ds_read_b128 v[228:231], v168
	v_mfma_f32_32x32x16_bf16 v[64:79], v[178:181], v[232:235], v[64:79]
	v_mfma_f32_32x32x16_bf16 v[0:15], v[220:223], v[232:235], v[0:15]
	ds_read_b128 v[232:235], v168 offset:4608
	s_setprio 0
	global_load_dwordx4 v[178:181], v[128:129], off offset:640
	global_load_dwordx4 v[220:223], v[132:133], off offset:640
	s_setprio 1
	s_waitcnt lgkmcnt(1)
	v_mfma_f32_32x32x16_bf16 v[112:127], v[172:175], v[228:231], v[112:127]
	v_mfma_f32_32x32x16_bf16 v[48:63], v[224:227], v[228:231], v[48:63]
	s_waitcnt lgkmcnt(0)
	v_mfma_f32_32x32x16_bf16 v[96:111], v[172:175], v[232:235], v[96:111]
	v_mfma_f32_32x32x16_bf16 v[32:47], v[224:227], v[232:235], v[32:47]
	ds_read_b128 v[228:231], v168 offset:9216
	ds_read_b128 v[232:235], v168 offset:13824
	s_waitcnt vmcnt(7)
	ds_write_b128 v191, v[158:161] offset:9216
	s_waitcnt vmcnt(6)
	ds_write_b128 v191, v[162:165] offset:46080
	ds_read_b128 v[158:161], v169 offset:32
	ds_read_b128 v[162:165], v169 offset:4640
	s_waitcnt lgkmcnt(5)
	v_mfma_f32_32x32x16_bf16 v[80:95], v[172:175], v[228:231], v[80:95]
	v_mfma_f32_32x32x16_bf16 v[16:31], v[224:227], v[228:231], v[16:31]
	ds_read_b128 v[228:231], v168 offset:32
	s_waitcnt lgkmcnt(5)
; template <bool trans>
; DI void gemm_core(const GTile& tl, const GTile& nx, bool has_next  , bool chain  , bool pre, u32x4 (&ra)[4], u32x4 (&rb)[4], char* smem, f32x16 (&acc)[2][4]) {
;     ...
;   const int nk = K / 64;
;   if (!pre) { G_LOAD(0); G_STORE(0); G_LOAD(1); }
;   for (int kt = 0; kt < nk; ++kt) {
;     __syncthreads();
;     G_COMPUTE(kt & 1, kt);
;   }
	v_mfma_f32_32x32x16_bf16 v[64:79], v[172:175], v[232:235], v[64:79]
	v_mfma_f32_32x32x16_bf16 v[0:15], v[224:227], v[232:235], v[0:15]
	ds_read_b128 v[232:235], v168 offset:4640
	s_setprio 0
	global_load_dwordx4 v[172:175], v[136:137], off offset:640
	global_load_dwordx4 v[224:227], v[140:141], off offset:640
	s_setprio 1
	s_waitcnt lgkmcnt(1)
	v_mfma_f32_32x32x16_bf16 v[112:127], v[158:161], v[228:231], v[112:127]
	v_mfma_f32_32x32x16_bf16 v[48:63], v[162:165], v[228:231], v[48:63]
	s_waitcnt lgkmcnt(0)
	v_mfma_f32_32x32x16_bf16 v[96:111], v[158:161], v[232:235], v[96:111]
	v_mfma_f32_32x32x16_bf16 v[32:47], v[162:165], v[232:235], v[32:47]
	ds_read_b128 v[228:231], v168 offset:9248
	ds_read_b128 v[232:235], v168 offset:13856
	s_waitcnt vmcnt(7)
	ds_write_b128 v191, v[200:203] offset:18432
	s_waitcnt vmcnt(6)
	ds_write_b128 v191, v[208:211] offset:55296
	ds_read_b128 v[200:203], v169 offset:64
	ds_read_b128 v[208:211], v169 offset:4672
	s_waitcnt lgkmcnt(5)
	v_mfma_f32_32x32x16_bf16 v[80:95], v[158:161], v[228:231], v[80:95]
	v_mfma_f32_32x32x16_bf16 v[16:31], v[162:165], v[228:231], v[16:31]
	ds_read_b128 v[228:231], v168 offset:64
	s_waitcnt lgkmcnt(5)
	v_mfma_f32_32x32x16_bf16 v[64:79], v[158:161], v[232:235], v[64:79]
	v_mfma_f32_32x32x16_bf16 v[0:15], v[162:165], v[232:235], v[0:15]
	ds_read_b128 v[232:235], v168 offset:4672
	s_setprio 0
	global_load_dwordx4 v[158:161], v[144:145], off offset:640
	global_load_dwordx4 v[162:165], v[148:149], off offset:640
	s_setprio 1
	s_waitcnt lgkmcnt(1)
	v_mfma_f32_32x32x16_bf16 v[112:127], v[200:203], v[228:231], v[112:127]
	v_mfma_f32_32x32x16_bf16 v[48:63], v[208:211], v[228:231], v[48:63]
	s_waitcnt lgkmcnt(0)
	v_mfma_f32_32x32x16_bf16 v[96:111], v[200:203], v[232:235], v[96:111]
	v_mfma_f32_32x32x16_bf16 v[32:47], v[208:211], v[232:235], v[32:47]
	ds_read_b128 v[228:231], v168 offset:9280
	ds_read_b128 v[232:235], v168 offset:13888
	s_waitcnt vmcnt(7)
	ds_write_b128 v191, v[212:215] offset:27648
	s_waitcnt vmcnt(6)
	ds_write_b128 v191, v[216:219] offset:64512
	ds_read_b128 v[212:215], v169 offset:96
	ds_read_b128 v[216:219], v169 offset:4704
	s_waitcnt lgkmcnt(5)
	v_mfma_f32_32x32x16_bf16 v[80:95], v[200:203], v[228:231], v[80:95]
	v_mfma_f32_32x32x16_bf16 v[16:31], v[208:211], v[228:231], v[16:31]
	ds_read_b128 v[228:231], v168 offset:96
	s_waitcnt lgkmcnt(5)
	v_mfma_f32_32x32x16_bf16 v[64:79], v[200:203], v[232:235], v[64:79]
	v_mfma_f32_32x32x16_bf16 v[0:15], v[208:211], v[232:235], v[0:15]
	ds_read_b128 v[232:235], v168 offset:4704
	s_setprio 0
	global_load_dwordx4 v[200:203], v[152:153], off offset:640
	global_load_dwordx4 v[208:211], v[156:157], off offset:640
	s_setprio 1
	s_waitcnt lgkmcnt(1)
	v_mfma_f32_32x32x16_bf16 v[112:127], v[212:215], v[228:231], v[112:127]
	v_mfma_f32_32x32x16_bf16 v[48:63], v[216:219], v[228:231], v[48:63]
	s_waitcnt lgkmcnt(0)
	v_mfma_f32_32x32x16_bf16 v[96:111], v[212:215], v[232:235], v[96:111]
	v_mfma_f32_32x32x16_bf16 v[32:47], v[216:219], v[232:235], v[32:47]
	ds_read_b128 v[228:231], v168 offset:9312
	ds_read_b128 v[232:235], v168 offset:13920
	s_waitcnt lgkmcnt(0)
	s_barrier
	s_waitcnt vmcnt(7)
	ds_write_b128 v195, v[178:181]
	s_waitcnt vmcnt(6)
	ds_write_b128 v196, v[220:223]
	ds_read_b128 v[178:181], v192 offset:36864
	ds_read_b128 v[220:223], v192 offset:41472
	v_mfma_f32_32x32x16_bf16 v[80:95], v[212:215], v[228:231], v[80:95]
	v_mfma_f32_32x32x16_bf16 v[16:31], v[216:219], v[228:231], v[16:31]
	ds_read_b128 v[228:231], v184
	v_mfma_f32_32x32x16_bf16 v[64:79], v[212:215], v[232:235], v[64:79]
	v_mfma_f32_32x32x16_bf16 v[0:15], v[216:219], v[232:235], v[0:15]
	ds_read_b128 v[232:235], v184 offset:4608
	s_setprio 0
	global_load_dwordx4 v[212:215], v[128:129], off offset:768
	global_load_dwordx4 v[216:219], v[132:133], off offset:768
	s_setprio 1
	s_waitcnt lgkmcnt(1)
	v_mfma_f32_32x32x16_bf16 v[112:127], v[178:181], v[228:231], v[112:127]
	v_mfma_f32_32x32x16_bf16 v[48:63], v[220:223], v[228:231], v[48:63]
	s_waitcnt lgkmcnt(0)
	v_mfma_f32_32x32x16_bf16 v[96:111], v[178:181], v[232:235], v[96:111]
	v_mfma_f32_32x32x16_bf16 v[32:47], v[220:223], v[232:235], v[32:47]
	ds_read_b128 v[228:231], v184 offset:9216
	ds_read_b128 v[232:235], v184 offset:13824
	s_waitcnt vmcnt(7)
	ds_write_b128 v194, v[172:175]
	s_waitcnt vmcnt(6)
	ds_write_b128 v193, v[224:227]
	ds_read_b128 v[172:175], v192 offset:36896
	ds_read_b128 v[224:227], v192 offset:41504
	s_waitcnt lgkmcnt(5)
	v_mfma_f32_32x32x16_bf16 v[80:95], v[178:181], v[228:231], v[80:95]
	v_mfma_f32_32x32x16_bf16 v[16:31], v[220:223], v[228:231], v[16:31]
	ds_read_b128 v[228:231], v184 offset:32
	s_waitcnt lgkmcnt(5)
	v_mfma_f32_32x32x16_bf16 v[64:79], v[178:181], v[232:235], v[64:79]
	v_mfma_f32_32x32x16_bf16 v[0:15], v[220:223], v[232:235], v[0:15]
	ds_read_b128 v[232:235], v184 offset:4640
	s_setprio 0
	global_load_dwordx4 v[178:181], v[136:137], off offset:768
	global_load_dwordx4 v[220:223], v[140:141], off offset:768
	s_setprio 1
	s_waitcnt lgkmcnt(1)
	v_mfma_f32_32x32x16_bf16 v[112:127], v[172:175], v[228:231], v[112:127]
	v_mfma_f32_32x32x16_bf16 v[48:63], v[224:227], v[228:231], v[48:63]
	s_waitcnt lgkmcnt(0)
	v_mfma_f32_32x32x16_bf16 v[96:111], v[172:175], v[232:235], v[96:111]
	v_mfma_f32_32x32x16_bf16 v[32:47], v[224:227], v[232:235], v[32:47]
	ds_read_b128 v[228:231], v184 offset:9248
	ds_read_b128 v[232:235], v184 offset:13856
	s_waitcnt vmcnt(7)
	ds_write_b128 v177, v[158:161]
	s_waitcnt vmcnt(6)
	ds_write_b128 v176, v[162:165]
	ds_read_b128 v[158:161], v192 offset:36928
	ds_read_b128 v[162:165], v192 offset:41536
	s_waitcnt lgkmcnt(5)
; template <bool trans>
; DI void gemm_core(const GTile& tl, const GTile& nx, bool has_next  , bool chain  , bool pre, u32x4 (&ra)[4], u32x4 (&rb)[4], char* smem, f32x16 (&acc)[2][4]) {
;     ...
;   const int nk = K / 64;
;   if (!pre) { G_LOAD(0); G_STORE(0); G_LOAD(1); }
;   for (int kt = 0; kt < nk; ++kt) {
;     __syncthreads();
;     G_COMPUTE(kt & 1, kt);
;   }
	v_mfma_f32_32x32x16_bf16 v[80:95], v[172:175], v[228:231], v[80:95]
	v_mfma_f32_32x32x16_bf16 v[16:31], v[224:227], v[228:231], v[16:31]
	ds_read_b128 v[228:231], v184 offset:64
	s_waitcnt lgkmcnt(5)
	v_mfma_f32_32x32x16_bf16 v[64:79], v[172:175], v[232:235], v[64:79]
	v_mfma_f32_32x32x16_bf16 v[0:15], v[224:227], v[232:235], v[0:15]
	ds_read_b128 v[232:235], v184 offset:4672
	s_setprio 0
	global_load_dwordx4 v[172:175], v[144:145], off offset:768
	global_load_dwordx4 v[224:227], v[148:149], off offset:768
	s_setprio 1
	s_waitcnt lgkmcnt(1)
	v_mfma_f32_32x32x16_bf16 v[112:127], v[158:161], v[228:231], v[112:127]
	v_mfma_f32_32x32x16_bf16 v[48:63], v[162:165], v[228:231], v[48:63]
	s_waitcnt lgkmcnt(0)
	v_mfma_f32_32x32x16_bf16 v[96:111], v[158:161], v[232:235], v[96:111]
	v_mfma_f32_32x32x16_bf16 v[32:47], v[162:165], v[232:235], v[32:47]
	ds_read_b128 v[228:231], v184 offset:9280
	ds_read_b128 v[232:235], v184 offset:13888
	s_waitcnt vmcnt(7)
	ds_write_b128 v171, v[200:203]
	s_waitcnt vmcnt(6)
	ds_write_b128 v170, v[208:211]
	ds_read_b128 v[200:203], v192 offset:36960
	ds_read_b128 v[208:211], v192 offset:41568
	s_waitcnt lgkmcnt(5)
	v_mfma_f32_32x32x16_bf16 v[80:95], v[158:161], v[228:231], v[80:95]
	v_mfma_f32_32x32x16_bf16 v[16:31], v[162:165], v[228:231], v[16:31]
	ds_read_b128 v[228:231], v184 offset:96
	s_waitcnt lgkmcnt(5)
	v_mfma_f32_32x32x16_bf16 v[64:79], v[158:161], v[232:235], v[64:79]
	v_mfma_f32_32x32x16_bf16 v[0:15], v[162:165], v[232:235], v[0:15]
	ds_read_b128 v[232:235], v184 offset:4704
	s_setprio 0
	global_load_dwordx4 v[158:161], v[152:153], off offset:768
	global_load_dwordx4 v[162:165], v[156:157], off offset:768
	s_setprio 1
	s_waitcnt lgkmcnt(1)
	v_mfma_f32_32x32x16_bf16 v[112:127], v[200:203], v[228:231], v[112:127]
	v_mfma_f32_32x32x16_bf16 v[48:63], v[208:211], v[228:231], v[48:63]
	s_waitcnt lgkmcnt(0)
	v_mfma_f32_32x32x16_bf16 v[96:111], v[200:203], v[232:235], v[96:111]
	v_mfma_f32_32x32x16_bf16 v[32:47], v[208:211], v[232:235], v[32:47]
	ds_read_b128 v[228:231], v184 offset:9312
	ds_read_b128 v[232:235], v184 offset:13920
	s_waitcnt lgkmcnt(0)
	s_barrier
	s_waitcnt vmcnt(7)
	ds_write_b128 v191, v[212:215]
	s_waitcnt vmcnt(6)
	ds_write_b128 v191, v[216:219] offset:36864
	ds_read_b128 v[212:215], v169
	ds_read_b128 v[216:219], v169 offset:4608
	v_mfma_f32_32x32x16_bf16 v[80:95], v[200:203], v[228:231], v[80:95]
	v_mfma_f32_32x32x16_bf16 v[16:31], v[208:211], v[228:231], v[16:31]
	ds_read_b128 v[228:231], v168
	v_mfma_f32_32x32x16_bf16 v[64:79], v[200:203], v[232:235], v[64:79]
	v_mfma_f32_32x32x16_bf16 v[0:15], v[208:211], v[232:235], v[0:15]
	ds_read_b128 v[232:235], v168 offset:4608
	s_setprio 0
	global_load_dwordx4 v[200:203], v[128:129], off offset:896
	global_load_dwordx4 v[208:211], v[132:133], off offset:896
	s_setprio 1
	s_waitcnt lgkmcnt(1)
	v_mfma_f32_32x32x16_bf16 v[112:127], v[212:215], v[228:231], v[112:127]
	v_mfma_f32_32x32x16_bf16 v[48:63], v[216:219], v[228:231], v[48:63]
	s_waitcnt lgkmcnt(0)
	v_mfma_f32_32x32x16_bf16 v[96:111], v[212:215], v[232:235], v[96:111]
	v_mfma_f32_32x32x16_bf16 v[32:47], v[216:219], v[232:235], v[32:47]
	ds_read_b128 v[228:231], v168 offset:9216
	ds_read_b128 v[232:235], v168 offset:13824
	s_waitcnt vmcnt(7)
	ds_write_b128 v191, v[178:181] offset:9216
	s_waitcnt vmcnt(6)
	ds_write_b128 v191, v[220:223] offset:46080
	ds_read_b128 v[178:181], v169 offset:32
	ds_read_b128 v[220:223], v169 offset:4640
	s_waitcnt lgkmcnt(5)
	v_mfma_f32_32x32x16_bf16 v[80:95], v[212:215], v[228:231], v[80:95]
	v_mfma_f32_32x32x16_bf16 v[16:31], v[216:219], v[228:231], v[16:31]
	ds_read_b128 v[228:231], v168 offset:32
	s_waitcnt lgkmcnt(5)
	v_mfma_f32_32x32x16_bf16 v[64:79], v[212:215], v[232:235], v[64:79]
	v_mfma_f32_32x32x16_bf16 v[0:15], v[216:219], v[232:235], v[0:15]
	ds_read_b128 v[232:235], v168 offset:4640
	s_setprio 0
	global_load_dwordx4 v[212:215], v[136:137], off offset:896
	global_load_dwordx4 v[216:219], v[140:141], off offset:896
	s_setprio 1
	s_waitcnt lgkmcnt(1)
	v_mfma_f32_32x32x16_bf16 v[112:127], v[178:181], v[228:231], v[112:127]
	v_mfma_f32_32x32x16_bf16 v[48:63], v[220:223], v[228:231], v[48:63]
	s_waitcnt lgkmcnt(0)
	v_mfma_f32_32x32x16_bf16 v[96:111], v[178:181], v[232:235], v[96:111]
	v_mfma_f32_32x32x16_bf16 v[32:47], v[220:223], v[232:235], v[32:47]
	ds_read_b128 v[228:231], v168 offset:9248
	ds_read_b128 v[232:235], v168 offset:13856
	s_waitcnt vmcnt(7)
	ds_write_b128 v191, v[172:175] offset:18432
	s_waitcnt vmcnt(6)
	ds_write_b128 v191, v[224:227] offset:55296
	ds_read_b128 v[172:175], v169 offset:64
	ds_read_b128 v[224:227], v169 offset:4672
	s_waitcnt lgkmcnt(5)
	v_mfma_f32_32x32x16_bf16 v[80:95], v[178:181], v[228:231], v[80:95]
	v_mfma_f32_32x32x16_bf16 v[16:31], v[220:223], v[228:231], v[16:31]
	ds_read_b128 v[228:231], v168 offset:64
	s_waitcnt lgkmcnt(5)
	v_mfma_f32_32x32x16_bf16 v[64:79], v[178:181], v[232:235], v[64:79]
	v_mfma_f32_32x32x16_bf16 v[0:15], v[220:223], v[232:235], v[0:15]
	ds_read_b128 v[232:235], v168 offset:4672
	s_setprio 0
	global_load_dwordx4 v[178:181], v[144:145], off offset:896
	global_load_dwordx4 v[220:223], v[148:149], off offset:896
	s_setprio 1
	s_waitcnt lgkmcnt(1)
	v_mfma_f32_32x32x16_bf16 v[112:127], v[172:175], v[228:231], v[112:127]
	v_mfma_f32_32x32x16_bf16 v[48:63], v[224:227], v[228:231], v[48:63]
	s_waitcnt lgkmcnt(0)
	v_mfma_f32_32x32x16_bf16 v[96:111], v[172:175], v[232:235], v[96:111]
	v_mfma_f32_32x32x16_bf16 v[32:47], v[224:227], v[232:235], v[32:47]
	ds_read_b128 v[228:231], v168 offset:9280
	ds_read_b128 v[232:235], v168 offset:13888
	s_waitcnt vmcnt(7)
	ds_write_b128 v191, v[158:161] offset:27648
	s_waitcnt vmcnt(6)
	ds_write_b128 v191, v[162:165] offset:64512
	ds_read_b128 v[158:161], v169 offset:96
	ds_read_b128 v[162:165], v169 offset:4704
	s_waitcnt lgkmcnt(5)
	v_mfma_f32_32x32x16_bf16 v[80:95], v[172:175], v[228:231], v[80:95]
	v_mfma_f32_32x32x16_bf16 v[16:31], v[224:227], v[228:231], v[16:31]
	ds_read_b128 v[228:231], v168 offset:96
	s_waitcnt lgkmcnt(5)
	v_mfma_f32_32x32x16_bf16 v[64:79], v[172:175], v[232:235], v[64:79]
	v_mfma_f32_32x32x16_bf16 v[0:15], v[224:227], v[232:235], v[0:15]
	ds_read_b128 v[232:235], v168 offset:4704
	s_setprio 0
	global_load_dwordx4 v[172:175], v[152:153], off offset:896
	global_load_dwordx4 v[224:227], v[156:157], off offset:896
	s_setprio 1
	s_waitcnt lgkmcnt(1)
	v_mfma_f32_32x32x16_bf16 v[112:127], v[158:161], v[228:231], v[112:127]
	v_mfma_f32_32x32x16_bf16 v[48:63], v[162:165], v[228:231], v[48:63]
	s_waitcnt lgkmcnt(0)
	v_mfma_f32_32x32x16_bf16 v[96:111], v[158:161], v[232:235], v[96:111]
	v_mfma_f32_32x32x16_bf16 v[32:47], v[162:165], v[232:235], v[32:47]
	ds_read_b128 v[228:231], v168 offset:9312
	ds_read_b128 v[232:235], v168 offset:13920
	s_waitcnt lgkmcnt(0)
	s_barrier
; template <bool trans>
; DI void gemm_core(const GTile& tl, const GTile& nx, bool has_next  , bool chain  , bool pre, u32x4 (&ra)[4], u32x4 (&rb)[4], char* smem, f32x16 (&acc)[2][4]) {
;     ...
;   const int nk = K / 64;
;   if (!pre) { G_LOAD(0); G_STORE(0); G_LOAD(1); }
;   for (int kt = 0; kt < nk; ++kt) {
;     __syncthreads();
;     G_COMPUTE(kt & 1, kt);
;   }
	s_waitcnt vmcnt(7)
	ds_write_b128 v195, v[200:203]
	s_waitcnt vmcnt(6)
	ds_write_b128 v196, v[208:211]
	ds_read_b128 v[200:203], v192 offset:36864
	ds_read_b128 v[208:211], v192 offset:41472
	v_mfma_f32_32x32x16_bf16 v[80:95], v[158:161], v[228:231], v[80:95]
	v_mfma_f32_32x32x16_bf16 v[16:31], v[162:165], v[228:231], v[16:31]
	ds_read_b128 v[228:231], v184
	v_mfma_f32_32x32x16_bf16 v[64:79], v[158:161], v[232:235], v[64:79]
	v_mfma_f32_32x32x16_bf16 v[0:15], v[162:165], v[232:235], v[0:15]
	ds_read_b128 v[232:235], v184 offset:4608
	s_setprio 0
	global_load_dwordx4 v[158:161], v[128:129], off offset:1024
	global_load_dwordx4 v[162:165], v[132:133], off offset:1024
	s_setprio 1
	s_waitcnt lgkmcnt(1)
	v_mfma_f32_32x32x16_bf16 v[112:127], v[200:203], v[228:231], v[112:127]
	v_mfma_f32_32x32x16_bf16 v[48:63], v[208:211], v[228:231], v[48:63]
	s_waitcnt lgkmcnt(0)
	v_mfma_f32_32x32x16_bf16 v[96:111], v[200:203], v[232:235], v[96:111]
	v_mfma_f32_32x32x16_bf16 v[32:47], v[208:211], v[232:235], v[32:47]
	ds_read_b128 v[228:231], v184 offset:9216
	ds_read_b128 v[232:235], v184 offset:13824
	s_waitcnt vmcnt(7)
	ds_write_b128 v194, v[212:215]
	s_waitcnt vmcnt(6)
	ds_write_b128 v193, v[216:219]
	ds_read_b128 v[212:215], v192 offset:36896
	ds_read_b128 v[216:219], v192 offset:41504
	s_waitcnt lgkmcnt(5)
	v_mfma_f32_32x32x16_bf16 v[80:95], v[200:203], v[228:231], v[80:95]
	v_mfma_f32_32x32x16_bf16 v[16:31], v[208:211], v[228:231], v[16:31]
	ds_read_b128 v[228:231], v184 offset:32
	s_waitcnt lgkmcnt(5)
	v_mfma_f32_32x32x16_bf16 v[64:79], v[200:203], v[232:235], v[64:79]
	v_mfma_f32_32x32x16_bf16 v[0:15], v[208:211], v[232:235], v[0:15]
	ds_read_b128 v[232:235], v184 offset:4640
	s_setprio 0
	global_load_dwordx4 v[200:203], v[136:137], off offset:1024
	global_load_dwordx4 v[208:211], v[140:141], off offset:1024
	s_setprio 1
	s_waitcnt lgkmcnt(1)
	v_mfma_f32_32x32x16_bf16 v[112:127], v[212:215], v[228:231], v[112:127]
	v_mfma_f32_32x32x16_bf16 v[48:63], v[216:219], v[228:231], v[48:63]
	s_waitcnt lgkmcnt(0)
	v_mfma_f32_32x32x16_bf16 v[96:111], v[212:215], v[232:235], v[96:111]
	v_mfma_f32_32x32x16_bf16 v[32:47], v[216:219], v[232:235], v[32:47]
	ds_read_b128 v[228:231], v184 offset:9248
	ds_read_b128 v[232:235], v184 offset:13856
	s_waitcnt vmcnt(7)
	ds_write_b128 v177, v[178:181]
	s_waitcnt vmcnt(6)
	ds_write_b128 v176, v[220:223]
	ds_read_b128 v[178:181], v192 offset:36928
	ds_read_b128 v[220:223], v192 offset:41536
	s_waitcnt lgkmcnt(5)
	v_mfma_f32_32x32x16_bf16 v[80:95], v[212:215], v[228:231], v[80:95]
	v_mfma_f32_32x32x16_bf16 v[16:31], v[216:219], v[228:231], v[16:31]
	ds_read_b128 v[228:231], v184 offset:64
	s_waitcnt lgkmcnt(5)
	v_mfma_f32_32x32x16_bf16 v[64:79], v[212:215], v[232:235], v[64:79]
	v_mfma_f32_32x32x16_bf16 v[0:15], v[216:219], v[232:235], v[0:15]
	ds_read_b128 v[232:235], v184 offset:4672
	s_setprio 0
	global_load_dwordx4 v[212:215], v[144:145], off offset:1024
	global_load_dwordx4 v[216:219], v[148:149], off offset:1024
	s_setprio 1
	s_waitcnt lgkmcnt(1)
	v_mfma_f32_32x32x16_bf16 v[112:127], v[178:181], v[228:231], v[112:127]
	v_mfma_f32_32x32x16_bf16 v[48:63], v[220:223], v[228:231], v[48:63]
	s_waitcnt lgkmcnt(0)
	v_mfma_f32_32x32x16_bf16 v[96:111], v[178:181], v[232:235], v[96:111]
	v_mfma_f32_32x32x16_bf16 v[32:47], v[220:223], v[232:235], v[32:47]
	ds_read_b128 v[228:231], v184 offset:9280
	ds_read_b128 v[232:235], v184 offset:13888
	s_waitcnt vmcnt(7)
	ds_write_b128 v171, v[172:175]
	s_waitcnt vmcnt(6)
	ds_write_b128 v170, v[224:227]
	ds_read_b128 v[172:175], v192 offset:36960
	ds_read_b128 v[224:227], v192 offset:41568
	s_waitcnt lgkmcnt(5)
	v_mfma_f32_32x32x16_bf16 v[80:95], v[178:181], v[228:231], v[80:95]
	v_mfma_f32_32x32x16_bf16 v[16:31], v[220:223], v[228:231], v[16:31]
	ds_read_b128 v[228:231], v184 offset:96
	s_waitcnt lgkmcnt(5)
	v_mfma_f32_32x32x16_bf16 v[64:79], v[178:181], v[232:235], v[64:79]
	v_mfma_f32_32x32x16_bf16 v[0:15], v[220:223], v[232:235], v[0:15]
	ds_read_b128 v[232:235], v184 offset:4704
	s_setprio 0
	global_load_dwordx4 v[178:181], v[152:153], off offset:1024
	global_load_dwordx4 v[220:223], v[156:157], off offset:1024
	s_setprio 1
	s_waitcnt lgkmcnt(1)
	v_mfma_f32_32x32x16_bf16 v[112:127], v[172:175], v[228:231], v[112:127]
	v_mfma_f32_32x32x16_bf16 v[48:63], v[224:227], v[228:231], v[48:63]
	s_waitcnt lgkmcnt(0)
	v_mfma_f32_32x32x16_bf16 v[96:111], v[172:175], v[232:235], v[96:111]
	v_mfma_f32_32x32x16_bf16 v[32:47], v[224:227], v[232:235], v[32:47]
	ds_read_b128 v[228:231], v184 offset:9312
	ds_read_b128 v[232:235], v184 offset:13920
	s_waitcnt lgkmcnt(0)
	s_barrier
; template <bool trans>
; DI void gemm_core(const GTile& tl, const GTile& nx, bool has_next  , bool chain  , bool pre, u32x4 (&ra)[4], u32x4 (&rb)[4], char* smem, f32x16 (&acc)[2][4]) {
;     ...
;   const int nk = K / 64;
;   if (!pre) { G_LOAD(0); G_STORE(0); G_LOAD(1); }
;   for (int kt = 0; kt < nk; ++kt) {
;     __syncthreads();
;     G_COMPUTE(kt & 1, kt);
;   }
	s_waitcnt vmcnt(7)
	ds_write_b128 v191, v[158:161]
	s_waitcnt vmcnt(6)
	ds_write_b128 v191, v[162:165] offset:36864
	ds_read_b128 v[158:161], v169
	ds_read_b128 v[162:165], v169 offset:4608
	v_mfma_f32_32x32x16_bf16 v[80:95], v[172:175], v[228:231], v[80:95]
	v_mfma_f32_32x32x16_bf16 v[16:31], v[224:227], v[228:231], v[16:31]
	ds_read_b128 v[228:231], v168
	v_mfma_f32_32x32x16_bf16 v[64:79], v[172:175], v[232:235], v[64:79]
	v_mfma_f32_32x32x16_bf16 v[0:15], v[224:227], v[232:235], v[0:15]
	ds_read_b128 v[232:235], v168 offset:4608
	s_setprio 0
	global_load_dwordx4 v[172:175], v[128:129], off offset:1152
	global_load_dwordx4 v[224:227], v[132:133], off offset:1152
	s_setprio 1
	s_waitcnt lgkmcnt(1)
	v_mfma_f32_32x32x16_bf16 v[112:127], v[158:161], v[228:231], v[112:127]
	v_mfma_f32_32x32x16_bf16 v[48:63], v[162:165], v[228:231], v[48:63]
	s_waitcnt lgkmcnt(0)
	v_mfma_f32_32x32x16_bf16 v[96:111], v[158:161], v[232:235], v[96:111]
	v_mfma_f32_32x32x16_bf16 v[32:47], v[162:165], v[232:235], v[32:47]
	ds_read_b128 v[228:231], v168 offset:9216
	ds_read_b128 v[232:235], v168 offset:13824
	s_waitcnt vmcnt(7)
	ds_write_b128 v191, v[200:203] offset:9216
	s_waitcnt vmcnt(6)
	ds_write_b128 v191, v[208:211] offset:46080
	ds_read_b128 v[200:203], v169 offset:32
	ds_read_b128 v[208:211], v169 offset:4640
	s_waitcnt lgkmcnt(5)
	v_mfma_f32_32x32x16_bf16 v[80:95], v[158:161], v[228:231], v[80:95]
	v_mfma_f32_32x32x16_bf16 v[16:31], v[162:165], v[228:231], v[16:31]
	ds_read_b128 v[228:231], v168 offset:32
	s_waitcnt lgkmcnt(5)
	v_mfma_f32_32x32x16_bf16 v[64:79], v[158:161], v[232:235], v[64:79]
	v_mfma_f32_32x32x16_bf16 v[0:15], v[162:165], v[232:235], v[0:15]
	ds_read_b128 v[232:235], v168 offset:4640
	s_setprio 0
	global_load_dwordx4 v[158:161], v[136:137], off offset:1152
	global_load_dwordx4 v[162:165], v[140:141], off offset:1152
	s_setprio 1
	s_waitcnt lgkmcnt(1)
	v_mfma_f32_32x32x16_bf16 v[112:127], v[200:203], v[228:231], v[112:127]
	v_mfma_f32_32x32x16_bf16 v[48:63], v[208:211], v[228:231], v[48:63]
	s_waitcnt lgkmcnt(0)
	v_mfma_f32_32x32x16_bf16 v[96:111], v[200:203], v[232:235], v[96:111]
	v_mfma_f32_32x32x16_bf16 v[32:47], v[208:211], v[232:235], v[32:47]
	ds_read_b128 v[228:231], v168 offset:9248
	ds_read_b128 v[232:235], v168 offset:13856
	s_waitcnt vmcnt(7)
	ds_write_b128 v191, v[212:215] offset:18432
	s_waitcnt vmcnt(6)
	ds_write_b128 v191, v[216:219] offset:55296
	ds_read_b128 v[212:215], v169 offset:64
	ds_read_b128 v[216:219], v169 offset:4672
	s_waitcnt lgkmcnt(5)
	v_mfma_f32_32x32x16_bf16 v[80:95], v[200:203], v[228:231], v[80:95]
	v_mfma_f32_32x32x16_bf16 v[16:31], v[208:211], v[228:231], v[16:31]
	ds_read_b128 v[228:231], v168 offset:64
	s_waitcnt lgkmcnt(5)
	v_mfma_f32_32x32x16_bf16 v[64:79], v[200:203], v[232:235], v[64:79]
	v_mfma_f32_32x32x16_bf16 v[0:15], v[208:211], v[232:235], v[0:15]
	ds_read_b128 v[232:235], v168 offset:4672
	s_setprio 0
	global_load_dwordx4 v[200:203], v[144:145], off offset:1152
	global_load_dwordx4 v[208:211], v[148:149], off offset:1152
	s_setprio 1
	s_waitcnt lgkmcnt(1)
	v_mfma_f32_32x32x16_bf16 v[112:127], v[212:215], v[228:231], v[112:127]
	v_mfma_f32_32x32x16_bf16 v[48:63], v[216:219], v[228:231], v[48:63]
	s_waitcnt lgkmcnt(0)
	v_mfma_f32_32x32x16_bf16 v[96:111], v[212:215], v[232:235], v[96:111]
	v_mfma_f32_32x32x16_bf16 v[32:47], v[216:219], v[232:235], v[32:47]
	ds_read_b128 v[228:231], v168 offset:9280
	ds_read_b128 v[232:235], v168 offset:13888
	s_waitcnt vmcnt(7)
	ds_write_b128 v191, v[178:181] offset:27648
	s_waitcnt vmcnt(6)
	ds_write_b128 v191, v[220:223] offset:64512
	ds_read_b128 v[178:181], v169 offset:96
	ds_read_b128 v[220:223], v169 offset:4704
	s_waitcnt lgkmcnt(5)
	v_mfma_f32_32x32x16_bf16 v[80:95], v[212:215], v[228:231], v[80:95]
	v_mfma_f32_32x32x16_bf16 v[16:31], v[216:219], v[228:231], v[16:31]
	ds_read_b128 v[228:231], v168 offset:96
	s_waitcnt lgkmcnt(5)
	v_mfma_f32_32x32x16_bf16 v[64:79], v[212:215], v[232:235], v[64:79]
	v_mfma_f32_32x32x16_bf16 v[0:15], v[216:219], v[232:235], v[0:15]
	ds_read_b128 v[232:235], v168 offset:4704
	s_setprio 0
	global_load_dwordx4 v[212:215], v[152:153], off offset:1152
	global_load_dwordx4 v[216:219], v[156:157], off offset:1152
	s_setprio 1
	s_waitcnt lgkmcnt(1)
	v_mfma_f32_32x32x16_bf16 v[112:127], v[178:181], v[228:231], v[112:127]
	v_mfma_f32_32x32x16_bf16 v[48:63], v[220:223], v[228:231], v[48:63]
	s_waitcnt lgkmcnt(0)
	v_mfma_f32_32x32x16_bf16 v[96:111], v[178:181], v[232:235], v[96:111]
	v_mfma_f32_32x32x16_bf16 v[32:47], v[220:223], v[232:235], v[32:47]
	ds_read_b128 v[228:231], v168 offset:9312
	ds_read_b128 v[232:235], v168 offset:13920
	s_waitcnt lgkmcnt(0)
	s_barrier
; template <bool trans>
; DI void gemm_core(const GTile& tl, const GTile& nx, bool has_next  , bool chain  , bool pre, u32x4 (&ra)[4], u32x4 (&rb)[4], char* smem, f32x16 (&acc)[2][4]) {
;     ...
;   const int nk = K / 64;
;   if (!pre) { G_LOAD(0); G_STORE(0); G_LOAD(1); }
;   for (int kt = 0; kt < nk; ++kt) {
;     __syncthreads();
;     G_COMPUTE(kt & 1, kt);
;   }
	s_waitcnt vmcnt(7)
	ds_write_b128 v195, v[172:175]
	s_waitcnt vmcnt(6)
	ds_write_b128 v196, v[224:227]
	ds_read_b128 v[172:175], v192 offset:36864
	ds_read_b128 v[224:227], v192 offset:41472
	v_mfma_f32_32x32x16_bf16 v[80:95], v[178:181], v[228:231], v[80:95]
	v_mfma_f32_32x32x16_bf16 v[16:31], v[220:223], v[228:231], v[16:31]
	ds_read_b128 v[228:231], v184
	v_mfma_f32_32x32x16_bf16 v[64:79], v[178:181], v[232:235], v[64:79]
	v_mfma_f32_32x32x16_bf16 v[0:15], v[220:223], v[232:235], v[0:15]
	ds_read_b128 v[232:235], v184 offset:4608
	s_setprio 0
	global_load_dwordx4 v[178:181], v[128:129], off offset:1280
	global_load_dwordx4 v[220:223], v[132:133], off offset:1280
	s_setprio 1
	s_waitcnt lgkmcnt(1)
	v_mfma_f32_32x32x16_bf16 v[112:127], v[172:175], v[228:231], v[112:127]
	v_mfma_f32_32x32x16_bf16 v[48:63], v[224:227], v[228:231], v[48:63]
	s_waitcnt lgkmcnt(0)
	v_mfma_f32_32x32x16_bf16 v[96:111], v[172:175], v[232:235], v[96:111]
	v_mfma_f32_32x32x16_bf16 v[32:47], v[224:227], v[232:235], v[32:47]
	ds_read_b128 v[228:231], v184 offset:9216
	ds_read_b128 v[232:235], v184 offset:13824
	s_waitcnt vmcnt(7)
	ds_write_b128 v194, v[158:161]
	s_waitcnt vmcnt(6)
	ds_write_b128 v193, v[162:165]
	ds_read_b128 v[158:161], v192 offset:36896
	ds_read_b128 v[162:165], v192 offset:41504
	s_waitcnt lgkmcnt(5)
	v_mfma_f32_32x32x16_bf16 v[80:95], v[172:175], v[228:231], v[80:95]
	v_mfma_f32_32x32x16_bf16 v[16:31], v[224:227], v[228:231], v[16:31]
	ds_read_b128 v[228:231], v184 offset:32
	s_waitcnt lgkmcnt(5)
	v_mfma_f32_32x32x16_bf16 v[64:79], v[172:175], v[232:235], v[64:79]
	v_mfma_f32_32x32x16_bf16 v[0:15], v[224:227], v[232:235], v[0:15]
	ds_read_b128 v[232:235], v184 offset:4640
	s_setprio 0
	global_load_dwordx4 v[172:175], v[136:137], off offset:1280
	global_load_dwordx4 v[224:227], v[140:141], off offset:1280
	s_setprio 1
	s_waitcnt lgkmcnt(1)
	v_mfma_f32_32x32x16_bf16 v[112:127], v[158:161], v[228:231], v[112:127]
	v_mfma_f32_32x32x16_bf16 v[48:63], v[162:165], v[228:231], v[48:63]
	s_waitcnt lgkmcnt(0)
	v_mfma_f32_32x32x16_bf16 v[96:111], v[158:161], v[232:235], v[96:111]
	v_mfma_f32_32x32x16_bf16 v[32:47], v[162:165], v[232:235], v[32:47]
	ds_read_b128 v[228:231], v184 offset:9248
	ds_read_b128 v[232:235], v184 offset:13856
	s_waitcnt vmcnt(7)
	ds_write_b128 v177, v[200:203]
	s_waitcnt vmcnt(6)
	ds_write_b128 v176, v[208:211]
	ds_read_b128 v[200:203], v192 offset:36928
	ds_read_b128 v[208:211], v192 offset:41536
	s_waitcnt lgkmcnt(5)
	v_mfma_f32_32x32x16_bf16 v[80:95], v[158:161], v[228:231], v[80:95]
	v_mfma_f32_32x32x16_bf16 v[16:31], v[162:165], v[228:231], v[16:31]
	ds_read_b128 v[228:231], v184 offset:64
	s_waitcnt lgkmcnt(5)
	v_mfma_f32_32x32x16_bf16 v[64:79], v[158:161], v[232:235], v[64:79]
	v_mfma_f32_32x32x16_bf16 v[0:15], v[162:165], v[232:235], v[0:15]
	ds_read_b128 v[232:235], v184 offset:4672
	s_setprio 0
	global_load_dwordx4 v[158:161], v[144:145], off offset:1280
	global_load_dwordx4 v[162:165], v[148:149], off offset:1280
	s_setprio 1
	s_waitcnt lgkmcnt(1)
	v_mfma_f32_32x32x16_bf16 v[112:127], v[200:203], v[228:231], v[112:127]
	v_mfma_f32_32x32x16_bf16 v[48:63], v[208:211], v[228:231], v[48:63]
	s_waitcnt lgkmcnt(0)
	v_mfma_f32_32x32x16_bf16 v[96:111], v[200:203], v[232:235], v[96:111]
	v_mfma_f32_32x32x16_bf16 v[32:47], v[208:211], v[232:235], v[32:47]
	ds_read_b128 v[228:231], v184 offset:9280
	ds_read_b128 v[232:235], v184 offset:13888
	s_waitcnt vmcnt(7)
	ds_write_b128 v171, v[212:215]
	s_waitcnt vmcnt(6)
	ds_write_b128 v170, v[216:219]
	ds_read_b128 v[212:215], v192 offset:36960
	ds_read_b128 v[216:219], v192 offset:41568
	s_waitcnt lgkmcnt(5)
	v_mfma_f32_32x32x16_bf16 v[80:95], v[200:203], v[228:231], v[80:95]
	v_mfma_f32_32x32x16_bf16 v[16:31], v[208:211], v[228:231], v[16:31]
	ds_read_b128 v[228:231], v184 offset:96
	s_waitcnt lgkmcnt(5)
	v_mfma_f32_32x32x16_bf16 v[64:79], v[200:203], v[232:235], v[64:79]
	v_mfma_f32_32x32x16_bf16 v[0:15], v[208:211], v[232:235], v[0:15]
	ds_read_b128 v[232:235], v184 offset:4704
	s_setprio 0
	global_load_dwordx4 v[200:203], v[152:153], off offset:1280
	global_load_dwordx4 v[208:211], v[156:157], off offset:1280
	s_setprio 1
	s_waitcnt lgkmcnt(1)
	v_mfma_f32_32x32x16_bf16 v[112:127], v[212:215], v[228:231], v[112:127]
	v_mfma_f32_32x32x16_bf16 v[48:63], v[216:219], v[228:231], v[48:63]
	s_waitcnt lgkmcnt(0)
	v_mfma_f32_32x32x16_bf16 v[96:111], v[212:215], v[232:235], v[96:111]
	v_mfma_f32_32x32x16_bf16 v[32:47], v[216:219], v[232:235], v[32:47]
	ds_read_b128 v[228:231], v184 offset:9312
	ds_read_b128 v[232:235], v184 offset:13920
	s_waitcnt lgkmcnt(0)
	s_barrier
; template <bool trans>
; DI void gemm_core(const GTile& tl, const GTile& nx, bool has_next  , bool chain  , bool pre, u32x4 (&ra)[4], u32x4 (&rb)[4], char* smem, f32x16 (&acc)[2][4]) {
;     ...
;   const int nk = K / 64;
;   if (!pre) { G_LOAD(0); G_STORE(0); G_LOAD(1); }
;   for (int kt = 0; kt < nk; ++kt) {
;     __syncthreads();
;     G_COMPUTE(kt & 1, kt);
;   }
	s_waitcnt vmcnt(7)
	ds_write_b128 v191, v[178:181]
	s_waitcnt vmcnt(6)
	ds_write_b128 v191, v[220:223] offset:36864
	ds_read_b128 v[178:181], v169
	ds_read_b128 v[220:223], v169 offset:4608
	v_mfma_f32_32x32x16_bf16 v[80:95], v[212:215], v[228:231], v[80:95]
	v_mfma_f32_32x32x16_bf16 v[16:31], v[216:219], v[228:231], v[16:31]
	ds_read_b128 v[228:231], v168
	v_mfma_f32_32x32x16_bf16 v[64:79], v[212:215], v[232:235], v[64:79]
	v_mfma_f32_32x32x16_bf16 v[0:15], v[216:219], v[232:235], v[0:15]
	ds_read_b128 v[232:235], v168 offset:4608
	s_setprio 0
	global_load_dwordx4 v[212:215], v[128:129], off offset:1408
	global_load_dwordx4 v[216:219], v[132:133], off offset:1408
	s_setprio 1
	s_waitcnt lgkmcnt(1)
	v_mfma_f32_32x32x16_bf16 v[112:127], v[178:181], v[228:231], v[112:127]
	v_mfma_f32_32x32x16_bf16 v[48:63], v[220:223], v[228:231], v[48:63]
	s_waitcnt lgkmcnt(0)
	v_mfma_f32_32x32x16_bf16 v[96:111], v[178:181], v[232:235], v[96:111]
	v_mfma_f32_32x32x16_bf16 v[32:47], v[220:223], v[232:235], v[32:47]
	ds_read_b128 v[228:231], v168 offset:9216
	ds_read_b128 v[232:235], v168 offset:13824
	s_waitcnt vmcnt(7)
	ds_write_b128 v191, v[172:175] offset:9216
	s_waitcnt vmcnt(6)
	ds_write_b128 v191, v[224:227] offset:46080
	ds_read_b128 v[172:175], v169 offset:32
	ds_read_b128 v[224:227], v169 offset:4640
	s_waitcnt lgkmcnt(5)
	v_mfma_f32_32x32x16_bf16 v[80:95], v[178:181], v[228:231], v[80:95]
	v_mfma_f32_32x32x16_bf16 v[16:31], v[220:223], v[228:231], v[16:31]
	ds_read_b128 v[228:231], v168 offset:32
	s_waitcnt lgkmcnt(5)
	v_mfma_f32_32x32x16_bf16 v[64:79], v[178:181], v[232:235], v[64:79]
	v_mfma_f32_32x32x16_bf16 v[0:15], v[220:223], v[232:235], v[0:15]
	ds_read_b128 v[232:235], v168 offset:4640
	s_setprio 0
	global_load_dwordx4 v[178:181], v[136:137], off offset:1408
	global_load_dwordx4 v[220:223], v[140:141], off offset:1408
	s_setprio 1
	s_waitcnt lgkmcnt(1)
	v_mfma_f32_32x32x16_bf16 v[112:127], v[172:175], v[228:231], v[112:127]
	v_mfma_f32_32x32x16_bf16 v[48:63], v[224:227], v[228:231], v[48:63]
	s_waitcnt lgkmcnt(0)
	v_mfma_f32_32x32x16_bf16 v[96:111], v[172:175], v[232:235], v[96:111]
	v_mfma_f32_32x32x16_bf16 v[32:47], v[224:227], v[232:235], v[32:47]
	ds_read_b128 v[228:231], v168 offset:9248
	ds_read_b128 v[232:235], v168 offset:13856
	s_waitcnt vmcnt(7)
	ds_write_b128 v191, v[158:161] offset:18432
	s_waitcnt vmcnt(6)
	ds_write_b128 v191, v[162:165] offset:55296
	ds_read_b128 v[158:161], v169 offset:64
	ds_read_b128 v[162:165], v169 offset:4672
	s_waitcnt lgkmcnt(5)
	v_mfma_f32_32x32x16_bf16 v[80:95], v[172:175], v[228:231], v[80:95]
	v_mfma_f32_32x32x16_bf16 v[16:31], v[224:227], v[228:231], v[16:31]
	ds_read_b128 v[228:231], v168 offset:64
	s_waitcnt lgkmcnt(5)
	v_mfma_f32_32x32x16_bf16 v[64:79], v[172:175], v[232:235], v[64:79]
	v_mfma_f32_32x32x16_bf16 v[0:15], v[224:227], v[232:235], v[0:15]
	ds_read_b128 v[232:235], v168 offset:4672
	s_setprio 0
	global_load_dwordx4 v[172:175], v[144:145], off offset:1408
	global_load_dwordx4 v[224:227], v[148:149], off offset:1408
	s_setprio 1
	s_waitcnt lgkmcnt(1)
	v_mfma_f32_32x32x16_bf16 v[112:127], v[158:161], v[228:231], v[112:127]
	v_mfma_f32_32x32x16_bf16 v[48:63], v[162:165], v[228:231], v[48:63]
	s_waitcnt lgkmcnt(0)
	v_mfma_f32_32x32x16_bf16 v[96:111], v[158:161], v[232:235], v[96:111]
	v_mfma_f32_32x32x16_bf16 v[32:47], v[162:165], v[232:235], v[32:47]
	ds_read_b128 v[228:231], v168 offset:9280
	ds_read_b128 v[232:235], v168 offset:13888
	s_waitcnt vmcnt(7)
	ds_write_b128 v191, v[200:203] offset:27648
	s_waitcnt vmcnt(6)
	ds_write_b128 v191, v[208:211] offset:64512
	ds_read_b128 v[200:203], v169 offset:96
	ds_read_b128 v[208:211], v169 offset:4704
	s_waitcnt lgkmcnt(5)
	v_mfma_f32_32x32x16_bf16 v[80:95], v[158:161], v[228:231], v[80:95]
	v_mfma_f32_32x32x16_bf16 v[16:31], v[162:165], v[228:231], v[16:31]
	ds_read_b128 v[228:231], v168 offset:96
	s_waitcnt lgkmcnt(5)
	v_mfma_f32_32x32x16_bf16 v[64:79], v[158:161], v[232:235], v[64:79]
	v_mfma_f32_32x32x16_bf16 v[0:15], v[162:165], v[232:235], v[0:15]
	ds_read_b128 v[232:235], v168 offset:4704
	s_setprio 0
	global_load_dwordx4 v[158:161], v[152:153], off offset:1408
	global_load_dwordx4 v[162:165], v[156:157], off offset:1408
	s_setprio 1
	s_waitcnt lgkmcnt(1)
	v_mfma_f32_32x32x16_bf16 v[112:127], v[200:203], v[228:231], v[112:127]
	v_mfma_f32_32x32x16_bf16 v[48:63], v[208:211], v[228:231], v[48:63]
	s_waitcnt lgkmcnt(0)
	v_mfma_f32_32x32x16_bf16 v[96:111], v[200:203], v[232:235], v[96:111]
	v_mfma_f32_32x32x16_bf16 v[32:47], v[208:211], v[232:235], v[32:47]
	ds_read_b128 v[228:231], v168 offset:9312
	ds_read_b128 v[232:235], v168 offset:13920
	s_waitcnt lgkmcnt(0)
	s_barrier
; template <bool trans>
; DI void gemm_core(const GTile& tl, const GTile& nx, bool has_next  , bool chain  , bool pre, u32x4 (&ra)[4], u32x4 (&rb)[4], char* smem, f32x16 (&acc)[2][4]) {
;     ...
;   const int nk = K / 64;
;   if (!pre) { G_LOAD(0); G_STORE(0); G_LOAD(1); }
;   for (int kt = 0; kt < nk; ++kt) {
;     __syncthreads();
;     G_COMPUTE(kt & 1, kt);
;   }
	s_waitcnt vmcnt(7)
	ds_write_b128 v195, v[212:215]
	s_waitcnt vmcnt(6)
	ds_write_b128 v196, v[216:219]
	ds_read_b128 v[212:215], v192 offset:36864
	ds_read_b128 v[216:219], v192 offset:41472
	v_mfma_f32_32x32x16_bf16 v[80:95], v[200:203], v[228:231], v[80:95]
	v_mfma_f32_32x32x16_bf16 v[16:31], v[208:211], v[228:231], v[16:31]
	ds_read_b128 v[228:231], v184
	v_mfma_f32_32x32x16_bf16 v[64:79], v[200:203], v[232:235], v[64:79]
	v_mfma_f32_32x32x16_bf16 v[0:15], v[208:211], v[232:235], v[0:15]
	ds_read_b128 v[232:235], v184 offset:4608
	s_setprio 0
	global_load_dwordx4 v[200:203], v[128:129], off offset:1536
	global_load_dwordx4 v[208:211], v[132:133], off offset:1536
	s_setprio 1
	s_waitcnt lgkmcnt(1)
	v_mfma_f32_32x32x16_bf16 v[112:127], v[212:215], v[228:231], v[112:127]
	v_mfma_f32_32x32x16_bf16 v[48:63], v[216:219], v[228:231], v[48:63]
	s_waitcnt lgkmcnt(0)
	v_mfma_f32_32x32x16_bf16 v[96:111], v[212:215], v[232:235], v[96:111]
	v_mfma_f32_32x32x16_bf16 v[32:47], v[216:219], v[232:235], v[32:47]
	ds_read_b128 v[228:231], v184 offset:9216
	ds_read_b128 v[232:235], v184 offset:13824
	s_waitcnt vmcnt(7)
	ds_write_b128 v194, v[178:181]
	s_waitcnt vmcnt(6)
	ds_write_b128 v193, v[220:223]
	ds_read_b128 v[178:181], v192 offset:36896
	ds_read_b128 v[220:223], v192 offset:41504
	s_waitcnt lgkmcnt(5)
	v_mfma_f32_32x32x16_bf16 v[80:95], v[212:215], v[228:231], v[80:95]
	v_mfma_f32_32x32x16_bf16 v[16:31], v[216:219], v[228:231], v[16:31]
	ds_read_b128 v[228:231], v184 offset:32
	s_waitcnt lgkmcnt(5)
	v_mfma_f32_32x32x16_bf16 v[64:79], v[212:215], v[232:235], v[64:79]
	v_mfma_f32_32x32x16_bf16 v[0:15], v[216:219], v[232:235], v[0:15]
	ds_read_b128 v[232:235], v184 offset:4640
	s_setprio 0
	global_load_dwordx4 v[212:215], v[136:137], off offset:1536
	global_load_dwordx4 v[216:219], v[140:141], off offset:1536
	s_setprio 1
	s_waitcnt lgkmcnt(1)
	v_mfma_f32_32x32x16_bf16 v[112:127], v[178:181], v[228:231], v[112:127]
	v_mfma_f32_32x32x16_bf16 v[48:63], v[220:223], v[228:231], v[48:63]
	s_waitcnt lgkmcnt(0)
	v_mfma_f32_32x32x16_bf16 v[96:111], v[178:181], v[232:235], v[96:111]
	v_mfma_f32_32x32x16_bf16 v[32:47], v[220:223], v[232:235], v[32:47]
	ds_read_b128 v[228:231], v184 offset:9248
	ds_read_b128 v[232:235], v184 offset:13856
	s_waitcnt vmcnt(7)
	ds_write_b128 v177, v[172:175]
	s_waitcnt vmcnt(6)
	ds_write_b128 v176, v[224:227]
	ds_read_b128 v[172:175], v192 offset:36928
	ds_read_b128 v[224:227], v192 offset:41536
	s_waitcnt lgkmcnt(5)
	v_mfma_f32_32x32x16_bf16 v[80:95], v[178:181], v[228:231], v[80:95]
	v_mfma_f32_32x32x16_bf16 v[16:31], v[220:223], v[228:231], v[16:31]
	ds_read_b128 v[228:231], v184 offset:64
	s_waitcnt lgkmcnt(5)
	v_mfma_f32_32x32x16_bf16 v[64:79], v[178:181], v[232:235], v[64:79]
	v_mfma_f32_32x32x16_bf16 v[0:15], v[220:223], v[232:235], v[0:15]
	ds_read_b128 v[232:235], v184 offset:4672
	s_setprio 0
	global_load_dwordx4 v[178:181], v[144:145], off offset:1536
	global_load_dwordx4 v[220:223], v[148:149], off offset:1536
	s_setprio 1
	s_waitcnt lgkmcnt(1)
	v_mfma_f32_32x32x16_bf16 v[112:127], v[172:175], v[228:231], v[112:127]
	v_mfma_f32_32x32x16_bf16 v[48:63], v[224:227], v[228:231], v[48:63]
	s_waitcnt lgkmcnt(0)
	v_mfma_f32_32x32x16_bf16 v[96:111], v[172:175], v[232:235], v[96:111]
	v_mfma_f32_32x32x16_bf16 v[32:47], v[224:227], v[232:235], v[32:47]
	ds_read_b128 v[228:231], v184 offset:9280
	ds_read_b128 v[232:235], v184 offset:13888
	s_waitcnt vmcnt(7)
	ds_write_b128 v171, v[158:161]
	s_waitcnt vmcnt(6)
	ds_write_b128 v170, v[162:165]
	ds_read_b128 v[158:161], v192 offset:36960
	ds_read_b128 v[162:165], v192 offset:41568
	s_waitcnt lgkmcnt(5)
	v_mfma_f32_32x32x16_bf16 v[80:95], v[172:175], v[228:231], v[80:95]
	v_mfma_f32_32x32x16_bf16 v[16:31], v[224:227], v[228:231], v[16:31]
	ds_read_b128 v[228:231], v184 offset:96
	s_waitcnt lgkmcnt(5)
	v_mfma_f32_32x32x16_bf16 v[64:79], v[172:175], v[232:235], v[64:79]
	v_mfma_f32_32x32x16_bf16 v[0:15], v[224:227], v[232:235], v[0:15]
	ds_read_b128 v[232:235], v184 offset:4704
	s_setprio 0
	global_load_dwordx4 v[172:175], v[152:153], off offset:1536
	global_load_dwordx4 v[224:227], v[156:157], off offset:1536
	s_setprio 1
	s_waitcnt lgkmcnt(1)
	v_mfma_f32_32x32x16_bf16 v[112:127], v[158:161], v[228:231], v[112:127]
	v_mfma_f32_32x32x16_bf16 v[48:63], v[162:165], v[228:231], v[48:63]
	s_waitcnt lgkmcnt(0)
	v_mfma_f32_32x32x16_bf16 v[96:111], v[158:161], v[232:235], v[96:111]
	v_mfma_f32_32x32x16_bf16 v[32:47], v[162:165], v[232:235], v[32:47]
	ds_read_b128 v[228:231], v184 offset:9312
	ds_read_b128 v[232:235], v184 offset:13920
	s_waitcnt lgkmcnt(0)
	s_barrier
; template <bool trans>
; DI void gemm_core(const GTile& tl, const GTile& nx, bool has_next  , bool chain  , bool pre, u32x4 (&ra)[4], u32x4 (&rb)[4], char* smem, f32x16 (&acc)[2][4]) {
;     ...
;   const int nk = K / 64;
;   if (!pre) { G_LOAD(0); G_STORE(0); G_LOAD(1); }
;   for (int kt = 0; kt < nk; ++kt) {
;     __syncthreads();
;     G_COMPUTE(kt & 1, kt);
;   }
	s_waitcnt vmcnt(7)
	ds_write_b128 v191, v[200:203]
	s_waitcnt vmcnt(6)
	ds_write_b128 v191, v[208:211] offset:36864
	ds_read_b128 v[200:203], v169
	ds_read_b128 v[208:211], v169 offset:4608
	v_mfma_f32_32x32x16_bf16 v[80:95], v[158:161], v[228:231], v[80:95]
	v_mfma_f32_32x32x16_bf16 v[16:31], v[162:165], v[228:231], v[16:31]
	ds_read_b128 v[228:231], v168
	v_mfma_f32_32x32x16_bf16 v[64:79], v[158:161], v[232:235], v[64:79]
	v_mfma_f32_32x32x16_bf16 v[0:15], v[162:165], v[232:235], v[0:15]
	ds_read_b128 v[232:235], v168 offset:4608
	s_setprio 0
	global_load_dwordx4 v[158:161], v[128:129], off offset:1664
	global_load_dwordx4 v[162:165], v[132:133], off offset:1664
	s_setprio 1
	s_waitcnt lgkmcnt(1)
	v_mfma_f32_32x32x16_bf16 v[112:127], v[200:203], v[228:231], v[112:127]
	v_mfma_f32_32x32x16_bf16 v[48:63], v[208:211], v[228:231], v[48:63]
	s_waitcnt lgkmcnt(0)
	v_mfma_f32_32x32x16_bf16 v[96:111], v[200:203], v[232:235], v[96:111]
	v_mfma_f32_32x32x16_bf16 v[32:47], v[208:211], v[232:235], v[32:47]
	ds_read_b128 v[228:231], v168 offset:9216
	ds_read_b128 v[232:235], v168 offset:13824
	s_waitcnt vmcnt(7)
	ds_write_b128 v191, v[212:215] offset:9216
	s_waitcnt vmcnt(6)
	ds_write_b128 v191, v[216:219] offset:46080
	ds_read_b128 v[212:215], v169 offset:32
	ds_read_b128 v[216:219], v169 offset:4640
	s_waitcnt lgkmcnt(5)
	v_mfma_f32_32x32x16_bf16 v[80:95], v[200:203], v[228:231], v[80:95]
	v_mfma_f32_32x32x16_bf16 v[16:31], v[208:211], v[228:231], v[16:31]
	ds_read_b128 v[228:231], v168 offset:32
	s_waitcnt lgkmcnt(5)
	v_mfma_f32_32x32x16_bf16 v[64:79], v[200:203], v[232:235], v[64:79]
	v_mfma_f32_32x32x16_bf16 v[0:15], v[208:211], v[232:235], v[0:15]
	ds_read_b128 v[232:235], v168 offset:4640
	s_setprio 0
	global_load_dwordx4 v[200:203], v[136:137], off offset:1664
	global_load_dwordx4 v[208:211], v[140:141], off offset:1664
	s_setprio 1
	s_waitcnt lgkmcnt(1)
	v_mfma_f32_32x32x16_bf16 v[112:127], v[212:215], v[228:231], v[112:127]
	v_mfma_f32_32x32x16_bf16 v[48:63], v[216:219], v[228:231], v[48:63]
	s_waitcnt lgkmcnt(0)
	v_mfma_f32_32x32x16_bf16 v[96:111], v[212:215], v[232:235], v[96:111]
	v_mfma_f32_32x32x16_bf16 v[32:47], v[216:219], v[232:235], v[32:47]
	ds_read_b128 v[228:231], v168 offset:9248
	ds_read_b128 v[232:235], v168 offset:13856
	s_waitcnt vmcnt(7)
	ds_write_b128 v191, v[178:181] offset:18432
	s_waitcnt vmcnt(6)
	ds_write_b128 v191, v[220:223] offset:55296
	ds_read_b128 v[178:181], v169 offset:64
	ds_read_b128 v[220:223], v169 offset:4672
	s_waitcnt lgkmcnt(5)
	v_mfma_f32_32x32x16_bf16 v[80:95], v[212:215], v[228:231], v[80:95]
	v_mfma_f32_32x32x16_bf16 v[16:31], v[216:219], v[228:231], v[16:31]
	ds_read_b128 v[228:231], v168 offset:64
	s_waitcnt lgkmcnt(5)
	v_mfma_f32_32x32x16_bf16 v[64:79], v[212:215], v[232:235], v[64:79]
	v_mfma_f32_32x32x16_bf16 v[0:15], v[216:219], v[232:235], v[0:15]
	ds_read_b128 v[232:235], v168 offset:4672
	s_setprio 0
	global_load_dwordx4 v[212:215], v[144:145], off offset:1664
	global_load_dwordx4 v[216:219], v[148:149], off offset:1664
	s_setprio 1
	s_waitcnt lgkmcnt(1)
	v_mfma_f32_32x32x16_bf16 v[112:127], v[178:181], v[228:231], v[112:127]
	v_mfma_f32_32x32x16_bf16 v[48:63], v[220:223], v[228:231], v[48:63]
	s_waitcnt lgkmcnt(0)
	v_mfma_f32_32x32x16_bf16 v[96:111], v[178:181], v[232:235], v[96:111]
	v_mfma_f32_32x32x16_bf16 v[32:47], v[220:223], v[232:235], v[32:47]
	ds_read_b128 v[228:231], v168 offset:9280
	ds_read_b128 v[232:235], v168 offset:13888
	s_waitcnt vmcnt(7)
	ds_write_b128 v191, v[172:175] offset:27648
	s_waitcnt vmcnt(6)
	ds_write_b128 v191, v[224:227] offset:64512
	ds_read_b128 v[172:175], v169 offset:96
	ds_read_b128 v[224:227], v169 offset:4704
	s_waitcnt lgkmcnt(5)
	v_mfma_f32_32x32x16_bf16 v[80:95], v[178:181], v[228:231], v[80:95]
	v_mfma_f32_32x32x16_bf16 v[16:31], v[220:223], v[228:231], v[16:31]
	ds_read_b128 v[228:231], v168 offset:96
	s_waitcnt lgkmcnt(5)
	v_mfma_f32_32x32x16_bf16 v[64:79], v[178:181], v[232:235], v[64:79]
	v_mfma_f32_32x32x16_bf16 v[0:15], v[220:223], v[232:235], v[0:15]
	ds_read_b128 v[232:235], v168 offset:4704
	s_setprio 0
	global_load_dwordx4 v[178:181], v[152:153], off offset:1664
	global_load_dwordx4 v[220:223], v[156:157], off offset:1664
	s_setprio 1
	s_waitcnt lgkmcnt(1)
	v_mfma_f32_32x32x16_bf16 v[112:127], v[172:175], v[228:231], v[112:127]
	v_mfma_f32_32x32x16_bf16 v[48:63], v[224:227], v[228:231], v[48:63]
	s_waitcnt lgkmcnt(0)
	v_mfma_f32_32x32x16_bf16 v[96:111], v[172:175], v[232:235], v[96:111]
	v_mfma_f32_32x32x16_bf16 v[32:47], v[224:227], v[232:235], v[32:47]
	ds_read_b128 v[228:231], v168 offset:9312
	ds_read_b128 v[232:235], v168 offset:13920
	s_waitcnt lgkmcnt(0)
	s_barrier
; template <bool trans>
; DI void gemm_core(const GTile& tl, const GTile& nx, bool has_next  , bool chain  , bool pre, u32x4 (&ra)[4], u32x4 (&rb)[4], char* smem, f32x16 (&acc)[2][4]) {
;     ...
;   const int nk = K / 64;
;   if (!pre) { G_LOAD(0); G_STORE(0); G_LOAD(1); }
;   for (int kt = 0; kt < nk; ++kt) {
;     __syncthreads();
;     G_COMPUTE(kt & 1, kt);
;   }
	s_waitcnt vmcnt(7)
	ds_write_b128 v195, v[158:161]
	s_waitcnt vmcnt(6)
	ds_write_b128 v196, v[162:165]
	ds_read_b128 v[158:161], v192 offset:36864
	ds_read_b128 v[162:165], v192 offset:41472
	v_mfma_f32_32x32x16_bf16 v[80:95], v[172:175], v[228:231], v[80:95]
	v_mfma_f32_32x32x16_bf16 v[16:31], v[224:227], v[228:231], v[16:31]
	ds_read_b128 v[228:231], v184
	v_mfma_f32_32x32x16_bf16 v[64:79], v[172:175], v[232:235], v[64:79]
	v_mfma_f32_32x32x16_bf16 v[0:15], v[224:227], v[232:235], v[0:15]
	ds_read_b128 v[232:235], v184 offset:4608
	s_setprio 0
	global_load_dwordx4 v[172:175], v[128:129], off offset:1792
	global_load_dwordx4 v[224:227], v[132:133], off offset:1792
	s_setprio 1
	s_waitcnt lgkmcnt(1)
	v_mfma_f32_32x32x16_bf16 v[112:127], v[158:161], v[228:231], v[112:127]
	v_mfma_f32_32x32x16_bf16 v[48:63], v[162:165], v[228:231], v[48:63]
	s_waitcnt lgkmcnt(0)
	v_mfma_f32_32x32x16_bf16 v[96:111], v[158:161], v[232:235], v[96:111]
	v_mfma_f32_32x32x16_bf16 v[32:47], v[162:165], v[232:235], v[32:47]
	ds_read_b128 v[228:231], v184 offset:9216
	ds_read_b128 v[232:235], v184 offset:13824
	s_waitcnt vmcnt(7)
	ds_write_b128 v194, v[200:203]
	s_waitcnt vmcnt(6)
	ds_write_b128 v193, v[208:211]
	ds_read_b128 v[200:203], v192 offset:36896
	ds_read_b128 v[208:211], v192 offset:41504
	s_waitcnt lgkmcnt(5)
	v_mfma_f32_32x32x16_bf16 v[80:95], v[158:161], v[228:231], v[80:95]
	v_mfma_f32_32x32x16_bf16 v[16:31], v[162:165], v[228:231], v[16:31]
	ds_read_b128 v[228:231], v184 offset:32
	s_waitcnt lgkmcnt(5)
	v_mfma_f32_32x32x16_bf16 v[64:79], v[158:161], v[232:235], v[64:79]
	v_mfma_f32_32x32x16_bf16 v[0:15], v[162:165], v[232:235], v[0:15]
	ds_read_b128 v[232:235], v184 offset:4640
	s_setprio 0
	global_load_dwordx4 v[158:161], v[136:137], off offset:1792
	global_load_dwordx4 v[162:165], v[140:141], off offset:1792
	s_setprio 1
	s_waitcnt lgkmcnt(1)
	v_mfma_f32_32x32x16_bf16 v[112:127], v[200:203], v[228:231], v[112:127]
	v_mfma_f32_32x32x16_bf16 v[48:63], v[208:211], v[228:231], v[48:63]
	s_waitcnt lgkmcnt(0)
	v_mfma_f32_32x32x16_bf16 v[96:111], v[200:203], v[232:235], v[96:111]
	v_mfma_f32_32x32x16_bf16 v[32:47], v[208:211], v[232:235], v[32:47]
	ds_read_b128 v[228:231], v184 offset:9248
	ds_read_b128 v[232:235], v184 offset:13856
	s_waitcnt vmcnt(7)
	ds_write_b128 v177, v[212:215]
	s_waitcnt vmcnt(6)
	ds_write_b128 v176, v[216:219]
	ds_read_b128 v[212:215], v192 offset:36928
	ds_read_b128 v[216:219], v192 offset:41536
	s_waitcnt lgkmcnt(5)
	v_mfma_f32_32x32x16_bf16 v[80:95], v[200:203], v[228:231], v[80:95]
	v_mfma_f32_32x32x16_bf16 v[16:31], v[208:211], v[228:231], v[16:31]
	ds_read_b128 v[228:231], v184 offset:64
	s_waitcnt lgkmcnt(5)
	v_mfma_f32_32x32x16_bf16 v[64:79], v[200:203], v[232:235], v[64:79]
	v_mfma_f32_32x32x16_bf16 v[0:15], v[208:211], v[232:235], v[0:15]
	ds_read_b128 v[232:235], v184 offset:4672
	s_setprio 0
	global_load_dwordx4 v[200:203], v[144:145], off offset:1792
	global_load_dwordx4 v[208:211], v[148:149], off offset:1792
	s_setprio 1
	s_waitcnt lgkmcnt(1)
	v_mfma_f32_32x32x16_bf16 v[112:127], v[212:215], v[228:231], v[112:127]
	v_mfma_f32_32x32x16_bf16 v[48:63], v[216:219], v[228:231], v[48:63]
	s_waitcnt lgkmcnt(0)
	v_mfma_f32_32x32x16_bf16 v[96:111], v[212:215], v[232:235], v[96:111]
	v_mfma_f32_32x32x16_bf16 v[32:47], v[216:219], v[232:235], v[32:47]
	ds_read_b128 v[228:231], v184 offset:9280
	ds_read_b128 v[232:235], v184 offset:13888
	s_waitcnt vmcnt(7)
	ds_write_b128 v171, v[178:181]
	s_waitcnt vmcnt(6)
	ds_write_b128 v170, v[220:223]
	ds_read_b128 v[178:181], v192 offset:36960
	ds_read_b128 v[220:223], v192 offset:41568
	s_waitcnt lgkmcnt(5)
	v_mfma_f32_32x32x16_bf16 v[80:95], v[212:215], v[228:231], v[80:95]
	v_mfma_f32_32x32x16_bf16 v[16:31], v[216:219], v[228:231], v[16:31]
	ds_read_b128 v[228:231], v184 offset:96
	s_waitcnt lgkmcnt(5)
	v_mfma_f32_32x32x16_bf16 v[64:79], v[212:215], v[232:235], v[64:79]
	v_mfma_f32_32x32x16_bf16 v[0:15], v[216:219], v[232:235], v[0:15]
	ds_read_b128 v[232:235], v184 offset:4704
	s_setprio 0
	global_load_dwordx4 v[212:215], v[152:153], off offset:1792
	global_load_dwordx4 v[216:219], v[156:157], off offset:1792
	s_setprio 1
	s_waitcnt lgkmcnt(1)
	v_mfma_f32_32x32x16_bf16 v[112:127], v[178:181], v[228:231], v[112:127]
	v_mfma_f32_32x32x16_bf16 v[48:63], v[220:223], v[228:231], v[48:63]
	s_waitcnt lgkmcnt(0)
	v_mfma_f32_32x32x16_bf16 v[96:111], v[178:181], v[232:235], v[96:111]
	v_mfma_f32_32x32x16_bf16 v[32:47], v[220:223], v[232:235], v[32:47]
	ds_read_b128 v[228:231], v184 offset:9312
	ds_read_b128 v[232:235], v184 offset:13920
	s_waitcnt lgkmcnt(0)
	s_barrier
; template <bool trans>
; DI void gemm_core(const GTile& tl, const GTile& nx, bool has_next  , bool chain  , bool pre, u32x4 (&ra)[4], u32x4 (&rb)[4], char* smem, f32x16 (&acc)[2][4]) {
;     ...
;   const int nk = K / 64;
;   if (!pre) { G_LOAD(0); G_STORE(0); G_LOAD(1); }
;   for (int kt = 0; kt < nk; ++kt) {
;     __syncthreads();
;     G_COMPUTE(kt & 1, kt);
;   }
	s_waitcnt vmcnt(7)
	ds_write_b128 v191, v[172:175]
	s_waitcnt vmcnt(6)
	ds_write_b128 v191, v[224:227] offset:36864
	ds_read_b128 v[172:175], v169
	ds_read_b128 v[224:227], v169 offset:4608
	v_mfma_f32_32x32x16_bf16 v[80:95], v[178:181], v[228:231], v[80:95]
	v_mfma_f32_32x32x16_bf16 v[16:31], v[220:223], v[228:231], v[16:31]
	ds_read_b128 v[228:231], v168
	v_mfma_f32_32x32x16_bf16 v[64:79], v[178:181], v[232:235], v[64:79]
	v_mfma_f32_32x32x16_bf16 v[0:15], v[220:223], v[232:235], v[0:15]
	ds_read_b128 v[232:235], v168 offset:4608
	s_setprio 0
	global_load_dwordx4 v[178:181], v[128:129], off offset:1920
	global_load_dwordx4 v[220:223], v[132:133], off offset:1920
	s_setprio 1
	s_waitcnt lgkmcnt(1)
	v_mfma_f32_32x32x16_bf16 v[112:127], v[172:175], v[228:231], v[112:127]
	v_mfma_f32_32x32x16_bf16 v[48:63], v[224:227], v[228:231], v[48:63]
	s_waitcnt lgkmcnt(0)
	v_mfma_f32_32x32x16_bf16 v[96:111], v[172:175], v[232:235], v[96:111]
	v_mfma_f32_32x32x16_bf16 v[32:47], v[224:227], v[232:235], v[32:47]
	ds_read_b128 v[228:231], v168 offset:9216
	ds_read_b128 v[232:235], v168 offset:13824
	s_waitcnt vmcnt(7)
	ds_write_b128 v191, v[158:161] offset:9216
	s_waitcnt vmcnt(6)
	ds_write_b128 v191, v[162:165] offset:46080
	ds_read_b128 v[158:161], v169 offset:32
	ds_read_b128 v[162:165], v169 offset:4640
	s_waitcnt lgkmcnt(5)
	v_mfma_f32_32x32x16_bf16 v[80:95], v[172:175], v[228:231], v[80:95]
	v_mfma_f32_32x32x16_bf16 v[16:31], v[224:227], v[228:231], v[16:31]
	ds_read_b128 v[228:231], v168 offset:32
	s_waitcnt lgkmcnt(5)
	v_mfma_f32_32x32x16_bf16 v[64:79], v[172:175], v[232:235], v[64:79]
	v_mfma_f32_32x32x16_bf16 v[0:15], v[224:227], v[232:235], v[0:15]
	ds_read_b128 v[232:235], v168 offset:4640
	s_setprio 0
	global_load_dwordx4 v[172:175], v[136:137], off offset:1920
	global_load_dwordx4 v[224:227], v[140:141], off offset:1920
	s_setprio 1
	s_waitcnt lgkmcnt(1)
	v_mfma_f32_32x32x16_bf16 v[112:127], v[158:161], v[228:231], v[112:127]
	v_mfma_f32_32x32x16_bf16 v[48:63], v[162:165], v[228:231], v[48:63]
	s_waitcnt lgkmcnt(0)
	v_mfma_f32_32x32x16_bf16 v[96:111], v[158:161], v[232:235], v[96:111]
	v_mfma_f32_32x32x16_bf16 v[32:47], v[162:165], v[232:235], v[32:47]
	ds_read_b128 v[228:231], v168 offset:9248
	ds_read_b128 v[232:235], v168 offset:13856
	s_waitcnt vmcnt(7)
	ds_write_b128 v191, v[200:203] offset:18432
	s_waitcnt vmcnt(6)
	ds_write_b128 v191, v[208:211] offset:55296
	ds_read_b128 v[200:203], v169 offset:64
	ds_read_b128 v[208:211], v169 offset:4672
	s_waitcnt lgkmcnt(5)
	v_mfma_f32_32x32x16_bf16 v[80:95], v[158:161], v[228:231], v[80:95]
	v_mfma_f32_32x32x16_bf16 v[16:31], v[162:165], v[228:231], v[16:31]
	ds_read_b128 v[228:231], v168 offset:64
	s_waitcnt lgkmcnt(5)
	v_mfma_f32_32x32x16_bf16 v[64:79], v[158:161], v[232:235], v[64:79]
	v_mfma_f32_32x32x16_bf16 v[0:15], v[162:165], v[232:235], v[0:15]
	ds_read_b128 v[232:235], v168 offset:4672
	s_setprio 0
	global_load_dwordx4 v[158:161], v[144:145], off offset:1920
	global_load_dwordx4 v[162:165], v[148:149], off offset:1920
	s_setprio 1
	s_waitcnt lgkmcnt(1)
	v_mfma_f32_32x32x16_bf16 v[112:127], v[200:203], v[228:231], v[112:127]
	v_mfma_f32_32x32x16_bf16 v[48:63], v[208:211], v[228:231], v[48:63]
	s_waitcnt lgkmcnt(0)
	v_mfma_f32_32x32x16_bf16 v[96:111], v[200:203], v[232:235], v[96:111]
	v_mfma_f32_32x32x16_bf16 v[32:47], v[208:211], v[232:235], v[32:47]
	ds_read_b128 v[228:231], v168 offset:9280
	ds_read_b128 v[232:235], v168 offset:13888
	s_waitcnt vmcnt(7)
	ds_write_b128 v191, v[212:215] offset:27648
	s_waitcnt vmcnt(6)
	ds_write_b128 v191, v[216:219] offset:64512
	ds_read_b128 v[212:215], v169 offset:96
	ds_read_b128 v[216:219], v169 offset:4704
	s_waitcnt lgkmcnt(5)
	v_mfma_f32_32x32x16_bf16 v[80:95], v[200:203], v[228:231], v[80:95]
	v_mfma_f32_32x32x16_bf16 v[16:31], v[208:211], v[228:231], v[16:31]
	ds_read_b128 v[228:231], v168 offset:96
	s_waitcnt lgkmcnt(5)
	v_mfma_f32_32x32x16_bf16 v[64:79], v[200:203], v[232:235], v[64:79]
	v_mfma_f32_32x32x16_bf16 v[0:15], v[208:211], v[232:235], v[0:15]
	ds_read_b128 v[232:235], v168 offset:4704
	s_setprio 0
	global_load_dwordx4 v[200:203], v[152:153], off offset:1920
	global_load_dwordx4 v[208:211], v[156:157], off offset:1920
	s_setprio 1
	s_waitcnt lgkmcnt(1)
	v_mfma_f32_32x32x16_bf16 v[112:127], v[212:215], v[228:231], v[112:127]
	v_mfma_f32_32x32x16_bf16 v[48:63], v[216:219], v[228:231], v[48:63]
	s_waitcnt lgkmcnt(0)
	v_mfma_f32_32x32x16_bf16 v[96:111], v[212:215], v[232:235], v[96:111]
	v_mfma_f32_32x32x16_bf16 v[32:47], v[216:219], v[232:235], v[32:47]
	ds_read_b128 v[228:231], v168 offset:9312
	ds_read_b128 v[232:235], v168 offset:13920
	s_waitcnt lgkmcnt(0)
	s_barrier
; template <bool trans>
; DI void gemm_core(const GTile& tl, const GTile& nx, bool has_next  , bool chain  , bool pre, u32x4 (&ra)[4], u32x4 (&rb)[4], char* smem, f32x16 (&acc)[2][4]) {
;     ...
;   const int nk = K / 64;
;   if (!pre) { G_LOAD(0); G_STORE(0); G_LOAD(1); }
;   for (int kt = 0; kt < nk; ++kt) {
;     __syncthreads();
;     G_COMPUTE(kt & 1, kt);
;   }
	s_waitcnt vmcnt(7)
	ds_write_b128 v195, v[178:181]
	s_waitcnt vmcnt(6)
	ds_write_b128 v196, v[220:223]
	ds_read_b128 v[178:181], v192 offset:36864
	ds_read_b128 v[220:223], v192 offset:41472
	v_mfma_f32_32x32x16_bf16 v[80:95], v[212:215], v[228:231], v[80:95]
	v_mfma_f32_32x32x16_bf16 v[16:31], v[216:219], v[228:231], v[16:31]
	ds_read_b128 v[228:231], v184
	v_mfma_f32_32x32x16_bf16 v[64:79], v[212:215], v[232:235], v[64:79]
	v_mfma_f32_32x32x16_bf16 v[0:15], v[216:219], v[232:235], v[0:15]
	ds_read_b128 v[232:235], v184 offset:4608
	s_setprio 0
	global_load_dwordx4 v[212:215], v[128:129], off offset:2048
	global_load_dwordx4 v[216:219], v[132:133], off offset:2048
	s_setprio 1
	s_waitcnt lgkmcnt(1)
	v_mfma_f32_32x32x16_bf16 v[112:127], v[178:181], v[228:231], v[112:127]
	v_mfma_f32_32x32x16_bf16 v[48:63], v[220:223], v[228:231], v[48:63]
	s_waitcnt lgkmcnt(0)
	v_mfma_f32_32x32x16_bf16 v[96:111], v[178:181], v[232:235], v[96:111]
	v_mfma_f32_32x32x16_bf16 v[32:47], v[220:223], v[232:235], v[32:47]
	ds_read_b128 v[228:231], v184 offset:9216
	ds_read_b128 v[232:235], v184 offset:13824
	s_waitcnt vmcnt(7)
	ds_write_b128 v194, v[172:175]
	s_waitcnt vmcnt(6)
	ds_write_b128 v193, v[224:227]
	ds_read_b128 v[172:175], v192 offset:36896
	ds_read_b128 v[224:227], v192 offset:41504
	s_waitcnt lgkmcnt(5)
	v_mfma_f32_32x32x16_bf16 v[80:95], v[178:181], v[228:231], v[80:95]
	v_mfma_f32_32x32x16_bf16 v[16:31], v[220:223], v[228:231], v[16:31]
	ds_read_b128 v[228:231], v184 offset:32
	s_waitcnt lgkmcnt(5)
	v_mfma_f32_32x32x16_bf16 v[64:79], v[178:181], v[232:235], v[64:79]
	v_mfma_f32_32x32x16_bf16 v[0:15], v[220:223], v[232:235], v[0:15]
	ds_read_b128 v[232:235], v184 offset:4640
	s_setprio 0
	global_load_dwordx4 v[178:181], v[136:137], off offset:2048
	global_load_dwordx4 v[220:223], v[140:141], off offset:2048
	s_setprio 1
	s_waitcnt lgkmcnt(1)
	v_mfma_f32_32x32x16_bf16 v[112:127], v[172:175], v[228:231], v[112:127]
	v_mfma_f32_32x32x16_bf16 v[48:63], v[224:227], v[228:231], v[48:63]
	s_waitcnt lgkmcnt(0)
	v_mfma_f32_32x32x16_bf16 v[96:111], v[172:175], v[232:235], v[96:111]
	v_mfma_f32_32x32x16_bf16 v[32:47], v[224:227], v[232:235], v[32:47]
	ds_read_b128 v[228:231], v184 offset:9248
	ds_read_b128 v[232:235], v184 offset:13856
	s_waitcnt vmcnt(7)
	ds_write_b128 v177, v[158:161]
	s_waitcnt vmcnt(6)
	ds_write_b128 v176, v[162:165]
	ds_read_b128 v[158:161], v192 offset:36928
	ds_read_b128 v[162:165], v192 offset:41536
	s_waitcnt lgkmcnt(5)
	v_mfma_f32_32x32x16_bf16 v[80:95], v[172:175], v[228:231], v[80:95]
	v_mfma_f32_32x32x16_bf16 v[16:31], v[224:227], v[228:231], v[16:31]
	ds_read_b128 v[228:231], v184 offset:64
	s_waitcnt lgkmcnt(5)
	v_mfma_f32_32x32x16_bf16 v[64:79], v[172:175], v[232:235], v[64:79]
	v_mfma_f32_32x32x16_bf16 v[0:15], v[224:227], v[232:235], v[0:15]
	ds_read_b128 v[232:235], v184 offset:4672
	s_setprio 0
	global_load_dwordx4 v[172:175], v[144:145], off offset:2048
	global_load_dwordx4 v[224:227], v[148:149], off offset:2048
	s_setprio 1
	s_waitcnt lgkmcnt(1)
	v_mfma_f32_32x32x16_bf16 v[112:127], v[158:161], v[228:231], v[112:127]
	v_mfma_f32_32x32x16_bf16 v[48:63], v[162:165], v[228:231], v[48:63]
	s_waitcnt lgkmcnt(0)
	v_mfma_f32_32x32x16_bf16 v[96:111], v[158:161], v[232:235], v[96:111]
	v_mfma_f32_32x32x16_bf16 v[32:47], v[162:165], v[232:235], v[32:47]
	ds_read_b128 v[228:231], v184 offset:9280
	ds_read_b128 v[232:235], v184 offset:13888
	s_waitcnt vmcnt(7)
	ds_write_b128 v171, v[200:203]
	s_waitcnt vmcnt(6)
	ds_write_b128 v170, v[208:211]
	ds_read_b128 v[200:203], v192 offset:36960
	ds_read_b128 v[208:211], v192 offset:41568
	s_waitcnt lgkmcnt(5)
	v_mfma_f32_32x32x16_bf16 v[80:95], v[158:161], v[228:231], v[80:95]
	v_mfma_f32_32x32x16_bf16 v[16:31], v[162:165], v[228:231], v[16:31]
	ds_read_b128 v[228:231], v184 offset:96
	s_waitcnt lgkmcnt(5)
	v_mfma_f32_32x32x16_bf16 v[64:79], v[158:161], v[232:235], v[64:79]
	v_mfma_f32_32x32x16_bf16 v[0:15], v[162:165], v[232:235], v[0:15]
	ds_read_b128 v[232:235], v184 offset:4704
	s_setprio 0
	global_load_dwordx4 v[158:161], v[152:153], off offset:2048
	global_load_dwordx4 v[162:165], v[156:157], off offset:2048
	s_setprio 1
	s_waitcnt lgkmcnt(1)
	v_mfma_f32_32x32x16_bf16 v[112:127], v[200:203], v[228:231], v[112:127]
	v_mfma_f32_32x32x16_bf16 v[48:63], v[208:211], v[228:231], v[48:63]
	s_waitcnt lgkmcnt(0)
	v_mfma_f32_32x32x16_bf16 v[96:111], v[200:203], v[232:235], v[96:111]
	v_mfma_f32_32x32x16_bf16 v[32:47], v[208:211], v[232:235], v[32:47]
	ds_read_b128 v[228:231], v184 offset:9312
	ds_read_b128 v[232:235], v184 offset:13920
	s_waitcnt lgkmcnt(0)
	s_barrier
; template <bool trans>
; DI void gemm_core(const GTile& tl, const GTile& nx, bool has_next  , bool chain  , bool pre, u32x4 (&ra)[4], u32x4 (&rb)[4], char* smem, f32x16 (&acc)[2][4]) {
;     ...
;   const int nk = K / 64;
;   if (!pre) { G_LOAD(0); G_STORE(0); G_LOAD(1); }
;   for (int kt = 0; kt < nk; ++kt) {
;     __syncthreads();
;     G_COMPUTE(kt & 1, kt);
;   }
	s_waitcnt vmcnt(7)
	ds_write_b128 v191, v[212:215]
	s_waitcnt vmcnt(6)
	ds_write_b128 v191, v[216:219] offset:36864
	ds_read_b128 v[212:215], v169
	ds_read_b128 v[216:219], v169 offset:4608
	v_mfma_f32_32x32x16_bf16 v[80:95], v[200:203], v[228:231], v[80:95]
	v_mfma_f32_32x32x16_bf16 v[16:31], v[208:211], v[228:231], v[16:31]
	ds_read_b128 v[228:231], v168
	v_mfma_f32_32x32x16_bf16 v[64:79], v[200:203], v[232:235], v[64:79]
	v_mfma_f32_32x32x16_bf16 v[0:15], v[208:211], v[232:235], v[0:15]
	ds_read_b128 v[232:235], v168 offset:4608
	s_setprio 0
	global_load_dwordx4 v[200:203], v[128:129], off offset:2176
	global_load_dwordx4 v[208:211], v[132:133], off offset:2176
	s_setprio 1
	s_waitcnt lgkmcnt(1)
	v_mfma_f32_32x32x16_bf16 v[112:127], v[212:215], v[228:231], v[112:127]
	v_mfma_f32_32x32x16_bf16 v[48:63], v[216:219], v[228:231], v[48:63]
	s_waitcnt lgkmcnt(0)
	v_mfma_f32_32x32x16_bf16 v[96:111], v[212:215], v[232:235], v[96:111]
	v_mfma_f32_32x32x16_bf16 v[32:47], v[216:219], v[232:235], v[32:47]
	ds_read_b128 v[228:231], v168 offset:9216
	ds_read_b128 v[232:235], v168 offset:13824
	s_waitcnt vmcnt(7)
	ds_write_b128 v191, v[178:181] offset:9216
	s_waitcnt vmcnt(6)
	ds_write_b128 v191, v[220:223] offset:46080
	ds_read_b128 v[178:181], v169 offset:32
	ds_read_b128 v[220:223], v169 offset:4640
	s_waitcnt lgkmcnt(5)
	v_mfma_f32_32x32x16_bf16 v[80:95], v[212:215], v[228:231], v[80:95]
	v_mfma_f32_32x32x16_bf16 v[16:31], v[216:219], v[228:231], v[16:31]
	ds_read_b128 v[228:231], v168 offset:32
	s_waitcnt lgkmcnt(5)
	v_mfma_f32_32x32x16_bf16 v[64:79], v[212:215], v[232:235], v[64:79]
	v_mfma_f32_32x32x16_bf16 v[0:15], v[216:219], v[232:235], v[0:15]
	ds_read_b128 v[232:235], v168 offset:4640
	s_setprio 0
	global_load_dwordx4 v[212:215], v[136:137], off offset:2176
	global_load_dwordx4 v[216:219], v[140:141], off offset:2176
	s_setprio 1
	s_waitcnt lgkmcnt(1)
	v_mfma_f32_32x32x16_bf16 v[112:127], v[178:181], v[228:231], v[112:127]
	v_mfma_f32_32x32x16_bf16 v[48:63], v[220:223], v[228:231], v[48:63]
	s_waitcnt lgkmcnt(0)
	v_mfma_f32_32x32x16_bf16 v[96:111], v[178:181], v[232:235], v[96:111]
	v_mfma_f32_32x32x16_bf16 v[32:47], v[220:223], v[232:235], v[32:47]
	ds_read_b128 v[228:231], v168 offset:9248
	ds_read_b128 v[232:235], v168 offset:13856
	s_waitcnt vmcnt(7)
	ds_write_b128 v191, v[172:175] offset:18432
	s_waitcnt vmcnt(6)
	ds_write_b128 v191, v[224:227] offset:55296
	ds_read_b128 v[172:175], v169 offset:64
	ds_read_b128 v[224:227], v169 offset:4672
	s_waitcnt lgkmcnt(5)
	v_mfma_f32_32x32x16_bf16 v[80:95], v[178:181], v[228:231], v[80:95]
	v_mfma_f32_32x32x16_bf16 v[16:31], v[220:223], v[228:231], v[16:31]
	ds_read_b128 v[228:231], v168 offset:64
	s_waitcnt lgkmcnt(5)
	v_mfma_f32_32x32x16_bf16 v[64:79], v[178:181], v[232:235], v[64:79]
	v_mfma_f32_32x32x16_bf16 v[0:15], v[220:223], v[232:235], v[0:15]
	ds_read_b128 v[232:235], v168 offset:4672
	s_setprio 0
	global_load_dwordx4 v[178:181], v[144:145], off offset:2176
	global_load_dwordx4 v[220:223], v[148:149], off offset:2176
	s_setprio 1
	s_waitcnt lgkmcnt(1)
	v_mfma_f32_32x32x16_bf16 v[112:127], v[172:175], v[228:231], v[112:127]
	v_mfma_f32_32x32x16_bf16 v[48:63], v[224:227], v[228:231], v[48:63]
	s_waitcnt lgkmcnt(0)
	v_mfma_f32_32x32x16_bf16 v[96:111], v[172:175], v[232:235], v[96:111]
	v_mfma_f32_32x32x16_bf16 v[32:47], v[224:227], v[232:235], v[32:47]
	ds_read_b128 v[228:231], v168 offset:9280
	ds_read_b128 v[232:235], v168 offset:13888
	s_waitcnt vmcnt(7)
	ds_write_b128 v191, v[158:161] offset:27648
	s_waitcnt vmcnt(6)
	ds_write_b128 v191, v[162:165] offset:64512
	ds_read_b128 v[158:161], v169 offset:96
	ds_read_b128 v[162:165], v169 offset:4704
	s_waitcnt lgkmcnt(5)
	v_mfma_f32_32x32x16_bf16 v[80:95], v[172:175], v[228:231], v[80:95]
	v_mfma_f32_32x32x16_bf16 v[16:31], v[224:227], v[228:231], v[16:31]
	ds_read_b128 v[228:231], v168 offset:96
	s_waitcnt lgkmcnt(5)
	v_mfma_f32_32x32x16_bf16 v[64:79], v[172:175], v[232:235], v[64:79]
	v_mfma_f32_32x32x16_bf16 v[0:15], v[224:227], v[232:235], v[0:15]
	ds_read_b128 v[232:235], v168 offset:4704
	s_setprio 0
	global_load_dwordx4 v[172:175], v[152:153], off offset:2176
	global_load_dwordx4 v[224:227], v[156:157], off offset:2176
	s_setprio 1
	s_waitcnt lgkmcnt(1)
	v_mfma_f32_32x32x16_bf16 v[112:127], v[158:161], v[228:231], v[112:127]
	v_mfma_f32_32x32x16_bf16 v[48:63], v[162:165], v[228:231], v[48:63]
	s_waitcnt lgkmcnt(0)
	v_mfma_f32_32x32x16_bf16 v[96:111], v[158:161], v[232:235], v[96:111]
	v_mfma_f32_32x32x16_bf16 v[32:47], v[162:165], v[232:235], v[32:47]
	ds_read_b128 v[228:231], v168 offset:9312
	ds_read_b128 v[232:235], v168 offset:13920
	s_waitcnt lgkmcnt(0)
	s_barrier
; template <bool trans>
; DI void gemm_core(const GTile& tl, const GTile& nx, bool has_next  , bool chain  , bool pre, u32x4 (&ra)[4], u32x4 (&rb)[4], char* smem, f32x16 (&acc)[2][4]) {
;     ...
;   const int nk = K / 64;
;   if (!pre) { G_LOAD(0); G_STORE(0); G_LOAD(1); }
;   for (int kt = 0; kt < nk; ++kt) {
;     __syncthreads();
;     G_COMPUTE(kt & 1, kt);
;   }
	s_waitcnt vmcnt(7)
	ds_write_b128 v195, v[200:203]
	s_waitcnt vmcnt(6)
	ds_write_b128 v196, v[208:211]
	ds_read_b128 v[200:203], v192 offset:36864
	ds_read_b128 v[208:211], v192 offset:41472
	v_mfma_f32_32x32x16_bf16 v[80:95], v[158:161], v[228:231], v[80:95]
	v_mfma_f32_32x32x16_bf16 v[16:31], v[162:165], v[228:231], v[16:31]
	ds_read_b128 v[228:231], v184
	v_mfma_f32_32x32x16_bf16 v[64:79], v[158:161], v[232:235], v[64:79]
	v_mfma_f32_32x32x16_bf16 v[0:15], v[162:165], v[232:235], v[0:15]
	ds_read_b128 v[232:235], v184 offset:4608
	s_setprio 0
	global_load_dwordx4 v[158:161], v[128:129], off offset:2304
	global_load_dwordx4 v[162:165], v[132:133], off offset:2304
	s_setprio 1
	s_waitcnt lgkmcnt(1)
	v_mfma_f32_32x32x16_bf16 v[112:127], v[200:203], v[228:231], v[112:127]
	v_mfma_f32_32x32x16_bf16 v[48:63], v[208:211], v[228:231], v[48:63]
	s_waitcnt lgkmcnt(0)
	v_mfma_f32_32x32x16_bf16 v[96:111], v[200:203], v[232:235], v[96:111]
	v_mfma_f32_32x32x16_bf16 v[32:47], v[208:211], v[232:235], v[32:47]
	ds_read_b128 v[228:231], v184 offset:9216
	ds_read_b128 v[232:235], v184 offset:13824
	s_waitcnt vmcnt(7)
	ds_write_b128 v194, v[212:215]
	s_waitcnt vmcnt(6)
	ds_write_b128 v193, v[216:219]
	ds_read_b128 v[212:215], v192 offset:36896
	ds_read_b128 v[216:219], v192 offset:41504
	s_waitcnt lgkmcnt(5)
	v_mfma_f32_32x32x16_bf16 v[80:95], v[200:203], v[228:231], v[80:95]
	v_mfma_f32_32x32x16_bf16 v[16:31], v[208:211], v[228:231], v[16:31]
	ds_read_b128 v[228:231], v184 offset:32
	s_waitcnt lgkmcnt(5)
	v_mfma_f32_32x32x16_bf16 v[64:79], v[200:203], v[232:235], v[64:79]
	v_mfma_f32_32x32x16_bf16 v[0:15], v[208:211], v[232:235], v[0:15]
	ds_read_b128 v[232:235], v184 offset:4640
	s_setprio 0
	global_load_dwordx4 v[200:203], v[136:137], off offset:2304
	global_load_dwordx4 v[208:211], v[140:141], off offset:2304
	s_setprio 1
	s_waitcnt lgkmcnt(1)
	v_mfma_f32_32x32x16_bf16 v[112:127], v[212:215], v[228:231], v[112:127]
	v_mfma_f32_32x32x16_bf16 v[48:63], v[216:219], v[228:231], v[48:63]
	s_waitcnt lgkmcnt(0)
	v_mfma_f32_32x32x16_bf16 v[96:111], v[212:215], v[232:235], v[96:111]
	v_mfma_f32_32x32x16_bf16 v[32:47], v[216:219], v[232:235], v[32:47]
	ds_read_b128 v[228:231], v184 offset:9248
	ds_read_b128 v[232:235], v184 offset:13856
	s_waitcnt vmcnt(7)
	ds_write_b128 v177, v[178:181]
	s_waitcnt vmcnt(6)
	ds_write_b128 v176, v[220:223]
	ds_read_b128 v[178:181], v192 offset:36928
	ds_read_b128 v[220:223], v192 offset:41536
	s_waitcnt lgkmcnt(5)
	v_mfma_f32_32x32x16_bf16 v[80:95], v[212:215], v[228:231], v[80:95]
	v_mfma_f32_32x32x16_bf16 v[16:31], v[216:219], v[228:231], v[16:31]
	ds_read_b128 v[228:231], v184 offset:64
	s_waitcnt lgkmcnt(5)
	v_mfma_f32_32x32x16_bf16 v[64:79], v[212:215], v[232:235], v[64:79]
	v_mfma_f32_32x32x16_bf16 v[0:15], v[216:219], v[232:235], v[0:15]
	ds_read_b128 v[232:235], v184 offset:4672
	s_setprio 0
	global_load_dwordx4 v[212:215], v[144:145], off offset:2304
	global_load_dwordx4 v[216:219], v[148:149], off offset:2304
	s_setprio 1
	s_waitcnt lgkmcnt(1)
	v_mfma_f32_32x32x16_bf16 v[112:127], v[178:181], v[228:231], v[112:127]
	v_mfma_f32_32x32x16_bf16 v[48:63], v[220:223], v[228:231], v[48:63]
	s_waitcnt lgkmcnt(0)
	v_mfma_f32_32x32x16_bf16 v[96:111], v[178:181], v[232:235], v[96:111]
	v_mfma_f32_32x32x16_bf16 v[32:47], v[220:223], v[232:235], v[32:47]
	ds_read_b128 v[228:231], v184 offset:9280
	ds_read_b128 v[232:235], v184 offset:13888
	s_waitcnt vmcnt(7)
	ds_write_b128 v171, v[172:175]
	s_waitcnt vmcnt(6)
	ds_write_b128 v170, v[224:227]
	ds_read_b128 v[172:175], v192 offset:36960
	ds_read_b128 v[224:227], v192 offset:41568
	s_waitcnt lgkmcnt(5)
	v_mfma_f32_32x32x16_bf16 v[80:95], v[178:181], v[228:231], v[80:95]
	v_mfma_f32_32x32x16_bf16 v[16:31], v[220:223], v[228:231], v[16:31]
	ds_read_b128 v[228:231], v184 offset:96
	s_waitcnt lgkmcnt(5)
	v_mfma_f32_32x32x16_bf16 v[64:79], v[178:181], v[232:235], v[64:79]
	v_mfma_f32_32x32x16_bf16 v[0:15], v[220:223], v[232:235], v[0:15]
	ds_read_b128 v[232:235], v184 offset:4704
	s_setprio 0
	global_load_dwordx4 v[178:181], v[152:153], off offset:2304
	global_load_dwordx4 v[220:223], v[156:157], off offset:2304
	s_setprio 1
	s_waitcnt lgkmcnt(1)
	v_mfma_f32_32x32x16_bf16 v[112:127], v[172:175], v[228:231], v[112:127]
	v_mfma_f32_32x32x16_bf16 v[48:63], v[224:227], v[228:231], v[48:63]
	s_waitcnt lgkmcnt(0)
	v_mfma_f32_32x32x16_bf16 v[96:111], v[172:175], v[232:235], v[96:111]
	v_mfma_f32_32x32x16_bf16 v[32:47], v[224:227], v[232:235], v[32:47]
	ds_read_b128 v[228:231], v184 offset:9312
	ds_read_b128 v[232:235], v184 offset:13920
	s_waitcnt lgkmcnt(0)
	s_barrier
; template <bool trans>
; DI void gemm_core(const GTile& tl, const GTile& nx, bool has_next  , bool chain  , bool pre, u32x4 (&ra)[4], u32x4 (&rb)[4], char* smem, f32x16 (&acc)[2][4]) {
;     ...
;   const int nk = K / 64;
;   if (!pre) { G_LOAD(0); G_STORE(0); G_LOAD(1); }
;   for (int kt = 0; kt < nk; ++kt) {
;     __syncthreads();
;     G_COMPUTE(kt & 1, kt);
;   }
	s_waitcnt vmcnt(7)
	ds_write_b128 v191, v[158:161]
	s_waitcnt vmcnt(6)
	ds_write_b128 v191, v[162:165] offset:36864
	ds_read_b128 v[158:161], v169
	ds_read_b128 v[162:165], v169 offset:4608
	v_mfma_f32_32x32x16_bf16 v[80:95], v[172:175], v[228:231], v[80:95]
	v_mfma_f32_32x32x16_bf16 v[16:31], v[224:227], v[228:231], v[16:31]
	ds_read_b128 v[228:231], v168
	v_mfma_f32_32x32x16_bf16 v[64:79], v[172:175], v[232:235], v[64:79]
	v_mfma_f32_32x32x16_bf16 v[0:15], v[224:227], v[232:235], v[0:15]
	ds_read_b128 v[232:235], v168 offset:4608
	s_setprio 0
	global_load_dwordx4 v[172:175], v[128:129], off offset:2432
	global_load_dwordx4 v[224:227], v[132:133], off offset:2432
	s_setprio 1
	s_waitcnt lgkmcnt(1)
	v_mfma_f32_32x32x16_bf16 v[112:127], v[158:161], v[228:231], v[112:127]
	v_mfma_f32_32x32x16_bf16 v[48:63], v[162:165], v[228:231], v[48:63]
	s_waitcnt lgkmcnt(0)
	v_mfma_f32_32x32x16_bf16 v[96:111], v[158:161], v[232:235], v[96:111]
	v_mfma_f32_32x32x16_bf16 v[32:47], v[162:165], v[232:235], v[32:47]
	ds_read_b128 v[228:231], v168 offset:9216
	ds_read_b128 v[232:235], v168 offset:13824
	s_waitcnt vmcnt(7)
	ds_write_b128 v191, v[200:203] offset:9216
	s_waitcnt vmcnt(6)
	ds_write_b128 v191, v[208:211] offset:46080
	ds_read_b128 v[200:203], v169 offset:32
	ds_read_b128 v[208:211], v169 offset:4640
	s_waitcnt lgkmcnt(5)
	v_mfma_f32_32x32x16_bf16 v[80:95], v[158:161], v[228:231], v[80:95]
	v_mfma_f32_32x32x16_bf16 v[16:31], v[162:165], v[228:231], v[16:31]
	ds_read_b128 v[228:231], v168 offset:32
	s_waitcnt lgkmcnt(5)
	v_mfma_f32_32x32x16_bf16 v[64:79], v[158:161], v[232:235], v[64:79]
	v_mfma_f32_32x32x16_bf16 v[0:15], v[162:165], v[232:235], v[0:15]
	ds_read_b128 v[232:235], v168 offset:4640
	s_setprio 0
	global_load_dwordx4 v[158:161], v[136:137], off offset:2432
	global_load_dwordx4 v[162:165], v[140:141], off offset:2432
	s_setprio 1
	s_waitcnt lgkmcnt(1)
	v_mfma_f32_32x32x16_bf16 v[112:127], v[200:203], v[228:231], v[112:127]
	v_mfma_f32_32x32x16_bf16 v[48:63], v[208:211], v[228:231], v[48:63]
	s_waitcnt lgkmcnt(0)
	v_mfma_f32_32x32x16_bf16 v[96:111], v[200:203], v[232:235], v[96:111]
	v_mfma_f32_32x32x16_bf16 v[32:47], v[208:211], v[232:235], v[32:47]
	ds_read_b128 v[228:231], v168 offset:9248
	ds_read_b128 v[232:235], v168 offset:13856
	s_waitcnt vmcnt(7)
	ds_write_b128 v191, v[212:215] offset:18432
	s_waitcnt vmcnt(6)
	ds_write_b128 v191, v[216:219] offset:55296
	ds_read_b128 v[212:215], v169 offset:64
	ds_read_b128 v[216:219], v169 offset:4672
	s_waitcnt lgkmcnt(5)
	v_mfma_f32_32x32x16_bf16 v[80:95], v[200:203], v[228:231], v[80:95]
	v_mfma_f32_32x32x16_bf16 v[16:31], v[208:211], v[228:231], v[16:31]
	ds_read_b128 v[228:231], v168 offset:64
	s_waitcnt lgkmcnt(5)
	v_mfma_f32_32x32x16_bf16 v[64:79], v[200:203], v[232:235], v[64:79]
	v_mfma_f32_32x32x16_bf16 v[0:15], v[208:211], v[232:235], v[0:15]
	ds_read_b128 v[232:235], v168 offset:4672
	s_setprio 0
	global_load_dwordx4 v[200:203], v[144:145], off offset:2432
	global_load_dwordx4 v[208:211], v[148:149], off offset:2432
	s_setprio 1
	s_waitcnt lgkmcnt(1)
	v_mfma_f32_32x32x16_bf16 v[112:127], v[212:215], v[228:231], v[112:127]
	v_mfma_f32_32x32x16_bf16 v[48:63], v[216:219], v[228:231], v[48:63]
	s_waitcnt lgkmcnt(0)
	v_mfma_f32_32x32x16_bf16 v[96:111], v[212:215], v[232:235], v[96:111]
	v_mfma_f32_32x32x16_bf16 v[32:47], v[216:219], v[232:235], v[32:47]
	ds_read_b128 v[228:231], v168 offset:9280
	ds_read_b128 v[232:235], v168 offset:13888
	s_waitcnt vmcnt(7)
	ds_write_b128 v191, v[178:181] offset:27648
	s_waitcnt vmcnt(6)
	ds_write_b128 v191, v[220:223] offset:64512
	ds_read_b128 v[178:181], v169 offset:96
	ds_read_b128 v[220:223], v169 offset:4704
	s_waitcnt lgkmcnt(5)
	v_mfma_f32_32x32x16_bf16 v[80:95], v[212:215], v[228:231], v[80:95]
	v_mfma_f32_32x32x16_bf16 v[16:31], v[216:219], v[228:231], v[16:31]
	ds_read_b128 v[228:231], v168 offset:96
	s_waitcnt lgkmcnt(5)
	v_mfma_f32_32x32x16_bf16 v[64:79], v[212:215], v[232:235], v[64:79]
	v_mfma_f32_32x32x16_bf16 v[0:15], v[216:219], v[232:235], v[0:15]
	ds_read_b128 v[232:235], v168 offset:4704
	s_setprio 0
	global_load_dwordx4 v[212:215], v[152:153], off offset:2432
	global_load_dwordx4 v[216:219], v[156:157], off offset:2432
	s_setprio 1
	s_waitcnt lgkmcnt(1)
	v_mfma_f32_32x32x16_bf16 v[112:127], v[178:181], v[228:231], v[112:127]
	v_mfma_f32_32x32x16_bf16 v[48:63], v[220:223], v[228:231], v[48:63]
	s_waitcnt lgkmcnt(0)
	v_mfma_f32_32x32x16_bf16 v[96:111], v[178:181], v[232:235], v[96:111]
	v_mfma_f32_32x32x16_bf16 v[32:47], v[220:223], v[232:235], v[32:47]
	ds_read_b128 v[228:231], v168 offset:9312
	ds_read_b128 v[232:235], v168 offset:13920
	s_waitcnt lgkmcnt(0)
	s_barrier
; template <bool trans>
; DI void gemm_core(const GTile& tl, const GTile& nx, bool has_next  , bool chain  , bool pre, u32x4 (&ra)[4], u32x4 (&rb)[4], char* smem, f32x16 (&acc)[2][4]) {
;     ...
;   const int nk = K / 64;
;   if (!pre) { G_LOAD(0); G_STORE(0); G_LOAD(1); }
;   for (int kt = 0; kt < nk; ++kt) {
;     __syncthreads();
;     G_COMPUTE(kt & 1, kt);
;   }
	s_waitcnt vmcnt(7)
	ds_write_b128 v195, v[172:175]
	s_waitcnt vmcnt(6)
	ds_write_b128 v196, v[224:227]
	ds_read_b128 v[172:175], v192 offset:36864
	ds_read_b128 v[224:227], v192 offset:41472
	v_mfma_f32_32x32x16_bf16 v[80:95], v[178:181], v[228:231], v[80:95]
	v_mfma_f32_32x32x16_bf16 v[16:31], v[220:223], v[228:231], v[16:31]
	ds_read_b128 v[228:231], v184
	v_mfma_f32_32x32x16_bf16 v[64:79], v[178:181], v[232:235], v[64:79]
	v_mfma_f32_32x32x16_bf16 v[0:15], v[220:223], v[232:235], v[0:15]
	ds_read_b128 v[232:235], v184 offset:4608
	s_setprio 0
	global_load_dwordx4 v[178:181], v[128:129], off offset:2560
	global_load_dwordx4 v[220:223], v[132:133], off offset:2560
	s_setprio 1
	s_waitcnt lgkmcnt(1)
	v_mfma_f32_32x32x16_bf16 v[112:127], v[172:175], v[228:231], v[112:127]
	v_mfma_f32_32x32x16_bf16 v[48:63], v[224:227], v[228:231], v[48:63]
	s_waitcnt lgkmcnt(0)
	v_mfma_f32_32x32x16_bf16 v[96:111], v[172:175], v[232:235], v[96:111]
	v_mfma_f32_32x32x16_bf16 v[32:47], v[224:227], v[232:235], v[32:47]
	ds_read_b128 v[228:231], v184 offset:9216
	ds_read_b128 v[232:235], v184 offset:13824
	s_waitcnt vmcnt(7)
	ds_write_b128 v194, v[158:161]
	s_waitcnt vmcnt(6)
	ds_write_b128 v193, v[162:165]
	ds_read_b128 v[158:161], v192 offset:36896
	ds_read_b128 v[162:165], v192 offset:41504
	s_waitcnt lgkmcnt(5)
	v_mfma_f32_32x32x16_bf16 v[80:95], v[172:175], v[228:231], v[80:95]
	v_mfma_f32_32x32x16_bf16 v[16:31], v[224:227], v[228:231], v[16:31]
	ds_read_b128 v[228:231], v184 offset:32
	s_waitcnt lgkmcnt(5)
	v_mfma_f32_32x32x16_bf16 v[64:79], v[172:175], v[232:235], v[64:79]
	v_mfma_f32_32x32x16_bf16 v[0:15], v[224:227], v[232:235], v[0:15]
	ds_read_b128 v[232:235], v184 offset:4640
	s_setprio 0
	global_load_dwordx4 v[172:175], v[136:137], off offset:2560
	global_load_dwordx4 v[224:227], v[140:141], off offset:2560
	s_setprio 1
	s_waitcnt lgkmcnt(1)
	v_mfma_f32_32x32x16_bf16 v[112:127], v[158:161], v[228:231], v[112:127]
	v_mfma_f32_32x32x16_bf16 v[48:63], v[162:165], v[228:231], v[48:63]
	s_waitcnt lgkmcnt(0)
	v_mfma_f32_32x32x16_bf16 v[96:111], v[158:161], v[232:235], v[96:111]
	v_mfma_f32_32x32x16_bf16 v[32:47], v[162:165], v[232:235], v[32:47]
	ds_read_b128 v[228:231], v184 offset:9248
	ds_read_b128 v[232:235], v184 offset:13856
	s_waitcnt vmcnt(7)
	ds_write_b128 v177, v[200:203]
	s_waitcnt vmcnt(6)
	ds_write_b128 v176, v[208:211]
	ds_read_b128 v[200:203], v192 offset:36928
	ds_read_b128 v[208:211], v192 offset:41536
	s_waitcnt lgkmcnt(5)
	v_mfma_f32_32x32x16_bf16 v[80:95], v[158:161], v[228:231], v[80:95]
	v_mfma_f32_32x32x16_bf16 v[16:31], v[162:165], v[228:231], v[16:31]
	ds_read_b128 v[228:231], v184 offset:64
	s_waitcnt lgkmcnt(5)
	v_mfma_f32_32x32x16_bf16 v[64:79], v[158:161], v[232:235], v[64:79]
	v_mfma_f32_32x32x16_bf16 v[0:15], v[162:165], v[232:235], v[0:15]
	ds_read_b128 v[232:235], v184 offset:4672
	s_setprio 0
	global_load_dwordx4 v[158:161], v[144:145], off offset:2560
	global_load_dwordx4 v[162:165], v[148:149], off offset:2560
	s_setprio 1
	s_waitcnt lgkmcnt(1)
	v_mfma_f32_32x32x16_bf16 v[112:127], v[200:203], v[228:231], v[112:127]
	v_mfma_f32_32x32x16_bf16 v[48:63], v[208:211], v[228:231], v[48:63]
	s_waitcnt lgkmcnt(0)
	v_mfma_f32_32x32x16_bf16 v[96:111], v[200:203], v[232:235], v[96:111]
	v_mfma_f32_32x32x16_bf16 v[32:47], v[208:211], v[232:235], v[32:47]
	ds_read_b128 v[228:231], v184 offset:9280
	ds_read_b128 v[232:235], v184 offset:13888
	s_waitcnt vmcnt(7)
	ds_write_b128 v171, v[212:215]
	s_waitcnt vmcnt(6)
	ds_write_b128 v170, v[216:219]
	ds_read_b128 v[212:215], v192 offset:36960
	ds_read_b128 v[216:219], v192 offset:41568
	s_waitcnt lgkmcnt(5)
	v_mfma_f32_32x32x16_bf16 v[80:95], v[200:203], v[228:231], v[80:95]
	v_mfma_f32_32x32x16_bf16 v[16:31], v[208:211], v[228:231], v[16:31]
	ds_read_b128 v[228:231], v184 offset:96
	s_waitcnt lgkmcnt(5)
	v_mfma_f32_32x32x16_bf16 v[64:79], v[200:203], v[232:235], v[64:79]
	v_mfma_f32_32x32x16_bf16 v[0:15], v[208:211], v[232:235], v[0:15]
	ds_read_b128 v[232:235], v184 offset:4704
	s_setprio 0
	global_load_dwordx4 v[200:203], v[152:153], off offset:2560
	global_load_dwordx4 v[208:211], v[156:157], off offset:2560
	s_setprio 1
	s_waitcnt lgkmcnt(1)
	v_mfma_f32_32x32x16_bf16 v[112:127], v[212:215], v[228:231], v[112:127]
	v_mfma_f32_32x32x16_bf16 v[48:63], v[216:219], v[228:231], v[48:63]
	s_waitcnt lgkmcnt(0)
	v_mfma_f32_32x32x16_bf16 v[96:111], v[212:215], v[232:235], v[96:111]
	v_mfma_f32_32x32x16_bf16 v[32:47], v[216:219], v[232:235], v[32:47]
	ds_read_b128 v[228:231], v184 offset:9312
	ds_read_b128 v[232:235], v184 offset:13920
	s_waitcnt lgkmcnt(0)
	s_barrier
; template <bool trans>
; DI void gemm_core(const GTile& tl, const GTile& nx, bool has_next  , bool chain  , bool pre, u32x4 (&ra)[4], u32x4 (&rb)[4], char* smem, f32x16 (&acc)[2][4]) {
;     ...
;   const int nk = K / 64;
;   if (!pre) { G_LOAD(0); G_STORE(0); G_LOAD(1); }
;   for (int kt = 0; kt < nk; ++kt) {
;     __syncthreads();
;     G_COMPUTE(kt & 1, kt);
;   }
	s_waitcnt vmcnt(7)
	ds_write_b128 v191, v[178:181]
	s_waitcnt vmcnt(6)
	ds_write_b128 v191, v[220:223] offset:36864
	ds_read_b128 v[178:181], v169
	ds_read_b128 v[220:223], v169 offset:4608
	v_mfma_f32_32x32x16_bf16 v[80:95], v[212:215], v[228:231], v[80:95]
	v_mfma_f32_32x32x16_bf16 v[16:31], v[216:219], v[228:231], v[16:31]
	ds_read_b128 v[228:231], v168
	v_mfma_f32_32x32x16_bf16 v[64:79], v[212:215], v[232:235], v[64:79]
	v_mfma_f32_32x32x16_bf16 v[0:15], v[216:219], v[232:235], v[0:15]
	ds_read_b128 v[232:235], v168 offset:4608
	s_setprio 0
	global_load_dwordx4 v[212:215], v[128:129], off offset:2688
	global_load_dwordx4 v[216:219], v[132:133], off offset:2688
	s_setprio 1
	s_waitcnt lgkmcnt(1)
	v_mfma_f32_32x32x16_bf16 v[112:127], v[178:181], v[228:231], v[112:127]
	v_mfma_f32_32x32x16_bf16 v[48:63], v[220:223], v[228:231], v[48:63]
	s_waitcnt lgkmcnt(0)
	v_mfma_f32_32x32x16_bf16 v[96:111], v[178:181], v[232:235], v[96:111]
	v_mfma_f32_32x32x16_bf16 v[32:47], v[220:223], v[232:235], v[32:47]
	ds_read_b128 v[228:231], v168 offset:9216
	ds_read_b128 v[232:235], v168 offset:13824
	s_waitcnt vmcnt(7)
	ds_write_b128 v191, v[172:175] offset:9216
	s_waitcnt vmcnt(6)
	ds_write_b128 v191, v[224:227] offset:46080
	ds_read_b128 v[172:175], v169 offset:32
	ds_read_b128 v[224:227], v169 offset:4640
	s_waitcnt lgkmcnt(5)
	v_mfma_f32_32x32x16_bf16 v[80:95], v[178:181], v[228:231], v[80:95]
	v_mfma_f32_32x32x16_bf16 v[16:31], v[220:223], v[228:231], v[16:31]
	ds_read_b128 v[228:231], v168 offset:32
	s_waitcnt lgkmcnt(5)
	v_mfma_f32_32x32x16_bf16 v[64:79], v[178:181], v[232:235], v[64:79]
	v_mfma_f32_32x32x16_bf16 v[0:15], v[220:223], v[232:235], v[0:15]
	ds_read_b128 v[232:235], v168 offset:4640
	s_setprio 0
	global_load_dwordx4 v[178:181], v[136:137], off offset:2688
	global_load_dwordx4 v[220:223], v[140:141], off offset:2688
	s_setprio 1
	s_waitcnt lgkmcnt(1)
	v_mfma_f32_32x32x16_bf16 v[112:127], v[172:175], v[228:231], v[112:127]
	v_mfma_f32_32x32x16_bf16 v[48:63], v[224:227], v[228:231], v[48:63]
	s_waitcnt lgkmcnt(0)
	v_mfma_f32_32x32x16_bf16 v[96:111], v[172:175], v[232:235], v[96:111]
	v_mfma_f32_32x32x16_bf16 v[32:47], v[224:227], v[232:235], v[32:47]
	ds_read_b128 v[228:231], v168 offset:9248
	ds_read_b128 v[232:235], v168 offset:13856
	s_waitcnt vmcnt(7)
	ds_write_b128 v191, v[158:161] offset:18432
	s_waitcnt vmcnt(6)
	ds_write_b128 v191, v[162:165] offset:55296
	ds_read_b128 v[158:161], v169 offset:64
	ds_read_b128 v[162:165], v169 offset:4672
	s_waitcnt lgkmcnt(5)
	v_mfma_f32_32x32x16_bf16 v[80:95], v[172:175], v[228:231], v[80:95]
	v_mfma_f32_32x32x16_bf16 v[16:31], v[224:227], v[228:231], v[16:31]
	ds_read_b128 v[228:231], v168 offset:64
	s_waitcnt lgkmcnt(5)
	v_mfma_f32_32x32x16_bf16 v[64:79], v[172:175], v[232:235], v[64:79]
	v_mfma_f32_32x32x16_bf16 v[0:15], v[224:227], v[232:235], v[0:15]
	ds_read_b128 v[232:235], v168 offset:4672
	s_setprio 0
	global_load_dwordx4 v[172:175], v[144:145], off offset:2688
	global_load_dwordx4 v[224:227], v[148:149], off offset:2688
	s_setprio 1
	s_waitcnt lgkmcnt(1)
	v_mfma_f32_32x32x16_bf16 v[112:127], v[158:161], v[228:231], v[112:127]
	v_mfma_f32_32x32x16_bf16 v[48:63], v[162:165], v[228:231], v[48:63]
	s_waitcnt lgkmcnt(0)
	v_mfma_f32_32x32x16_bf16 v[96:111], v[158:161], v[232:235], v[96:111]
	v_mfma_f32_32x32x16_bf16 v[32:47], v[162:165], v[232:235], v[32:47]
	ds_read_b128 v[228:231], v168 offset:9280
	ds_read_b128 v[232:235], v168 offset:13888
	s_waitcnt vmcnt(7)
	ds_write_b128 v191, v[200:203] offset:27648
	s_waitcnt vmcnt(6)
	ds_write_b128 v191, v[208:211] offset:64512
	ds_read_b128 v[200:203], v169 offset:96
	ds_read_b128 v[208:211], v169 offset:4704
	s_waitcnt lgkmcnt(5)
	v_mfma_f32_32x32x16_bf16 v[80:95], v[158:161], v[228:231], v[80:95]
	v_mfma_f32_32x32x16_bf16 v[16:31], v[162:165], v[228:231], v[16:31]
	ds_read_b128 v[228:231], v168 offset:96
	s_waitcnt lgkmcnt(5)
	v_mfma_f32_32x32x16_bf16 v[64:79], v[158:161], v[232:235], v[64:79]
	v_mfma_f32_32x32x16_bf16 v[0:15], v[162:165], v[232:235], v[0:15]
	ds_read_b128 v[232:235], v168 offset:4704
	s_setprio 0
	global_load_dwordx4 v[158:161], v[152:153], off offset:2688
	global_load_dwordx4 v[162:165], v[156:157], off offset:2688
	s_setprio 1
	s_waitcnt lgkmcnt(1)
	v_mfma_f32_32x32x16_bf16 v[112:127], v[200:203], v[228:231], v[112:127]
	v_mfma_f32_32x32x16_bf16 v[48:63], v[208:211], v[228:231], v[48:63]
	s_waitcnt lgkmcnt(0)
	v_mfma_f32_32x32x16_bf16 v[96:111], v[200:203], v[232:235], v[96:111]
	v_mfma_f32_32x32x16_bf16 v[32:47], v[208:211], v[232:235], v[32:47]
	ds_read_b128 v[228:231], v168 offset:9312
	ds_read_b128 v[232:235], v168 offset:13920
	s_waitcnt lgkmcnt(0)
	s_barrier
; template <bool trans>
; DI void gemm_core(const GTile& tl, const GTile& nx, bool has_next  , bool chain  , bool pre, u32x4 (&ra)[4], u32x4 (&rb)[4], char* smem, f32x16 (&acc)[2][4]) {
;     ...
;   const int nk = K / 64;
;   if (!pre) { G_LOAD(0); G_STORE(0); G_LOAD(1); }
;   for (int kt = 0; kt < nk; ++kt) {
;     __syncthreads();
;     G_COMPUTE(kt & 1, kt);
;   }
	s_waitcnt vmcnt(7)
	ds_write_b128 v195, v[212:215]
	s_waitcnt vmcnt(6)
	ds_write_b128 v196, v[216:219]
	ds_read_b128 v[212:215], v192 offset:36864
	ds_read_b128 v[216:219], v192 offset:41472
	v_mfma_f32_32x32x16_bf16 v[80:95], v[200:203], v[228:231], v[80:95]
	v_mfma_f32_32x32x16_bf16 v[16:31], v[208:211], v[228:231], v[16:31]
	ds_read_b128 v[228:231], v184
	v_mfma_f32_32x32x16_bf16 v[64:79], v[200:203], v[232:235], v[64:79]
	v_mfma_f32_32x32x16_bf16 v[0:15], v[208:211], v[232:235], v[0:15]
	ds_read_b128 v[232:235], v184 offset:4608
	s_setprio 0
	global_load_dwordx4 v[200:203], v[128:129], off offset:2816
	global_load_dwordx4 v[208:211], v[132:133], off offset:2816
	s_setprio 1
	s_waitcnt lgkmcnt(1)
	v_mfma_f32_32x32x16_bf16 v[112:127], v[212:215], v[228:231], v[112:127]
	v_mfma_f32_32x32x16_bf16 v[48:63], v[216:219], v[228:231], v[48:63]
	s_waitcnt lgkmcnt(0)
	v_mfma_f32_32x32x16_bf16 v[96:111], v[212:215], v[232:235], v[96:111]
	v_mfma_f32_32x32x16_bf16 v[32:47], v[216:219], v[232:235], v[32:47]
	ds_read_b128 v[228:231], v184 offset:9216
	ds_read_b128 v[232:235], v184 offset:13824
	s_waitcnt vmcnt(7)
	ds_write_b128 v194, v[178:181]
	s_waitcnt vmcnt(6)
	ds_write_b128 v193, v[220:223]
	ds_read_b128 v[178:181], v192 offset:36896
	ds_read_b128 v[220:223], v192 offset:41504
	s_waitcnt lgkmcnt(5)
	v_mfma_f32_32x32x16_bf16 v[80:95], v[212:215], v[228:231], v[80:95]
	v_mfma_f32_32x32x16_bf16 v[16:31], v[216:219], v[228:231], v[16:31]
	ds_read_b128 v[228:231], v184 offset:32
	s_waitcnt lgkmcnt(5)
	v_mfma_f32_32x32x16_bf16 v[64:79], v[212:215], v[232:235], v[64:79]
	v_mfma_f32_32x32x16_bf16 v[0:15], v[216:219], v[232:235], v[0:15]
	ds_read_b128 v[232:235], v184 offset:4640
	s_setprio 0
	global_load_dwordx4 v[212:215], v[136:137], off offset:2816
	global_load_dwordx4 v[216:219], v[140:141], off offset:2816
	s_setprio 1
	s_waitcnt lgkmcnt(1)
	v_mfma_f32_32x32x16_bf16 v[112:127], v[178:181], v[228:231], v[112:127]
	v_mfma_f32_32x32x16_bf16 v[48:63], v[220:223], v[228:231], v[48:63]
	s_waitcnt lgkmcnt(0)
	v_mfma_f32_32x32x16_bf16 v[96:111], v[178:181], v[232:235], v[96:111]
	v_mfma_f32_32x32x16_bf16 v[32:47], v[220:223], v[232:235], v[32:47]
	ds_read_b128 v[228:231], v184 offset:9248
	ds_read_b128 v[232:235], v184 offset:13856
	s_waitcnt vmcnt(7)
	ds_write_b128 v177, v[172:175]
	s_waitcnt vmcnt(6)
	ds_write_b128 v176, v[224:227]
	ds_read_b128 v[172:175], v192 offset:36928
	ds_read_b128 v[224:227], v192 offset:41536
	s_waitcnt lgkmcnt(5)
	v_mfma_f32_32x32x16_bf16 v[80:95], v[178:181], v[228:231], v[80:95]
	v_mfma_f32_32x32x16_bf16 v[16:31], v[220:223], v[228:231], v[16:31]
	ds_read_b128 v[228:231], v184 offset:64
	s_waitcnt lgkmcnt(5)
	v_mfma_f32_32x32x16_bf16 v[64:79], v[178:181], v[232:235], v[64:79]
	v_mfma_f32_32x32x16_bf16 v[0:15], v[220:223], v[232:235], v[0:15]
	ds_read_b128 v[232:235], v184 offset:4672
	s_setprio 0
	global_load_dwordx4 v[178:181], v[144:145], off offset:2816
	global_load_dwordx4 v[220:223], v[148:149], off offset:2816
	s_setprio 1
	s_waitcnt lgkmcnt(1)
	v_mfma_f32_32x32x16_bf16 v[112:127], v[172:175], v[228:231], v[112:127]
	v_mfma_f32_32x32x16_bf16 v[48:63], v[224:227], v[228:231], v[48:63]
	s_waitcnt lgkmcnt(0)
	v_mfma_f32_32x32x16_bf16 v[96:111], v[172:175], v[232:235], v[96:111]
	v_mfma_f32_32x32x16_bf16 v[32:47], v[224:227], v[232:235], v[32:47]
	ds_read_b128 v[228:231], v184 offset:9280
	ds_read_b128 v[232:235], v184 offset:13888
	s_waitcnt vmcnt(7)
	ds_write_b128 v171, v[158:161]
	s_waitcnt vmcnt(6)
	ds_write_b128 v170, v[162:165]
	ds_read_b128 v[158:161], v192 offset:36960
	ds_read_b128 v[162:165], v192 offset:41568
	s_waitcnt lgkmcnt(5)
	v_mfma_f32_32x32x16_bf16 v[80:95], v[172:175], v[228:231], v[80:95]
	v_mfma_f32_32x32x16_bf16 v[16:31], v[224:227], v[228:231], v[16:31]
	ds_read_b128 v[228:231], v184 offset:96
	s_waitcnt lgkmcnt(5)
	v_mfma_f32_32x32x16_bf16 v[64:79], v[172:175], v[232:235], v[64:79]
	v_mfma_f32_32x32x16_bf16 v[0:15], v[224:227], v[232:235], v[0:15]
	ds_read_b128 v[232:235], v184 offset:4704
	s_setprio 0
	global_load_dwordx4 v[172:175], v[152:153], off offset:2816
	global_load_dwordx4 v[224:227], v[156:157], off offset:2816
	s_setprio 1
	s_waitcnt lgkmcnt(1)
	v_mfma_f32_32x32x16_bf16 v[112:127], v[158:161], v[228:231], v[112:127]
	v_mfma_f32_32x32x16_bf16 v[48:63], v[162:165], v[228:231], v[48:63]
	s_waitcnt lgkmcnt(0)
	v_mfma_f32_32x32x16_bf16 v[96:111], v[158:161], v[232:235], v[96:111]
	v_mfma_f32_32x32x16_bf16 v[32:47], v[162:165], v[232:235], v[32:47]
	ds_read_b128 v[228:231], v184 offset:9312
	ds_read_b128 v[232:235], v184 offset:13920
	s_waitcnt lgkmcnt(0)
	s_barrier
; template <bool trans>
; DI void gemm_core(const GTile& tl, const GTile& nx, bool has_next  , bool chain  , bool pre, u32x4 (&ra)[4], u32x4 (&rb)[4], char* smem, f32x16 (&acc)[2][4]) {
;     ...
;   const int nk = K / 64;
;   if (!pre) { G_LOAD(0); G_STORE(0); G_LOAD(1); }
;   for (int kt = 0; kt < nk; ++kt) {
;     __syncthreads();
;     G_COMPUTE(kt & 1, kt);
;   }
	s_waitcnt vmcnt(7)
	ds_write_b128 v191, v[200:203]
	s_waitcnt vmcnt(6)
	ds_write_b128 v191, v[208:211] offset:36864
	ds_read_b128 v[200:203], v169
	ds_read_b128 v[208:211], v169 offset:4608
	v_mfma_f32_32x32x16_bf16 v[80:95], v[158:161], v[228:231], v[80:95]
	v_mfma_f32_32x32x16_bf16 v[16:31], v[162:165], v[228:231], v[16:31]
	ds_read_b128 v[228:231], v168
	v_mfma_f32_32x32x16_bf16 v[64:79], v[158:161], v[232:235], v[64:79]
	v_mfma_f32_32x32x16_bf16 v[0:15], v[162:165], v[232:235], v[0:15]
	ds_read_b128 v[232:235], v168 offset:4608
	s_setprio 0
	global_load_dwordx4 v[158:161], v[128:129], off offset:2944
	global_load_dwordx4 v[162:165], v[132:133], off offset:2944
	s_setprio 1
	s_waitcnt lgkmcnt(1)
	v_mfma_f32_32x32x16_bf16 v[112:127], v[200:203], v[228:231], v[112:127]
	v_mfma_f32_32x32x16_bf16 v[48:63], v[208:211], v[228:231], v[48:63]
	s_waitcnt lgkmcnt(0)
	v_mfma_f32_32x32x16_bf16 v[96:111], v[200:203], v[232:235], v[96:111]
	v_mfma_f32_32x32x16_bf16 v[32:47], v[208:211], v[232:235], v[32:47]
	ds_read_b128 v[228:231], v168 offset:9216
	ds_read_b128 v[232:235], v168 offset:13824
	s_waitcnt vmcnt(7)
	ds_write_b128 v191, v[212:215] offset:9216
	s_waitcnt vmcnt(6)
	ds_write_b128 v191, v[216:219] offset:46080
	ds_read_b128 v[212:215], v169 offset:32
	ds_read_b128 v[216:219], v169 offset:4640
	s_waitcnt lgkmcnt(5)
	v_mfma_f32_32x32x16_bf16 v[80:95], v[200:203], v[228:231], v[80:95]
	v_mfma_f32_32x32x16_bf16 v[16:31], v[208:211], v[228:231], v[16:31]
	ds_read_b128 v[228:231], v168 offset:32
	s_waitcnt lgkmcnt(5)
	v_mfma_f32_32x32x16_bf16 v[64:79], v[200:203], v[232:235], v[64:79]
	v_mfma_f32_32x32x16_bf16 v[0:15], v[208:211], v[232:235], v[0:15]
	ds_read_b128 v[232:235], v168 offset:4640
	s_setprio 0
	global_load_dwordx4 v[200:203], v[136:137], off offset:2944
	global_load_dwordx4 v[208:211], v[140:141], off offset:2944
	s_setprio 1
	s_waitcnt lgkmcnt(1)
	v_mfma_f32_32x32x16_bf16 v[112:127], v[212:215], v[228:231], v[112:127]
	v_mfma_f32_32x32x16_bf16 v[48:63], v[216:219], v[228:231], v[48:63]
	s_waitcnt lgkmcnt(0)
	v_mfma_f32_32x32x16_bf16 v[96:111], v[212:215], v[232:235], v[96:111]
	v_mfma_f32_32x32x16_bf16 v[32:47], v[216:219], v[232:235], v[32:47]
	ds_read_b128 v[228:231], v168 offset:9248
	ds_read_b128 v[232:235], v168 offset:13856
	s_waitcnt vmcnt(7)
	ds_write_b128 v191, v[178:181] offset:18432
	s_waitcnt vmcnt(6)
	ds_write_b128 v191, v[220:223] offset:55296
	ds_read_b128 v[178:181], v169 offset:64
	ds_read_b128 v[220:223], v169 offset:4672
	s_waitcnt lgkmcnt(5)
	v_mfma_f32_32x32x16_bf16 v[80:95], v[212:215], v[228:231], v[80:95]
	v_mfma_f32_32x32x16_bf16 v[16:31], v[216:219], v[228:231], v[16:31]
	ds_read_b128 v[228:231], v168 offset:64
	s_waitcnt lgkmcnt(5)
	v_mfma_f32_32x32x16_bf16 v[64:79], v[212:215], v[232:235], v[64:79]
	v_mfma_f32_32x32x16_bf16 v[0:15], v[216:219], v[232:235], v[0:15]
	ds_read_b128 v[232:235], v168 offset:4672
	s_setprio 0
	global_load_dwordx4 v[212:215], v[144:145], off offset:2944
	global_load_dwordx4 v[216:219], v[148:149], off offset:2944
	s_setprio 1
	s_waitcnt lgkmcnt(1)
	v_mfma_f32_32x32x16_bf16 v[112:127], v[178:181], v[228:231], v[112:127]
	v_mfma_f32_32x32x16_bf16 v[48:63], v[220:223], v[228:231], v[48:63]
	s_waitcnt lgkmcnt(0)
	v_mfma_f32_32x32x16_bf16 v[96:111], v[178:181], v[232:235], v[96:111]
	v_mfma_f32_32x32x16_bf16 v[32:47], v[220:223], v[232:235], v[32:47]
	ds_read_b128 v[228:231], v168 offset:9280
	ds_read_b128 v[232:235], v168 offset:13888
	s_waitcnt vmcnt(7)
	ds_write_b128 v191, v[172:175] offset:27648
	s_waitcnt vmcnt(6)
	ds_write_b128 v191, v[224:227] offset:64512
	ds_read_b128 v[172:175], v169 offset:96
	ds_read_b128 v[224:227], v169 offset:4704
	s_waitcnt lgkmcnt(5)
	v_mfma_f32_32x32x16_bf16 v[80:95], v[178:181], v[228:231], v[80:95]
	v_mfma_f32_32x32x16_bf16 v[16:31], v[220:223], v[228:231], v[16:31]
	ds_read_b128 v[228:231], v168 offset:96
	s_waitcnt lgkmcnt(5)
	v_mfma_f32_32x32x16_bf16 v[64:79], v[178:181], v[232:235], v[64:79]
	v_mfma_f32_32x32x16_bf16 v[0:15], v[220:223], v[232:235], v[0:15]
	ds_read_b128 v[232:235], v168 offset:4704
	s_setprio 0
	global_load_dwordx4 v[178:181], v[152:153], off offset:2944
	global_load_dwordx4 v[220:223], v[156:157], off offset:2944
	s_setprio 1
	s_waitcnt lgkmcnt(1)
	v_mfma_f32_32x32x16_bf16 v[112:127], v[172:175], v[228:231], v[112:127]
	v_mfma_f32_32x32x16_bf16 v[48:63], v[224:227], v[228:231], v[48:63]
	s_waitcnt lgkmcnt(0)
	v_mfma_f32_32x32x16_bf16 v[96:111], v[172:175], v[232:235], v[96:111]
	v_mfma_f32_32x32x16_bf16 v[32:47], v[224:227], v[232:235], v[32:47]
	ds_read_b128 v[228:231], v168 offset:9312
	ds_read_b128 v[232:235], v168 offset:13920
	s_waitcnt lgkmcnt(0)
	s_barrier
; template <bool trans>
; DI void gemm_core(const GTile& tl, const GTile& nx, bool has_next  , bool chain  , bool pre, u32x4 (&ra)[4], u32x4 (&rb)[4], char* smem, f32x16 (&acc)[2][4]) {
;     ...
;   const int nk = K / 64;
;   if (!pre) { G_LOAD(0); G_STORE(0); G_LOAD(1); }
;   for (int kt = 0; kt < nk; ++kt) {
;     __syncthreads();
;     G_COMPUTE(kt & 1, kt);
;   }
	s_waitcnt vmcnt(7)
	ds_write_b128 v195, v[158:161]
	s_waitcnt vmcnt(6)
	ds_write_b128 v196, v[162:165]
	ds_read_b128 v[158:161], v192 offset:36864
	ds_read_b128 v[162:165], v192 offset:41472
	v_mfma_f32_32x32x16_bf16 v[80:95], v[172:175], v[228:231], v[80:95]
	v_mfma_f32_32x32x16_bf16 v[16:31], v[224:227], v[228:231], v[16:31]
	ds_read_b128 v[228:231], v184
	v_mfma_f32_32x32x16_bf16 v[64:79], v[172:175], v[232:235], v[64:79]
	v_mfma_f32_32x32x16_bf16 v[0:15], v[224:227], v[232:235], v[0:15]
	ds_read_b128 v[232:235], v184 offset:4608
	s_setprio 0
	global_load_dwordx4 v[172:175], v[128:129], off offset:3072
	global_load_dwordx4 v[224:227], v[132:133], off offset:3072
	s_setprio 1
	s_waitcnt lgkmcnt(1)
	v_mfma_f32_32x32x16_bf16 v[112:127], v[158:161], v[228:231], v[112:127]
	v_mfma_f32_32x32x16_bf16 v[48:63], v[162:165], v[228:231], v[48:63]
	s_waitcnt lgkmcnt(0)
	v_mfma_f32_32x32x16_bf16 v[96:111], v[158:161], v[232:235], v[96:111]
	v_mfma_f32_32x32x16_bf16 v[32:47], v[162:165], v[232:235], v[32:47]
	ds_read_b128 v[228:231], v184 offset:9216
	ds_read_b128 v[232:235], v184 offset:13824
	s_waitcnt vmcnt(7)
	ds_write_b128 v194, v[200:203]
	s_waitcnt vmcnt(6)
	ds_write_b128 v193, v[208:211]
	ds_read_b128 v[200:203], v192 offset:36896
	ds_read_b128 v[208:211], v192 offset:41504
	s_waitcnt lgkmcnt(5)
	v_mfma_f32_32x32x16_bf16 v[80:95], v[158:161], v[228:231], v[80:95]
	v_mfma_f32_32x32x16_bf16 v[16:31], v[162:165], v[228:231], v[16:31]
	ds_read_b128 v[228:231], v184 offset:32
	s_waitcnt lgkmcnt(5)
	v_mfma_f32_32x32x16_bf16 v[64:79], v[158:161], v[232:235], v[64:79]
	v_mfma_f32_32x32x16_bf16 v[0:15], v[162:165], v[232:235], v[0:15]
	ds_read_b128 v[232:235], v184 offset:4640
	s_setprio 0
	global_load_dwordx4 v[158:161], v[136:137], off offset:3072
	global_load_dwordx4 v[162:165], v[140:141], off offset:3072
	s_setprio 1
	s_waitcnt lgkmcnt(1)
	v_mfma_f32_32x32x16_bf16 v[112:127], v[200:203], v[228:231], v[112:127]
	v_mfma_f32_32x32x16_bf16 v[48:63], v[208:211], v[228:231], v[48:63]
	s_waitcnt lgkmcnt(0)
	v_mfma_f32_32x32x16_bf16 v[96:111], v[200:203], v[232:235], v[96:111]
	v_mfma_f32_32x32x16_bf16 v[32:47], v[208:211], v[232:235], v[32:47]
	ds_read_b128 v[228:231], v184 offset:9248
	ds_read_b128 v[232:235], v184 offset:13856
	s_waitcnt vmcnt(7)
	ds_write_b128 v177, v[212:215]
	s_waitcnt vmcnt(6)
	ds_write_b128 v176, v[216:219]
	ds_read_b128 v[212:215], v192 offset:36928
	ds_read_b128 v[216:219], v192 offset:41536
	s_waitcnt lgkmcnt(5)
	v_mfma_f32_32x32x16_bf16 v[80:95], v[200:203], v[228:231], v[80:95]
	v_mfma_f32_32x32x16_bf16 v[16:31], v[208:211], v[228:231], v[16:31]
	ds_read_b128 v[228:231], v184 offset:64
	s_waitcnt lgkmcnt(5)
	v_mfma_f32_32x32x16_bf16 v[64:79], v[200:203], v[232:235], v[64:79]
	v_mfma_f32_32x32x16_bf16 v[0:15], v[208:211], v[232:235], v[0:15]
	ds_read_b128 v[232:235], v184 offset:4672
	s_setprio 0
	global_load_dwordx4 v[200:203], v[144:145], off offset:3072
	global_load_dwordx4 v[208:211], v[148:149], off offset:3072
	s_setprio 1
	s_waitcnt lgkmcnt(1)
	v_mfma_f32_32x32x16_bf16 v[112:127], v[212:215], v[228:231], v[112:127]
	v_mfma_f32_32x32x16_bf16 v[48:63], v[216:219], v[228:231], v[48:63]
	s_waitcnt lgkmcnt(0)
	v_mfma_f32_32x32x16_bf16 v[96:111], v[212:215], v[232:235], v[96:111]
	v_mfma_f32_32x32x16_bf16 v[32:47], v[216:219], v[232:235], v[32:47]
	ds_read_b128 v[228:231], v184 offset:9280
	ds_read_b128 v[232:235], v184 offset:13888
	s_waitcnt vmcnt(7)
	ds_write_b128 v171, v[178:181]
	s_waitcnt vmcnt(6)
	ds_write_b128 v170, v[220:223]
	ds_read_b128 v[178:181], v192 offset:36960
	ds_read_b128 v[220:223], v192 offset:41568
	s_waitcnt lgkmcnt(5)
	v_mfma_f32_32x32x16_bf16 v[80:95], v[212:215], v[228:231], v[80:95]
	v_mfma_f32_32x32x16_bf16 v[16:31], v[216:219], v[228:231], v[16:31]
	ds_read_b128 v[228:231], v184 offset:96
	s_waitcnt lgkmcnt(5)
	v_mfma_f32_32x32x16_bf16 v[64:79], v[212:215], v[232:235], v[64:79]
	v_mfma_f32_32x32x16_bf16 v[0:15], v[216:219], v[232:235], v[0:15]
	ds_read_b128 v[232:235], v184 offset:4704
	s_setprio 0
	global_load_dwordx4 v[212:215], v[152:153], off offset:3072
	global_load_dwordx4 v[216:219], v[156:157], off offset:3072
	s_setprio 1
	s_waitcnt lgkmcnt(1)
	v_mfma_f32_32x32x16_bf16 v[112:127], v[178:181], v[228:231], v[112:127]
	v_mfma_f32_32x32x16_bf16 v[48:63], v[220:223], v[228:231], v[48:63]
	s_waitcnt lgkmcnt(0)
	v_mfma_f32_32x32x16_bf16 v[96:111], v[178:181], v[232:235], v[96:111]
	v_mfma_f32_32x32x16_bf16 v[32:47], v[220:223], v[232:235], v[32:47]
	ds_read_b128 v[228:231], v184 offset:9312
	ds_read_b128 v[232:235], v184 offset:13920
	s_waitcnt lgkmcnt(0)
	s_barrier
; template <bool trans>
; DI void gemm_core(const GTile& tl, const GTile& nx, bool has_next  , bool chain  , bool pre, u32x4 (&ra)[4], u32x4 (&rb)[4], char* smem, f32x16 (&acc)[2][4]) {
;     ...
;   const int nk = K / 64;
;   if (!pre) { G_LOAD(0); G_STORE(0); G_LOAD(1); }
;   for (int kt = 0; kt < nk; ++kt) {
;     __syncthreads();
;     G_COMPUTE(kt & 1, kt);
;   }
	s_waitcnt vmcnt(7)
	ds_write_b128 v191, v[172:175]
	s_waitcnt vmcnt(6)
	ds_write_b128 v191, v[224:227] offset:36864
	ds_read_b128 v[172:175], v169
	ds_read_b128 v[224:227], v169 offset:4608
	v_mfma_f32_32x32x16_bf16 v[80:95], v[178:181], v[228:231], v[80:95]
	v_mfma_f32_32x32x16_bf16 v[16:31], v[220:223], v[228:231], v[16:31]
	ds_read_b128 v[228:231], v168
	v_mfma_f32_32x32x16_bf16 v[64:79], v[178:181], v[232:235], v[64:79]
	v_mfma_f32_32x32x16_bf16 v[0:15], v[220:223], v[232:235], v[0:15]
	ds_read_b128 v[232:235], v168 offset:4608
	s_setprio 0
	global_load_dwordx4 v[178:181], v[128:129], off offset:3200
	global_load_dwordx4 v[220:223], v[132:133], off offset:3200
	s_setprio 1
	s_waitcnt lgkmcnt(1)
	v_mfma_f32_32x32x16_bf16 v[112:127], v[172:175], v[228:231], v[112:127]
	v_mfma_f32_32x32x16_bf16 v[48:63], v[224:227], v[228:231], v[48:63]
	s_waitcnt lgkmcnt(0)
	v_mfma_f32_32x32x16_bf16 v[96:111], v[172:175], v[232:235], v[96:111]
	v_mfma_f32_32x32x16_bf16 v[32:47], v[224:227], v[232:235], v[32:47]
	ds_read_b128 v[228:231], v168 offset:9216
	ds_read_b128 v[232:235], v168 offset:13824
	s_waitcnt vmcnt(7)
	ds_write_b128 v191, v[158:161] offset:9216
	s_waitcnt vmcnt(6)
	ds_write_b128 v191, v[162:165] offset:46080
	ds_read_b128 v[158:161], v169 offset:32
	ds_read_b128 v[162:165], v169 offset:4640
	s_waitcnt lgkmcnt(5)
	v_mfma_f32_32x32x16_bf16 v[80:95], v[172:175], v[228:231], v[80:95]
	v_mfma_f32_32x32x16_bf16 v[16:31], v[224:227], v[228:231], v[16:31]
	ds_read_b128 v[228:231], v168 offset:32
	s_waitcnt lgkmcnt(5)
	v_mfma_f32_32x32x16_bf16 v[64:79], v[172:175], v[232:235], v[64:79]
	v_mfma_f32_32x32x16_bf16 v[0:15], v[224:227], v[232:235], v[0:15]
	ds_read_b128 v[232:235], v168 offset:4640
	s_setprio 0
	global_load_dwordx4 v[172:175], v[136:137], off offset:3200
	global_load_dwordx4 v[224:227], v[140:141], off offset:3200
	s_setprio 1
	s_waitcnt lgkmcnt(1)
	v_mfma_f32_32x32x16_bf16 v[112:127], v[158:161], v[228:231], v[112:127]
	v_mfma_f32_32x32x16_bf16 v[48:63], v[162:165], v[228:231], v[48:63]
	s_waitcnt lgkmcnt(0)
	v_mfma_f32_32x32x16_bf16 v[96:111], v[158:161], v[232:235], v[96:111]
	v_mfma_f32_32x32x16_bf16 v[32:47], v[162:165], v[232:235], v[32:47]
	ds_read_b128 v[228:231], v168 offset:9248
	ds_read_b128 v[232:235], v168 offset:13856
	s_waitcnt vmcnt(7)
	ds_write_b128 v191, v[200:203] offset:18432
	s_waitcnt vmcnt(6)
	ds_write_b128 v191, v[208:211] offset:55296
	ds_read_b128 v[200:203], v169 offset:64
	ds_read_b128 v[208:211], v169 offset:4672
	s_waitcnt lgkmcnt(5)
	v_mfma_f32_32x32x16_bf16 v[80:95], v[158:161], v[228:231], v[80:95]
	v_mfma_f32_32x32x16_bf16 v[16:31], v[162:165], v[228:231], v[16:31]
	ds_read_b128 v[228:231], v168 offset:64
	s_waitcnt lgkmcnt(5)
	v_mfma_f32_32x32x16_bf16 v[64:79], v[158:161], v[232:235], v[64:79]
	v_mfma_f32_32x32x16_bf16 v[0:15], v[162:165], v[232:235], v[0:15]
	ds_read_b128 v[232:235], v168 offset:4672
	s_setprio 0
	global_load_dwordx4 v[158:161], v[144:145], off offset:3200
	global_load_dwordx4 v[162:165], v[148:149], off offset:3200
	s_setprio 1
	s_waitcnt lgkmcnt(1)
	v_mfma_f32_32x32x16_bf16 v[112:127], v[200:203], v[228:231], v[112:127]
	v_mfma_f32_32x32x16_bf16 v[48:63], v[208:211], v[228:231], v[48:63]
	s_waitcnt lgkmcnt(0)
	v_mfma_f32_32x32x16_bf16 v[96:111], v[200:203], v[232:235], v[96:111]
	v_mfma_f32_32x32x16_bf16 v[32:47], v[208:211], v[232:235], v[32:47]
	ds_read_b128 v[228:231], v168 offset:9280
	ds_read_b128 v[232:235], v168 offset:13888
	s_waitcnt vmcnt(7)
	ds_write_b128 v191, v[212:215] offset:27648
	s_waitcnt vmcnt(6)
	ds_write_b128 v191, v[216:219] offset:64512
	ds_read_b128 v[212:215], v169 offset:96
	ds_read_b128 v[216:219], v169 offset:4704
	s_waitcnt lgkmcnt(5)
	v_mfma_f32_32x32x16_bf16 v[80:95], v[200:203], v[228:231], v[80:95]
	v_mfma_f32_32x32x16_bf16 v[16:31], v[208:211], v[228:231], v[16:31]
	ds_read_b128 v[228:231], v168 offset:96
	s_waitcnt lgkmcnt(5)
	v_mfma_f32_32x32x16_bf16 v[64:79], v[200:203], v[232:235], v[64:79]
	v_mfma_f32_32x32x16_bf16 v[0:15], v[208:211], v[232:235], v[0:15]
	ds_read_b128 v[232:235], v168 offset:4704
	s_setprio 0
	global_load_dwordx4 v[200:203], v[152:153], off offset:3200
	global_load_dwordx4 v[208:211], v[156:157], off offset:3200
	s_setprio 1
	s_waitcnt lgkmcnt(1)
	v_mfma_f32_32x32x16_bf16 v[112:127], v[212:215], v[228:231], v[112:127]
	v_mfma_f32_32x32x16_bf16 v[48:63], v[216:219], v[228:231], v[48:63]
	s_waitcnt lgkmcnt(0)
	v_mfma_f32_32x32x16_bf16 v[96:111], v[212:215], v[232:235], v[96:111]
	v_mfma_f32_32x32x16_bf16 v[32:47], v[216:219], v[232:235], v[32:47]
	ds_read_b128 v[228:231], v168 offset:9312
	ds_read_b128 v[232:235], v168 offset:13920
	s_waitcnt lgkmcnt(0)
	s_barrier
; template <bool trans>
; DI void gemm_core(const GTile& tl, const GTile& nx, bool has_next  , bool chain  , bool pre, u32x4 (&ra)[4], u32x4 (&rb)[4], char* smem, f32x16 (&acc)[2][4]) {
;     ...
;   const int nk = K / 64;
;   if (!pre) { G_LOAD(0); G_STORE(0); G_LOAD(1); }
;   for (int kt = 0; kt < nk; ++kt) {
;     __syncthreads();
;     G_COMPUTE(kt & 1, kt);
;   }
	s_waitcnt vmcnt(7)
	ds_write_b128 v195, v[178:181]
	s_waitcnt vmcnt(6)
	ds_write_b128 v196, v[220:223]
	ds_read_b128 v[178:181], v192 offset:36864
	ds_read_b128 v[220:223], v192 offset:41472
	v_mfma_f32_32x32x16_bf16 v[80:95], v[212:215], v[228:231], v[80:95]
	v_mfma_f32_32x32x16_bf16 v[16:31], v[216:219], v[228:231], v[16:31]
	ds_read_b128 v[228:231], v184
	v_mfma_f32_32x32x16_bf16 v[64:79], v[212:215], v[232:235], v[64:79]
	v_mfma_f32_32x32x16_bf16 v[0:15], v[216:219], v[232:235], v[0:15]
	ds_read_b128 v[232:235], v184 offset:4608
	s_setprio 0
	global_load_dwordx4 v[212:215], v[128:129], off offset:3328
	global_load_dwordx4 v[216:219], v[132:133], off offset:3328
	s_setprio 1
	s_waitcnt lgkmcnt(1)
	v_mfma_f32_32x32x16_bf16 v[112:127], v[178:181], v[228:231], v[112:127]
	v_mfma_f32_32x32x16_bf16 v[48:63], v[220:223], v[228:231], v[48:63]
	s_waitcnt lgkmcnt(0)
	v_mfma_f32_32x32x16_bf16 v[96:111], v[178:181], v[232:235], v[96:111]
	v_mfma_f32_32x32x16_bf16 v[32:47], v[220:223], v[232:235], v[32:47]
	ds_read_b128 v[228:231], v184 offset:9216
	ds_read_b128 v[232:235], v184 offset:13824
	s_waitcnt vmcnt(7)
	ds_write_b128 v194, v[172:175]
	s_waitcnt vmcnt(6)
	ds_write_b128 v193, v[224:227]
	ds_read_b128 v[172:175], v192 offset:36896
	ds_read_b128 v[224:227], v192 offset:41504
	s_waitcnt lgkmcnt(5)
	v_mfma_f32_32x32x16_bf16 v[80:95], v[178:181], v[228:231], v[80:95]
	v_mfma_f32_32x32x16_bf16 v[16:31], v[220:223], v[228:231], v[16:31]
	ds_read_b128 v[228:231], v184 offset:32
	s_waitcnt lgkmcnt(5)
	v_mfma_f32_32x32x16_bf16 v[64:79], v[178:181], v[232:235], v[64:79]
	v_mfma_f32_32x32x16_bf16 v[0:15], v[220:223], v[232:235], v[0:15]
	ds_read_b128 v[232:235], v184 offset:4640
	s_setprio 0
	global_load_dwordx4 v[178:181], v[136:137], off offset:3328
	global_load_dwordx4 v[220:223], v[140:141], off offset:3328
	s_setprio 1
	s_waitcnt lgkmcnt(1)
	v_mfma_f32_32x32x16_bf16 v[112:127], v[172:175], v[228:231], v[112:127]
	v_mfma_f32_32x32x16_bf16 v[48:63], v[224:227], v[228:231], v[48:63]
	s_waitcnt lgkmcnt(0)
	v_mfma_f32_32x32x16_bf16 v[96:111], v[172:175], v[232:235], v[96:111]
	v_mfma_f32_32x32x16_bf16 v[32:47], v[224:227], v[232:235], v[32:47]
	ds_read_b128 v[228:231], v184 offset:9248
	ds_read_b128 v[232:235], v184 offset:13856
	s_waitcnt vmcnt(7)
	ds_write_b128 v177, v[158:161]
	s_waitcnt vmcnt(6)
	ds_write_b128 v176, v[162:165]
	ds_read_b128 v[158:161], v192 offset:36928
	ds_read_b128 v[162:165], v192 offset:41536
	s_waitcnt lgkmcnt(5)
	v_mfma_f32_32x32x16_bf16 v[80:95], v[172:175], v[228:231], v[80:95]
	v_mfma_f32_32x32x16_bf16 v[16:31], v[224:227], v[228:231], v[16:31]
	ds_read_b128 v[228:231], v184 offset:64
	s_waitcnt lgkmcnt(5)
	v_mfma_f32_32x32x16_bf16 v[64:79], v[172:175], v[232:235], v[64:79]
	v_mfma_f32_32x32x16_bf16 v[0:15], v[224:227], v[232:235], v[0:15]
	ds_read_b128 v[232:235], v184 offset:4672
	s_setprio 0
	global_load_dwordx4 v[172:175], v[144:145], off offset:3328
	global_load_dwordx4 v[224:227], v[148:149], off offset:3328
	s_setprio 1
	s_waitcnt lgkmcnt(1)
	v_mfma_f32_32x32x16_bf16 v[112:127], v[158:161], v[228:231], v[112:127]
	v_mfma_f32_32x32x16_bf16 v[48:63], v[162:165], v[228:231], v[48:63]
	s_waitcnt lgkmcnt(0)
	v_mfma_f32_32x32x16_bf16 v[96:111], v[158:161], v[232:235], v[96:111]
	v_mfma_f32_32x32x16_bf16 v[32:47], v[162:165], v[232:235], v[32:47]
	ds_read_b128 v[228:231], v184 offset:9280
	ds_read_b128 v[232:235], v184 offset:13888
	s_waitcnt vmcnt(7)
	ds_write_b128 v171, v[200:203]
	s_waitcnt vmcnt(6)
	ds_write_b128 v170, v[208:211]
	ds_read_b128 v[200:203], v192 offset:36960
	ds_read_b128 v[208:211], v192 offset:41568
	s_waitcnt lgkmcnt(5)
	v_mfma_f32_32x32x16_bf16 v[80:95], v[158:161], v[228:231], v[80:95]
	v_mfma_f32_32x32x16_bf16 v[16:31], v[162:165], v[228:231], v[16:31]
	ds_read_b128 v[228:231], v184 offset:96
	s_waitcnt lgkmcnt(5)
	v_mfma_f32_32x32x16_bf16 v[64:79], v[158:161], v[232:235], v[64:79]
	v_mfma_f32_32x32x16_bf16 v[0:15], v[162:165], v[232:235], v[0:15]
	ds_read_b128 v[232:235], v184 offset:4704
	s_setprio 0
	global_load_dwordx4 v[158:161], v[152:153], off offset:3328
	global_load_dwordx4 v[162:165], v[156:157], off offset:3328
	s_setprio 1
	s_waitcnt lgkmcnt(1)
	v_mfma_f32_32x32x16_bf16 v[112:127], v[200:203], v[228:231], v[112:127]
	v_mfma_f32_32x32x16_bf16 v[48:63], v[208:211], v[228:231], v[48:63]
	s_waitcnt lgkmcnt(0)
	v_mfma_f32_32x32x16_bf16 v[96:111], v[200:203], v[232:235], v[96:111]
	v_mfma_f32_32x32x16_bf16 v[32:47], v[208:211], v[232:235], v[32:47]
	ds_read_b128 v[228:231], v184 offset:9312
	ds_read_b128 v[232:235], v184 offset:13920
	s_waitcnt lgkmcnt(0)
	s_barrier
; template <bool trans>
; DI void gemm_core(const GTile& tl, const GTile& nx, bool has_next  , bool chain  , bool pre, u32x4 (&ra)[4], u32x4 (&rb)[4], char* smem, f32x16 (&acc)[2][4]) {
;     ...
;   const int nk = K / 64;
;   if (!pre) { G_LOAD(0); G_STORE(0); G_LOAD(1); }
;   for (int kt = 0; kt < nk; ++kt) {
;     __syncthreads();
;     G_COMPUTE(kt & 1, kt);
;   }
	s_waitcnt vmcnt(7)
	ds_write_b128 v191, v[212:215]
	s_waitcnt vmcnt(6)
	ds_write_b128 v191, v[216:219] offset:36864
	ds_read_b128 v[212:215], v169
	ds_read_b128 v[216:219], v169 offset:4608
	v_mfma_f32_32x32x16_bf16 v[80:95], v[200:203], v[228:231], v[80:95]
	v_mfma_f32_32x32x16_bf16 v[16:31], v[208:211], v[228:231], v[16:31]
	ds_read_b128 v[228:231], v168
	v_mfma_f32_32x32x16_bf16 v[64:79], v[200:203], v[232:235], v[64:79]
	v_mfma_f32_32x32x16_bf16 v[0:15], v[208:211], v[232:235], v[0:15]
	ds_read_b128 v[232:235], v168 offset:4608
	s_setprio 0
	global_load_dwordx4 v[200:203], v[128:129], off offset:3456
	global_load_dwordx4 v[208:211], v[132:133], off offset:3456
	s_setprio 1
	s_waitcnt lgkmcnt(1)
	v_mfma_f32_32x32x16_bf16 v[112:127], v[212:215], v[228:231], v[112:127]
	v_mfma_f32_32x32x16_bf16 v[48:63], v[216:219], v[228:231], v[48:63]
	s_waitcnt lgkmcnt(0)
	v_mfma_f32_32x32x16_bf16 v[96:111], v[212:215], v[232:235], v[96:111]
	v_mfma_f32_32x32x16_bf16 v[32:47], v[216:219], v[232:235], v[32:47]
	ds_read_b128 v[228:231], v168 offset:9216
	ds_read_b128 v[232:235], v168 offset:13824
	s_waitcnt vmcnt(7)
	ds_write_b128 v191, v[178:181] offset:9216
	s_waitcnt vmcnt(6)
	ds_write_b128 v191, v[220:223] offset:46080
	ds_read_b128 v[178:181], v169 offset:32
	ds_read_b128 v[220:223], v169 offset:4640
	s_waitcnt lgkmcnt(5)
	v_mfma_f32_32x32x16_bf16 v[80:95], v[212:215], v[228:231], v[80:95]
	v_mfma_f32_32x32x16_bf16 v[16:31], v[216:219], v[228:231], v[16:31]
	ds_read_b128 v[228:231], v168 offset:32
	s_waitcnt lgkmcnt(5)
	v_mfma_f32_32x32x16_bf16 v[64:79], v[212:215], v[232:235], v[64:79]
	v_mfma_f32_32x32x16_bf16 v[0:15], v[216:219], v[232:235], v[0:15]
	ds_read_b128 v[232:235], v168 offset:4640
	s_setprio 0
	global_load_dwordx4 v[212:215], v[136:137], off offset:3456
	global_load_dwordx4 v[216:219], v[140:141], off offset:3456
	s_setprio 1
	s_waitcnt lgkmcnt(1)
	v_mfma_f32_32x32x16_bf16 v[112:127], v[178:181], v[228:231], v[112:127]
	v_mfma_f32_32x32x16_bf16 v[48:63], v[220:223], v[228:231], v[48:63]
	s_waitcnt lgkmcnt(0)
	v_mfma_f32_32x32x16_bf16 v[96:111], v[178:181], v[232:235], v[96:111]
	v_mfma_f32_32x32x16_bf16 v[32:47], v[220:223], v[232:235], v[32:47]
	ds_read_b128 v[228:231], v168 offset:9248
	ds_read_b128 v[232:235], v168 offset:13856
	s_waitcnt vmcnt(7)
	ds_write_b128 v191, v[172:175] offset:18432
	s_waitcnt vmcnt(6)
	ds_write_b128 v191, v[224:227] offset:55296
	ds_read_b128 v[172:175], v169 offset:64
	ds_read_b128 v[224:227], v169 offset:4672
	s_waitcnt lgkmcnt(5)
	v_mfma_f32_32x32x16_bf16 v[80:95], v[178:181], v[228:231], v[80:95]
	v_mfma_f32_32x32x16_bf16 v[16:31], v[220:223], v[228:231], v[16:31]
	ds_read_b128 v[228:231], v168 offset:64
	s_waitcnt lgkmcnt(5)
	v_mfma_f32_32x32x16_bf16 v[64:79], v[178:181], v[232:235], v[64:79]
	v_mfma_f32_32x32x16_bf16 v[0:15], v[220:223], v[232:235], v[0:15]
	ds_read_b128 v[232:235], v168 offset:4672
	s_setprio 0
	global_load_dwordx4 v[178:181], v[144:145], off offset:3456
	global_load_dwordx4 v[220:223], v[148:149], off offset:3456
	s_setprio 1
	s_waitcnt lgkmcnt(1)
	v_mfma_f32_32x32x16_bf16 v[112:127], v[172:175], v[228:231], v[112:127]
	v_mfma_f32_32x32x16_bf16 v[48:63], v[224:227], v[228:231], v[48:63]
	s_waitcnt lgkmcnt(0)
	v_mfma_f32_32x32x16_bf16 v[96:111], v[172:175], v[232:235], v[96:111]
	v_mfma_f32_32x32x16_bf16 v[32:47], v[224:227], v[232:235], v[32:47]
	ds_read_b128 v[228:231], v168 offset:9280
	ds_read_b128 v[232:235], v168 offset:13888
	s_waitcnt vmcnt(7)
	ds_write_b128 v191, v[158:161] offset:27648
	s_waitcnt vmcnt(6)
	ds_write_b128 v191, v[162:165] offset:64512
	ds_read_b128 v[158:161], v169 offset:96
	ds_read_b128 v[162:165], v169 offset:4704
	s_waitcnt lgkmcnt(5)
	v_mfma_f32_32x32x16_bf16 v[80:95], v[172:175], v[228:231], v[80:95]
	v_mfma_f32_32x32x16_bf16 v[16:31], v[224:227], v[228:231], v[16:31]
	ds_read_b128 v[228:231], v168 offset:96
	s_waitcnt lgkmcnt(5)
	v_mfma_f32_32x32x16_bf16 v[64:79], v[172:175], v[232:235], v[64:79]
	v_mfma_f32_32x32x16_bf16 v[0:15], v[224:227], v[232:235], v[0:15]
	ds_read_b128 v[232:235], v168 offset:4704
	s_setprio 0
	global_load_dwordx4 v[172:175], v[152:153], off offset:3456
	global_load_dwordx4 v[224:227], v[156:157], off offset:3456
	s_setprio 1
	s_waitcnt lgkmcnt(1)
	v_mfma_f32_32x32x16_bf16 v[112:127], v[158:161], v[228:231], v[112:127]
	v_mfma_f32_32x32x16_bf16 v[48:63], v[162:165], v[228:231], v[48:63]
	s_waitcnt lgkmcnt(0)
	v_mfma_f32_32x32x16_bf16 v[96:111], v[158:161], v[232:235], v[96:111]
	v_mfma_f32_32x32x16_bf16 v[32:47], v[162:165], v[232:235], v[32:47]
	ds_read_b128 v[228:231], v168 offset:9312
	ds_read_b128 v[232:235], v168 offset:13920
	s_waitcnt lgkmcnt(0)
	s_barrier
; template <bool trans>
; DI void gemm_core(const GTile& tl, const GTile& nx, bool has_next  , bool chain  , bool pre, u32x4 (&ra)[4], u32x4 (&rb)[4], char* smem, f32x16 (&acc)[2][4]) {
;     ...
;   const int nk = K / 64;
;   if (!pre) { G_LOAD(0); G_STORE(0); G_LOAD(1); }
;   for (int kt = 0; kt < nk; ++kt) {
;     __syncthreads();
;     G_COMPUTE(kt & 1, kt);
;   }
	s_waitcnt vmcnt(7)
	ds_write_b128 v195, v[200:203]
	s_waitcnt vmcnt(6)
	ds_write_b128 v196, v[208:211]
	ds_read_b128 v[200:203], v192 offset:36864
	ds_read_b128 v[208:211], v192 offset:41472
	v_mfma_f32_32x32x16_bf16 v[80:95], v[158:161], v[228:231], v[80:95]
	v_mfma_f32_32x32x16_bf16 v[16:31], v[162:165], v[228:231], v[16:31]
	ds_read_b128 v[228:231], v184
	v_mfma_f32_32x32x16_bf16 v[64:79], v[158:161], v[232:235], v[64:79]
	v_mfma_f32_32x32x16_bf16 v[0:15], v[162:165], v[232:235], v[0:15]
	ds_read_b128 v[232:235], v184 offset:4608
	s_setprio 0
	global_load_dwordx4 v[158:161], v[128:129], off offset:3584
	global_load_dwordx4 v[162:165], v[132:133], off offset:3584
	s_setprio 1
	s_waitcnt lgkmcnt(1)
	v_mfma_f32_32x32x16_bf16 v[112:127], v[200:203], v[228:231], v[112:127]
	v_mfma_f32_32x32x16_bf16 v[48:63], v[208:211], v[228:231], v[48:63]
	s_waitcnt lgkmcnt(0)
	v_mfma_f32_32x32x16_bf16 v[96:111], v[200:203], v[232:235], v[96:111]
	v_mfma_f32_32x32x16_bf16 v[32:47], v[208:211], v[232:235], v[32:47]
	ds_read_b128 v[228:231], v184 offset:9216
	ds_read_b128 v[232:235], v184 offset:13824
	s_waitcnt vmcnt(7)
	ds_write_b128 v194, v[212:215]
	s_waitcnt vmcnt(6)
	ds_write_b128 v193, v[216:219]
	ds_read_b128 v[212:215], v192 offset:36896
	ds_read_b128 v[216:219], v192 offset:41504
	s_waitcnt lgkmcnt(5)
	v_mfma_f32_32x32x16_bf16 v[80:95], v[200:203], v[228:231], v[80:95]
	v_mfma_f32_32x32x16_bf16 v[16:31], v[208:211], v[228:231], v[16:31]
	ds_read_b128 v[228:231], v184 offset:32
	s_waitcnt lgkmcnt(5)
	v_mfma_f32_32x32x16_bf16 v[64:79], v[200:203], v[232:235], v[64:79]
	v_mfma_f32_32x32x16_bf16 v[0:15], v[208:211], v[232:235], v[0:15]
	ds_read_b128 v[232:235], v184 offset:4640
	s_setprio 0
	global_load_dwordx4 v[200:203], v[136:137], off offset:3584
	global_load_dwordx4 v[208:211], v[140:141], off offset:3584
	s_setprio 1
	s_waitcnt lgkmcnt(1)
	v_mfma_f32_32x32x16_bf16 v[112:127], v[212:215], v[228:231], v[112:127]
	v_mfma_f32_32x32x16_bf16 v[48:63], v[216:219], v[228:231], v[48:63]
	s_waitcnt lgkmcnt(0)
	v_mfma_f32_32x32x16_bf16 v[96:111], v[212:215], v[232:235], v[96:111]
	v_mfma_f32_32x32x16_bf16 v[32:47], v[216:219], v[232:235], v[32:47]
	ds_read_b128 v[228:231], v184 offset:9248
	ds_read_b128 v[232:235], v184 offset:13856
	s_waitcnt vmcnt(7)
	ds_write_b128 v177, v[178:181]
	s_waitcnt vmcnt(6)
	ds_write_b128 v176, v[220:223]
	ds_read_b128 v[178:181], v192 offset:36928
	ds_read_b128 v[220:223], v192 offset:41536
	s_waitcnt lgkmcnt(5)
	v_mfma_f32_32x32x16_bf16 v[80:95], v[212:215], v[228:231], v[80:95]
	v_mfma_f32_32x32x16_bf16 v[16:31], v[216:219], v[228:231], v[16:31]
	ds_read_b128 v[228:231], v184 offset:64
	s_waitcnt lgkmcnt(5)
	v_mfma_f32_32x32x16_bf16 v[64:79], v[212:215], v[232:235], v[64:79]
	v_mfma_f32_32x32x16_bf16 v[0:15], v[216:219], v[232:235], v[0:15]
	ds_read_b128 v[232:235], v184 offset:4672
	s_setprio 0
	global_load_dwordx4 v[212:215], v[144:145], off offset:3584
	global_load_dwordx4 v[216:219], v[148:149], off offset:3584
	s_setprio 1
	s_waitcnt lgkmcnt(1)
	v_mfma_f32_32x32x16_bf16 v[112:127], v[178:181], v[228:231], v[112:127]
	v_mfma_f32_32x32x16_bf16 v[48:63], v[220:223], v[228:231], v[48:63]
	s_waitcnt lgkmcnt(0)
	v_mfma_f32_32x32x16_bf16 v[96:111], v[178:181], v[232:235], v[96:111]
	v_mfma_f32_32x32x16_bf16 v[32:47], v[220:223], v[232:235], v[32:47]
	ds_read_b128 v[228:231], v184 offset:9280
	ds_read_b128 v[232:235], v184 offset:13888
	s_waitcnt vmcnt(7)
	ds_write_b128 v171, v[172:175]
	s_waitcnt vmcnt(6)
	ds_write_b128 v170, v[224:227]
	ds_read_b128 v[172:175], v192 offset:36960
	ds_read_b128 v[224:227], v192 offset:41568
	s_waitcnt lgkmcnt(5)
	v_mfma_f32_32x32x16_bf16 v[80:95], v[178:181], v[228:231], v[80:95]
	v_mfma_f32_32x32x16_bf16 v[16:31], v[220:223], v[228:231], v[16:31]
	ds_read_b128 v[228:231], v184 offset:96
	s_waitcnt lgkmcnt(5)
	v_mfma_f32_32x32x16_bf16 v[64:79], v[178:181], v[232:235], v[64:79]
	v_mfma_f32_32x32x16_bf16 v[0:15], v[220:223], v[232:235], v[0:15]
	ds_read_b128 v[232:235], v184 offset:4704
	s_setprio 0
	global_load_dwordx4 v[178:181], v[152:153], off offset:3584
	global_load_dwordx4 v[220:223], v[156:157], off offset:3584
	s_setprio 1
	s_waitcnt lgkmcnt(1)
	v_mfma_f32_32x32x16_bf16 v[112:127], v[172:175], v[228:231], v[112:127]
	v_mfma_f32_32x32x16_bf16 v[48:63], v[224:227], v[228:231], v[48:63]
	s_waitcnt lgkmcnt(0)
	v_mfma_f32_32x32x16_bf16 v[96:111], v[172:175], v[232:235], v[96:111]
	v_mfma_f32_32x32x16_bf16 v[32:47], v[224:227], v[232:235], v[32:47]
	ds_read_b128 v[228:231], v184 offset:9312
	ds_read_b128 v[232:235], v184 offset:13920
	s_waitcnt lgkmcnt(0)
	s_barrier
; template <bool trans>
; DI void gemm_core(const GTile& tl, const GTile& nx, bool has_next  , bool chain  , bool pre, u32x4 (&ra)[4], u32x4 (&rb)[4], char* smem, f32x16 (&acc)[2][4]) {
;     ...
;   const int nk = K / 64;
;   if (!pre) { G_LOAD(0); G_STORE(0); G_LOAD(1); }
;   for (int kt = 0; kt < nk; ++kt) {
;     __syncthreads();
;     G_COMPUTE(kt & 1, kt);
;   }
	s_waitcnt vmcnt(7)
	ds_write_b128 v191, v[158:161]
	s_waitcnt vmcnt(6)
	ds_write_b128 v191, v[162:165] offset:36864
	ds_read_b128 v[158:161], v169
	ds_read_b128 v[162:165], v169 offset:4608
	v_mfma_f32_32x32x16_bf16 v[80:95], v[172:175], v[228:231], v[80:95]
	v_mfma_f32_32x32x16_bf16 v[16:31], v[224:227], v[228:231], v[16:31]
	ds_read_b128 v[228:231], v168
	v_mfma_f32_32x32x16_bf16 v[64:79], v[172:175], v[232:235], v[64:79]
	v_mfma_f32_32x32x16_bf16 v[0:15], v[224:227], v[232:235], v[0:15]
	ds_read_b128 v[232:235], v168 offset:4608
	s_setprio 0
	global_load_dwordx4 v[172:175], v[128:129], off offset:3712
	global_load_dwordx4 v[224:227], v[132:133], off offset:3712
	s_setprio 1
	s_waitcnt lgkmcnt(1)
	v_mfma_f32_32x32x16_bf16 v[112:127], v[158:161], v[228:231], v[112:127]
	v_mfma_f32_32x32x16_bf16 v[48:63], v[162:165], v[228:231], v[48:63]
	s_waitcnt lgkmcnt(0)
	v_mfma_f32_32x32x16_bf16 v[96:111], v[158:161], v[232:235], v[96:111]
	v_mfma_f32_32x32x16_bf16 v[32:47], v[162:165], v[232:235], v[32:47]
	ds_read_b128 v[228:231], v168 offset:9216
	ds_read_b128 v[232:235], v168 offset:13824
	s_waitcnt vmcnt(7)
	ds_write_b128 v191, v[200:203] offset:9216
	s_waitcnt vmcnt(6)
	ds_write_b128 v191, v[208:211] offset:46080
	ds_read_b128 v[200:203], v169 offset:32
	ds_read_b128 v[208:211], v169 offset:4640
	s_waitcnt lgkmcnt(5)
	v_mfma_f32_32x32x16_bf16 v[80:95], v[158:161], v[228:231], v[80:95]
	v_mfma_f32_32x32x16_bf16 v[16:31], v[162:165], v[228:231], v[16:31]
	ds_read_b128 v[228:231], v168 offset:32
	s_waitcnt lgkmcnt(5)
	v_mfma_f32_32x32x16_bf16 v[64:79], v[158:161], v[232:235], v[64:79]
	v_mfma_f32_32x32x16_bf16 v[0:15], v[162:165], v[232:235], v[0:15]
	ds_read_b128 v[232:235], v168 offset:4640
	s_setprio 0
	global_load_dwordx4 v[158:161], v[136:137], off offset:3712
	global_load_dwordx4 v[162:165], v[140:141], off offset:3712
	s_setprio 1
	s_waitcnt lgkmcnt(1)
	v_mfma_f32_32x32x16_bf16 v[112:127], v[200:203], v[228:231], v[112:127]
	v_mfma_f32_32x32x16_bf16 v[48:63], v[208:211], v[228:231], v[48:63]
	s_waitcnt lgkmcnt(0)
	v_mfma_f32_32x32x16_bf16 v[96:111], v[200:203], v[232:235], v[96:111]
	v_mfma_f32_32x32x16_bf16 v[32:47], v[208:211], v[232:235], v[32:47]
	ds_read_b128 v[228:231], v168 offset:9248
	ds_read_b128 v[232:235], v168 offset:13856
	s_waitcnt vmcnt(7)
	ds_write_b128 v191, v[212:215] offset:18432
	s_waitcnt vmcnt(6)
	ds_write_b128 v191, v[216:219] offset:55296
	ds_read_b128 v[212:215], v169 offset:64
	ds_read_b128 v[216:219], v169 offset:4672
	s_waitcnt lgkmcnt(5)
	v_mfma_f32_32x32x16_bf16 v[80:95], v[200:203], v[228:231], v[80:95]
	v_mfma_f32_32x32x16_bf16 v[16:31], v[208:211], v[228:231], v[16:31]
	ds_read_b128 v[228:231], v168 offset:64
	s_waitcnt lgkmcnt(5)
	v_mfma_f32_32x32x16_bf16 v[64:79], v[200:203], v[232:235], v[64:79]
	v_mfma_f32_32x32x16_bf16 v[0:15], v[208:211], v[232:235], v[0:15]
	ds_read_b128 v[232:235], v168 offset:4672
	s_setprio 0
	global_load_dwordx4 v[200:203], v[144:145], off offset:3712
	global_load_dwordx4 v[208:211], v[148:149], off offset:3712
	s_setprio 1
	s_waitcnt lgkmcnt(1)
	v_mfma_f32_32x32x16_bf16 v[112:127], v[212:215], v[228:231], v[112:127]
	v_mfma_f32_32x32x16_bf16 v[48:63], v[216:219], v[228:231], v[48:63]
	s_waitcnt lgkmcnt(0)
	v_mfma_f32_32x32x16_bf16 v[96:111], v[212:215], v[232:235], v[96:111]
	v_mfma_f32_32x32x16_bf16 v[32:47], v[216:219], v[232:235], v[32:47]
	ds_read_b128 v[228:231], v168 offset:9280
	ds_read_b128 v[232:235], v168 offset:13888
	s_waitcnt vmcnt(7)
	ds_write_b128 v191, v[178:181] offset:27648
	s_waitcnt vmcnt(6)
	ds_write_b128 v191, v[220:223] offset:64512
	ds_read_b128 v[178:181], v169 offset:96
	ds_read_b128 v[220:223], v169 offset:4704
	s_waitcnt lgkmcnt(5)
	v_mfma_f32_32x32x16_bf16 v[80:95], v[212:215], v[228:231], v[80:95]
	v_mfma_f32_32x32x16_bf16 v[16:31], v[216:219], v[228:231], v[16:31]
	ds_read_b128 v[228:231], v168 offset:96
	s_waitcnt lgkmcnt(5)
	v_mfma_f32_32x32x16_bf16 v[64:79], v[212:215], v[232:235], v[64:79]
	v_mfma_f32_32x32x16_bf16 v[0:15], v[216:219], v[232:235], v[0:15]
	ds_read_b128 v[232:235], v168 offset:4704
	s_setprio 0
	global_load_dwordx4 v[212:215], v[152:153], off offset:3712
	global_load_dwordx4 v[216:219], v[156:157], off offset:3712
	s_setprio 1
	s_waitcnt lgkmcnt(1)
	v_mfma_f32_32x32x16_bf16 v[112:127], v[178:181], v[228:231], v[112:127]
	v_mfma_f32_32x32x16_bf16 v[48:63], v[220:223], v[228:231], v[48:63]
	s_waitcnt lgkmcnt(0)
	v_mfma_f32_32x32x16_bf16 v[96:111], v[178:181], v[232:235], v[96:111]
	v_mfma_f32_32x32x16_bf16 v[32:47], v[220:223], v[232:235], v[32:47]
	ds_read_b128 v[228:231], v168 offset:9312
	ds_read_b128 v[232:235], v168 offset:13920
	s_waitcnt lgkmcnt(0)
	s_barrier
; template <bool trans>
; DI void gemm_core(const GTile& tl, const GTile& nx, bool has_next  , bool chain  , bool pre, u32x4 (&ra)[4], u32x4 (&rb)[4], char* smem, f32x16 (&acc)[2][4]) {
;     ...
;   const int nk = K / 64;
;   if (!pre) { G_LOAD(0); G_STORE(0); G_LOAD(1); }
;   for (int kt = 0; kt < nk; ++kt) {
;     __syncthreads();
;     G_COMPUTE(kt & 1, kt);
;   }
	s_waitcnt vmcnt(7)
	ds_write_b128 v195, v[172:175]
	s_waitcnt vmcnt(6)
	ds_write_b128 v196, v[224:227]
	ds_read_b128 v[172:175], v192 offset:36864
	ds_read_b128 v[224:227], v192 offset:41472
	v_mfma_f32_32x32x16_bf16 v[80:95], v[178:181], v[228:231], v[80:95]
	v_mfma_f32_32x32x16_bf16 v[16:31], v[220:223], v[228:231], v[16:31]
	ds_read_b128 v[228:231], v184
	v_mfma_f32_32x32x16_bf16 v[64:79], v[178:181], v[232:235], v[64:79]
	v_mfma_f32_32x32x16_bf16 v[0:15], v[220:223], v[232:235], v[0:15]
	ds_read_b128 v[232:235], v184 offset:4608
	s_setprio 0
	global_load_dwordx4 v[178:181], v[128:129], off offset:3840
	global_load_dwordx4 v[220:223], v[132:133], off offset:3840
	s_setprio 1
	s_waitcnt lgkmcnt(1)
	v_mfma_f32_32x32x16_bf16 v[112:127], v[172:175], v[228:231], v[112:127]
	v_mfma_f32_32x32x16_bf16 v[48:63], v[224:227], v[228:231], v[48:63]
	s_waitcnt lgkmcnt(0)
	v_mfma_f32_32x32x16_bf16 v[96:111], v[172:175], v[232:235], v[96:111]
	v_mfma_f32_32x32x16_bf16 v[32:47], v[224:227], v[232:235], v[32:47]
	ds_read_b128 v[228:231], v184 offset:9216
	ds_read_b128 v[232:235], v184 offset:13824
	s_waitcnt vmcnt(7)
	ds_write_b128 v194, v[158:161]
	s_waitcnt vmcnt(6)
	ds_write_b128 v193, v[162:165]
	ds_read_b128 v[158:161], v192 offset:36896
	ds_read_b128 v[162:165], v192 offset:41504
	s_waitcnt lgkmcnt(5)
	v_mfma_f32_32x32x16_bf16 v[80:95], v[172:175], v[228:231], v[80:95]
	v_mfma_f32_32x32x16_bf16 v[16:31], v[224:227], v[228:231], v[16:31]
	ds_read_b128 v[228:231], v184 offset:32
	s_waitcnt lgkmcnt(5)
	v_mfma_f32_32x32x16_bf16 v[64:79], v[172:175], v[232:235], v[64:79]
	v_mfma_f32_32x32x16_bf16 v[0:15], v[224:227], v[232:235], v[0:15]
	ds_read_b128 v[232:235], v184 offset:4640
	s_setprio 0
	global_load_dwordx4 v[172:175], v[136:137], off offset:3840
	global_load_dwordx4 v[224:227], v[140:141], off offset:3840
	s_setprio 1
	s_waitcnt lgkmcnt(1)
	v_mfma_f32_32x32x16_bf16 v[112:127], v[158:161], v[228:231], v[112:127]
	v_mfma_f32_32x32x16_bf16 v[48:63], v[162:165], v[228:231], v[48:63]
	s_waitcnt lgkmcnt(0)
	v_mfma_f32_32x32x16_bf16 v[96:111], v[158:161], v[232:235], v[96:111]
	v_mfma_f32_32x32x16_bf16 v[32:47], v[162:165], v[232:235], v[32:47]
	ds_read_b128 v[228:231], v184 offset:9248
	ds_read_b128 v[232:235], v184 offset:13856
	s_waitcnt vmcnt(7)
	ds_write_b128 v177, v[200:203]
	s_waitcnt vmcnt(6)
	ds_write_b128 v176, v[208:211]
	ds_read_b128 v[200:203], v192 offset:36928
	ds_read_b128 v[208:211], v192 offset:41536
	s_waitcnt lgkmcnt(5)
	v_mfma_f32_32x32x16_bf16 v[80:95], v[158:161], v[228:231], v[80:95]
	v_mfma_f32_32x32x16_bf16 v[16:31], v[162:165], v[228:231], v[16:31]
	ds_read_b128 v[228:231], v184 offset:64
	s_waitcnt lgkmcnt(5)
	v_mfma_f32_32x32x16_bf16 v[64:79], v[158:161], v[232:235], v[64:79]
	v_mfma_f32_32x32x16_bf16 v[0:15], v[162:165], v[232:235], v[0:15]
	ds_read_b128 v[232:235], v184 offset:4672
	s_setprio 0
	global_load_dwordx4 v[158:161], v[144:145], off offset:3840
	global_load_dwordx4 v[162:165], v[148:149], off offset:3840
	s_setprio 1
	s_waitcnt lgkmcnt(1)
	v_mfma_f32_32x32x16_bf16 v[112:127], v[200:203], v[228:231], v[112:127]
	v_mfma_f32_32x32x16_bf16 v[48:63], v[208:211], v[228:231], v[48:63]
	s_waitcnt lgkmcnt(0)
	v_mfma_f32_32x32x16_bf16 v[96:111], v[200:203], v[232:235], v[96:111]
	v_mfma_f32_32x32x16_bf16 v[32:47], v[208:211], v[232:235], v[32:47]
	ds_read_b128 v[228:231], v184 offset:9280
	ds_read_b128 v[232:235], v184 offset:13888
	s_waitcnt vmcnt(7)
	ds_write_b128 v171, v[212:215]
	s_waitcnt vmcnt(6)
	ds_write_b128 v170, v[216:219]
	ds_read_b128 v[212:215], v192 offset:36960
	ds_read_b128 v[216:219], v192 offset:41568
	s_waitcnt lgkmcnt(5)
	v_mfma_f32_32x32x16_bf16 v[80:95], v[200:203], v[228:231], v[80:95]
	v_mfma_f32_32x32x16_bf16 v[16:31], v[208:211], v[228:231], v[16:31]
	ds_read_b128 v[228:231], v184 offset:96
	s_waitcnt lgkmcnt(5)
	v_mfma_f32_32x32x16_bf16 v[64:79], v[200:203], v[232:235], v[64:79]
	v_mfma_f32_32x32x16_bf16 v[0:15], v[208:211], v[232:235], v[0:15]
	ds_read_b128 v[232:235], v184 offset:4704
	s_setprio 0
	global_load_dwordx4 v[200:203], v[152:153], off offset:3840
	global_load_dwordx4 v[208:211], v[156:157], off offset:3840
	s_setprio 1
	s_waitcnt lgkmcnt(1)
	v_mfma_f32_32x32x16_bf16 v[112:127], v[212:215], v[228:231], v[112:127]
	v_mfma_f32_32x32x16_bf16 v[48:63], v[216:219], v[228:231], v[48:63]
	s_waitcnt lgkmcnt(0)
	v_mfma_f32_32x32x16_bf16 v[96:111], v[212:215], v[232:235], v[96:111]
	v_mfma_f32_32x32x16_bf16 v[32:47], v[216:219], v[232:235], v[32:47]
	ds_read_b128 v[228:231], v184 offset:9312
	ds_read_b128 v[232:235], v184 offset:13920
	s_waitcnt lgkmcnt(1)
	v_mfma_f32_32x32x16_bf16 v[80:95], v[212:215], v[228:231], v[80:95]
	v_mfma_f32_32x32x16_bf16 v[16:31], v[216:219], v[228:231], v[16:31]
	s_waitcnt lgkmcnt(0)
	v_mfma_f32_32x32x16_bf16 v[64:79], v[212:215], v[232:235], v[64:79]
	v_mfma_f32_32x32x16_bf16 v[0:15], v[216:219], v[232:235], v[0:15]
	s_setprio 0
	s_barrier
; template <bool trans>
; DI void gemm_core(const GTile& tl, const GTile& nx, bool has_next  , bool chain  , bool pre, u32x4 (&ra)[4], u32x4 (&rb)[4], char* smem, f32x16 (&acc)[2][4]) {
;     ...
;   const int nk = K / 64;
;   if (!pre) { G_LOAD(0); G_STORE(0); G_LOAD(1); }
;   for (int kt = 0; kt < nk; ++kt) {
;     __syncthreads();
;     G_COMPUTE(kt & 1, kt);
;   }
	global_load_dwordx4 v[128:131], v[128:129], off offset:3968
	s_nop 0
	global_load_dwordx4 v[132:135], v[132:133], off offset:3968
	s_waitcnt vmcnt(9)
	ds_write_b128 v191, v[178:181]
	s_waitcnt vmcnt(8)
	ds_write_b128 v191, v[220:223] offset:36864
	ds_read_b128 v[178:181], v169
	ds_read_b128 v[212:215], v169 offset:4608
	ds_read_b128 v[216:219], v168
	ds_read_b128 v[220:223], v168 offset:4608
	s_setprio 1
	s_waitcnt lgkmcnt(1)
	v_mfma_f32_32x32x16_bf16 v[112:127], v[178:181], v[216:219], v[112:127]
	v_mfma_f32_32x32x16_bf16 v[48:63], v[212:215], v[216:219], v[48:63]
	s_waitcnt lgkmcnt(0)
	v_mfma_f32_32x32x16_bf16 v[96:111], v[178:181], v[220:223], v[96:111]
	v_mfma_f32_32x32x16_bf16 v[32:47], v[212:215], v[220:223], v[32:47]
	ds_read_b128 v[216:219], v168 offset:9216
	ds_read_b128 v[220:223], v168 offset:13824
	s_waitcnt lgkmcnt(1)
	v_mfma_f32_32x32x16_bf16 v[80:95], v[178:181], v[216:219], v[80:95]
	v_mfma_f32_32x32x16_bf16 v[16:31], v[212:215], v[216:219], v[16:31]
	s_waitcnt lgkmcnt(0)
	v_mfma_f32_32x32x16_bf16 v[64:79], v[178:181], v[220:223], v[64:79]
	v_mfma_f32_32x32x16_bf16 v[0:15], v[212:215], v[220:223], v[0:15]
	s_setprio 0
	global_load_dwordx4 v[136:139], v[136:137], off offset:3968
	s_nop 0
	global_load_dwordx4 v[140:143], v[140:141], off offset:3968
	s_waitcnt vmcnt(9)
	ds_write_b128 v191, v[172:175] offset:9216
	s_waitcnt vmcnt(8)
	ds_write_b128 v191, v[224:227] offset:46080
	ds_read_b128 v[172:175], v169 offset:32
	ds_read_b128 v[178:181], v169 offset:4640
	ds_read_b128 v[212:215], v168 offset:32
	ds_read_b128 v[216:219], v168 offset:4640
	s_setprio 1
	s_waitcnt lgkmcnt(1)
	v_mfma_f32_32x32x16_bf16 v[112:127], v[172:175], v[212:215], v[112:127]
	v_mfma_f32_32x32x16_bf16 v[48:63], v[178:181], v[212:215], v[48:63]
	s_waitcnt lgkmcnt(0)
	v_mfma_f32_32x32x16_bf16 v[96:111], v[172:175], v[216:219], v[96:111]
	v_mfma_f32_32x32x16_bf16 v[32:47], v[178:181], v[216:219], v[32:47]
	ds_read_b128 v[212:215], v168 offset:9248
	ds_read_b128 v[216:219], v168 offset:13856
	s_waitcnt lgkmcnt(1)
	v_mfma_f32_32x32x16_bf16 v[80:95], v[172:175], v[212:215], v[80:95]
	v_mfma_f32_32x32x16_bf16 v[16:31], v[178:181], v[212:215], v[16:31]
	s_waitcnt lgkmcnt(0)
	v_mfma_f32_32x32x16_bf16 v[64:79], v[172:175], v[216:219], v[64:79]
	v_mfma_f32_32x32x16_bf16 v[0:15], v[178:181], v[216:219], v[0:15]
	s_setprio 0
	global_load_dwordx4 v[144:147], v[144:145], off offset:3968
	s_nop 0
	global_load_dwordx4 v[148:151], v[148:149], off offset:3968
	s_waitcnt vmcnt(9)
	ds_write_b128 v191, v[158:161] offset:18432
	s_waitcnt vmcnt(8)
	ds_write_b128 v191, v[162:165] offset:55296
	ds_read_b128 v[158:161], v169 offset:64
	ds_read_b128 v[162:165], v169 offset:4672
	ds_read_b128 v[172:175], v168 offset:64
	ds_read_b128 v[178:181], v168 offset:4672
	s_setprio 1
	s_waitcnt lgkmcnt(1)
	v_mfma_f32_32x32x16_bf16 v[112:127], v[158:161], v[172:175], v[112:127]
	v_mfma_f32_32x32x16_bf16 v[48:63], v[162:165], v[172:175], v[48:63]
	s_waitcnt lgkmcnt(0)
	v_mfma_f32_32x32x16_bf16 v[96:111], v[158:161], v[178:181], v[96:111]
	v_mfma_f32_32x32x16_bf16 v[32:47], v[162:165], v[178:181], v[32:47]
	ds_read_b128 v[172:175], v168 offset:9280
	ds_read_b128 v[178:181], v168 offset:13888
	s_waitcnt lgkmcnt(1)
	v_mfma_f32_32x32x16_bf16 v[80:95], v[158:161], v[172:175], v[80:95]
	v_mfma_f32_32x32x16_bf16 v[16:31], v[162:165], v[172:175], v[16:31]
	s_waitcnt lgkmcnt(0)
	v_mfma_f32_32x32x16_bf16 v[64:79], v[158:161], v[178:181], v[64:79]
	v_mfma_f32_32x32x16_bf16 v[0:15], v[162:165], v[178:181], v[0:15]
	s_setprio 0
	global_load_dwordx4 v[152:155], v[152:153], off offset:3968
	s_nop 0
	global_load_dwordx4 v[156:159], v[156:157], off offset:3968
	s_waitcnt vmcnt(9)
	ds_write_b128 v191, v[200:203] offset:27648
	s_waitcnt vmcnt(8)
	ds_write_b128 v191, v[208:211] offset:64512
	ds_read_b128 v[160:163], v169 offset:96
	ds_read_b128 v[164:167], v169 offset:4704
	ds_read_b128 v[172:175], v168 offset:96
	ds_read_b128 v[178:181], v168 offset:4704
	s_setprio 1
	s_waitcnt lgkmcnt(1)
	v_mfma_f32_32x32x16_bf16 v[112:127], v[160:163], v[172:175], v[112:127]
	v_mfma_f32_32x32x16_bf16 v[48:63], v[164:167], v[172:175], v[48:63]
	s_waitcnt lgkmcnt(0)
	v_mfma_f32_32x32x16_bf16 v[96:111], v[160:163], v[178:181], v[96:111]
	v_mfma_f32_32x32x16_bf16 v[32:47], v[164:167], v[178:181], v[32:47]
	ds_read_b128 v[172:175], v168 offset:9312
	ds_read_b128 v[178:181], v168 offset:13920
	s_waitcnt lgkmcnt(1)
	v_mfma_f32_32x32x16_bf16 v[80:95], v[160:163], v[172:175], v[80:95]
	v_mfma_f32_32x32x16_bf16 v[16:31], v[164:167], v[172:175], v[16:31]
	s_waitcnt lgkmcnt(0)
	v_mfma_f32_32x32x16_bf16 v[64:79], v[160:163], v[178:181], v[64:79]
	v_mfma_f32_32x32x16_bf16 v[0:15], v[164:167], v[178:181], v[0:15]
	s_setprio 0
	s_and_b64 vcc, exec, s[10:11]
	s_barrier
	s_waitcnt vmcnt(7)
	ds_write_b128 v195, v[128:131]
	s_waitcnt vmcnt(6)
	ds_write_b128 v196, v[132:135]
	s_cbranch_vccnz .LBB0_1639
	global_load_dwordx4 v[128:131], v[188:189], off
	global_load_dwordx4 v[132:135], v[186:187], off
